# P5 FFT code: two v_mov building one register pair merged into one v_pk_mov_b32 (125 sites)
# baseline (speedup 1.0000x reference)
.LBB0_492:
	s_or_b64 exec, exec, s[72:73]
	s_waitcnt vmcnt(0)
	v_lshlrev_b32_e32 v27, 16, v27
	v_lshlrev_b32_e32 v25, 16, v25
	v_mov_b32_e32 v11, v10
	v_mov_b32_e32 v13, v12
	v_pk_mov_b32 v[20:21], v[14:15], v[14:15] op_sel:[0,0]
	v_pk_mov_b32 v[22:23], v[14:15], v[14:15] op_sel:[1,1]
	v_and_b32_e32 v32, 0xffff0000, v6
	v_mov_b32_e32 v26, v32
	v_lshlrev_b32_e32 v28, 16, v6
	v_pk_mul_f32 v[26:27], v[14:15], v[26:27]
	v_lshlrev_b32_e32 v33, 16, v7
	v_pk_fma_f32 v[26:27], v[14:15], v[28:29], v[26:27] op_sel:[0,0,1] op_sel_hi:[1,0,0]
	v_and_b32_e32 v29, 16, v8
	v_and_b32_e32 v28, 0xffff0000, v7
	v_mov_b32_e32 v6, v28
	v_pk_mov_b32 v[28:29], v[32:33], v[28:29] op_sel:[1,0]
	v_lshlrev_b32_e32 v17, 1, v30
	v_pk_mul_f32 v[28:29], v[20:21], v[28:29]
	v_lshlrev_b32_e32 v7, 16, v8
	v_pk_fma_f32 v[28:29], v[22:23], v[32:33], v[28:29]
	v_and_b32_e32 v17, -8, v17
	v_pk_fma_f32 v[26:27], v[10:11], v[32:33], v[26:27]
	v_pk_fma_f32 v[28:29], v[10:11], v[6:7], v[28:29]
	v_add_u32_e32 v17, v18, v17
	v_pk_add_f32 v[26:27], v[12:13], v[26:27]
	v_pk_add_f32 v[28:29], v[12:13], v[28:29]
	ds_write2_b64 v17, v[26:27], v[28:29] offset1:1
	v_and_b32_e32 v27, 16, v9
	v_and_b32_e32 v26, 0xffff0000, v8
	v_lshlrev_b32_e32 v29, 16, v9
	v_mov_b32_e32 v28, v26
	v_pk_mov_b32 v[26:27], v[6:7], v[26:27] op_sel:[1,0]
	v_pk_mov_b32 v[8:9], v[8:9], v[2:3] op_sel:[1,0]
	v_pk_mul_f32 v[26:27], v[20:21], v[26:27]
	v_and_b32_e32 v9, 16, v9
	v_and_b32_e32 v8, 0xffff0000, v8
	v_pk_fma_f32 v[6:7], v[22:23], v[6:7], v[26:27]
	v_mov_b32_e32 v26, v8
	v_pk_mov_b32 v[8:9], v[28:29], v[8:9] op_sel:[1,0]
	v_lshlrev_b32_e32 v27, 16, v2
	v_pk_mul_f32 v[8:9], v[20:21], v[8:9]
	v_pk_fma_f32 v[6:7], v[10:11], v[28:29], v[6:7]
	v_pk_fma_f32 v[8:9], v[22:23], v[28:29], v[8:9]
	v_pk_add_f32 v[6:7], v[12:13], v[6:7]
	v_pk_fma_f32 v[8:9], v[10:11], v[26:27], v[8:9]
	v_and_b32_e32 v24, 0xffff0000, v5
	v_pk_add_f32 v[8:9], v[12:13], v[8:9]
	ds_write2_b64 v17, v[6:7], v[8:9] offset0:2 offset1:3
	v_and_b32_e32 v7, 16, v3
	v_and_b32_e32 v6, 0xffff0000, v2
	v_mov_b32_e32 v8, v6
	v_pk_mov_b32 v[6:7], v[26:27], v[6:7] op_sel:[1,0]
	v_lshlrev_b32_e32 v9, 16, v3
	v_pk_mul_f32 v[6:7], v[20:21], v[6:7]
	v_cmp_lt_i32_e32 vcc, s93, v30
	v_pk_fma_f32 v[6:7], v[22:23], v[26:27], v[6:7]
	v_and_b32_e32 v27, 16, v4
	v_and_b32_e32 v26, 0xffff0000, v3
	v_mov_b32_e32 v2, v26
	v_pk_mov_b32 v[26:27], v[8:9], v[26:27] op_sel:[1,0]
	v_pk_fma_f32 v[6:7], v[10:11], v[8:9], v[6:7]
	v_pk_mul_f32 v[26:27], v[20:21], v[26:27]
	v_lshlrev_b32_e32 v3, 16, v4
	v_pk_fma_f32 v[8:9], v[22:23], v[8:9], v[26:27]
	v_pk_add_f32 v[6:7], v[12:13], v[6:7]
	v_pk_fma_f32 v[8:9], v[10:11], v[2:3], v[8:9]
	v_add_u32_e32 v18, 0x8000, v18
	v_pk_add_f32 v[8:9], v[12:13], v[8:9]
	ds_write2_b64 v17, v[6:7], v[8:9] offset0:4 offset1:5
	v_and_b32_e32 v7, 16, v5
	v_and_b32_e32 v6, 0xffff0000, v4
	v_mov_b32_e32 v4, v6
	v_pk_mov_b32 v[6:7], v[2:3], v[6:7] op_sel:[1,0]
	v_lshlrev_b32_e32 v5, 16, v5
	v_pk_mul_f32 v[6:7], v[20:21], v[6:7]
	v_add_u32_e32 v16, 0x2000, v16
	v_pk_fma_f32 v[2:3], v[22:23], v[2:3], v[6:7]
	v_pk_mov_b32 v[6:7], v[4:5], v[24:25] op_sel:[1,0]
	s_nop 0
	v_pk_mul_f32 v[6:7], v[20:21], v[6:7]
	v_pk_fma_f32 v[2:3], v[10:11], v[4:5], v[2:3]
	v_pk_fma_f32 v[4:5], v[22:23], v[4:5], v[6:7]
	v_pk_add_f32 v[2:3], v[12:13], v[2:3]
	v_pk_fma_f32 v[4:5], v[10:11], v[24:25], v[4:5]
	s_or_b64 s[70:71], vcc, s[70:71]
	v_pk_add_f32 v[4:5], v[12:13], v[4:5]
	ds_write2_b64 v17, v[2:3], v[4:5] offset0:6 offset1:7
	v_add_u32_e32 v2, 0x200, v30
	v_mov_b32_e32 v30, v2
	s_andn2_b64 exec, exec, s[70:71]
	s_cbranch_execz .LBB0_497

.LBB0_499:
	v_mov_b32_e32 v2, v210
	s_mov_b32 s43, s8
	v_and_b32_e32 v3, 0x1ff, v2
	v_lshlrev_b32_e32 v2, 5, v2
	v_and_or_b32 v2, v2, s94, v3
	v_ashrrev_i32_e32 v4, 5, v2
	v_lshlrev_b32_e32 v2, 3, v2
	v_lshlrev_b32_e32 v4, 3, v4
	v_add3_u32 v18, 0, v2, v4
	ds_read_b64 v[128:129], v18
	ds_read_b64 v[134:135], v18 offset:4224
	ds_read_b64 v[136:137], v18 offset:8448
	ds_read_b64 v[138:139], v18 offset:12672
	ds_read_b64 v[140:141], v18 offset:16896
	ds_read_b64 v[142:143], v18 offset:21120
	ds_read_b64 v[132:133], v18 offset:25344
	ds_read_b64 v[130:131], v18 offset:29568
	ds_read_b64 v[144:145], v18 offset:33792
	ds_read_b64 v[148:149], v18 offset:38016
	ds_read_b64 v[150:151], v18 offset:42240
	ds_read_b64 v[152:153], v18 offset:46464
	s_waitcnt lgkmcnt(10)
	v_pk_mul_f32 v[162:163], v[134:135], s[10:11]
	s_mov_b32 s74, s11
	v_pk_fma_f32 v[162:163], v[134:135], s[8:9], v[162:163] op_sel:[0,0,1] op_sel_hi:[1,0,0]
	s_waitcnt lgkmcnt(2)
	v_pk_mul_f32 v[178:179], v[148:149], s[42:43]
	v_pk_add_f32 v[194:195], v[134:135], v[148:149]
	v_pk_add_f32 v[134:135], v[134:135], v[148:149] neg_lo:[0,1] neg_hi:[0,1]
	v_pk_mul_f32 v[164:165], v[136:137], s[18:19]
	s_mov_b32 s41, s16
	v_pk_fma_f32 v[178:179], v[148:149], s[74:75], v[178:179] op_sel:[0,0,1] op_sel_hi:[1,0,0] neg_lo:[1,0,0] neg_hi:[1,0,0]
	v_pk_mul_f32 v[148:149], v[134:135], s[18:19]
	v_pk_fma_f32 v[164:165], v[136:137], s[16:17], v[164:165] op_sel:[0,0,1] op_sel_hi:[1,0,0]
	s_mov_b32 s80, s19
	s_waitcnt lgkmcnt(1)
	v_pk_mul_f32 v[180:181], v[150:151], s[40:41]
	v_pk_fma_f32 v[134:135], v[134:135], s[16:17], v[148:149] op_sel:[0,0,1] op_sel_hi:[1,0,0]
	v_pk_add_f32 v[148:149], v[136:137], v[150:151]
	v_pk_add_f32 v[136:137], v[136:137], v[150:151] neg_lo:[0,1] neg_hi:[0,1]
	v_pk_mul_f32 v[166:167], v[138:139], s[26:27]
	s_mov_b32 s78, s37
	s_mov_b32 s39, s24
	v_pk_fma_f32 v[180:181], v[150:151], s[80:81], v[180:181] op_sel:[0,0,1] op_sel_hi:[1,0,0] neg_lo:[1,0,0] neg_hi:[1,0,0]
	v_pk_mul_f32 v[150:151], v[136:137], s[36:37]
	ds_read_b64 v[154:155], v18 offset:50688
	ds_read_b64 v[156:157], v18 offset:54912
	ds_read_b64 v[158:159], v18 offset:59136
	ds_read_b64 v[160:161], v18 offset:63360
	v_pk_fma_f32 v[166:167], v[138:139], s[24:25], v[166:167] op_sel:[0,0,1] op_sel_hi:[1,0,0]
	s_mov_b32 s0, s27
	s_waitcnt lgkmcnt(4)
	v_pk_mul_f32 v[182:183], v[152:153], s[38:39]
	v_pk_fma_f32 v[136:137], v[136:137], s[78:79], v[150:151] op_sel:[0,0,1] op_sel_hi:[1,0,0]
	v_pk_add_f32 v[150:151], v[138:139], v[152:153]
	v_pk_add_f32 v[138:139], v[138:139], v[152:153] neg_lo:[0,1] neg_hi:[0,1]
	v_pk_mul_f32 v[168:169], v[140:141], s[36:37]
	v_pk_fma_f32 v[182:183], v[152:153], s[0:1], v[182:183] op_sel:[0,0,1] op_sel_hi:[1,0,0] neg_lo:[1,0,0] neg_hi:[1,0,0]
	v_pk_mul_f32 v[152:153], v[138:139], s[40:41]
	v_pk_fma_f32 v[168:169], v[140:141], s[78:79], v[168:169] op_sel:[0,0,1] op_sel_hi:[1,0,0]
	v_pk_mul_f32 v[170:171], v[142:143], s[38:39]
	s_waitcnt lgkmcnt(3)
	v_pk_mul_f32 v[184:185], v[154:155], s[36:37]
	v_pk_fma_f32 v[138:139], v[138:139], s[80:81], v[152:153] op_sel:[0,0,1] op_sel_hi:[1,0,0]
	v_pk_add_f32 v[152:153], v[140:141], v[154:155]
	v_pk_add_f32 v[140:141], v[140:141], v[154:155] neg_lo:[0,1] neg_hi:[0,1]
	v_pk_fma_f32 v[170:171], v[142:143], s[0:1], v[170:171] op_sel:[0,0,1] op_sel_hi:[1,0,0]
	v_pk_fma_f32 v[184:185], v[154:155], s[78:79], v[184:185] op_sel:[0,0,1] op_sel_hi:[1,0,0] neg_lo:[1,0,0] neg_hi:[1,0,0]
	s_waitcnt lgkmcnt(2)
	v_pk_mul_f32 v[186:187], v[156:157], s[26:27]
	v_pk_mul_f32 v[154:155], v[140:141], 1.0 op_sel:[1,0] op_sel_hi:[0,0] neg_hi:[1,0]
	v_pk_add_f32 v[140:141], v[142:143], v[156:157]
	v_pk_add_f32 v[142:143], v[142:143], v[156:157] neg_lo:[0,1] neg_hi:[0,1]
	v_pk_mul_f32 v[172:173], v[132:133], s[40:41]
	v_pk_fma_f32 v[186:187], v[156:157], s[24:25], v[186:187] op_sel:[0,0,1] op_sel_hi:[1,0,0] neg_lo:[1,0,0] neg_hi:[1,0,0]
	v_pk_mul_f32 v[156:157], v[142:143], s[40:41]
	v_pk_fma_f32 v[172:173], v[132:133], s[80:81], v[172:173] op_sel:[0,0,1] op_sel_hi:[1,0,0]
	s_waitcnt lgkmcnt(1)
	v_pk_mul_f32 v[188:189], v[158:159], s[18:19]
	v_pk_fma_f32 v[142:143], v[142:143], s[80:81], v[156:157] op_sel:[0,0,1] op_sel_hi:[1,0,0] neg_lo:[1,0,0] neg_hi:[1,0,0]
	v_pk_add_f32 v[156:157], v[132:133], v[158:159]
	v_pk_add_f32 v[132:133], v[132:133], v[158:159] neg_lo:[0,1] neg_hi:[0,1]
	v_pk_mul_f32 v[174:175], v[130:131], s[42:43]
	v_pk_fma_f32 v[188:189], v[158:159], s[16:17], v[188:189] op_sel:[0,0,1] op_sel_hi:[1,0,0] neg_lo:[1,0,0] neg_hi:[1,0,0]
	v_pk_mul_f32 v[158:159], v[132:133], s[36:37]
	v_pk_fma_f32 v[174:175], v[130:131], s[74:75], v[174:175] op_sel:[0,0,1] op_sel_hi:[1,0,0]
	s_waitcnt lgkmcnt(0)
	v_pk_mul_f32 v[190:191], v[160:161], s[10:11]
	v_pk_fma_f32 v[132:133], v[132:133], s[78:79], v[158:159] op_sel:[0,0,1] op_sel_hi:[1,0,0] neg_lo:[1,0,0] neg_hi:[1,0,0]
	v_pk_add_f32 v[158:159], v[130:131], v[160:161]
	v_pk_add_f32 v[130:131], v[130:131], v[160:161] neg_lo:[0,1] neg_hi:[0,1]
	v_pk_mul_f32 v[176:177], v[144:145], 1.0 op_sel:[1,0] op_sel_hi:[0,0] neg_hi:[1,0]
	v_pk_fma_f32 v[190:191], v[160:161], s[8:9], v[190:191] op_sel:[0,0,1] op_sel_hi:[1,0,0] neg_lo:[1,0,0] neg_hi:[1,0,0]
	v_pk_mul_f32 v[160:161], v[130:131], s[18:19]
	v_pk_add_f32 v[192:193], v[128:129], v[144:145]
	v_pk_add_f32 v[144:145], v[128:129], v[144:145] neg_lo:[0,1] neg_hi:[0,1]
	v_pk_fma_f32 v[130:131], v[130:131], s[16:17], v[160:161] op_sel:[0,0,1] op_sel_hi:[1,0,0] neg_lo:[1,0,0] neg_hi:[1,0,0]
	v_pk_add_f32 v[160:161], v[128:129], v[176:177]
	v_pk_add_f32 v[128:129], v[128:129], v[176:177] neg_lo:[0,1] neg_hi:[0,1]
	v_pk_add_f32 v[176:177], v[162:163], v[178:179]
	v_pk_add_f32 v[162:163], v[162:163], v[178:179] neg_lo:[0,1] neg_hi:[0,1]
	v_cvt_f32_u32_e32 v2, v3
	v_pk_mul_f32 v[178:179], v[162:163], s[18:19]
	s_add_i32 s76, s72, s48
	v_pk_fma_f32 v[162:163], v[162:163], s[16:17], v[178:179] op_sel:[0,0,1] op_sel_hi:[1,0,0]
	v_pk_add_f32 v[178:179], v[164:165], v[180:181]
	v_pk_add_f32 v[164:165], v[164:165], v[180:181] neg_lo:[0,1] neg_hi:[0,1]
	v_mul_f32_e32 v2, 0x38800000, v2
	v_pk_mul_f32 v[180:181], v[164:165], s[36:37]
	v_sin_f32_e32 v34, v2
	v_pk_fma_f32 v[164:165], v[164:165], s[78:79], v[180:181] op_sel:[0,0,1] op_sel_hi:[1,0,0]
	v_pk_add_f32 v[180:181], v[166:167], v[182:183]
	v_pk_add_f32 v[166:167], v[166:167], v[182:183] neg_lo:[0,1] neg_hi:[0,1]
	v_cos_f32_e32 v30, v2
	v_pk_mul_f32 v[182:183], v[166:167], s[40:41]
	v_xor_b32_e32 v31, 0x80000000, v34
	v_pk_fma_f32 v[166:167], v[166:167], s[80:81], v[182:183] op_sel:[0,0,1] op_sel_hi:[1,0,0]
	v_pk_add_f32 v[182:183], v[168:169], v[184:185]
	v_pk_add_f32 v[184:185], v[168:169], v[184:185] neg_lo:[0,1] neg_hi:[0,1]
	v_mov_b32_e32 v35, v31
	v_pk_add_f32 v[168:169], v[170:171], v[186:187]
	v_pk_add_f32 v[170:171], v[170:171], v[186:187] neg_lo:[0,1] neg_hi:[0,1]
	v_pk_mul_f32 v[2:3], v[30:31], v[34:35] op_sel:[1,0] op_sel_hi:[0,1]
	v_pk_mul_f32 v[186:187], v[170:171], s[40:41]
	v_pk_fma_f32 v[44:45], v[30:31], v[30:31], v[2:3] op_sel_hi:[1,0,1]
	v_pk_fma_f32 v[170:171], v[170:171], s[80:81], v[186:187] op_sel:[0,0,1] op_sel_hi:[1,0,0] neg_lo:[1,0,0] neg_hi:[1,0,0]
	v_pk_add_f32 v[186:187], v[172:173], v[188:189]
	v_pk_add_f32 v[172:173], v[172:173], v[188:189] neg_lo:[0,1] neg_hi:[0,1]
	v_pk_mul_f32 v[2:3], v[34:35], v[44:45] op_sel:[0,1] op_sel_hi:[1,0]
	v_pk_mul_f32 v[188:189], v[172:173], s[36:37]
	v_pk_mul_f32 v[54:55], v[44:45], 1.0 op_sel:[1,0] op_sel_hi:[1,0] neg_lo:[1,0]
	v_pk_fma_f32 v[172:173], v[172:173], s[78:79], v[188:189] op_sel:[0,0,1] op_sel_hi:[1,0,0] neg_lo:[1,0,0] neg_hi:[1,0,0]
	v_pk_add_f32 v[188:189], v[174:175], v[190:191]
	v_pk_add_f32 v[174:175], v[174:175], v[190:191] neg_lo:[0,1] neg_hi:[0,1]
	s_nop 0
	v_pk_mul_f32 v[190:191], v[174:175], s[18:19]
	v_pk_fma_f32 v[46:47], v[30:31], v[44:45], v[2:3] op_sel_hi:[0,1,1]
	v_pk_fma_f32 v[174:175], v[174:175], s[16:17], v[190:191] op_sel:[0,0,1] op_sel_hi:[1,0,0] neg_lo:[1,0,0] neg_hi:[1,0,0]
	v_pk_add_f32 v[190:191], v[192:193], v[152:153]
	v_pk_add_f32 v[152:153], v[192:193], v[152:153] neg_lo:[0,1] neg_hi:[0,1]
	v_pk_add_f32 v[192:193], v[194:195], v[140:141]
	v_pk_add_f32 v[140:141], v[194:195], v[140:141] neg_lo:[0,1] neg_hi:[0,1]
	v_pk_mul_f32 v[2:3], v[44:45], v[54:55] op_sel:[1,0] op_sel_hi:[0,1]
	v_pk_mul_f32 v[194:195], v[140:141], s[36:37]
	v_pk_fma_f32 v[52:53], v[44:45], v[44:45], v[2:3] op_sel_hi:[1,0,1]
	v_pk_fma_f32 v[140:141], v[140:141], s[78:79], v[194:195] op_sel:[0,0,1] op_sel_hi:[1,0,0]
	v_pk_add_f32 v[194:195], v[148:149], v[156:157]
	v_pk_add_f32 v[156:157], v[148:149], v[156:157] neg_lo:[0,1] neg_hi:[0,1]
	v_pk_mul_f32 v[58:59], v[52:53], 1.0 op_sel:[1,0] op_sel_hi:[1,0] neg_lo:[1,0]
	v_pk_add_f32 v[148:149], v[150:151], v[158:159]
	v_pk_add_f32 v[150:151], v[150:151], v[158:159] neg_lo:[0,1] neg_hi:[0,1]
	s_nop 0
	v_pk_mul_f32 v[158:159], v[150:151], s[36:37]
	v_pk_mul_f32 v[2:3], v[52:53], v[58:59] op_sel:[1,0] op_sel_hi:[0,1]
	v_pk_fma_f32 v[150:151], v[150:151], s[78:79], v[158:159] op_sel:[0,0,1] op_sel_hi:[1,0,0] neg_lo:[1,0,0] neg_hi:[1,0,0]
	v_pk_add_f32 v[158:159], v[144:145], v[154:155]
	v_pk_add_f32 v[144:145], v[144:145], v[154:155] neg_lo:[0,1] neg_hi:[0,1]
	v_pk_add_f32 v[154:155], v[134:135], v[142:143]
	v_pk_add_f32 v[134:135], v[134:135], v[142:143] neg_lo:[0,1] neg_hi:[0,1]
	v_pk_fma_f32 v[48:49], v[52:53], v[52:53], v[2:3] op_sel_hi:[1,0,1]
	v_pk_mul_f32 v[142:143], v[134:135], s[36:37]
	v_pk_mul_f32 v[2:3], v[58:59], v[48:49] op_sel:[0,1] op_sel_hi:[1,0]
	v_pk_fma_f32 v[134:135], v[134:135], s[78:79], v[142:143] op_sel:[0,0,1] op_sel_hi:[1,0,0]
	v_pk_add_f32 v[142:143], v[136:137], v[132:133]
	v_pk_add_f32 v[136:137], v[136:137], v[132:133] neg_lo:[0,1] neg_hi:[0,1]
	v_pk_fma_f32 v[36:37], v[52:53], v[48:49], v[2:3] op_sel_hi:[0,1,1]
	v_pk_add_f32 v[132:133], v[138:139], v[130:131]
	v_pk_add_f32 v[130:131], v[138:139], v[130:131] neg_lo:[0,1] neg_hi:[0,1]
	v_pk_mul_f32 v[2:3], v[58:59], v[36:37] op_sel:[0,1] op_sel_hi:[1,0]
	v_pk_mul_f32 v[138:139], v[130:131], s[36:37]
	v_pk_fma_f32 v[26:27], v[52:53], v[36:37], v[2:3] op_sel_hi:[0,1,1]
	v_pk_fma_f32 v[130:131], v[130:131], s[78:79], v[138:139] op_sel:[0,0,1] op_sel_hi:[1,0,0] neg_lo:[1,0,0] neg_hi:[1,0,0]
	v_pk_add_f32 v[138:139], v[160:161], v[182:183]
	v_pk_add_f32 v[160:161], v[160:161], v[182:183] neg_lo:[0,1] neg_hi:[0,1]
	v_pk_add_f32 v[182:183], v[176:177], v[168:169]
	v_pk_add_f32 v[168:169], v[176:177], v[168:169] neg_lo:[0,1] neg_hi:[0,1]
	v_pk_mul_f32 v[2:3], v[58:59], v[26:27] op_sel:[0,1] op_sel_hi:[1,0]
	v_pk_mul_f32 v[176:177], v[168:169], s[36:37]
	v_pk_fma_f32 v[20:21], v[52:53], v[26:27], v[2:3] op_sel_hi:[0,1,1]
	v_pk_fma_f32 v[168:169], v[168:169], s[78:79], v[176:177] op_sel:[0,0,1] op_sel_hi:[1,0,0]
	v_pk_add_f32 v[176:177], v[178:179], v[186:187]
	v_pk_add_f32 v[186:187], v[178:179], v[186:187] neg_lo:[0,1] neg_hi:[0,1]
	v_pk_mul_f32 v[2:3], v[58:59], v[20:21] op_sel:[0,1] op_sel_hi:[1,0]
	v_pk_add_f32 v[178:179], v[180:181], v[188:189]
	v_pk_add_f32 v[180:181], v[180:181], v[188:189] neg_lo:[0,1] neg_hi:[0,1]
	v_pk_fma_f32 v[10:11], v[52:53], v[20:21], v[2:3] op_sel_hi:[0,1,1]
	v_pk_mul_f32 v[188:189], v[180:181], s[36:37]
	v_pk_mul_f32 v[2:3], v[58:59], v[10:11] op_sel:[0,1] op_sel_hi:[1,0]
	v_pk_fma_f32 v[180:181], v[180:181], s[78:79], v[188:189] op_sel:[0,0,1] op_sel_hi:[1,0,0] neg_lo:[1,0,0] neg_hi:[1,0,0]
	v_pk_add_f32 v[188:189], v[128:129], v[184:185] op_sel:[0,1] op_sel_hi:[1,0] neg_hi:[0,1]
	v_pk_add_f32 v[128:129], v[128:129], v[184:185] op_sel:[0,1] op_sel_hi:[1,0] neg_lo:[0,1]
	v_pk_add_f32 v[184:185], v[162:163], v[170:171]
	v_pk_add_f32 v[162:163], v[162:163], v[170:171] neg_lo:[0,1] neg_hi:[0,1]
	v_pk_fma_f32 v[4:5], v[52:53], v[10:11], v[2:3] op_sel_hi:[0,1,1]
	v_pk_mul_f32 v[170:171], v[162:163], s[36:37]
	v_pk_mul_f32 v[8:9], v[54:55], v[4:5] op_sel:[0,1] op_sel_hi:[1,0]
	v_pk_fma_f32 v[162:163], v[162:163], s[78:79], v[170:171] op_sel:[0,0,1] op_sel_hi:[1,0,0]
	v_pk_add_f32 v[170:171], v[164:165], v[172:173]
	v_pk_add_f32 v[172:173], v[164:165], v[172:173] neg_lo:[0,1] neg_hi:[0,1]
	v_pk_mul_f32 v[14:15], v[34:35], v[4:5] op_sel:[0,1] op_sel_hi:[1,0]
	v_pk_add_f32 v[164:165], v[166:167], v[174:175]
	v_pk_add_f32 v[166:167], v[166:167], v[174:175] neg_lo:[0,1] neg_hi:[0,1]
	v_pk_mul_f32 v[32:33], v[54:55], v[10:11] op_sel:[0,1] op_sel_hi:[1,0]
	v_pk_mul_f32 v[174:175], v[166:167], s[36:37]
	v_pk_mul_f32 v[40:41], v[34:35], v[10:11] op_sel:[0,1] op_sel_hi:[1,0]
	v_pk_fma_f32 v[166:167], v[166:167], s[78:79], v[174:175] op_sel:[0,0,1] op_sel_hi:[1,0,0] neg_lo:[1,0,0] neg_hi:[1,0,0]
	v_pk_add_f32 v[174:175], v[190:191], v[194:195]
	v_pk_add_f32 v[190:191], v[190:191], v[194:195] neg_lo:[0,1] neg_hi:[0,1]
	v_pk_add_f32 v[194:195], v[192:193], v[148:149]
	v_pk_add_f32 v[192:193], v[192:193], v[148:149] neg_lo:[0,1] neg_hi:[0,1]
	v_pk_mul_f32 v[62:63], v[54:55], v[20:21] op_sel:[0,1] op_sel_hi:[1,0]
	v_pk_add_f32 v[148:149], v[152:153], v[156:157] op_sel:[0,1] op_sel_hi:[1,0] neg_hi:[0,1]
	v_pk_add_f32 v[152:153], v[152:153], v[156:157] op_sel:[0,1] op_sel_hi:[1,0] neg_lo:[0,1]
	v_pk_add_f32 v[156:157], v[140:141], v[150:151]
	v_pk_add_f32 v[150:151], v[140:141], v[150:151] neg_lo:[0,1] neg_hi:[0,1]
	v_pk_mul_f32 v[66:67], v[34:35], v[20:21] op_sel:[0,1] op_sel_hi:[1,0]
	v_pk_add_f32 v[140:141], v[158:159], v[142:143]
	v_pk_add_f32 v[142:143], v[158:159], v[142:143] neg_lo:[0,1] neg_hi:[0,1]
	v_pk_add_f32 v[158:159], v[154:155], v[132:133]
	v_pk_add_f32 v[154:155], v[154:155], v[132:133] neg_lo:[0,1] neg_hi:[0,1]
	v_pk_mul_f32 v[78:79], v[54:55], v[26:27] op_sel:[0,1] op_sel_hi:[1,0]
	v_pk_add_f32 v[132:133], v[144:145], v[136:137] op_sel:[0,1] op_sel_hi:[1,0] neg_hi:[0,1]
	v_pk_add_f32 v[136:137], v[144:145], v[136:137] op_sel:[0,1] op_sel_hi:[1,0] neg_lo:[0,1]
	v_pk_add_f32 v[144:145], v[134:135], v[130:131]
	v_pk_add_f32 v[134:135], v[134:135], v[130:131] neg_lo:[0,1] neg_hi:[0,1]
	v_pk_mul_f32 v[82:83], v[34:35], v[26:27] op_sel:[0,1] op_sel_hi:[1,0]
	v_pk_add_f32 v[130:131], v[138:139], v[176:177]
	v_pk_add_f32 v[138:139], v[138:139], v[176:177] neg_lo:[0,1] neg_hi:[0,1]
	v_pk_add_f32 v[176:177], v[182:183], v[178:179]
	v_pk_add_f32 v[182:183], v[182:183], v[178:179] neg_lo:[0,1] neg_hi:[0,1]
	v_pk_mul_f32 v[92:93], v[54:55], v[36:37] op_sel:[0,1] op_sel_hi:[1,0]
	v_pk_add_f32 v[178:179], v[160:161], v[186:187] op_sel:[0,1] op_sel_hi:[1,0] neg_hi:[0,1]
	v_pk_add_f32 v[160:161], v[160:161], v[186:187] op_sel:[0,1] op_sel_hi:[1,0] neg_lo:[0,1]
	v_pk_add_f32 v[186:187], v[168:169], v[180:181]
	v_pk_add_f32 v[180:181], v[168:169], v[180:181] neg_lo:[0,1] neg_hi:[0,1]
	v_pk_mul_f32 v[96:97], v[34:35], v[36:37] op_sel:[0,1] op_sel_hi:[1,0]
	v_pk_add_f32 v[168:169], v[188:189], v[170:171]
	v_pk_add_f32 v[170:171], v[188:189], v[170:171] neg_lo:[0,1] neg_hi:[0,1]
	v_pk_add_f32 v[188:189], v[184:185], v[164:165]
	v_pk_add_f32 v[184:185], v[184:185], v[164:165] neg_lo:[0,1] neg_hi:[0,1]
	v_pk_mul_f32 v[106:107], v[54:55], v[48:49] op_sel:[0,1] op_sel_hi:[1,0]
	v_pk_add_f32 v[164:165], v[128:129], v[172:173] op_sel:[0,1] op_sel_hi:[1,0] neg_hi:[0,1]
	v_pk_add_f32 v[128:129], v[128:129], v[172:173] op_sel:[0,1] op_sel_hi:[1,0] neg_lo:[0,1]
	v_pk_add_f32 v[172:173], v[162:163], v[166:167]
	v_pk_add_f32 v[166:167], v[162:163], v[166:167] neg_lo:[0,1] neg_hi:[0,1]
	v_pk_mul_f32 v[110:111], v[34:35], v[48:49] op_sel:[0,1] op_sel_hi:[1,0]
	v_pk_add_f32 v[162:163], v[174:175], v[194:195]
	v_pk_add_f32 v[174:175], v[174:175], v[194:195] neg_lo:[0,1] neg_hi:[0,1]
	v_pk_add_f32 v[194:195], v[190:191], v[192:193] op_sel:[0,1] op_sel_hi:[1,0] neg_hi:[0,1]
	v_pk_add_f32 v[190:191], v[190:191], v[192:193] op_sel:[0,1] op_sel_hi:[1,0] neg_lo:[0,1]
	v_pk_add_f32 v[192:193], v[148:149], v[156:157]
	v_pk_add_f32 v[148:149], v[148:149], v[156:157] neg_lo:[0,1] neg_hi:[0,1]
	v_pk_add_f32 v[156:157], v[152:153], v[150:151] op_sel:[0,1] op_sel_hi:[1,0] neg_hi:[0,1]
	v_pk_add_f32 v[150:151], v[152:153], v[150:151] op_sel:[0,1] op_sel_hi:[1,0] neg_lo:[0,1]
	v_pk_add_f32 v[152:153], v[140:141], v[158:159]
	v_pk_add_f32 v[140:141], v[140:141], v[158:159] neg_lo:[0,1] neg_hi:[0,1]
	v_pk_add_f32 v[158:159], v[142:143], v[154:155] op_sel:[0,1] op_sel_hi:[1,0] neg_hi:[0,1]
	v_pk_add_f32 v[142:143], v[142:143], v[154:155] op_sel:[0,1] op_sel_hi:[1,0] neg_lo:[0,1]
	v_pk_add_f32 v[154:155], v[132:133], v[144:145]
	v_pk_add_f32 v[132:133], v[132:133], v[144:145] neg_lo:[0,1] neg_hi:[0,1]
	v_pk_add_f32 v[144:145], v[136:137], v[134:135] op_sel:[0,1] op_sel_hi:[1,0] neg_hi:[0,1]
	v_pk_add_f32 v[134:135], v[136:137], v[134:135] op_sel:[0,1] op_sel_hi:[1,0] neg_lo:[0,1]
	v_pk_add_f32 v[136:137], v[130:131], v[176:177]
	v_pk_mul_f32 v[120:121], v[54:55], v[52:53] op_sel:[0,1] op_sel_hi:[1,0]
	v_pk_mul_f32 v[124:125], v[34:35], v[52:53] op_sel:[0,1] op_sel_hi:[1,0]
	v_pk_mul_f32 v[34:35], v[34:35], v[136:137] op_sel:[0,1] op_sel_hi:[1,0]
	v_pk_mul_f32 v[72:73], v[46:47], 1.0 op_sel:[1,0] op_sel_hi:[1,0] neg_lo:[1,0]
	v_pk_fma_f32 v[8:9], v[44:45], v[4:5], v[8:9] op_sel_hi:[0,1,1]
	v_pk_fma_f32 v[14:15], v[30:31], v[4:5], v[14:15] op_sel_hi:[0,1,1]
	v_xor_b32_e32 v22, 0x80000000, v5
	v_pk_fma_f32 v[32:33], v[44:45], v[10:11], v[32:33] op_sel_hi:[0,1,1]
	v_pk_fma_f32 v[40:41], v[30:31], v[10:11], v[40:41] op_sel_hi:[0,1,1]
	v_pk_fma_f32 v[62:63], v[44:45], v[20:21], v[62:63] op_sel_hi:[0,1,1]
	v_pk_fma_f32 v[66:67], v[30:31], v[20:21], v[66:67] op_sel_hi:[0,1,1]
	v_pk_fma_f32 v[78:79], v[44:45], v[26:27], v[78:79] op_sel_hi:[0,1,1]
	v_pk_fma_f32 v[82:83], v[30:31], v[26:27], v[82:83] op_sel_hi:[0,1,1]
	v_pk_fma_f32 v[92:93], v[44:45], v[36:37], v[92:93] op_sel_hi:[0,1,1]
	v_pk_fma_f32 v[96:97], v[30:31], v[36:37], v[96:97] op_sel_hi:[0,1,1]
	v_pk_fma_f32 v[106:107], v[44:45], v[48:49], v[106:107] op_sel_hi:[0,1,1]
	v_pk_fma_f32 v[110:111], v[30:31], v[48:49], v[110:111] op_sel_hi:[0,1,1]
	v_pk_fma_f32 v[120:121], v[44:45], v[52:53], v[120:121] op_sel_hi:[0,1,1]
	v_pk_fma_f32 v[124:125], v[30:31], v[52:53], v[124:125] op_sel_hi:[0,1,1]
	v_mov_b32_e32 v23, v5
	v_pk_add_f32 v[130:131], v[130:131], v[176:177] neg_lo:[0,1] neg_hi:[0,1]
	v_pk_add_f32 v[176:177], v[138:139], v[182:183] op_sel:[0,1] op_sel_hi:[1,0] neg_hi:[0,1]
	v_pk_add_f32 v[138:139], v[138:139], v[182:183] op_sel:[0,1] op_sel_hi:[1,0] neg_lo:[0,1]
	v_pk_add_f32 v[182:183], v[178:179], v[186:187]
	v_pk_add_f32 v[178:179], v[178:179], v[186:187] neg_lo:[0,1] neg_hi:[0,1]
	v_pk_add_f32 v[186:187], v[160:161], v[180:181] op_sel:[0,1] op_sel_hi:[1,0] neg_hi:[0,1]
	v_pk_add_f32 v[160:161], v[160:161], v[180:181] op_sel:[0,1] op_sel_hi:[1,0] neg_lo:[0,1]
	v_pk_add_f32 v[180:181], v[168:169], v[188:189]
	v_pk_fma_f32 v[30:31], v[30:31], v[136:137], v[34:35] op_sel_hi:[0,1,1]
	v_pk_mul_f32 v[34:35], v[54:55], v[152:153] op_sel:[0,1] op_sel_hi:[1,0]
	v_pk_mul_f32 v[2:3], v[72:73], v[4:5] op_sel:[0,1] op_sel_hi:[1,0]
	v_xor_b32_e32 v12, 0x80000000, v9
	v_pk_mul_f32 v[24:25], v[72:73], v[10:11] op_sel:[0,1] op_sel_hi:[1,0]
	v_xor_b32_e32 v38, 0x80000000, v33
	v_xor_b32_e32 v50, 0x80000000, v11
	v_pk_mul_f32 v[56:57], v[72:73], v[20:21] op_sel:[0,1] op_sel_hi:[1,0]
	v_xor_b32_e32 v64, 0x80000000, v63
	v_xor_b32_e32 v70, 0x80000000, v21
	v_pk_mul_f32 v[74:75], v[72:73], v[26:27] op_sel:[0,1] op_sel_hi:[1,0]
	v_xor_b32_e32 v80, 0x80000000, v79
	v_xor_b32_e32 v86, 0x80000000, v27
	v_pk_mul_f32 v[88:89], v[72:73], v[36:37] op_sel:[0,1] op_sel_hi:[1,0]
	v_xor_b32_e32 v94, 0x80000000, v93
	v_xor_b32_e32 v100, 0x80000000, v37
	v_pk_mul_f32 v[102:103], v[72:73], v[48:49] op_sel:[0,1] op_sel_hi:[1,0]
	v_pk_mul_f32 v[108:109], v[106:107], 1.0 op_sel:[1,0] op_sel_hi:[1,0] neg_lo:[1,0]
	v_pk_mul_f32 v[114:115], v[48:49], 1.0 op_sel:[1,0] op_sel_hi:[1,0] neg_lo:[1,0]
	v_pk_mul_f32 v[116:117], v[52:53], v[72:73] op_sel:[1,0] op_sel_hi:[0,1]
	v_pk_mul_f32 v[122:123], v[120:121], 1.0 op_sel:[1,0] op_sel_hi:[1,0] neg_lo:[1,0]
	v_mov_b32_e32 v101, v37
	v_mov_b32_e32 v95, v93
	v_mov_b32_e32 v87, v27
	v_mov_b32_e32 v81, v79
	v_mov_b32_e32 v71, v21
	v_mov_b32_e32 v65, v63
	v_mov_b32_e32 v51, v11
	v_mov_b32_e32 v39, v33
	v_mov_b32_e32 v13, v9
	v_pk_fma_f32 v[34:35], v[44:45], v[152:153], v[34:35] op_sel_hi:[0,1,1]
	v_pk_mul_f32 v[44:45], v[72:73], v[180:181] op_sel:[0,1] op_sel_hi:[1,0]
	v_pk_mul_f32 v[22:23], v[150:151], v[22:23] op_sel:[1,0] op_sel_hi:[0,1]
	v_pk_fma_f32 v[2:3], v[46:47], v[4:5], v[2:3] op_sel_hi:[0,1,1]
	v_pk_fma_f32 v[24:25], v[46:47], v[10:11], v[24:25] op_sel_hi:[0,1,1]
	v_pk_fma_f32 v[56:57], v[46:47], v[20:21], v[56:57] op_sel_hi:[0,1,1]
	v_pk_fma_f32 v[74:75], v[46:47], v[26:27], v[74:75] op_sel_hi:[0,1,1]
	v_pk_mul_f32 v[84:85], v[82:83], 1.0 op_sel:[1,0] op_sel_hi:[1,0] neg_lo:[1,0]
	v_pk_fma_f32 v[88:89], v[46:47], v[36:37], v[88:89] op_sel_hi:[0,1,1]
	v_pk_fma_f32 v[102:103], v[46:47], v[48:49], v[102:103] op_sel_hi:[0,1,1]
	v_pk_fma_f32 v[116:117], v[52:53], v[46:47], v[116:117] op_sel_hi:[1,0,1]
	v_pk_fma_f32 v[44:45], v[46:47], v[180:181], v[44:45] op_sel_hi:[0,1,1]
	v_pk_mul_f32 v[46:47], v[58:59], v[192:193] op_sel:[0,1] op_sel_hi:[1,0]
	v_pk_mul_f32 v[54:55], v[122:123], v[154:155] op_sel:[0,1] op_sel_hi:[1,0]
	v_pk_mul_f32 v[72:73], v[114:115], v[194:195] op_sel:[0,1] op_sel_hi:[1,0]
	v_pk_mul_f32 v[108:109], v[108:109], v[158:159] op_sel:[0,1] op_sel_hi:[1,0]
	v_pk_mul_f32 v[100:101], v[100:101], v[156:157] op_sel:[0,1] op_sel_hi:[1,0]
	v_pk_mul_f32 v[94:95], v[94:95], v[144:145] op_sel:[0,1] op_sel_hi:[1,0]
	v_pk_mul_f32 v[86:87], v[174:175], v[86:87] op_sel:[1,0] op_sel_hi:[0,1]
	v_pk_mul_f32 v[80:81], v[140:141], v[80:81] op_sel:[1,0] op_sel_hi:[0,1]
	v_pk_mul_f32 v[70:71], v[148:149], v[70:71] op_sel:[1,0] op_sel_hi:[0,1]
	v_pk_mul_f32 v[64:65], v[132:133], v[64:65] op_sel:[1,0] op_sel_hi:[0,1]
	v_pk_mul_f32 v[50:51], v[190:191], v[50:51] op_sel:[1,0] op_sel_hi:[0,1]
	v_pk_mul_f32 v[38:39], v[142:143], v[38:39] op_sel:[1,0] op_sel_hi:[0,1]
	v_pk_fma_f32 v[4:5], v[150:151], v[4:5], v[22:23] op_sel_hi:[1,0,1]
	v_pk_mul_f32 v[12:13], v[134:135], v[12:13] op_sel:[1,0] op_sel_hi:[0,1]
	v_pk_mul_f32 v[112:113], v[110:111], 1.0 op_sel:[1,0] op_sel_hi:[1,0] neg_lo:[1,0]
	v_pk_fma_f32 v[46:47], v[52:53], v[192:193], v[46:47] op_sel_hi:[0,1,1]
	v_pk_fma_f32 v[54:55], v[120:121], v[154:155], v[54:55] op_sel_hi:[0,1,1]
	v_pk_fma_f32 v[48:49], v[48:49], v[194:195], v[72:73] op_sel_hi:[0,1,1]
	v_pk_fma_f32 v[106:107], v[106:107], v[158:159], v[108:109] op_sel_hi:[0,1,1]
	v_pk_fma_f32 v[36:37], v[36:37], v[156:157], v[100:101] op_sel_hi:[0,1,1]
	v_pk_fma_f32 v[92:93], v[92:93], v[144:145], v[94:95] op_sel_hi:[0,1,1]
	v_pk_fma_f32 v[26:27], v[174:175], v[26:27], v[86:87] op_sel_hi:[1,0,1]
	v_pk_mul_f32 v[84:85], v[130:131], v[84:85] op_sel:[1,0] op_sel_hi:[0,1]
	v_pk_fma_f32 v[78:79], v[140:141], v[78:79], v[80:81] op_sel_hi:[1,0,1]
	v_pk_fma_f32 v[20:21], v[148:149], v[20:21], v[70:71] op_sel_hi:[1,0,1]
	v_pk_fma_f32 v[62:63], v[132:133], v[62:63], v[64:65] op_sel_hi:[1,0,1]
	v_pk_fma_f32 v[10:11], v[190:191], v[10:11], v[50:51] op_sel_hi:[1,0,1]
	v_pk_fma_f32 v[32:33], v[142:143], v[32:33], v[38:39] op_sel_hi:[1,0,1]
	v_pk_fma_f32 v[8:9], v[134:135], v[8:9], v[12:13] op_sel_hi:[1,0,1]
	ds_write_b64 v18, v[162:163]
	ds_write_b64 v18, v[26:27] offset:4224
	ds_write_b64 v18, v[48:49] offset:8448
	ds_write_b64 v18, v[10:11] offset:12672
	ds_write_b64 v18, v[46:47] offset:16896
	ds_write_b64 v18, v[20:21] offset:21120
	ds_write_b64 v18, v[36:37] offset:25344
	ds_write_b64 v18, v[4:5] offset:29568
	ds_write_b64 v18, v[34:35] offset:33792
	ds_write_b64 v18, v[78:79] offset:38016
	ds_write_b64 v18, v[106:107] offset:42240
	ds_write_b64 v18, v[32:33] offset:46464
	ds_write_b64 v18, v[54:55] offset:50688
	ds_write_b64 v18, v[62:63] offset:54912
	ds_write_b64 v18, v[92:93] offset:59136
	ds_write_b64 v18, v[8:9] offset:63360
	v_add_u32_e32 v4, 0x10800, v18
	v_pk_mul_f32 v[42:43], v[40:41], 1.0 op_sel:[1,0] op_sel_hi:[1,0] neg_lo:[1,0]
	v_pk_mul_f32 v[72:73], v[112:113], v[176:177] op_sel:[0,1] op_sel_hi:[1,0]
	v_pk_fma_f32 v[82:83], v[130:131], v[82:83], v[84:85] op_sel_hi:[1,0,1]
	ds_write_b64 v4, v[30:31]
	v_add_u32_e32 v4, 0x11880, v18
	v_pk_mul_f32 v[126:127], v[124:125], 1.0 op_sel:[1,0] op_sel_hi:[1,0] neg_lo:[1,0]
	v_pk_fma_f32 v[72:73], v[110:111], v[176:177], v[72:73] op_sel_hi:[0,1,1]
	v_pk_mul_f32 v[42:43], v[138:139], v[42:43] op_sel:[1,0] op_sel_hi:[0,1]
	ds_write_b64 v4, v[82:83]
	v_add_u32_e32 v4, 0x12900, v18
	v_pk_mul_f32 v[68:69], v[66:67], 1.0 op_sel:[1,0] op_sel_hi:[1,0] neg_lo:[1,0]
	v_pk_mul_f32 v[52:53], v[126:127], v[182:183] op_sel:[0,1] op_sel_hi:[1,0]
	v_pk_fma_f32 v[40:41], v[138:139], v[40:41], v[42:43] op_sel_hi:[1,0,1]
	ds_write_b64 v4, v[72:73]
	v_add_u32_e32 v4, 0x13980, v18
	v_pk_mul_f32 v[98:99], v[96:97], 1.0 op_sel:[1,0] op_sel_hi:[1,0] neg_lo:[1,0]
	v_pk_fma_f32 v[52:53], v[124:125], v[182:183], v[52:53] op_sel_hi:[0,1,1]
	v_pk_mul_f32 v[68:69], v[178:179], v[68:69] op_sel:[1,0] op_sel_hi:[0,1]
	ds_write_b64 v4, v[40:41]
	v_add_u32_e32 v4, 0x14a00, v18
	v_pk_mul_f32 v[16:17], v[14:15], 1.0 op_sel:[1,0] op_sel_hi:[1,0] neg_lo:[1,0]
	v_pk_mul_f32 v[98:99], v[98:99], v[186:187] op_sel:[0,1] op_sel_hi:[1,0]
	v_pk_fma_f32 v[66:67], v[178:179], v[66:67], v[68:69] op_sel_hi:[1,0,1]
	ds_write_b64 v4, v[52:53]
	v_add_u32_e32 v4, 0x15a80, v18
	v_pk_fma_f32 v[96:97], v[96:97], v[186:187], v[98:99] op_sel_hi:[0,1,1]
	v_pk_mul_f32 v[16:17], v[160:161], v[16:17] op_sel:[1,0] op_sel_hi:[0,1]
	ds_write_b64 v4, v[66:67]
	v_add_u32_e32 v4, 0x16b00, v18
	v_pk_mul_f32 v[76:77], v[74:75], 1.0 op_sel:[1,0] op_sel_hi:[1,0] neg_lo:[1,0]
	v_pk_add_f32 v[168:169], v[168:169], v[188:189] neg_lo:[0,1] neg_hi:[0,1]
	v_pk_fma_f32 v[14:15], v[160:161], v[14:15], v[16:17] op_sel_hi:[1,0,1]
	ds_write_b64 v4, v[96:97]
	v_add_u32_e32 v4, 0x17b80, v18
	v_pk_mul_f32 v[104:105], v[102:103], 1.0 op_sel:[1,0] op_sel_hi:[1,0] neg_lo:[1,0]
	v_pk_add_f32 v[188:189], v[170:171], v[184:185] op_sel:[0,1] op_sel_hi:[1,0] neg_hi:[0,1]
	v_pk_mul_f32 v[76:77], v[168:169], v[76:77] op_sel:[1,0] op_sel_hi:[0,1]
	ds_write_b64 v4, v[14:15]
	v_add_u32_e32 v4, 0x18c00, v18
	v_pk_mul_f32 v[28:29], v[24:25], 1.0 op_sel:[1,0] op_sel_hi:[1,0] neg_lo:[1,0]
	v_pk_add_f32 v[170:171], v[170:171], v[184:185] op_sel:[0,1] op_sel_hi:[1,0] neg_lo:[0,1]
	v_pk_mul_f32 v[104:105], v[104:105], v[188:189] op_sel:[0,1] op_sel_hi:[1,0]
	v_pk_fma_f32 v[74:75], v[168:169], v[74:75], v[76:77] op_sel_hi:[1,0,1]
	ds_write_b64 v4, v[44:45]
	v_add_u32_e32 v4, 0x19c80, v18
	v_pk_mul_f32 v[118:119], v[116:117], 1.0 op_sel:[1,0] op_sel_hi:[1,0] neg_lo:[1,0]
	v_pk_add_f32 v[184:185], v[164:165], v[172:173]
	v_pk_fma_f32 v[102:103], v[102:103], v[188:189], v[104:105] op_sel_hi:[0,1,1]
	v_pk_mul_f32 v[28:29], v[170:171], v[28:29] op_sel:[1,0] op_sel_hi:[0,1]
	ds_write_b64 v4, v[74:75]
	v_add_u32_e32 v4, 0x1ad00, v18
	v_pk_mul_f32 v[60:61], v[56:57], 1.0 op_sel:[1,0] op_sel_hi:[1,0] neg_lo:[1,0]
	v_pk_add_f32 v[164:165], v[164:165], v[172:173] neg_lo:[0,1] neg_hi:[0,1]
	v_pk_mul_f32 v[58:59], v[118:119], v[184:185] op_sel:[0,1] op_sel_hi:[1,0]
	v_pk_fma_f32 v[24:25], v[170:171], v[24:25], v[28:29] op_sel_hi:[1,0,1]
	ds_write_b64 v4, v[102:103]
	v_add_u32_e32 v4, 0x1bd80, v18
	v_pk_mul_f32 v[90:91], v[88:89], 1.0 op_sel:[1,0] op_sel_hi:[1,0] neg_lo:[1,0]
	v_pk_add_f32 v[172:173], v[128:129], v[166:167] op_sel:[0,1] op_sel_hi:[1,0] neg_hi:[0,1]
	v_pk_fma_f32 v[58:59], v[116:117], v[184:185], v[58:59] op_sel_hi:[0,1,1]
	v_pk_mul_f32 v[60:61], v[164:165], v[60:61] op_sel:[1,0] op_sel_hi:[0,1]
	ds_write_b64 v4, v[24:25]
	v_add_u32_e32 v4, 0x1ce00, v18
	v_pk_mul_f32 v[6:7], v[2:3], 1.0 op_sel:[1,0] op_sel_hi:[1,0] neg_lo:[1,0]
	v_pk_add_f32 v[128:129], v[128:129], v[166:167] op_sel:[0,1] op_sel_hi:[1,0] neg_lo:[0,1]
	v_pk_mul_f32 v[90:91], v[90:91], v[172:173] op_sel:[0,1] op_sel_hi:[1,0]
	v_pk_fma_f32 v[56:57], v[164:165], v[56:57], v[60:61] op_sel_hi:[1,0,1]
	ds_write_b64 v4, v[58:59]
	v_add_u32_e32 v4, 0x1de80, v18
	v_pk_fma_f32 v[88:89], v[88:89], v[172:173], v[90:91] op_sel_hi:[0,1,1]
	v_pk_mul_f32 v[6:7], v[128:129], v[6:7] op_sel:[1,0] op_sel_hi:[0,1]
	ds_write_b64 v4, v[56:57]
	v_add_u32_e32 v4, 0x1ef00, v18
	v_pk_fma_f32 v[2:3], v[128:129], v[2:3], v[6:7] op_sel_hi:[1,0,1]
	ds_write_b64 v4, v[88:89]
	v_add_u32_e32 v4, 0x1ff80, v18
	ds_write_b64 v4, v[2:3]
	v_mov_b32_e32 v2, v210
	s_waitcnt lgkmcnt(0)
	s_barrier
	s_ashr_i32 s77, s76, 31
	v_and_b32_e32 v3, 15, v2
	v_lshlrev_b32_e32 v2, 5, v2
	v_and_b32_e32 v4, 0xfffffe00, v2
	v_lshl_add_u32 v5, v4, 3, 0
	v_lshlrev_b32_e32 v6, 3, v3
	v_ashrrev_i32_e32 v7, 2, v4
	v_add3_u32 v18, v5, v6, v7
	v_add_u32_e32 v196, 0x800, v18
	ds_read2_b64 v[128:131], v18 offset1:16
	ds_read2_b64 v[132:135], v18 offset0:33 offset1:49
	ds_read2_b64 v[136:139], v18 offset0:66 offset1:82
	ds_read2_b64 v[140:143], v18 offset0:99 offset1:115
	ds_read2_b64 v[148:151], v18 offset0:132 offset1:148
	ds_read2_b64 v[152:155], v18 offset0:165 offset1:181
	ds_read2_b64 v[156:159], v18 offset0:198 offset1:214
	ds_read2_b64 v[160:163], v18 offset0:231 offset1:247
	ds_read2_b64 v[164:167], v196 offset0:8 offset1:24
	ds_read2_b64 v[168:171], v196 offset0:41 offset1:57
	ds_read2_b64 v[172:175], v196 offset0:74 offset1:90
	ds_read2_b64 v[176:179], v196 offset0:107 offset1:123
	ds_read2_b64 v[180:183], v196 offset0:140 offset1:156
	ds_read2_b64 v[184:187], v196 offset0:173 offset1:189
	ds_read2_b64 v[188:191], v196 offset0:206 offset1:222
	ds_read2_b64 v[192:195], v196 offset0:239 offset1:255
	s_waitcnt lgkmcnt(7)
	v_pk_add_f32 v[144:145], v[128:129], v[164:165]
	v_pk_add_f32 v[128:129], v[128:129], v[164:165] neg_lo:[0,1] neg_hi:[0,1]
	v_pk_add_f32 v[164:165], v[130:131], v[166:167]
	v_pk_add_f32 v[130:131], v[130:131], v[166:167] neg_lo:[0,1] neg_hi:[0,1]
	v_cvt_f32_ubyte0_e32 v2, v3
	v_pk_mul_f32 v[166:167], v[130:131], s[10:11]
	v_mul_f32_e32 v3, 0x3b000000, v2
	v_pk_fma_f32 v[130:131], v[130:131], s[8:9], v[166:167] op_sel:[0,0,1] op_sel_hi:[1,0,0]
	s_waitcnt lgkmcnt(6)
	v_pk_add_f32 v[166:167], v[132:133], v[168:169]
	v_pk_add_f32 v[132:133], v[132:133], v[168:169] neg_lo:[0,1] neg_hi:[0,1]
	v_sin_f32_e32 v2, v3
	v_pk_mul_f32 v[168:169], v[132:133], s[18:19]
	v_cos_f32_e32 v4, v3
	v_pk_fma_f32 v[132:133], v[132:133], s[16:17], v[168:169] op_sel:[0,0,1] op_sel_hi:[1,0,0]
	v_pk_add_f32 v[168:169], v[134:135], v[170:171]
	v_pk_add_f32 v[134:135], v[134:135], v[170:171] neg_lo:[0,1] neg_hi:[0,1]
	v_xor_b32_e32 v5, 0x80000000, v2
	v_pk_mul_f32 v[170:171], v[134:135], s[26:27]
	v_mov_b32_e32 v3, v5
	v_pk_fma_f32 v[134:135], v[134:135], s[24:25], v[170:171] op_sel:[0,0,1] op_sel_hi:[1,0,0]
	s_waitcnt lgkmcnt(5)
	v_pk_add_f32 v[170:171], v[136:137], v[172:173]
	v_pk_add_f32 v[136:137], v[136:137], v[172:173] neg_lo:[0,1] neg_hi:[0,1]
	v_pk_mul_f32 v[6:7], v[4:5], v[2:3] op_sel:[1,0] op_sel_hi:[0,1]
	v_pk_mul_f32 v[172:173], v[136:137], s[36:37]
	v_pk_fma_f32 v[6:7], v[4:5], v[4:5], v[6:7] op_sel_hi:[1,0,1]
	v_pk_fma_f32 v[136:137], v[136:137], s[78:79], v[172:173] op_sel:[0,0,1] op_sel_hi:[1,0,0]
	v_pk_add_f32 v[172:173], v[138:139], v[174:175]
	v_pk_add_f32 v[138:139], v[138:139], v[174:175] neg_lo:[0,1] neg_hi:[0,1]
	v_pk_mul_f32 v[12:13], v[6:7], 1.0 op_sel:[1,0] op_sel_hi:[1,0] neg_lo:[1,0]
	v_pk_mul_f32 v[174:175], v[138:139], s[38:39]
	s_nop 0
	v_pk_fma_f32 v[138:139], v[138:139], s[0:1], v[174:175] op_sel:[0,0,1] op_sel_hi:[1,0,0]
	s_waitcnt lgkmcnt(4)
	v_pk_add_f32 v[174:175], v[140:141], v[176:177]
	v_pk_add_f32 v[140:141], v[140:141], v[176:177] neg_lo:[0,1] neg_hi:[0,1]
	v_pk_mul_f32 v[10:11], v[6:7], v[12:13] op_sel:[1,0] op_sel_hi:[0,1]
	v_pk_mul_f32 v[176:177], v[140:141], s[40:41]
	v_pk_fma_f32 v[10:11], v[6:7], v[6:7], v[10:11] op_sel_hi:[1,0,1]
	v_pk_fma_f32 v[140:141], v[140:141], s[80:81], v[176:177] op_sel:[0,0,1] op_sel_hi:[1,0,0]
	v_pk_add_f32 v[176:177], v[142:143], v[178:179]
	v_pk_add_f32 v[142:143], v[142:143], v[178:179] neg_lo:[0,1] neg_hi:[0,1]
	v_pk_mul_f32 v[14:15], v[10:11], 1.0 op_sel:[1,0] op_sel_hi:[1,0] neg_lo:[1,0]
	v_pk_mul_f32 v[178:179], v[142:143], s[42:43]
	s_nop 0
	v_pk_fma_f32 v[142:143], v[142:143], s[74:75], v[178:179] op_sel:[0,0,1] op_sel_hi:[1,0,0]
	s_waitcnt lgkmcnt(3)
	v_pk_add_f32 v[178:179], v[148:149], v[180:181]
	v_pk_add_f32 v[180:181], v[148:149], v[180:181] neg_lo:[0,1] neg_hi:[0,1]
	v_pk_mul_f32 v[28:29], v[10:11], v[14:15] op_sel:[1,0] op_sel_hi:[0,1]
	v_pk_add_f32 v[148:149], v[150:151], v[182:183]
	v_pk_add_f32 v[150:151], v[150:151], v[182:183] neg_lo:[0,1] neg_hi:[0,1]
	v_pk_fma_f32 v[28:29], v[10:11], v[10:11], v[28:29] op_sel_hi:[1,0,1]
	v_pk_mul_f32 v[182:183], v[150:151], s[42:43]
	v_pk_mul_f32 v[44:45], v[14:15], v[28:29] op_sel:[0,1] op_sel_hi:[1,0]
	v_pk_fma_f32 v[150:151], v[150:151], s[74:75], v[182:183] op_sel:[0,0,1] op_sel_hi:[1,0,0] neg_lo:[1,0,0] neg_hi:[1,0,0]
	s_waitcnt lgkmcnt(2)
	v_pk_add_f32 v[182:183], v[152:153], v[184:185]
	v_pk_add_f32 v[152:153], v[152:153], v[184:185] neg_lo:[0,1] neg_hi:[0,1]
	v_pk_fma_f32 v[44:45], v[10:11], v[28:29], v[44:45] op_sel_hi:[0,1,1]
	v_pk_mul_f32 v[184:185], v[152:153], s[40:41]
	v_pk_mul_f32 v[60:61], v[14:15], v[44:45] op_sel:[0,1] op_sel_hi:[1,0]
	v_pk_fma_f32 v[152:153], v[152:153], s[80:81], v[184:185] op_sel:[0,0,1] op_sel_hi:[1,0,0] neg_lo:[1,0,0] neg_hi:[1,0,0]
	v_pk_add_f32 v[184:185], v[154:155], v[186:187]
	v_pk_add_f32 v[154:155], v[154:155], v[186:187] neg_lo:[0,1] neg_hi:[0,1]
	v_pk_fma_f32 v[60:61], v[10:11], v[44:45], v[60:61] op_sel_hi:[0,1,1]
	v_pk_mul_f32 v[186:187], v[154:155], s[38:39]
	v_pk_mul_f32 v[76:77], v[14:15], v[60:61] op_sel:[0,1] op_sel_hi:[1,0]
	v_pk_fma_f32 v[154:155], v[154:155], s[0:1], v[186:187] op_sel:[0,0,1] op_sel_hi:[1,0,0] neg_lo:[1,0,0] neg_hi:[1,0,0]
	s_waitcnt lgkmcnt(1)
	v_pk_add_f32 v[186:187], v[156:157], v[188:189]
	v_pk_add_f32 v[156:157], v[156:157], v[188:189] neg_lo:[0,1] neg_hi:[0,1]
	v_pk_fma_f32 v[76:77], v[10:11], v[60:61], v[76:77] op_sel_hi:[0,1,1]
	v_pk_mul_f32 v[188:189], v[156:157], s[36:37]
	v_pk_mul_f32 v[92:93], v[14:15], v[76:77] op_sel:[0,1] op_sel_hi:[1,0]
	v_pk_fma_f32 v[156:157], v[156:157], s[78:79], v[188:189] op_sel:[0,0,1] op_sel_hi:[1,0,0] neg_lo:[1,0,0] neg_hi:[1,0,0]
	v_pk_add_f32 v[188:189], v[158:159], v[190:191]
	v_pk_add_f32 v[158:159], v[158:159], v[190:191] neg_lo:[0,1] neg_hi:[0,1]
	v_pk_fma_f32 v[92:93], v[10:11], v[76:77], v[92:93] op_sel_hi:[0,1,1]
	v_pk_mul_f32 v[190:191], v[158:159], s[26:27]
	v_pk_mul_f32 v[108:109], v[14:15], v[92:93] op_sel:[0,1] op_sel_hi:[1,0]
	v_pk_fma_f32 v[158:159], v[158:159], s[24:25], v[190:191] op_sel:[0,0,1] op_sel_hi:[1,0,0] neg_lo:[1,0,0] neg_hi:[1,0,0]
	s_waitcnt lgkmcnt(0)
	v_pk_add_f32 v[190:191], v[160:161], v[192:193]
	v_pk_add_f32 v[160:161], v[160:161], v[192:193] neg_lo:[0,1] neg_hi:[0,1]
	v_pk_mul_f32 v[8:9], v[2:3], v[6:7] op_sel:[0,1] op_sel_hi:[1,0]
	v_pk_mul_f32 v[192:193], v[160:161], s[18:19]
	v_pk_fma_f32 v[108:109], v[10:11], v[92:93], v[108:109] op_sel_hi:[0,1,1]
	v_pk_fma_f32 v[160:161], v[160:161], s[16:17], v[192:193] op_sel:[0,0,1] op_sel_hi:[1,0,0] neg_lo:[1,0,0] neg_hi:[1,0,0]
	v_pk_add_f32 v[192:193], v[162:163], v[194:195]
	v_pk_add_f32 v[162:163], v[162:163], v[194:195] neg_lo:[0,1] neg_hi:[0,1]
	v_pk_fma_f32 v[8:9], v[4:5], v[6:7], v[8:9] op_sel_hi:[0,1,1]
	v_pk_mul_f32 v[194:195], v[162:163], s[10:11]
	v_pk_mul_f32 v[16:17], v[2:3], v[10:11] op_sel:[0,1] op_sel_hi:[1,0]
	v_pk_fma_f32 v[162:163], v[162:163], s[8:9], v[194:195] op_sel:[0,0,1] op_sel_hi:[1,0,0] neg_lo:[1,0,0] neg_hi:[1,0,0]
	v_pk_add_f32 v[194:195], v[144:145], v[178:179]
	v_pk_add_f32 v[144:145], v[144:145], v[178:179] neg_lo:[0,1] neg_hi:[0,1]
	v_pk_add_f32 v[178:179], v[164:165], v[148:149]
	v_pk_add_f32 v[148:149], v[164:165], v[148:149] neg_lo:[0,1] neg_hi:[0,1]
	v_pk_mul_f32 v[32:33], v[2:3], v[28:29] op_sel:[0,1] op_sel_hi:[1,0]
	v_pk_mul_f32 v[164:165], v[148:149], s[18:19]
	v_pk_mul_f32 v[48:49], v[2:3], v[44:45] op_sel:[0,1] op_sel_hi:[1,0]
	v_pk_fma_f32 v[148:149], v[148:149], s[16:17], v[164:165] op_sel:[0,0,1] op_sel_hi:[1,0,0]
	v_pk_add_f32 v[164:165], v[166:167], v[182:183]
	v_pk_add_f32 v[166:167], v[166:167], v[182:183] neg_lo:[0,1] neg_hi:[0,1]
	v_pk_mul_f32 v[64:65], v[2:3], v[60:61] op_sel:[0,1] op_sel_hi:[1,0]
	v_pk_mul_f32 v[182:183], v[166:167], s[36:37]
	v_pk_mul_f32 v[80:81], v[2:3], v[76:77] op_sel:[0,1] op_sel_hi:[1,0]
	v_pk_fma_f32 v[166:167], v[166:167], s[78:79], v[182:183] op_sel:[0,0,1] op_sel_hi:[1,0,0]
	v_pk_add_f32 v[182:183], v[168:169], v[184:185]
	v_pk_add_f32 v[168:169], v[168:169], v[184:185] neg_lo:[0,1] neg_hi:[0,1]
	v_pk_mul_f32 v[96:97], v[2:3], v[92:93] op_sel:[0,1] op_sel_hi:[1,0]
	v_pk_mul_f32 v[184:185], v[168:169], s[40:41]
	v_pk_mul_f32 v[112:113], v[2:3], v[108:109] op_sel:[0,1] op_sel_hi:[1,0]
	v_pk_fma_f32 v[168:169], v[168:169], s[80:81], v[184:185] op_sel:[0,0,1] op_sel_hi:[1,0,0]
	v_pk_add_f32 v[184:185], v[170:171], v[186:187]
	v_pk_add_f32 v[186:187], v[170:171], v[186:187] neg_lo:[0,1] neg_hi:[0,1]
	v_pk_mul_f32 v[22:23], v[8:9], 1.0 op_sel:[1,0] op_sel_hi:[1,0] neg_lo:[1,0]
	v_pk_add_f32 v[170:171], v[172:173], v[188:189]
	v_pk_add_f32 v[172:173], v[172:173], v[188:189] neg_lo:[0,1] neg_hi:[0,1]
	s_nop 0
	v_pk_mul_f32 v[188:189], v[172:173], s[40:41]
	v_pk_fma_f32 v[16:17], v[4:5], v[10:11], v[16:17] op_sel_hi:[0,1,1]
	v_pk_fma_f32 v[172:173], v[172:173], s[80:81], v[188:189] op_sel:[0,0,1] op_sel_hi:[1,0,0] neg_lo:[1,0,0] neg_hi:[1,0,0]
	v_pk_add_f32 v[188:189], v[174:175], v[190:191]
	v_pk_add_f32 v[174:175], v[174:175], v[190:191] neg_lo:[0,1] neg_hi:[0,1]
	v_pk_mul_f32 v[20:21], v[12:13], v[10:11] op_sel:[0,1] op_sel_hi:[1,0]
	v_pk_mul_f32 v[190:191], v[174:175], s[36:37]
	v_pk_fma_f32 v[32:33], v[4:5], v[28:29], v[32:33] op_sel_hi:[0,1,1]
	v_pk_fma_f32 v[174:175], v[174:175], s[78:79], v[190:191] op_sel:[0,0,1] op_sel_hi:[1,0,0] neg_lo:[1,0,0] neg_hi:[1,0,0]
	v_pk_add_f32 v[190:191], v[176:177], v[192:193]
	v_pk_add_f32 v[176:177], v[176:177], v[192:193] neg_lo:[0,1] neg_hi:[0,1]
	v_pk_mul_f32 v[36:37], v[12:13], v[28:29] op_sel:[0,1] op_sel_hi:[1,0]
	v_pk_mul_f32 v[192:193], v[176:177], s[18:19]
	v_pk_fma_f32 v[48:49], v[4:5], v[44:45], v[48:49] op_sel_hi:[0,1,1]
	v_pk_fma_f32 v[176:177], v[176:177], s[16:17], v[192:193] op_sel:[0,0,1] op_sel_hi:[1,0,0] neg_lo:[1,0,0] neg_hi:[1,0,0]
	v_pk_add_f32 v[192:193], v[128:129], v[180:181] op_sel:[0,1] op_sel_hi:[1,0] neg_hi:[0,1]
	v_pk_add_f32 v[128:129], v[128:129], v[180:181] op_sel:[0,1] op_sel_hi:[1,0] neg_lo:[0,1]
	v_pk_add_f32 v[180:181], v[130:131], v[150:151]
	v_pk_add_f32 v[130:131], v[130:131], v[150:151] neg_lo:[0,1] neg_hi:[0,1]
	v_pk_mul_f32 v[52:53], v[12:13], v[44:45] op_sel:[0,1] op_sel_hi:[1,0]
	v_pk_mul_f32 v[150:151], v[130:131], s[18:19]
	v_pk_fma_f32 v[64:65], v[4:5], v[60:61], v[64:65] op_sel_hi:[0,1,1]
	v_pk_fma_f32 v[130:131], v[130:131], s[16:17], v[150:151] op_sel:[0,0,1] op_sel_hi:[1,0,0]
	v_pk_add_f32 v[150:151], v[132:133], v[152:153]
	v_pk_add_f32 v[132:133], v[132:133], v[152:153] neg_lo:[0,1] neg_hi:[0,1]
	v_pk_mul_f32 v[68:69], v[12:13], v[60:61] op_sel:[0,1] op_sel_hi:[1,0]
	v_pk_mul_f32 v[152:153], v[132:133], s[36:37]
	v_pk_fma_f32 v[80:81], v[4:5], v[76:77], v[80:81] op_sel_hi:[0,1,1]
	v_pk_fma_f32 v[132:133], v[132:133], s[78:79], v[152:153] op_sel:[0,0,1] op_sel_hi:[1,0,0]
	v_pk_add_f32 v[152:153], v[134:135], v[154:155]
	v_pk_add_f32 v[134:135], v[134:135], v[154:155] neg_lo:[0,1] neg_hi:[0,1]
	v_pk_mul_f32 v[84:85], v[12:13], v[76:77] op_sel:[0,1] op_sel_hi:[1,0]
	v_pk_mul_f32 v[154:155], v[134:135], s[40:41]
	v_pk_fma_f32 v[96:97], v[4:5], v[92:93], v[96:97] op_sel_hi:[0,1,1]
	v_pk_fma_f32 v[134:135], v[134:135], s[80:81], v[154:155] op_sel:[0,0,1] op_sel_hi:[1,0,0]
	v_pk_add_f32 v[154:155], v[136:137], v[156:157]
	v_pk_add_f32 v[156:157], v[136:137], v[156:157] neg_lo:[0,1] neg_hi:[0,1]
	v_pk_mul_f32 v[100:101], v[12:13], v[92:93] op_sel:[0,1] op_sel_hi:[1,0]
	v_pk_add_f32 v[136:137], v[138:139], v[158:159]
	v_pk_add_f32 v[138:139], v[138:139], v[158:159] neg_lo:[0,1] neg_hi:[0,1]
	v_pk_fma_f32 v[112:113], v[4:5], v[108:109], v[112:113] op_sel_hi:[0,1,1]
	v_pk_mul_f32 v[158:159], v[138:139], s[40:41]
	v_pk_mul_f32 v[116:117], v[12:13], v[108:109] op_sel:[0,1] op_sel_hi:[1,0]
	v_pk_fma_f32 v[138:139], v[138:139], s[80:81], v[158:159] op_sel:[0,0,1] op_sel_hi:[1,0,0] neg_lo:[1,0,0] neg_hi:[1,0,0]
	v_pk_add_f32 v[158:159], v[140:141], v[160:161]
	v_pk_add_f32 v[140:141], v[140:141], v[160:161] neg_lo:[0,1] neg_hi:[0,1]
	v_pk_fma_f32 v[20:21], v[6:7], v[10:11], v[20:21] op_sel_hi:[0,1,1]
	v_pk_mul_f32 v[160:161], v[140:141], s[36:37]
	v_pk_mul_f32 v[24:25], v[10:11], v[22:23] op_sel:[1,0] op_sel_hi:[0,1]
	v_pk_fma_f32 v[140:141], v[140:141], s[78:79], v[160:161] op_sel:[0,0,1] op_sel_hi:[1,0,0] neg_lo:[1,0,0] neg_hi:[1,0,0]
	v_pk_add_f32 v[160:161], v[142:143], v[162:163]
	v_pk_add_f32 v[142:143], v[142:143], v[162:163] neg_lo:[0,1] neg_hi:[0,1]
	v_pk_fma_f32 v[36:37], v[6:7], v[28:29], v[36:37] op_sel_hi:[0,1,1]
	v_pk_mul_f32 v[162:163], v[142:143], s[18:19]
	v_pk_mul_f32 v[40:41], v[22:23], v[28:29] op_sel:[0,1] op_sel_hi:[1,0]
	v_pk_fma_f32 v[142:143], v[142:143], s[16:17], v[162:163] op_sel:[0,0,1] op_sel_hi:[1,0,0] neg_lo:[1,0,0] neg_hi:[1,0,0]
	v_pk_add_f32 v[162:163], v[194:195], v[184:185]
	v_pk_add_f32 v[184:185], v[194:195], v[184:185] neg_lo:[0,1] neg_hi:[0,1]
	v_pk_add_f32 v[194:195], v[178:179], v[170:171]
	v_pk_add_f32 v[170:171], v[178:179], v[170:171] neg_lo:[0,1] neg_hi:[0,1]
	v_pk_fma_f32 v[52:53], v[6:7], v[44:45], v[52:53] op_sel_hi:[0,1,1]
	v_pk_mul_f32 v[178:179], v[170:171], s[36:37]
	v_pk_mul_f32 v[56:57], v[22:23], v[44:45] op_sel:[0,1] op_sel_hi:[1,0]
	v_pk_fma_f32 v[170:171], v[170:171], s[78:79], v[178:179] op_sel:[0,0,1] op_sel_hi:[1,0,0]
	v_pk_add_f32 v[178:179], v[164:165], v[188:189]
	v_pk_add_f32 v[188:189], v[164:165], v[188:189] neg_lo:[0,1] neg_hi:[0,1]
	v_pk_fma_f32 v[68:69], v[6:7], v[60:61], v[68:69] op_sel_hi:[0,1,1]
	v_pk_add_f32 v[164:165], v[182:183], v[190:191]
	v_pk_add_f32 v[182:183], v[182:183], v[190:191] neg_lo:[0,1] neg_hi:[0,1]
	v_pk_mul_f32 v[72:73], v[22:23], v[60:61] op_sel:[0,1] op_sel_hi:[1,0]
	v_pk_mul_f32 v[190:191], v[182:183], s[36:37]
	v_pk_fma_f32 v[84:85], v[6:7], v[76:77], v[84:85] op_sel_hi:[0,1,1]
	v_pk_fma_f32 v[182:183], v[182:183], s[78:79], v[190:191] op_sel:[0,0,1] op_sel_hi:[1,0,0] neg_lo:[1,0,0] neg_hi:[1,0,0]
	v_pk_add_f32 v[190:191], v[144:145], v[186:187] op_sel:[0,1] op_sel_hi:[1,0] neg_hi:[0,1]
	v_pk_add_f32 v[144:145], v[144:145], v[186:187] op_sel:[0,1] op_sel_hi:[1,0] neg_lo:[0,1]
	v_pk_add_f32 v[186:187], v[148:149], v[172:173]
	v_pk_add_f32 v[148:149], v[148:149], v[172:173] neg_lo:[0,1] neg_hi:[0,1]
	v_pk_mul_f32 v[88:89], v[22:23], v[76:77] op_sel:[0,1] op_sel_hi:[1,0]
	v_pk_mul_f32 v[172:173], v[148:149], s[36:37]
	v_pk_fma_f32 v[100:101], v[6:7], v[92:93], v[100:101] op_sel_hi:[0,1,1]
	v_pk_fma_f32 v[148:149], v[148:149], s[78:79], v[172:173] op_sel:[0,0,1] op_sel_hi:[1,0,0]
	v_pk_add_f32 v[172:173], v[166:167], v[174:175]
	v_pk_add_f32 v[174:175], v[166:167], v[174:175] neg_lo:[0,1] neg_hi:[0,1]
	v_pk_mul_f32 v[104:105], v[22:23], v[92:93] op_sel:[0,1] op_sel_hi:[1,0]
	v_pk_add_f32 v[166:167], v[168:169], v[176:177]
	v_pk_add_f32 v[168:169], v[168:169], v[176:177] neg_lo:[0,1] neg_hi:[0,1]
	v_pk_fma_f32 v[116:117], v[6:7], v[108:109], v[116:117] op_sel_hi:[0,1,1]
	v_pk_mul_f32 v[176:177], v[168:169], s[36:37]
	v_pk_mul_f32 v[120:121], v[22:23], v[108:109] op_sel:[0,1] op_sel_hi:[1,0]
	v_pk_fma_f32 v[168:169], v[168:169], s[78:79], v[176:177] op_sel:[0,0,1] op_sel_hi:[1,0,0] neg_lo:[1,0,0] neg_hi:[1,0,0]
	v_pk_add_f32 v[176:177], v[192:193], v[154:155]
	v_pk_add_f32 v[154:155], v[192:193], v[154:155] neg_lo:[0,1] neg_hi:[0,1]
	v_pk_add_f32 v[192:193], v[180:181], v[136:137]
	v_pk_add_f32 v[136:137], v[180:181], v[136:137] neg_lo:[0,1] neg_hi:[0,1]
	v_xor_b32_e32 v26, 0x80000000, v17
	v_pk_mul_f32 v[180:181], v[136:137], s[36:37]
	v_xor_b32_e32 v30, 0x80000000, v21
	v_pk_fma_f32 v[136:137], v[136:137], s[78:79], v[180:181] op_sel:[0,0,1] op_sel_hi:[1,0,0]
	v_pk_add_f32 v[180:181], v[150:151], v[158:159]
	v_pk_add_f32 v[158:159], v[150:151], v[158:159] neg_lo:[0,1] neg_hi:[0,1]
	v_pk_fma_f32 v[24:25], v[10:11], v[8:9], v[24:25] op_sel_hi:[1,0,1]
	v_pk_add_f32 v[150:151], v[152:153], v[160:161]
	v_pk_add_f32 v[152:153], v[152:153], v[160:161] neg_lo:[0,1] neg_hi:[0,1]
	v_pk_fma_f32 v[40:41], v[8:9], v[28:29], v[40:41] op_sel_hi:[0,1,1]
	v_pk_mul_f32 v[160:161], v[152:153], s[36:37]
	v_pk_fma_f32 v[56:57], v[8:9], v[44:45], v[56:57] op_sel_hi:[0,1,1]
	v_pk_fma_f32 v[152:153], v[152:153], s[78:79], v[160:161] op_sel:[0,0,1] op_sel_hi:[1,0,0] neg_lo:[1,0,0] neg_hi:[1,0,0]
	v_pk_add_f32 v[160:161], v[128:129], v[156:157] op_sel:[0,1] op_sel_hi:[1,0] neg_hi:[0,1]
	v_pk_add_f32 v[128:129], v[128:129], v[156:157] op_sel:[0,1] op_sel_hi:[1,0] neg_lo:[0,1]
	v_pk_add_f32 v[156:157], v[130:131], v[138:139]
	v_pk_add_f32 v[130:131], v[130:131], v[138:139] neg_lo:[0,1] neg_hi:[0,1]
	v_pk_fma_f32 v[72:73], v[8:9], v[60:61], v[72:73] op_sel_hi:[0,1,1]
	v_pk_mul_f32 v[138:139], v[130:131], s[36:37]
	v_pk_fma_f32 v[88:89], v[8:9], v[76:77], v[88:89] op_sel_hi:[0,1,1]
	v_pk_fma_f32 v[130:131], v[130:131], s[78:79], v[138:139] op_sel:[0,0,1] op_sel_hi:[1,0,0]
	v_pk_add_f32 v[138:139], v[132:133], v[140:141]
	v_pk_add_f32 v[140:141], v[132:133], v[140:141] neg_lo:[0,1] neg_hi:[0,1]
	v_pk_fma_f32 v[104:105], v[8:9], v[92:93], v[104:105] op_sel_hi:[0,1,1]
	v_pk_add_f32 v[132:133], v[134:135], v[142:143]
	v_pk_add_f32 v[134:135], v[134:135], v[142:143] neg_lo:[0,1] neg_hi:[0,1]
	v_pk_fma_f32 v[120:121], v[8:9], v[108:109], v[120:121] op_sel_hi:[0,1,1]
	v_pk_mul_f32 v[142:143], v[134:135], s[36:37]
	v_mov_b32_e32 v27, v17
	v_pk_fma_f32 v[134:135], v[134:135], s[78:79], v[142:143] op_sel:[0,0,1] op_sel_hi:[1,0,0] neg_lo:[1,0,0] neg_hi:[1,0,0]
	v_pk_add_f32 v[142:143], v[162:163], v[178:179]
	v_pk_add_f32 v[162:163], v[162:163], v[178:179] neg_lo:[0,1] neg_hi:[0,1]
	v_pk_add_f32 v[178:179], v[194:195], v[164:165]
	v_pk_add_f32 v[194:195], v[194:195], v[164:165] neg_lo:[0,1] neg_hi:[0,1]
	v_mov_b32_e32 v31, v21
	v_pk_add_f32 v[164:165], v[184:185], v[188:189] op_sel:[0,1] op_sel_hi:[1,0] neg_hi:[0,1]
	v_pk_add_f32 v[184:185], v[184:185], v[188:189] op_sel:[0,1] op_sel_hi:[1,0] neg_lo:[0,1]
	v_pk_add_f32 v[188:189], v[170:171], v[182:183]
	v_pk_add_f32 v[182:183], v[170:171], v[182:183] neg_lo:[0,1] neg_hi:[0,1]
	v_xor_b32_e32 v34, 0x80000000, v25
	v_pk_add_f32 v[170:171], v[190:191], v[172:173]
	v_pk_add_f32 v[172:173], v[190:191], v[172:173] neg_lo:[0,1] neg_hi:[0,1]
	v_pk_add_f32 v[190:191], v[186:187], v[166:167]
	v_pk_add_f32 v[186:187], v[186:187], v[166:167] neg_lo:[0,1] neg_hi:[0,1]
	v_xor_b32_e32 v38, 0x80000000, v29
	v_pk_add_f32 v[166:167], v[144:145], v[174:175] op_sel:[0,1] op_sel_hi:[1,0] neg_hi:[0,1]
	v_pk_add_f32 v[144:145], v[144:145], v[174:175] op_sel:[0,1] op_sel_hi:[1,0] neg_lo:[0,1]
	v_pk_add_f32 v[174:175], v[148:149], v[168:169]
	v_pk_add_f32 v[168:169], v[148:149], v[168:169] neg_lo:[0,1] neg_hi:[0,1]
	v_xor_b32_e32 v42, 0x80000000, v33
	v_pk_add_f32 v[148:149], v[176:177], v[180:181]
	v_pk_add_f32 v[176:177], v[176:177], v[180:181] neg_lo:[0,1] neg_hi:[0,1]
	v_pk_add_f32 v[180:181], v[192:193], v[150:151]
	v_pk_add_f32 v[192:193], v[192:193], v[150:151] neg_lo:[0,1] neg_hi:[0,1]
	v_xor_b32_e32 v46, 0x80000000, v37
	v_pk_add_f32 v[150:151], v[154:155], v[158:159] op_sel:[0,1] op_sel_hi:[1,0] neg_hi:[0,1]
	v_pk_add_f32 v[154:155], v[154:155], v[158:159] op_sel:[0,1] op_sel_hi:[1,0] neg_lo:[0,1]
	v_pk_add_f32 v[158:159], v[136:137], v[152:153]
	v_pk_add_f32 v[152:153], v[136:137], v[152:153] neg_lo:[0,1] neg_hi:[0,1]
	v_mov_b32_e32 v35, v25
	v_pk_add_f32 v[136:137], v[160:161], v[138:139]
	v_pk_add_f32 v[138:139], v[160:161], v[138:139] neg_lo:[0,1] neg_hi:[0,1]
	v_pk_add_f32 v[160:161], v[156:157], v[132:133]
	v_pk_add_f32 v[156:157], v[156:157], v[132:133] neg_lo:[0,1] neg_hi:[0,1]
	v_mov_b32_e32 v39, v29
	v_pk_add_f32 v[132:133], v[128:129], v[140:141] op_sel:[0,1] op_sel_hi:[1,0] neg_hi:[0,1]
	v_pk_add_f32 v[128:129], v[128:129], v[140:141] op_sel:[0,1] op_sel_hi:[1,0] neg_lo:[0,1]
	v_pk_add_f32 v[140:141], v[130:131], v[134:135]
	v_pk_add_f32 v[134:135], v[130:131], v[134:135] neg_lo:[0,1] neg_hi:[0,1]
	v_mov_b32_e32 v43, v33
	v_pk_add_f32 v[130:131], v[142:143], v[178:179]
	v_pk_add_f32 v[142:143], v[142:143], v[178:179] neg_lo:[0,1] neg_hi:[0,1]
	v_pk_add_f32 v[178:179], v[162:163], v[194:195] op_sel:[0,1] op_sel_hi:[1,0] neg_hi:[0,1]
	v_pk_add_f32 v[162:163], v[162:163], v[194:195] op_sel:[0,1] op_sel_hi:[1,0] neg_lo:[0,1]
	v_pk_add_f32 v[194:195], v[164:165], v[188:189]
	v_pk_add_f32 v[164:165], v[164:165], v[188:189] neg_lo:[0,1] neg_hi:[0,1]
	v_pk_add_f32 v[188:189], v[184:185], v[182:183] op_sel:[0,1] op_sel_hi:[1,0] neg_hi:[0,1]
	v_pk_add_f32 v[182:183], v[184:185], v[182:183] op_sel:[0,1] op_sel_hi:[1,0] neg_lo:[0,1]
	v_pk_add_f32 v[184:185], v[170:171], v[190:191]
	v_pk_add_f32 v[170:171], v[170:171], v[190:191] neg_lo:[0,1] neg_hi:[0,1]
	v_pk_add_f32 v[190:191], v[172:173], v[186:187] op_sel:[0,1] op_sel_hi:[1,0] neg_hi:[0,1]
	v_pk_add_f32 v[172:173], v[172:173], v[186:187] op_sel:[0,1] op_sel_hi:[1,0] neg_lo:[0,1]
	v_pk_add_f32 v[186:187], v[166:167], v[174:175]
	v_pk_add_f32 v[166:167], v[166:167], v[174:175] neg_lo:[0,1] neg_hi:[0,1]
	v_pk_add_f32 v[174:175], v[144:145], v[168:169] op_sel:[0,1] op_sel_hi:[1,0] neg_hi:[0,1]
	v_pk_add_f32 v[144:145], v[144:145], v[168:169] op_sel:[0,1] op_sel_hi:[1,0] neg_lo:[0,1]
	v_pk_add_f32 v[168:169], v[148:149], v[180:181]
	v_pk_add_f32 v[148:149], v[148:149], v[180:181] neg_lo:[0,1] neg_hi:[0,1]
	v_pk_mul_f32 v[2:3], v[2:3], v[168:169] op_sel:[0,1] op_sel_hi:[1,0]
	v_pk_add_f32 v[180:181], v[176:177], v[192:193] op_sel:[0,1] op_sel_hi:[1,0] neg_hi:[0,1]
	v_pk_add_f32 v[176:177], v[176:177], v[192:193] op_sel:[0,1] op_sel_hi:[1,0] neg_lo:[0,1]
	v_pk_add_f32 v[192:193], v[150:151], v[158:159]
	v_pk_add_f32 v[150:151], v[150:151], v[158:159] neg_lo:[0,1] neg_hi:[0,1]
	v_pk_add_f32 v[158:159], v[154:155], v[152:153] op_sel:[0,1] op_sel_hi:[1,0] neg_hi:[0,1]
	v_pk_add_f32 v[152:153], v[154:155], v[152:153] op_sel:[0,1] op_sel_hi:[1,0] neg_lo:[0,1]
	v_pk_add_f32 v[154:155], v[136:137], v[160:161]
	v_pk_fma_f32 v[2:3], v[4:5], v[168:169], v[2:3] op_sel_hi:[0,1,1]
	v_pk_mul_f32 v[4:5], v[12:13], v[184:185] op_sel:[0,1] op_sel_hi:[1,0]
	v_mov_b32_e32 v47, v37
	v_pk_fma_f32 v[4:5], v[6:7], v[184:185], v[4:5] op_sel_hi:[0,1,1]
	v_pk_mul_f32 v[6:7], v[22:23], v[154:155] op_sel:[0,1] op_sel_hi:[1,0]
	v_pk_add_f32 v[136:137], v[136:137], v[160:161] neg_lo:[0,1] neg_hi:[0,1]
	v_pk_fma_f32 v[6:7], v[8:9], v[154:155], v[6:7] op_sel_hi:[0,1,1]
	v_pk_mul_f32 v[8:9], v[14:15], v[194:195] op_sel:[0,1] op_sel_hi:[1,0]
	v_pk_add_f32 v[160:161], v[138:139], v[156:157] op_sel:[0,1] op_sel_hi:[1,0] neg_hi:[0,1]
	v_pk_add_f32 v[138:139], v[138:139], v[156:157] op_sel:[0,1] op_sel_hi:[1,0] neg_lo:[0,1]
	v_pk_add_f32 v[156:157], v[132:133], v[140:141]
	v_pk_fma_f32 v[8:9], v[10:11], v[194:195], v[8:9] op_sel_hi:[0,1,1]
	v_pk_mul_f32 v[10:11], v[26:27], v[192:193] op_sel:[0,1] op_sel_hi:[1,0]
	v_pk_mul_f32 v[12:13], v[30:31], v[186:187] op_sel:[0,1] op_sel_hi:[1,0]
	v_xor_b32_e32 v50, 0x80000000, v41
	v_xor_b32_e32 v54, 0x80000000, v45
	v_xor_b32_e32 v58, 0x80000000, v49
	v_xor_b32_e32 v62, 0x80000000, v53
	v_xor_b32_e32 v66, 0x80000000, v57
	v_xor_b32_e32 v70, 0x80000000, v61
	v_xor_b32_e32 v74, 0x80000000, v65
	v_mov_b32_e32 v51, v41
	v_mov_b32_e32 v55, v45
	v_mov_b32_e32 v59, v49
	v_mov_b32_e32 v63, v53
	v_mov_b32_e32 v67, v57
	v_mov_b32_e32 v71, v61
	v_mov_b32_e32 v75, v65
	v_pk_add_f32 v[132:133], v[132:133], v[140:141] neg_lo:[0,1] neg_hi:[0,1]
	v_pk_add_f32 v[140:141], v[128:129], v[134:135] op_sel:[0,1] op_sel_hi:[1,0] neg_hi:[0,1]
	v_pk_fma_f32 v[10:11], v[16:17], v[192:193], v[10:11] op_sel_hi:[0,1,1]
	v_pk_fma_f32 v[12:13], v[20:21], v[186:187], v[12:13] op_sel_hi:[0,1,1]
	v_pk_mul_f32 v[14:15], v[34:35], v[156:157] op_sel:[0,1] op_sel_hi:[1,0]
	v_pk_mul_f32 v[16:17], v[38:39], v[178:179] op_sel:[0,1] op_sel_hi:[1,0]
	v_pk_mul_f32 v[20:21], v[42:43], v[180:181] op_sel:[0,1] op_sel_hi:[1,0]
	v_pk_mul_f32 v[22:23], v[46:47], v[190:191] op_sel:[0,1] op_sel_hi:[1,0]
	v_xor_b32_e32 v78, 0x80000000, v69
	v_xor_b32_e32 v82, 0x80000000, v73
	v_xor_b32_e32 v86, 0x80000000, v77
	v_xor_b32_e32 v90, 0x80000000, v81
	v_xor_b32_e32 v94, 0x80000000, v85
	v_xor_b32_e32 v98, 0x80000000, v89
	v_xor_b32_e32 v102, 0x80000000, v93
	v_xor_b32_e32 v106, 0x80000000, v97
	v_xor_b32_e32 v110, 0x80000000, v101
	v_xor_b32_e32 v114, 0x80000000, v105
	v_xor_b32_e32 v118, 0x80000000, v109
	v_xor_b32_e32 v122, 0x80000000, v113
	v_xor_b32_e32 v124, 0x80000000, v117
	v_xor_b32_e32 v126, 0x80000000, v121
	v_mov_b32_e32 v79, v69
	v_mov_b32_e32 v83, v73
	v_mov_b32_e32 v87, v77
	v_mov_b32_e32 v91, v81
	v_mov_b32_e32 v95, v85
	v_mov_b32_e32 v99, v89
	v_mov_b32_e32 v103, v93
	v_mov_b32_e32 v107, v97
	v_mov_b32_e32 v111, v101
	v_mov_b32_e32 v115, v105
	v_mov_b32_e32 v119, v109
	v_mov_b32_e32 v123, v113
	v_mov_b32_e32 v125, v117
	v_mov_b32_e32 v127, v121
	v_pk_add_f32 v[128:129], v[128:129], v[134:135] op_sel:[0,1] op_sel_hi:[1,0] neg_lo:[0,1]
	v_pk_fma_f32 v[14:15], v[24:25], v[156:157], v[14:15] op_sel_hi:[0,1,1]
	v_pk_fma_f32 v[16:17], v[28:29], v[178:179], v[16:17] op_sel_hi:[0,1,1]
	v_pk_fma_f32 v[20:21], v[32:33], v[180:181], v[20:21] op_sel_hi:[0,1,1]
	v_pk_fma_f32 v[22:23], v[36:37], v[190:191], v[22:23] op_sel_hi:[0,1,1]
	v_pk_mul_f32 v[24:25], v[50:51], v[160:161] op_sel:[0,1] op_sel_hi:[1,0]
	v_pk_mul_f32 v[26:27], v[54:55], v[188:189] op_sel:[0,1] op_sel_hi:[1,0]
	v_pk_mul_f32 v[28:29], v[58:59], v[158:159] op_sel:[0,1] op_sel_hi:[1,0]
	v_pk_mul_f32 v[30:31], v[62:63], v[174:175] op_sel:[0,1] op_sel_hi:[1,0]
	v_pk_mul_f32 v[32:33], v[66:67], v[140:141] op_sel:[0,1] op_sel_hi:[1,0]
	v_pk_mul_f32 v[34:35], v[70:71], v[142:143] op_sel:[0,1] op_sel_hi:[1,0]
	v_pk_mul_f32 v[36:37], v[74:75], v[148:149] op_sel:[0,1] op_sel_hi:[1,0]
	v_pk_fma_f32 v[24:25], v[40:41], v[160:161], v[24:25] op_sel_hi:[0,1,1]
	v_pk_fma_f32 v[26:27], v[44:45], v[188:189], v[26:27] op_sel_hi:[0,1,1]
	v_pk_fma_f32 v[28:29], v[48:49], v[158:159], v[28:29] op_sel_hi:[0,1,1]
	v_pk_fma_f32 v[30:31], v[52:53], v[174:175], v[30:31] op_sel_hi:[0,1,1]
	v_pk_fma_f32 v[32:33], v[56:57], v[140:141], v[32:33] op_sel_hi:[0,1,1]
	v_pk_fma_f32 v[34:35], v[60:61], v[142:143], v[34:35] op_sel_hi:[0,1,1]
	v_pk_fma_f32 v[36:37], v[64:65], v[148:149], v[36:37] op_sel_hi:[0,1,1]
	v_pk_mul_f32 v[38:39], v[78:79], v[170:171] op_sel:[0,1] op_sel_hi:[1,0]
	v_pk_mul_f32 v[40:41], v[82:83], v[136:137] op_sel:[0,1] op_sel_hi:[1,0]
	v_pk_mul_f32 v[42:43], v[86:87], v[164:165] op_sel:[0,1] op_sel_hi:[1,0]
	v_pk_mul_f32 v[44:45], v[90:91], v[150:151] op_sel:[0,1] op_sel_hi:[1,0]
	v_pk_mul_f32 v[46:47], v[94:95], v[166:167] op_sel:[0,1] op_sel_hi:[1,0]
	v_pk_mul_f32 v[48:49], v[98:99], v[132:133] op_sel:[0,1] op_sel_hi:[1,0]
	v_pk_mul_f32 v[50:51], v[102:103], v[162:163] op_sel:[0,1] op_sel_hi:[1,0]
	v_pk_mul_f32 v[52:53], v[106:107], v[176:177] op_sel:[0,1] op_sel_hi:[1,0]
	v_pk_mul_f32 v[54:55], v[110:111], v[172:173] op_sel:[0,1] op_sel_hi:[1,0]
	v_pk_mul_f32 v[56:57], v[114:115], v[138:139] op_sel:[0,1] op_sel_hi:[1,0]
	v_pk_mul_f32 v[58:59], v[118:119], v[182:183] op_sel:[0,1] op_sel_hi:[1,0]
	v_pk_mul_f32 v[60:61], v[122:123], v[152:153] op_sel:[0,1] op_sel_hi:[1,0]
	v_pk_mul_f32 v[62:63], v[124:125], v[144:145] op_sel:[0,1] op_sel_hi:[1,0]
	v_pk_mul_f32 v[64:65], v[126:127], v[128:129] op_sel:[0,1] op_sel_hi:[1,0]
	v_pk_fma_f32 v[38:39], v[68:69], v[170:171], v[38:39] op_sel_hi:[0,1,1]
	v_pk_fma_f32 v[40:41], v[72:73], v[136:137], v[40:41] op_sel_hi:[0,1,1]
	v_pk_fma_f32 v[42:43], v[76:77], v[164:165], v[42:43] op_sel_hi:[0,1,1]
	v_pk_fma_f32 v[44:45], v[80:81], v[150:151], v[44:45] op_sel_hi:[0,1,1]
	v_pk_fma_f32 v[46:47], v[84:85], v[166:167], v[46:47] op_sel_hi:[0,1,1]
	v_pk_fma_f32 v[48:49], v[88:89], v[132:133], v[48:49] op_sel_hi:[0,1,1]
	v_pk_fma_f32 v[50:51], v[92:93], v[162:163], v[50:51] op_sel_hi:[0,1,1]
	v_pk_fma_f32 v[52:53], v[96:97], v[176:177], v[52:53] op_sel_hi:[0,1,1]
	v_pk_fma_f32 v[54:55], v[100:101], v[172:173], v[54:55] op_sel_hi:[0,1,1]
	v_pk_fma_f32 v[56:57], v[104:105], v[138:139], v[56:57] op_sel_hi:[0,1,1]
	v_pk_fma_f32 v[58:59], v[108:109], v[182:183], v[58:59] op_sel_hi:[0,1,1]
	v_pk_fma_f32 v[60:61], v[112:113], v[152:153], v[60:61] op_sel_hi:[0,1,1]
	v_pk_fma_f32 v[62:63], v[116:117], v[144:145], v[62:63] op_sel_hi:[0,1,1]
	v_pk_fma_f32 v[64:65], v[120:121], v[128:129], v[64:65] op_sel_hi:[0,1,1]
	ds_write2_b64 v18, v[130:131], v[34:35] offset1:16
	ds_write2_b64 v18, v[16:17], v[50:51] offset0:33 offset1:49
	ds_write2_b64 v18, v[8:9], v[42:43] offset0:66 offset1:82
	ds_write2_b64 v18, v[26:27], v[58:59] offset0:99 offset1:115
	ds_write2_b64 v18, v[4:5], v[38:39] offset0:132 offset1:148
	ds_write2_b64 v18, v[22:23], v[54:55] offset0:165 offset1:181
	ds_write2_b64 v18, v[12:13], v[46:47] offset0:198 offset1:214
	ds_write2_b64 v18, v[30:31], v[62:63] offset0:231 offset1:247
	ds_write2_b64 v196, v[2:3], v[36:37] offset0:8 offset1:24
	ds_write2_b64 v196, v[20:21], v[52:53] offset0:41 offset1:57
	ds_write2_b64 v196, v[10:11], v[44:45] offset0:74 offset1:90
	ds_write2_b64 v196, v[28:29], v[60:61] offset0:107 offset1:123
	ds_write2_b64 v196, v[6:7], v[40:41] offset0:140 offset1:156
	ds_write2_b64 v196, v[24:25], v[56:57] offset0:173 offset1:189
	ds_write2_b64 v196, v[14:15], v[48:49] offset0:206 offset1:222
	ds_write2_b64 v196, v[32:33], v[64:65] offset0:239 offset1:255
	v_ashrrev_i32_e32 v2, 31, v210
	v_lshrrev_b32_e32 v2, 23, v2
	v_add_u32_e32 v2, v210, v2
	s_lshl_b64 s[74:75], s[76:77], 16
	v_and_b32_e32 v2, 0xfffffe00, v2
	s_add_u32 s0, s54, s74
	v_sub_u32_e32 v2, v210, v2
	s_addc_u32 s1, s55, s75
	v_ashrrev_i32_e32 v3, 31, v2
	v_lshl_add_u64 v[14:15], v[2:3], 3, s[0:1]
	v_add_co_u32_e32 v2, vcc, s92, v14
	s_mov_b32 s0, 0x8000
	s_nop 0
	v_addc_co_u32_e32 v3, vcc, 0, v15, vcc
	v_add_co_u32_e32 v4, vcc, s95, v14
	s_waitcnt lgkmcnt(0)
	s_nop 0
	v_addc_co_u32_e32 v5, vcc, 0, v15, vcc
	v_add_co_u32_e32 v8, vcc, s96, v14
	s_barrier
	s_nop 0
	v_addc_co_u32_e32 v9, vcc, 0, v15, vcc
	global_load_dwordx2 v[24:25], v[4:5], off offset:-4096 nt
	global_load_dwordx2 v[12:13], v[4:5], off nt
	global_load_dwordx2 v[6:7], v[8:9], off offset:-4096 nt
	s_nop 0
	global_load_dwordx2 v[4:5], v[8:9], off nt
	v_add_co_u32_e32 v8, vcc, s0, v14
	s_waitcnt vmcnt(3)
	v_cvt_f32_f16_sdwa v174, v24 dst_sel:DWORD dst_unused:UNUSED_PAD src0_sel:WORD_1
	v_addc_co_u32_e32 v9, vcc, 0, v15, vcc
	v_add_co_u32_e32 v10, vcc, s34, v14
	v_cvt_f32_f16_e32 v175, v25
	s_nop 0
	v_addc_co_u32_e32 v11, vcc, 0, v15, vcc
	global_load_dwordx2 v[16:17], v[8:9], off offset:-4096 nt
	global_load_dwordx2 v[122:123], v[8:9], off nt
	global_load_dwordx2 v[46:47], v[10:11], off offset:-4096 nt
	global_load_dwordx2 v[36:37], v[10:11], off nt
	v_add_co_u32_e32 v8, vcc, s35, v14
	v_cvt_f32_f16_sdwa v177, v25 dst_sel:DWORD dst_unused:UNUSED_PAD src0_sel:WORD_1
	s_nop 0
	v_addc_co_u32_e32 v9, vcc, 0, v15, vcc
	v_add_co_u32_e32 v22, vcc, s30, v14
	v_cvt_f32_f16_e32 v176, v24
	s_nop 0
	v_addc_co_u32_e32 v23, vcc, 0, v15, vcc
	global_load_dwordx2 v[26:27], v[8:9], off offset:-4096 nt
	global_load_dwordx2 v[20:21], v[8:9], off nt
	global_load_dwordx2 v[10:11], v[22:23], off offset:-4096 nt
	s_nop 0
	global_load_dwordx2 v[8:9], v[22:23], off nt
	v_add_co_u32_e32 v22, vcc, s31, v14
	s_waitcnt vmcnt(10)
	v_cvt_f32_f16_sdwa v164, v12 dst_sel:DWORD dst_unused:UNUSED_PAD src0_sel:WORD_1
	v_addc_co_u32_e32 v23, vcc, 0, v15, vcc
	global_load_dwordx2 v[30:31], v[2:3], off offset:-4096 nt
	global_load_dwordx2 v[28:29], v[2:3], off nt
	s_nop 0
	global_load_dwordx2 v[2:3], v[22:23], off nt
	global_load_dwordx2 v[32:33], v[14:15], off nt
	v_mov_b32_e32 v14, v210
	v_cvt_f32_f16_e32 v165, v13
	v_ashrrev_i32_e32 v15, 31, v14
	v_lshrrev_b32_e32 v15, 23, v15
	v_add_u32_e32 v15, v14, v15
	v_ashrrev_i32_e32 v15, 9, v15
	v_mul_i32_i24_e32 v18, 0x200, v15
	v_sub_u32_e32 v18, v14, v18
	v_lshlrev_b32_e32 v14, 14, v15
	v_lshlrev_b32_e32 v15, 1, v18
	v_bfrev_b32_e32 v15, v15
	v_lshrrev_b32_e32 v15, 22, v15
	v_sub_u32_e32 v15, 0x400, v15
	v_bfrev_b32_e32 v15, v15
	v_lshrrev_b32_e32 v15, 18, v15
	v_and_b32_e32 v15, 0x3ff0, v15
	v_cmp_eq_u32_e64 s[0:1], 0, v18
	v_lshl_add_u32 v22, v18, 5, v14
	v_lshl_add_u32 v23, v22, 3, 0
	v_cndmask_b32_e64 v15, v15, 16, s[0:1]
	v_or_b32_e32 v14, v15, v14
	v_ashrrev_i32_e32 v22, 2, v22
	v_ashrrev_i32_e32 v15, 5, v14
	v_add_u32_e32 v211, v23, v22
	v_lshlrev_b32_e32 v14, 3, v14
	v_lshlrev_b32_e32 v15, 3, v15
	v_add3_u32 v212, 0, v14, v15
	ds_read2_b64 v[38:41], v211 offset1:1
	ds_read2_b64 v[42:45], v211 offset0:2 offset1:3
	ds_read2_b64 v[48:51], v212 offset1:1
	ds_read2_b64 v[52:55], v212 offset0:2 offset1:3
	ds_read2_b64 v[56:59], v211 offset0:4 offset1:5
	ds_read2_b64 v[60:63], v211 offset0:6 offset1:7
	ds_read2_b64 v[68:71], v212 offset0:4 offset1:5
	ds_read2_b64 v[72:75], v212 offset0:6 offset1:7
	ds_read2_b64 v[64:67], v211 offset0:8 offset1:9
	ds_read2_b64 v[76:79], v211 offset0:10 offset1:11
	ds_read2_b64 v[80:83], v212 offset0:8 offset1:9
	ds_read2_b64 v[98:101], v212 offset0:10 offset1:11
	ds_read2_b64 v[84:87], v211 offset0:12 offset1:13
	ds_read2_b64 v[88:91], v211 offset0:14 offset1:15
	ds_read2_b64 v[102:105], v212 offset0:12 offset1:13
	ds_read2_b64 v[106:109], v212 offset0:14 offset1:15
	s_waitcnt lgkmcnt(7)
	v_pk_add_f32 v[14:15], v[38:39], v[64:65]
	v_pk_add_f32 v[22:23], v[38:39], v[64:65] neg_lo:[0,1] neg_hi:[0,1]
	v_pk_add_f32 v[38:39], v[40:41], v[66:67] neg_lo:[0,1] neg_hi:[0,1]
	v_pk_add_f32 v[34:35], v[40:41], v[66:67]
	v_pk_mul_f32 v[40:41], v[38:39], s[18:19]
	v_cmp_ne_u32_e32 vcc, 0, v18
	v_pk_fma_f32 v[38:39], v[38:39], s[16:17], v[40:41] op_sel:[0,0,1] op_sel_hi:[1,0,0]
	s_waitcnt lgkmcnt(6)
	v_pk_add_f32 v[40:41], v[42:43], v[76:77]
	v_pk_add_f32 v[42:43], v[42:43], v[76:77] neg_lo:[0,1] neg_hi:[0,1]
	v_bfrev_b32_e32 v18, v18
	v_pk_mul_f32 v[64:65], v[42:43], s[36:37]
	v_lshrrev_b32_e32 v18, 23, v18
	v_pk_fma_f32 v[42:43], v[42:43], s[78:79], v[64:65] op_sel:[0,0,1] op_sel_hi:[1,0,0]
	v_pk_add_f32 v[64:65], v[44:45], v[78:79]
	v_pk_add_f32 v[44:45], v[44:45], v[78:79] neg_lo:[0,1] neg_hi:[0,1]
	s_waitcnt lgkmcnt(3)
	v_pk_add_f32 v[78:79], v[58:59], v[86:87]
	v_pk_mul_f32 v[66:67], v[44:45], s[40:41]
	v_pk_add_f32 v[58:59], v[58:59], v[86:87] neg_lo:[0,1] neg_hi:[0,1]
	v_pk_fma_f32 v[44:45], v[44:45], s[80:81], v[66:67] op_sel:[0,0,1] op_sel_hi:[1,0,0]
	v_pk_add_f32 v[66:67], v[56:57], v[84:85]
	v_pk_add_f32 v[76:77], v[56:57], v[84:85] neg_lo:[0,1] neg_hi:[0,1]
	v_pk_mul_f32 v[84:85], v[58:59], s[40:41]
	s_nop 0
	v_pk_fma_f32 v[58:59], v[58:59], s[80:81], v[84:85] op_sel:[0,0,1] op_sel_hi:[1,0,0] neg_lo:[1,0,0] neg_hi:[1,0,0]
	s_waitcnt lgkmcnt(2)
	v_pk_add_f32 v[84:85], v[60:61], v[88:89]
	v_pk_add_f32 v[60:61], v[60:61], v[88:89] neg_lo:[0,1] neg_hi:[0,1]
	s_nop 0
	v_pk_mul_f32 v[86:87], v[60:61], s[36:37]
	v_pk_add_f32 v[56:57], v[22:23], v[76:77] op_sel:[0,1] op_sel_hi:[1,0] neg_hi:[0,1]
	v_pk_fma_f32 v[60:61], v[60:61], s[78:79], v[86:87] op_sel:[0,0,1] op_sel_hi:[1,0,0] neg_lo:[1,0,0] neg_hi:[1,0,0]
	v_pk_add_f32 v[86:87], v[62:63], v[90:91]
	v_pk_add_f32 v[62:63], v[62:63], v[90:91] neg_lo:[0,1] neg_hi:[0,1]
	v_pk_add_f32 v[90:91], v[64:65], v[86:87]
	v_pk_mul_f32 v[88:89], v[62:63], s[18:19]
	v_pk_add_f32 v[64:65], v[64:65], v[86:87] neg_lo:[0,1] neg_hi:[0,1]
	v_pk_fma_f32 v[62:63], v[62:63], s[16:17], v[88:89] op_sel:[0,0,1] op_sel_hi:[1,0,0] neg_lo:[1,0,0] neg_hi:[1,0,0]
	v_pk_add_f32 v[88:89], v[14:15], v[66:67]
	v_pk_add_f32 v[14:15], v[14:15], v[66:67] neg_lo:[0,1] neg_hi:[0,1]
	v_pk_add_f32 v[66:67], v[34:35], v[78:79]
	v_pk_add_f32 v[34:35], v[34:35], v[78:79] neg_lo:[0,1] neg_hi:[0,1]
	v_pk_add_f32 v[22:23], v[22:23], v[76:77] op_sel:[0,1] op_sel_hi:[1,0] neg_lo:[0,1]
	v_pk_mul_f32 v[78:79], v[34:35], s[36:37]
	v_pk_add_f32 v[76:77], v[38:39], v[58:59]
	v_pk_add_f32 v[38:39], v[38:39], v[58:59] neg_lo:[0,1] neg_hi:[0,1]
	v_pk_fma_f32 v[34:35], v[34:35], s[78:79], v[78:79] op_sel:[0,0,1] op_sel_hi:[1,0,0]
	v_pk_add_f32 v[78:79], v[40:41], v[84:85]
	v_pk_add_f32 v[84:85], v[40:41], v[84:85] neg_lo:[0,1] neg_hi:[0,1]
	v_pk_mul_f32 v[86:87], v[64:65], s[36:37]
	v_pk_mul_f32 v[58:59], v[38:39], s[36:37]
	v_pk_fma_f32 v[64:65], v[64:65], s[78:79], v[86:87] op_sel:[0,0,1] op_sel_hi:[1,0,0] neg_lo:[1,0,0] neg_hi:[1,0,0]
	v_pk_fma_f32 v[38:39], v[38:39], s[78:79], v[58:59] op_sel:[0,0,1] op_sel_hi:[1,0,0]
	v_pk_add_f32 v[58:59], v[42:43], v[60:61]
	v_pk_add_f32 v[86:87], v[44:45], v[62:63]
	v_pk_add_f32 v[44:45], v[44:45], v[62:63] neg_lo:[0,1] neg_hi:[0,1]
	s_nop 0
	v_pk_mul_f32 v[62:63], v[44:45], s[36:37]
	v_pk_add_f32 v[40:41], v[14:15], v[84:85] op_sel:[0,1] op_sel_hi:[1,0] neg_hi:[0,1]
	v_pk_add_f32 v[14:15], v[14:15], v[84:85] op_sel:[0,1] op_sel_hi:[1,0] neg_lo:[0,1]
	v_pk_add_f32 v[84:85], v[34:35], v[64:65]
	v_pk_add_f32 v[64:65], v[34:35], v[64:65] neg_lo:[0,1] neg_hi:[0,1]
	v_pk_add_f32 v[94:95], v[56:57], v[58:59]
	v_pk_add_f32 v[56:57], v[56:57], v[58:59] neg_lo:[0,1] neg_hi:[0,1]
	v_pk_add_f32 v[58:59], v[76:77], v[86:87]
	v_pk_fma_f32 v[44:45], v[44:45], s[78:79], v[62:63] op_sel:[0,0,1] op_sel_hi:[1,0,0] neg_lo:[1,0,0] neg_hi:[1,0,0]
	v_pk_add_f32 v[62:63], v[88:89], v[78:79]
	v_pk_add_f32 v[78:79], v[88:89], v[78:79] neg_lo:[0,1] neg_hi:[0,1]
	v_pk_add_f32 v[88:89], v[66:67], v[90:91]
	v_pk_add_f32 v[110:111], v[76:77], v[86:87] neg_lo:[0,1] neg_hi:[0,1]
	v_pk_add_f32 v[86:87], v[94:95], v[58:59]
	v_pk_add_f32 v[34:35], v[94:95], v[58:59] neg_lo:[0,1] neg_hi:[0,1]
	v_pk_add_f32 v[58:59], v[50:51], v[82:83]
	v_pk_add_f32 v[50:51], v[50:51], v[82:83] neg_lo:[0,1] neg_hi:[0,1]
	v_pk_add_f32 v[60:61], v[42:43], v[60:61] neg_lo:[0,1] neg_hi:[0,1]
	v_pk_add_f32 v[148:149], v[62:63], v[88:89]
	v_pk_add_f32 v[138:139], v[62:63], v[88:89] neg_lo:[0,1] neg_hi:[0,1]
	v_pk_mul_f32 v[62:63], v[50:51], s[18:19]
	v_pk_add_f32 v[90:91], v[66:67], v[90:91] neg_lo:[0,1] neg_hi:[0,1]
	v_pk_fma_f32 v[50:51], v[50:51], s[16:17], v[62:63] op_sel:[0,0,1] op_sel_hi:[1,0,0]
	v_pk_add_f32 v[62:63], v[52:53], v[98:99]
	v_pk_add_f32 v[52:53], v[52:53], v[98:99] neg_lo:[0,1] neg_hi:[0,1]
	v_pk_add_f32 v[112:113], v[22:23], v[60:61] op_sel:[0,1] op_sel_hi:[1,0] neg_hi:[0,1]
	v_pk_add_f32 v[114:115], v[22:23], v[60:61] op_sel:[0,1] op_sel_hi:[1,0] neg_lo:[0,1]
	v_pk_add_f32 v[96:97], v[40:41], v[84:85]
	v_pk_add_f32 v[66:67], v[40:41], v[84:85] neg_lo:[0,1] neg_hi:[0,1]
	v_pk_add_f32 v[60:61], v[14:15], v[64:65] op_sel:[0,1] op_sel_hi:[1,0] neg_hi:[0,1]
	v_pk_add_f32 v[84:85], v[14:15], v[64:65] op_sel:[0,1] op_sel_hi:[1,0] neg_lo:[0,1]
	v_pk_mul_f32 v[64:65], v[52:53], s[36:37]
	s_nop 0
	v_pk_fma_f32 v[52:53], v[52:53], s[78:79], v[64:65] op_sel:[0,0,1] op_sel_hi:[1,0,0]
	v_pk_add_f32 v[64:65], v[54:55], v[100:101]
	v_pk_add_f32 v[54:55], v[54:55], v[100:101] neg_lo:[0,1] neg_hi:[0,1]
	s_nop 0
	v_pk_mul_f32 v[76:77], v[54:55], s[40:41]
	v_pk_add_f32 v[92:93], v[78:79], v[90:91] op_sel:[0,1] op_sel_hi:[1,0] neg_hi:[0,1]
	v_pk_fma_f32 v[54:55], v[54:55], s[80:81], v[76:77] op_sel:[0,0,1] op_sel_hi:[1,0,0]
	s_waitcnt lgkmcnt(1)
	v_pk_add_f32 v[76:77], v[68:69], v[102:103]
	v_pk_add_f32 v[88:89], v[78:79], v[90:91] op_sel:[0,1] op_sel_hi:[1,0] neg_lo:[0,1]
	v_pk_add_f32 v[78:79], v[68:69], v[102:103] neg_lo:[0,1] neg_hi:[0,1]
	v_pk_add_f32 v[68:69], v[70:71], v[104:105]
	v_pk_add_f32 v[70:71], v[70:71], v[104:105] neg_lo:[0,1] neg_hi:[0,1]
	v_pk_add_f32 v[22:23], v[38:39], v[44:45]
	v_pk_add_f32 v[116:117], v[38:39], v[44:45] neg_lo:[0,1] neg_hi:[0,1]
	v_pk_add_f32 v[40:41], v[56:57], v[110:111] op_sel:[0,1] op_sel_hi:[1,0] neg_hi:[0,1]
	v_pk_add_f32 v[44:45], v[56:57], v[110:111] op_sel:[0,1] op_sel_hi:[1,0] neg_lo:[0,1]
	v_pk_add_f32 v[56:57], v[48:49], v[80:81]
	v_pk_add_f32 v[48:49], v[48:49], v[80:81] neg_lo:[0,1] neg_hi:[0,1]
	v_pk_mul_f32 v[80:81], v[70:71], s[40:41]
	v_cvt_f32_u32_e32 v18, v18
	v_pk_fma_f32 v[70:71], v[70:71], s[80:81], v[80:81] op_sel:[0,0,1] op_sel_hi:[1,0,0] neg_lo:[1,0,0] neg_hi:[1,0,0]
	s_waitcnt lgkmcnt(0)
	v_pk_add_f32 v[80:81], v[72:73], v[106:107]
	v_pk_add_f32 v[72:73], v[72:73], v[106:107] neg_lo:[0,1] neg_hi:[0,1]
	v_mul_f32_e32 v18, 0x38000000, v18
	v_pk_mul_f32 v[82:83], v[72:73], s[36:37]
	v_cndmask_b32_e64 v18, v18, v208, s[0:1]
	v_pk_fma_f32 v[72:73], v[72:73], s[78:79], v[82:83] op_sel:[0,0,1] op_sel_hi:[1,0,0] neg_lo:[1,0,0] neg_hi:[1,0,0]
	v_pk_add_f32 v[82:83], v[74:75], v[108:109]
	v_pk_add_f32 v[74:75], v[74:75], v[108:109] neg_lo:[0,1] neg_hi:[0,1]
	s_nop 0
	v_pk_mul_f32 v[90:91], v[74:75], s[18:19]
	s_nop 0
	v_pk_fma_f32 v[74:75], v[74:75], s[16:17], v[90:91] op_sel:[0,0,1] op_sel_hi:[1,0,0] neg_lo:[1,0,0] neg_hi:[1,0,0]
	v_pk_add_f32 v[90:91], v[56:57], v[76:77]
	v_pk_add_f32 v[56:57], v[56:57], v[76:77] neg_lo:[0,1] neg_hi:[0,1]
	v_pk_add_f32 v[76:77], v[58:59], v[68:69]
	v_pk_add_f32 v[58:59], v[58:59], v[68:69] neg_lo:[0,1] neg_hi:[0,1]
	v_pk_add_f32 v[14:15], v[114:115], v[116:117] op_sel:[0,1] op_sel_hi:[1,0] neg_hi:[0,1]
	v_pk_mul_f32 v[68:69], v[58:59], s[36:37]
	v_pk_add_f32 v[38:39], v[114:115], v[116:117] op_sel:[0,1] op_sel_hi:[1,0] neg_lo:[0,1]
	v_pk_fma_f32 v[58:59], v[58:59], s[78:79], v[68:69] op_sel:[0,0,1] op_sel_hi:[1,0,0]
	v_pk_add_f32 v[68:69], v[62:63], v[80:81]
	v_pk_add_f32 v[80:81], v[62:63], v[80:81] neg_lo:[0,1] neg_hi:[0,1]
	s_waitcnt vmcnt(0)
	v_cvt_f32_f16_e32 v193, v33
	s_nop 0
	s_nop 0
	v_pk_add_f32 v[62:63], v[64:65], v[82:83]
	v_pk_add_f32 v[64:65], v[64:65], v[82:83] neg_lo:[0,1] neg_hi:[0,1]
	v_cvt_f32_f16_sdwa v192, v32 dst_sel:DWORD dst_unused:UNUSED_PAD src0_sel:WORD_1
	v_pk_mul_f32 v[82:83], v[64:65], s[36:37]
	v_cvt_f32_f16_e32 v194, v32
	v_pk_fma_f32 v[64:65], v[64:65], s[78:79], v[82:83] op_sel:[0,0,1] op_sel_hi:[1,0,0] neg_lo:[1,0,0] neg_hi:[1,0,0]
	v_pk_add_f32 v[82:83], v[48:49], v[78:79] op_sel:[0,1] op_sel_hi:[1,0] neg_hi:[0,1]
	v_pk_add_f32 v[48:49], v[48:49], v[78:79] op_sel:[0,1] op_sel_hi:[1,0] neg_lo:[0,1]
	v_pk_add_f32 v[78:79], v[50:51], v[70:71]
	v_pk_add_f32 v[50:51], v[50:51], v[70:71] neg_lo:[0,1] neg_hi:[0,1]
	v_cvt_f32_f16_sdwa v195, v33 dst_sel:DWORD dst_unused:UNUSED_PAD src0_sel:WORD_1
	v_pk_mul_f32 v[70:71], v[50:51], s[36:37]
	v_cvt_f32_f16_sdwa v170, v30 dst_sel:DWORD dst_unused:UNUSED_PAD src0_sel:WORD_1
	v_pk_fma_f32 v[50:51], v[50:51], s[78:79], v[70:71] op_sel:[0,0,1] op_sel_hi:[1,0,0]
	v_pk_add_f32 v[70:71], v[52:53], v[72:73]
	v_pk_add_f32 v[72:73], v[52:53], v[72:73] neg_lo:[0,1] neg_hi:[0,1]
	v_cvt_f32_f16_e32 v171, v31
	s_nop 0
	s_nop 0
	v_pk_add_f32 v[52:53], v[54:55], v[74:75]
	v_pk_add_f32 v[54:55], v[54:55], v[74:75] neg_lo:[0,1] neg_hi:[0,1]
	v_cvt_f32_f16_sdwa v185, v31 dst_sel:DWORD dst_unused:UNUSED_PAD src0_sel:WORD_1
	v_pk_mul_f32 v[74:75], v[54:55], s[36:37]
	v_cvt_f32_f16_e32 v184, v30
	v_pk_fma_f32 v[54:55], v[54:55], s[78:79], v[74:75] op_sel:[0,0,1] op_sel_hi:[1,0,0] neg_lo:[1,0,0] neg_hi:[1,0,0]
	v_pk_add_f32 v[74:75], v[90:91], v[68:69]
	v_pk_add_f32 v[68:69], v[90:91], v[68:69] neg_lo:[0,1] neg_hi:[0,1]
	v_pk_add_f32 v[90:91], v[76:77], v[62:63]
	v_pk_add_f32 v[62:63], v[76:77], v[62:63] neg_lo:[0,1] neg_hi:[0,1]
	v_cvt_f32_f16_sdwa v172, v28 dst_sel:DWORD dst_unused:UNUSED_PAD src0_sel:WORD_1
	v_pk_mul_f32 v[76:77], v[62:63], 1.0 op_sel:[1,0] op_sel_hi:[0,0] neg_hi:[1,0]
	s_nop 0
	v_pk_add_f32 v[62:63], v[56:57], v[80:81] op_sel:[0,1] op_sel_hi:[1,0] neg_hi:[0,1]
	v_pk_add_f32 v[56:57], v[56:57], v[80:81] op_sel:[0,1] op_sel_hi:[1,0] neg_lo:[0,1]
	v_pk_add_f32 v[80:81], v[58:59], v[64:65]
	v_pk_add_f32 v[58:59], v[58:59], v[64:65] neg_lo:[0,1] neg_hi:[0,1]
	v_cvt_f32_f16_e32 v173, v29
	v_pk_mul_f32 v[64:65], v[58:59], 1.0 op_sel:[1,0] op_sel_hi:[0,0] neg_hi:[1,0]
	v_pk_add_f32 v[58:59], v[82:83], v[70:71]
	v_pk_add_f32 v[70:71], v[82:83], v[70:71] neg_lo:[0,1] neg_hi:[0,1]
	v_pk_add_f32 v[82:83], v[78:79], v[52:53]
	v_pk_add_f32 v[52:53], v[78:79], v[52:53] neg_lo:[0,1] neg_hi:[0,1]
	v_pk_add_f32 v[118:119], v[58:59], v[82:83]
	v_pk_add_f32 v[134:135], v[58:59], v[82:83] neg_lo:[0,1] neg_hi:[0,1]
	v_cos_f32_e32 v83, v18
	v_sin_f32_e32 v82, v18
	v_cvt_f32_f16_sdwa v181, v29 dst_sel:DWORD dst_unused:UNUSED_PAD src0_sel:WORD_1
	v_cvt_f32_f16_e32 v180, v28
	v_cvt_f32_f16_sdwa v167, v13 dst_sel:DWORD dst_unused:UNUSED_PAD src0_sel:WORD_1
	v_cvt_f32_f16_e32 v166, v12
	v_cvt_f32_f16_e32 v154, v6
	v_cvt_f32_f16_e32 v155, v7
	v_cvt_f32_f16_sdwa v157, v7 dst_sel:DWORD dst_unused:UNUSED_PAD src0_sel:WORD_1
	v_cvt_f32_f16_sdwa v156, v6 dst_sel:DWORD dst_unused:UNUSED_PAD src0_sel:WORD_1
	v_cvt_f32_f16_sdwa v140, v4 dst_sel:DWORD dst_unused:UNUSED_PAD src0_sel:WORD_1
	v_cvt_f32_f16_e32 v141, v5
	v_cvt_f32_f16_sdwa v143, v5 dst_sel:DWORD dst_unused:UNUSED_PAD src0_sel:WORD_1
	v_cvt_f32_f16_e32 v142, v4
	v_cvt_f32_f16_e32 v124, v16
	v_cvt_f32_f16_e32 v125, v17
	v_cvt_f32_f16_sdwa v127, v17 dst_sel:DWORD dst_unused:UNUSED_PAD src0_sel:WORD_1
	v_cvt_f32_f16_sdwa v126, v16 dst_sel:DWORD dst_unused:UNUSED_PAD src0_sel:WORD_1
	v_cvt_f32_f16_sdwa v114, v122 dst_sel:DWORD dst_unused:UNUSED_PAD src0_sel:WORD_1
	v_cvt_f32_f16_e32 v115, v123
	v_cvt_f32_f16_sdwa v117, v123 dst_sel:DWORD dst_unused:UNUSED_PAD src0_sel:WORD_1
	v_cvt_f32_f16_e32 v116, v122
	v_pk_mul_f32 v[78:79], v[52:53], 1.0 op_sel:[1,0] op_sel_hi:[0,0] neg_hi:[1,0]
	s_nop 0
	v_pk_add_f32 v[52:53], v[48:49], v[72:73] op_sel:[0,1] op_sel_hi:[1,0] neg_hi:[0,1]
	v_pk_add_f32 v[48:49], v[48:49], v[72:73] op_sel:[0,1] op_sel_hi:[1,0] neg_lo:[0,1]
	v_pk_add_f32 v[72:73], v[50:51], v[54:55]
	v_pk_add_f32 v[50:51], v[50:51], v[54:55] neg_lo:[0,1] neg_hi:[0,1]
	v_pk_fma_f32 v[160:161], v[82:83], 0, v[82:83] op_sel:[0,0,1] op_sel_hi:[1,0,0] neg_lo:[1,0,0] neg_hi:[1,0,0]
	v_pk_mul_f32 v[54:55], v[50:51], 1.0 op_sel:[1,0] op_sel_hi:[0,0] neg_hi:[1,0]
	v_pk_fma_f32 v[198:199], v[82:83], 0, v[82:83] op_sel:[0,0,1] op_sel_hi:[1,0,0]
	v_pk_add_f32 v[42:43], v[112:113], v[22:23]
	v_pk_add_f32 v[22:23], v[112:113], v[22:23] neg_lo:[0,1] neg_hi:[0,1]
	v_pk_add_f32 v[98:99], v[74:75], v[90:91]
	v_pk_add_f32 v[100:101], v[74:75], v[90:91] neg_lo:[0,1] neg_hi:[0,1]
	v_pk_add_f32 v[102:103], v[68:69], v[76:77]
	v_pk_add_f32 v[106:107], v[68:69], v[76:77] neg_lo:[0,1] neg_hi:[0,1]
	v_pk_add_f32 v[104:105], v[62:63], v[80:81]
	v_pk_add_f32 v[108:109], v[62:63], v[80:81] neg_lo:[0,1] neg_hi:[0,1]
	v_pk_add_f32 v[110:111], v[56:57], v[64:65]
	v_pk_add_f32 v[112:113], v[56:57], v[64:65] neg_lo:[0,1] neg_hi:[0,1]
	v_pk_add_f32 v[152:153], v[70:71], v[78:79]
	v_pk_add_f32 v[162:163], v[70:71], v[78:79] neg_lo:[0,1] neg_hi:[0,1]
	v_pk_add_f32 v[178:179], v[52:53], v[72:73]
	v_pk_add_f32 v[182:183], v[52:53], v[72:73] neg_lo:[0,1] neg_hi:[0,1]
	v_pk_add_f32 v[188:189], v[48:49], v[54:55]
	v_pk_add_f32 v[196:197], v[48:49], v[54:55] neg_lo:[0,1] neg_hi:[0,1]
	v_pk_mul_f32 v[186:187], v[82:83], 0 op_sel_hi:[1,0]
	v_pk_mov_b32 v[190:191], v[160:161], v[198:199] op_sel:[0,1]
	v_mul_f32_e32 v18, 0x3f3504f3, v83
	v_mul_f32_e32 v158, 0xbec3ef15, v83
	v_mul_f32_e32 v132, 0xbf6c835e, v83
	s_and_saveexec_b64 s[0:1], vcc
	s_xor_b64 s[0:1], exec, s[0:1]
	s_cbranch_execz .LBB0_501
	v_pk_add_f32 v[4:5], v[148:149], v[196:197]
	v_pk_add_f32 v[6:7], v[148:149], v[196:197] neg_lo:[0,1] neg_hi:[0,1]
	v_mul_f32_e32 v4, 0.5, v4
	v_mul_f32_e32 v12, 0.5, v7
	v_mov_b32_e32 v7, v5
	v_pk_mul_f32 v[6:7], v[6:7], s[44:45]
	v_pk_mov_b32 v[16:17], v[198:199], v[160:161] op_sel:[1,0]
	v_pk_mul_f32 v[24:25], v[190:191], v[6:7] op_sel:[0,1] op_sel_hi:[1,0]
	v_pk_mul_f32 v[6:7], v[190:191], v[6:7]
	v_pk_add_f32 v[24:25], v[24:25], v[24:25] op_sel:[0,1] op_sel_hi:[0,1]
	v_pk_add_f32 v[28:29], v[4:5], v[24:25] op_sel_hi:[0,1] neg_hi:[0,1]
	v_pk_add_f32 v[4:5], v[6:7], v[6:7] op_sel:[0,1] op_sel_hi:[0,1] neg_lo:[0,1] neg_hi:[0,1]
	v_pk_add_f32 v[6:7], v[12:13], v[4:5] op_sel_hi:[0,1] neg_hi:[0,1]
	v_pk_mul_f32 v[4:5], v[6:7], v[194:195]
	v_pk_mul_f32 v[6:7], v[6:7], v[192:193]
	v_pk_fma_f32 v[4:5], v[28:29], v[192:193], v[4:5]
	v_pk_fma_f32 v[6:7], v[28:29], v[194:195], v[6:7] neg_lo:[0,0,1] neg_hi:[0,0,1]
	s_mov_b32 s78, s19
	v_pk_add_f32 v[12:13], v[6:7], v[4:5] op_sel:[0,1] op_sel_hi:[1,0] neg_lo:[0,1]
	v_pk_add_f32 v[28:29], v[6:7], v[4:5] op_sel:[0,1] op_sel_hi:[1,0]
	v_pk_add_f32 v[4:5], v[4:5], v[6:7] op_sel:[1,0] op_sel_hi:[0,1] neg_lo:[0,1] neg_hi:[0,1]
	s_nop 0
	v_pk_mul_f32 v[12:13], v[12:13], 0.5 op_sel_hi:[1,0]
	v_mov_b32_e32 v29, v5
	v_mul_f32_e32 v24, v190, v12
	v_pk_fma_f32 v[30:31], v[190:191], v[12:13], v[24:25] op_sel_hi:[1,1,0] neg_lo:[1,0,0] neg_hi:[1,0,0]
	v_mul_f32_e32 v24, v160, v13
	v_pk_fma_f32 v[12:13], v[16:17], v[12:13], v[24:25] op_sel_hi:[1,1,0]
	v_mov_b32_e32 v16, v83
	v_mov_b32_e32 v30, v12
	v_pk_fma_f32 v[4:5], v[28:29], 0.5, v[12:13] op_sel_hi:[1,0,1] neg_lo:[0,0,1] neg_hi:[0,0,1]
	v_pk_fma_f32 v[122:123], v[28:29], 0.5, v[30:31] op_sel_hi:[1,0,1]
	v_pk_fma_f32 v[6:7], v[28:29], 0.5, v[30:31] op_sel_hi:[1,0,1] neg_lo:[1,0,0] neg_hi:[1,0,0]
	v_mov_b32_e32 v5, v123
	v_pk_mul_f32 v[24:25], v[4:5], s[6:7] op_sel_hi:[1,0]
	v_pk_add_f32 v[4:5], v[138:139], v[188:189]
	v_pk_add_f32 v[12:13], v[138:139], v[188:189] neg_lo:[0,1] neg_hi:[0,1]
	v_mov_b32_e32 v17, v82
	v_mul_f32_e32 v6, 0.5, v13
	v_pk_add_f32 v[28:29], v[186:187], v[16:17] neg_lo:[0,1] neg_hi:[0,1]
	v_pk_add_f32 v[30:31], v[186:187], v[16:17]
	v_mov_b32_e32 v13, v5
	v_pk_mov_b32 v[32:33], v[28:29], v[30:31] op_sel:[1,0]
	v_pk_mul_f32 v[12:13], v[12:13], s[44:45]
	v_mul_f32_e32 v4, 0.5, v4
	v_pk_mul_f32 v[48:49], v[32:33], v[12:13] op_sel:[0,1] op_sel_hi:[1,0]
	v_pk_mul_f32 v[12:13], v[32:33], v[12:13]
	v_pk_add_f32 v[48:49], v[48:49], v[48:49] op_sel:[0,1] op_sel_hi:[0,1]
	v_pk_add_f32 v[50:51], v[4:5], v[48:49] op_sel_hi:[0,1] neg_hi:[0,1]
	v_pk_add_f32 v[4:5], v[12:13], v[12:13] op_sel:[0,1] op_sel_hi:[0,1] neg_lo:[0,1] neg_hi:[0,1]
	v_pk_add_f32 v[12:13], v[6:7], v[4:5] op_sel_hi:[0,1] neg_hi:[0,1]
	v_pk_mul_f32 v[4:5], v[12:13], v[184:185]
	v_pk_mul_f32 v[12:13], v[12:13], v[170:171]
	v_pk_fma_f32 v[4:5], v[50:51], v[170:171], v[4:5]
	v_pk_fma_f32 v[12:13], v[50:51], v[184:185], v[12:13] neg_lo:[0,0,1] neg_hi:[0,0,1]
	v_mov_b32_e32 v31, v29
	v_pk_add_f32 v[48:49], v[12:13], v[4:5] op_sel:[0,1] op_sel_hi:[1,0] neg_lo:[0,1]
	v_pk_add_f32 v[50:51], v[12:13], v[4:5] op_sel:[0,1] op_sel_hi:[1,0]
	v_pk_add_f32 v[4:5], v[4:5], v[12:13] op_sel:[1,0] op_sel_hi:[0,1] neg_lo:[0,1] neg_hi:[0,1]
	v_pk_mul_f32 v[48:49], v[48:49], 0.5 op_sel_hi:[1,0]
	v_mov_b32_e32 v51, v5
	v_mul_f32_e32 v6, v29, v48
	v_pk_fma_f32 v[32:33], v[32:33], v[48:49], v[6:7] op_sel_hi:[1,1,0] neg_lo:[1,0,0] neg_hi:[1,0,0]
	v_mul_f32_e32 v6, v29, v49
	v_pk_fma_f32 v[28:29], v[30:31], v[48:49], v[6:7] op_sel_hi:[1,1,0]
	v_pk_mul_f32 v[12:13], v[16:17], s[36:37]
	v_mov_b32_e32 v32, v28
	v_pk_fma_f32 v[4:5], v[50:51], 0.5, v[28:29] op_sel_hi:[1,0,1] neg_lo:[0,0,1] neg_hi:[0,0,1]
	v_pk_fma_f32 v[138:139], v[50:51], 0.5, v[32:33] op_sel_hi:[1,0,1]
	v_pk_add_f32 v[16:17], v[92:93], v[182:183]
	v_mov_b32_e32 v5, v139
	v_pk_add_f32 v[28:29], v[92:93], v[182:183] neg_lo:[0,1] neg_hi:[0,1]
	v_pk_mul_f32 v[30:31], v[4:5], s[6:7] op_sel_hi:[1,0]
	v_pk_fma_f32 v[4:5], v[50:51], 0.5, v[32:33] op_sel_hi:[1,0,1] neg_lo:[1,0,0] neg_hi:[1,0,0]
	v_mul_f32_e32 v6, 0.5, v29
	v_pk_add_f32 v[32:33], v[18:19], v[12:13] op_sel:[0,1] op_sel_hi:[0,1] neg_lo:[0,1] neg_hi:[0,1]
	v_pk_add_f32 v[48:49], v[18:19], v[12:13] op_sel:[0,1] op_sel_hi:[0,1]
	v_mov_b32_e32 v29, v17
	v_mul_f32_e32 v4, 0.5, v16
	v_pk_mov_b32 v[50:51], v[32:33], v[48:49] op_sel:[0,1]
	v_pk_mul_f32 v[16:17], v[28:29], s[44:45]
	v_pk_mov_b32 v[48:49], v[48:49], v[32:33] op_sel:[1,0]
	v_pk_mul_f32 v[28:29], v[50:51], v[16:17] op_sel:[0,1] op_sel_hi:[1,0]
	v_pk_mul_f32 v[16:17], v[50:51], v[16:17]
	v_pk_add_f32 v[28:29], v[28:29], v[28:29] op_sel:[0,1] op_sel_hi:[0,1]
	v_pk_add_f32 v[52:53], v[4:5], v[28:29] op_sel_hi:[0,1] neg_hi:[0,1]
	v_pk_add_f32 v[16:17], v[16:17], v[16:17] op_sel:[0,1] op_sel_hi:[0,1] neg_lo:[0,1] neg_hi:[0,1]
	v_pk_add_f32 v[28:29], v[6:7], v[16:17] op_sel_hi:[0,1] neg_hi:[0,1]
	v_pk_mul_f32 v[16:17], v[28:29], v[180:181]
	v_pk_mul_f32 v[28:29], v[28:29], v[172:173]
	v_pk_fma_f32 v[16:17], v[52:53], v[172:173], v[16:17]
	v_pk_fma_f32 v[28:29], v[52:53], v[180:181], v[28:29] neg_lo:[0,0,1] neg_hi:[0,0,1]
	v_sub_f32_e32 v6, v89, v179
	v_pk_add_f32 v[52:53], v[28:29], v[16:17] op_sel:[0,1] op_sel_hi:[1,0] neg_lo:[0,1]
	v_pk_add_f32 v[54:55], v[28:29], v[16:17] op_sel:[0,1] op_sel_hi:[1,0]
	v_pk_add_f32 v[16:17], v[16:17], v[28:29] op_sel:[1,0] op_sel_hi:[0,1] neg_lo:[0,1] neg_hi:[0,1]
	v_pk_mul_f32 v[52:53], v[52:53], 0.5 op_sel_hi:[1,0]
	v_mov_b32_e32 v55, v17
	v_mul_f32_e32 v4, v32, v52
	v_pk_fma_f32 v[56:57], v[50:51], v[52:53], v[4:5] op_sel_hi:[1,1,0] neg_lo:[1,0,0] neg_hi:[1,0,0]
	v_mul_f32_e32 v4, v32, v53
	v_pk_fma_f32 v[48:49], v[48:49], v[52:53], v[4:5] op_sel_hi:[1,1,0]
	v_pk_add_f32 v[28:29], v[88:89], v[178:179]
	v_mov_b32_e32 v56, v48
	v_pk_fma_f32 v[16:17], v[54:55], 0.5, v[48:49] op_sel_hi:[1,0,1] neg_lo:[0,0,1] neg_hi:[0,0,1]
	v_pk_mov_b32 v[48:49], v[12:13], v[88:89] op_sel:[0,0]
	v_pk_mov_b32 v[12:13], v[12:13], v[178:179] op_sel:[1,0]
	v_mul_f32_e32 v18, 0.5, v29
	v_pk_add_f32 v[12:13], v[48:49], v[12:13] neg_lo:[0,1] neg_hi:[0,1]
	v_mul_f32_e32 v4, 0.5, v28
	v_pk_mul_f32 v[48:49], v[12:13], v[18:19]
	v_mov_b32_e32 v13, v32
	v_pk_fma_f32 v[50:51], v[50:51], v[48:49], v[48:49] op_sel:[0,1,0] op_sel_hi:[1,0,1]
	v_mov_b32_e32 v48, v49
	v_mov_b32_e32 v49, v18
	v_pk_mul_f32 v[48:49], v[12:13], v[48:49]
	v_pk_add_f32 v[52:53], v[4:5], v[50:51]
	v_mul_f32_e32 v6, 0.5, v6
	v_fma_f32 v53, v28, 0.5, -v50
	v_pk_add_f32 v[28:29], v[48:49], v[48:49] op_sel:[0,1] op_sel_hi:[0,1] neg_lo:[0,1] neg_hi:[0,1]
	v_pk_add_f32 v[48:49], v[6:7], v[28:29] op_sel_hi:[0,1] neg_hi:[0,1]
	v_pk_mul_f32 v[28:29], v[48:49], v[176:177]
	v_pk_mul_f32 v[48:49], v[48:49], v[174:175]
	v_pk_fma_f32 v[28:29], v[52:53], v[174:175], v[28:29]
	v_pk_fma_f32 v[48:49], v[52:53], v[176:177], v[48:49] neg_lo:[0,0,1] neg_hi:[0,0,1]
	v_pk_fma_f32 v[92:93], v[54:55], 0.5, v[56:57] op_sel_hi:[1,0,1]
	v_pk_add_f32 v[50:51], v[48:49], v[28:29] op_sel:[0,1] op_sel_hi:[1,0] neg_lo:[0,1]
	v_pk_add_f32 v[52:53], v[48:49], v[28:29] op_sel:[0,1] op_sel_hi:[1,0]
	v_mov_b32_e32 v17, v93
	v_pk_mul_f32 v[50:51], v[50:51], 0.5 op_sel_hi:[1,0]
	v_pk_mul_f32 v[64:65], v[16:17], s[6:7] op_sel_hi:[1,0]
	v_mul_f32_e32 v4, v12, v50
	v_pk_fma_f32 v[16:17], v[54:55], 0.5, v[56:57] op_sel_hi:[1,0,1] neg_lo:[1,0,0] neg_hi:[1,0,0]
	v_pk_fma_f32 v[54:55], v[12:13], v[50:51], v[4:5] op_sel_hi:[1,1,0] neg_lo:[1,0,0] neg_hi:[1,0,0]
	v_mov_b32_e32 v33, v12
	v_mul_f32_e32 v4, v12, v51
	v_pk_fma_f32 v[12:13], v[32:33], v[50:51], v[4:5] op_sel_hi:[1,1,0]
	v_pk_add_f32 v[28:29], v[28:29], v[48:49] op_sel:[1,0] op_sel_hi:[0,1] neg_lo:[0,1] neg_hi:[0,1]
	v_mov_b32_e32 v53, v29
	v_mov_b32_e32 v54, v12
	v_pk_fma_f32 v[12:13], v[52:53], 0.5, v[12:13] op_sel_hi:[1,0,1] neg_lo:[0,0,1] neg_hi:[0,0,1]
	v_pk_fma_f32 v[88:89], v[52:53], 0.5, v[54:55] op_sel_hi:[1,0,1]
	s_mov_b32 s79, s16
	v_mov_b32_e32 v13, v89
	v_pk_mul_f32 v[68:69], v[12:13], s[6:7] op_sel_hi:[1,0]
	v_pk_fma_f32 v[12:13], v[52:53], 0.5, v[54:55] op_sel_hi:[1,0,1] neg_lo:[1,0,0] neg_hi:[1,0,0]
	v_mov_b32_e32 v4, v83
	s_mov_b32 s17, s19
	v_pk_mul_f32 v[48:49], v[82:83], s[78:79] op_sel_hi:[0,1]
	v_pk_add_f32 v[28:29], v[96:97], v[162:163]
	v_pk_add_f32 v[32:33], v[96:97], v[162:163] neg_lo:[0,1] neg_hi:[0,1]
	v_pk_fma_f32 v[52:53], v[4:5], s[16:17], v[48:49] op_sel_hi:[0,1,1] neg_lo:[0,0,1] neg_hi:[0,0,1]
	v_mul_f32_e32 v12, 0.5, v33
	v_pk_fma_f32 v[50:51], v[4:5], s[16:17], v[48:49] op_sel_hi:[0,1,1]
	v_mov_b32_e32 v33, v29
	v_mul_f32_e32 v6, 0.5, v28
	v_pk_mov_b32 v[54:55], v[52:53], v[50:51] op_sel:[0,1]
	v_pk_mul_f32 v[28:29], v[32:33], s[44:45]
	v_pk_mov_b32 v[56:57], v[50:51], v[52:53] op_sel:[1,0]
	v_pk_mul_f32 v[32:33], v[54:55], v[28:29] op_sel:[0,1] op_sel_hi:[1,0]
	v_pk_mul_f32 v[28:29], v[54:55], v[28:29]
	v_pk_add_f32 v[32:33], v[32:33], v[32:33] op_sel:[0,1] op_sel_hi:[0,1]
	v_pk_add_f32 v[58:59], v[6:7], v[32:33] op_sel_hi:[0,1] neg_hi:[0,1]
	v_pk_add_f32 v[28:29], v[28:29], v[28:29] op_sel:[0,1] op_sel_hi:[0,1] neg_lo:[0,1] neg_hi:[0,1]
	v_pk_add_f32 v[32:33], v[12:13], v[28:29] op_sel_hi:[0,1] neg_hi:[0,1]
	v_pk_mul_f32 v[28:29], v[32:33], v[166:167]
	v_pk_mul_f32 v[32:33], v[32:33], v[164:165]
	v_pk_fma_f32 v[28:29], v[58:59], v[164:165], v[28:29]
	v_pk_fma_f32 v[32:33], v[58:59], v[166:167], v[32:33] neg_lo:[0,0,1] neg_hi:[0,0,1]
	v_mov_b32_e32 v159, v66
	v_pk_add_f32 v[58:59], v[32:33], v[28:29] op_sel:[0,1] op_sel_hi:[1,0] neg_lo:[0,1]
	v_pk_add_f32 v[70:71], v[32:33], v[28:29] op_sel:[0,1] op_sel_hi:[1,0]
	v_pk_add_f32 v[28:29], v[28:29], v[32:33] op_sel:[1,0] op_sel_hi:[0,1] neg_lo:[0,1] neg_hi:[0,1]
	v_pk_mul_f32 v[58:59], v[58:59], 0.5 op_sel_hi:[1,0]
	v_mov_b32_e32 v71, v29
	v_mul_f32_e32 v6, v52, v58
	v_pk_fma_f32 v[72:73], v[54:55], v[58:59], v[6:7] op_sel_hi:[1,1,0] neg_lo:[1,0,0] neg_hi:[1,0,0]
	v_mul_f32_e32 v6, v52, v59
	v_pk_fma_f32 v[56:57], v[56:57], v[58:59], v[6:7] op_sel_hi:[1,1,0]
	v_sub_f32_e32 v12, v67, v153
	v_mov_b32_e32 v72, v56
	v_pk_fma_f32 v[28:29], v[70:71], 0.5, v[56:57] op_sel_hi:[1,0,1] neg_lo:[0,0,1] neg_hi:[0,0,1]
	v_pk_fma_f32 v[96:97], v[70:71], 0.5, v[72:73] op_sel_hi:[1,0,1]
	v_pk_mov_b32 v[56:57], v[48:49], v[152:153] op_sel:[1,0]
	v_mov_b32_e32 v29, v97
	v_pk_mul_f32 v[62:63], v[28:29], s[6:7] op_sel_hi:[1,0]
	v_pk_add_f32 v[28:29], v[66:67], v[152:153]
	v_pk_add_f32 v[56:57], v[158:159], v[56:57] neg_lo:[0,1] neg_hi:[0,1]
	v_mul_f32_e32 v18, 0.5, v29
	v_pk_mul_f32 v[58:59], v[56:57], v[18:19]
	v_mul_f32_e32 v6, 0.5, v28
	v_pk_fma_f32 v[54:55], v[54:55], v[58:59], v[58:59] op_sel:[0,1,0] op_sel_hi:[1,0,1]
	v_pk_mov_b32 v[66:67], v[56:57], v[52:53] op_sel:[0,0]
	v_mov_b32_e32 v58, v59
	v_mov_b32_e32 v59, v18
	v_pk_mul_f32 v[58:59], v[66:67], v[58:59]
	v_pk_add_f32 v[66:67], v[6:7], v[54:55]
	v_mul_f32_e32 v12, 0.5, v12
	v_fma_f32 v67, v28, 0.5, -v54
	v_pk_add_f32 v[28:29], v[58:59], v[58:59] op_sel:[0,1] op_sel_hi:[0,1] neg_lo:[0,1] neg_hi:[0,1]
	v_pk_add_f32 v[54:55], v[12:13], v[28:29] op_sel_hi:[0,1] neg_hi:[0,1]
	v_pk_mul_f32 v[28:29], v[54:55], v[156:157]
	v_pk_mul_f32 v[54:55], v[54:55], v[154:155]
	v_pk_fma_f32 v[32:33], v[70:71], 0.5, v[72:73] op_sel_hi:[1,0,1] neg_lo:[1,0,0] neg_hi:[1,0,0]
	v_pk_fma_f32 v[58:59], v[66:67], v[154:155], v[28:29] neg_lo:[0,0,1] neg_hi:[0,0,1]
	v_pk_fma_f32 v[28:29], v[66:67], v[154:155], v[28:29]
	v_pk_fma_f32 v[70:71], v[66:67], v[156:157], v[54:55]
	v_pk_fma_f32 v[54:55], v[66:67], v[156:157], v[54:55] neg_lo:[0,0,1] neg_hi:[0,0,1]
	v_pk_add_f32 v[72:73], v[58:59], v[28:29] op_sel:[0,1] op_sel_hi:[1,0]
	v_pk_add_f32 v[66:67], v[70:71], v[54:55] op_sel_hi:[0,1] neg_lo:[0,1] neg_hi:[0,1]
	v_pk_add_f32 v[28:29], v[58:59], v[28:29] op_sel_hi:[0,1] neg_lo:[0,1] neg_hi:[0,1]
	v_pk_add_f32 v[54:55], v[70:71], v[54:55] op_sel:[0,1] op_sel_hi:[1,0]
	v_mov_b32_e32 v73, v67
	v_mov_b32_e32 v55, v29
	v_pk_mul_f32 v[28:29], v[54:55], 0.5 op_sel_hi:[1,0]
	v_mov_b32_e32 v133, v84
	v_pk_mul_f32 v[54:55], v[52:53], v[28:29] op_sel:[0,1] op_sel_hi:[0,0]
	v_pk_fma_f32 v[58:59], v[56:57], v[28:29], v[54:55] op_sel_hi:[0,1,1]
	v_pk_fma_f32 v[28:29], v[56:57], v[28:29], v[54:55] op_sel_hi:[0,1,1] neg_hi:[0,0,1]
	v_pk_fma_f32 v[54:55], v[72:73], 0.5, v[58:59] op_sel_hi:[1,0,1] neg_lo:[0,0,1] neg_hi:[0,0,1]
	v_pk_fma_f32 v[66:67], v[72:73], 0.5, v[28:29] op_sel_hi:[1,0,1]
	v_pk_add_f32 v[56:57], v[60:61], v[134:135] neg_lo:[0,1] neg_hi:[0,1]
	v_mov_b32_e32 v55, v67
	v_pk_mul_f32 v[90:91], v[54:55], s[6:7] op_sel_hi:[1,0]
	v_pk_add_f32 v[54:55], v[134:135], v[60:61]
	v_mul_f32_e32 v12, 0.5, v57
	v_mov_b32_e32 v57, v55
	v_mul_f32_e32 v6, 0.5, v54
	v_pk_mov_b32 v[58:59], v[52:53], v[50:51] op_sel:[1,0]
	v_pk_mul_f32 v[54:55], v[56:57], s[44:45]
	v_pk_fma_f32 v[28:29], v[72:73], 0.5, v[28:29] op_sel_hi:[1,0,1] neg_lo:[1,0,0] neg_hi:[1,0,0]
	v_pk_mul_f32 v[56:57], v[58:59], v[54:55] op_sel:[0,1] op_sel_hi:[1,0]
	v_pk_mul_f32 v[54:55], v[58:59], v[54:55]
	v_pk_add_f32 v[56:57], v[56:57], v[56:57] op_sel:[0,1] op_sel_hi:[0,1]
	v_pk_add_f32 v[60:61], v[6:7], v[56:57] op_sel_hi:[0,1] neg_hi:[0,1]
	v_pk_add_f32 v[54:55], v[54:55], v[54:55] op_sel:[0,1] op_sel_hi:[0,1] neg_lo:[0,1] neg_hi:[0,1]
	v_pk_add_f32 v[56:57], v[12:13], v[54:55] op_sel_hi:[0,1] neg_hi:[0,1]
	v_pk_mul_f32 v[54:55], v[56:57], v[142:143]
	v_pk_mul_f32 v[56:57], v[56:57], v[140:141]
	v_pk_fma_f32 v[54:55], v[60:61], v[140:141], v[54:55]
	v_pk_fma_f32 v[56:57], v[60:61], v[142:143], v[56:57] neg_lo:[0,0,1] neg_hi:[0,0,1]
	v_mov_b32_e32 v51, v53
	v_pk_add_f32 v[60:61], v[56:57], v[54:55] op_sel:[0,1] op_sel_hi:[1,0] neg_lo:[0,1]
	v_pk_add_f32 v[70:71], v[56:57], v[54:55] op_sel:[0,1] op_sel_hi:[1,0]
	v_pk_add_f32 v[54:55], v[54:55], v[56:57] op_sel:[1,0] op_sel_hi:[0,1] neg_lo:[0,1] neg_hi:[0,1]
	v_pk_mul_f32 v[60:61], v[60:61], 0.5 op_sel_hi:[1,0]
	v_mov_b32_e32 v71, v55
	v_mul_f32_e32 v6, v53, v60
	v_pk_fma_f32 v[72:73], v[58:59], v[60:61], v[6:7] op_sel_hi:[1,1,0] neg_lo:[1,0,0] neg_hi:[1,0,0]
	v_mul_f32_e32 v6, v53, v61
	v_pk_fma_f32 v[50:51], v[50:51], v[60:61], v[6:7] op_sel_hi:[1,1,0]
	v_pk_add_f32 v[54:55], v[118:119], v[84:85]
	v_mov_b32_e32 v72, v50
	v_mov_b32_e32 v49, v118
	v_pk_fma_f32 v[50:51], v[70:71], 0.5, v[50:51] op_sel_hi:[1,0,1] neg_lo:[0,0,1] neg_hi:[0,0,1]
	v_pk_fma_f32 v[60:61], v[70:71], 0.5, v[72:73] op_sel_hi:[1,0,1]
	v_mul_f32_e32 v18, 0.5, v55
	v_pk_add_f32 v[48:49], v[132:133], v[48:49] neg_lo:[0,1] neg_hi:[0,1]
	v_mov_b32_e32 v51, v61
	v_pk_mul_f32 v[56:57], v[48:49], v[18:19]
	v_pk_mul_f32 v[94:95], v[50:51], s[6:7] op_sel_hi:[1,0]
	v_pk_fma_f32 v[50:51], v[70:71], 0.5, v[72:73] op_sel_hi:[1,0,1] neg_lo:[1,0,0] neg_hi:[1,0,0]
	v_mul_f32_e32 v6, 0.5, v54
	v_pk_fma_f32 v[58:59], v[58:59], v[56:57], v[56:57] op_sel:[0,1,0] op_sel_hi:[1,0,1]
	v_pk_mov_b32 v[70:71], v[48:49], v[52:53] op_sel:[0,1]
	v_mov_b32_e32 v56, v57
	v_mov_b32_e32 v57, v18
	v_sub_f32_e32 v12, v85, v119
	v_pk_mul_f32 v[56:57], v[70:71], v[56:57]
	v_pk_add_f32 v[70:71], v[6:7], v[58:59]
	v_mul_f32_e32 v12, 0.5, v12
	v_fma_f32 v71, v54, 0.5, -v58
	v_pk_add_f32 v[54:55], v[56:57], v[56:57] op_sel:[0,1] op_sel_hi:[0,1] neg_lo:[0,1] neg_hi:[0,1]
	v_pk_add_f32 v[56:57], v[12:13], v[54:55] op_sel_hi:[0,1] neg_hi:[0,1]
	v_pk_mul_f32 v[54:55], v[56:57], v[126:127]
	v_pk_mul_f32 v[56:57], v[56:57], v[124:125]
	v_pk_fma_f32 v[58:59], v[70:71], v[124:125], v[54:55] neg_lo:[0,0,1] neg_hi:[0,0,1]
	v_pk_fma_f32 v[54:55], v[70:71], v[124:125], v[54:55]
	v_pk_fma_f32 v[72:73], v[70:71], v[126:127], v[56:57]
	v_pk_fma_f32 v[56:57], v[70:71], v[126:127], v[56:57] neg_lo:[0,0,1] neg_hi:[0,0,1]
	v_pk_add_f32 v[70:71], v[58:59], v[54:55] op_sel:[0,1] op_sel_hi:[1,0]
	v_pk_add_f32 v[74:75], v[72:73], v[56:57] op_sel_hi:[0,1] neg_lo:[0,1] neg_hi:[0,1]
	v_pk_add_f32 v[54:55], v[58:59], v[54:55] op_sel_hi:[0,1] neg_lo:[0,1] neg_hi:[0,1]
	v_pk_add_f32 v[56:57], v[72:73], v[56:57] op_sel:[0,1] op_sel_hi:[1,0]
	v_mov_b32_e32 v71, v75
	v_mov_b32_e32 v57, v55
	v_pk_mul_f32 v[54:55], v[56:57], 0.5 op_sel_hi:[1,0]
	s_mov_b32 s78, s11
	v_pk_mul_f32 v[52:53], v[52:53], v[54:55] op_sel:[1,1] op_sel_hi:[1,0]
	s_mov_b32 s79, s8
	v_pk_fma_f32 v[56:57], v[48:49], v[54:55], v[52:53] op_sel_hi:[0,1,1]
	v_pk_fma_f32 v[48:49], v[48:49], v[54:55], v[52:53] op_sel_hi:[0,1,1] neg_hi:[0,0,1]
	s_nop 0
	v_pk_fma_f32 v[52:53], v[70:71], 0.5, v[56:57] op_sel_hi:[1,0,1] neg_lo:[0,0,1] neg_hi:[0,0,1]
	v_pk_fma_f32 v[84:85], v[70:71], 0.5, v[48:49] op_sel_hi:[1,0,1]
	s_mov_b32 s9, s11
	v_mov_b32_e32 v53, v85
	v_pk_mul_f32 v[80:81], v[52:53], s[6:7] op_sel_hi:[1,0]
	v_pk_mul_f32 v[118:119], v[82:83], s[78:79] op_sel_hi:[0,1]
	v_pk_add_f32 v[52:53], v[86:87], v[112:113]
	v_pk_add_f32 v[54:55], v[86:87], v[112:113] neg_lo:[0,1] neg_hi:[0,1]
	v_pk_fma_f32 v[58:59], v[4:5], s[8:9], v[118:119] op_sel_hi:[0,1,1] neg_lo:[0,0,1] neg_hi:[0,0,1]
	v_mul_f32_e32 v12, 0.5, v55
	v_pk_fma_f32 v[72:73], v[4:5], s[8:9], v[118:119] op_sel_hi:[0,1,1]
	v_mov_b32_e32 v55, v53
	v_mul_f32_e32 v6, 0.5, v52
	v_pk_mov_b32 v[56:57], v[58:59], v[72:73] op_sel:[0,1]
	v_pk_mul_f32 v[52:53], v[54:55], s[44:45]
	v_pk_fma_f32 v[48:49], v[70:71], 0.5, v[48:49] op_sel_hi:[1,0,1] neg_lo:[1,0,0] neg_hi:[1,0,0]
	v_pk_mul_f32 v[54:55], v[56:57], v[52:53] op_sel:[0,1] op_sel_hi:[1,0]
	v_pk_mul_f32 v[52:53], v[56:57], v[52:53]
	v_pk_add_f32 v[54:55], v[54:55], v[54:55] op_sel:[0,1] op_sel_hi:[0,1]
	v_pk_add_f32 v[74:75], v[6:7], v[54:55] op_sel_hi:[0,1] neg_hi:[0,1]
	v_pk_add_f32 v[52:53], v[52:53], v[52:53] op_sel:[0,1] op_sel_hi:[0,1] neg_lo:[0,1] neg_hi:[0,1]
	v_pk_add_f32 v[54:55], v[12:13], v[52:53] op_sel_hi:[0,1] neg_hi:[0,1]
	v_pk_mul_f32 v[52:53], v[54:55], v[116:117]
	v_pk_mul_f32 v[54:55], v[54:55], v[114:115]
	v_pk_fma_f32 v[52:53], v[74:75], v[114:115], v[52:53]
	v_pk_fma_f32 v[54:55], v[74:75], v[116:117], v[54:55] neg_lo:[0,0,1] neg_hi:[0,0,1]
	v_pk_mov_b32 v[70:71], v[72:73], v[58:59] op_sel:[1,0]
	v_pk_add_f32 v[74:75], v[54:55], v[52:53] op_sel:[0,1] op_sel_hi:[1,0] neg_lo:[0,1]
	v_pk_add_f32 v[76:77], v[54:55], v[52:53] op_sel:[0,1] op_sel_hi:[1,0]
	v_pk_add_f32 v[52:53], v[52:53], v[54:55] op_sel:[1,0] op_sel_hi:[0,1] neg_lo:[0,1] neg_hi:[0,1]
	v_pk_mul_f32 v[74:75], v[74:75], 0.5 op_sel_hi:[1,0]
	v_mov_b32_e32 v77, v53
	v_mul_f32_e32 v6, v58, v74
	v_pk_fma_f32 v[112:113], v[56:57], v[74:75], v[6:7] op_sel_hi:[1,1,0] neg_lo:[1,0,0] neg_hi:[1,0,0]
	v_mul_f32_e32 v6, v58, v75
	v_pk_fma_f32 v[70:71], v[70:71], v[74:75], v[6:7] op_sel_hi:[1,1,0]
	v_pk_add_f32 v[54:55], v[34:35], v[110:111]
	v_mov_b32_e32 v112, v70
	v_pk_fma_f32 v[52:53], v[76:77], 0.5, v[70:71] op_sel_hi:[1,0,1] neg_lo:[0,0,1] neg_hi:[0,0,1]
	v_pk_fma_f32 v[86:87], v[76:77], 0.5, v[112:113] op_sel_hi:[1,0,1]
	v_sub_f32_e32 v12, v35, v111
	v_mov_b32_e32 v53, v87
	v_pk_mul_f32 v[78:79], v[52:53], s[6:7] op_sel_hi:[1,0]
	v_mul_f32_e32 v52, 0xbe47c5c2, v83
	v_mov_b32_e32 v53, v34
	v_pk_mov_b32 v[34:35], v[118:119], v[110:111] op_sel:[1,0]
	v_mul_f32_e32 v18, 0.5, v55
	v_pk_add_f32 v[34:35], v[52:53], v[34:35] neg_lo:[0,1] neg_hi:[0,1]
	v_mov_b32_e32 v71, v58
	v_pk_mul_f32 v[52:53], v[34:35], v[18:19]
	v_mov_b32_e32 v70, v34
	v_pk_fma_f32 v[56:57], v[56:57], v[52:53], v[52:53] op_sel:[0,1,0] op_sel_hi:[1,0,1]
	v_mov_b32_e32 v52, v53
	v_mov_b32_e32 v53, v18
	v_mul_f32_e32 v6, 0.5, v54
	v_pk_mul_f32 v[52:53], v[70:71], v[52:53]
	v_cvt_f32_f16_e32 v70, v46
	v_cvt_f32_f16_e32 v71, v47
	v_cvt_f32_f16_sdwa v47, v47 dst_sel:DWORD dst_unused:UNUSED_PAD src0_sel:WORD_1
	v_cvt_f32_f16_sdwa v46, v46 dst_sel:DWORD dst_unused:UNUSED_PAD src0_sel:WORD_1
	v_pk_fma_f32 v[74:75], v[76:77], 0.5, v[112:113] op_sel_hi:[1,0,1] neg_lo:[1,0,0] neg_hi:[1,0,0]
	v_mul_f32_e32 v12, 0.5, v12
	v_pk_add_f32 v[76:77], v[6:7], v[56:57]
	v_pk_add_f32 v[52:53], v[52:53], v[52:53] op_sel:[0,1] op_sel_hi:[0,1] neg_lo:[0,1] neg_hi:[0,1]
	v_fma_f32 v77, v54, 0.5, -v56
	v_pk_add_f32 v[54:55], v[12:13], v[52:53] op_sel_hi:[0,1] neg_hi:[0,1]
	v_pk_mul_f32 v[52:53], v[54:55], v[46:47]
	v_pk_mul_f32 v[54:55], v[54:55], v[70:71]
	v_pk_fma_f32 v[56:57], v[76:77], v[70:71], v[52:53] neg_lo:[0,0,1] neg_hi:[0,0,1]
	v_pk_fma_f32 v[52:53], v[76:77], v[70:71], v[52:53]
	v_pk_fma_f32 v[70:71], v[76:77], v[46:47], v[54:55]
	v_pk_fma_f32 v[46:47], v[76:77], v[46:47], v[54:55] neg_lo:[0,0,1] neg_hi:[0,0,1]
	v_pk_add_f32 v[54:55], v[56:57], v[52:53] op_sel:[0,1] op_sel_hi:[1,0]
	v_pk_add_f32 v[76:77], v[70:71], v[46:47] op_sel_hi:[0,1] neg_lo:[0,1] neg_hi:[0,1]
	v_pk_add_f32 v[52:53], v[56:57], v[52:53] op_sel_hi:[0,1] neg_lo:[0,1] neg_hi:[0,1]
	v_pk_add_f32 v[46:47], v[70:71], v[46:47] op_sel:[0,1] op_sel_hi:[1,0]
	v_mov_b32_e32 v55, v77
	v_mov_b32_e32 v47, v53
	v_pk_mul_f32 v[46:47], v[46:47], 0.5 op_sel_hi:[1,0]
	s_mov_b32 s25, s27
	v_pk_mul_f32 v[52:53], v[58:59], v[46:47] op_sel:[0,1] op_sel_hi:[0,0]
	v_pk_fma_f32 v[56:57], v[34:35], v[46:47], v[52:53] op_sel_hi:[0,1,1]
	v_pk_fma_f32 v[46:47], v[34:35], v[46:47], v[52:53] op_sel_hi:[0,1,1] neg_hi:[0,0,1]
	s_nop 0
	v_pk_fma_f32 v[52:53], v[54:55], 0.5, v[56:57] op_sel_hi:[1,0,1] neg_lo:[0,0,1] neg_hi:[0,0,1]
	v_pk_fma_f32 v[34:35], v[54:55], 0.5, v[46:47] op_sel_hi:[1,0,1]
	s_mov_b32 s78, s27
	v_mov_b32_e32 v53, v35
	v_pk_mul_f32 v[136:137], v[52:53], s[6:7] op_sel_hi:[1,0]
	v_pk_fma_f32 v[52:53], v[54:55], 0.5, v[46:47] op_sel_hi:[1,0,1] neg_lo:[1,0,0] neg_hi:[1,0,0]
	s_mov_b32 s79, s24
	v_pk_mul_f32 v[46:47], v[82:83], s[24:25] op_sel_hi:[0,1]
	v_pk_add_f32 v[54:55], v[108:109], v[40:41]
	v_pk_add_f32 v[40:41], v[40:41], v[108:109] neg_lo:[0,1] neg_hi:[0,1]
	v_pk_fma_f32 v[108:109], v[4:5], s[78:79], v[46:47] op_sel_hi:[0,1,1] neg_lo:[0,0,1] neg_hi:[0,0,1]
	v_mul_f32_e32 v12, 0.5, v41
	v_pk_fma_f32 v[70:71], v[4:5], s[78:79], v[46:47] op_sel_hi:[0,1,1]
	v_mov_b32_e32 v41, v55
	v_pk_mov_b32 v[56:57], v[108:109], v[70:71] op_sel:[0,1]
	s_nop 0
	v_pk_mul_f32 v[40:41], v[40:41], s[44:45]
	v_mul_f32_e32 v6, 0.5, v54
	v_pk_mul_f32 v[54:55], v[56:57], v[40:41] op_sel:[0,1] op_sel_hi:[1,0]
	v_cvt_f32_f16_sdwa v76, v36 dst_sel:DWORD dst_unused:UNUSED_PAD src0_sel:WORD_1
	v_cvt_f32_f16_e32 v77, v37
	v_cvt_f32_f16_sdwa v37, v37 dst_sel:DWORD dst_unused:UNUSED_PAD src0_sel:WORD_1
	v_cvt_f32_f16_e32 v36, v36
	v_pk_mul_f32 v[40:41], v[56:57], v[40:41]
	v_pk_add_f32 v[54:55], v[54:55], v[54:55] op_sel:[0,1] op_sel_hi:[0,1]
	v_pk_add_f32 v[112:113], v[6:7], v[54:55] op_sel_hi:[0,1] neg_hi:[0,1]
	s_nop 0
	v_pk_add_f32 v[40:41], v[40:41], v[40:41] op_sel:[0,1] op_sel_hi:[0,1] neg_lo:[0,1] neg_hi:[0,1]
	v_pk_add_f32 v[54:55], v[12:13], v[40:41] op_sel_hi:[0,1] neg_hi:[0,1]
	v_pk_mul_f32 v[40:41], v[54:55], v[36:37]
	v_pk_mul_f32 v[54:55], v[54:55], v[76:77]
	v_pk_fma_f32 v[40:41], v[112:113], v[76:77], v[40:41]
	v_pk_fma_f32 v[36:37], v[112:113], v[36:37], v[54:55] neg_lo:[0,0,1] neg_hi:[0,0,1]
	v_pk_mov_b32 v[110:111], v[70:71], v[108:109] op_sel:[1,0]
	v_pk_add_f32 v[54:55], v[36:37], v[40:41] op_sel:[0,1] op_sel_hi:[1,0] neg_lo:[0,1]
	v_pk_add_f32 v[76:77], v[36:37], v[40:41] op_sel:[0,1] op_sel_hi:[1,0]
	v_pk_add_f32 v[36:37], v[40:41], v[36:37] op_sel:[1,0] op_sel_hi:[0,1] neg_lo:[0,1] neg_hi:[0,1]
	v_pk_mul_f32 v[54:55], v[54:55], 0.5 op_sel_hi:[1,0]
	v_mov_b32_e32 v77, v37
	v_mul_f32_e32 v4, v108, v54
	v_pk_fma_f32 v[112:113], v[56:57], v[54:55], v[4:5] op_sel_hi:[1,1,0] neg_lo:[1,0,0] neg_hi:[1,0,0]
	v_mul_f32_e32 v4, v108, v55
	v_pk_fma_f32 v[54:55], v[110:111], v[54:55], v[4:5] op_sel_hi:[1,1,0]
	v_sub_f32_e32 v6, v45, v105
	v_mov_b32_e32 v112, v54
	v_pk_fma_f32 v[40:41], v[76:77], 0.5, v[54:55] op_sel_hi:[1,0,1] neg_lo:[0,0,1] neg_hi:[0,0,1]
	v_pk_fma_f32 v[36:37], v[76:77], 0.5, v[112:113] op_sel_hi:[1,0,1]
	v_pk_add_f32 v[54:55], v[104:105], v[44:45]
	v_mov_b32_e32 v41, v37
	v_pk_mul_f32 v[130:131], v[40:41], s[6:7] op_sel_hi:[1,0]
	v_mul_f32_e32 v40, 0xbf54db31, v83
	v_mov_b32_e32 v41, v44
	v_pk_mov_b32 v[44:45], v[46:47], v[104:105] op_sel:[1,0]
	v_mul_f32_e32 v18, 0.5, v55
	v_pk_add_f32 v[40:41], v[40:41], v[44:45] neg_lo:[0,1] neg_hi:[0,1]
	v_mov_b32_e32 v105, v108
	v_pk_mul_f32 v[44:45], v[40:41], v[18:19]
	v_mov_b32_e32 v104, v40
	v_pk_fma_f32 v[56:57], v[56:57], v[44:45], v[44:45] op_sel:[0,1,0] op_sel_hi:[1,0,1]
	v_mov_b32_e32 v44, v45
	v_mov_b32_e32 v45, v18
	v_mul_f32_e32 v4, 0.5, v54
	v_pk_mul_f32 v[44:45], v[104:105], v[44:45]
	v_cvt_f32_f16_e32 v104, v26
	v_cvt_f32_f16_e32 v105, v27
	v_cvt_f32_f16_sdwa v27, v27 dst_sel:DWORD dst_unused:UNUSED_PAD src0_sel:WORD_1
	v_cvt_f32_f16_sdwa v26, v26 dst_sel:DWORD dst_unused:UNUSED_PAD src0_sel:WORD_1
	v_mul_f32_e32 v6, 0.5, v6
	v_pk_add_f32 v[110:111], v[4:5], v[56:57]
	v_pk_add_f32 v[44:45], v[44:45], v[44:45] op_sel:[0,1] op_sel_hi:[0,1] neg_lo:[0,1] neg_hi:[0,1]
	v_fma_f32 v111, v54, 0.5, -v56
	v_pk_add_f32 v[54:55], v[6:7], v[44:45] op_sel_hi:[0,1] neg_hi:[0,1]
	v_pk_mul_f32 v[44:45], v[54:55], v[26:27]
	v_pk_mul_f32 v[54:55], v[54:55], v[104:105]
	v_pk_fma_f32 v[56:57], v[110:111], v[104:105], v[44:45] neg_lo:[0,0,1] neg_hi:[0,0,1]
	v_pk_fma_f32 v[44:45], v[110:111], v[104:105], v[44:45]
	v_pk_fma_f32 v[104:105], v[110:111], v[26:27], v[54:55]
	v_pk_fma_f32 v[26:27], v[110:111], v[26:27], v[54:55] neg_lo:[0,0,1] neg_hi:[0,0,1]
	v_pk_add_f32 v[54:55], v[56:57], v[44:45] op_sel:[0,1] op_sel_hi:[1,0]
	v_pk_add_f32 v[110:111], v[104:105], v[26:27] op_sel_hi:[0,1] neg_lo:[0,1] neg_hi:[0,1]
	v_pk_add_f32 v[44:45], v[56:57], v[44:45] op_sel_hi:[0,1] neg_lo:[0,1] neg_hi:[0,1]
	v_pk_add_f32 v[26:27], v[104:105], v[26:27] op_sel:[0,1] op_sel_hi:[1,0]
	v_mov_b32_e32 v55, v111
	v_mov_b32_e32 v27, v45
	v_pk_mul_f32 v[26:27], v[26:27], 0.5 op_sel_hi:[1,0]
	v_mov_b32_e32 v47, v102
	v_pk_mul_f32 v[44:45], v[108:109], v[26:27] op_sel:[0,1] op_sel_hi:[0,0]
	v_pk_fma_f32 v[56:57], v[40:41], v[26:27], v[44:45] op_sel_hi:[0,1,1]
	v_pk_fma_f32 v[40:41], v[40:41], v[26:27], v[44:45] op_sel_hi:[0,1,1] neg_hi:[0,0,1]
	v_pk_fma_f32 v[44:45], v[54:55], 0.5, v[56:57] op_sel_hi:[1,0,1] neg_lo:[0,0,1] neg_hi:[0,0,1]
	v_pk_fma_f32 v[26:27], v[54:55], 0.5, v[40:41] op_sel_hi:[1,0,1]
	v_pk_fma_f32 v[56:57], v[54:55], 0.5, v[40:41] op_sel_hi:[1,0,1] neg_lo:[1,0,0] neg_hi:[1,0,0]
	v_pk_add_f32 v[40:41], v[106:107], v[42:43]
	v_pk_add_f32 v[42:43], v[42:43], v[106:107] neg_lo:[0,1] neg_hi:[0,1]
	v_mov_b32_e32 v45, v27
	v_mul_f32_e32 v6, 0.5, v43
	v_mov_b32_e32 v43, v41
	v_pk_mul_f32 v[120:121], v[44:45], s[6:7] op_sel_hi:[1,0]
	v_mul_f32_e32 v4, 0.5, v40
	v_pk_mov_b32 v[44:45], v[108:109], v[70:71] op_sel:[1,0]
	v_pk_mul_f32 v[40:41], v[42:43], s[44:45]
	v_cvt_f32_f16_sdwa v54, v20 dst_sel:DWORD dst_unused:UNUSED_PAD src0_sel:WORD_1
	v_pk_mul_f32 v[42:43], v[44:45], v[40:41] op_sel:[0,1] op_sel_hi:[1,0]
	v_cvt_f32_f16_e32 v55, v21
	v_cvt_f32_f16_sdwa v21, v21 dst_sel:DWORD dst_unused:UNUSED_PAD src0_sel:WORD_1
	v_cvt_f32_f16_e32 v20, v20
	v_pk_mul_f32 v[40:41], v[44:45], v[40:41]
	v_pk_add_f32 v[42:43], v[42:43], v[42:43] op_sel:[0,1] op_sel_hi:[0,1]
	v_pk_add_f32 v[104:105], v[4:5], v[42:43] op_sel_hi:[0,1] neg_hi:[0,1]
	s_nop 0
	v_pk_add_f32 v[40:41], v[40:41], v[40:41] op_sel:[0,1] op_sel_hi:[0,1] neg_lo:[0,1] neg_hi:[0,1]
	v_pk_add_f32 v[42:43], v[6:7], v[40:41] op_sel_hi:[0,1] neg_hi:[0,1]
	v_pk_mul_f32 v[40:41], v[42:43], v[20:21]
	v_pk_mul_f32 v[42:43], v[42:43], v[54:55]
	v_pk_fma_f32 v[40:41], v[104:105], v[54:55], v[40:41]
	v_pk_fma_f32 v[20:21], v[104:105], v[20:21], v[42:43] neg_lo:[0,0,1] neg_hi:[0,0,1]
	v_mov_b32_e32 v71, v109
	v_pk_add_f32 v[42:43], v[20:21], v[40:41] op_sel:[0,1] op_sel_hi:[1,0] neg_lo:[0,1]
	v_pk_add_f32 v[54:55], v[20:21], v[40:41] op_sel:[0,1] op_sel_hi:[1,0]
	v_pk_add_f32 v[20:21], v[40:41], v[20:21] op_sel:[1,0] op_sel_hi:[0,1] neg_lo:[0,1] neg_hi:[0,1]
	v_pk_mul_f32 v[42:43], v[42:43], 0.5 op_sel_hi:[1,0]
	v_mov_b32_e32 v55, v21
	v_mul_f32_e32 v4, v109, v42
	v_pk_fma_f32 v[104:105], v[44:45], v[42:43], v[4:5] op_sel_hi:[1,1,0] neg_lo:[1,0,0] neg_hi:[1,0,0]
	v_mul_f32_e32 v4, v109, v43
	v_pk_fma_f32 v[42:43], v[70:71], v[42:43], v[4:5] op_sel_hi:[1,1,0]
	v_sub_f32_e32 v6, v23, v103
	v_mov_b32_e32 v104, v42
	v_pk_fma_f32 v[40:41], v[54:55], 0.5, v[42:43] op_sel_hi:[1,0,1] neg_lo:[0,0,1] neg_hi:[0,0,1]
	v_pk_fma_f32 v[20:21], v[54:55], 0.5, v[104:105] op_sel_hi:[1,0,1]
	v_pk_add_f32 v[42:43], v[102:103], v[22:23]
	v_mov_b32_e32 v41, v21
	v_pk_mul_f32 v[128:129], v[40:41], s[6:7] op_sel_hi:[1,0]
	v_mul_f32_e32 v40, 0xbf0e39da, v83
	v_mov_b32_e32 v41, v22
	v_mul_f32_e32 v18, 0.5, v43
	v_pk_add_f32 v[22:23], v[40:41], v[46:47] neg_lo:[0,1] neg_hi:[0,1]
	v_mov_b32_e32 v47, v109
	v_pk_mul_f32 v[40:41], v[22:23], v[18:19]
	v_mov_b32_e32 v46, v22
	v_pk_fma_f32 v[44:45], v[44:45], v[40:41], v[40:41] op_sel:[0,1,0] op_sel_hi:[1,0,1]
	v_mov_b32_e32 v40, v41
	v_mov_b32_e32 v41, v18
	v_mul_f32_e32 v4, 0.5, v42
	v_pk_mul_f32 v[40:41], v[46:47], v[40:41]
	v_cvt_f32_f16_e32 v46, v10
	v_cvt_f32_f16_e32 v47, v11
	v_cvt_f32_f16_sdwa v11, v11 dst_sel:DWORD dst_unused:UNUSED_PAD src0_sel:WORD_1
	v_cvt_f32_f16_sdwa v10, v10 dst_sel:DWORD dst_unused:UNUSED_PAD src0_sel:WORD_1
	v_pk_fma_f32 v[70:71], v[54:55], 0.5, v[104:105] op_sel_hi:[1,0,1] neg_lo:[1,0,0] neg_hi:[1,0,0]
	v_mul_f32_e32 v6, 0.5, v6
	v_pk_add_f32 v[54:55], v[4:5], v[44:45]
	v_pk_add_f32 v[40:41], v[40:41], v[40:41] op_sel:[0,1] op_sel_hi:[0,1] neg_lo:[0,1] neg_hi:[0,1]
	v_fma_f32 v55, v42, 0.5, -v44
	v_pk_add_f32 v[42:43], v[6:7], v[40:41] op_sel_hi:[0,1] neg_hi:[0,1]
	v_pk_mul_f32 v[40:41], v[42:43], v[10:11]
	v_pk_mul_f32 v[42:43], v[42:43], v[46:47]
	v_pk_fma_f32 v[44:45], v[54:55], v[46:47], v[40:41] neg_lo:[0,0,1] neg_hi:[0,0,1]
	v_pk_fma_f32 v[40:41], v[54:55], v[46:47], v[40:41]
	v_pk_fma_f32 v[46:47], v[54:55], v[10:11], v[42:43]
	v_pk_fma_f32 v[10:11], v[54:55], v[10:11], v[42:43] neg_lo:[0,0,1] neg_hi:[0,0,1]
	v_pk_add_f32 v[42:43], v[44:45], v[40:41] op_sel:[0,1] op_sel_hi:[1,0]
	v_pk_add_f32 v[54:55], v[46:47], v[10:11] op_sel_hi:[0,1] neg_lo:[0,1] neg_hi:[0,1]
	v_pk_add_f32 v[40:41], v[44:45], v[40:41] op_sel_hi:[0,1] neg_lo:[0,1] neg_hi:[0,1]
	v_pk_add_f32 v[10:11], v[46:47], v[10:11] op_sel:[0,1] op_sel_hi:[1,0]
	v_mov_b32_e32 v43, v55
	v_mov_b32_e32 v11, v41
	v_pk_mul_f32 v[10:11], v[10:11], 0.5 op_sel_hi:[1,0]
	v_mov_b32_e32 v119, v98
	v_pk_mul_f32 v[40:41], v[108:109], v[10:11] op_sel:[1,1] op_sel_hi:[1,0]
	v_pk_fma_f32 v[76:77], v[76:77], 0.5, v[112:113] op_sel_hi:[1,0,1] neg_lo:[1,0,0] neg_hi:[1,0,0]
	v_pk_fma_f32 v[44:45], v[22:23], v[10:11], v[40:41] op_sel_hi:[0,1,1]
	v_pk_fma_f32 v[10:11], v[22:23], v[10:11], v[40:41] op_sel_hi:[0,1,1] neg_hi:[0,0,1]
	v_pk_fma_f32 v[22:23], v[42:43], 0.5, v[44:45] op_sel_hi:[1,0,1] neg_lo:[0,0,1] neg_hi:[0,0,1]
	v_pk_fma_f32 v[40:41], v[42:43], 0.5, v[10:11] op_sel_hi:[1,0,1]
	v_pk_fma_f32 v[54:55], v[42:43], 0.5, v[10:11] op_sel_hi:[1,0,1] neg_lo:[1,0,0] neg_hi:[1,0,0]
	v_pk_add_f32 v[10:11], v[100:101], v[14:15]
	v_pk_add_f32 v[14:15], v[14:15], v[100:101] neg_lo:[0,1] neg_hi:[0,1]
	v_mov_b32_e32 v23, v41
	v_mul_f32_e32 v6, 0.5, v15
	v_mov_b32_e32 v15, v11
	v_pk_mul_f32 v[150:151], v[22:23], s[6:7] op_sel_hi:[1,0]
	v_mul_f32_e32 v4, 0.5, v10
	v_pk_mov_b32 v[22:23], v[58:59], v[72:73] op_sel:[1,0]
	v_pk_mul_f32 v[10:11], v[14:15], s[44:45]
	v_cvt_f32_f16_sdwa v42, v8 dst_sel:DWORD dst_unused:UNUSED_PAD src0_sel:WORD_1
	v_pk_mul_f32 v[14:15], v[22:23], v[10:11] op_sel:[0,1] op_sel_hi:[1,0]
	v_cvt_f32_f16_e32 v43, v9
	v_cvt_f32_f16_sdwa v9, v9 dst_sel:DWORD dst_unused:UNUSED_PAD src0_sel:WORD_1
	v_cvt_f32_f16_e32 v8, v8
	v_pk_mul_f32 v[10:11], v[22:23], v[10:11]
	v_pk_add_f32 v[14:15], v[14:15], v[14:15] op_sel:[0,1] op_sel_hi:[0,1]
	v_pk_add_f32 v[44:45], v[4:5], v[14:15] op_sel_hi:[0,1] neg_hi:[0,1]
	s_nop 0
	v_pk_add_f32 v[10:11], v[10:11], v[10:11] op_sel:[0,1] op_sel_hi:[0,1] neg_lo:[0,1] neg_hi:[0,1]
	v_pk_add_f32 v[14:15], v[6:7], v[10:11] op_sel_hi:[0,1] neg_hi:[0,1]
	v_pk_mul_f32 v[10:11], v[14:15], v[8:9]
	v_pk_mul_f32 v[14:15], v[14:15], v[42:43]
	v_pk_fma_f32 v[10:11], v[44:45], v[42:43], v[10:11]
	v_pk_fma_f32 v[8:9], v[44:45], v[8:9], v[14:15] neg_lo:[0,0,1] neg_hi:[0,0,1]
	v_mov_b32_e32 v73, v59
	v_pk_add_f32 v[14:15], v[8:9], v[10:11] op_sel:[0,1] op_sel_hi:[1,0] neg_lo:[0,1]
	v_pk_add_f32 v[42:43], v[8:9], v[10:11] op_sel:[0,1] op_sel_hi:[1,0]
	v_pk_add_f32 v[8:9], v[10:11], v[8:9] op_sel:[1,0] op_sel_hi:[0,1] neg_lo:[0,1] neg_hi:[0,1]
	v_pk_mul_f32 v[14:15], v[14:15], 0.5 op_sel_hi:[1,0]
	v_mov_b32_e32 v43, v9
	v_mul_f32_e32 v4, v59, v14
	v_pk_fma_f32 v[44:45], v[22:23], v[14:15], v[4:5] op_sel_hi:[1,1,0] neg_lo:[1,0,0] neg_hi:[1,0,0]
	v_mul_f32_e32 v4, v59, v15
	v_pk_fma_f32 v[14:15], v[72:73], v[14:15], v[4:5] op_sel_hi:[1,1,0]
	v_sub_f32_e32 v6, v39, v99
	v_mov_b32_e32 v44, v14
	v_pk_fma_f32 v[8:9], v[42:43], 0.5, v[14:15] op_sel_hi:[1,0,1] neg_lo:[0,0,1] neg_hi:[0,0,1]
	v_pk_fma_f32 v[10:11], v[42:43], 0.5, v[44:45] op_sel_hi:[1,0,1]
	v_pk_add_f32 v[14:15], v[98:99], v[38:39]
	v_mov_b32_e32 v9, v11
	v_pk_mul_f32 v[168:169], v[8:9], s[6:7] op_sel_hi:[1,0]
	v_mul_f32_e32 v8, 0xbf7b14be, v83
	v_mov_b32_e32 v9, v38
	v_mul_f32_e32 v18, 0.5, v15
	v_pk_add_f32 v[8:9], v[8:9], v[118:119] neg_lo:[0,1] neg_hi:[0,1]
	v_pk_fma_f32 v[72:73], v[42:43], 0.5, v[44:45] op_sel_hi:[1,0,1] neg_lo:[1,0,0] neg_hi:[1,0,0]
	v_pk_mul_f32 v[38:39], v[8:9], v[18:19]
	v_pk_mov_b32 v[42:43], v[8:9], v[58:59] op_sel:[0,1]
	v_pk_fma_f32 v[22:23], v[22:23], v[38:39], v[38:39] op_sel:[0,1,0] op_sel_hi:[1,0,1]
	v_mov_b32_e32 v38, v39
	v_mov_b32_e32 v39, v18
	v_mul_f32_e32 v4, 0.5, v14
	v_pk_mul_f32 v[38:39], v[42:43], v[38:39]
	v_cvt_f32_f16_e32 v44, v2
	v_cvt_f32_f16_e32 v45, v3
	v_cvt_f32_f16_sdwa v3, v3 dst_sel:DWORD dst_unused:UNUSED_PAD src0_sel:WORD_1
	v_cvt_f32_f16_sdwa v2, v2 dst_sel:DWORD dst_unused:UNUSED_PAD src0_sel:WORD_1
	v_mul_f32_e32 v6, 0.5, v6
	v_pk_add_f32 v[46:47], v[4:5], v[22:23]
	v_fma_f32 v4, v14, 0.5, -v22
	v_pk_add_f32 v[22:23], v[38:39], v[38:39] op_sel:[0,1] op_sel_hi:[0,1] neg_lo:[0,1] neg_hi:[0,1]
	v_pk_add_f32 v[38:39], v[6:7], v[22:23] op_sel_hi:[0,1] neg_hi:[0,1]
	v_pk_mov_b32 v[14:15], v[46:47], v[4:5] op_sel:[0,0]
	v_pk_mul_f32 v[22:23], v[4:5], v[44:45] op_sel_hi:[0,1]
	v_pk_mul_f32 v[82:83], v[38:39], v[2:3]
	v_pk_mul_f32 v[46:47], v[46:47], v[2:3]
	v_pk_mul_f32 v[38:39], v[38:39], v[44:45]
	v_pk_fma_f32 v[98:99], v[14:15], v[44:45], v[82:83] neg_lo:[0,0,1] neg_hi:[0,0,1]
	v_pk_fma_f32 v[2:3], v[14:15], v[2:3], v[38:39] neg_lo:[0,0,1] neg_hi:[0,0,1]
	v_add_f32_e32 v4, v23, v83
	v_add_f32_e32 v6, v46, v38
	v_pk_add_f32 v[22:23], v[6:7], v[2:3] op_sel_hi:[0,1] neg_lo:[0,1] neg_hi:[0,1]
	v_pk_add_f32 v[38:39], v[98:99], v[4:5] op_sel_hi:[1,0] neg_lo:[0,1] neg_hi:[0,1]
	v_pk_add_f32 v[2:3], v[6:7], v[2:3] op_sel_hi:[0,1]
	v_mov_b32_e32 v39, v3
	v_pk_mul_f32 v[2:3], v[38:39], 0.5 op_sel_hi:[1,0]
	v_pk_add_f32 v[14:15], v[98:99], v[4:5] op_sel_hi:[1,0]
	v_mul_f32_e32 v4, v59, v3
	v_pk_fma_f32 v[38:39], v[42:43], v[2:3], v[4:5] op_sel_hi:[1,1,0] neg_lo:[0,0,1] neg_hi:[0,0,1]
	v_pk_mov_b32 v[42:43], v[58:59], v[8:9] op_sel:[1,0]
	v_mul_f32_e32 v4, v8, v3
	v_pk_fma_f32 v[2:3], v[42:43], v[2:3], v[4:5] op_sel_hi:[1,1,0]
	v_mov_b32_e32 v15, v23
	v_pk_fma_f32 v[8:9], v[14:15], 0.5, v[2:3] op_sel_hi:[1,0,1] neg_lo:[0,0,1] neg_hi:[0,0,1]
	v_pk_fma_f32 v[42:43], v[14:15], 0.5, v[38:39] op_sel_hi:[1,0,0]
	v_pk_fma_f32 v[2:3], v[14:15], 0.5, v[2:3] op_sel_hi:[1,0,1]
	v_mov_b32_e32 v9, v43
	v_pk_fma_f32 v[58:59], v[22:23], 0.5, v[38:39] op_sel_hi:[1,0,0] neg_lo:[1,0,0] neg_hi:[1,0,0]
	v_pk_mul_f32 v[144:145], v[8:9], s[6:7] op_sel_hi:[1,0]
	v_mov_b32_e32 v58, v2
	v_mov_b32_e32 v72, v10
	v_mov_b32_e32 v54, v40
	v_mov_b32_e32 v70, v20
	v_mov_b32_e32 v56, v26
	v_mov_b32_e32 v76, v36
	v_mov_b32_e32 v52, v34
	v_mov_b32_e32 v74, v86
	v_mov_b32_e32 v48, v84
	v_mov_b32_e32 v50, v60
	v_mov_b32_e32 v28, v66
	v_mov_b32_e32 v32, v96
	v_mov_b32_e32 v12, v88
	v_mov_b32_e32 v16, v92
	v_mov_b32_e32 v4, v138
	v_mov_b32_e32 v6, v122
.LBB0_501:
	s_andn2_saveexec_b64 s[0:1], s[0:1]
	s_cbranch_execz .LBB0_503
	v_pk_add_f32 v[4:5], v[98:99], v[196:197]
	v_pk_add_f32 v[6:7], v[98:99], v[196:197] neg_lo:[0,1] neg_hi:[0,1]
	v_mul_f32_e32 v4, 0.5, v4
	v_mul_f32_e32 v12, 0.5, v7
	v_mov_b32_e32 v7, v5
	v_pk_mul_f32 v[6:7], v[6:7], s[44:45]
	v_pk_mov_b32 v[16:17], v[198:199], v[160:161] op_sel:[1,0]
	v_pk_mul_f32 v[24:25], v[190:191], v[6:7] op_sel:[0,1] op_sel_hi:[1,0]
	v_pk_mul_f32 v[6:7], v[190:191], v[6:7]
	v_pk_add_f32 v[24:25], v[24:25], v[24:25] op_sel:[0,1] op_sel_hi:[0,1]
	v_pk_add_f32 v[28:29], v[4:5], v[24:25] op_sel_hi:[0,1] neg_hi:[0,1]
	v_pk_add_f32 v[4:5], v[6:7], v[6:7] op_sel:[0,1] op_sel_hi:[0,1] neg_lo:[0,1] neg_hi:[0,1]
	v_pk_add_f32 v[6:7], v[12:13], v[4:5] op_sel_hi:[0,1] neg_hi:[0,1]
	v_pk_mul_f32 v[4:5], v[6:7], v[194:195]
	v_pk_mul_f32 v[6:7], v[6:7], v[192:193]
	v_pk_fma_f32 v[4:5], v[28:29], v[192:193], v[4:5]
	v_pk_fma_f32 v[6:7], v[28:29], v[194:195], v[6:7] neg_lo:[0,0,1] neg_hi:[0,0,1]
	s_mov_b32 s78, s19
	v_pk_add_f32 v[12:13], v[6:7], v[4:5] op_sel:[0,1] op_sel_hi:[1,0] neg_lo:[0,1]
	v_pk_add_f32 v[24:25], v[6:7], v[4:5] op_sel:[0,1] op_sel_hi:[1,0]
	v_pk_add_f32 v[4:5], v[4:5], v[6:7] op_sel:[1,0] op_sel_hi:[0,1] neg_lo:[0,1] neg_hi:[0,1]
	s_nop 0
	v_pk_mul_f32 v[12:13], v[12:13], 0.5 op_sel_hi:[1,0]
	v_mov_b32_e32 v25, v5
	v_mul_f32_e32 v28, v191, v13
	v_mul_f32_e32 v30, v160, v13
	v_pk_fma_f32 v[28:29], v[190:191], v[12:13], v[28:29] op_sel_hi:[1,1,0] neg_lo:[0,0,1] neg_hi:[0,0,1]
	v_pk_fma_f32 v[12:13], v[16:17], v[12:13], v[30:31] op_sel_hi:[1,1,0]
	v_mov_b32_e32 v7, v28
	v_mov_b32_e32 v6, v12
	v_pk_fma_f32 v[58:59], v[24:25], 0.5, v[12:13] op_sel_hi:[1,0,1] neg_lo:[0,0,1] neg_hi:[0,0,1]
	v_pk_fma_f32 v[98:99], v[24:25], 0.5, v[6:7] op_sel_hi:[1,0,1]
	v_pk_fma_f32 v[6:7], v[24:25], 0.5, v[12:13] op_sel_hi:[1,0,1]
	v_pk_fma_f32 v[160:161], v[4:5], 0.5, v[28:29] op_sel_hi:[1,0,0] neg_lo:[1,0,0] neg_hi:[1,0,0]
	v_pk_add_f32 v[4:5], v[100:101], v[188:189]
	v_pk_add_f32 v[12:13], v[100:101], v[188:189] neg_lo:[0,1] neg_hi:[0,1]
	v_pk_mov_b32 v[24:25], v[82:83], v[82:83] op_sel:[1,0]
	v_mul_f32_e32 v16, 0.5, v13
	v_pk_add_f32 v[28:29], v[186:187], v[24:25] neg_lo:[0,1] neg_hi:[0,1]
	v_pk_add_f32 v[30:31], v[186:187], v[24:25]
	v_mov_b32_e32 v13, v5
	v_pk_mov_b32 v[32:33], v[28:29], v[30:31] op_sel:[1,0]
	v_pk_mul_f32 v[12:13], v[12:13], s[44:45]
	v_mul_f32_e32 v4, 0.5, v4
	v_pk_mul_f32 v[48:49], v[32:33], v[12:13] op_sel:[0,1] op_sel_hi:[1,0]
	v_pk_mul_f32 v[12:13], v[32:33], v[12:13]
	v_pk_add_f32 v[48:49], v[48:49], v[48:49] op_sel:[0,1] op_sel_hi:[0,1]
	v_pk_add_f32 v[50:51], v[4:5], v[48:49] op_sel_hi:[0,1] neg_hi:[0,1]
	v_pk_add_f32 v[4:5], v[12:13], v[12:13] op_sel:[0,1] op_sel_hi:[0,1] neg_lo:[0,1] neg_hi:[0,1]
	v_pk_add_f32 v[12:13], v[16:17], v[4:5] op_sel_hi:[0,1] neg_hi:[0,1]
	v_pk_mul_f32 v[4:5], v[12:13], v[184:185]
	v_pk_mul_f32 v[12:13], v[12:13], v[170:171]
	v_pk_fma_f32 v[4:5], v[50:51], v[170:171], v[4:5]
	v_pk_fma_f32 v[12:13], v[50:51], v[184:185], v[12:13] neg_lo:[0,0,1] neg_hi:[0,0,1]
	v_mov_b32_e32 v31, v29
	v_pk_add_f32 v[16:17], v[12:13], v[4:5] op_sel:[0,1] op_sel_hi:[1,0] neg_lo:[0,1]
	v_pk_add_f32 v[48:49], v[12:13], v[4:5] op_sel:[0,1] op_sel_hi:[1,0]
	v_pk_add_f32 v[12:13], v[4:5], v[12:13] op_sel:[1,0] op_sel_hi:[0,1] neg_lo:[0,1] neg_hi:[0,1]
	v_pk_mul_f32 v[16:17], v[16:17], 0.5 op_sel_hi:[1,0]
	v_mov_b32_e32 v49, v13
	v_mul_f32_e32 v28, v30, v17
	v_pk_fma_f32 v[32:33], v[32:33], v[16:17], v[28:29] op_sel_hi:[1,1,0] neg_lo:[0,0,1] neg_hi:[0,0,1]
	v_mul_f32_e32 v28, v29, v17
	v_pk_fma_f32 v[16:17], v[30:31], v[16:17], v[28:29] op_sel_hi:[1,1,0]
	v_mov_b32_e32 v5, v32
	v_mov_b32_e32 v4, v16
	v_pk_fma_f32 v[72:73], v[48:49], 0.5, v[16:17] op_sel_hi:[1,0,1] neg_lo:[0,0,1] neg_hi:[0,0,1]
	v_pk_fma_f32 v[100:101], v[48:49], 0.5, v[4:5] op_sel_hi:[1,0,1]
	v_pk_fma_f32 v[4:5], v[48:49], 0.5, v[16:17] op_sel_hi:[1,0,1]
	v_pk_fma_f32 v[170:171], v[12:13], 0.5, v[32:33] op_sel_hi:[1,0,0] neg_lo:[1,0,0] neg_hi:[1,0,0]
	v_pk_mul_f32 v[12:13], v[24:25], s[36:37]
	v_pk_add_f32 v[16:17], v[102:103], v[182:183]
	v_pk_add_f32 v[24:25], v[102:103], v[182:183] neg_lo:[0,1] neg_hi:[0,1]
	v_pk_add_f32 v[30:31], v[18:19], v[12:13] op_sel:[0,1] op_sel_hi:[0,1] neg_lo:[0,1] neg_hi:[0,1]
	v_mul_f32_e32 v28, 0.5, v25
	v_pk_add_f32 v[32:33], v[18:19], v[12:13] op_sel:[0,1] op_sel_hi:[0,1]
	v_mov_b32_e32 v25, v17
	v_pk_mov_b32 v[48:49], v[30:31], v[32:33] op_sel:[0,1]
	v_pk_mul_f32 v[24:25], v[24:25], s[44:45]
	v_mul_f32_e32 v16, 0.5, v16
	v_pk_mul_f32 v[52:53], v[48:49], v[24:25] op_sel:[0,1] op_sel_hi:[1,0]
	v_pk_mul_f32 v[24:25], v[48:49], v[24:25]
	v_pk_add_f32 v[52:53], v[52:53], v[52:53] op_sel:[0,1] op_sel_hi:[0,1]
	v_pk_add_f32 v[54:55], v[16:17], v[52:53] op_sel_hi:[0,1] neg_hi:[0,1]
	v_pk_add_f32 v[16:17], v[24:25], v[24:25] op_sel:[0,1] op_sel_hi:[0,1] neg_lo:[0,1] neg_hi:[0,1]
	v_pk_add_f32 v[24:25], v[28:29], v[16:17] op_sel_hi:[0,1] neg_hi:[0,1]
	v_pk_mul_f32 v[16:17], v[24:25], v[180:181]
	v_pk_mul_f32 v[24:25], v[24:25], v[172:173]
	v_pk_fma_f32 v[16:17], v[54:55], v[172:173], v[16:17]
	v_pk_fma_f32 v[24:25], v[54:55], v[180:181], v[24:25] neg_lo:[0,0,1] neg_hi:[0,0,1]
	v_pk_mov_b32 v[50:51], v[32:33], v[30:31] op_sel:[1,0]
	v_pk_add_f32 v[28:29], v[24:25], v[16:17] op_sel:[0,1] op_sel_hi:[1,0] neg_lo:[0,1]
	v_pk_add_f32 v[52:53], v[24:25], v[16:17] op_sel:[0,1] op_sel_hi:[1,0]
	v_pk_add_f32 v[24:25], v[16:17], v[24:25] op_sel:[1,0] op_sel_hi:[0,1] neg_lo:[0,1] neg_hi:[0,1]
	v_pk_mul_f32 v[28:29], v[28:29], 0.5 op_sel_hi:[1,0]
	v_mov_b32_e32 v53, v25
	v_mul_f32_e32 v18, v33, v29
	v_pk_fma_f32 v[32:33], v[48:49], v[28:29], v[18:19] op_sel_hi:[1,1,0] neg_lo:[0,0,1] neg_hi:[0,0,1]
	v_mul_f32_e32 v18, v30, v29
	v_pk_fma_f32 v[28:29], v[50:51], v[28:29], v[18:19] op_sel_hi:[1,1,0]
	v_pk_fma_f32 v[172:173], v[24:25], 0.5, v[32:33] op_sel_hi:[1,0,0] neg_lo:[1,0,0] neg_hi:[1,0,0]
	v_pk_add_f32 v[24:25], v[106:107], v[178:179]
	v_pk_mov_b32 v[50:51], v[12:13], v[106:107] op_sel:[0,0]
	v_pk_mov_b32 v[12:13], v[12:13], v[178:179] op_sel:[1,0]
	v_mul_f32_e32 v18, 0.5, v25
	v_pk_add_f32 v[12:13], v[50:51], v[12:13] neg_lo:[0,1] neg_hi:[0,1]
	v_pk_mov_b32 v[16:17], v[28:29], v[32:33] op_sel:[0,0]
	v_pk_mul_f32 v[50:51], v[12:13], v[18:19]
	v_pk_fma_f32 v[54:55], v[52:53], 0.5, v[28:29] op_sel_hi:[1,0,1] neg_lo:[0,0,1] neg_hi:[0,0,1]
	v_pk_fma_f32 v[102:103], v[52:53], 0.5, v[16:17] op_sel_hi:[1,0,1]
	v_pk_fma_f32 v[16:17], v[52:53], 0.5, v[28:29] op_sel_hi:[1,0,1]
	v_mul_f32_e32 v28, 0.5, v24
	v_pk_fma_f32 v[48:49], v[48:49], v[50:51], v[50:51] op_sel:[0,1,0] op_sel_hi:[1,0,1]
	v_mov_b32_e32 v13, v30
	v_mov_b32_e32 v50, v51
	v_mov_b32_e32 v51, v18
	v_sub_f32_e32 v5, v107, v179
	v_pk_mul_f32 v[50:51], v[12:13], v[50:51]
	v_pk_add_f32 v[28:29], v[28:29], v[48:49]
	v_mul_f32_e32 v32, 0.5, v5
	v_fma_f32 v29, v24, 0.5, -v48
	v_pk_add_f32 v[24:25], v[50:51], v[50:51] op_sel:[0,1] op_sel_hi:[0,1] neg_lo:[0,1] neg_hi:[0,1]
	v_pk_add_f32 v[48:49], v[32:33], v[24:25] op_sel_hi:[0,1] neg_hi:[0,1]
	v_pk_mul_f32 v[24:25], v[48:49], v[176:177]
	v_pk_mul_f32 v[32:33], v[48:49], v[174:175]
	v_pk_fma_f32 v[24:25], v[28:29], v[174:175], v[24:25]
	v_pk_fma_f32 v[28:29], v[28:29], v[176:177], v[32:33] neg_lo:[0,0,1] neg_hi:[0,0,1]
	v_mov_b32_e32 v31, v12
	v_pk_add_f32 v[32:33], v[28:29], v[24:25] op_sel:[0,1] op_sel_hi:[1,0] neg_lo:[0,1]
	v_pk_add_f32 v[48:49], v[28:29], v[24:25] op_sel:[0,1] op_sel_hi:[1,0]
	v_pk_add_f32 v[24:25], v[24:25], v[28:29] op_sel:[1,0] op_sel_hi:[0,1] neg_lo:[0,1] neg_hi:[0,1]
	v_pk_mul_f32 v[32:33], v[32:33], 0.5 op_sel_hi:[1,0]
	v_mov_b32_e32 v49, v25
	v_mul_f32_e32 v18, v30, v33
	v_pk_fma_f32 v[50:51], v[12:13], v[32:33], v[18:19] op_sel_hi:[1,1,0] neg_lo:[0,0,1] neg_hi:[0,0,1]
	v_mul_f32_e32 v12, v12, v33
	v_pk_fma_f32 v[12:13], v[30:31], v[32:33], v[12:13] op_sel_hi:[1,1,0]
	v_mov_b32_e32 v29, v50
	v_mov_b32_e32 v28, v12
	s_mov_b32 s79, s16
	v_pk_fma_f32 v[106:107], v[48:49], 0.5, v[28:29] op_sel_hi:[1,0,1]
	v_pk_fma_f32 v[174:175], v[24:25], 0.5, v[50:51] op_sel_hi:[1,0,0] neg_lo:[1,0,0] neg_hi:[1,0,0]
	v_mov_b32_e32 v18, v83
	s_mov_b32 s17, s19
	v_pk_mul_f32 v[24:25], v[82:83], s[78:79] op_sel_hi:[0,1]
	v_pk_add_f32 v[28:29], v[104:105], v[162:163]
	v_pk_add_f32 v[30:31], v[104:105], v[162:163] neg_lo:[0,1] neg_hi:[0,1]
	v_pk_fma_f32 v[70:71], v[48:49], 0.5, v[12:13] op_sel_hi:[1,0,1] neg_lo:[0,0,1] neg_hi:[0,0,1]
	v_pk_fma_f32 v[12:13], v[48:49], 0.5, v[12:13] op_sel_hi:[1,0,1]
	v_mul_f32_e32 v32, 0.5, v31
	v_pk_fma_f32 v[48:49], v[18:19], s[16:17], v[24:25] op_sel_hi:[0,1,1] neg_lo:[0,0,1] neg_hi:[0,0,1]
	v_pk_fma_f32 v[50:51], v[18:19], s[16:17], v[24:25] op_sel_hi:[0,1,1]
	v_mov_b32_e32 v31, v29
	v_pk_mov_b32 v[52:53], v[48:49], v[50:51] op_sel:[0,1]
	v_pk_mul_f32 v[30:31], v[30:31], s[44:45]
	v_mul_f32_e32 v28, 0.5, v28
	v_pk_mul_f32 v[62:63], v[52:53], v[30:31] op_sel:[0,1] op_sel_hi:[1,0]
	v_pk_mul_f32 v[30:31], v[52:53], v[30:31]
	v_pk_add_f32 v[62:63], v[62:63], v[62:63] op_sel:[0,1] op_sel_hi:[0,1]
	v_pk_add_f32 v[64:65], v[28:29], v[62:63] op_sel_hi:[0,1] neg_hi:[0,1]
	v_pk_add_f32 v[28:29], v[30:31], v[30:31] op_sel:[0,1] op_sel_hi:[0,1] neg_lo:[0,1] neg_hi:[0,1]
	v_pk_add_f32 v[30:31], v[32:33], v[28:29] op_sel_hi:[0,1] neg_hi:[0,1]
	v_pk_mul_f32 v[28:29], v[30:31], v[166:167]
	v_pk_mul_f32 v[30:31], v[30:31], v[164:165]
	v_pk_fma_f32 v[28:29], v[64:65], v[164:165], v[28:29]
	v_pk_fma_f32 v[30:31], v[64:65], v[166:167], v[30:31] neg_lo:[0,0,1] neg_hi:[0,0,1]
	v_pk_mov_b32 v[56:57], v[50:51], v[48:49] op_sel:[1,0]
	v_pk_add_f32 v[32:33], v[30:31], v[28:29] op_sel:[0,1] op_sel_hi:[1,0] neg_lo:[0,1]
	v_pk_add_f32 v[62:63], v[30:31], v[28:29] op_sel:[0,1] op_sel_hi:[1,0]
	v_pk_add_f32 v[28:29], v[28:29], v[30:31] op_sel:[1,0] op_sel_hi:[0,1] neg_lo:[0,1] neg_hi:[0,1]
	v_pk_mul_f32 v[32:33], v[32:33], 0.5 op_sel_hi:[1,0]
	v_mov_b32_e32 v63, v29
	v_mul_f32_e32 v18, v51, v33
	v_pk_fma_f32 v[52:53], v[52:53], v[32:33], v[18:19] op_sel_hi:[1,1,0] neg_lo:[0,0,1] neg_hi:[0,0,1]
	v_mul_f32_e32 v18, v48, v33
	v_pk_fma_f32 v[32:33], v[56:57], v[32:33], v[18:19] op_sel_hi:[1,1,0]
	v_mov_b32_e32 v31, v52
	v_mov_b32_e32 v30, v32
	v_pk_fma_f32 v[56:57], v[62:63], 0.5, v[32:33] op_sel_hi:[1,0,1] neg_lo:[0,0,1] neg_hi:[0,0,1]
	v_pk_fma_f32 v[82:83], v[62:63], 0.5, v[30:31] op_sel_hi:[1,0,1]
	v_pk_fma_f32 v[32:33], v[62:63], 0.5, v[32:33] op_sel_hi:[1,0,1]
	v_pk_fma_f32 v[104:105], v[28:29], 0.5, v[52:53] op_sel_hi:[1,0,0] neg_lo:[1,0,0] neg_hi:[1,0,0]
	v_pk_add_f32 v[28:29], v[108:109], v[152:153]
	v_mov_b32_e32 v159, v108
	v_pk_mov_b32 v[62:63], v[24:25], v[152:153] op_sel:[1,0]
	v_mul_f32_e32 v18, 0.5, v29
	v_pk_add_f32 v[62:63], v[158:159], v[62:63] neg_lo:[0,1] neg_hi:[0,1]
	v_sub_f32_e32 v5, v109, v153
	v_pk_mul_f32 v[64:65], v[62:63], v[18:19]
	v_mov_b32_e32 v63, v48
	v_pk_fma_f32 v[68:69], v[48:49], v[64:65], v[64:65] op_sel:[0,1,0] op_sel_hi:[1,0,1]
	v_mov_b32_e32 v64, v65
	v_mov_b32_e32 v65, v18
	v_pk_mul_f32 v[64:65], v[62:63], v[64:65]
	v_mul_f32_e32 v30, 0.5, v28
	v_mul_f32_e32 v52, 0.5, v5
	v_pk_add_f32 v[64:65], v[64:65], v[64:65] op_sel:[0,1] op_sel_hi:[0,1] neg_lo:[0,1] neg_hi:[0,1]
	v_pk_add_f32 v[30:31], v[30:31], v[68:69]
	v_fma_f32 v18, v28, 0.5, -v68
	v_pk_add_f32 v[68:69], v[52:53], v[64:65] op_sel_hi:[0,1] neg_hi:[0,1]
	v_pk_mov_b32 v[28:29], v[30:31], v[18:19] op_sel:[0,0]
	v_pk_mul_f32 v[52:53], v[18:19], v[154:155] op_sel_hi:[0,1]
	v_pk_mul_f32 v[64:65], v[68:69], v[156:157]
	v_pk_mul_f32 v[30:31], v[30:31], v[156:157]
	v_pk_mul_f32 v[68:69], v[68:69], v[154:155]
	v_pk_fma_f32 v[74:75], v[28:29], v[154:155], v[64:65] neg_lo:[0,0,1] neg_hi:[0,0,1]
	v_pk_fma_f32 v[28:29], v[28:29], v[156:157], v[68:69] neg_lo:[0,0,1] neg_hi:[0,0,1]
	v_add_f32_e32 v18, v53, v65
	v_add_f32_e32 v30, v30, v68
	v_pk_add_f32 v[64:65], v[30:31], v[28:29] op_sel_hi:[0,1] neg_lo:[0,1] neg_hi:[0,1]
	v_pk_add_f32 v[68:69], v[74:75], v[18:19] op_sel_hi:[1,0] neg_lo:[0,1] neg_hi:[0,1]
	v_pk_add_f32 v[28:29], v[30:31], v[28:29] op_sel_hi:[0,1]
	v_mov_b32_e32 v69, v29
	v_pk_mul_f32 v[28:29], v[68:69], 0.5 op_sel_hi:[1,0]
	v_pk_add_f32 v[52:53], v[74:75], v[18:19] op_sel_hi:[1,0]
	v_mul_f32_e32 v18, v48, v29
	v_pk_fma_f32 v[30:31], v[62:63], v[28:29], v[18:19] op_sel_hi:[1,1,0] neg_lo:[0,0,1] neg_hi:[0,0,1]
	v_pk_mov_b32 v[68:69], v[48:49], v[62:63] op_sel:[0,0]
	v_mul_f32_e32 v18, v62, v29
	v_pk_fma_f32 v[28:29], v[68:69], v[28:29], v[18:19] op_sel_hi:[1,1,0]
	v_mov_b32_e32 v53, v65
	v_pk_mov_b32 v[62:63], v[28:29], v[30:31] op_sel:[0,0]
	v_pk_fma_f32 v[76:77], v[52:53], 0.5, v[28:29] op_sel_hi:[1,0,1] neg_lo:[0,0,1] neg_hi:[0,0,1]
	v_pk_fma_f32 v[108:109], v[52:53], 0.5, v[62:63] op_sel_hi:[1,0,1]
	v_pk_fma_f32 v[28:29], v[52:53], 0.5, v[28:29] op_sel_hi:[1,0,1]
	v_pk_fma_f32 v[152:153], v[64:65], 0.5, v[30:31] op_sel_hi:[1,0,0] neg_lo:[1,0,0] neg_hi:[1,0,0]
	v_pk_add_f32 v[30:31], v[134:135], v[110:111]
	v_pk_add_f32 v[52:53], v[110:111], v[134:135] neg_lo:[0,1] neg_hi:[0,1]
	v_mul_f32_e32 v18, 0.5, v30
	v_mul_f32_e32 v30, 0.5, v53
	v_mov_b32_e32 v53, v31
	v_pk_mov_b32 v[62:63], v[48:49], v[50:51] op_sel:[1,0]
	v_pk_mul_f32 v[52:53], v[52:53], s[44:45]
	v_mov_b32_e32 v51, v49
	v_pk_mul_f32 v[64:65], v[62:63], v[52:53] op_sel:[0,1] op_sel_hi:[1,0]
	v_pk_mul_f32 v[52:53], v[62:63], v[52:53]
	v_pk_add_f32 v[64:65], v[64:65], v[64:65] op_sel:[0,1] op_sel_hi:[0,1]
	v_pk_add_f32 v[68:69], v[18:19], v[64:65] op_sel_hi:[0,1] neg_hi:[0,1]
	v_pk_add_f32 v[52:53], v[52:53], v[52:53] op_sel:[0,1] op_sel_hi:[0,1] neg_lo:[0,1] neg_hi:[0,1]
	v_pk_add_f32 v[64:65], v[30:31], v[52:53] op_sel_hi:[0,1] neg_hi:[0,1]
	v_pk_mul_f32 v[30:31], v[64:65], v[142:143]
	v_pk_mul_f32 v[52:53], v[64:65], v[140:141]
	v_pk_fma_f32 v[30:31], v[68:69], v[140:141], v[30:31]
	v_pk_fma_f32 v[52:53], v[68:69], v[142:143], v[52:53] neg_lo:[0,0,1] neg_hi:[0,0,1]
	v_mov_b32_e32 v133, v112
	v_pk_add_f32 v[64:65], v[52:53], v[30:31] op_sel:[0,1] op_sel_hi:[1,0] neg_lo:[0,1]
	v_pk_add_f32 v[68:69], v[52:53], v[30:31] op_sel:[0,1] op_sel_hi:[1,0]
	v_pk_add_f32 v[30:31], v[30:31], v[52:53] op_sel:[1,0] op_sel_hi:[0,1] neg_lo:[0,1] neg_hi:[0,1]
	v_pk_mul_f32 v[64:65], v[64:65], 0.5 op_sel_hi:[1,0]
	v_mov_b32_e32 v69, v31
	v_mul_f32_e32 v18, v50, v65
	v_pk_fma_f32 v[74:75], v[62:63], v[64:65], v[18:19] op_sel_hi:[1,1,0] neg_lo:[0,0,1] neg_hi:[0,0,1]
	v_mul_f32_e32 v18, v49, v65
	v_pk_fma_f32 v[134:135], v[30:31], 0.5, v[74:75] op_sel_hi:[1,0,0] neg_lo:[1,0,0] neg_hi:[1,0,0]
	v_pk_add_f32 v[30:31], v[118:119], v[112:113]
	v_mov_b32_e32 v25, v118
	v_pk_fma_f32 v[50:51], v[50:51], v[64:65], v[18:19] op_sel_hi:[1,1,0]
	v_mul_f32_e32 v18, 0.5, v31
	v_pk_add_f32 v[24:25], v[132:133], v[24:25] neg_lo:[0,1] neg_hi:[0,1]
	v_mov_b32_e32 v65, v74
	v_pk_mul_f32 v[74:75], v[24:25], v[18:19]
	v_mov_b32_e32 v64, v50
	v_pk_fma_f32 v[62:63], v[62:63], v[74:75], v[74:75] op_sel:[0,1,0] op_sel_hi:[1,0,1]
	v_pk_mov_b32 v[78:79], v[24:25], v[48:49] op_sel:[0,1]
	v_mov_b32_e32 v74, v75
	v_mov_b32_e32 v75, v18
	v_pk_fma_f32 v[110:111], v[68:69], 0.5, v[64:65] op_sel_hi:[1,0,1]
	v_mul_f32_e32 v64, 0.5, v30
	v_sub_f32_e32 v5, v113, v119
	v_pk_mul_f32 v[74:75], v[78:79], v[74:75]
	v_pk_fma_f32 v[52:53], v[68:69], 0.5, v[50:51] op_sel_hi:[1,0,1] neg_lo:[0,0,1] neg_hi:[0,0,1]
	v_pk_fma_f32 v[50:51], v[68:69], 0.5, v[50:51] op_sel_hi:[1,0,1]
	v_mul_f32_e32 v68, 0.5, v5
	v_pk_add_f32 v[64:65], v[64:65], v[62:63]
	v_fma_f32 v18, v30, 0.5, -v62
	v_pk_add_f32 v[62:63], v[74:75], v[74:75] op_sel:[0,1] op_sel_hi:[0,1] neg_lo:[0,1] neg_hi:[0,1]
	v_pk_add_f32 v[74:75], v[68:69], v[62:63] op_sel_hi:[0,1] neg_hi:[0,1]
	v_pk_mov_b32 v[30:31], v[64:65], v[18:19] op_sel:[0,0]
	v_pk_mul_f32 v[62:63], v[18:19], v[124:125] op_sel_hi:[0,1]
	v_pk_mul_f32 v[68:69], v[74:75], v[126:127]
	v_pk_mul_f32 v[64:65], v[64:65], v[126:127]
	v_pk_mul_f32 v[74:75], v[74:75], v[124:125]
	v_pk_fma_f32 v[80:81], v[30:31], v[124:125], v[68:69] neg_lo:[0,0,1] neg_hi:[0,0,1]
	v_pk_fma_f32 v[30:31], v[30:31], v[126:127], v[74:75] neg_lo:[0,0,1] neg_hi:[0,0,1]
	v_add_f32_e32 v18, v63, v69
	v_add_f32_e32 v64, v64, v74
	v_pk_add_f32 v[68:69], v[64:65], v[30:31] op_sel_hi:[0,1] neg_lo:[0,1] neg_hi:[0,1]
	v_pk_add_f32 v[74:75], v[80:81], v[18:19] op_sel_hi:[1,0] neg_lo:[0,1] neg_hi:[0,1]
	v_pk_add_f32 v[30:31], v[64:65], v[30:31] op_sel_hi:[0,1]
	v_mov_b32_e32 v75, v31
	v_pk_mul_f32 v[30:31], v[74:75], 0.5 op_sel_hi:[1,0]
	v_pk_add_f32 v[62:63], v[80:81], v[18:19] op_sel_hi:[1,0]
	v_mul_f32_e32 v18, v49, v31
	v_pk_fma_f32 v[64:65], v[78:79], v[30:31], v[18:19] op_sel_hi:[1,1,0] neg_lo:[0,0,1] neg_hi:[0,0,1]
	v_pk_mov_b32 v[48:49], v[48:49], v[24:25] op_sel:[1,0]
	v_mul_f32_e32 v18, v24, v31
	v_pk_fma_f32 v[24:25], v[48:49], v[30:31], v[18:19] op_sel_hi:[1,1,0]
	v_mov_b32_e32 v63, v69
	v_pk_mov_b32 v[30:31], v[24:25], v[64:65] op_sel:[0,0]
	v_pk_fma_f32 v[74:75], v[62:63], 0.5, v[24:25] op_sel_hi:[1,0,1] neg_lo:[0,0,1] neg_hi:[0,0,1]
	v_pk_fma_f32 v[112:113], v[62:63], 0.5, v[30:31] op_sel_hi:[1,0,1]
	v_pk_fma_f32 v[48:49], v[62:63], 0.5, v[24:25] op_sel_hi:[1,0,1]
	v_mov_b32_e32 v62, v115
	v_mov_b32_e32 v18, v117
	v_mov_b32_e32 v30, v117
	v_pk_mul_f32 v[62:63], v[138:139], v[62:63] op_sel_hi:[1,0]
	v_pk_fma_f32 v[118:119], v[68:69], 0.5, v[64:65] op_sel_hi:[1,0,0] neg_lo:[1,0,0] neg_hi:[1,0,0]
	v_pk_fma_f32 v[64:65], v[138:139], v[18:19], v[62:63] op_sel:[1,0,0] op_sel_hi:[0,1,1]
	v_pk_fma_f32 v[30:31], v[138:139], v[30:31], v[62:63] op_sel:[1,0,0] op_sel_hi:[0,0,1] neg_lo:[0,0,1] neg_hi:[0,0,1]
	v_pk_add_f32 v[62:63], v[86:87], v[38:39]
	v_pk_add_f32 v[38:39], v[86:87], v[38:39] neg_lo:[0,1] neg_hi:[0,1]
	v_mul_f32_e32 v18, 0.5, v62
	v_mul_f32_e32 v62, 0.5, v39
	v_mov_b32_e32 v39, v63
	v_mov_b32_e32 v65, v31
	v_pk_mul_f32 v[38:39], v[38:39], s[44:45]
	s_mov_b32 s80, s11
	s_mov_b32 s81, s8
	s_mov_b32 s9, s11
	v_cvt_f32_f16_sdwa v69, v47 dst_sel:DWORD dst_unused:UNUSED_PAD src0_sel:WORD_1
	v_cvt_f32_f16_sdwa v78, v46 dst_sel:DWORD dst_unused:UNUSED_PAD src0_sel:WORD_1
	v_pk_mul_f32 v[30:31], v[64:65], s[6:7]
	v_pk_mul_f32 v[64:65], v[38:39], s[80:81]
	v_pk_mul_f32 v[38:39], v[38:39], s[8:9]
	v_cvt_f32_f16_e32 v68, v46
	v_cvt_f32_f16_e32 v79, v47
	v_pk_add_f32 v[64:65], v[64:65], v[64:65] op_sel:[1,0] op_sel_hi:[1,0]
	v_pk_add_f32 v[38:39], v[38:39], v[38:39] op_sel:[0,1] op_sel_hi:[0,1] neg_lo:[0,1] neg_hi:[0,1]
	v_pk_add_f32 v[80:81], v[18:19], v[64:65] op_sel_hi:[0,1]
	v_pk_add_f32 v[90:91], v[62:63], v[38:39] op_sel_hi:[0,1]
	v_pk_add_f32 v[38:39], v[62:63], v[38:39] op_sel_hi:[0,1] neg_lo:[0,1] neg_hi:[0,1]
	v_pk_mov_b32 v[46:47], v[68:69], v[78:79] op_sel:[1,0]
	v_pk_add_f32 v[64:65], v[18:19], v[64:65] op_sel_hi:[0,1] neg_lo:[0,1] neg_hi:[0,1]
	v_pk_mov_b32 v[62:63], v[90:91], v[38:39] op_sel:[0,1]
	v_pk_mov_b32 v[38:39], v[38:39], v[80:81] op_sel:[1,0]
	v_pk_mov_b32 v[86:87], v[80:81], v[64:65] op_sel:[0,1]
	v_pk_mov_b32 v[64:65], v[64:65], v[90:91] op_sel:[1,0]
	v_pk_mov_b32 v[90:91], v[78:79], v[68:69] op_sel:[1,0]
	v_pk_mul_f32 v[38:39], v[38:39], v[46:47]
	v_pk_mul_f32 v[46:47], v[62:63], v[78:79]
	v_pk_fma_f32 v[38:39], v[64:65], v[90:91], v[38:39]
	v_pk_fma_f32 v[46:47], v[86:87], v[68:69], v[46:47] neg_lo:[0,0,1] neg_hi:[0,0,1]
	s_mov_b32 s82, s45
	v_pk_add_f32 v[62:63], v[46:47], v[38:39] neg_lo:[0,1]
	v_pk_add_f32 v[64:65], v[46:47], v[38:39]
	v_pk_add_f32 v[38:39], v[38:39], v[46:47] neg_lo:[0,1] neg_hi:[0,1]
	s_nop 0
	v_pk_mul_f32 v[62:63], v[62:63], 0.5 op_sel_hi:[1,0]
	v_mov_b32_e32 v65, v39
	v_mul_f32_e32 v18, 0x3f7b14be, v62
	v_pk_fma_f32 v[68:69], v[62:63], s[8:9], v[18:19] op_sel_hi:[1,1,0] neg_lo:[1,0,0] neg_hi:[1,0,0]
	v_mul_f32_e32 v18, 0x3f7b14be, v63
	v_pk_fma_f32 v[62:63], v[62:63], s[80:81], v[18:19] op_sel_hi:[1,1,0]
	v_mov_b32_e32 v39, v69
	v_mov_b32_e32 v38, v62
	v_pk_fma_f32 v[46:47], v[64:65], 0.5, v[62:63] op_sel_hi:[1,0,1] neg_lo:[0,0,1] neg_hi:[0,0,1]
	v_pk_fma_f32 v[38:39], v[64:65], 0.5, v[38:39] op_sel_hi:[1,0,1]
	s_mov_b32 s83, s44
	v_mov_b32_e32 v47, v39
	v_pk_mul_f32 v[78:79], v[46:47], s[6:7] op_sel_hi:[1,0]
	v_pk_fma_f32 v[46:47], v[64:65], 0.5, v[68:69] op_sel_hi:[1,0,1] neg_lo:[1,0,0] neg_hi:[1,0,0]
	s_mov_b32 s84, s19
	v_mov_b32_e32 v39, v47
	v_pk_mul_f32 v[144:145], v[38:39], s[6:7] op_sel_hi:[1,0]
	v_pk_add_f32 v[38:39], v[96:97], v[84:85]
	v_pk_add_f32 v[46:47], v[96:97], v[84:85] neg_lo:[0,1] neg_hi:[0,1]
	v_mov_b32_e32 v80, v38
	v_pk_mov_b32 v[38:39], v[38:39], v[46:47] op_sel:[1,0]
	v_cvt_f32_f16_sdwa v62, v36 dst_sel:DWORD dst_unused:UNUSED_PAD src0_sel:WORD_1
	v_pk_mul_f32 v[38:39], v[38:39], s[82:83]
	v_mov_b32_e32 v81, v47
	v_pk_mul_f32 v[46:47], v[38:39], s[84:85] op_sel_hi:[1,0]
	v_cvt_f32_f16_e32 v63, v37
	v_cvt_f32_f16_e32 v65, v36
	v_cvt_f32_f16_sdwa v36, v37 dst_sel:DWORD dst_unused:UNUSED_PAD src0_sel:WORD_1
	v_pk_fma_f32 v[84:85], v[38:39], s[16:17], v[46:47] op_sel:[0,0,1] op_sel_hi:[1,0,0] neg_hi:[0,0,1]
	s_nop 0
	v_mov_b32_e32 v37, v62
	s_nop 0
	v_pk_fma_f32 v[38:39], v[80:81], 0.5, v[84:85] op_sel_hi:[1,0,1] neg_lo:[0,0,1] neg_hi:[0,0,1]
	v_pk_fma_f32 v[46:47], v[80:81], 0.5, v[84:85] op_sel_hi:[1,0,1]
	v_mov_b32_e32 v64, v63
	v_pk_mov_b32 v[84:85], v[38:39], v[46:47] op_sel:[1,0]
	v_mov_b32_e32 v69, v36
	v_pk_mov_b32 v[80:81], v[38:39], v[46:47] op_sel:[0,1]
	v_pk_mul_f32 v[36:37], v[84:85], v[36:37]
	v_mov_b32_e32 v68, v65
	v_pk_fma_f32 v[36:37], v[80:81], v[64:65], v[36:37]
	v_mov_b32_e32 v65, v38
	v_mov_b32_e32 v38, v47
	v_mov_b32_e32 v64, v46
	v_pk_mul_f32 v[38:39], v[38:39], v[62:63]
	v_sub_f32_e32 v13, v148, v149
	v_pk_fma_f32 v[38:39], v[64:65], v[68:69], v[38:39] neg_lo:[0,0,1] neg_hi:[0,0,1]
	v_add_f32_e32 v5, v148, v149
	v_mul_f32_e32 v13, v13, v114
	v_pk_add_f32 v[46:47], v[36:37], v[38:39]
	v_mul_f32_e32 v7, v5, v116
	v_fma_mix_f32 v25, v5, v122, -v13 op_sel_hi:[0,1,0]
	v_pk_add_f32 v[64:65], v[36:37], v[38:39] neg_hi:[0,1]
	v_sub_f32_e32 v5, v38, v36
	v_mul_f32_e32 v36, 0.5, v47
	v_mul_f32_e32 v18, 0.5, v5
	v_pk_mul_f32 v[36:37], v[36:37], s[16:17] op_sel_hi:[0,1]
	v_pk_fma_f32 v[38:39], v[18:19], s[78:79], v[36:37] op_sel_hi:[0,1,1]
	v_pk_fma_f32 v[36:37], v[18:19], s[78:79], v[36:37] op_sel_hi:[0,1,1] neg_lo:[0,0,1] neg_hi:[0,0,1]
	v_pk_mov_b32 v[46:47], v[38:39], v[36:37] op_sel:[0,1]
	v_pk_fma_f32 v[38:39], v[64:65], 0.5, v[38:39] op_sel_hi:[1,0,1] neg_lo:[0,0,1] neg_hi:[0,0,1]
	v_pk_fma_f32 v[46:47], v[64:65], 0.5, v[46:47] op_sel_hi:[1,0,1]
	v_pk_fma_f32 v[36:37], v[64:65], 0.5, v[36:37] op_sel_hi:[1,0,1] neg_lo:[1,0,0] neg_hi:[1,0,0]
	v_mov_b32_e32 v39, v47
	v_pk_mul_f32 v[62:63], v[38:39], s[6:7] op_sel_hi:[1,0]
	v_mov_b32_e32 v47, v37
	v_pk_add_f32 v[36:37], v[42:43], v[44:45]
	v_pk_add_f32 v[38:39], v[42:43], v[44:45] neg_lo:[0,1] neg_hi:[0,1]
	v_mov_b32_e32 v64, v36
	v_pk_mov_b32 v[36:37], v[36:37], v[38:39] op_sel:[1,0]
	s_mov_b32 s86, s27
	v_pk_mul_f32 v[36:37], v[36:37], s[82:83]
	v_cvt_f32_f16_sdwa v42, v26 dst_sel:DWORD dst_unused:UNUSED_PAD src0_sel:WORD_1
	v_mov_b32_e32 v65, v39
	v_pk_mul_f32 v[38:39], v[36:37], s[86:87] op_sel_hi:[1,0]
	v_cvt_f32_f16_e32 v43, v27
	v_cvt_f32_f16_e32 v45, v26
	v_cvt_f32_f16_sdwa v26, v27 dst_sel:DWORD dst_unused:UNUSED_PAD src0_sel:WORD_1
	v_pk_fma_f32 v[68:69], v[36:37], s[24:25], v[38:39] op_sel:[0,0,1] op_sel_hi:[1,0,0] neg_hi:[0,0,1]
	s_nop 0
	v_mov_b32_e32 v27, v42
	s_nop 0
	v_pk_fma_f32 v[36:37], v[64:65], 0.5, v[68:69] op_sel_hi:[1,0,1] neg_lo:[0,0,1] neg_hi:[0,0,1]
	v_pk_fma_f32 v[38:39], v[64:65], 0.5, v[68:69] op_sel_hi:[1,0,1]
	v_pk_mul_f32 v[80:81], v[46:47], s[6:7] op_sel_hi:[1,0]
	v_pk_mov_b32 v[68:69], v[36:37], v[38:39] op_sel:[1,0]
	v_mov_b32_e32 v44, v43
	v_mov_b32_e32 v47, v26
	v_pk_mov_b32 v[64:65], v[36:37], v[38:39] op_sel:[0,1]
	v_pk_mul_f32 v[26:27], v[68:69], v[26:27]
	v_mov_b32_e32 v46, v45
	v_pk_fma_f32 v[26:27], v[64:65], v[44:45], v[26:27]
	v_mov_b32_e32 v45, v36
	v_mov_b32_e32 v36, v39
	v_mov_b32_e32 v44, v38
	v_pk_mul_f32 v[36:37], v[36:37], v[42:43]
	s_mov_b32 s25, s27
	v_pk_fma_f32 v[36:37], v[44:45], v[46:47], v[36:37] neg_lo:[0,0,1] neg_hi:[0,0,1]
	s_mov_b32 s88, s27
	v_pk_add_f32 v[38:39], v[26:27], v[36:37]
	v_pk_add_f32 v[42:43], v[26:27], v[36:37] neg_hi:[0,1]
	v_sub_f32_e32 v5, v36, v26
	v_mul_f32_e32 v26, 0.5, v39
	v_mul_f32_e32 v18, 0.5, v5
	s_mov_b32 s89, s24
	v_pk_mul_f32 v[26:27], v[26:27], s[24:25] op_sel_hi:[0,1]
	v_pk_fma_f32 v[36:37], v[18:19], s[88:89], v[26:27] op_sel_hi:[0,1,1]
	v_pk_fma_f32 v[26:27], v[18:19], s[88:89], v[26:27] op_sel_hi:[0,1,1] neg_lo:[0,0,1] neg_hi:[0,0,1]
	s_nop 0
	v_pk_mov_b32 v[38:39], v[36:37], v[26:27] op_sel:[0,1]
	v_pk_fma_f32 v[36:37], v[42:43], 0.5, v[36:37] op_sel_hi:[1,0,1] neg_lo:[0,0,1] neg_hi:[0,0,1]
	v_pk_fma_f32 v[38:39], v[42:43], 0.5, v[38:39] op_sel_hi:[1,0,1]
	v_pk_fma_f32 v[26:27], v[42:43], 0.5, v[26:27] op_sel_hi:[1,0,1] neg_lo:[1,0,0] neg_hi:[1,0,0]
	v_mov_b32_e32 v37, v39
	v_pk_mul_f32 v[128:129], v[36:37], s[6:7] op_sel_hi:[1,0]
	v_mov_b32_e32 v39, v27
	v_pk_add_f32 v[26:27], v[92:93], v[88:89]
	v_pk_add_f32 v[36:37], v[92:93], v[88:89] neg_lo:[0,1] neg_hi:[0,1]
	v_add_f32_e32 v24, v7, v13
	v_pk_mul_f32 v[120:121], v[38:39], s[6:7] op_sel_hi:[1,0]
	v_mul_f32_e32 v5, 0.5, v27
	v_mul_f32_e32 v7, -0.5, v36
	v_cvt_f32_f16_sdwa v38, v20 dst_sel:DWORD dst_unused:UNUSED_PAD src0_sel:WORD_1
	v_mul_f32_e32 v5, 0x3f3504f3, v5
	v_mul_f32_e32 v13, 0x3f3504f3, v7
	v_cvt_f32_f16_e32 v39, v21
	v_cvt_f32_f16_e32 v43, v20
	v_cvt_f32_f16_sdwa v20, v21 dst_sel:DWORD dst_unused:UNUSED_PAD src0_sel:WORD_1
	v_mov_b32_e32 v27, v37
	v_add_f32_e32 v36, v13, v5
	v_fma_f32 v37, v7, s37, -v5
	v_pk_fma_f32 v[46:47], v[26:27], 0.5, v[36:37] op_sel_hi:[1,0,1] neg_lo:[0,0,1] neg_hi:[0,0,1]
	v_pk_fma_f32 v[26:27], v[26:27], 0.5, v[36:37] op_sel_hi:[1,0,1]
	v_mov_b32_e32 v21, v38
	v_pk_mov_b32 v[64:65], v[46:47], v[26:27] op_sel:[1,0]
	v_mov_b32_e32 v42, v39
	v_mov_b32_e32 v45, v20
	v_pk_mov_b32 v[36:37], v[46:47], v[26:27] op_sel:[0,1]
	v_pk_mul_f32 v[20:21], v[64:65], v[20:21]
	v_mov_b32_e32 v44, v43
	v_pk_fma_f32 v[20:21], v[36:37], v[42:43], v[20:21]
	v_mov_b32_e32 v37, v46
	v_mov_b32_e32 v46, v27
	v_mov_b32_e32 v36, v26
	v_pk_mul_f32 v[26:27], v[46:47], v[38:39]
	v_pk_mul_f32 v[24:25], v[24:25], 0.5 op_sel_hi:[1,0]
	v_pk_fma_f32 v[26:27], v[36:37], v[44:45], v[26:27] neg_lo:[0,0,1] neg_hi:[0,0,1]
	v_pk_mul_f32 v[24:25], v[24:25], s[6:7] op_sel_hi:[1,0]
	v_pk_add_f32 v[36:37], v[20:21], v[26:27]
	v_sub_f32_e32 v5, v26, v20
	v_mul_f32_e32 v7, 0.5, v37
	v_mul_f32_e32 v5, 0.5, v5
	v_mul_f32_e32 v7, 0x3f3504f3, v7
	v_pk_add_f32 v[38:39], v[20:21], v[26:27] neg_hi:[0,1]
	v_mul_f32_e32 v13, 0x3f3504f3, v5
	v_fma_f32 v18, v5, s37, -v7
	v_add_f32_e32 v20, v13, v7
	v_mov_b32_e32 v21, v18
	v_pk_fma_f32 v[26:27], v[38:39], 0.5, v[20:21] op_sel_hi:[1,0,1] neg_lo:[0,0,1]
	v_pk_fma_f32 v[20:21], v[38:39], 0.5, v[20:21] op_sel_hi:[1,0,1]
	v_cvt_f32_f16_e32 v37, v10
	v_pk_mul_f32 v[64:65], v[26:27], s[6:7] op_sel_hi:[1,0]
	v_pk_fma_f32 v[26:27], v[38:39], 0.5, v[18:19] op_sel_hi:[1,0,0] neg_lo:[1,0,0] neg_hi:[1,0,0]
	v_mov_b32_e32 v38, v37
	v_mov_b32_e32 v21, v27
	v_pk_mul_f32 v[68:69], v[20:21], s[6:7] op_sel_hi:[1,0]
	v_pk_add_f32 v[20:21], v[40:41], v[22:23]
	v_pk_add_f32 v[22:23], v[40:41], v[22:23] neg_lo:[0,1] neg_hi:[0,1]
	v_mov_b32_e32 v40, v20
	v_pk_mov_b32 v[20:21], v[20:21], v[22:23] op_sel:[1,0]
	v_cvt_f32_f16_sdwa v26, v10 dst_sel:DWORD dst_unused:UNUSED_PAD src0_sel:WORD_1
	v_pk_mul_f32 v[20:21], v[20:21], s[82:83]
	v_mov_b32_e32 v41, v23
	v_pk_mul_f32 v[22:23], v[20:21], s[24:25] op_sel_hi:[1,0]
	v_cvt_f32_f16_e32 v27, v11
	v_cvt_f32_f16_sdwa v10, v11 dst_sel:DWORD dst_unused:UNUSED_PAD src0_sel:WORD_1
	v_pk_fma_f32 v[42:43], v[20:21], s[86:87], v[22:23] op_sel:[0,0,1] op_sel_hi:[1,0,0] neg_hi:[0,0,1]
	s_nop 0
	v_mov_b32_e32 v11, v26
	s_nop 0
	v_pk_fma_f32 v[20:21], v[40:41], 0.5, v[42:43] op_sel_hi:[1,0,1] neg_lo:[0,0,1] neg_hi:[0,0,1]
	v_pk_fma_f32 v[22:23], v[40:41], 0.5, v[42:43] op_sel_hi:[1,0,1]
	v_mov_b32_e32 v36, v27
	v_pk_mov_b32 v[42:43], v[20:21], v[22:23] op_sel:[1,0]
	v_mov_b32_e32 v39, v10
	v_pk_mov_b32 v[40:41], v[20:21], v[22:23] op_sel:[0,1]
	v_pk_mul_f32 v[10:11], v[42:43], v[10:11]
	v_mov_b32_e32 v7, v161
	v_pk_fma_f32 v[10:11], v[40:41], v[36:37], v[10:11]
	v_mov_b32_e32 v37, v20
	v_mov_b32_e32 v20, v23
	v_mov_b32_e32 v36, v22
	v_pk_mul_f32 v[20:21], v[20:21], v[26:27]
	v_mov_b32_e32 v17, v173
	v_pk_fma_f32 v[20:21], v[36:37], v[38:39], v[20:21] neg_lo:[0,0,1] neg_hi:[0,0,1]
	v_mov_b32_e32 v13, v175
	v_pk_add_f32 v[22:23], v[10:11], v[20:21]
	v_sub_f32_e32 v5, v20, v10
	v_mul_f32_e32 v18, 0.5, v23
	v_pk_add_f32 v[26:27], v[10:11], v[20:21] neg_hi:[0,1]
	v_mul_f32_e32 v10, 0.5, v5
	v_pk_mul_f32 v[20:21], v[18:19], s[88:89] op_sel_hi:[0,1]
	v_pk_fma_f32 v[22:23], v[10:11], s[24:25], v[20:21] op_sel_hi:[0,1,1]
	v_pk_fma_f32 v[10:11], v[10:11], s[24:25], v[20:21] op_sel_hi:[0,1,1] neg_lo:[0,0,1] neg_hi:[0,0,1]
	v_pk_mov_b32 v[20:21], v[22:23], v[10:11] op_sel:[0,1]
	v_pk_fma_f32 v[22:23], v[26:27], 0.5, v[22:23] op_sel_hi:[1,0,1] neg_lo:[0,0,1] neg_hi:[0,0,1]
	v_pk_fma_f32 v[20:21], v[26:27], 0.5, v[20:21] op_sel_hi:[1,0,1]
	v_pk_fma_f32 v[10:11], v[26:27], 0.5, v[10:11] op_sel_hi:[1,0,1] neg_lo:[1,0,0] neg_hi:[1,0,0]
	v_mov_b32_e32 v23, v21
	v_mov_b32_e32 v21, v11
	v_pk_mul_f32 v[150:151], v[20:21], s[6:7] op_sel_hi:[1,0]
	v_pk_add_f32 v[10:11], v[66:67], v[60:61]
	v_pk_add_f32 v[20:21], v[60:61], v[66:67] neg_lo:[0,1] neg_hi:[0,1]
	v_mov_b32_e32 v38, v10
	v_pk_mov_b32 v[10:11], v[10:11], v[20:21] op_sel:[1,0]
	v_pk_mul_f32 v[130:131], v[22:23], s[6:7] op_sel_hi:[1,0]
	v_pk_mul_f32 v[10:11], v[10:11], s[82:83]
	v_cvt_f32_f16_sdwa v22, v8 dst_sel:DWORD dst_unused:UNUSED_PAD src0_sel:WORD_1
	v_mov_b32_e32 v39, v21
	v_pk_mul_f32 v[20:21], v[10:11], s[16:17] op_sel_hi:[1,0]
	v_cvt_f32_f16_e32 v23, v9
	v_cvt_f32_f16_e32 v27, v8
	v_cvt_f32_f16_sdwa v8, v9 dst_sel:DWORD dst_unused:UNUSED_PAD src0_sel:WORD_1
	v_pk_fma_f32 v[40:41], v[10:11], s[84:85], v[20:21] op_sel:[0,0,1] op_sel_hi:[1,0,0] neg_hi:[0,0,1]
	s_nop 0
	v_mov_b32_e32 v9, v22
	s_nop 0
	v_pk_fma_f32 v[10:11], v[38:39], 0.5, v[40:41] op_sel_hi:[1,0,1] neg_lo:[0,0,1] neg_hi:[0,0,1]
	v_pk_fma_f32 v[20:21], v[38:39], 0.5, v[40:41] op_sel_hi:[1,0,1]
	v_mov_b32_e32 v26, v23
	v_pk_mov_b32 v[40:41], v[10:11], v[20:21] op_sel:[1,0]
	v_mov_b32_e32 v37, v8
	v_pk_mov_b32 v[38:39], v[10:11], v[20:21] op_sel:[0,1]
	v_pk_mul_f32 v[8:9], v[40:41], v[8:9]
	v_mov_b32_e32 v36, v27
	v_pk_fma_f32 v[8:9], v[38:39], v[26:27], v[8:9]
	v_mov_b32_e32 v27, v10
	v_mov_b32_e32 v10, v21
	v_mov_b32_e32 v26, v20
	v_pk_mul_f32 v[10:11], v[10:11], v[22:23]
	v_mov_b32_e32 v33, v105
	v_pk_fma_f32 v[10:11], v[26:27], v[36:37], v[10:11] neg_lo:[0,0,1] neg_hi:[0,0,1]
	v_mov_b32_e32 v29, v153
	v_pk_add_f32 v[20:21], v[8:9], v[10:11]
	v_pk_add_f32 v[22:23], v[8:9], v[10:11] neg_hi:[0,1]
	v_sub_f32_e32 v5, v10, v8
	v_mul_f32_e32 v10, 0.5, v21
	v_mul_f32_e32 v8, 0.5, v5
	v_pk_mul_f32 v[10:11], v[10:11], s[78:79] op_sel_hi:[0,1]
	v_pk_fma_f32 v[20:21], v[8:9], s[16:17], v[10:11] op_sel_hi:[0,1,1]
	v_pk_fma_f32 v[8:9], v[8:9], s[16:17], v[10:11] op_sel_hi:[0,1,1] neg_lo:[0,0,1] neg_hi:[0,0,1]
	v_pk_mov_b32 v[10:11], v[20:21], v[8:9] op_sel:[0,1]
	v_pk_fma_f32 v[20:21], v[22:23], 0.5, v[20:21] op_sel_hi:[1,0,1] neg_lo:[0,0,1] neg_hi:[0,0,1]
	v_pk_fma_f32 v[10:11], v[22:23], 0.5, v[10:11] op_sel_hi:[1,0,1]
	v_pk_fma_f32 v[8:9], v[22:23], 0.5, v[8:9] op_sel_hi:[1,0,1] neg_lo:[1,0,0] neg_hi:[1,0,0]
	v_mov_b32_e32 v21, v11
	v_mov_b32_e32 v11, v9
	v_pk_mul_f32 v[90:91], v[10:11], s[6:7] op_sel_hi:[1,0]
	v_pk_add_f32 v[8:9], v[34:35], v[14:15]
	v_pk_add_f32 v[10:11], v[14:15], v[34:35] neg_lo:[0,1] neg_hi:[0,1]
	v_mov_b32_e32 v26, v8
	v_pk_mov_b32 v[8:9], v[8:9], v[10:11] op_sel:[1,0]
	v_cvt_f32_f16_sdwa v14, v2 dst_sel:DWORD dst_unused:UNUSED_PAD src0_sel:WORD_1
	v_pk_mul_f32 v[8:9], v[8:9], s[82:83]
	v_mov_b32_e32 v27, v11
	s_mov_b32 s78, s11
	v_pk_mul_f32 v[10:11], v[8:9], s[8:9] op_sel_hi:[1,0]
	v_pk_mul_f32 v[94:95], v[20:21], s[6:7] op_sel_hi:[1,0]
	v_cvt_f32_f16_e32 v15, v3
	v_cvt_f32_f16_e32 v21, v2
	v_cvt_f32_f16_sdwa v2, v3 dst_sel:DWORD dst_unused:UNUSED_PAD src0_sel:WORD_1
	v_pk_fma_f32 v[34:35], v[8:9], s[78:79], v[10:11] op_sel:[0,0,1] op_sel_hi:[1,0,0] neg_hi:[0,0,1]
	s_nop 0
	v_mov_b32_e32 v3, v14
	s_nop 0
	v_pk_fma_f32 v[8:9], v[26:27], 0.5, v[34:35] op_sel_hi:[1,0,1] neg_lo:[0,0,1] neg_hi:[0,0,1]
	v_pk_fma_f32 v[10:11], v[26:27], 0.5, v[34:35] op_sel_hi:[1,0,1]
	v_mov_b32_e32 v20, v15
	v_pk_mov_b32 v[34:35], v[8:9], v[10:11] op_sel:[1,0]
	v_mov_b32_e32 v23, v2
	v_pk_mov_b32 v[26:27], v[8:9], v[10:11] op_sel:[0,1]
	v_pk_mul_f32 v[2:3], v[34:35], v[2:3]
	v_mov_b32_e32 v22, v21
	v_pk_fma_f32 v[2:3], v[26:27], v[20:21], v[2:3]
	v_mov_b32_e32 v21, v8
	v_mov_b32_e32 v8, v11
	v_mov_b32_e32 v20, v10
	v_pk_mul_f32 v[8:9], v[8:9], v[14:15]
	v_mov_b32_e32 v5, v171
	v_pk_fma_f32 v[8:9], v[20:21], v[22:23], v[8:9] neg_lo:[0,0,1] neg_hi:[0,0,1]
	v_mov_b32_e32 v51, v135
	v_pk_add_f32 v[10:11], v[2:3], v[8:9]
	v_pk_add_f32 v[14:15], v[2:3], v[8:9] neg_hi:[0,1]
	v_sub_f32_e32 v2, v8, v2
	v_mul_f32_e32 v8, 0.5, v11
	v_mul_f32_e32 v2, 0.5, v2
	v_pk_mul_f32 v[8:9], v[8:9], s[80:81] op_sel_hi:[0,1]
	v_pk_fma_f32 v[10:11], v[2:3], s[8:9], v[8:9] op_sel_hi:[0,1,1]
	v_pk_fma_f32 v[2:3], v[2:3], s[8:9], v[8:9] op_sel_hi:[0,1,1] neg_lo:[0,0,1] neg_hi:[0,0,1]
	v_pk_mov_b32 v[8:9], v[10:11], v[2:3] op_sel:[0,1]
	v_pk_fma_f32 v[10:11], v[14:15], 0.5, v[10:11] op_sel_hi:[1,0,1] neg_lo:[0,0,1] neg_hi:[0,0,1]
	v_pk_fma_f32 v[8:9], v[14:15], 0.5, v[8:9] op_sel_hi:[1,0,1]
	v_pk_fma_f32 v[2:3], v[14:15], 0.5, v[2:3] op_sel_hi:[1,0,1] neg_lo:[1,0,0] neg_hi:[1,0,0]
	v_mov_b32_e32 v11, v9
	v_mov_b32_e32 v9, v3
	v_pk_mul_f32 v[168:169], v[10:11], s[6:7] op_sel_hi:[1,0]
	v_pk_mul_f32 v[136:137], v[8:9], s[6:7] op_sel_hi:[1,0]
	v_mov_b32_e32 v49, v119
	v_mov_b32_e32 v75, v113
	v_mov_b32_e32 v53, v111
	v_mov_b32_e32 v77, v109
	v_mov_b32_e32 v57, v83
	v_mov_b32_e32 v71, v107
	v_mov_b32_e32 v55, v103
	v_mov_b32_e32 v73, v101
	v_mov_b32_e32 v59, v99

.LBB0_511:
	s_or_b64 exec, exec, s[0:1]
	v_mov_b32_e32 v25, v210
	s_mov_b32 s72, s37
	v_and_b32_e32 v28, 0x1ff, v25
	v_cvt_f32_u32_e32 v34, v28
	v_lshlrev_b32_e32 v25, 5, v25
	v_and_or_b32 v25, v25, s94, v28
	v_ashrrev_i32_e32 v28, 5, v25
	v_mul_f32_e32 v34, 0x38800000, v34
	v_sin_f32_e32 v43, v34
	v_cos_f32_e32 v42, v34
	v_lshlrev_b32_e32 v25, 3, v25
	v_lshlrev_b32_e32 v28, 3, v28
	v_pk_mul_f32 v[44:45], v[42:43], 1.0 op_sel:[1,0] op_sel_hi:[1,0] neg_lo:[1,0]
	s_nop 0
	v_pk_mul_f32 v[46:47], v[42:43], v[44:45] op_sel:[1,0] op_sel_hi:[0,1]
	v_pk_fma_f32 v[46:47], v[42:43], v[42:43], v[46:47] op_sel_hi:[1,0,1]
	v_add3_u32 v25, 0, v25, v28
	v_pk_mul_f32 v[50:51], 1.0, v[46:47] op_sel:[0,1] op_sel_hi:[0,1] neg_lo:[0,1]
	v_pk_mul_f32 v[52:53], v[46:47], v[50:51] op_sel:[1,0] op_sel_hi:[0,1]
	v_pk_fma_f32 v[52:53], v[46:47], v[46:47], v[52:53] op_sel_hi:[1,0,1]
	v_add_u32_e32 v28, 0x10800, v25
	v_pk_mul_f32 v[54:55], 1.0, v[52:53] op_sel:[0,1] op_sel_hi:[0,1] neg_lo:[0,1]
	v_pk_mul_f32 v[70:71], v[52:53], v[54:55] op_sel:[1,0] op_sel_hi:[0,1]
	v_pk_fma_f32 v[70:71], v[52:53], v[52:53], v[70:71] op_sel_hi:[1,0,1]
	v_pk_mul_f32 v[48:49], v[44:45], v[46:47] op_sel:[0,1] op_sel_hi:[1,0]
	v_pk_mul_f32 v[86:87], v[54:55], v[70:71] op_sel:[0,1] op_sel_hi:[1,0]
	ds_read_b64 v[168:169], v25
	ds_read_b64 v[170:171], v25 offset:4224
	ds_read_b64 v[172:173], v25 offset:8448
	ds_read_b64 v[174:175], v25 offset:12672
	ds_read_b64 v[176:177], v25 offset:16896
	ds_read_b64 v[178:179], v25 offset:21120
	ds_read_b64 v[180:181], v25 offset:25344
	ds_read_b64 v[182:183], v25 offset:29568
	ds_read_b64 v[184:185], v25 offset:33792
	ds_read_b64 v[186:187], v25 offset:38016
	ds_read_b64 v[188:189], v25 offset:42240
	ds_read_b64 v[190:191], v25 offset:46464
	ds_read_b64 v[192:193], v25 offset:50688
	ds_read_b64 v[194:195], v25 offset:54912
	ds_read_b64 v[196:197], v25 offset:59136
	ds_read_b64 v[198:199], v25 offset:63360
	v_pk_fma_f32 v[86:87], v[52:53], v[70:71], v[86:87] op_sel_hi:[0,1,1]
	v_pk_mul_f32 v[102:103], v[54:55], v[86:87] op_sel:[0,1] op_sel_hi:[1,0]
	v_add_u32_e32 v34, 0x11880, v25
	v_pk_fma_f32 v[102:103], v[52:53], v[86:87], v[102:103] op_sel_hi:[0,1,1]
	v_pk_mul_f32 v[118:119], v[54:55], v[102:103] op_sel:[0,1] op_sel_hi:[1,0]
	v_add_u32_e32 v38, 0x12900, v25
	v_pk_fma_f32 v[118:119], v[52:53], v[102:103], v[118:119] op_sel_hi:[0,1,1]
	v_pk_mul_f32 v[134:135], v[54:55], v[118:119] op_sel:[0,1] op_sel_hi:[1,0]
	v_add_u32_e32 v40, 0x13980, v25
	v_pk_fma_f32 v[134:135], v[52:53], v[118:119], v[134:135] op_sel_hi:[0,1,1]
	v_pk_mul_f32 v[152:153], v[54:55], v[134:135] op_sel:[0,1] op_sel_hi:[1,0]
	ds_read_b64 v[212:213], v28
	ds_read_b64 v[214:215], v34
	ds_read_b64 v[216:217], v38
	ds_read_b64 v[218:219], v40
	v_add_u32_e32 v28, 0x14a00, v25
	v_pk_fma_f32 v[48:49], v[42:43], v[46:47], v[48:49] op_sel_hi:[0,1,1]
	v_pk_fma_f32 v[152:153], v[52:53], v[134:135], v[152:153] op_sel_hi:[0,1,1]
	v_add_u32_e32 v34, 0x15a80, v25
	v_add_u32_e32 v38, 0x16b00, v25
	v_add_u32_e32 v40, 0x17b80, v25
	ds_read_b64 v[220:221], v28
	ds_read_b64 v[222:223], v34
	ds_read_b64 v[224:225], v38
	ds_read_b64 v[226:227], v40
	v_add_u32_e32 v28, 0x18c00, v25
	v_pk_mul_f32 v[56:57], v[48:49], 1.0 op_sel:[1,0] op_sel_hi:[1,0] neg_lo:[1,0]
	v_pk_mul_f32 v[58:59], v[44:45], v[52:53] op_sel:[0,1] op_sel_hi:[1,0]
	v_pk_mul_f32 v[74:75], v[44:45], v[70:71] op_sel:[0,1] op_sel_hi:[1,0]
	v_pk_mul_f32 v[90:91], v[44:45], v[86:87] op_sel:[0,1] op_sel_hi:[1,0]
	v_pk_mul_f32 v[106:107], v[44:45], v[102:103] op_sel:[0,1] op_sel_hi:[1,0]
	v_pk_mul_f32 v[122:123], v[44:45], v[118:119] op_sel:[0,1] op_sel_hi:[1,0]
	v_pk_mul_f32 v[138:139], v[44:45], v[134:135] op_sel:[0,1] op_sel_hi:[1,0]
	v_pk_mul_f32 v[156:157], v[44:45], v[152:153] op_sel:[0,1] op_sel_hi:[1,0]
	v_add_u32_e32 v34, 0x19c80, v25
	v_add_u32_e32 v38, 0x1ad00, v25
	v_add_u32_e32 v40, 0x1bd80, v25
	ds_read_b64 v[228:229], v28
	ds_read_b64 v[230:231], v34
	ds_read_b64 v[232:233], v38
	ds_read_b64 v[234:235], v40
	v_add_u32_e32 v28, 0x1ce00, v25
	s_waitcnt lgkmcnt(11)
	v_pk_mul_f32 v[44:45], v[44:45], v[212:213] op_sel:[0,1] op_sel_hi:[1,0]
	v_pk_fma_f32 v[58:59], v[42:43], v[52:53], v[58:59] op_sel_hi:[0,1,1]
	v_pk_mul_f32 v[62:63], v[50:51], v[52:53] op_sel:[0,1] op_sel_hi:[1,0]
	v_pk_mul_f32 v[66:67], v[52:53], v[56:57] op_sel:[1,0] op_sel_hi:[0,1]
	v_pk_fma_f32 v[74:75], v[42:43], v[70:71], v[74:75] op_sel_hi:[0,1,1]
	v_pk_mul_f32 v[78:79], v[50:51], v[70:71] op_sel:[0,1] op_sel_hi:[1,0]
	v_pk_fma_f32 v[90:91], v[42:43], v[86:87], v[90:91] op_sel_hi:[0,1,1]
	v_pk_mul_f32 v[94:95], v[50:51], v[86:87] op_sel:[0,1] op_sel_hi:[1,0]
	v_pk_fma_f32 v[106:107], v[42:43], v[102:103], v[106:107] op_sel_hi:[0,1,1]
	v_pk_mul_f32 v[110:111], v[50:51], v[102:103] op_sel:[0,1] op_sel_hi:[1,0]
	v_pk_fma_f32 v[122:123], v[42:43], v[118:119], v[122:123] op_sel_hi:[0,1,1]
	v_pk_mul_f32 v[126:127], v[50:51], v[118:119] op_sel:[0,1] op_sel_hi:[1,0]
	v_pk_fma_f32 v[138:139], v[42:43], v[134:135], v[138:139] op_sel_hi:[0,1,1]
	v_pk_mul_f32 v[142:143], v[50:51], v[134:135] op_sel:[0,1] op_sel_hi:[1,0]
	v_pk_fma_f32 v[156:157], v[42:43], v[152:153], v[156:157] op_sel_hi:[0,1,1]
	v_pk_mul_f32 v[160:161], v[50:51], v[152:153] op_sel:[0,1] op_sel_hi:[1,0]
	v_add_u32_e32 v34, 0x1de80, v25
	v_add_u32_e32 v38, 0x1ef00, v25
	v_add_u32_e32 v40, 0x1ff80, v25
	ds_read_b64 v[236:237], v28
	ds_read_b64 v[238:239], v34
	ds_read_b64 v[240:241], v38
	ds_read_b64 v[242:243], v40
	v_pk_fma_f32 v[42:43], v[42:43], v[212:213], v[44:45] op_sel_hi:[0,1,1]
	v_pk_mul_f32 v[44:45], v[184:185], v[50:51] op_sel:[1,0] op_sel_hi:[0,1]
	v_pk_fma_f32 v[62:63], v[46:47], v[52:53], v[62:63] op_sel_hi:[0,1,1]
	v_pk_fma_f32 v[66:67], v[52:53], v[48:49], v[66:67] op_sel_hi:[1,0,1]
	v_pk_fma_f32 v[78:79], v[46:47], v[70:71], v[78:79] op_sel_hi:[0,1,1]
	v_pk_mul_f32 v[82:83], v[56:57], v[70:71] op_sel:[0,1] op_sel_hi:[1,0]
	v_pk_fma_f32 v[94:95], v[46:47], v[86:87], v[94:95] op_sel_hi:[0,1,1]
	v_pk_mul_f32 v[98:99], v[56:57], v[86:87] op_sel:[0,1] op_sel_hi:[1,0]
	v_pk_fma_f32 v[110:111], v[46:47], v[102:103], v[110:111] op_sel_hi:[0,1,1]
	v_pk_mul_f32 v[114:115], v[56:57], v[102:103] op_sel:[0,1] op_sel_hi:[1,0]
	v_pk_fma_f32 v[126:127], v[46:47], v[118:119], v[126:127] op_sel_hi:[0,1,1]
	v_pk_mul_f32 v[130:131], v[56:57], v[118:119] op_sel:[0,1] op_sel_hi:[1,0]
	v_pk_fma_f32 v[142:143], v[46:47], v[134:135], v[142:143] op_sel_hi:[0,1,1]
	v_pk_mul_f32 v[148:149], v[56:57], v[134:135] op_sel:[0,1] op_sel_hi:[1,0]
	v_pk_fma_f32 v[160:161], v[46:47], v[152:153], v[160:161] op_sel_hi:[0,1,1]
	v_pk_mul_f32 v[164:165], v[56:57], v[152:153] op_sel:[0,1] op_sel_hi:[1,0]
	v_pk_fma_f32 v[44:45], v[184:185], v[46:47], v[44:45] op_sel_hi:[1,0,1]
	s_waitcnt lgkmcnt(7)
	v_pk_mul_f32 v[46:47], v[56:57], v[228:229] op_sel:[0,1] op_sel_hi:[1,0]
	v_xor_b32_e32 v60, 0x80000000, v59
	v_xor_b32_e32 v64, 0x80000000, v63
	v_xor_b32_e32 v68, 0x80000000, v67
	v_xor_b32_e32 v72, 0x80000000, v71
	v_pk_fma_f32 v[82:83], v[48:49], v[70:71], v[82:83] op_sel_hi:[0,1,1]
	v_pk_fma_f32 v[98:99], v[48:49], v[86:87], v[98:99] op_sel_hi:[0,1,1]
	v_pk_fma_f32 v[114:115], v[48:49], v[102:103], v[114:115] op_sel_hi:[0,1,1]
	v_pk_fma_f32 v[130:131], v[48:49], v[118:119], v[130:131] op_sel_hi:[0,1,1]
	v_pk_fma_f32 v[148:149], v[48:49], v[134:135], v[148:149] op_sel_hi:[0,1,1]
	v_pk_fma_f32 v[164:165], v[48:49], v[152:153], v[164:165] op_sel_hi:[0,1,1]
	v_mov_b32_e32 v61, v59
	v_mov_b32_e32 v65, v63
	v_mov_b32_e32 v69, v67
	v_mov_b32_e32 v73, v71
	v_pk_fma_f32 v[46:47], v[48:49], v[228:229], v[46:47] op_sel_hi:[0,1,1]
	v_pk_mul_f32 v[48:49], v[176:177], v[54:55] op_sel:[1,0] op_sel_hi:[0,1]
	v_xor_b32_e32 v76, 0x80000000, v75
	v_xor_b32_e32 v80, 0x80000000, v79
	v_xor_b32_e32 v84, 0x80000000, v83
	v_xor_b32_e32 v88, 0x80000000, v87
	v_xor_b32_e32 v92, 0x80000000, v91
	v_xor_b32_e32 v96, 0x80000000, v95
	v_xor_b32_e32 v100, 0x80000000, v99
	v_xor_b32_e32 v104, 0x80000000, v103
	v_xor_b32_e32 v136, 0x80000000, v135
	v_mov_b32_e32 v77, v75
	v_mov_b32_e32 v81, v79
	v_mov_b32_e32 v85, v83
	v_mov_b32_e32 v89, v87
	v_mov_b32_e32 v93, v91
	v_mov_b32_e32 v97, v95
	v_mov_b32_e32 v101, v99
	v_mov_b32_e32 v105, v103
	v_mov_b32_e32 v137, v135
	v_pk_fma_f32 v[48:49], v[176:177], v[52:53], v[48:49] op_sel_hi:[1,0,1]
	v_pk_mul_f32 v[50:51], v[60:61], v[220:221] op_sel:[0,1] op_sel_hi:[1,0]
	v_pk_mul_f32 v[52:53], v[192:193], v[64:65] op_sel:[1,0] op_sel_hi:[0,1]
	s_waitcnt lgkmcnt(3)
	v_pk_mul_f32 v[54:55], v[68:69], v[236:237] op_sel:[0,1] op_sel_hi:[1,0]
	v_pk_mul_f32 v[56:57], v[172:173], v[72:73] op_sel:[1,0] op_sel_hi:[0,1]
	v_xor_b32_e32 v108, 0x80000000, v107
	v_xor_b32_e32 v112, 0x80000000, v111
	v_xor_b32_e32 v116, 0x80000000, v115
	v_xor_b32_e32 v120, 0x80000000, v119
	v_xor_b32_e32 v124, 0x80000000, v123
	v_xor_b32_e32 v128, 0x80000000, v127
	v_xor_b32_e32 v132, 0x80000000, v131
	v_xor_b32_e32 v140, 0x80000000, v139
	v_xor_b32_e32 v144, 0x80000000, v143
	v_xor_b32_e32 v150, 0x80000000, v149
	v_xor_b32_e32 v154, 0x80000000, v153
	v_xor_b32_e32 v158, 0x80000000, v157
	v_xor_b32_e32 v162, 0x80000000, v161
	v_xor_b32_e32 v166, 0x80000000, v165
	v_mov_b32_e32 v109, v107
	v_mov_b32_e32 v113, v111
	v_mov_b32_e32 v117, v115
	v_mov_b32_e32 v121, v119
	v_mov_b32_e32 v125, v123
	v_mov_b32_e32 v129, v127
	v_mov_b32_e32 v133, v131
	v_mov_b32_e32 v141, v139
	v_mov_b32_e32 v145, v143
	v_mov_b32_e32 v151, v149
	v_mov_b32_e32 v155, v153
	v_mov_b32_e32 v159, v157
	v_mov_b32_e32 v163, v161
	v_mov_b32_e32 v167, v165
	v_pk_fma_f32 v[50:51], v[58:59], v[220:221], v[50:51] op_sel_hi:[0,1,1]
	v_pk_fma_f32 v[52:53], v[192:193], v[62:63], v[52:53] op_sel_hi:[1,0,1]
	v_pk_fma_f32 v[54:55], v[66:67], v[236:237], v[54:55] op_sel_hi:[0,1,1]
	v_pk_fma_f32 v[56:57], v[172:173], v[70:71], v[56:57] op_sel_hi:[1,0,1]
	v_pk_mul_f32 v[58:59], v[216:217], v[76:77] op_sel:[1,0] op_sel_hi:[0,1]
	v_pk_mul_f32 v[60:61], v[188:189], v[80:81] op_sel:[1,0] op_sel_hi:[0,1]
	v_pk_mul_f32 v[62:63], v[84:85], v[232:233] op_sel:[0,1] op_sel_hi:[1,0]
	v_pk_mul_f32 v[64:65], v[180:181], v[88:89] op_sel:[1,0] op_sel_hi:[0,1]
	v_pk_mul_f32 v[66:67], v[224:225], v[92:93] op_sel:[1,0] op_sel_hi:[0,1]
	v_pk_mul_f32 v[68:69], v[196:197], v[96:97] op_sel:[1,0] op_sel_hi:[0,1]
	s_waitcnt lgkmcnt(1)
	v_pk_mul_f32 v[70:71], v[100:101], v[240:241] op_sel:[0,1] op_sel_hi:[1,0]
	v_pk_mul_f32 v[72:73], v[170:171], v[104:105] op_sel:[1,0] op_sel_hi:[0,1]
	v_pk_mul_f32 v[88:89], v[174:175], v[136:137] op_sel:[1,0] op_sel_hi:[0,1]
	v_pk_fma_f32 v[58:59], v[216:217], v[74:75], v[58:59] op_sel_hi:[1,0,1]
	v_pk_fma_f32 v[60:61], v[188:189], v[78:79], v[60:61] op_sel_hi:[1,0,1]
	v_pk_fma_f32 v[62:63], v[82:83], v[232:233], v[62:63] op_sel_hi:[0,1,1]
	v_pk_fma_f32 v[64:65], v[180:181], v[86:87], v[64:65] op_sel_hi:[1,0,1]
	v_pk_fma_f32 v[66:67], v[224:225], v[90:91], v[66:67] op_sel_hi:[1,0,1]
	v_pk_fma_f32 v[68:69], v[196:197], v[94:95], v[68:69] op_sel_hi:[1,0,1]
	v_pk_fma_f32 v[70:71], v[98:99], v[240:241], v[70:71] op_sel_hi:[0,1,1]
	v_pk_fma_f32 v[72:73], v[170:171], v[102:103], v[72:73] op_sel_hi:[1,0,1]
	v_pk_mul_f32 v[74:75], v[214:215], v[108:109] op_sel:[1,0] op_sel_hi:[0,1]
	v_pk_mul_f32 v[76:77], v[186:187], v[112:113] op_sel:[1,0] op_sel_hi:[0,1]
	v_pk_mul_f32 v[78:79], v[230:231], v[116:117] op_sel:[1,0] op_sel_hi:[0,1]
	v_pk_mul_f32 v[80:81], v[178:179], v[120:121] op_sel:[1,0] op_sel_hi:[0,1]
	v_pk_mul_f32 v[82:83], v[222:223], v[124:125] op_sel:[1,0] op_sel_hi:[0,1]
	v_pk_mul_f32 v[84:85], v[194:195], v[128:129] op_sel:[1,0] op_sel_hi:[0,1]
	v_pk_mul_f32 v[86:87], v[132:133], v[238:239] op_sel:[0,1] op_sel_hi:[1,0]
	v_pk_fma_f32 v[88:89], v[174:175], v[134:135], v[88:89] op_sel_hi:[1,0,1]
	v_pk_mul_f32 v[90:91], v[218:219], v[140:141] op_sel:[1,0] op_sel_hi:[0,1]
	v_pk_mul_f32 v[92:93], v[190:191], v[144:145] op_sel:[1,0] op_sel_hi:[0,1]
	v_pk_mul_f32 v[94:95], v[234:235], v[150:151] op_sel:[1,0] op_sel_hi:[0,1]
	v_pk_mul_f32 v[96:97], v[182:183], v[154:155] op_sel:[1,0] op_sel_hi:[0,1]
	v_pk_mul_f32 v[98:99], v[226:227], v[158:159] op_sel:[1,0] op_sel_hi:[0,1]
	v_pk_mul_f32 v[100:101], v[198:199], v[162:163] op_sel:[1,0] op_sel_hi:[0,1]
	s_waitcnt lgkmcnt(0)
	v_pk_mul_f32 v[102:103], v[242:243], v[166:167] op_sel:[1,0] op_sel_hi:[0,1]
	v_pk_fma_f32 v[74:75], v[214:215], v[106:107], v[74:75] op_sel_hi:[1,0,1]
	v_pk_fma_f32 v[76:77], v[186:187], v[110:111], v[76:77] op_sel_hi:[1,0,1]
	v_pk_fma_f32 v[78:79], v[230:231], v[114:115], v[78:79] op_sel_hi:[1,0,1]
	v_pk_fma_f32 v[80:81], v[178:179], v[118:119], v[80:81] op_sel_hi:[1,0,1]
	v_pk_fma_f32 v[82:83], v[222:223], v[122:123], v[82:83] op_sel_hi:[1,0,1]
	v_pk_fma_f32 v[84:85], v[194:195], v[126:127], v[84:85] op_sel_hi:[1,0,1]
	v_pk_fma_f32 v[86:87], v[130:131], v[238:239], v[86:87] op_sel_hi:[0,1,1]
	v_pk_fma_f32 v[90:91], v[218:219], v[138:139], v[90:91] op_sel_hi:[1,0,1]
	v_pk_fma_f32 v[92:93], v[190:191], v[142:143], v[92:93] op_sel_hi:[1,0,1]
	v_pk_fma_f32 v[94:95], v[234:235], v[148:149], v[94:95] op_sel_hi:[1,0,1]
	v_pk_fma_f32 v[96:97], v[182:183], v[152:153], v[96:97] op_sel_hi:[1,0,1]
	v_pk_fma_f32 v[98:99], v[226:227], v[156:157], v[98:99] op_sel_hi:[1,0,1]
	v_pk_fma_f32 v[100:101], v[198:199], v[160:161], v[100:101] op_sel_hi:[1,0,1]
	v_pk_fma_f32 v[102:103], v[242:243], v[164:165], v[102:103] op_sel_hi:[1,0,1]
	v_pk_add_f32 v[104:105], v[168:169], v[72:73]
	v_pk_add_f32 v[106:107], v[56:57], v[88:89]
	v_pk_add_f32 v[56:57], v[56:57], v[88:89] neg_lo:[0,1] neg_hi:[0,1]
	v_pk_add_f32 v[72:73], v[168:169], v[72:73] neg_lo:[0,1] neg_hi:[0,1]
	v_pk_add_f32 v[88:89], v[48:49], v[80:81]
	v_pk_add_f32 v[48:49], v[48:49], v[80:81] neg_lo:[0,1] neg_hi:[0,1]
	v_pk_add_f32 v[80:81], v[64:65], v[96:97]
	v_pk_add_f32 v[64:65], v[64:65], v[96:97] neg_lo:[0,1] neg_hi:[0,1]
	v_pk_add_f32 v[96:97], v[44:45], v[76:77]
	v_pk_add_f32 v[44:45], v[44:45], v[76:77] neg_lo:[0,1] neg_hi:[0,1]
	v_pk_add_f32 v[76:77], v[60:61], v[92:93]
	v_pk_add_f32 v[60:61], v[60:61], v[92:93] neg_lo:[0,1] neg_hi:[0,1]
	v_pk_add_f32 v[92:93], v[52:53], v[84:85]
	v_pk_add_f32 v[52:53], v[52:53], v[84:85] neg_lo:[0,1] neg_hi:[0,1]
	v_pk_add_f32 v[84:85], v[68:69], v[100:101]
	v_pk_add_f32 v[68:69], v[68:69], v[100:101] neg_lo:[0,1] neg_hi:[0,1]
	v_pk_add_f32 v[100:101], v[42:43], v[74:75]
	v_pk_add_f32 v[42:43], v[42:43], v[74:75] neg_lo:[0,1] neg_hi:[0,1]
	v_pk_add_f32 v[74:75], v[58:59], v[90:91]
	v_pk_add_f32 v[58:59], v[58:59], v[90:91] neg_lo:[0,1] neg_hi:[0,1]
	v_pk_add_f32 v[90:91], v[50:51], v[82:83]
	v_pk_add_f32 v[50:51], v[50:51], v[82:83] neg_lo:[0,1] neg_hi:[0,1]
	v_pk_add_f32 v[82:83], v[66:67], v[98:99]
	v_pk_add_f32 v[66:67], v[66:67], v[98:99] neg_lo:[0,1] neg_hi:[0,1]
	v_pk_add_f32 v[98:99], v[46:47], v[78:79]
	v_pk_add_f32 v[46:47], v[46:47], v[78:79] neg_lo:[0,1] neg_hi:[0,1]
	v_pk_add_f32 v[78:79], v[62:63], v[94:95]
	v_pk_add_f32 v[62:63], v[62:63], v[94:95] neg_lo:[0,1] neg_hi:[0,1]
	v_pk_add_f32 v[94:95], v[54:55], v[86:87]
	v_pk_add_f32 v[54:55], v[54:55], v[86:87] neg_lo:[0,1] neg_hi:[0,1]
	v_pk_add_f32 v[86:87], v[70:71], v[102:103]
	v_pk_add_f32 v[70:71], v[70:71], v[102:103] neg_lo:[0,1] neg_hi:[0,1]
	v_pk_add_f32 v[102:103], v[104:105], v[106:107]
	v_pk_add_f32 v[104:105], v[104:105], v[106:107] neg_lo:[0,1] neg_hi:[0,1]
	v_pk_mul_f32 v[106:107], v[56:57], 1.0 op_sel:[1,0] op_sel_hi:[0,0] neg_lo:[1,0]
	v_pk_add_f32 v[56:57], v[72:73], v[106:107]
	v_pk_add_f32 v[72:73], v[72:73], v[106:107] neg_lo:[0,1] neg_hi:[0,1]
	v_pk_add_f32 v[106:107], v[88:89], v[80:81]
	v_pk_add_f32 v[80:81], v[88:89], v[80:81] neg_lo:[0,1] neg_hi:[0,1]
	v_pk_mul_f32 v[88:89], v[64:65], 1.0 op_sel:[1,0] op_sel_hi:[0,0] neg_lo:[1,0]
	v_pk_add_f32 v[64:65], v[48:49], v[88:89]
	v_pk_add_f32 v[48:49], v[48:49], v[88:89] neg_lo:[0,1] neg_hi:[0,1]
	v_pk_add_f32 v[88:89], v[96:97], v[76:77]
	v_pk_add_f32 v[76:77], v[96:97], v[76:77] neg_lo:[0,1] neg_hi:[0,1]
	v_pk_mul_f32 v[96:97], v[60:61], 1.0 op_sel:[1,0] op_sel_hi:[0,0] neg_lo:[1,0]
	v_pk_add_f32 v[60:61], v[44:45], v[96:97]
	v_pk_add_f32 v[44:45], v[44:45], v[96:97] neg_lo:[0,1] neg_hi:[0,1]
	v_pk_add_f32 v[96:97], v[92:93], v[84:85]
	v_pk_add_f32 v[84:85], v[92:93], v[84:85] neg_lo:[0,1] neg_hi:[0,1]
	v_pk_mul_f32 v[92:93], v[68:69], 1.0 op_sel:[1,0] op_sel_hi:[0,0] neg_lo:[1,0]
	v_pk_add_f32 v[68:69], v[52:53], v[92:93]
	v_pk_add_f32 v[52:53], v[52:53], v[92:93] neg_lo:[0,1] neg_hi:[0,1]
	v_pk_add_f32 v[92:93], v[100:101], v[74:75]
	v_pk_add_f32 v[74:75], v[100:101], v[74:75] neg_lo:[0,1] neg_hi:[0,1]
	v_pk_mul_f32 v[100:101], v[58:59], 1.0 op_sel:[1,0] op_sel_hi:[0,0] neg_lo:[1,0]
	v_pk_add_f32 v[58:59], v[42:43], v[100:101]
	v_pk_add_f32 v[42:43], v[42:43], v[100:101] neg_lo:[0,1] neg_hi:[0,1]
	v_pk_add_f32 v[100:101], v[90:91], v[82:83]
	v_pk_add_f32 v[82:83], v[90:91], v[82:83] neg_lo:[0,1] neg_hi:[0,1]
	v_pk_mul_f32 v[90:91], v[66:67], 1.0 op_sel:[1,0] op_sel_hi:[0,0] neg_lo:[1,0]
	v_pk_add_f32 v[66:67], v[50:51], v[90:91]
	v_pk_add_f32 v[50:51], v[50:51], v[90:91] neg_lo:[0,1] neg_hi:[0,1]
	v_pk_add_f32 v[90:91], v[98:99], v[78:79]
	v_pk_add_f32 v[78:79], v[98:99], v[78:79] neg_lo:[0,1] neg_hi:[0,1]
	v_pk_mul_f32 v[98:99], v[62:63], 1.0 op_sel:[1,0] op_sel_hi:[0,0] neg_lo:[1,0]
	v_pk_add_f32 v[62:63], v[46:47], v[98:99]
	v_pk_add_f32 v[46:47], v[46:47], v[98:99] neg_lo:[0,1] neg_hi:[0,1]
	v_pk_add_f32 v[98:99], v[94:95], v[86:87]
	v_pk_add_f32 v[86:87], v[94:95], v[86:87] neg_lo:[0,1] neg_hi:[0,1]
	v_pk_mul_f32 v[94:95], v[70:71], 1.0 op_sel:[1,0] op_sel_hi:[0,0] neg_lo:[1,0]
	s_mov_b32 s73, s36
	v_pk_add_f32 v[70:71], v[54:55], v[94:95]
	v_pk_add_f32 v[54:55], v[54:55], v[94:95] neg_lo:[0,1] neg_hi:[0,1]
	v_pk_add_f32 v[94:95], v[102:103], v[106:107]
	v_pk_add_f32 v[102:103], v[102:103], v[106:107] neg_lo:[0,1] neg_hi:[0,1]
	s_mov_b32 s0, s37
	v_pk_mul_f32 v[106:107], v[64:65], s[72:73]
	s_mov_b32 s74, s19
	v_pk_fma_f32 v[64:65], v[64:65], s[0:1], v[106:107] op_sel:[0,0,1] op_sel_hi:[1,0,0]
	s_mov_b32 s75, s18
	v_pk_add_f32 v[106:107], v[56:57], v[64:65]
	v_pk_add_f32 v[56:57], v[56:57], v[64:65] neg_lo:[0,1] neg_hi:[0,1]
	v_pk_mul_f32 v[64:65], v[80:81], 1.0 op_sel:[1,0] op_sel_hi:[0,0] neg_lo:[1,0]
	s_nop 0
	v_pk_add_f32 v[80:81], v[104:105], v[64:65]
	v_pk_add_f32 v[64:65], v[104:105], v[64:65] neg_lo:[0,1] neg_hi:[0,1]
	v_pk_mul_f32 v[104:105], v[48:49], s[72:73]
	s_mov_b32 s76, s19
	v_pk_fma_f32 v[48:49], v[48:49], s[0:1], v[104:105] op_sel:[0,0,1] op_sel_hi:[1,0,0] neg_lo:[1,0,0] neg_hi:[1,0,0]
	s_mov_b32 s62, s11
	v_pk_add_f32 v[104:105], v[72:73], v[48:49]
	v_pk_add_f32 v[48:49], v[72:73], v[48:49] neg_lo:[0,1] neg_hi:[0,1]
	v_pk_add_f32 v[72:73], v[88:89], v[96:97]
	v_pk_add_f32 v[88:89], v[88:89], v[96:97] neg_lo:[0,1] neg_hi:[0,1]
	v_pk_mul_f32 v[96:97], v[68:69], s[72:73]
	s_mov_b32 s63, s10
	v_pk_fma_f32 v[68:69], v[68:69], s[0:1], v[96:97] op_sel:[0,0,1] op_sel_hi:[1,0,0]
	s_mov_b32 s78, s27
	v_pk_add_f32 v[96:97], v[60:61], v[68:69]
	v_pk_add_f32 v[60:61], v[60:61], v[68:69] neg_lo:[0,1] neg_hi:[0,1]
	v_pk_mul_f32 v[68:69], v[84:85], 1.0 op_sel:[1,0] op_sel_hi:[0,0] neg_lo:[1,0]
	s_nop 0
	v_pk_add_f32 v[84:85], v[76:77], v[68:69]
	v_pk_add_f32 v[68:69], v[76:77], v[68:69] neg_lo:[0,1] neg_hi:[0,1]
	v_pk_mul_f32 v[76:77], v[52:53], s[72:73]
	v_pk_mul_f32 v[108:109], v[96:97], s[74:75]
	v_pk_fma_f32 v[52:53], v[52:53], s[0:1], v[76:77] op_sel:[0,0,1] op_sel_hi:[1,0,0] neg_lo:[1,0,0] neg_hi:[1,0,0]
	v_pk_fma_f32 v[96:97], v[96:97], s[16:17], v[108:109] op_sel:[0,0,1] op_sel_hi:[1,0,0]
	v_pk_add_f32 v[76:77], v[44:45], v[52:53]
	v_pk_add_f32 v[44:45], v[44:45], v[52:53] neg_lo:[0,1] neg_hi:[0,1]
	v_pk_add_f32 v[52:53], v[92:93], v[100:101]
	v_pk_add_f32 v[92:93], v[92:93], v[100:101] neg_lo:[0,1] neg_hi:[0,1]
	v_pk_mul_f32 v[100:101], v[66:67], s[72:73]
	s_mov_b32 s17, s40
	v_pk_fma_f32 v[66:67], v[66:67], s[0:1], v[100:101] op_sel:[0,0,1] op_sel_hi:[1,0,0]
	v_pk_add_f32 v[108:109], v[106:107], v[96:97]
	v_pk_add_f32 v[100:101], v[58:59], v[66:67]
	v_pk_add_f32 v[58:59], v[58:59], v[66:67] neg_lo:[0,1] neg_hi:[0,1]
	v_pk_mul_f32 v[66:67], v[82:83], 1.0 op_sel:[1,0] op_sel_hi:[0,0] neg_lo:[1,0]
	v_pk_add_f32 v[82:83], v[74:75], v[66:67]
	v_pk_add_f32 v[66:67], v[74:75], v[66:67] neg_lo:[0,1] neg_hi:[0,1]
	v_pk_mul_f32 v[74:75], v[50:51], s[72:73]
	v_pk_add_f32 v[96:97], v[106:107], v[96:97] neg_lo:[0,1] neg_hi:[0,1]
	v_pk_fma_f32 v[50:51], v[50:51], s[0:1], v[74:75] op_sel:[0,0,1] op_sel_hi:[1,0,0] neg_lo:[1,0,0] neg_hi:[1,0,0]
	v_pk_mul_f32 v[106:107], v[84:85], s[72:73]
	v_pk_add_f32 v[74:75], v[42:43], v[50:51]
	v_pk_add_f32 v[42:43], v[42:43], v[50:51] neg_lo:[0,1] neg_hi:[0,1]
	v_pk_add_f32 v[50:51], v[90:91], v[98:99]
	v_pk_add_f32 v[90:91], v[90:91], v[98:99] neg_lo:[0,1] neg_hi:[0,1]
	v_pk_mul_f32 v[98:99], v[70:71], s[72:73]
	v_pk_fma_f32 v[84:85], v[84:85], s[0:1], v[106:107] op_sel:[0,0,1] op_sel_hi:[1,0,0]
	v_pk_fma_f32 v[70:71], v[70:71], s[0:1], v[98:99] op_sel:[0,0,1] op_sel_hi:[1,0,0]
	v_pk_add_f32 v[106:107], v[80:81], v[84:85]
	v_pk_add_f32 v[98:99], v[62:63], v[70:71]
	v_pk_add_f32 v[62:63], v[62:63], v[70:71] neg_lo:[0,1] neg_hi:[0,1]
	v_pk_mul_f32 v[70:71], v[86:87], 1.0 op_sel:[1,0] op_sel_hi:[0,0] neg_lo:[1,0]
	v_pk_mul_f32 v[110:111], v[98:99], s[74:75]
	v_pk_add_f32 v[86:87], v[78:79], v[70:71]
	v_pk_add_f32 v[70:71], v[78:79], v[70:71] neg_lo:[0,1] neg_hi:[0,1]
	v_pk_mul_f32 v[78:79], v[54:55], s[72:73]
	v_pk_fma_f32 v[98:99], v[98:99], s[16:17], v[110:111] op_sel:[0,0,1] op_sel_hi:[1,0,0]
	v_pk_fma_f32 v[54:55], v[54:55], s[0:1], v[78:79] op_sel:[0,0,1] op_sel_hi:[1,0,0] neg_lo:[1,0,0] neg_hi:[1,0,0]
	v_pk_add_f32 v[110:111], v[100:101], v[98:99]
	v_pk_add_f32 v[98:99], v[100:101], v[98:99] neg_lo:[0,1] neg_hi:[0,1]
	v_pk_mul_f32 v[100:101], v[86:87], s[72:73]
	v_pk_add_f32 v[78:79], v[46:47], v[54:55]
	v_pk_fma_f32 v[86:87], v[86:87], s[0:1], v[100:101] op_sel:[0,0,1] op_sel_hi:[1,0,0]
	v_pk_add_f32 v[46:47], v[46:47], v[54:55] neg_lo:[0,1] neg_hi:[0,1]
	v_pk_add_f32 v[100:101], v[82:83], v[86:87]
	v_pk_add_f32 v[82:83], v[82:83], v[86:87] neg_lo:[0,1] neg_hi:[0,1]
	v_pk_mul_f32 v[86:87], v[78:79], s[16:17]
	v_pk_add_f32 v[80:81], v[80:81], v[84:85] neg_lo:[0,1] neg_hi:[0,1]
	v_pk_fma_f32 v[78:79], v[78:79], s[76:77], v[86:87] op_sel:[0,0,1] op_sel_hi:[1,0,0]
	v_pk_mul_f32 v[84:85], v[76:77], s[16:17]
	v_pk_add_f32 v[86:87], v[74:75], v[78:79]
	v_pk_add_f32 v[74:75], v[74:75], v[78:79] neg_lo:[0,1] neg_hi:[0,1]
	v_pk_mul_f32 v[78:79], v[90:91], 1.0 op_sel:[1,0] op_sel_hi:[0,0] neg_lo:[1,0]
	v_pk_add_f32 v[90:91], v[92:93], v[78:79]
	v_pk_add_f32 v[78:79], v[92:93], v[78:79] neg_lo:[0,1] neg_hi:[0,1]
	v_pk_mul_f32 v[92:93], v[62:63], s[16:17]
	v_pk_fma_f32 v[76:77], v[76:77], s[76:77], v[84:85] op_sel:[0,0,1] op_sel_hi:[1,0,0]
	v_pk_fma_f32 v[62:63], v[62:63], s[76:77], v[92:93] op_sel:[0,0,1] op_sel_hi:[1,0,0] neg_lo:[1,0,0] neg_hi:[1,0,0]
	v_pk_add_f32 v[84:85], v[104:105], v[76:77]
	v_pk_add_f32 v[92:93], v[58:59], v[62:63]
	v_pk_add_f32 v[58:59], v[58:59], v[62:63] neg_lo:[0,1] neg_hi:[0,1]
	v_pk_mul_f32 v[62:63], v[70:71], s[72:73]
	v_pk_add_f32 v[76:77], v[104:105], v[76:77] neg_lo:[0,1] neg_hi:[0,1]
	v_pk_fma_f32 v[62:63], v[70:71], s[0:1], v[62:63] op_sel:[0,0,1] op_sel_hi:[1,0,0] neg_lo:[1,0,0] neg_hi:[1,0,0]
	v_pk_mul_f32 v[104:105], v[88:89], 1.0 op_sel:[1,0] op_sel_hi:[0,0] neg_lo:[1,0]
	v_pk_add_f32 v[70:71], v[66:67], v[62:63]
	v_pk_add_f32 v[62:63], v[66:67], v[62:63] neg_lo:[0,1] neg_hi:[0,1]
	v_pk_mul_f32 v[66:67], v[46:47], s[74:75]
	s_nop 0
	v_pk_fma_f32 v[46:47], v[46:47], s[16:17], v[66:67] op_sel:[0,0,1] op_sel_hi:[1,0,0] neg_lo:[1,0,0] neg_hi:[1,0,0]
	s_mov_b32 s79, s26
	v_pk_add_f32 v[66:67], v[42:43], v[46:47]
	v_pk_add_f32 v[42:43], v[42:43], v[46:47] neg_lo:[0,1] neg_hi:[0,1]
	v_pk_mul_f32 v[46:47], v[110:111], s[62:63]
	v_pk_add_f32 v[88:89], v[102:103], v[104:105]
	v_pk_fma_f32 v[46:47], v[110:111], s[8:9], v[46:47] op_sel:[0,0,1] op_sel_hi:[1,0,0]
	v_pk_add_f32 v[102:103], v[102:103], v[104:105] neg_lo:[0,1] neg_hi:[0,1]
	v_pk_add_f32 v[46:47], v[108:109], v[46:47]
	v_pk_mul_f32 v[108:109], v[100:101], s[74:75]
	v_pk_mul_f32 v[104:105], v[60:61], s[16:17]
	v_pk_fma_f32 v[100:101], v[100:101], s[16:17], v[108:109] op_sel:[0,0,1] op_sel_hi:[1,0,0]
	v_pk_fma_f32 v[60:61], v[60:61], s[76:77], v[104:105] op_sel:[0,0,1] op_sel_hi:[1,0,0] neg_lo:[1,0,0] neg_hi:[1,0,0]
	v_pk_add_f32 v[100:101], v[106:107], v[100:101]
	v_pk_mul_f32 v[106:107], v[86:87], s[78:79]
	v_pk_add_f32 v[104:105], v[56:57], v[60:61]
	v_pk_fma_f32 v[86:87], v[86:87], s[24:25], v[106:107] op_sel:[0,0,1] op_sel_hi:[1,0,0]
	v_pk_add_f32 v[56:57], v[56:57], v[60:61] neg_lo:[0,1] neg_hi:[0,1]
	v_pk_mul_f32 v[60:61], v[68:69], s[72:73]
	v_pk_add_f32 v[84:85], v[84:85], v[86:87]
	v_pk_mul_f32 v[86:87], v[90:91], s[72:73]
	v_pk_fma_f32 v[60:61], v[68:69], s[0:1], v[60:61] op_sel:[0,0,1] op_sel_hi:[1,0,0] neg_lo:[1,0,0] neg_hi:[1,0,0]
	v_pk_fma_f32 v[86:87], v[90:91], s[0:1], v[86:87] op_sel:[0,0,1] op_sel_hi:[1,0,0]
	v_pk_mul_f32 v[90:91], v[70:71], s[16:17]
	v_pk_add_f32 v[68:69], v[64:65], v[60:61]
	v_pk_fma_f32 v[70:71], v[70:71], s[76:77], v[90:91] op_sel:[0,0,1] op_sel_hi:[1,0,0]
	s_mov_b32 s9, s42
	s_mov_b32 s25, s38
	v_pk_add_f32 v[68:69], v[68:69], v[70:71]
	s_mov_b32 s82, s11
	v_pk_mul_f32 v[70:71], v[66:67], s[8:9]
	s_mov_b32 s80, s27
	v_pk_fma_f32 v[66:67], v[66:67], s[82:83], v[70:71] op_sel:[0,0,1] op_sel_hi:[1,0,0]
	v_pk_mul_f32 v[70:71], v[74:75], s[24:25]
	v_pk_add_f32 v[60:61], v[64:65], v[60:61] neg_lo:[0,1] neg_hi:[0,1]
	v_pk_fma_f32 v[70:71], v[74:75], s[80:81], v[70:71] op_sel:[0,0,1] op_sel_hi:[1,0,0] neg_lo:[1,0,0] neg_hi:[1,0,0]
	v_pk_mul_f32 v[64:65], v[44:45], s[74:75]
	v_pk_add_f32 v[70:71], v[76:77], v[70:71]
	v_pk_mul_f32 v[76:77], v[58:59], s[78:79]
	v_pk_fma_f32 v[44:45], v[44:45], s[16:17], v[64:65] op_sel:[0,0,1] op_sel_hi:[1,0,0] neg_lo:[1,0,0] neg_hi:[1,0,0]
	v_pk_fma_f32 v[58:59], v[58:59], s[24:25], v[76:77] op_sel:[0,0,1] op_sel_hi:[1,0,0] neg_lo:[1,0,0] neg_hi:[1,0,0]
	v_pk_add_f32 v[64:65], v[48:49], v[44:45]
	v_pk_add_f32 v[56:57], v[56:57], v[58:59]
	v_pk_mul_f32 v[58:59], v[62:63], s[74:75]
	v_pk_add_f32 v[44:45], v[48:49], v[44:45] neg_lo:[0,1] neg_hi:[0,1]
	v_pk_fma_f32 v[58:59], s[16:17], v[62:63], v[58:59] op_sel:[0,0,1] op_sel_hi:[0,1,0] neg_lo:[0,1,0] neg_hi:[0,1,0]
	v_pk_add_f32 v[58:59], v[60:61], v[58:59]
	v_pk_mul_f32 v[60:61], v[42:43], s[62:63]
	v_pk_add_f32 v[54:55], v[94:95], v[72:73] neg_lo:[0,1] neg_hi:[0,1]
	v_pk_add_f32 v[64:65], v[64:65], v[66:67]
	v_pk_add_f32 v[66:67], v[52:53], v[50:51] neg_lo:[0,1] neg_hi:[0,1]
	v_pk_fma_f32 v[42:43], v[42:43], s[8:9], v[60:61] op_sel:[0,0,1] op_sel_hi:[1,0,0] neg_lo:[1,0,0] neg_hi:[1,0,0]
	v_pk_add_f32 v[86:87], v[88:89], v[86:87]
	v_pk_mul_f32 v[88:89], v[92:93], s[24:25]
	v_pk_add_f32 v[48:49], v[54:55], v[66:67] op_sel:[0,1] op_sel_hi:[1,0] neg_lo:[0,1]
	v_pk_mul_f32 v[54:55], v[98:99], s[8:9]
	v_pk_mul_f32 v[66:67], v[82:83], s[16:17]
	v_pk_mul_f32 v[74:75], v[78:79], s[72:73]
	v_pk_add_f32 v[42:43], v[44:45], v[42:43]
	v_pk_add_f32 v[44:45], v[94:95], v[72:73]
	v_pk_add_f32 v[50:51], v[52:53], v[50:51]
	v_pk_fma_f32 v[88:89], v[92:93], s[80:81], v[88:89] op_sel:[0,0,1] op_sel_hi:[1,0,0]
	v_pk_fma_f32 v[54:55], v[98:99], s[82:83], v[54:55] op_sel:[0,0,1] op_sel_hi:[1,0,0] neg_lo:[1,0,0] neg_hi:[1,0,0]
	v_pk_fma_f32 v[66:67], v[82:83], s[76:77], v[66:67] op_sel:[0,0,1] op_sel_hi:[1,0,0] neg_lo:[1,0,0] neg_hi:[1,0,0]
	v_pk_fma_f32 v[74:75], v[78:79], s[0:1], v[74:75] op_sel:[0,0,1] op_sel_hi:[1,0,0] neg_lo:[1,0,0] neg_hi:[1,0,0]
	v_pk_add_f32 v[44:45], v[44:45], v[50:51]
	v_lshl_add_u32 v21, v21, 3, v36
	v_pk_add_f32 v[88:89], v[104:105], v[88:89]
	v_pk_add_f32 v[54:55], v[96:97], v[54:55]
	v_pk_add_f32 v[66:67], v[80:81], v[66:67]
	v_pk_add_f32 v[74:75], v[102:103], v[74:75]
	ds_write_b64 v25, v[44:45]
	ds_write_b64 v25, v[46:47] offset:4224
	ds_write_b64 v25, v[100:101] offset:8448
	ds_write_b64 v25, v[84:85] offset:12672
	ds_write_b64 v25, v[86:87] offset:16896
	ds_write_b64 v25, v[88:89] offset:21120
	ds_write_b64 v25, v[68:69] offset:25344
	ds_write_b64 v25, v[64:65] offset:29568
	ds_write_b64 v25, v[48:49] offset:33792
	ds_write_b64 v25, v[54:55] offset:38016
	ds_write_b64 v25, v[66:67] offset:42240
	ds_write_b64 v25, v[70:71] offset:46464
	ds_write_b64 v25, v[74:75] offset:50688
	ds_write_b64 v25, v[56:57] offset:54912
	ds_write_b64 v25, v[58:59] offset:59136
	ds_write_b64 v25, v[42:43] offset:63360
	v_ashrrev_i32_e32 v25, 5, v21
	v_lshlrev_b32_e32 v21, 3, v21
	v_lshlrev_b32_e32 v25, 3, v25
	s_waitcnt vmcnt(0)
	v_lshlrev_b32_e32 v41, 16, v41
	v_lshlrev_b32_e32 v39, 16, v39
	v_lshlrev_b32_e32 v35, 16, v35
	v_lshlrev_b32_e32 v29, 16, v29
	v_and_b32_e32 v48, 0xffff0000, v14
	v_add3_u32 v21, 0, v21, v25
	v_mov_b32_e32 v40, v48
	s_waitcnt lgkmcnt(0)
	s_barrier
	v_pk_mul_f32 v[44:45], v[30:31], v[40:41]
	ds_read2_b64 v[40:43], v21 offset1:1
	v_lshlrev_b32_e32 v28, 16, v14
	v_lshlrev_b32_e32 v49, 16, v15
	v_pk_fma_f32 v[44:45], v[30:31], v[28:29], v[44:45] op_sel:[0,0,1] op_sel_hi:[1,0,0]
	v_mov_b32_e32 v28, v31
	v_pk_fma_f32 v[44:45], v[20:21], v[48:49], v[44:45] op_sel_hi:[0,1,1]
	v_pk_add_f32 v[50:51], v[24:25], v[44:45] op_sel_hi:[0,1]
	ds_read2_b64 v[44:47], v21 offset0:2 offset1:3
	s_waitcnt lgkmcnt(1)
	v_pk_mul_f32 v[40:41], v[50:51], v[40:41]
	v_and_b32_e32 v51, 16, v16
	v_and_b32_e32 v50, 0xffff0000, v15
	v_pk_mov_b32 v[14:15], v[48:49], v[50:51] op_sel:[1,0]
	v_lshlrev_b32_e32 v53, 16, v16
	v_pk_mul_f32 v[14:15], v[30:31], v[14:15] op_sel_hi:[0,1]
	v_mov_b32_e32 v52, v50
	v_pk_fma_f32 v[14:15], v[28:29], v[48:49], v[14:15] op_sel_hi:[0,1,1]
	v_pk_fma_f32 v[14:15], v[20:21], v[52:53], v[14:15] op_sel_hi:[0,1,1]
	v_pk_add_f32 v[14:15], v[24:25], v[14:15] op_sel_hi:[0,1]
	v_pk_mul_f32 v[14:15], v[14:15], v[42:43]
	v_and_b32_e32 v43, 16, v17
	v_and_b32_e32 v42, 0xffff0000, v16
	v_lshlrev_b32_e32 v49, 16, v17
	v_mov_b32_e32 v48, v42
	v_pk_mov_b32 v[42:43], v[52:53], v[42:43] op_sel:[1,0]
	v_pk_mov_b32 v[16:17], v[16:17], v[10:11] op_sel:[1,0]
	v_pk_mul_f32 v[42:43], v[30:31], v[42:43] op_sel_hi:[0,1]
	v_and_b32_e32 v17, 16, v17
	v_and_b32_e32 v16, 0xffff0000, v16
	v_pk_fma_f32 v[42:43], v[28:29], v[52:53], v[42:43] op_sel_hi:[0,1,1]
	v_mov_b32_e32 v50, v16
	v_pk_mov_b32 v[16:17], v[48:49], v[16:17] op_sel:[1,0]
	v_pk_fma_f32 v[42:43], v[20:21], v[48:49], v[42:43] op_sel_hi:[0,1,1]
	v_pk_mul_f32 v[16:17], v[30:31], v[16:17] op_sel_hi:[0,1]
	v_pk_add_f32 v[42:43], v[24:25], v[42:43] op_sel_hi:[0,1]
	v_lshlrev_b32_e32 v51, 16, v10
	v_pk_fma_f32 v[16:17], v[28:29], v[48:49], v[16:17] op_sel_hi:[0,1,1]
	s_waitcnt lgkmcnt(0)
	v_pk_mul_f32 v[42:43], v[42:43], v[44:45]
	v_pk_fma_f32 v[16:17], v[20:21], v[50:51], v[16:17] op_sel_hi:[0,1,1]
	v_and_b32_e32 v45, 16, v11
	v_and_b32_e32 v44, 0xffff0000, v10
	v_pk_add_f32 v[16:17], v[24:25], v[16:17] op_sel_hi:[0,1]
	v_mov_b32_e32 v52, v44
	v_pk_mov_b32 v[44:45], v[50:51], v[44:45] op_sel:[1,0]
	v_pk_mul_f32 v[16:17], v[16:17], v[46:47]
	v_pk_mul_f32 v[48:49], v[30:31], v[44:45] op_sel_hi:[0,1]
	ds_read2_b64 v[44:47], v21 offset0:4 offset1:5
	v_lshlrev_b32_e32 v53, 16, v11
	v_pk_fma_f32 v[48:49], v[28:29], v[50:51], v[48:49] op_sel_hi:[0,1,1]
	v_pk_fma_f32 v[48:49], v[20:21], v[52:53], v[48:49] op_sel_hi:[0,1,1]
	v_pk_add_f32 v[54:55], v[24:25], v[48:49] op_sel_hi:[0,1]
	ds_read2_b64 v[48:51], v21 offset0:6 offset1:7
	s_waitcnt lgkmcnt(1)
	v_pk_mul_f32 v[44:45], v[54:55], v[44:45]
	v_and_b32_e32 v55, 16, v12
	v_and_b32_e32 v54, 0xffff0000, v11
	v_pk_mov_b32 v[10:11], v[52:53], v[54:55] op_sel:[1,0]
	v_lshlrev_b32_e32 v57, 16, v12
	v_pk_mul_f32 v[10:11], v[30:31], v[10:11] op_sel_hi:[0,1]
	v_mov_b32_e32 v56, v54
	v_pk_fma_f32 v[10:11], v[28:29], v[52:53], v[10:11] op_sel_hi:[0,1,1]
	v_pk_fma_f32 v[10:11], v[20:21], v[56:57], v[10:11] op_sel_hi:[0,1,1]
	v_pk_add_f32 v[10:11], v[24:25], v[10:11] op_sel_hi:[0,1]
	v_and_b32_e32 v38, 0xffff0000, v13
	v_pk_mul_f32 v[10:11], v[10:11], v[46:47]
	v_and_b32_e32 v47, 16, v13
	v_and_b32_e32 v46, 0xffff0000, v12
	v_lshlrev_b32_e32 v53, 16, v13
	v_mov_b32_e32 v52, v46
	v_pk_mov_b32 v[12:13], v[56:57], v[46:47] op_sel:[1,0]
	v_pk_mov_b32 v[46:47], v[52:53], v[38:39] op_sel:[1,0]
	v_pk_mul_f32 v[12:13], v[30:31], v[12:13] op_sel_hi:[0,1]
	v_pk_mul_f32 v[46:47], v[30:31], v[46:47] op_sel_hi:[0,1]
	v_pk_fma_f32 v[12:13], v[28:29], v[56:57], v[12:13] op_sel_hi:[0,1,1]
	v_pk_fma_f32 v[46:47], v[28:29], v[52:53], v[46:47] op_sel_hi:[0,1,1]
	v_pk_fma_f32 v[12:13], v[20:21], v[52:53], v[12:13] op_sel_hi:[0,1,1]
	v_pk_fma_f32 v[38:39], v[20:21], v[38:39], v[46:47] op_sel_hi:[0,1,1]
	s_xor_b64 s[70:71], s[70:71], -1
	v_pk_add_f32 v[12:13], v[24:25], v[12:13] op_sel_hi:[0,1]
	v_pk_add_f32 v[38:39], v[24:25], v[38:39] op_sel_hi:[0,1]
	s_waitcnt lgkmcnt(0)
	v_pk_mul_f32 v[12:13], v[12:13], v[48:49]
	v_pk_mul_f32 v[38:39], v[38:39], v[50:51]
	s_mov_b64 s[0:1], -1
	s_and_b64 vcc, exec, s[70:71]
	s_cbranch_vccz .LBB0_513
	v_bfe_u32 v46, v15, 16, 1
	v_add3_u32 v47, v15, v46, s4
	v_bfe_u32 v46, v14, 16, 1
	v_bfe_u32 v48, v16, 16, 1
	v_bfe_u32 v50, v42, 16, 1
	v_bfe_u32 v34, v17, 16, 1
	v_bfe_u32 v49, v40, 16, 1
	v_add3_u32 v50, v42, v50, s4
	v_add3_u32 v48, v16, v48, s4
	v_add3_u32 v46, v14, v46, s4
	v_bfe_u32 v25, v43, 16, 1
	v_bfe_u32 v28, v41, 16, 1
	v_add3_u32 v34, v17, v34, s4
	v_add3_u32 v49, v40, v49, s4
	v_lshrrev_b32_e32 v51, 16, v46
	v_lshrrev_b32_e32 v52, 16, v48
	v_lshrrev_b32_e32 v48, 16, v50
	v_bfe_u32 v50, v11, 16, 1
	v_add3_u32 v28, v41, v28, s4
	v_add3_u32 v25, v43, v25, s4
	v_lshrrev_b32_e32 v46, 16, v49
	v_and_or_b32 v49, v34, s91, v52
	v_and_or_b32 v47, v47, s91, v51
	v_add3_u32 v51, v11, v50, s4
	v_bfe_u32 v50, v10, 16, 1
	v_bfe_u32 v52, v38, 16, 1
	v_bfe_u32 v53, v44, 16, 1
	v_bfe_u32 v54, v12, 16, 1
	v_lshl_add_u64 v[36:37], v[36:37], 1, s[50:51]
	v_and_or_b32 v48, v25, s91, v48
	v_and_or_b32 v46, v28, s91, v46
	v_bfe_u32 v25, v13, 16, 1
	v_bfe_u32 v28, v45, 16, 1
	v_bfe_u32 v34, v39, 16, 1
	v_add3_u32 v54, v12, v54, s4
	v_add3_u32 v53, v44, v53, s4
	v_add3_u32 v52, v38, v52, s4
	v_add3_u32 v50, v10, v50, s4
	v_add3_u32 v34, v39, v34, s4
	v_add3_u32 v28, v45, v28, s4
	v_add3_u32 v25, v13, v25, s4
	v_lshrrev_b32_e32 v55, 16, v50
	v_lshrrev_b32_e32 v56, 16, v52
	v_lshrrev_b32_e32 v50, 16, v53
	v_lshrrev_b32_e32 v52, 16, v54
	v_lshl_add_u64 v[32:33], v[32:33], 1, v[36:37]
	v_and_or_b32 v52, v25, s91, v52
	v_and_or_b32 v50, v28, s91, v50
	v_and_or_b32 v53, v34, s91, v56
	v_and_or_b32 v51, v51, s91, v55
	global_store_dwordx4 v[32:33], v[46:49], off
	global_store_dwordx4 v[32:33], v[50:53], off offset:16
	s_mov_b64 s[0:1], 0

.LBB0_515:
	v_lshl_add_u32 v10, v18, 3, v26
	v_ashrrev_i32_e32 v11, 5, v10
	v_lshlrev_b32_e32 v10, 3, v10
	v_lshlrev_b32_e32 v11, 3, v11
	v_add3_u32 v18, 0, v10, v11
	s_waitcnt vmcnt(0)
	v_and_b32_e32 v32, 0xffff0000, v6
	v_mov_b32_e32 v34, v32
	ds_read2_b64 v[10:13], v18 offset1:1
	v_lshlrev_b32_e32 v14, 16, v6
	v_pk_mul_f32 v[16:17], v[30:31], v[34:35]
	v_mov_b32_e32 v21, v20
	v_lshlrev_b32_e32 v33, 16, v7
	v_pk_fma_f32 v[14:15], v[30:31], v[14:15], v[16:17] op_sel:[0,0,1] op_sel_hi:[1,0,0]
	v_mov_b32_e32 v25, v24
	v_pk_fma_f32 v[14:15], v[20:21], v[32:33], v[14:15]
	v_pk_mov_b32 v[36:37], v[30:31], v[30:31] op_sel:[0,0]
	v_pk_mov_b32 v[38:39], v[30:31], v[30:31] op_sel:[1,1]
	v_pk_add_f32 v[30:31], v[24:25], v[14:15]
	ds_read2_b64 v[14:17], v18 offset0:2 offset1:3
	s_waitcnt lgkmcnt(1)
	v_pk_mul_f32 v[10:11], v[30:31], v[10:11]
	v_and_b32_e32 v31, 16, v8
	v_and_b32_e32 v30, 0xffff0000, v7
	v_pk_mov_b32 v[6:7], v[32:33], v[30:31] op_sel:[1,0]
	v_lshlrev_b32_e32 v35, 16, v8
	v_pk_mul_f32 v[6:7], v[36:37], v[6:7]
	v_mov_b32_e32 v34, v30
	v_pk_fma_f32 v[6:7], v[38:39], v[32:33], v[6:7]
	v_lshlrev_b32_e32 v31, 16, v9
	v_pk_fma_f32 v[6:7], v[20:21], v[34:35], v[6:7]
	v_lshlrev_b32_e32 v33, 16, v2
	v_pk_add_f32 v[6:7], v[24:25], v[6:7]
	v_lshlrev_b32_e32 v43, 16, v4
	v_pk_mul_f32 v[6:7], v[6:7], v[12:13]
	v_and_b32_e32 v13, 16, v9
	v_and_b32_e32 v12, 0xffff0000, v8
	v_mov_b32_e32 v30, v12
	v_pk_mov_b32 v[12:13], v[34:35], v[12:13] op_sel:[1,0]
	v_pk_mov_b32 v[8:9], v[8:9], v[2:3] op_sel:[1,0]
	v_pk_mul_f32 v[12:13], v[36:37], v[12:13]
	v_and_b32_e32 v9, 16, v9
	v_and_b32_e32 v8, 0xffff0000, v8
	v_pk_fma_f32 v[12:13], v[38:39], v[34:35], v[12:13]
	v_mov_b32_e32 v32, v8
	v_pk_mov_b32 v[8:9], v[30:31], v[8:9] op_sel:[1,0]
	v_pk_fma_f32 v[12:13], v[20:21], v[30:31], v[12:13]
	v_pk_mul_f32 v[8:9], v[36:37], v[8:9]
	v_pk_add_f32 v[12:13], v[24:25], v[12:13]
	v_pk_fma_f32 v[8:9], v[38:39], v[30:31], v[8:9]
	s_waitcnt lgkmcnt(0)
	v_pk_mul_f32 v[12:13], v[12:13], v[14:15]
	v_pk_fma_f32 v[8:9], v[20:21], v[32:33], v[8:9]
	v_and_b32_e32 v15, 16, v3
	v_and_b32_e32 v14, 0xffff0000, v2
	v_pk_add_f32 v[8:9], v[24:25], v[8:9]
	v_mov_b32_e32 v34, v14
	v_pk_mov_b32 v[14:15], v[32:33], v[14:15] op_sel:[1,0]
	v_pk_mul_f32 v[8:9], v[8:9], v[16:17]
	v_pk_mul_f32 v[30:31], v[36:37], v[14:15]
	ds_read2_b64 v[14:17], v18 offset0:4 offset1:5
	v_lshlrev_b32_e32 v35, 16, v3
	v_pk_fma_f32 v[30:31], v[38:39], v[32:33], v[30:31]
	v_and_b32_e32 v28, 0xffff0000, v5
	v_pk_fma_f32 v[30:31], v[20:21], v[34:35], v[30:31]
	s_andn2_b64 vcc, exec, s[70:71]
	v_pk_add_f32 v[40:41], v[24:25], v[30:31]
	ds_read2_b64 v[30:33], v18 offset0:6 offset1:7
	s_waitcnt lgkmcnt(1)
	v_pk_mul_f32 v[14:15], v[40:41], v[14:15]
	v_and_b32_e32 v41, 16, v4
	v_and_b32_e32 v40, 0xffff0000, v3
	v_pk_mov_b32 v[2:3], v[34:35], v[40:41] op_sel:[1,0]
	v_mov_b32_e32 v42, v40
	v_pk_mul_f32 v[2:3], v[36:37], v[2:3]
	s_nop 0
	v_pk_fma_f32 v[2:3], v[38:39], v[34:35], v[2:3]
	v_lshlrev_b32_e32 v35, 16, v5
	v_pk_fma_f32 v[2:3], v[20:21], v[42:43], v[2:3]
	s_nop 0
	v_pk_add_f32 v[2:3], v[24:25], v[2:3]
	s_nop 0
	v_pk_mul_f32 v[2:3], v[2:3], v[16:17]
	v_and_b32_e32 v17, 16, v5
	v_and_b32_e32 v16, 0xffff0000, v4
	v_mov_b32_e32 v34, v16
	v_pk_mov_b32 v[4:5], v[42:43], v[16:17] op_sel:[1,0]
	v_pk_mov_b32 v[16:17], v[34:35], v[28:29] op_sel:[1,0]
	v_pk_mul_f32 v[4:5], v[36:37], v[4:5]
	v_pk_mul_f32 v[16:17], v[36:37], v[16:17]
	v_pk_fma_f32 v[4:5], v[38:39], v[42:43], v[4:5]
	v_pk_fma_f32 v[16:17], v[38:39], v[34:35], v[16:17]
	v_pk_fma_f32 v[4:5], v[20:21], v[34:35], v[4:5]
	v_pk_fma_f32 v[16:17], v[20:21], v[28:29], v[16:17]
	v_pk_add_f32 v[4:5], v[24:25], v[4:5]
	v_pk_add_f32 v[16:17], v[24:25], v[16:17]
	v_cndmask_b32_e64 v20, 0, 1, s[70:71]
	s_waitcnt lgkmcnt(0)
	v_pk_mul_f32 v[4:5], v[4:5], v[30:31]
	v_pk_mul_f32 v[16:17], v[16:17], v[32:33]
	v_cmp_ne_u32_e64 s[0:1], 1, v20
	s_mov_b64 s[70:71], -1
	s_cbranch_vccnz .LBB0_517
	v_lshl_add_u64 v[20:21], v[26:27], 1, s[50:51]
	v_bfe_u32 v26, v9, 16, 1
	v_bfe_u32 v27, v7, 16, 1
	v_add3_u32 v28, v7, v27, s4
	v_add3_u32 v27, v9, v26, s4
	v_bfe_u32 v26, v6, 16, 1
	v_bfe_u32 v30, v10, 16, 1
	v_bfe_u32 v31, v12, 16, 1
	v_bfe_u32 v24, v13, 16, 1
	v_bfe_u32 v25, v11, 16, 1
	v_add3_u32 v31, v12, v31, s4
	v_add3_u32 v30, v10, v30, s4
	v_add3_u32 v26, v6, v26, s4
	v_add3_u32 v25, v11, v25, s4
	v_add3_u32 v24, v13, v24, s4
	v_bfe_u32 v29, v8, 16, 1
	v_lshrrev_b32_e32 v32, 16, v26
	v_lshrrev_b32_e32 v30, 16, v30
	v_lshrrev_b32_e32 v26, 16, v31
	v_add3_u32 v29, v8, v29, s4
	v_and_or_b32 v26, v24, s91, v26
	v_and_or_b32 v24, v25, s91, v30
	v_bfe_u32 v30, v17, 16, 1
	v_bfe_u32 v31, v3, 16, 1
	v_lshrrev_b32_e32 v29, 16, v29
	v_and_or_b32 v25, v28, s91, v32
	v_add3_u32 v32, v3, v31, s4
	v_add3_u32 v31, v17, v30, s4
	v_bfe_u32 v30, v2, 16, 1
	v_bfe_u32 v33, v16, 16, 1
	v_bfe_u32 v34, v14, 16, 1
	v_bfe_u32 v35, v4, 16, 1
	v_and_or_b32 v27, v27, s91, v29
	v_bfe_u32 v28, v5, 16, 1
	v_bfe_u32 v29, v15, 16, 1
	v_add3_u32 v35, v4, v35, s4
	v_add3_u32 v34, v14, v34, s4
	v_add3_u32 v33, v16, v33, s4
	v_add3_u32 v30, v2, v30, s4
	v_add3_u32 v29, v15, v29, s4
	v_add3_u32 v28, v5, v28, s4
	v_lshrrev_b32_e32 v36, 16, v30
	v_lshrrev_b32_e32 v33, 16, v33
	v_lshrrev_b32_e32 v34, 16, v34
	v_lshrrev_b32_e32 v30, 16, v35
	v_lshl_add_u64 v[20:21], v[22:23], 1, v[20:21]
	s_mov_b64 s[70:71], 0
	v_and_or_b32 v30, v28, s91, v30
	v_and_or_b32 v28, v29, s91, v34
	v_and_or_b32 v31, v31, s91, v33
	v_and_or_b32 v29, v32, s91, v36
	global_store_dwordx4 v[20:21], v[24:27], off
	global_store_dwordx4 v[20:21], v[28:31], off offset:16

.LBB0_521:
	s_or_b64 exec, exec, s[64:65]
	s_waitcnt vmcnt(0)
	v_lshlrev_b32_e32 v29, 16, v29
	v_lshlrev_b32_e32 v27, 16, v27
	v_mov_b32_e32 v11, v10
	v_mov_b32_e32 v13, v12
	v_pk_mov_b32 v[20:21], v[14:15], v[14:15] op_sel:[0,0]
	v_pk_mov_b32 v[22:23], v[14:15], v[14:15] op_sel:[1,1]
	v_and_b32_e32 v34, 0xffff0000, v6
	v_mov_b32_e32 v28, v34
	v_lshlrev_b32_e32 v30, 16, v6
	v_pk_mul_f32 v[28:29], v[14:15], v[28:29]
	v_lshlrev_b32_e32 v35, 16, v7
	v_pk_fma_f32 v[28:29], v[14:15], v[30:31], v[28:29] op_sel:[0,0,1] op_sel_hi:[1,0,0]
	v_and_b32_e32 v31, 16, v8
	v_and_b32_e32 v30, 0xffff0000, v7
	v_mov_b32_e32 v6, v30
	v_pk_mov_b32 v[30:31], v[34:35], v[30:31] op_sel:[1,0]
	v_lshlrev_b32_e32 v25, 1, v33
	v_pk_mul_f32 v[30:31], v[20:21], v[30:31]
	v_lshlrev_b32_e32 v7, 16, v8
	v_pk_fma_f32 v[30:31], v[22:23], v[34:35], v[30:31]
	v_and_b32_e32 v25, -8, v25
	v_pk_fma_f32 v[28:29], v[10:11], v[34:35], v[28:29]
	v_pk_fma_f32 v[30:31], v[10:11], v[6:7], v[30:31]
	v_add_u32_e32 v25, v32, v25
	v_pk_add_f32 v[28:29], v[12:13], v[28:29]
	v_pk_add_f32 v[30:31], v[12:13], v[30:31]
	ds_write2_b64 v25, v[28:29], v[30:31] offset1:1
	v_and_b32_e32 v29, 16, v9
	v_and_b32_e32 v28, 0xffff0000, v8
	v_lshlrev_b32_e32 v31, 16, v9
	v_mov_b32_e32 v30, v28
	v_pk_mov_b32 v[28:29], v[6:7], v[28:29] op_sel:[1,0]
	v_pk_mov_b32 v[8:9], v[8:9], v[2:3] op_sel:[1,0]
	v_pk_mul_f32 v[28:29], v[20:21], v[28:29]
	v_and_b32_e32 v9, 16, v9
	v_and_b32_e32 v8, 0xffff0000, v8
	v_pk_fma_f32 v[6:7], v[22:23], v[6:7], v[28:29]
	v_mov_b32_e32 v28, v8
	v_pk_mov_b32 v[8:9], v[30:31], v[8:9] op_sel:[1,0]
	v_lshlrev_b32_e32 v29, 16, v2
	v_pk_mul_f32 v[8:9], v[20:21], v[8:9]
	v_pk_fma_f32 v[6:7], v[10:11], v[30:31], v[6:7]
	v_pk_fma_f32 v[8:9], v[22:23], v[30:31], v[8:9]
	v_pk_add_f32 v[6:7], v[12:13], v[6:7]
	v_pk_fma_f32 v[8:9], v[10:11], v[28:29], v[8:9]
	v_and_b32_e32 v26, 0xffff0000, v5
	v_pk_add_f32 v[8:9], v[12:13], v[8:9]
	ds_write2_b64 v25, v[6:7], v[8:9] offset0:2 offset1:3
	v_and_b32_e32 v7, 16, v3
	v_and_b32_e32 v6, 0xffff0000, v2
	v_mov_b32_e32 v8, v6
	v_pk_mov_b32 v[6:7], v[28:29], v[6:7] op_sel:[1,0]
	v_lshlrev_b32_e32 v9, 16, v3
	v_pk_mul_f32 v[6:7], v[20:21], v[6:7]
	v_cmp_lt_i32_e32 vcc, -1, v33
	v_pk_fma_f32 v[6:7], v[22:23], v[28:29], v[6:7]
	v_and_b32_e32 v29, 16, v4
	v_and_b32_e32 v28, 0xffff0000, v3
	v_mov_b32_e32 v2, v28
	v_pk_mov_b32 v[28:29], v[8:9], v[28:29] op_sel:[1,0]
	v_pk_fma_f32 v[6:7], v[10:11], v[8:9], v[6:7]
	v_pk_mul_f32 v[28:29], v[20:21], v[28:29]
	v_lshlrev_b32_e32 v3, 16, v4
	v_pk_fma_f32 v[8:9], v[22:23], v[8:9], v[28:29]
	v_pk_add_f32 v[6:7], v[12:13], v[6:7]
	v_pk_fma_f32 v[8:9], v[10:11], v[2:3], v[8:9]
	v_add_u32_e32 v32, 0x8000, v32
	v_pk_add_f32 v[8:9], v[12:13], v[8:9]
	ds_write2_b64 v25, v[6:7], v[8:9] offset0:4 offset1:5
	v_and_b32_e32 v7, 16, v5
	v_and_b32_e32 v6, 0xffff0000, v4
	v_mov_b32_e32 v4, v6
	v_pk_mov_b32 v[6:7], v[2:3], v[6:7] op_sel:[1,0]
	v_lshlrev_b32_e32 v5, 16, v5
	v_pk_mul_f32 v[6:7], v[20:21], v[6:7]
	v_add_u32_e32 v24, 0x2000, v24
	v_pk_fma_f32 v[2:3], v[22:23], v[2:3], v[6:7]
	v_pk_mov_b32 v[6:7], v[4:5], v[26:27] op_sel:[1,0]
	s_nop 0
	v_pk_mul_f32 v[6:7], v[20:21], v[6:7]
	v_pk_fma_f32 v[2:3], v[10:11], v[4:5], v[2:3]
	v_pk_fma_f32 v[4:5], v[22:23], v[4:5], v[6:7]
	v_pk_add_f32 v[2:3], v[12:13], v[2:3]
	v_pk_fma_f32 v[4:5], v[10:11], v[26:27], v[4:5]
	s_or_b64 s[62:63], vcc, s[62:63]
	v_pk_add_f32 v[4:5], v[12:13], v[4:5]
	v_mov_b32_e32 v26, v33
	ds_write2_b64 v25, v[2:3], v[4:5] offset0:6 offset1:7
	s_andn2_b64 exec, exec, s[62:63]
	s_cbranch_execz .LBB0_526

.LBB0_527:
	s_or_b64 exec, exec, s[64:65]
	s_waitcnt vmcnt(0)
	v_lshlrev_b32_e32 v27, 16, v27
	v_lshlrev_b32_e32 v25, 16, v25
	v_and_b32_e32 v28, 0xffff0000, v6
	v_lshlrev_b32_e32 v29, 16, v7
	v_mov_b32_e32 v26, v28
	v_and_b32_e32 v35, 16, v8
	v_and_b32_e32 v34, 0xffff0000, v7
	v_lshlrev_b32_e32 v18, 16, v6
	v_pk_mul_f32 v[26:27], v[14:15], v[26:27]
	v_mov_b32_e32 v6, v34
	v_pk_mov_b32 v[34:35], v[28:29], v[34:35] op_sel:[1,0]
	v_pk_fma_f32 v[26:27], v[14:15], v[18:19], v[26:27] op_sel:[0,0,1] op_sel_hi:[1,0,0]
	v_pk_mul_f32 v[34:35], v[20:21], v[34:35]
	v_pk_fma_f32 v[26:27], v[10:11], v[28:29], v[26:27]
	v_lshlrev_b32_e32 v7, 16, v8
	v_pk_fma_f32 v[28:29], v[22:23], v[28:29], v[34:35]
	v_ashrrev_i32_e32 v17, 5, v31
	v_pk_fma_f32 v[28:29], v[10:11], v[6:7], v[28:29]
	v_lshl_add_u32 v17, v17, 3, v30
	v_pk_add_f32 v[26:27], v[12:13], v[26:27]
	v_pk_add_f32 v[28:29], v[12:13], v[28:29]
	ds_write2_b64 v17, v[26:27], v[28:29] offset1:1
	v_and_b32_e32 v27, 16, v9
	v_and_b32_e32 v26, 0xffff0000, v8
	v_lshlrev_b32_e32 v29, 16, v9
	v_mov_b32_e32 v28, v26
	v_pk_mov_b32 v[26:27], v[6:7], v[26:27] op_sel:[1,0]
	v_pk_mov_b32 v[8:9], v[8:9], v[2:3] op_sel:[1,0]
	v_pk_mul_f32 v[26:27], v[20:21], v[26:27]
	v_and_b32_e32 v9, 16, v9
	v_and_b32_e32 v8, 0xffff0000, v8
	v_pk_fma_f32 v[6:7], v[22:23], v[6:7], v[26:27]
	v_mov_b32_e32 v26, v8
	v_pk_mov_b32 v[8:9], v[28:29], v[8:9] op_sel:[1,0]
	v_lshlrev_b32_e32 v27, 16, v2
	v_pk_mul_f32 v[8:9], v[20:21], v[8:9]
	v_pk_fma_f32 v[6:7], v[10:11], v[28:29], v[6:7]
	v_pk_fma_f32 v[8:9], v[22:23], v[28:29], v[8:9]
	v_pk_add_f32 v[6:7], v[12:13], v[6:7]
	v_pk_fma_f32 v[8:9], v[10:11], v[26:27], v[8:9]
	v_and_b32_e32 v24, 0xffff0000, v5
	v_pk_add_f32 v[8:9], v[12:13], v[8:9]
	ds_write2_b64 v17, v[6:7], v[8:9] offset0:2 offset1:3
	v_and_b32_e32 v7, 16, v3
	v_and_b32_e32 v6, 0xffff0000, v2
	v_mov_b32_e32 v8, v6
	v_pk_mov_b32 v[6:7], v[26:27], v[6:7] op_sel:[1,0]
	v_lshlrev_b32_e32 v9, 16, v3
	v_pk_mul_f32 v[6:7], v[20:21], v[6:7]
	v_cmp_lt_i32_e32 vcc, -1, v32
	v_pk_fma_f32 v[6:7], v[22:23], v[26:27], v[6:7]
	v_and_b32_e32 v27, 16, v4
	v_and_b32_e32 v26, 0xffff0000, v3
	v_mov_b32_e32 v2, v26
	v_pk_mov_b32 v[26:27], v[8:9], v[26:27] op_sel:[1,0]
	v_pk_fma_f32 v[6:7], v[10:11], v[8:9], v[6:7]
	v_pk_mul_f32 v[26:27], v[20:21], v[26:27]
	v_lshlrev_b32_e32 v3, 16, v4
	v_pk_fma_f32 v[8:9], v[22:23], v[8:9], v[26:27]
	v_pk_add_f32 v[6:7], v[12:13], v[6:7]
	v_pk_fma_f32 v[8:9], v[10:11], v[2:3], v[8:9]
	v_add_u32_e32 v30, 0x8000, v30
	v_pk_add_f32 v[8:9], v[12:13], v[8:9]
	ds_write2_b64 v17, v[6:7], v[8:9] offset0:4 offset1:5
	v_and_b32_e32 v7, 16, v5
	v_and_b32_e32 v6, 0xffff0000, v4
	v_mov_b32_e32 v4, v6
	v_pk_mov_b32 v[6:7], v[2:3], v[6:7] op_sel:[1,0]
	v_lshlrev_b32_e32 v5, 16, v5
	v_pk_mul_f32 v[6:7], v[20:21], v[6:7]
	v_add_u32_e32 v31, 0x1000, v31
	v_pk_fma_f32 v[2:3], v[22:23], v[2:3], v[6:7]
	v_pk_mov_b32 v[6:7], v[4:5], v[24:25] op_sel:[1,0]
	s_nop 0
	v_pk_mul_f32 v[6:7], v[20:21], v[6:7]
	v_pk_fma_f32 v[2:3], v[10:11], v[4:5], v[2:3]
	v_pk_fma_f32 v[4:5], v[22:23], v[4:5], v[6:7]
	v_pk_add_f32 v[2:3], v[12:13], v[2:3]
	v_pk_fma_f32 v[4:5], v[10:11], v[24:25], v[4:5]
	v_add_u32_e32 v16, 0x2000, v16
	v_pk_add_f32 v[4:5], v[12:13], v[4:5]
	s_or_b64 s[62:63], vcc, s[62:63]
	v_mov_b32_e32 v18, v32
	ds_write2_b64 v17, v[2:3], v[4:5] offset0:6 offset1:7
	s_andn2_b64 exec, exec, s[62:63]
	s_cbranch_execz .LBB0_532

.LBB0_534:
	v_mov_b32_e32 v2, v210
	s_mov_b32 s43, s8
	v_and_b32_e32 v3, 0xff, v2
	v_lshlrev_b32_e32 v4, 5, v2
	v_and_or_b32 v3, v4, s33, v3
	v_ashrrev_i32_e32 v4, 5, v3
	v_lshlrev_b32_e32 v3, 3, v3
	v_lshlrev_b32_e32 v4, 3, v4
	v_add3_u32 v18, 0, v3, v4
	ds_read_b64 v[128:129], v18
	ds_read_b64 v[132:133], v18 offset:2112
	ds_read_b64 v[134:135], v18 offset:4224
	ds_read_b64 v[136:137], v18 offset:6336
	ds_read_b64 v[138:139], v18 offset:8448
	ds_read_b64 v[140:141], v18 offset:10560
	ds_read_b64 v[142:143], v18 offset:12672
	ds_read_b64 v[130:131], v18 offset:14784
	ds_read_b64 v[144:145], v18 offset:16896
	ds_read_b64 v[148:149], v18 offset:19008
	ds_read_b64 v[150:151], v18 offset:21120
	ds_read_b64 v[152:153], v18 offset:23232
	s_waitcnt lgkmcnt(10)
	v_pk_mul_f32 v[162:163], v[132:133], s[10:11]
	s_mov_b32 s64, s11
	v_pk_fma_f32 v[162:163], v[132:133], s[8:9], v[162:163] op_sel:[0,0,1] op_sel_hi:[1,0,0]
	s_waitcnt lgkmcnt(2)
	v_pk_mul_f32 v[178:179], v[148:149], s[42:43]
	v_pk_add_f32 v[194:195], v[132:133], v[148:149]
	v_pk_add_f32 v[132:133], v[132:133], v[148:149] neg_lo:[0,1] neg_hi:[0,1]
	v_pk_mul_f32 v[164:165], v[134:135], s[18:19]
	s_mov_b32 s41, s16
	v_pk_fma_f32 v[178:179], v[148:149], s[64:65], v[178:179] op_sel:[0,0,1] op_sel_hi:[1,0,0] neg_lo:[1,0,0] neg_hi:[1,0,0]
	v_pk_mul_f32 v[148:149], v[132:133], s[18:19]
	v_pk_fma_f32 v[164:165], v[134:135], s[16:17], v[164:165] op_sel:[0,0,1] op_sel_hi:[1,0,0]
	s_mov_b32 s68, s19
	s_waitcnt lgkmcnt(1)
	v_pk_mul_f32 v[180:181], v[150:151], s[40:41]
	v_pk_fma_f32 v[132:133], v[132:133], s[16:17], v[148:149] op_sel:[0,0,1] op_sel_hi:[1,0,0]
	v_pk_add_f32 v[148:149], v[134:135], v[150:151]
	v_pk_add_f32 v[134:135], v[134:135], v[150:151] neg_lo:[0,1] neg_hi:[0,1]
	v_pk_mul_f32 v[166:167], v[136:137], s[26:27]
	s_mov_b32 s66, s37
	s_mov_b32 s39, s24
	v_pk_fma_f32 v[180:181], v[150:151], s[68:69], v[180:181] op_sel:[0,0,1] op_sel_hi:[1,0,0] neg_lo:[1,0,0] neg_hi:[1,0,0]
	v_pk_mul_f32 v[150:151], v[134:135], s[36:37]
	ds_read_b64 v[154:155], v18 offset:25344
	ds_read_b64 v[156:157], v18 offset:27456
	ds_read_b64 v[158:159], v18 offset:29568
	ds_read_b64 v[160:161], v18 offset:31680
	v_pk_fma_f32 v[166:167], v[136:137], s[24:25], v[166:167] op_sel:[0,0,1] op_sel_hi:[1,0,0]
	s_mov_b32 s0, s27
	s_waitcnt lgkmcnt(4)
	v_pk_mul_f32 v[182:183], v[152:153], s[38:39]
	v_pk_fma_f32 v[134:135], v[134:135], s[66:67], v[150:151] op_sel:[0,0,1] op_sel_hi:[1,0,0]
	v_pk_add_f32 v[150:151], v[136:137], v[152:153]
	v_pk_add_f32 v[136:137], v[136:137], v[152:153] neg_lo:[0,1] neg_hi:[0,1]
	v_pk_mul_f32 v[168:169], v[138:139], s[36:37]
	v_pk_fma_f32 v[182:183], v[152:153], s[0:1], v[182:183] op_sel:[0,0,1] op_sel_hi:[1,0,0] neg_lo:[1,0,0] neg_hi:[1,0,0]
	v_pk_mul_f32 v[152:153], v[136:137], s[40:41]
	v_pk_fma_f32 v[168:169], v[138:139], s[66:67], v[168:169] op_sel:[0,0,1] op_sel_hi:[1,0,0]
	v_pk_mul_f32 v[170:171], v[140:141], s[38:39]
	s_waitcnt lgkmcnt(3)
	v_pk_mul_f32 v[184:185], v[154:155], s[36:37]
	v_pk_fma_f32 v[136:137], v[136:137], s[68:69], v[152:153] op_sel:[0,0,1] op_sel_hi:[1,0,0]
	v_pk_add_f32 v[152:153], v[138:139], v[154:155]
	v_pk_add_f32 v[138:139], v[138:139], v[154:155] neg_lo:[0,1] neg_hi:[0,1]
	v_pk_fma_f32 v[170:171], v[140:141], s[0:1], v[170:171] op_sel:[0,0,1] op_sel_hi:[1,0,0]
	v_pk_fma_f32 v[184:185], v[154:155], s[66:67], v[184:185] op_sel:[0,0,1] op_sel_hi:[1,0,0] neg_lo:[1,0,0] neg_hi:[1,0,0]
	s_waitcnt lgkmcnt(2)
	v_pk_mul_f32 v[186:187], v[156:157], s[26:27]
	v_pk_mul_f32 v[154:155], v[138:139], 1.0 op_sel:[1,0] op_sel_hi:[0,0] neg_hi:[1,0]
	v_pk_add_f32 v[138:139], v[140:141], v[156:157]
	v_pk_add_f32 v[140:141], v[140:141], v[156:157] neg_lo:[0,1] neg_hi:[0,1]
	v_pk_mul_f32 v[172:173], v[142:143], s[40:41]
	v_pk_fma_f32 v[186:187], v[156:157], s[24:25], v[186:187] op_sel:[0,0,1] op_sel_hi:[1,0,0] neg_lo:[1,0,0] neg_hi:[1,0,0]
	v_pk_mul_f32 v[156:157], v[140:141], s[40:41]
	v_pk_fma_f32 v[172:173], v[142:143], s[68:69], v[172:173] op_sel:[0,0,1] op_sel_hi:[1,0,0]
	s_waitcnt lgkmcnt(1)
	v_pk_mul_f32 v[188:189], v[158:159], s[18:19]
	v_pk_fma_f32 v[140:141], v[140:141], s[68:69], v[156:157] op_sel:[0,0,1] op_sel_hi:[1,0,0] neg_lo:[1,0,0] neg_hi:[1,0,0]
	v_pk_add_f32 v[156:157], v[142:143], v[158:159]
	v_pk_add_f32 v[142:143], v[142:143], v[158:159] neg_lo:[0,1] neg_hi:[0,1]
	v_pk_mul_f32 v[174:175], v[130:131], s[42:43]
	v_pk_fma_f32 v[188:189], v[158:159], s[16:17], v[188:189] op_sel:[0,0,1] op_sel_hi:[1,0,0] neg_lo:[1,0,0] neg_hi:[1,0,0]
	v_pk_mul_f32 v[158:159], v[142:143], s[36:37]
	v_pk_fma_f32 v[174:175], v[130:131], s[64:65], v[174:175] op_sel:[0,0,1] op_sel_hi:[1,0,0]
	s_waitcnt lgkmcnt(0)
	v_pk_mul_f32 v[190:191], v[160:161], s[10:11]
	v_pk_fma_f32 v[142:143], v[142:143], s[66:67], v[158:159] op_sel:[0,0,1] op_sel_hi:[1,0,0] neg_lo:[1,0,0] neg_hi:[1,0,0]
	v_pk_add_f32 v[158:159], v[130:131], v[160:161]
	v_pk_add_f32 v[130:131], v[130:131], v[160:161] neg_lo:[0,1] neg_hi:[0,1]
	v_pk_mul_f32 v[176:177], v[144:145], 1.0 op_sel:[1,0] op_sel_hi:[0,0] neg_hi:[1,0]
	v_pk_fma_f32 v[190:191], v[160:161], s[8:9], v[190:191] op_sel:[0,0,1] op_sel_hi:[1,0,0] neg_lo:[1,0,0] neg_hi:[1,0,0]
	v_pk_mul_f32 v[160:161], v[130:131], s[18:19]
	v_pk_add_f32 v[192:193], v[128:129], v[144:145]
	v_pk_add_f32 v[144:145], v[128:129], v[144:145] neg_lo:[0,1] neg_hi:[0,1]
	v_pk_fma_f32 v[130:131], v[130:131], s[16:17], v[160:161] op_sel:[0,0,1] op_sel_hi:[1,0,0] neg_lo:[1,0,0] neg_hi:[1,0,0]
	v_pk_add_f32 v[160:161], v[128:129], v[176:177]
	v_pk_add_f32 v[128:129], v[128:129], v[176:177] neg_lo:[0,1] neg_hi:[0,1]
	v_pk_add_f32 v[176:177], v[162:163], v[178:179]
	v_pk_add_f32 v[162:163], v[162:163], v[178:179] neg_lo:[0,1] neg_hi:[0,1]
	v_cvt_f32_ubyte0_e32 v2, v2
	v_pk_mul_f32 v[178:179], v[162:163], s[18:19]
	v_mul_f32_e32 v2, 0x39000000, v2
	v_pk_fma_f32 v[162:163], v[162:163], s[16:17], v[178:179] op_sel:[0,0,1] op_sel_hi:[1,0,0]
	v_pk_add_f32 v[178:179], v[164:165], v[180:181]
	v_pk_add_f32 v[164:165], v[164:165], v[180:181] neg_lo:[0,1] neg_hi:[0,1]
	v_sin_f32_e32 v34, v2
	v_pk_mul_f32 v[180:181], v[164:165], s[36:37]
	v_cos_f32_e32 v30, v2
	v_pk_fma_f32 v[164:165], v[164:165], s[66:67], v[180:181] op_sel:[0,0,1] op_sel_hi:[1,0,0]
	v_pk_add_f32 v[180:181], v[166:167], v[182:183]
	v_pk_add_f32 v[166:167], v[166:167], v[182:183] neg_lo:[0,1] neg_hi:[0,1]
	v_xor_b32_e32 v31, 0x80000000, v34
	v_pk_mul_f32 v[182:183], v[166:167], s[40:41]
	v_mov_b32_e32 v35, v31
	v_pk_fma_f32 v[166:167], v[166:167], s[68:69], v[182:183] op_sel:[0,0,1] op_sel_hi:[1,0,0]
	v_pk_add_f32 v[182:183], v[168:169], v[184:185]
	v_pk_add_f32 v[184:185], v[168:169], v[184:185] neg_lo:[0,1] neg_hi:[0,1]
	v_pk_mul_f32 v[2:3], v[30:31], v[34:35] op_sel:[1,0] op_sel_hi:[0,1]
	v_pk_add_f32 v[168:169], v[170:171], v[186:187]
	v_pk_add_f32 v[170:171], v[170:171], v[186:187] neg_lo:[0,1] neg_hi:[0,1]
	v_pk_fma_f32 v[44:45], v[30:31], v[30:31], v[2:3] op_sel_hi:[1,0,1]
	v_pk_mul_f32 v[186:187], v[170:171], s[40:41]
	v_pk_mul_f32 v[2:3], v[34:35], v[44:45] op_sel:[0,1] op_sel_hi:[1,0]
	v_pk_fma_f32 v[170:171], v[170:171], s[68:69], v[186:187] op_sel:[0,0,1] op_sel_hi:[1,0,0] neg_lo:[1,0,0] neg_hi:[1,0,0]
	v_pk_add_f32 v[186:187], v[172:173], v[188:189]
	v_pk_add_f32 v[172:173], v[172:173], v[188:189] neg_lo:[0,1] neg_hi:[0,1]
	v_pk_mul_f32 v[54:55], v[44:45], 1.0 op_sel:[1,0] op_sel_hi:[1,0] neg_lo:[1,0]
	v_pk_mul_f32 v[188:189], v[172:173], s[36:37]
	s_nop 0
	v_pk_fma_f32 v[172:173], v[172:173], s[66:67], v[188:189] op_sel:[0,0,1] op_sel_hi:[1,0,0] neg_lo:[1,0,0] neg_hi:[1,0,0]
	v_pk_add_f32 v[188:189], v[174:175], v[190:191]
	v_pk_add_f32 v[174:175], v[174:175], v[190:191] neg_lo:[0,1] neg_hi:[0,1]
	v_pk_fma_f32 v[46:47], v[30:31], v[44:45], v[2:3] op_sel_hi:[0,1,1]
	v_pk_mul_f32 v[190:191], v[174:175], s[18:19]
	v_pk_mul_f32 v[2:3], v[44:45], v[54:55] op_sel:[1,0] op_sel_hi:[0,1]
	v_pk_fma_f32 v[174:175], v[174:175], s[16:17], v[190:191] op_sel:[0,0,1] op_sel_hi:[1,0,0] neg_lo:[1,0,0] neg_hi:[1,0,0]
	v_pk_add_f32 v[190:191], v[192:193], v[152:153]
	v_pk_add_f32 v[152:153], v[192:193], v[152:153] neg_lo:[0,1] neg_hi:[0,1]
	v_pk_add_f32 v[192:193], v[194:195], v[138:139]
	v_pk_add_f32 v[138:139], v[194:195], v[138:139] neg_lo:[0,1] neg_hi:[0,1]
	v_pk_fma_f32 v[52:53], v[44:45], v[44:45], v[2:3] op_sel_hi:[1,0,1]
	v_pk_mul_f32 v[194:195], v[138:139], s[36:37]
	v_pk_mul_f32 v[58:59], v[52:53], 1.0 op_sel:[1,0] op_sel_hi:[1,0] neg_lo:[1,0]
	v_pk_fma_f32 v[138:139], v[138:139], s[66:67], v[194:195] op_sel:[0,0,1] op_sel_hi:[1,0,0]
	v_pk_add_f32 v[194:195], v[148:149], v[156:157]
	v_pk_add_f32 v[156:157], v[148:149], v[156:157] neg_lo:[0,1] neg_hi:[0,1]
	v_pk_add_f32 v[148:149], v[150:151], v[158:159]
	v_pk_add_f32 v[150:151], v[150:151], v[158:159] neg_lo:[0,1] neg_hi:[0,1]
	v_pk_mul_f32 v[2:3], v[52:53], v[58:59] op_sel:[1,0] op_sel_hi:[0,1]
	v_pk_mul_f32 v[158:159], v[150:151], s[36:37]
	v_pk_fma_f32 v[48:49], v[52:53], v[52:53], v[2:3] op_sel_hi:[1,0,1]
	v_pk_fma_f32 v[150:151], v[150:151], s[66:67], v[158:159] op_sel:[0,0,1] op_sel_hi:[1,0,0] neg_lo:[1,0,0] neg_hi:[1,0,0]
	v_pk_add_f32 v[158:159], v[144:145], v[154:155]
	v_pk_add_f32 v[144:145], v[144:145], v[154:155] neg_lo:[0,1] neg_hi:[0,1]
	v_pk_add_f32 v[154:155], v[132:133], v[140:141]
	v_pk_add_f32 v[132:133], v[132:133], v[140:141] neg_lo:[0,1] neg_hi:[0,1]
	v_pk_mul_f32 v[2:3], v[58:59], v[48:49] op_sel:[0,1] op_sel_hi:[1,0]
	v_pk_mul_f32 v[140:141], v[132:133], s[36:37]
	v_pk_fma_f32 v[36:37], v[52:53], v[48:49], v[2:3] op_sel_hi:[0,1,1]
	v_pk_fma_f32 v[132:133], v[132:133], s[66:67], v[140:141] op_sel:[0,0,1] op_sel_hi:[1,0,0]
	v_pk_add_f32 v[140:141], v[134:135], v[142:143]
	v_pk_add_f32 v[142:143], v[134:135], v[142:143] neg_lo:[0,1] neg_hi:[0,1]
	v_pk_mul_f32 v[2:3], v[58:59], v[36:37] op_sel:[0,1] op_sel_hi:[1,0]
	v_pk_add_f32 v[134:135], v[136:137], v[130:131]
	v_pk_add_f32 v[130:131], v[136:137], v[130:131] neg_lo:[0,1] neg_hi:[0,1]
	v_pk_fma_f32 v[26:27], v[52:53], v[36:37], v[2:3] op_sel_hi:[0,1,1]
	v_pk_mul_f32 v[136:137], v[130:131], s[36:37]
	v_pk_mul_f32 v[2:3], v[58:59], v[26:27] op_sel:[0,1] op_sel_hi:[1,0]
	v_pk_fma_f32 v[130:131], v[130:131], s[66:67], v[136:137] op_sel:[0,0,1] op_sel_hi:[1,0,0] neg_lo:[1,0,0] neg_hi:[1,0,0]
	v_pk_add_f32 v[136:137], v[160:161], v[182:183]
	v_pk_add_f32 v[160:161], v[160:161], v[182:183] neg_lo:[0,1] neg_hi:[0,1]
	v_pk_add_f32 v[182:183], v[176:177], v[168:169]
	v_pk_add_f32 v[168:169], v[176:177], v[168:169] neg_lo:[0,1] neg_hi:[0,1]
	v_pk_fma_f32 v[20:21], v[52:53], v[26:27], v[2:3] op_sel_hi:[0,1,1]
	v_pk_mul_f32 v[176:177], v[168:169], s[36:37]
	v_pk_mul_f32 v[2:3], v[58:59], v[20:21] op_sel:[0,1] op_sel_hi:[1,0]
	v_pk_fma_f32 v[168:169], v[168:169], s[66:67], v[176:177] op_sel:[0,0,1] op_sel_hi:[1,0,0]
	v_pk_add_f32 v[176:177], v[178:179], v[186:187]
	v_pk_add_f32 v[186:187], v[178:179], v[186:187] neg_lo:[0,1] neg_hi:[0,1]
	v_pk_fma_f32 v[10:11], v[52:53], v[20:21], v[2:3] op_sel_hi:[0,1,1]
	v_pk_add_f32 v[178:179], v[180:181], v[188:189]
	v_pk_add_f32 v[180:181], v[180:181], v[188:189] neg_lo:[0,1] neg_hi:[0,1]
	v_pk_mul_f32 v[2:3], v[58:59], v[10:11] op_sel:[0,1] op_sel_hi:[1,0]
	v_pk_mul_f32 v[188:189], v[180:181], s[36:37]
	v_pk_fma_f32 v[4:5], v[52:53], v[10:11], v[2:3] op_sel_hi:[0,1,1]
	v_pk_fma_f32 v[180:181], v[180:181], s[66:67], v[188:189] op_sel:[0,0,1] op_sel_hi:[1,0,0] neg_lo:[1,0,0] neg_hi:[1,0,0]
	v_pk_add_f32 v[188:189], v[128:129], v[184:185] op_sel:[0,1] op_sel_hi:[1,0] neg_hi:[0,1]
	v_pk_add_f32 v[128:129], v[128:129], v[184:185] op_sel:[0,1] op_sel_hi:[1,0] neg_lo:[0,1]
	v_pk_add_f32 v[184:185], v[162:163], v[170:171]
	v_pk_add_f32 v[162:163], v[162:163], v[170:171] neg_lo:[0,1] neg_hi:[0,1]
	v_pk_mul_f32 v[72:73], v[46:47], 1.0 op_sel:[1,0] op_sel_hi:[1,0] neg_lo:[1,0]
	v_pk_mul_f32 v[170:171], v[162:163], s[36:37]
	s_nop 0
	v_pk_fma_f32 v[162:163], v[162:163], s[66:67], v[170:171] op_sel:[0,0,1] op_sel_hi:[1,0,0]
	v_pk_add_f32 v[170:171], v[164:165], v[172:173]
	v_pk_add_f32 v[172:173], v[164:165], v[172:173] neg_lo:[0,1] neg_hi:[0,1]
	v_pk_mul_f32 v[2:3], v[72:73], v[4:5] op_sel:[0,1] op_sel_hi:[1,0]
	v_pk_add_f32 v[164:165], v[166:167], v[174:175]
	v_pk_add_f32 v[166:167], v[166:167], v[174:175] neg_lo:[0,1] neg_hi:[0,1]
	v_pk_mul_f32 v[14:15], v[34:35], v[4:5] op_sel:[0,1] op_sel_hi:[1,0]
	v_pk_mul_f32 v[174:175], v[166:167], s[36:37]
	v_pk_mul_f32 v[40:41], v[34:35], v[10:11] op_sel:[0,1] op_sel_hi:[1,0]
	v_pk_fma_f32 v[166:167], v[166:167], s[66:67], v[174:175] op_sel:[0,0,1] op_sel_hi:[1,0,0] neg_lo:[1,0,0] neg_hi:[1,0,0]
	v_pk_add_f32 v[174:175], v[190:191], v[194:195]
	v_pk_add_f32 v[190:191], v[190:191], v[194:195] neg_lo:[0,1] neg_hi:[0,1]
	v_pk_add_f32 v[194:195], v[192:193], v[148:149]
	v_pk_add_f32 v[192:193], v[192:193], v[148:149] neg_lo:[0,1] neg_hi:[0,1]
	v_pk_mul_f32 v[66:67], v[34:35], v[20:21] op_sel:[0,1] op_sel_hi:[1,0]
	v_pk_add_f32 v[148:149], v[152:153], v[156:157] op_sel:[0,1] op_sel_hi:[1,0] neg_hi:[0,1]
	v_pk_add_f32 v[152:153], v[152:153], v[156:157] op_sel:[0,1] op_sel_hi:[1,0] neg_lo:[0,1]
	v_pk_add_f32 v[156:157], v[138:139], v[150:151]
	v_pk_add_f32 v[150:151], v[138:139], v[150:151] neg_lo:[0,1] neg_hi:[0,1]
	v_pk_mul_f32 v[82:83], v[34:35], v[26:27] op_sel:[0,1] op_sel_hi:[1,0]
	v_pk_add_f32 v[138:139], v[158:159], v[140:141]
	v_pk_add_f32 v[140:141], v[158:159], v[140:141] neg_lo:[0,1] neg_hi:[0,1]
	v_pk_add_f32 v[158:159], v[154:155], v[134:135]
	v_pk_add_f32 v[154:155], v[154:155], v[134:135] neg_lo:[0,1] neg_hi:[0,1]
	v_pk_mul_f32 v[96:97], v[34:35], v[36:37] op_sel:[0,1] op_sel_hi:[1,0]
	v_pk_add_f32 v[134:135], v[144:145], v[142:143] op_sel:[0,1] op_sel_hi:[1,0] neg_hi:[0,1]
	v_pk_add_f32 v[142:143], v[144:145], v[142:143] op_sel:[0,1] op_sel_hi:[1,0] neg_lo:[0,1]
	v_pk_add_f32 v[144:145], v[132:133], v[130:131]
	v_pk_add_f32 v[132:133], v[132:133], v[130:131] neg_lo:[0,1] neg_hi:[0,1]
	v_pk_mul_f32 v[110:111], v[34:35], v[48:49] op_sel:[0,1] op_sel_hi:[1,0]
	v_pk_add_f32 v[130:131], v[136:137], v[176:177]
	v_pk_add_f32 v[136:137], v[136:137], v[176:177] neg_lo:[0,1] neg_hi:[0,1]
	v_pk_add_f32 v[176:177], v[182:183], v[178:179]
	v_pk_add_f32 v[182:183], v[182:183], v[178:179] neg_lo:[0,1] neg_hi:[0,1]
	v_pk_mul_f32 v[124:125], v[34:35], v[52:53] op_sel:[0,1] op_sel_hi:[1,0]
	v_pk_add_f32 v[178:179], v[160:161], v[186:187] op_sel:[0,1] op_sel_hi:[1,0] neg_hi:[0,1]
	v_pk_add_f32 v[160:161], v[160:161], v[186:187] op_sel:[0,1] op_sel_hi:[1,0] neg_lo:[0,1]
	v_pk_add_f32 v[186:187], v[168:169], v[180:181]
	v_pk_add_f32 v[180:181], v[168:169], v[180:181] neg_lo:[0,1] neg_hi:[0,1]
	v_pk_fma_f32 v[2:3], v[46:47], v[4:5], v[2:3] op_sel_hi:[0,1,1]
	v_pk_add_f32 v[168:169], v[188:189], v[170:171]
	v_pk_add_f32 v[170:171], v[188:189], v[170:171] neg_lo:[0,1] neg_hi:[0,1]
	v_pk_add_f32 v[188:189], v[184:185], v[164:165]
	v_pk_add_f32 v[184:185], v[184:185], v[164:165] neg_lo:[0,1] neg_hi:[0,1]
	v_pk_mul_f32 v[8:9], v[54:55], v[4:5] op_sel:[0,1] op_sel_hi:[1,0]
	v_pk_add_f32 v[164:165], v[128:129], v[172:173] op_sel:[0,1] op_sel_hi:[1,0] neg_hi:[0,1]
	v_pk_add_f32 v[128:129], v[128:129], v[172:173] op_sel:[0,1] op_sel_hi:[1,0] neg_lo:[0,1]
	v_pk_add_f32 v[172:173], v[162:163], v[166:167]
	v_pk_add_f32 v[166:167], v[162:163], v[166:167] neg_lo:[0,1] neg_hi:[0,1]
	v_pk_fma_f32 v[14:15], v[30:31], v[4:5], v[14:15] op_sel_hi:[0,1,1]
	v_pk_add_f32 v[162:163], v[174:175], v[194:195]
	v_pk_add_f32 v[174:175], v[174:175], v[194:195] neg_lo:[0,1] neg_hi:[0,1]
	v_pk_add_f32 v[194:195], v[190:191], v[192:193] op_sel:[0,1] op_sel_hi:[1,0] neg_hi:[0,1]
	v_pk_add_f32 v[190:191], v[190:191], v[192:193] op_sel:[0,1] op_sel_hi:[1,0] neg_lo:[0,1]
	v_pk_add_f32 v[192:193], v[148:149], v[156:157]
	v_pk_add_f32 v[148:149], v[148:149], v[156:157] neg_lo:[0,1] neg_hi:[0,1]
	v_pk_add_f32 v[156:157], v[152:153], v[150:151] op_sel:[0,1] op_sel_hi:[1,0] neg_hi:[0,1]
	v_pk_add_f32 v[150:151], v[152:153], v[150:151] op_sel:[0,1] op_sel_hi:[1,0] neg_lo:[0,1]
	v_pk_add_f32 v[152:153], v[138:139], v[158:159]
	v_pk_add_f32 v[138:139], v[138:139], v[158:159] neg_lo:[0,1] neg_hi:[0,1]
	v_pk_add_f32 v[158:159], v[140:141], v[154:155] op_sel:[0,1] op_sel_hi:[1,0] neg_hi:[0,1]
	v_pk_add_f32 v[140:141], v[140:141], v[154:155] op_sel:[0,1] op_sel_hi:[1,0] neg_lo:[0,1]
	v_pk_add_f32 v[154:155], v[134:135], v[144:145]
	v_pk_add_f32 v[134:135], v[134:135], v[144:145] neg_lo:[0,1] neg_hi:[0,1]
	v_pk_add_f32 v[144:145], v[142:143], v[132:133] op_sel:[0,1] op_sel_hi:[1,0] neg_hi:[0,1]
	v_pk_add_f32 v[132:133], v[142:143], v[132:133] op_sel:[0,1] op_sel_hi:[1,0] neg_lo:[0,1]
	v_pk_add_f32 v[142:143], v[130:131], v[176:177]
	v_pk_mul_f32 v[24:25], v[72:73], v[10:11] op_sel:[0,1] op_sel_hi:[1,0]
	v_pk_mul_f32 v[34:35], v[34:35], v[142:143] op_sel:[0,1] op_sel_hi:[1,0]
	v_pk_mul_f32 v[32:33], v[54:55], v[10:11] op_sel:[0,1] op_sel_hi:[1,0]
	v_pk_fma_f32 v[40:41], v[30:31], v[10:11], v[40:41] op_sel_hi:[0,1,1]
	v_pk_mul_f32 v[56:57], v[72:73], v[20:21] op_sel:[0,1] op_sel_hi:[1,0]
	v_pk_mul_f32 v[62:63], v[54:55], v[20:21] op_sel:[0,1] op_sel_hi:[1,0]
	v_pk_fma_f32 v[66:67], v[30:31], v[20:21], v[66:67] op_sel_hi:[0,1,1]
	v_pk_mul_f32 v[74:75], v[72:73], v[26:27] op_sel:[0,1] op_sel_hi:[1,0]
	v_pk_mul_f32 v[78:79], v[54:55], v[26:27] op_sel:[0,1] op_sel_hi:[1,0]
	v_pk_fma_f32 v[82:83], v[30:31], v[26:27], v[82:83] op_sel_hi:[0,1,1]
	v_pk_mul_f32 v[88:89], v[72:73], v[36:37] op_sel:[0,1] op_sel_hi:[1,0]
	v_pk_mul_f32 v[92:93], v[54:55], v[36:37] op_sel:[0,1] op_sel_hi:[1,0]
	v_pk_fma_f32 v[96:97], v[30:31], v[36:37], v[96:97] op_sel_hi:[0,1,1]
	v_pk_mul_f32 v[102:103], v[72:73], v[48:49] op_sel:[0,1] op_sel_hi:[1,0]
	v_pk_mul_f32 v[106:107], v[54:55], v[48:49] op_sel:[0,1] op_sel_hi:[1,0]
	v_pk_fma_f32 v[110:111], v[30:31], v[48:49], v[110:111] op_sel_hi:[0,1,1]
	v_pk_mul_f32 v[116:117], v[52:53], v[72:73] op_sel:[1,0] op_sel_hi:[0,1]
	v_pk_mul_f32 v[120:121], v[54:55], v[52:53] op_sel:[0,1] op_sel_hi:[1,0]
	v_pk_fma_f32 v[124:125], v[30:31], v[52:53], v[124:125] op_sel_hi:[0,1,1]
	v_pk_add_f32 v[130:131], v[130:131], v[176:177] neg_lo:[0,1] neg_hi:[0,1]
	v_pk_add_f32 v[176:177], v[136:137], v[182:183] op_sel:[0,1] op_sel_hi:[1,0] neg_hi:[0,1]
	v_pk_add_f32 v[136:137], v[136:137], v[182:183] op_sel:[0,1] op_sel_hi:[1,0] neg_lo:[0,1]
	v_pk_add_f32 v[182:183], v[178:179], v[186:187]
	v_pk_add_f32 v[178:179], v[178:179], v[186:187] neg_lo:[0,1] neg_hi:[0,1]
	v_pk_add_f32 v[186:187], v[160:161], v[180:181] op_sel:[0,1] op_sel_hi:[1,0] neg_hi:[0,1]
	v_pk_add_f32 v[160:161], v[160:161], v[180:181] op_sel:[0,1] op_sel_hi:[1,0] neg_lo:[0,1]
	v_pk_add_f32 v[180:181], v[168:169], v[188:189]
	v_pk_fma_f32 v[30:31], v[30:31], v[142:143], v[34:35] op_sel_hi:[0,1,1]
	v_pk_mul_f32 v[34:35], v[54:55], v[152:153] op_sel:[0,1] op_sel_hi:[1,0]
	v_xor_b32_e32 v6, 0x80000000, v3
	v_pk_fma_f32 v[8:9], v[44:45], v[4:5], v[8:9] op_sel_hi:[0,1,1]
	v_pk_fma_f32 v[24:25], v[46:47], v[10:11], v[24:25] op_sel_hi:[0,1,1]
	v_pk_fma_f32 v[32:33], v[44:45], v[10:11], v[32:33] op_sel_hi:[0,1,1]
	v_pk_fma_f32 v[56:57], v[46:47], v[20:21], v[56:57] op_sel_hi:[0,1,1]
	v_pk_fma_f32 v[62:63], v[44:45], v[20:21], v[62:63] op_sel_hi:[0,1,1]
	v_pk_fma_f32 v[74:75], v[46:47], v[26:27], v[74:75] op_sel_hi:[0,1,1]
	v_pk_fma_f32 v[78:79], v[44:45], v[26:27], v[78:79] op_sel_hi:[0,1,1]
	v_pk_fma_f32 v[88:89], v[46:47], v[36:37], v[88:89] op_sel_hi:[0,1,1]
	v_pk_fma_f32 v[92:93], v[44:45], v[36:37], v[92:93] op_sel_hi:[0,1,1]
	v_pk_fma_f32 v[102:103], v[46:47], v[48:49], v[102:103] op_sel_hi:[0,1,1]
	v_pk_fma_f32 v[106:107], v[44:45], v[48:49], v[106:107] op_sel_hi:[0,1,1]
	v_pk_mul_f32 v[114:115], v[48:49], 1.0 op_sel:[1,0] op_sel_hi:[1,0] neg_lo:[1,0]
	v_pk_fma_f32 v[116:117], v[52:53], v[46:47], v[116:117] op_sel_hi:[1,0,1]
	v_pk_fma_f32 v[120:121], v[44:45], v[52:53], v[120:121] op_sel_hi:[0,1,1]
	v_mov_b32_e32 v7, v3
	v_pk_add_f32 v[168:169], v[168:169], v[188:189] neg_lo:[0,1] neg_hi:[0,1]
	v_pk_add_f32 v[188:189], v[170:171], v[184:185] op_sel:[0,1] op_sel_hi:[1,0] neg_hi:[0,1]
	v_pk_add_f32 v[170:171], v[170:171], v[184:185] op_sel:[0,1] op_sel_hi:[1,0] neg_lo:[0,1]
	v_pk_add_f32 v[184:185], v[164:165], v[172:173]
	v_pk_add_f32 v[164:165], v[164:165], v[172:173] neg_lo:[0,1] neg_hi:[0,1]
	v_pk_add_f32 v[172:173], v[128:129], v[166:167] op_sel:[0,1] op_sel_hi:[1,0] neg_hi:[0,1]
	v_pk_add_f32 v[128:129], v[128:129], v[166:167] op_sel:[0,1] op_sel_hi:[1,0] neg_lo:[0,1]
	v_pk_fma_f32 v[34:35], v[44:45], v[152:153], v[34:35] op_sel_hi:[0,1,1]
	v_pk_mul_f32 v[44:45], v[72:73], v[180:181] op_sel:[0,1] op_sel_hi:[1,0]
	v_xor_b32_e32 v12, 0x80000000, v9
	v_xor_b32_e32 v16, 0x80000000, v15
	v_xor_b32_e32 v22, 0x80000000, v5
	v_xor_b32_e32 v28, 0x80000000, v25
	v_xor_b32_e32 v38, 0x80000000, v33
	v_xor_b32_e32 v42, 0x80000000, v41
	v_xor_b32_e32 v50, 0x80000000, v11
	v_xor_b32_e32 v60, 0x80000000, v57
	v_xor_b32_e32 v64, 0x80000000, v63
	v_xor_b32_e32 v68, 0x80000000, v67
	v_xor_b32_e32 v70, 0x80000000, v21
	v_xor_b32_e32 v76, 0x80000000, v75
	v_xor_b32_e32 v80, 0x80000000, v79
	v_xor_b32_e32 v84, 0x80000000, v83
	v_xor_b32_e32 v86, 0x80000000, v27
	v_xor_b32_e32 v90, 0x80000000, v89
	v_xor_b32_e32 v94, 0x80000000, v93
	v_xor_b32_e32 v98, 0x80000000, v97
	v_xor_b32_e32 v100, 0x80000000, v37
	v_xor_b32_e32 v104, 0x80000000, v103
	v_xor_b32_e32 v108, 0x80000000, v107
	v_xor_b32_e32 v112, 0x80000000, v111
	v_pk_mul_f32 v[118:119], v[116:117], 1.0 op_sel:[1,0] op_sel_hi:[1,0] neg_lo:[1,0]
	v_pk_mul_f32 v[122:123], v[120:121], 1.0 op_sel:[1,0] op_sel_hi:[1,0] neg_lo:[1,0]
	v_pk_mul_f32 v[126:127], v[124:125], 1.0 op_sel:[1,0] op_sel_hi:[1,0] neg_lo:[1,0]
	v_mov_b32_e32 v113, v111
	v_mov_b32_e32 v109, v107
	v_mov_b32_e32 v105, v103
	v_mov_b32_e32 v101, v37
	v_mov_b32_e32 v99, v97
	v_mov_b32_e32 v95, v93
	v_mov_b32_e32 v91, v89
	v_mov_b32_e32 v87, v27
	v_mov_b32_e32 v85, v83
	v_mov_b32_e32 v81, v79
	v_mov_b32_e32 v77, v75
	v_mov_b32_e32 v71, v21
	v_mov_b32_e32 v69, v67
	v_mov_b32_e32 v65, v63
	v_mov_b32_e32 v61, v57
	v_mov_b32_e32 v51, v11
	v_mov_b32_e32 v43, v41
	v_mov_b32_e32 v39, v33
	v_mov_b32_e32 v29, v25
	v_mov_b32_e32 v23, v5
	v_mov_b32_e32 v17, v15
	v_mov_b32_e32 v13, v9
	v_pk_fma_f32 v[44:45], v[46:47], v[180:181], v[44:45] op_sel_hi:[0,1,1]
	v_pk_mul_f32 v[46:47], v[58:59], v[192:193] op_sel:[0,1] op_sel_hi:[1,0]
	v_pk_mul_f32 v[72:73], v[114:115], v[194:195] op_sel:[0,1] op_sel_hi:[1,0]
	v_pk_mul_f32 v[6:7], v[128:129], v[6:7] op_sel:[1,0] op_sel_hi:[0,1]
	v_pk_fma_f32 v[46:47], v[52:53], v[192:193], v[46:47] op_sel_hi:[0,1,1]
	v_pk_mul_f32 v[52:53], v[126:127], v[182:183] op_sel:[0,1] op_sel_hi:[1,0]
	v_pk_mul_f32 v[54:55], v[122:123], v[154:155] op_sel:[0,1] op_sel_hi:[1,0]
	v_pk_mul_f32 v[58:59], v[118:119], v[184:185] op_sel:[0,1] op_sel_hi:[1,0]
	v_pk_fma_f32 v[48:49], v[48:49], v[194:195], v[72:73] op_sel_hi:[0,1,1]
	v_pk_mul_f32 v[72:73], v[112:113], v[176:177] op_sel:[0,1] op_sel_hi:[1,0]
	v_pk_mul_f32 v[108:109], v[108:109], v[158:159] op_sel:[0,1] op_sel_hi:[1,0]
	v_pk_mul_f32 v[104:105], v[104:105], v[188:189] op_sel:[0,1] op_sel_hi:[1,0]
	v_pk_mul_f32 v[100:101], v[100:101], v[156:157] op_sel:[0,1] op_sel_hi:[1,0]
	v_pk_mul_f32 v[98:99], v[98:99], v[186:187] op_sel:[0,1] op_sel_hi:[1,0]
	v_pk_mul_f32 v[94:95], v[94:95], v[144:145] op_sel:[0,1] op_sel_hi:[1,0]
	v_pk_mul_f32 v[90:91], v[90:91], v[172:173] op_sel:[0,1] op_sel_hi:[1,0]
	v_pk_mul_f32 v[86:87], v[174:175], v[86:87] op_sel:[1,0] op_sel_hi:[0,1]
	v_pk_mul_f32 v[84:85], v[130:131], v[84:85] op_sel:[1,0] op_sel_hi:[0,1]
	v_pk_mul_f32 v[80:81], v[138:139], v[80:81] op_sel:[1,0] op_sel_hi:[0,1]
	v_pk_mul_f32 v[76:77], v[168:169], v[76:77] op_sel:[1,0] op_sel_hi:[0,1]
	v_pk_mul_f32 v[70:71], v[148:149], v[70:71] op_sel:[1,0] op_sel_hi:[0,1]
	v_pk_mul_f32 v[68:69], v[178:179], v[68:69] op_sel:[1,0] op_sel_hi:[0,1]
	v_pk_mul_f32 v[64:65], v[134:135], v[64:65] op_sel:[1,0] op_sel_hi:[0,1]
	v_pk_mul_f32 v[60:61], v[164:165], v[60:61] op_sel:[1,0] op_sel_hi:[0,1]
	v_pk_mul_f32 v[50:51], v[190:191], v[50:51] op_sel:[1,0] op_sel_hi:[0,1]
	v_pk_mul_f32 v[42:43], v[136:137], v[42:43] op_sel:[1,0] op_sel_hi:[0,1]
	v_pk_mul_f32 v[38:39], v[140:141], v[38:39] op_sel:[1,0] op_sel_hi:[0,1]
	v_pk_mul_f32 v[28:29], v[170:171], v[28:29] op_sel:[1,0] op_sel_hi:[0,1]
	v_pk_mul_f32 v[22:23], v[150:151], v[22:23] op_sel:[1,0] op_sel_hi:[0,1]
	v_pk_mul_f32 v[16:17], v[160:161], v[16:17] op_sel:[1,0] op_sel_hi:[0,1]
	v_pk_mul_f32 v[12:13], v[132:133], v[12:13] op_sel:[1,0] op_sel_hi:[0,1]
	v_pk_fma_f32 v[2:3], v[128:129], v[2:3], v[6:7] op_sel_hi:[1,0,1]
	v_pk_fma_f32 v[52:53], v[124:125], v[182:183], v[52:53] op_sel_hi:[0,1,1]
	v_pk_fma_f32 v[54:55], v[120:121], v[154:155], v[54:55] op_sel_hi:[0,1,1]
	v_pk_fma_f32 v[58:59], v[116:117], v[184:185], v[58:59] op_sel_hi:[0,1,1]
	v_pk_fma_f32 v[72:73], v[110:111], v[176:177], v[72:73] op_sel_hi:[0,1,1]
	v_pk_fma_f32 v[106:107], v[106:107], v[158:159], v[108:109] op_sel_hi:[0,1,1]
	v_pk_fma_f32 v[102:103], v[102:103], v[188:189], v[104:105] op_sel_hi:[0,1,1]
	v_pk_fma_f32 v[36:37], v[36:37], v[156:157], v[100:101] op_sel_hi:[0,1,1]
	v_pk_fma_f32 v[96:97], v[96:97], v[186:187], v[98:99] op_sel_hi:[0,1,1]
	v_pk_fma_f32 v[92:93], v[92:93], v[144:145], v[94:95] op_sel_hi:[0,1,1]
	v_pk_fma_f32 v[88:89], v[88:89], v[172:173], v[90:91] op_sel_hi:[0,1,1]
	v_pk_fma_f32 v[26:27], v[174:175], v[26:27], v[86:87] op_sel_hi:[1,0,1]
	v_pk_fma_f32 v[82:83], v[130:131], v[82:83], v[84:85] op_sel_hi:[1,0,1]
	v_pk_fma_f32 v[78:79], v[138:139], v[78:79], v[80:81] op_sel_hi:[1,0,1]
	v_pk_fma_f32 v[74:75], v[168:169], v[74:75], v[76:77] op_sel_hi:[1,0,1]
	v_pk_fma_f32 v[20:21], v[148:149], v[20:21], v[70:71] op_sel_hi:[1,0,1]
	v_pk_fma_f32 v[66:67], v[178:179], v[66:67], v[68:69] op_sel_hi:[1,0,1]
	v_pk_fma_f32 v[62:63], v[134:135], v[62:63], v[64:65] op_sel_hi:[1,0,1]
	v_pk_fma_f32 v[56:57], v[164:165], v[56:57], v[60:61] op_sel_hi:[1,0,1]
	v_pk_fma_f32 v[10:11], v[190:191], v[10:11], v[50:51] op_sel_hi:[1,0,1]
	v_pk_fma_f32 v[40:41], v[136:137], v[40:41], v[42:43] op_sel_hi:[1,0,1]
	v_pk_fma_f32 v[32:33], v[140:141], v[32:33], v[38:39] op_sel_hi:[1,0,1]
	v_pk_fma_f32 v[24:25], v[170:171], v[24:25], v[28:29] op_sel_hi:[1,0,1]
	v_pk_fma_f32 v[4:5], v[150:151], v[4:5], v[22:23] op_sel_hi:[1,0,1]
	v_pk_fma_f32 v[14:15], v[160:161], v[14:15], v[16:17] op_sel_hi:[1,0,1]
	v_pk_fma_f32 v[8:9], v[132:133], v[8:9], v[12:13] op_sel_hi:[1,0,1]
	ds_write_b64 v18, v[162:163]
	ds_write_b64 v18, v[26:27] offset:2112
	ds_write_b64 v18, v[48:49] offset:4224
	ds_write_b64 v18, v[10:11] offset:6336
	ds_write_b64 v18, v[46:47] offset:8448
	ds_write_b64 v18, v[20:21] offset:10560
	ds_write_b64 v18, v[36:37] offset:12672
	ds_write_b64 v18, v[4:5] offset:14784
	ds_write_b64 v18, v[34:35] offset:16896
	ds_write_b64 v18, v[78:79] offset:19008
	ds_write_b64 v18, v[106:107] offset:21120
	ds_write_b64 v18, v[32:33] offset:23232
	ds_write_b64 v18, v[54:55] offset:25344
	ds_write_b64 v18, v[62:63] offset:27456
	ds_write_b64 v18, v[92:93] offset:29568
	ds_write_b64 v18, v[8:9] offset:31680
	ds_write_b64 v18, v[30:31] offset:33792
	ds_write_b64 v18, v[82:83] offset:35904
	ds_write_b64 v18, v[72:73] offset:38016
	ds_write_b64 v18, v[40:41] offset:40128
	ds_write_b64 v18, v[52:53] offset:42240
	ds_write_b64 v18, v[66:67] offset:44352
	ds_write_b64 v18, v[96:97] offset:46464
	ds_write_b64 v18, v[14:15] offset:48576
	ds_write_b64 v18, v[44:45] offset:50688
	ds_write_b64 v18, v[74:75] offset:52800
	ds_write_b64 v18, v[102:103] offset:54912
	ds_write_b64 v18, v[24:25] offset:57024
	ds_write_b64 v18, v[58:59] offset:59136
	ds_write_b64 v18, v[56:57] offset:61248
	ds_write_b64 v18, v[88:89] offset:63360
	ds_write_b64 v18, v[2:3] offset:65472
	v_mov_b32_e32 v3, v210
	s_waitcnt lgkmcnt(0)
	s_barrier
	s_add_i32 s64, s62, s48
	v_and_b32_e32 v5, 15, v3
	v_cvt_f32_ubyte0_e32 v2, v5
	v_mul_f32_e32 v4, 0x3b800000, v2
	v_sin_f32_e32 v2, v4
	v_cos_f32_e32 v4, v4
	v_lshlrev_b32_e32 v64, 3, v5
	v_lshlrev_b32_e32 v18, 4, v3
	v_xor_b32_e32 v5, 0x80000000, v2
	v_mov_b32_e32 v3, v5
	v_pk_mul_f32 v[6:7], v[4:5], v[2:3] op_sel:[1,0] op_sel_hi:[0,1]
	v_pk_fma_f32 v[6:7], v[4:5], v[4:5], v[6:7] op_sel_hi:[1,0,1]
	s_ashr_i32 s65, s64, 31
	v_pk_mul_f32 v[12:13], 1.0, v[6:7] op_sel:[0,1] op_sel_hi:[0,1] neg_lo:[0,1]
	v_pk_mul_f32 v[10:11], v[6:7], v[12:13] op_sel:[1,0] op_sel_hi:[0,1]
	v_pk_fma_f32 v[10:11], v[6:7], v[6:7], v[10:11] op_sel_hi:[1,0,1]
	v_pk_mul_f32 v[8:9], v[2:3], v[6:7] op_sel:[0,1] op_sel_hi:[1,0]
	v_pk_mul_f32 v[14:15], 1.0, v[10:11] op_sel:[0,1] op_sel_hi:[0,1] neg_lo:[0,1]
	v_pk_mul_f32 v[32:33], v[10:11], v[14:15] op_sel:[1,0] op_sel_hi:[0,1]
	v_pk_fma_f32 v[32:33], v[10:11], v[10:11], v[32:33] op_sel_hi:[1,0,1]
	v_pk_mul_f32 v[16:17], v[2:3], v[10:11] op_sel:[0,1] op_sel_hi:[1,0]
	v_pk_mul_f32 v[48:49], v[14:15], v[32:33] op_sel:[0,1] op_sel_hi:[1,0]
	v_pk_mul_f32 v[36:37], v[2:3], v[32:33] op_sel:[0,1] op_sel_hi:[1,0]
	v_pk_fma_f32 v[48:49], v[10:11], v[32:33], v[48:49] op_sel_hi:[0,1,1]
	v_pk_mul_f32 v[52:53], v[2:3], v[48:49] op_sel:[0,1] op_sel_hi:[1,0]
	v_pk_fma_f32 v[8:9], v[4:5], v[6:7], v[8:9] op_sel_hi:[0,1,1]
	v_pk_fma_f32 v[16:17], v[4:5], v[10:11], v[16:17] op_sel_hi:[0,1,1]
	v_pk_fma_f32 v[36:37], v[4:5], v[32:33], v[36:37] op_sel_hi:[0,1,1]
	v_pk_fma_f32 v[52:53], v[4:5], v[48:49], v[52:53] op_sel_hi:[0,1,1]
	v_and_b32_e32 v5, 0xffffff00, v18
	v_lshlrev_b32_e32 v18, 3, v5
	v_add3_u32 v18, 0, v64, v18
	v_ashrrev_i32_e32 v64, 2, v5
	v_add_u32_e32 v106, v18, v64
	ds_read2_b64 v[64:67], v106 offset1:16
	ds_read2_b64 v[68:71], v106 offset0:33 offset1:49
	ds_read2_b64 v[72:75], v106 offset0:66 offset1:82
	ds_read2_b64 v[76:79], v106 offset0:132 offset1:148
	ds_read2_b64 v[80:83], v106 offset0:99 offset1:115
	ds_read2_b64 v[84:87], v106 offset0:165 offset1:181
	ds_read2_b64 v[88:91], v106 offset0:198 offset1:214
	ds_read2_b64 v[92:95], v106 offset0:231 offset1:247
	s_waitcnt lgkmcnt(4)
	v_pk_add_f32 v[96:97], v[64:65], v[76:77]
	v_pk_add_f32 v[64:65], v[64:65], v[76:77] neg_lo:[0,1] neg_hi:[0,1]
	v_pk_add_f32 v[76:77], v[66:67], v[78:79]
	v_pk_add_f32 v[66:67], v[66:67], v[78:79] neg_lo:[0,1] neg_hi:[0,1]
	s_waitcnt lgkmcnt(1)
	v_pk_add_f32 v[98:99], v[74:75], v[90:91]
	v_pk_mul_f32 v[78:79], v[66:67], s[18:19]
	v_pk_add_f32 v[74:75], v[74:75], v[90:91] neg_lo:[0,1] neg_hi:[0,1]
	v_pk_fma_f32 v[66:67], v[66:67], s[16:17], v[78:79] op_sel:[0,0,1] op_sel_hi:[1,0,0]
	v_pk_add_f32 v[78:79], v[68:69], v[84:85]
	v_pk_add_f32 v[68:69], v[68:69], v[84:85] neg_lo:[0,1] neg_hi:[0,1]
	v_pk_mul_f32 v[90:91], v[74:75], s[40:41]
	v_pk_mul_f32 v[84:85], v[68:69], s[36:37]
	v_pk_fma_f32 v[74:75], v[74:75], s[68:69], v[90:91] op_sel:[0,0,1] op_sel_hi:[1,0,0] neg_lo:[1,0,0] neg_hi:[1,0,0]
	v_pk_fma_f32 v[68:69], v[68:69], s[66:67], v[84:85] op_sel:[0,0,1] op_sel_hi:[1,0,0]
	v_pk_add_f32 v[84:85], v[70:71], v[86:87]
	v_pk_add_f32 v[70:71], v[70:71], v[86:87] neg_lo:[0,1] neg_hi:[0,1]
	s_waitcnt lgkmcnt(0)
	v_pk_add_f32 v[90:91], v[80:81], v[92:93]
	v_pk_add_f32 v[80:81], v[80:81], v[92:93] neg_lo:[0,1] neg_hi:[0,1]
	v_pk_mul_f32 v[86:87], v[70:71], s[40:41]
	v_pk_mul_f32 v[92:93], v[80:81], s[36:37]
	v_pk_fma_f32 v[70:71], v[70:71], s[68:69], v[86:87] op_sel:[0,0,1] op_sel_hi:[1,0,0]
	v_pk_add_f32 v[86:87], v[72:73], v[88:89]
	v_pk_add_f32 v[88:89], v[72:73], v[88:89] neg_lo:[0,1] neg_hi:[0,1]
	v_pk_fma_f32 v[80:81], v[80:81], s[66:67], v[92:93] op_sel:[0,0,1] op_sel_hi:[1,0,0] neg_lo:[1,0,0] neg_hi:[1,0,0]
	v_pk_add_f32 v[92:93], v[82:83], v[94:95]
	v_pk_add_f32 v[82:83], v[82:83], v[94:95] neg_lo:[0,1] neg_hi:[0,1]
	s_nop 0
	v_pk_mul_f32 v[94:95], v[82:83], s[18:19]
	s_nop 0
	v_pk_fma_f32 v[82:83], v[82:83], s[16:17], v[94:95] op_sel:[0,0,1] op_sel_hi:[1,0,0] neg_lo:[1,0,0] neg_hi:[1,0,0]
	v_pk_add_f32 v[94:95], v[96:97], v[86:87]
	v_pk_add_f32 v[86:87], v[96:97], v[86:87] neg_lo:[0,1] neg_hi:[0,1]
	v_pk_add_f32 v[96:97], v[76:77], v[98:99]
	v_pk_add_f32 v[76:77], v[76:77], v[98:99] neg_lo:[0,1] neg_hi:[0,1]
	v_pk_add_f32 v[100:101], v[84:85], v[92:93]
	v_pk_add_f32 v[84:85], v[84:85], v[92:93] neg_lo:[0,1] neg_hi:[0,1]
	v_pk_add_f32 v[72:73], v[64:65], v[88:89] op_sel:[0,1] op_sel_hi:[1,0] neg_hi:[0,1]
	v_pk_add_f32 v[64:65], v[64:65], v[88:89] op_sel:[0,1] op_sel_hi:[1,0] neg_lo:[0,1]
	v_pk_add_f32 v[88:89], v[66:67], v[74:75]
	v_pk_add_f32 v[66:67], v[66:67], v[74:75] neg_lo:[0,1] neg_hi:[0,1]
	v_pk_mul_f32 v[98:99], v[76:77], s[36:37]
	v_pk_mul_f32 v[92:93], v[84:85], s[36:37]
	v_pk_mul_f32 v[74:75], v[66:67], s[36:37]
	v_pk_fma_f32 v[76:77], v[76:77], s[66:67], v[98:99] op_sel:[0,0,1] op_sel_hi:[1,0,0]
	v_pk_add_f32 v[98:99], v[78:79], v[90:91]
	v_pk_add_f32 v[90:91], v[78:79], v[90:91] neg_lo:[0,1] neg_hi:[0,1]
	v_pk_fma_f32 v[84:85], v[84:85], s[66:67], v[92:93] op_sel:[0,0,1] op_sel_hi:[1,0,0] neg_lo:[1,0,0] neg_hi:[1,0,0]
	v_pk_fma_f32 v[66:67], v[66:67], s[66:67], v[74:75] op_sel:[0,0,1] op_sel_hi:[1,0,0]
	v_pk_add_f32 v[74:75], v[68:69], v[80:81]
	v_pk_add_f32 v[92:93], v[70:71], v[82:83]
	v_pk_add_f32 v[70:71], v[70:71], v[82:83] neg_lo:[0,1] neg_hi:[0,1]
	v_pk_add_f32 v[80:81], v[68:69], v[80:81] neg_lo:[0,1] neg_hi:[0,1]
	v_pk_mul_f32 v[82:83], v[70:71], s[36:37]
	v_pk_add_f32 v[102:103], v[72:73], v[74:75]
	v_pk_add_f32 v[72:73], v[72:73], v[74:75] neg_lo:[0,1] neg_hi:[0,1]
	v_pk_add_f32 v[74:75], v[88:89], v[92:93]
	v_pk_add_f32 v[92:93], v[88:89], v[92:93] neg_lo:[0,1] neg_hi:[0,1]
	v_pk_mul_f32 v[20:21], v[8:9], 1.0 op_sel:[1,0] op_sel_hi:[1,0] neg_lo:[1,0]
	v_pk_mul_f32 v[24:25], v[12:13], v[10:11] op_sel:[0,1] op_sel_hi:[1,0]
	v_pk_fma_f32 v[70:71], v[70:71], s[66:67], v[82:83] op_sel:[0,0,1] op_sel_hi:[1,0,0] neg_lo:[1,0,0] neg_hi:[1,0,0]
	v_pk_add_f32 v[78:79], v[86:87], v[90:91] op_sel:[0,1] op_sel_hi:[1,0] neg_hi:[0,1]
	v_pk_add_f32 v[86:87], v[86:87], v[90:91] op_sel:[0,1] op_sel_hi:[1,0] neg_lo:[0,1]
	v_pk_add_f32 v[90:91], v[76:77], v[84:85]
	v_pk_add_f32 v[84:85], v[76:77], v[84:85] neg_lo:[0,1] neg_hi:[0,1]
	v_pk_mul_f32 v[22:23], v[16:17], 1.0 op_sel:[1,0] op_sel_hi:[1,0] neg_lo:[1,0]
	v_pk_fma_f32 v[24:25], v[6:7], v[10:11], v[24:25] op_sel_hi:[0,1,1]
	v_pk_mul_f32 v[28:29], v[10:11], v[20:21] op_sel:[1,0] op_sel_hi:[0,1]
	v_pk_add_f32 v[68:69], v[64:65], v[80:81] op_sel:[0,1] op_sel_hi:[1,0] neg_hi:[0,1]
	v_pk_add_f32 v[64:65], v[64:65], v[80:81] op_sel:[0,1] op_sel_hi:[1,0] neg_lo:[0,1]
	v_pk_add_f32 v[80:81], v[66:67], v[70:71]
	v_pk_add_f32 v[70:71], v[66:67], v[70:71] neg_lo:[0,1] neg_hi:[0,1]
	v_pk_add_f32 v[88:89], v[72:73], v[92:93] op_sel:[0,1] op_sel_hi:[1,0] neg_hi:[0,1]
	v_pk_mul_f32 v[26:27], v[24:25], 1.0 op_sel:[1,0] op_sel_hi:[1,0] neg_lo:[1,0]
	v_pk_fma_f32 v[28:29], v[10:11], v[8:9], v[28:29] op_sel_hi:[1,0,1]
	v_pk_add_f32 v[76:77], v[86:87], v[84:85] op_sel:[0,1] op_sel_hi:[1,0] neg_hi:[0,1]
	v_pk_add_f32 v[72:73], v[72:73], v[92:93] op_sel:[0,1] op_sel_hi:[1,0] neg_lo:[0,1]
	v_pk_mul_f32 v[92:93], v[22:23], v[88:89] op_sel:[0,1] op_sel_hi:[1,0]
	v_pk_mul_f32 v[30:31], v[28:29], 1.0 op_sel:[1,0] op_sel_hi:[1,0] neg_lo:[1,0]
	v_pk_add_f32 v[82:83], v[94:95], v[98:99]
	v_pk_add_f32 v[94:95], v[94:95], v[98:99] neg_lo:[0,1] neg_hi:[0,1]
	v_pk_add_f32 v[98:99], v[96:97], v[100:101]
	v_pk_add_f32 v[66:67], v[64:65], v[70:71] op_sel:[0,1] op_sel_hi:[1,0] neg_hi:[0,1]
	v_pk_fma_f32 v[88:89], v[16:17], v[88:89], v[92:93] op_sel_hi:[0,1,1]
	v_pk_mul_f32 v[92:93], v[26:27], v[76:77] op_sel:[0,1] op_sel_hi:[1,0]
	v_pk_mul_f32 v[34:35], v[32:33], 1.0 op_sel:[1,0] op_sel_hi:[1,0] neg_lo:[1,0]
	v_pk_mul_f32 v[40:41], v[12:13], v[32:33] op_sel:[0,1] op_sel_hi:[1,0]
	v_pk_add_f32 v[104:105], v[82:83], v[98:99]
	v_pk_add_f32 v[82:83], v[82:83], v[98:99] neg_lo:[0,1] neg_hi:[0,1]
	v_pk_fma_f32 v[76:77], v[24:25], v[76:77], v[92:93] op_sel_hi:[0,1,1]
	v_pk_mul_f32 v[92:93], v[30:31], v[66:67] op_sel:[0,1] op_sel_hi:[1,0]
	v_pk_mul_f32 v[38:39], v[36:37], 1.0 op_sel:[1,0] op_sel_hi:[1,0] neg_lo:[1,0]
	v_pk_fma_f32 v[40:41], v[6:7], v[32:33], v[40:41] op_sel_hi:[0,1,1]
	v_pk_mul_f32 v[44:45], v[20:21], v[32:33] op_sel:[0,1] op_sel_hi:[1,0]
	v_pk_add_f32 v[84:85], v[86:87], v[84:85] op_sel:[0,1] op_sel_hi:[1,0] neg_lo:[0,1]
	v_pk_add_f32 v[86:87], v[102:103], v[74:75]
	v_pk_add_f32 v[74:75], v[102:103], v[74:75] neg_lo:[0,1] neg_hi:[0,1]
	v_pk_fma_f32 v[66:67], v[28:29], v[66:67], v[92:93] op_sel_hi:[0,1,1]
	v_pk_mul_f32 v[92:93], v[34:35], v[82:83] op_sel:[0,1] op_sel_hi:[1,0]
	v_pk_mul_f32 v[42:43], v[40:41], 1.0 op_sel:[1,0] op_sel_hi:[1,0] neg_lo:[1,0]
	v_pk_fma_f32 v[44:45], v[8:9], v[32:33], v[44:45] op_sel_hi:[0,1,1]
	v_pk_add_f32 v[100:101], v[96:97], v[100:101] neg_lo:[0,1] neg_hi:[0,1]
	v_pk_add_f32 v[98:99], v[78:79], v[90:91]
	v_pk_add_f32 v[78:79], v[78:79], v[90:91] neg_lo:[0,1] neg_hi:[0,1]
	v_pk_fma_f32 v[82:83], v[32:33], v[82:83], v[92:93] op_sel_hi:[0,1,1]
	v_pk_mul_f32 v[92:93], v[38:39], v[74:75] op_sel:[0,1] op_sel_hi:[1,0]
	v_pk_mul_f32 v[46:47], v[44:45], 1.0 op_sel:[1,0] op_sel_hi:[1,0] neg_lo:[1,0]
	v_pk_add_f32 v[90:91], v[68:69], v[80:81]
	v_pk_add_f32 v[68:69], v[68:69], v[80:81] neg_lo:[0,1] neg_hi:[0,1]
	v_pk_fma_f32 v[74:75], v[36:37], v[74:75], v[92:93] op_sel_hi:[0,1,1]
	v_pk_mul_f32 v[92:93], v[42:43], v[78:79] op_sel:[0,1] op_sel_hi:[1,0]
	v_pk_mul_f32 v[50:51], v[48:49], 1.0 op_sel:[1,0] op_sel_hi:[1,0] neg_lo:[1,0]
	v_pk_mul_f32 v[56:57], v[12:13], v[48:49] op_sel:[0,1] op_sel_hi:[1,0]
	v_pk_add_f32 v[96:97], v[94:95], v[100:101] op_sel:[0,1] op_sel_hi:[1,0] neg_hi:[0,1]
	v_pk_add_f32 v[94:95], v[94:95], v[100:101] op_sel:[0,1] op_sel_hi:[1,0] neg_lo:[0,1]
	v_pk_fma_f32 v[78:79], v[40:41], v[78:79], v[92:93] op_sel_hi:[0,1,1]
	v_pk_mul_f32 v[92:93], v[46:47], v[68:69] op_sel:[0,1] op_sel_hi:[1,0]
	v_pk_mul_f32 v[54:55], v[52:53], 1.0 op_sel:[1,0] op_sel_hi:[1,0] neg_lo:[1,0]
	v_pk_fma_f32 v[56:57], v[6:7], v[48:49], v[56:57] op_sel_hi:[0,1,1]
	v_pk_mul_f32 v[60:61], v[20:21], v[48:49] op_sel:[0,1] op_sel_hi:[1,0]
	v_pk_fma_f32 v[68:69], v[44:45], v[68:69], v[92:93] op_sel_hi:[0,1,1]
	v_pk_mul_f32 v[92:93], v[50:51], v[94:95] op_sel:[0,1] op_sel_hi:[1,0]
	v_pk_mul_f32 v[58:59], v[56:57], 1.0 op_sel:[1,0] op_sel_hi:[1,0] neg_lo:[1,0]
	v_pk_fma_f32 v[60:61], v[8:9], v[48:49], v[60:61] op_sel_hi:[0,1,1]
	v_pk_add_f32 v[64:65], v[64:65], v[70:71] op_sel:[0,1] op_sel_hi:[1,0] neg_lo:[0,1]
	v_pk_mul_f32 v[70:71], v[2:3], v[86:87] op_sel:[0,1] op_sel_hi:[1,0]
	v_pk_fma_f32 v[92:93], v[48:49], v[94:95], v[92:93] op_sel_hi:[0,1,1]
	v_pk_mul_f32 v[94:95], v[54:55], v[72:73] op_sel:[0,1] op_sel_hi:[1,0]
	v_pk_mul_f32 v[62:63], v[60:61], 1.0 op_sel:[1,0] op_sel_hi:[1,0] neg_lo:[1,0]
	v_pk_fma_f32 v[70:71], v[4:5], v[86:87], v[70:71] op_sel_hi:[0,1,1]
	v_pk_mul_f32 v[86:87], v[20:21], v[90:91] op_sel:[0,1] op_sel_hi:[1,0]
	v_pk_fma_f32 v[72:73], v[52:53], v[72:73], v[94:95] op_sel_hi:[0,1,1]
	v_pk_mul_f32 v[94:95], v[58:59], v[84:85] op_sel:[0,1] op_sel_hi:[1,0]
	v_add_u32_e32 v5, 0x2000, v5
	v_pk_mul_f32 v[80:81], v[12:13], v[98:99] op_sel:[0,1] op_sel_hi:[1,0]
	v_pk_fma_f32 v[86:87], v[8:9], v[90:91], v[86:87] op_sel_hi:[0,1,1]
	v_pk_mul_f32 v[90:91], v[14:15], v[96:97] op_sel:[0,1] op_sel_hi:[1,0]
	v_pk_fma_f32 v[84:85], v[56:57], v[84:85], v[94:95] op_sel_hi:[0,1,1]
	v_pk_mul_f32 v[94:95], v[62:63], v[64:65] op_sel:[0,1] op_sel_hi:[1,0]
	v_ashrrev_i32_e32 v5, 2, v5
	v_pk_fma_f32 v[80:81], v[6:7], v[98:99], v[80:81] op_sel_hi:[0,1,1]
	v_pk_fma_f32 v[90:91], v[10:11], v[96:97], v[90:91] op_sel_hi:[0,1,1]
	v_pk_fma_f32 v[64:65], v[60:61], v[64:65], v[94:95] op_sel_hi:[0,1,1]
	ds_write2_b64 v106, v[104:105], v[82:83] offset1:16
	ds_write2_b64 v106, v[90:91], v[92:93] offset0:33 offset1:49
	ds_write2_b64 v106, v[80:81], v[78:79] offset0:66 offset1:82
	ds_write2_b64 v106, v[76:77], v[84:85] offset0:99 offset1:115
	ds_write2_b64 v106, v[70:71], v[74:75] offset0:132 offset1:148
	ds_write2_b64 v106, v[88:89], v[72:73] offset0:165 offset1:181
	ds_write2_b64 v106, v[86:87], v[68:69] offset0:198 offset1:214
	ds_write2_b64 v106, v[66:67], v[64:65] offset0:231 offset1:247
	v_add3_u32 v18, v18, v5, s5
	ds_read2_b64 v[64:67], v18 offset1:16
	ds_read2_b64 v[68:71], v18 offset0:33 offset1:49
	ds_read2_b64 v[72:75], v18 offset0:66 offset1:82
	ds_read2_b64 v[76:79], v18 offset0:132 offset1:148
	ds_read2_b64 v[80:83], v18 offset0:99 offset1:115
	ds_read2_b64 v[84:87], v18 offset0:165 offset1:181
	ds_read2_b64 v[88:91], v18 offset0:198 offset1:214
	ds_read2_b64 v[92:95], v18 offset0:231 offset1:247
	s_waitcnt lgkmcnt(4)
	v_pk_add_f32 v[96:97], v[64:65], v[76:77]
	v_pk_add_f32 v[64:65], v[64:65], v[76:77] neg_lo:[0,1] neg_hi:[0,1]
	v_pk_add_f32 v[76:77], v[66:67], v[78:79]
	v_pk_add_f32 v[66:67], v[66:67], v[78:79] neg_lo:[0,1] neg_hi:[0,1]
	s_waitcnt lgkmcnt(1)
	v_pk_add_f32 v[98:99], v[74:75], v[90:91]
	v_pk_mul_f32 v[78:79], v[66:67], s[18:19]
	v_pk_add_f32 v[74:75], v[74:75], v[90:91] neg_lo:[0,1] neg_hi:[0,1]
	v_pk_fma_f32 v[66:67], v[66:67], s[16:17], v[78:79] op_sel:[0,0,1] op_sel_hi:[1,0,0]
	v_pk_add_f32 v[78:79], v[68:69], v[84:85]
	v_pk_add_f32 v[68:69], v[68:69], v[84:85] neg_lo:[0,1] neg_hi:[0,1]
	v_pk_mul_f32 v[90:91], v[74:75], s[40:41]
	v_pk_mul_f32 v[84:85], v[68:69], s[36:37]
	v_pk_fma_f32 v[74:75], v[74:75], s[68:69], v[90:91] op_sel:[0,0,1] op_sel_hi:[1,0,0] neg_lo:[1,0,0] neg_hi:[1,0,0]
	s_waitcnt lgkmcnt(0)
	v_pk_add_f32 v[90:91], v[80:81], v[92:93]
	v_pk_add_f32 v[80:81], v[80:81], v[92:93] neg_lo:[0,1] neg_hi:[0,1]
	v_pk_fma_f32 v[68:69], v[68:69], s[66:67], v[84:85] op_sel:[0,0,1] op_sel_hi:[1,0,0]
	v_pk_add_f32 v[84:85], v[70:71], v[86:87]
	v_pk_add_f32 v[70:71], v[70:71], v[86:87] neg_lo:[0,1] neg_hi:[0,1]
	v_pk_mul_f32 v[92:93], v[80:81], s[36:37]
	v_pk_mul_f32 v[86:87], v[70:71], s[40:41]
	v_pk_fma_f32 v[80:81], v[80:81], s[66:67], v[92:93] op_sel:[0,0,1] op_sel_hi:[1,0,0] neg_lo:[1,0,0] neg_hi:[1,0,0]
	v_pk_add_f32 v[92:93], v[82:83], v[94:95]
	v_pk_add_f32 v[82:83], v[82:83], v[94:95] neg_lo:[0,1] neg_hi:[0,1]
	v_pk_fma_f32 v[70:71], v[70:71], s[68:69], v[86:87] op_sel:[0,0,1] op_sel_hi:[1,0,0]
	v_pk_add_f32 v[86:87], v[72:73], v[88:89]
	v_pk_mul_f32 v[94:95], v[82:83], s[18:19]
	v_pk_add_f32 v[88:89], v[72:73], v[88:89] neg_lo:[0,1] neg_hi:[0,1]
	v_pk_fma_f32 v[82:83], v[82:83], s[16:17], v[94:95] op_sel:[0,0,1] op_sel_hi:[1,0,0] neg_lo:[1,0,0] neg_hi:[1,0,0]
	v_pk_add_f32 v[94:95], v[96:97], v[86:87]
	v_pk_add_f32 v[86:87], v[96:97], v[86:87] neg_lo:[0,1] neg_hi:[0,1]
	v_pk_add_f32 v[96:97], v[76:77], v[98:99]
	v_pk_add_f32 v[76:77], v[76:77], v[98:99] neg_lo:[0,1] neg_hi:[0,1]
	s_nop 0
	v_pk_mul_f32 v[98:99], v[76:77], s[36:37]
	v_pk_add_f32 v[100:101], v[84:85], v[92:93]
	v_pk_add_f32 v[84:85], v[84:85], v[92:93] neg_lo:[0,1] neg_hi:[0,1]
	v_pk_fma_f32 v[76:77], v[76:77], s[66:67], v[98:99] op_sel:[0,0,1] op_sel_hi:[1,0,0]
	v_pk_add_f32 v[98:99], v[78:79], v[90:91]
	v_pk_add_f32 v[90:91], v[78:79], v[90:91] neg_lo:[0,1] neg_hi:[0,1]
	v_pk_mul_f32 v[92:93], v[84:85], s[36:37]
	v_pk_add_f32 v[72:73], v[64:65], v[88:89] op_sel:[0,1] op_sel_hi:[1,0] neg_hi:[0,1]
	v_pk_add_f32 v[64:65], v[64:65], v[88:89] op_sel:[0,1] op_sel_hi:[1,0] neg_lo:[0,1]
	v_pk_add_f32 v[88:89], v[66:67], v[74:75]
	v_pk_add_f32 v[66:67], v[66:67], v[74:75] neg_lo:[0,1] neg_hi:[0,1]
	v_pk_fma_f32 v[84:85], v[84:85], s[66:67], v[92:93] op_sel:[0,0,1] op_sel_hi:[1,0,0] neg_lo:[1,0,0] neg_hi:[1,0,0]
	v_pk_mul_f32 v[74:75], v[66:67], s[36:37]
	s_nop 0
	v_pk_fma_f32 v[66:67], v[66:67], s[66:67], v[74:75] op_sel:[0,0,1] op_sel_hi:[1,0,0]
	v_pk_add_f32 v[74:75], v[68:69], v[80:81]
	v_pk_add_f32 v[92:93], v[70:71], v[82:83]
	v_pk_add_f32 v[70:71], v[70:71], v[82:83] neg_lo:[0,1] neg_hi:[0,1]
	v_pk_add_f32 v[78:79], v[86:87], v[90:91] op_sel:[0,1] op_sel_hi:[1,0] neg_hi:[0,1]
	v_pk_add_f32 v[86:87], v[86:87], v[90:91] op_sel:[0,1] op_sel_hi:[1,0] neg_lo:[0,1]
	v_pk_add_f32 v[90:91], v[76:77], v[84:85]
	v_pk_add_f32 v[84:85], v[76:77], v[84:85] neg_lo:[0,1] neg_hi:[0,1]
	v_pk_add_f32 v[80:81], v[68:69], v[80:81] neg_lo:[0,1] neg_hi:[0,1]
	v_pk_mul_f32 v[82:83], v[70:71], s[36:37]
	v_pk_add_f32 v[102:103], v[72:73], v[74:75]
	v_pk_add_f32 v[72:73], v[72:73], v[74:75] neg_lo:[0,1] neg_hi:[0,1]
	v_pk_add_f32 v[74:75], v[88:89], v[92:93]
	v_pk_fma_f32 v[70:71], v[70:71], s[66:67], v[82:83] op_sel:[0,0,1] op_sel_hi:[1,0,0] neg_lo:[1,0,0] neg_hi:[1,0,0]
	v_pk_add_f32 v[82:83], v[94:95], v[98:99]
	v_pk_add_f32 v[94:95], v[94:95], v[98:99] neg_lo:[0,1] neg_hi:[0,1]
	v_pk_add_f32 v[98:99], v[96:97], v[100:101]
	v_pk_add_f32 v[76:77], v[86:87], v[84:85] op_sel:[0,1] op_sel_hi:[1,0] neg_hi:[0,1]
	v_pk_add_f32 v[84:85], v[86:87], v[84:85] op_sel:[0,1] op_sel_hi:[1,0] neg_lo:[0,1]
	v_pk_add_f32 v[86:87], v[102:103], v[74:75]
	v_pk_add_f32 v[100:101], v[96:97], v[100:101] neg_lo:[0,1] neg_hi:[0,1]
	v_pk_add_f32 v[68:69], v[64:65], v[80:81] op_sel:[0,1] op_sel_hi:[1,0] neg_hi:[0,1]
	v_pk_add_f32 v[64:65], v[64:65], v[80:81] op_sel:[0,1] op_sel_hi:[1,0] neg_lo:[0,1]
	v_pk_add_f32 v[80:81], v[66:67], v[70:71]
	v_pk_add_f32 v[104:105], v[82:83], v[98:99]
	v_pk_add_f32 v[82:83], v[82:83], v[98:99] neg_lo:[0,1] neg_hi:[0,1]
	v_pk_add_f32 v[98:99], v[78:79], v[90:91]
	v_pk_mul_f32 v[2:3], v[2:3], v[86:87] op_sel:[0,1] op_sel_hi:[1,0]
	v_pk_add_f32 v[92:93], v[88:89], v[92:93] neg_lo:[0,1] neg_hi:[0,1]
	v_pk_add_f32 v[78:79], v[78:79], v[90:91] neg_lo:[0,1] neg_hi:[0,1]
	v_pk_add_f32 v[90:91], v[68:69], v[80:81]
	v_pk_fma_f32 v[2:3], v[4:5], v[86:87], v[2:3] op_sel_hi:[0,1,1]
	v_pk_mul_f32 v[4:5], v[12:13], v[98:99] op_sel:[0,1] op_sel_hi:[1,0]
	v_pk_add_f32 v[70:71], v[66:67], v[70:71] neg_lo:[0,1] neg_hi:[0,1]
	v_pk_add_f32 v[96:97], v[94:95], v[100:101] op_sel:[0,1] op_sel_hi:[1,0] neg_hi:[0,1]
	v_pk_fma_f32 v[4:5], v[6:7], v[98:99], v[4:5] op_sel_hi:[0,1,1]
	v_pk_mul_f32 v[6:7], v[20:21], v[90:91] op_sel:[0,1] op_sel_hi:[1,0]
	v_pk_add_f32 v[88:89], v[72:73], v[92:93] op_sel:[0,1] op_sel_hi:[1,0] neg_hi:[0,1]
	v_pk_fma_f32 v[6:7], v[8:9], v[90:91], v[6:7] op_sel_hi:[0,1,1]
	v_pk_mul_f32 v[8:9], v[14:15], v[96:97] op_sel:[0,1] op_sel_hi:[1,0]
	v_pk_add_f32 v[66:67], v[64:65], v[70:71] op_sel:[0,1] op_sel_hi:[1,0] neg_hi:[0,1]
	v_pk_fma_f32 v[8:9], v[10:11], v[96:97], v[8:9] op_sel_hi:[0,1,1]
	v_pk_mul_f32 v[10:11], v[22:23], v[88:89] op_sel:[0,1] op_sel_hi:[1,0]
	v_pk_add_f32 v[94:95], v[94:95], v[100:101] op_sel:[0,1] op_sel_hi:[1,0] neg_lo:[0,1]
	v_pk_add_f32 v[74:75], v[102:103], v[74:75] neg_lo:[0,1] neg_hi:[0,1]
	v_pk_add_f32 v[72:73], v[72:73], v[92:93] op_sel:[0,1] op_sel_hi:[1,0] neg_lo:[0,1]
	v_pk_add_f32 v[68:69], v[68:69], v[80:81] neg_lo:[0,1] neg_hi:[0,1]
	v_pk_add_f32 v[64:65], v[64:65], v[70:71] op_sel:[0,1] op_sel_hi:[1,0] neg_lo:[0,1]
	v_pk_fma_f32 v[10:11], v[16:17], v[88:89], v[10:11] op_sel_hi:[0,1,1]
	v_pk_mul_f32 v[12:13], v[26:27], v[76:77] op_sel:[0,1] op_sel_hi:[1,0]
	v_pk_mul_f32 v[14:15], v[30:31], v[66:67] op_sel:[0,1] op_sel_hi:[1,0]
	v_pk_mul_f32 v[16:17], v[34:35], v[82:83] op_sel:[0,1] op_sel_hi:[1,0]
	v_pk_fma_f32 v[12:13], v[24:25], v[76:77], v[12:13] op_sel_hi:[0,1,1]
	v_pk_fma_f32 v[14:15], v[28:29], v[66:67], v[14:15] op_sel_hi:[0,1,1]
	v_pk_fma_f32 v[16:17], v[32:33], v[82:83], v[16:17] op_sel_hi:[0,1,1]
	v_pk_mul_f32 v[20:21], v[38:39], v[74:75] op_sel:[0,1] op_sel_hi:[1,0]
	v_pk_mul_f32 v[22:23], v[42:43], v[78:79] op_sel:[0,1] op_sel_hi:[1,0]
	v_pk_mul_f32 v[24:25], v[46:47], v[68:69] op_sel:[0,1] op_sel_hi:[1,0]
	v_pk_mul_f32 v[26:27], v[50:51], v[94:95] op_sel:[0,1] op_sel_hi:[1,0]
	v_pk_mul_f32 v[28:29], v[54:55], v[72:73] op_sel:[0,1] op_sel_hi:[1,0]
	v_pk_mul_f32 v[30:31], v[58:59], v[84:85] op_sel:[0,1] op_sel_hi:[1,0]
	v_pk_mul_f32 v[32:33], v[62:63], v[64:65] op_sel:[0,1] op_sel_hi:[1,0]
	v_pk_fma_f32 v[20:21], v[36:37], v[74:75], v[20:21] op_sel_hi:[0,1,1]
	v_pk_fma_f32 v[22:23], v[40:41], v[78:79], v[22:23] op_sel_hi:[0,1,1]
	v_pk_fma_f32 v[24:25], v[44:45], v[68:69], v[24:25] op_sel_hi:[0,1,1]
	v_pk_fma_f32 v[26:27], v[48:49], v[94:95], v[26:27] op_sel_hi:[0,1,1]
	v_pk_fma_f32 v[28:29], v[52:53], v[72:73], v[28:29] op_sel_hi:[0,1,1]
	v_pk_fma_f32 v[30:31], v[56:57], v[84:85], v[30:31] op_sel_hi:[0,1,1]
	v_pk_fma_f32 v[32:33], v[60:61], v[64:65], v[32:33] op_sel_hi:[0,1,1]
	ds_write2_b64 v18, v[104:105], v[16:17] offset1:16
	ds_write2_b64 v18, v[8:9], v[26:27] offset0:33 offset1:49
	ds_write2_b64 v18, v[4:5], v[22:23] offset0:66 offset1:82
	ds_write2_b64 v18, v[12:13], v[30:31] offset0:99 offset1:115
	ds_write2_b64 v18, v[2:3], v[20:21] offset0:132 offset1:148
	ds_write2_b64 v18, v[10:11], v[28:29] offset0:165 offset1:181
	ds_write2_b64 v18, v[6:7], v[24:25] offset0:198 offset1:214
	ds_write2_b64 v18, v[14:15], v[32:33] offset0:231 offset1:247
	v_ashrrev_i32_e32 v2, 31, v210
	v_add_u32_sdwa v2, v210, v2 dst_sel:DWORD dst_unused:UNUSED_PAD src0_sel:DWORD src1_sel:BYTE_3
	s_lshl_b64 s[0:1], s[64:65], 15
	v_and_b32_e32 v2, 0xffffff00, v2
	s_add_u32 s0, s29, s0
	v_sub_u32_e32 v2, v210, v2
	s_addc_u32 s1, s85, s1
	v_ashrrev_i32_e32 v3, 31, v2
	v_lshl_add_u64 v[14:15], v[2:3], 3, s[0:1]
	s_movk_i32 s0, 0x1000
	v_add_co_u32_e32 v16, vcc, s0, v14
	s_movk_i32 s0, 0x3000
	s_nop 0
	v_addc_co_u32_e32 v17, vcc, 0, v15, vcc
	v_add_co_u32_e32 v2, vcc, s92, v14
	s_waitcnt lgkmcnt(0)
	s_nop 0
	v_addc_co_u32_e32 v3, vcc, 0, v15, vcc
	v_add_co_u32_e32 v22, vcc, s0, v14
	s_movk_i32 s0, 0x5000
	s_nop 0
	v_addc_co_u32_e32 v23, vcc, 0, v15, vcc
	v_add_co_u32_e32 v8, vcc, s95, v14
	s_barrier
	s_nop 0
	v_addc_co_u32_e32 v9, vcc, 0, v15, vcc
	v_add_co_u32_e32 v26, vcc, s0, v14
	s_nop 1
	v_addc_co_u32_e32 v27, vcc, 0, v15, vcc
	v_add_co_u32_e32 v10, vcc, s96, v14
	global_load_dwordx2 v[12:13], v[2:3], off nt
	global_load_dwordx2 v[6:7], v[2:3], off offset:2048 nt
	global_load_dwordx2 v[4:5], v[8:9], off offset:-4096 nt
	global_load_dwordx2 v[122:123], v[8:9], off nt
	v_addc_co_u32_e32 v11, vcc, 0, v15, vcc
	v_add_co_u32_e32 v28, vcc, s97, v14
	global_load_dwordx2 v[46:47], v[8:9], off offset:2048 nt
	global_load_dwordx2 v[38:39], v[10:11], off offset:-4096 nt
	global_load_dwordx2 v[20:21], v[10:11], off nt
	s_nop 0
	global_load_dwordx2 v[10:11], v[10:11], off offset:2048 nt
	v_addc_co_u32_e32 v29, vcc, 0, v15, vcc
	global_load_dwordx2 v[24:25], v[2:3], off offset:-4096 nt
	s_nop 0
	global_load_dwordx2 v[26:27], v[26:27], off offset:2048 nt
	s_nop 0
	global_load_dwordx2 v[8:9], v[28:29], off nt
	global_load_dwordx2 v[2:3], v[28:29], off offset:2048 nt
	global_load_dwordx2 v[30:31], v[14:15], off offset:2048 nt
	s_nop 0
	global_load_dwordx2 v[28:29], v[16:17], off offset:2048 nt
	s_nop 0
	global_load_dwordx2 v[16:17], v[22:23], off offset:2048 nt
	global_load_dwordx2 v[32:33], v[14:15], off nt
	v_mov_b32_e32 v14, v210
	s_waitcnt vmcnt(15)
	v_cvt_f32_f16_sdwa v164, v12 dst_sel:DWORD dst_unused:UNUSED_PAD src0_sel:WORD_1
	v_ashrrev_i32_e32 v15, 31, v14
	v_add_u32_sdwa v15, v14, v15 dst_sel:DWORD dst_unused:UNUSED_PAD src0_sel:DWORD src1_sel:BYTE_3
	v_ashrrev_i32_e32 v15, 8, v15
	v_mul_i32_i24_e32 v18, 0x100, v15
	v_sub_u32_e32 v18, v14, v18
	v_lshlrev_b32_e32 v14, 13, v15
	v_lshlrev_b32_e32 v15, 1, v18
	v_bfrev_b32_e32 v15, v15
	v_lshrrev_b32_e32 v15, 23, v15
	v_sub_u32_e32 v15, 0x200, v15
	v_bfrev_b32_e32 v15, v15
	v_lshrrev_b32_e32 v15, 19, v15
	v_and_b32_e32 v15, 0x1ff0, v15
	v_cmp_eq_u32_e64 s[0:1], 0, v18
	v_lshl_add_u32 v22, v18, 5, v14
	v_lshl_add_u32 v23, v22, 3, 0
	v_cndmask_b32_e64 v15, v15, 16, s[0:1]
	v_or_b32_e32 v14, v15, v14
	v_ashrrev_i32_e32 v22, 2, v22
	v_ashrrev_i32_e32 v15, 5, v14
	v_add_u32_e32 v211, v23, v22
	v_lshlrev_b32_e32 v14, 3, v14
	v_lshlrev_b32_e32 v15, 3, v15
	v_add3_u32 v212, 0, v14, v15
	ds_read2_b64 v[34:37], v211 offset1:1
	ds_read2_b64 v[40:43], v211 offset0:2 offset1:3
	ds_read2_b64 v[48:51], v212 offset1:1
	ds_read2_b64 v[52:55], v212 offset0:2 offset1:3
	ds_read2_b64 v[56:59], v211 offset0:4 offset1:5
	ds_read2_b64 v[60:63], v211 offset0:6 offset1:7
	ds_read2_b64 v[68:71], v212 offset0:4 offset1:5
	ds_read2_b64 v[72:75], v212 offset0:6 offset1:7
	ds_read2_b64 v[64:67], v211 offset0:8 offset1:9
	ds_read2_b64 v[76:79], v211 offset0:10 offset1:11
	ds_read2_b64 v[80:83], v212 offset0:8 offset1:9
	ds_read2_b64 v[98:101], v212 offset0:10 offset1:11
	ds_read2_b64 v[84:87], v211 offset0:12 offset1:13
	ds_read2_b64 v[88:91], v211 offset0:14 offset1:15
	ds_read2_b64 v[102:105], v212 offset0:12 offset1:13
	ds_read2_b64 v[106:109], v212 offset0:14 offset1:15
	s_waitcnt lgkmcnt(7)
	v_pk_add_f32 v[14:15], v[34:35], v[64:65]
	v_pk_add_f32 v[22:23], v[34:35], v[64:65] neg_lo:[0,1] neg_hi:[0,1]
	v_pk_add_f32 v[34:35], v[36:37], v[66:67]
	v_pk_add_f32 v[36:37], v[36:37], v[66:67] neg_lo:[0,1] neg_hi:[0,1]
	v_cmp_ne_u32_e32 vcc, 0, v18
	v_pk_mul_f32 v[44:45], v[36:37], s[18:19]
	v_bfrev_b32_e32 v18, v18
	v_pk_fma_f32 v[36:37], v[36:37], s[16:17], v[44:45] op_sel:[0,0,1] op_sel_hi:[1,0,0]
	s_waitcnt lgkmcnt(6)
	v_pk_add_f32 v[44:45], v[40:41], v[76:77]
	v_pk_add_f32 v[40:41], v[40:41], v[76:77] neg_lo:[0,1] neg_hi:[0,1]
	v_cvt_f32_ubyte3_e32 v18, v18
	v_pk_mul_f32 v[64:65], v[40:41], s[36:37]
	v_mul_f32_e32 v18, 0x38800000, v18
	v_pk_fma_f32 v[40:41], v[40:41], s[66:67], v[64:65] op_sel:[0,0,1] op_sel_hi:[1,0,0]
	v_pk_add_f32 v[64:65], v[42:43], v[78:79]
	v_pk_add_f32 v[42:43], v[42:43], v[78:79] neg_lo:[0,1] neg_hi:[0,1]
	s_waitcnt lgkmcnt(3)
	v_pk_add_f32 v[78:79], v[58:59], v[86:87]
	v_pk_mul_f32 v[66:67], v[42:43], s[40:41]
	v_pk_add_f32 v[58:59], v[58:59], v[86:87] neg_lo:[0,1] neg_hi:[0,1]
	v_pk_fma_f32 v[42:43], v[42:43], s[68:69], v[66:67] op_sel:[0,0,1] op_sel_hi:[1,0,0]
	v_pk_add_f32 v[66:67], v[56:57], v[84:85]
	v_pk_add_f32 v[76:77], v[56:57], v[84:85] neg_lo:[0,1] neg_hi:[0,1]
	v_pk_mul_f32 v[84:85], v[58:59], s[40:41]
	s_nop 0
	v_pk_fma_f32 v[58:59], v[58:59], s[68:69], v[84:85] op_sel:[0,0,1] op_sel_hi:[1,0,0] neg_lo:[1,0,0] neg_hi:[1,0,0]
	s_waitcnt lgkmcnt(2)
	v_pk_add_f32 v[84:85], v[60:61], v[88:89]
	v_pk_add_f32 v[60:61], v[60:61], v[88:89] neg_lo:[0,1] neg_hi:[0,1]
	s_nop 0
	v_pk_mul_f32 v[86:87], v[60:61], s[36:37]
	v_pk_add_f32 v[56:57], v[22:23], v[76:77] op_sel:[0,1] op_sel_hi:[1,0] neg_hi:[0,1]
	v_pk_fma_f32 v[60:61], v[60:61], s[66:67], v[86:87] op_sel:[0,0,1] op_sel_hi:[1,0,0] neg_lo:[1,0,0] neg_hi:[1,0,0]
	v_pk_add_f32 v[86:87], v[62:63], v[90:91]
	v_pk_add_f32 v[62:63], v[62:63], v[90:91] neg_lo:[0,1] neg_hi:[0,1]
	v_pk_add_f32 v[90:91], v[64:65], v[86:87]
	v_pk_mul_f32 v[88:89], v[62:63], s[18:19]
	v_pk_add_f32 v[64:65], v[64:65], v[86:87] neg_lo:[0,1] neg_hi:[0,1]
	v_pk_fma_f32 v[62:63], v[62:63], s[16:17], v[88:89] op_sel:[0,0,1] op_sel_hi:[1,0,0] neg_lo:[1,0,0] neg_hi:[1,0,0]
	v_pk_add_f32 v[88:89], v[14:15], v[66:67]
	v_pk_add_f32 v[14:15], v[14:15], v[66:67] neg_lo:[0,1] neg_hi:[0,1]
	v_pk_add_f32 v[66:67], v[34:35], v[78:79]
	v_pk_add_f32 v[34:35], v[34:35], v[78:79] neg_lo:[0,1] neg_hi:[0,1]
	v_pk_add_f32 v[22:23], v[22:23], v[76:77] op_sel:[0,1] op_sel_hi:[1,0] neg_lo:[0,1]
	v_pk_mul_f32 v[78:79], v[34:35], s[36:37]
	v_pk_add_f32 v[76:77], v[36:37], v[58:59]
	v_pk_add_f32 v[36:37], v[36:37], v[58:59] neg_lo:[0,1] neg_hi:[0,1]
	v_pk_fma_f32 v[34:35], v[34:35], s[66:67], v[78:79] op_sel:[0,0,1] op_sel_hi:[1,0,0]
	v_pk_add_f32 v[78:79], v[44:45], v[84:85]
	v_pk_add_f32 v[84:85], v[44:45], v[84:85] neg_lo:[0,1] neg_hi:[0,1]
	v_pk_mul_f32 v[86:87], v[64:65], s[36:37]
	v_pk_mul_f32 v[58:59], v[36:37], s[36:37]
	v_pk_fma_f32 v[64:65], v[64:65], s[66:67], v[86:87] op_sel:[0,0,1] op_sel_hi:[1,0,0] neg_lo:[1,0,0] neg_hi:[1,0,0]
	v_pk_fma_f32 v[36:37], v[36:37], s[66:67], v[58:59] op_sel:[0,0,1] op_sel_hi:[1,0,0]
	v_pk_add_f32 v[58:59], v[40:41], v[60:61]
	v_pk_add_f32 v[86:87], v[42:43], v[62:63]
	v_pk_add_f32 v[42:43], v[42:43], v[62:63] neg_lo:[0,1] neg_hi:[0,1]
	s_nop 0
	v_pk_mul_f32 v[62:63], v[42:43], s[36:37]
	v_pk_add_f32 v[44:45], v[14:15], v[84:85] op_sel:[0,1] op_sel_hi:[1,0] neg_hi:[0,1]
	v_pk_add_f32 v[14:15], v[14:15], v[84:85] op_sel:[0,1] op_sel_hi:[1,0] neg_lo:[0,1]
	v_pk_add_f32 v[84:85], v[34:35], v[64:65]
	v_pk_add_f32 v[64:65], v[34:35], v[64:65] neg_lo:[0,1] neg_hi:[0,1]
	v_pk_add_f32 v[94:95], v[56:57], v[58:59]
	v_pk_add_f32 v[56:57], v[56:57], v[58:59] neg_lo:[0,1] neg_hi:[0,1]
	v_pk_add_f32 v[58:59], v[76:77], v[86:87]
	v_pk_fma_f32 v[42:43], v[42:43], s[66:67], v[62:63] op_sel:[0,0,1] op_sel_hi:[1,0,0] neg_lo:[1,0,0] neg_hi:[1,0,0]
	v_pk_add_f32 v[62:63], v[88:89], v[78:79]
	v_pk_add_f32 v[78:79], v[88:89], v[78:79] neg_lo:[0,1] neg_hi:[0,1]
	v_pk_add_f32 v[88:89], v[66:67], v[90:91]
	v_pk_add_f32 v[110:111], v[76:77], v[86:87] neg_lo:[0,1] neg_hi:[0,1]
	v_pk_add_f32 v[86:87], v[94:95], v[58:59]
	v_pk_add_f32 v[34:35], v[94:95], v[58:59] neg_lo:[0,1] neg_hi:[0,1]
	v_pk_add_f32 v[58:59], v[50:51], v[82:83]
	v_pk_add_f32 v[50:51], v[50:51], v[82:83] neg_lo:[0,1] neg_hi:[0,1]
	v_pk_add_f32 v[60:61], v[40:41], v[60:61] neg_lo:[0,1] neg_hi:[0,1]
	v_pk_add_f32 v[148:149], v[62:63], v[88:89]
	v_pk_add_f32 v[138:139], v[62:63], v[88:89] neg_lo:[0,1] neg_hi:[0,1]
	v_pk_mul_f32 v[62:63], v[50:51], s[18:19]
	v_pk_add_f32 v[90:91], v[66:67], v[90:91] neg_lo:[0,1] neg_hi:[0,1]
	v_pk_fma_f32 v[50:51], v[50:51], s[16:17], v[62:63] op_sel:[0,0,1] op_sel_hi:[1,0,0]
	v_pk_add_f32 v[62:63], v[52:53], v[98:99]
	v_pk_add_f32 v[52:53], v[52:53], v[98:99] neg_lo:[0,1] neg_hi:[0,1]
	v_pk_add_f32 v[112:113], v[22:23], v[60:61] op_sel:[0,1] op_sel_hi:[1,0] neg_hi:[0,1]
	v_pk_add_f32 v[114:115], v[22:23], v[60:61] op_sel:[0,1] op_sel_hi:[1,0] neg_lo:[0,1]
	v_pk_add_f32 v[96:97], v[44:45], v[84:85]
	v_pk_add_f32 v[66:67], v[44:45], v[84:85] neg_lo:[0,1] neg_hi:[0,1]
	v_pk_add_f32 v[60:61], v[14:15], v[64:65] op_sel:[0,1] op_sel_hi:[1,0] neg_hi:[0,1]
	v_pk_add_f32 v[84:85], v[14:15], v[64:65] op_sel:[0,1] op_sel_hi:[1,0] neg_lo:[0,1]
	v_pk_mul_f32 v[64:65], v[52:53], s[36:37]
	s_nop 0
	v_pk_fma_f32 v[52:53], v[52:53], s[66:67], v[64:65] op_sel:[0,0,1] op_sel_hi:[1,0,0]
	v_pk_add_f32 v[64:65], v[54:55], v[100:101]
	v_pk_add_f32 v[54:55], v[54:55], v[100:101] neg_lo:[0,1] neg_hi:[0,1]
	s_nop 0
	v_pk_mul_f32 v[76:77], v[54:55], s[40:41]
	v_pk_add_f32 v[92:93], v[78:79], v[90:91] op_sel:[0,1] op_sel_hi:[1,0] neg_hi:[0,1]
	v_pk_fma_f32 v[54:55], v[54:55], s[68:69], v[76:77] op_sel:[0,0,1] op_sel_hi:[1,0,0]
	s_waitcnt lgkmcnt(1)
	v_pk_add_f32 v[76:77], v[68:69], v[102:103]
	v_pk_add_f32 v[88:89], v[78:79], v[90:91] op_sel:[0,1] op_sel_hi:[1,0] neg_lo:[0,1]
	v_pk_add_f32 v[78:79], v[68:69], v[102:103] neg_lo:[0,1] neg_hi:[0,1]
	v_pk_add_f32 v[68:69], v[70:71], v[104:105]
	v_pk_add_f32 v[70:71], v[70:71], v[104:105] neg_lo:[0,1] neg_hi:[0,1]
	v_pk_add_f32 v[40:41], v[56:57], v[110:111] op_sel:[0,1] op_sel_hi:[1,0] neg_hi:[0,1]
	v_pk_add_f32 v[44:45], v[56:57], v[110:111] op_sel:[0,1] op_sel_hi:[1,0] neg_lo:[0,1]
	v_pk_add_f32 v[56:57], v[48:49], v[80:81]
	v_pk_add_f32 v[48:49], v[48:49], v[80:81] neg_lo:[0,1] neg_hi:[0,1]
	v_pk_mul_f32 v[80:81], v[70:71], s[40:41]
	v_cndmask_b32_e64 v18, v18, v208, s[0:1]
	v_pk_fma_f32 v[70:71], v[70:71], s[68:69], v[80:81] op_sel:[0,0,1] op_sel_hi:[1,0,0] neg_lo:[1,0,0] neg_hi:[1,0,0]
	s_waitcnt lgkmcnt(0)
	v_pk_add_f32 v[80:81], v[72:73], v[106:107]
	v_pk_add_f32 v[72:73], v[72:73], v[106:107] neg_lo:[0,1] neg_hi:[0,1]
	v_pk_add_f32 v[22:23], v[36:37], v[42:43]
	v_pk_mul_f32 v[82:83], v[72:73], s[36:37]
	v_pk_add_f32 v[116:117], v[36:37], v[42:43] neg_lo:[0,1] neg_hi:[0,1]
	v_pk_fma_f32 v[72:73], v[72:73], s[66:67], v[82:83] op_sel:[0,0,1] op_sel_hi:[1,0,0] neg_lo:[1,0,0] neg_hi:[1,0,0]
	v_pk_add_f32 v[82:83], v[74:75], v[108:109]
	v_pk_add_f32 v[74:75], v[74:75], v[108:109] neg_lo:[0,1] neg_hi:[0,1]
	s_nop 0
	v_pk_mul_f32 v[90:91], v[74:75], s[18:19]
	s_nop 0
	v_pk_fma_f32 v[74:75], v[74:75], s[16:17], v[90:91] op_sel:[0,0,1] op_sel_hi:[1,0,0] neg_lo:[1,0,0] neg_hi:[1,0,0]
	v_pk_add_f32 v[90:91], v[56:57], v[76:77]
	v_pk_add_f32 v[56:57], v[56:57], v[76:77] neg_lo:[0,1] neg_hi:[0,1]
	v_pk_add_f32 v[76:77], v[58:59], v[68:69]
	v_pk_add_f32 v[58:59], v[58:59], v[68:69] neg_lo:[0,1] neg_hi:[0,1]
	v_pk_add_f32 v[14:15], v[114:115], v[116:117] op_sel:[0,1] op_sel_hi:[1,0] neg_hi:[0,1]
	v_pk_mul_f32 v[68:69], v[58:59], s[36:37]
	v_pk_add_f32 v[36:37], v[114:115], v[116:117] op_sel:[0,1] op_sel_hi:[1,0] neg_lo:[0,1]
	v_pk_fma_f32 v[58:59], v[58:59], s[66:67], v[68:69] op_sel:[0,0,1] op_sel_hi:[1,0,0]
	v_pk_add_f32 v[68:69], v[62:63], v[80:81]
	v_pk_add_f32 v[80:81], v[62:63], v[80:81] neg_lo:[0,1] neg_hi:[0,1]
	s_waitcnt vmcnt(0)
	v_cvt_f32_f16_e32 v193, v33
	s_nop 0
	s_nop 0
	v_pk_add_f32 v[62:63], v[64:65], v[82:83]
	v_pk_add_f32 v[64:65], v[64:65], v[82:83] neg_lo:[0,1] neg_hi:[0,1]
	v_cvt_f32_f16_sdwa v192, v32 dst_sel:DWORD dst_unused:UNUSED_PAD src0_sel:WORD_1
	v_pk_mul_f32 v[82:83], v[64:65], s[36:37]
	v_cvt_f32_f16_e32 v194, v32
	v_pk_fma_f32 v[64:65], v[64:65], s[66:67], v[82:83] op_sel:[0,0,1] op_sel_hi:[1,0,0] neg_lo:[1,0,0] neg_hi:[1,0,0]
	v_pk_add_f32 v[82:83], v[48:49], v[78:79] op_sel:[0,1] op_sel_hi:[1,0] neg_hi:[0,1]
	v_pk_add_f32 v[48:49], v[48:49], v[78:79] op_sel:[0,1] op_sel_hi:[1,0] neg_lo:[0,1]
	v_pk_add_f32 v[78:79], v[50:51], v[70:71]
	v_pk_add_f32 v[50:51], v[50:51], v[70:71] neg_lo:[0,1] neg_hi:[0,1]
	v_cvt_f32_f16_sdwa v195, v33 dst_sel:DWORD dst_unused:UNUSED_PAD src0_sel:WORD_1
	v_pk_mul_f32 v[70:71], v[50:51], s[36:37]
	v_cvt_f32_f16_sdwa v170, v30 dst_sel:DWORD dst_unused:UNUSED_PAD src0_sel:WORD_1
	v_pk_fma_f32 v[50:51], v[50:51], s[66:67], v[70:71] op_sel:[0,0,1] op_sel_hi:[1,0,0]
	v_pk_add_f32 v[70:71], v[52:53], v[72:73]
	v_pk_add_f32 v[72:73], v[52:53], v[72:73] neg_lo:[0,1] neg_hi:[0,1]
	v_cvt_f32_f16_e32 v171, v31
	s_nop 0
	s_nop 0
	v_pk_add_f32 v[52:53], v[54:55], v[74:75]
	v_pk_add_f32 v[54:55], v[54:55], v[74:75] neg_lo:[0,1] neg_hi:[0,1]
	v_cvt_f32_f16_sdwa v185, v31 dst_sel:DWORD dst_unused:UNUSED_PAD src0_sel:WORD_1
	v_pk_mul_f32 v[74:75], v[54:55], s[36:37]
	v_cvt_f32_f16_e32 v184, v30
	v_pk_fma_f32 v[54:55], v[54:55], s[66:67], v[74:75] op_sel:[0,0,1] op_sel_hi:[1,0,0] neg_lo:[1,0,0] neg_hi:[1,0,0]
	v_pk_add_f32 v[74:75], v[90:91], v[68:69]
	v_pk_add_f32 v[68:69], v[90:91], v[68:69] neg_lo:[0,1] neg_hi:[0,1]
	v_pk_add_f32 v[90:91], v[76:77], v[62:63]
	v_pk_add_f32 v[62:63], v[76:77], v[62:63] neg_lo:[0,1] neg_hi:[0,1]
	v_cvt_f32_f16_sdwa v172, v24 dst_sel:DWORD dst_unused:UNUSED_PAD src0_sel:WORD_1
	v_pk_mul_f32 v[76:77], v[62:63], 1.0 op_sel:[1,0] op_sel_hi:[0,0] neg_hi:[1,0]
	s_nop 0
	v_pk_add_f32 v[62:63], v[56:57], v[80:81] op_sel:[0,1] op_sel_hi:[1,0] neg_hi:[0,1]
	v_pk_add_f32 v[56:57], v[56:57], v[80:81] op_sel:[0,1] op_sel_hi:[1,0] neg_lo:[0,1]
	v_pk_add_f32 v[80:81], v[58:59], v[64:65]
	v_pk_add_f32 v[58:59], v[58:59], v[64:65] neg_lo:[0,1] neg_hi:[0,1]
	v_cvt_f32_f16_e32 v173, v25
	v_pk_mul_f32 v[64:65], v[58:59], 1.0 op_sel:[1,0] op_sel_hi:[0,0] neg_hi:[1,0]
	v_pk_add_f32 v[58:59], v[82:83], v[70:71]
	v_pk_add_f32 v[70:71], v[82:83], v[70:71] neg_lo:[0,1] neg_hi:[0,1]
	v_pk_add_f32 v[82:83], v[78:79], v[52:53]
	v_pk_add_f32 v[52:53], v[78:79], v[52:53] neg_lo:[0,1] neg_hi:[0,1]
	v_pk_add_f32 v[118:119], v[58:59], v[82:83]
	v_pk_add_f32 v[134:135], v[58:59], v[82:83] neg_lo:[0,1] neg_hi:[0,1]
	v_cos_f32_e32 v83, v18
	v_sin_f32_e32 v82, v18
	v_cvt_f32_f16_sdwa v181, v25 dst_sel:DWORD dst_unused:UNUSED_PAD src0_sel:WORD_1
	v_cvt_f32_f16_e32 v180, v24
	v_cvt_f32_f16_sdwa v174, v28 dst_sel:DWORD dst_unused:UNUSED_PAD src0_sel:WORD_1
	v_cvt_f32_f16_e32 v175, v29
	v_cvt_f32_f16_sdwa v179, v29 dst_sel:DWORD dst_unused:UNUSED_PAD src0_sel:WORD_1
	v_cvt_f32_f16_e32 v178, v28
	v_cvt_f32_f16_e32 v165, v13
	v_cvt_f32_f16_sdwa v167, v13 dst_sel:DWORD dst_unused:UNUSED_PAD src0_sel:WORD_1
	v_cvt_f32_f16_e32 v166, v12
	v_cvt_f32_f16_e32 v154, v6
	v_cvt_f32_f16_e32 v155, v7
	v_cvt_f32_f16_sdwa v157, v7 dst_sel:DWORD dst_unused:UNUSED_PAD src0_sel:WORD_1
	v_cvt_f32_f16_sdwa v156, v6 dst_sel:DWORD dst_unused:UNUSED_PAD src0_sel:WORD_1
	v_cvt_f32_f16_sdwa v140, v4 dst_sel:DWORD dst_unused:UNUSED_PAD src0_sel:WORD_1
	v_cvt_f32_f16_e32 v141, v5
	v_cvt_f32_f16_sdwa v143, v5 dst_sel:DWORD dst_unused:UNUSED_PAD src0_sel:WORD_1
	v_cvt_f32_f16_e32 v142, v4
	v_cvt_f32_f16_e32 v124, v16
	v_cvt_f32_f16_e32 v125, v17
	v_cvt_f32_f16_sdwa v127, v17 dst_sel:DWORD dst_unused:UNUSED_PAD src0_sel:WORD_1
	v_cvt_f32_f16_sdwa v126, v16 dst_sel:DWORD dst_unused:UNUSED_PAD src0_sel:WORD_1
	v_cvt_f32_f16_sdwa v114, v122 dst_sel:DWORD dst_unused:UNUSED_PAD src0_sel:WORD_1
	v_cvt_f32_f16_e32 v115, v123
	v_cvt_f32_f16_sdwa v117, v123 dst_sel:DWORD dst_unused:UNUSED_PAD src0_sel:WORD_1
	v_cvt_f32_f16_e32 v116, v122
	v_pk_mul_f32 v[78:79], v[52:53], 1.0 op_sel:[1,0] op_sel_hi:[0,0] neg_hi:[1,0]
	s_nop 0
	v_pk_add_f32 v[52:53], v[48:49], v[72:73] op_sel:[0,1] op_sel_hi:[1,0] neg_hi:[0,1]
	v_pk_add_f32 v[48:49], v[48:49], v[72:73] op_sel:[0,1] op_sel_hi:[1,0] neg_lo:[0,1]
	v_pk_add_f32 v[72:73], v[50:51], v[54:55]
	v_pk_add_f32 v[50:51], v[50:51], v[54:55] neg_lo:[0,1] neg_hi:[0,1]
	v_pk_fma_f32 v[160:161], v[82:83], 0, v[82:83] op_sel:[0,0,1] op_sel_hi:[1,0,0] neg_lo:[1,0,0] neg_hi:[1,0,0]
	v_pk_mul_f32 v[54:55], v[50:51], 1.0 op_sel:[1,0] op_sel_hi:[0,0] neg_hi:[1,0]
	v_pk_fma_f32 v[198:199], v[82:83], 0, v[82:83] op_sel:[0,0,1] op_sel_hi:[1,0,0]
	v_pk_add_f32 v[42:43], v[112:113], v[22:23]
	v_pk_add_f32 v[22:23], v[112:113], v[22:23] neg_lo:[0,1] neg_hi:[0,1]
	v_pk_add_f32 v[98:99], v[74:75], v[90:91]
	v_pk_add_f32 v[100:101], v[74:75], v[90:91] neg_lo:[0,1] neg_hi:[0,1]
	v_pk_add_f32 v[102:103], v[68:69], v[76:77]
	v_pk_add_f32 v[106:107], v[68:69], v[76:77] neg_lo:[0,1] neg_hi:[0,1]
	v_pk_add_f32 v[104:105], v[62:63], v[80:81]
	v_pk_add_f32 v[108:109], v[62:63], v[80:81] neg_lo:[0,1] neg_hi:[0,1]
	v_pk_add_f32 v[110:111], v[56:57], v[64:65]
	v_pk_add_f32 v[112:113], v[56:57], v[64:65] neg_lo:[0,1] neg_hi:[0,1]
	v_pk_add_f32 v[152:153], v[70:71], v[78:79]
	v_pk_add_f32 v[162:163], v[70:71], v[78:79] neg_lo:[0,1] neg_hi:[0,1]
	v_pk_add_f32 v[176:177], v[52:53], v[72:73]
	v_pk_add_f32 v[182:183], v[52:53], v[72:73] neg_lo:[0,1] neg_hi:[0,1]
	v_pk_add_f32 v[188:189], v[48:49], v[54:55]
	v_pk_add_f32 v[196:197], v[48:49], v[54:55] neg_lo:[0,1] neg_hi:[0,1]
	v_pk_mul_f32 v[186:187], v[82:83], 0 op_sel_hi:[1,0]
	v_pk_mov_b32 v[190:191], v[160:161], v[198:199] op_sel:[0,1]
	v_mul_f32_e32 v18, 0x3f3504f3, v83
	v_mul_f32_e32 v158, 0xbec3ef15, v83
	v_mul_f32_e32 v132, 0xbf6c835e, v83
	s_and_saveexec_b64 s[0:1], vcc
	s_xor_b64 s[0:1], exec, s[0:1]
	s_cbranch_execz .LBB0_536
	v_pk_add_f32 v[4:5], v[148:149], v[196:197]
	v_pk_add_f32 v[6:7], v[148:149], v[196:197] neg_lo:[0,1] neg_hi:[0,1]
	v_mul_f32_e32 v4, 0.5, v4
	v_mul_f32_e32 v12, 0.5, v7
	v_mov_b32_e32 v7, v5
	v_pk_mul_f32 v[6:7], v[6:7], s[44:45]
	v_pk_mov_b32 v[16:17], v[198:199], v[160:161] op_sel:[1,0]
	v_pk_mul_f32 v[24:25], v[190:191], v[6:7] op_sel:[0,1] op_sel_hi:[1,0]
	v_pk_mul_f32 v[6:7], v[190:191], v[6:7]
	v_pk_add_f32 v[24:25], v[24:25], v[24:25] op_sel:[0,1] op_sel_hi:[0,1]
	v_pk_add_f32 v[28:29], v[4:5], v[24:25] op_sel_hi:[0,1] neg_hi:[0,1]
	v_pk_add_f32 v[4:5], v[6:7], v[6:7] op_sel:[0,1] op_sel_hi:[0,1] neg_lo:[0,1] neg_hi:[0,1]
	v_pk_add_f32 v[6:7], v[12:13], v[4:5] op_sel_hi:[0,1] neg_hi:[0,1]
	v_pk_mul_f32 v[4:5], v[6:7], v[194:195]
	v_pk_mul_f32 v[6:7], v[6:7], v[192:193]
	v_pk_fma_f32 v[4:5], v[28:29], v[192:193], v[4:5]
	v_pk_fma_f32 v[6:7], v[28:29], v[194:195], v[6:7] neg_lo:[0,0,1] neg_hi:[0,0,1]
	s_mov_b32 s66, s19
	v_pk_add_f32 v[12:13], v[6:7], v[4:5] op_sel:[0,1] op_sel_hi:[1,0] neg_lo:[0,1]
	v_pk_add_f32 v[28:29], v[6:7], v[4:5] op_sel:[0,1] op_sel_hi:[1,0]
	v_pk_add_f32 v[4:5], v[4:5], v[6:7] op_sel:[1,0] op_sel_hi:[0,1] neg_lo:[0,1] neg_hi:[0,1]
	s_nop 0
	v_pk_mul_f32 v[12:13], v[12:13], 0.5 op_sel_hi:[1,0]
	v_mov_b32_e32 v29, v5
	v_mul_f32_e32 v24, v190, v12
	v_pk_fma_f32 v[30:31], v[190:191], v[12:13], v[24:25] op_sel_hi:[1,1,0] neg_lo:[1,0,0] neg_hi:[1,0,0]
	v_mul_f32_e32 v24, v160, v13
	v_pk_fma_f32 v[12:13], v[16:17], v[12:13], v[24:25] op_sel_hi:[1,1,0]
	v_mov_b32_e32 v16, v83
	v_mov_b32_e32 v30, v12
	v_pk_fma_f32 v[4:5], v[28:29], 0.5, v[12:13] op_sel_hi:[1,0,1] neg_lo:[0,0,1] neg_hi:[0,0,1]
	v_pk_fma_f32 v[122:123], v[28:29], 0.5, v[30:31] op_sel_hi:[1,0,1]
	v_pk_fma_f32 v[6:7], v[28:29], 0.5, v[30:31] op_sel_hi:[1,0,1] neg_lo:[1,0,0] neg_hi:[1,0,0]
	v_mov_b32_e32 v5, v123
	v_pk_mul_f32 v[24:25], v[4:5], s[46:47] op_sel_hi:[1,0]
	v_pk_add_f32 v[4:5], v[138:139], v[188:189]
	v_pk_add_f32 v[12:13], v[138:139], v[188:189] neg_lo:[0,1] neg_hi:[0,1]
	v_mov_b32_e32 v17, v82
	v_mul_f32_e32 v6, 0.5, v13
	v_pk_add_f32 v[28:29], v[186:187], v[16:17] neg_lo:[0,1] neg_hi:[0,1]
	v_pk_add_f32 v[30:31], v[186:187], v[16:17]
	v_mov_b32_e32 v13, v5
	v_pk_mov_b32 v[32:33], v[28:29], v[30:31] op_sel:[1,0]
	v_pk_mul_f32 v[12:13], v[12:13], s[44:45]
	v_mul_f32_e32 v4, 0.5, v4
	v_pk_mul_f32 v[48:49], v[32:33], v[12:13] op_sel:[0,1] op_sel_hi:[1,0]
	v_pk_mul_f32 v[12:13], v[32:33], v[12:13]
	v_pk_add_f32 v[48:49], v[48:49], v[48:49] op_sel:[0,1] op_sel_hi:[0,1]
	v_pk_add_f32 v[50:51], v[4:5], v[48:49] op_sel_hi:[0,1] neg_hi:[0,1]
	v_pk_add_f32 v[4:5], v[12:13], v[12:13] op_sel:[0,1] op_sel_hi:[0,1] neg_lo:[0,1] neg_hi:[0,1]
	v_pk_add_f32 v[12:13], v[6:7], v[4:5] op_sel_hi:[0,1] neg_hi:[0,1]
	v_pk_mul_f32 v[4:5], v[12:13], v[184:185]
	v_pk_mul_f32 v[12:13], v[12:13], v[170:171]
	v_pk_fma_f32 v[4:5], v[50:51], v[170:171], v[4:5]
	v_pk_fma_f32 v[12:13], v[50:51], v[184:185], v[12:13] neg_lo:[0,0,1] neg_hi:[0,0,1]
	v_mov_b32_e32 v31, v29
	v_pk_add_f32 v[48:49], v[12:13], v[4:5] op_sel:[0,1] op_sel_hi:[1,0] neg_lo:[0,1]
	v_pk_add_f32 v[50:51], v[12:13], v[4:5] op_sel:[0,1] op_sel_hi:[1,0]
	v_pk_add_f32 v[4:5], v[4:5], v[12:13] op_sel:[1,0] op_sel_hi:[0,1] neg_lo:[0,1] neg_hi:[0,1]
	v_pk_mul_f32 v[48:49], v[48:49], 0.5 op_sel_hi:[1,0]
	v_mov_b32_e32 v51, v5
	v_mul_f32_e32 v6, v29, v48
	v_pk_fma_f32 v[32:33], v[32:33], v[48:49], v[6:7] op_sel_hi:[1,1,0] neg_lo:[1,0,0] neg_hi:[1,0,0]
	v_mul_f32_e32 v6, v29, v49
	v_pk_fma_f32 v[28:29], v[30:31], v[48:49], v[6:7] op_sel_hi:[1,1,0]
	v_pk_mul_f32 v[12:13], v[16:17], s[36:37]
	v_mov_b32_e32 v32, v28
	v_pk_fma_f32 v[4:5], v[50:51], 0.5, v[28:29] op_sel_hi:[1,0,1] neg_lo:[0,0,1] neg_hi:[0,0,1]
	v_pk_fma_f32 v[138:139], v[50:51], 0.5, v[32:33] op_sel_hi:[1,0,1]
	v_pk_add_f32 v[16:17], v[92:93], v[182:183]
	v_mov_b32_e32 v5, v139
	v_pk_add_f32 v[28:29], v[92:93], v[182:183] neg_lo:[0,1] neg_hi:[0,1]
	v_pk_mul_f32 v[30:31], v[4:5], s[46:47] op_sel_hi:[1,0]
	v_pk_fma_f32 v[4:5], v[50:51], 0.5, v[32:33] op_sel_hi:[1,0,1] neg_lo:[1,0,0] neg_hi:[1,0,0]
	v_mul_f32_e32 v6, 0.5, v29
	v_pk_add_f32 v[32:33], v[18:19], v[12:13] op_sel:[0,1] op_sel_hi:[0,1] neg_lo:[0,1] neg_hi:[0,1]
	v_pk_add_f32 v[48:49], v[18:19], v[12:13] op_sel:[0,1] op_sel_hi:[0,1]
	v_mov_b32_e32 v29, v17
	v_mul_f32_e32 v4, 0.5, v16
	v_pk_mov_b32 v[50:51], v[32:33], v[48:49] op_sel:[0,1]
	v_pk_mul_f32 v[16:17], v[28:29], s[44:45]
	v_pk_mov_b32 v[48:49], v[48:49], v[32:33] op_sel:[1,0]
	v_pk_mul_f32 v[28:29], v[50:51], v[16:17] op_sel:[0,1] op_sel_hi:[1,0]
	v_pk_mul_f32 v[16:17], v[50:51], v[16:17]
	v_pk_add_f32 v[28:29], v[28:29], v[28:29] op_sel:[0,1] op_sel_hi:[0,1]
	v_pk_add_f32 v[52:53], v[4:5], v[28:29] op_sel_hi:[0,1] neg_hi:[0,1]
	v_pk_add_f32 v[16:17], v[16:17], v[16:17] op_sel:[0,1] op_sel_hi:[0,1] neg_lo:[0,1] neg_hi:[0,1]
	v_pk_add_f32 v[28:29], v[6:7], v[16:17] op_sel_hi:[0,1] neg_hi:[0,1]
	v_pk_mul_f32 v[16:17], v[28:29], v[180:181]
	v_pk_mul_f32 v[28:29], v[28:29], v[172:173]
	v_pk_fma_f32 v[16:17], v[52:53], v[172:173], v[16:17]
	v_pk_fma_f32 v[28:29], v[52:53], v[180:181], v[28:29] neg_lo:[0,0,1] neg_hi:[0,0,1]
	v_sub_f32_e32 v6, v89, v177
	v_pk_add_f32 v[52:53], v[28:29], v[16:17] op_sel:[0,1] op_sel_hi:[1,0] neg_lo:[0,1]
	v_pk_add_f32 v[54:55], v[28:29], v[16:17] op_sel:[0,1] op_sel_hi:[1,0]
	v_pk_add_f32 v[16:17], v[16:17], v[28:29] op_sel:[1,0] op_sel_hi:[0,1] neg_lo:[0,1] neg_hi:[0,1]
	v_pk_mul_f32 v[52:53], v[52:53], 0.5 op_sel_hi:[1,0]
	v_mov_b32_e32 v55, v17
	v_mul_f32_e32 v4, v32, v52
	v_pk_fma_f32 v[56:57], v[50:51], v[52:53], v[4:5] op_sel_hi:[1,1,0] neg_lo:[1,0,0] neg_hi:[1,0,0]
	v_mul_f32_e32 v4, v32, v53
	v_pk_fma_f32 v[48:49], v[48:49], v[52:53], v[4:5] op_sel_hi:[1,1,0]
	v_pk_add_f32 v[28:29], v[88:89], v[176:177]
	v_mov_b32_e32 v56, v48
	v_pk_fma_f32 v[16:17], v[54:55], 0.5, v[48:49] op_sel_hi:[1,0,1] neg_lo:[0,0,1] neg_hi:[0,0,1]
	v_pk_mov_b32 v[48:49], v[12:13], v[88:89] op_sel:[0,0]
	v_pk_mov_b32 v[12:13], v[12:13], v[176:177] op_sel:[1,0]
	v_mul_f32_e32 v18, 0.5, v29
	v_pk_add_f32 v[12:13], v[48:49], v[12:13] neg_lo:[0,1] neg_hi:[0,1]
	v_mul_f32_e32 v4, 0.5, v28
	v_pk_mul_f32 v[48:49], v[12:13], v[18:19]
	v_mov_b32_e32 v13, v32
	v_pk_fma_f32 v[50:51], v[50:51], v[48:49], v[48:49] op_sel:[0,1,0] op_sel_hi:[1,0,1]
	v_mov_b32_e32 v48, v49
	v_mov_b32_e32 v49, v18
	v_pk_mul_f32 v[48:49], v[12:13], v[48:49]
	v_pk_add_f32 v[52:53], v[4:5], v[50:51]
	v_mul_f32_e32 v6, 0.5, v6
	v_fma_f32 v53, v28, 0.5, -v50
	v_pk_add_f32 v[28:29], v[48:49], v[48:49] op_sel:[0,1] op_sel_hi:[0,1] neg_lo:[0,1] neg_hi:[0,1]
	v_pk_add_f32 v[48:49], v[6:7], v[28:29] op_sel_hi:[0,1] neg_hi:[0,1]
	v_pk_mul_f32 v[28:29], v[48:49], v[178:179]
	v_pk_mul_f32 v[48:49], v[48:49], v[174:175]
	v_pk_fma_f32 v[28:29], v[52:53], v[174:175], v[28:29]
	v_pk_fma_f32 v[48:49], v[52:53], v[178:179], v[48:49] neg_lo:[0,0,1] neg_hi:[0,0,1]
	v_pk_fma_f32 v[92:93], v[54:55], 0.5, v[56:57] op_sel_hi:[1,0,1]
	v_pk_add_f32 v[50:51], v[48:49], v[28:29] op_sel:[0,1] op_sel_hi:[1,0] neg_lo:[0,1]
	v_pk_add_f32 v[52:53], v[48:49], v[28:29] op_sel:[0,1] op_sel_hi:[1,0]
	v_mov_b32_e32 v17, v93
	v_pk_mul_f32 v[50:51], v[50:51], 0.5 op_sel_hi:[1,0]
	v_pk_mul_f32 v[64:65], v[16:17], s[46:47] op_sel_hi:[1,0]
	v_mul_f32_e32 v4, v12, v50
	v_pk_fma_f32 v[16:17], v[54:55], 0.5, v[56:57] op_sel_hi:[1,0,1] neg_lo:[1,0,0] neg_hi:[1,0,0]
	v_pk_fma_f32 v[54:55], v[12:13], v[50:51], v[4:5] op_sel_hi:[1,1,0] neg_lo:[1,0,0] neg_hi:[1,0,0]
	v_mov_b32_e32 v33, v12
	v_mul_f32_e32 v4, v12, v51
	v_pk_fma_f32 v[12:13], v[32:33], v[50:51], v[4:5] op_sel_hi:[1,1,0]
	v_pk_add_f32 v[28:29], v[28:29], v[48:49] op_sel:[1,0] op_sel_hi:[0,1] neg_lo:[0,1] neg_hi:[0,1]
	v_mov_b32_e32 v53, v29
	v_mov_b32_e32 v54, v12
	v_pk_fma_f32 v[12:13], v[52:53], 0.5, v[12:13] op_sel_hi:[1,0,1] neg_lo:[0,0,1] neg_hi:[0,0,1]
	v_pk_fma_f32 v[88:89], v[52:53], 0.5, v[54:55] op_sel_hi:[1,0,1]
	s_mov_b32 s67, s16
	v_mov_b32_e32 v13, v89
	v_pk_mul_f32 v[68:69], v[12:13], s[46:47] op_sel_hi:[1,0]
	v_pk_fma_f32 v[12:13], v[52:53], 0.5, v[54:55] op_sel_hi:[1,0,1] neg_lo:[1,0,0] neg_hi:[1,0,0]
	v_mov_b32_e32 v4, v83
	s_mov_b32 s17, s19
	v_pk_mul_f32 v[48:49], v[82:83], s[66:67] op_sel_hi:[0,1]
	v_pk_add_f32 v[28:29], v[96:97], v[162:163]
	v_pk_add_f32 v[32:33], v[96:97], v[162:163] neg_lo:[0,1] neg_hi:[0,1]
	v_pk_fma_f32 v[52:53], v[4:5], s[16:17], v[48:49] op_sel_hi:[0,1,1] neg_lo:[0,0,1] neg_hi:[0,0,1]
	v_mul_f32_e32 v12, 0.5, v33
	v_pk_fma_f32 v[50:51], v[4:5], s[16:17], v[48:49] op_sel_hi:[0,1,1]
	v_mov_b32_e32 v33, v29
	v_mul_f32_e32 v6, 0.5, v28
	v_pk_mov_b32 v[54:55], v[52:53], v[50:51] op_sel:[0,1]
	v_pk_mul_f32 v[28:29], v[32:33], s[44:45]
	v_pk_mov_b32 v[56:57], v[50:51], v[52:53] op_sel:[1,0]
	v_pk_mul_f32 v[32:33], v[54:55], v[28:29] op_sel:[0,1] op_sel_hi:[1,0]
	v_pk_mul_f32 v[28:29], v[54:55], v[28:29]
	v_pk_add_f32 v[32:33], v[32:33], v[32:33] op_sel:[0,1] op_sel_hi:[0,1]
	v_pk_add_f32 v[58:59], v[6:7], v[32:33] op_sel_hi:[0,1] neg_hi:[0,1]
	v_pk_add_f32 v[28:29], v[28:29], v[28:29] op_sel:[0,1] op_sel_hi:[0,1] neg_lo:[0,1] neg_hi:[0,1]
	v_pk_add_f32 v[32:33], v[12:13], v[28:29] op_sel_hi:[0,1] neg_hi:[0,1]
	v_pk_mul_f32 v[28:29], v[32:33], v[166:167]
	v_pk_mul_f32 v[32:33], v[32:33], v[164:165]
	v_pk_fma_f32 v[28:29], v[58:59], v[164:165], v[28:29]
	v_pk_fma_f32 v[32:33], v[58:59], v[166:167], v[32:33] neg_lo:[0,0,1] neg_hi:[0,0,1]
	v_mov_b32_e32 v159, v66
	v_pk_add_f32 v[58:59], v[32:33], v[28:29] op_sel:[0,1] op_sel_hi:[1,0] neg_lo:[0,1]
	v_pk_add_f32 v[70:71], v[32:33], v[28:29] op_sel:[0,1] op_sel_hi:[1,0]
	v_pk_add_f32 v[28:29], v[28:29], v[32:33] op_sel:[1,0] op_sel_hi:[0,1] neg_lo:[0,1] neg_hi:[0,1]
	v_pk_mul_f32 v[58:59], v[58:59], 0.5 op_sel_hi:[1,0]
	v_mov_b32_e32 v71, v29
	v_mul_f32_e32 v6, v52, v58
	v_pk_fma_f32 v[72:73], v[54:55], v[58:59], v[6:7] op_sel_hi:[1,1,0] neg_lo:[1,0,0] neg_hi:[1,0,0]
	v_mul_f32_e32 v6, v52, v59
	v_pk_fma_f32 v[56:57], v[56:57], v[58:59], v[6:7] op_sel_hi:[1,1,0]
	v_sub_f32_e32 v12, v67, v153
	v_mov_b32_e32 v72, v56
	v_pk_fma_f32 v[28:29], v[70:71], 0.5, v[56:57] op_sel_hi:[1,0,1] neg_lo:[0,0,1] neg_hi:[0,0,1]
	v_pk_fma_f32 v[96:97], v[70:71], 0.5, v[72:73] op_sel_hi:[1,0,1]
	v_pk_mov_b32 v[56:57], v[48:49], v[152:153] op_sel:[1,0]
	v_mov_b32_e32 v29, v97
	v_pk_mul_f32 v[62:63], v[28:29], s[46:47] op_sel_hi:[1,0]
	v_pk_add_f32 v[28:29], v[66:67], v[152:153]
	v_pk_add_f32 v[56:57], v[158:159], v[56:57] neg_lo:[0,1] neg_hi:[0,1]
	v_mul_f32_e32 v18, 0.5, v29
	v_pk_mul_f32 v[58:59], v[56:57], v[18:19]
	v_mul_f32_e32 v6, 0.5, v28
	v_pk_fma_f32 v[54:55], v[54:55], v[58:59], v[58:59] op_sel:[0,1,0] op_sel_hi:[1,0,1]
	v_pk_mov_b32 v[66:67], v[56:57], v[52:53] op_sel:[0,0]
	v_mov_b32_e32 v58, v59
	v_mov_b32_e32 v59, v18
	v_pk_mul_f32 v[58:59], v[66:67], v[58:59]
	v_pk_add_f32 v[66:67], v[6:7], v[54:55]
	v_mul_f32_e32 v12, 0.5, v12
	v_fma_f32 v67, v28, 0.5, -v54
	v_pk_add_f32 v[28:29], v[58:59], v[58:59] op_sel:[0,1] op_sel_hi:[0,1] neg_lo:[0,1] neg_hi:[0,1]
	v_pk_add_f32 v[54:55], v[12:13], v[28:29] op_sel_hi:[0,1] neg_hi:[0,1]
	v_pk_mul_f32 v[28:29], v[54:55], v[156:157]
	v_pk_mul_f32 v[54:55], v[54:55], v[154:155]
	v_pk_fma_f32 v[32:33], v[70:71], 0.5, v[72:73] op_sel_hi:[1,0,1] neg_lo:[1,0,0] neg_hi:[1,0,0]
	v_pk_fma_f32 v[58:59], v[66:67], v[154:155], v[28:29] neg_lo:[0,0,1] neg_hi:[0,0,1]
	v_pk_fma_f32 v[28:29], v[66:67], v[154:155], v[28:29]
	v_pk_fma_f32 v[70:71], v[66:67], v[156:157], v[54:55]
	v_pk_fma_f32 v[54:55], v[66:67], v[156:157], v[54:55] neg_lo:[0,0,1] neg_hi:[0,0,1]
	v_pk_add_f32 v[72:73], v[58:59], v[28:29] op_sel:[0,1] op_sel_hi:[1,0]
	v_pk_add_f32 v[66:67], v[70:71], v[54:55] op_sel_hi:[0,1] neg_lo:[0,1] neg_hi:[0,1]
	v_pk_add_f32 v[28:29], v[58:59], v[28:29] op_sel_hi:[0,1] neg_lo:[0,1] neg_hi:[0,1]
	v_pk_add_f32 v[54:55], v[70:71], v[54:55] op_sel:[0,1] op_sel_hi:[1,0]
	v_mov_b32_e32 v73, v67
	v_mov_b32_e32 v55, v29
	v_pk_mul_f32 v[28:29], v[54:55], 0.5 op_sel_hi:[1,0]
	v_mov_b32_e32 v133, v84
	v_pk_mul_f32 v[54:55], v[52:53], v[28:29] op_sel:[0,1] op_sel_hi:[0,0]
	v_pk_fma_f32 v[58:59], v[56:57], v[28:29], v[54:55] op_sel_hi:[0,1,1]
	v_pk_fma_f32 v[28:29], v[56:57], v[28:29], v[54:55] op_sel_hi:[0,1,1] neg_hi:[0,0,1]
	v_pk_fma_f32 v[54:55], v[72:73], 0.5, v[58:59] op_sel_hi:[1,0,1] neg_lo:[0,0,1] neg_hi:[0,0,1]
	v_pk_fma_f32 v[66:67], v[72:73], 0.5, v[28:29] op_sel_hi:[1,0,1]
	v_pk_add_f32 v[56:57], v[60:61], v[134:135] neg_lo:[0,1] neg_hi:[0,1]
	v_mov_b32_e32 v55, v67
	v_pk_mul_f32 v[90:91], v[54:55], s[46:47] op_sel_hi:[1,0]
	v_pk_add_f32 v[54:55], v[134:135], v[60:61]
	v_mul_f32_e32 v12, 0.5, v57
	v_mov_b32_e32 v57, v55
	v_mul_f32_e32 v6, 0.5, v54
	v_pk_mov_b32 v[58:59], v[52:53], v[50:51] op_sel:[1,0]
	v_pk_mul_f32 v[54:55], v[56:57], s[44:45]
	v_pk_fma_f32 v[28:29], v[72:73], 0.5, v[28:29] op_sel_hi:[1,0,1] neg_lo:[1,0,0] neg_hi:[1,0,0]
	v_pk_mul_f32 v[56:57], v[58:59], v[54:55] op_sel:[0,1] op_sel_hi:[1,0]
	v_pk_mul_f32 v[54:55], v[58:59], v[54:55]
	v_pk_add_f32 v[56:57], v[56:57], v[56:57] op_sel:[0,1] op_sel_hi:[0,1]
	v_pk_add_f32 v[60:61], v[6:7], v[56:57] op_sel_hi:[0,1] neg_hi:[0,1]
	v_pk_add_f32 v[54:55], v[54:55], v[54:55] op_sel:[0,1] op_sel_hi:[0,1] neg_lo:[0,1] neg_hi:[0,1]
	v_pk_add_f32 v[56:57], v[12:13], v[54:55] op_sel_hi:[0,1] neg_hi:[0,1]
	v_pk_mul_f32 v[54:55], v[56:57], v[142:143]
	v_pk_mul_f32 v[56:57], v[56:57], v[140:141]
	v_pk_fma_f32 v[54:55], v[60:61], v[140:141], v[54:55]
	v_pk_fma_f32 v[56:57], v[60:61], v[142:143], v[56:57] neg_lo:[0,0,1] neg_hi:[0,0,1]
	v_mov_b32_e32 v51, v53
	v_pk_add_f32 v[60:61], v[56:57], v[54:55] op_sel:[0,1] op_sel_hi:[1,0] neg_lo:[0,1]
	v_pk_add_f32 v[70:71], v[56:57], v[54:55] op_sel:[0,1] op_sel_hi:[1,0]
	v_pk_add_f32 v[54:55], v[54:55], v[56:57] op_sel:[1,0] op_sel_hi:[0,1] neg_lo:[0,1] neg_hi:[0,1]
	v_pk_mul_f32 v[60:61], v[60:61], 0.5 op_sel_hi:[1,0]
	v_mov_b32_e32 v71, v55
	v_mul_f32_e32 v6, v53, v60
	v_pk_fma_f32 v[72:73], v[58:59], v[60:61], v[6:7] op_sel_hi:[1,1,0] neg_lo:[1,0,0] neg_hi:[1,0,0]
	v_mul_f32_e32 v6, v53, v61
	v_pk_fma_f32 v[50:51], v[50:51], v[60:61], v[6:7] op_sel_hi:[1,1,0]
	v_pk_add_f32 v[54:55], v[118:119], v[84:85]
	v_mov_b32_e32 v72, v50
	v_mov_b32_e32 v49, v118
	v_pk_fma_f32 v[50:51], v[70:71], 0.5, v[50:51] op_sel_hi:[1,0,1] neg_lo:[0,0,1] neg_hi:[0,0,1]
	v_pk_fma_f32 v[60:61], v[70:71], 0.5, v[72:73] op_sel_hi:[1,0,1]
	v_mul_f32_e32 v18, 0.5, v55
	v_pk_add_f32 v[48:49], v[132:133], v[48:49] neg_lo:[0,1] neg_hi:[0,1]
	v_mov_b32_e32 v51, v61
	v_pk_mul_f32 v[56:57], v[48:49], v[18:19]
	v_pk_mul_f32 v[94:95], v[50:51], s[46:47] op_sel_hi:[1,0]
	v_pk_fma_f32 v[50:51], v[70:71], 0.5, v[72:73] op_sel_hi:[1,0,1] neg_lo:[1,0,0] neg_hi:[1,0,0]
	v_mul_f32_e32 v6, 0.5, v54
	v_pk_fma_f32 v[58:59], v[58:59], v[56:57], v[56:57] op_sel:[0,1,0] op_sel_hi:[1,0,1]
	v_pk_mov_b32 v[70:71], v[48:49], v[52:53] op_sel:[0,1]
	v_mov_b32_e32 v56, v57
	v_mov_b32_e32 v57, v18
	v_sub_f32_e32 v12, v85, v119
	v_pk_mul_f32 v[56:57], v[70:71], v[56:57]
	v_pk_add_f32 v[70:71], v[6:7], v[58:59]
	v_mul_f32_e32 v12, 0.5, v12
	v_fma_f32 v71, v54, 0.5, -v58
	v_pk_add_f32 v[54:55], v[56:57], v[56:57] op_sel:[0,1] op_sel_hi:[0,1] neg_lo:[0,1] neg_hi:[0,1]
	v_pk_add_f32 v[56:57], v[12:13], v[54:55] op_sel_hi:[0,1] neg_hi:[0,1]
	v_pk_mul_f32 v[54:55], v[56:57], v[126:127]
	v_pk_mul_f32 v[56:57], v[56:57], v[124:125]
	v_pk_fma_f32 v[58:59], v[70:71], v[124:125], v[54:55] neg_lo:[0,0,1] neg_hi:[0,0,1]
	v_pk_fma_f32 v[54:55], v[70:71], v[124:125], v[54:55]
	v_pk_fma_f32 v[72:73], v[70:71], v[126:127], v[56:57]
	v_pk_fma_f32 v[56:57], v[70:71], v[126:127], v[56:57] neg_lo:[0,0,1] neg_hi:[0,0,1]
	v_pk_add_f32 v[70:71], v[58:59], v[54:55] op_sel:[0,1] op_sel_hi:[1,0]
	v_pk_add_f32 v[74:75], v[72:73], v[56:57] op_sel_hi:[0,1] neg_lo:[0,1] neg_hi:[0,1]
	v_pk_add_f32 v[54:55], v[58:59], v[54:55] op_sel_hi:[0,1] neg_lo:[0,1] neg_hi:[0,1]
	v_pk_add_f32 v[56:57], v[72:73], v[56:57] op_sel:[0,1] op_sel_hi:[1,0]
	v_mov_b32_e32 v71, v75
	v_mov_b32_e32 v57, v55
	v_pk_mul_f32 v[54:55], v[56:57], 0.5 op_sel_hi:[1,0]
	s_mov_b32 s66, s11
	v_pk_mul_f32 v[52:53], v[52:53], v[54:55] op_sel:[1,1] op_sel_hi:[1,0]
	s_mov_b32 s67, s8
	v_pk_fma_f32 v[56:57], v[48:49], v[54:55], v[52:53] op_sel_hi:[0,1,1]
	v_pk_fma_f32 v[48:49], v[48:49], v[54:55], v[52:53] op_sel_hi:[0,1,1] neg_hi:[0,0,1]
	s_nop 0
	v_pk_fma_f32 v[52:53], v[70:71], 0.5, v[56:57] op_sel_hi:[1,0,1] neg_lo:[0,0,1] neg_hi:[0,0,1]
	v_pk_fma_f32 v[84:85], v[70:71], 0.5, v[48:49] op_sel_hi:[1,0,1]
	s_mov_b32 s9, s11
	v_mov_b32_e32 v53, v85
	v_pk_mul_f32 v[80:81], v[52:53], s[46:47] op_sel_hi:[1,0]
	v_pk_mul_f32 v[118:119], v[82:83], s[66:67] op_sel_hi:[0,1]
	v_pk_add_f32 v[52:53], v[86:87], v[112:113]
	v_pk_add_f32 v[54:55], v[86:87], v[112:113] neg_lo:[0,1] neg_hi:[0,1]
	v_pk_fma_f32 v[58:59], v[4:5], s[8:9], v[118:119] op_sel_hi:[0,1,1] neg_lo:[0,0,1] neg_hi:[0,0,1]
	v_mul_f32_e32 v12, 0.5, v55
	v_pk_fma_f32 v[72:73], v[4:5], s[8:9], v[118:119] op_sel_hi:[0,1,1]
	v_mov_b32_e32 v55, v53
	v_mul_f32_e32 v6, 0.5, v52
	v_pk_mov_b32 v[56:57], v[58:59], v[72:73] op_sel:[0,1]
	v_pk_mul_f32 v[52:53], v[54:55], s[44:45]
	v_pk_fma_f32 v[48:49], v[70:71], 0.5, v[48:49] op_sel_hi:[1,0,1] neg_lo:[1,0,0] neg_hi:[1,0,0]
	v_pk_mul_f32 v[54:55], v[56:57], v[52:53] op_sel:[0,1] op_sel_hi:[1,0]
	v_pk_mul_f32 v[52:53], v[56:57], v[52:53]
	v_pk_add_f32 v[54:55], v[54:55], v[54:55] op_sel:[0,1] op_sel_hi:[0,1]
	v_pk_add_f32 v[74:75], v[6:7], v[54:55] op_sel_hi:[0,1] neg_hi:[0,1]
	v_pk_add_f32 v[52:53], v[52:53], v[52:53] op_sel:[0,1] op_sel_hi:[0,1] neg_lo:[0,1] neg_hi:[0,1]
	v_pk_add_f32 v[54:55], v[12:13], v[52:53] op_sel_hi:[0,1] neg_hi:[0,1]
	v_pk_mul_f32 v[52:53], v[54:55], v[116:117]
	v_pk_mul_f32 v[54:55], v[54:55], v[114:115]
	v_pk_fma_f32 v[52:53], v[74:75], v[114:115], v[52:53]
	v_pk_fma_f32 v[54:55], v[74:75], v[116:117], v[54:55] neg_lo:[0,0,1] neg_hi:[0,0,1]
	v_pk_mov_b32 v[70:71], v[72:73], v[58:59] op_sel:[1,0]
	v_pk_add_f32 v[74:75], v[54:55], v[52:53] op_sel:[0,1] op_sel_hi:[1,0] neg_lo:[0,1]
	v_pk_add_f32 v[76:77], v[54:55], v[52:53] op_sel:[0,1] op_sel_hi:[1,0]
	v_pk_add_f32 v[52:53], v[52:53], v[54:55] op_sel:[1,0] op_sel_hi:[0,1] neg_lo:[0,1] neg_hi:[0,1]
	v_pk_mul_f32 v[74:75], v[74:75], 0.5 op_sel_hi:[1,0]
	v_mov_b32_e32 v77, v53
	v_mul_f32_e32 v6, v58, v74
	v_pk_fma_f32 v[112:113], v[56:57], v[74:75], v[6:7] op_sel_hi:[1,1,0] neg_lo:[1,0,0] neg_hi:[1,0,0]
	v_mul_f32_e32 v6, v58, v75
	v_pk_fma_f32 v[70:71], v[70:71], v[74:75], v[6:7] op_sel_hi:[1,1,0]
	v_pk_add_f32 v[54:55], v[34:35], v[110:111]
	v_mov_b32_e32 v112, v70
	v_pk_fma_f32 v[52:53], v[76:77], 0.5, v[70:71] op_sel_hi:[1,0,1] neg_lo:[0,0,1] neg_hi:[0,0,1]
	v_pk_fma_f32 v[86:87], v[76:77], 0.5, v[112:113] op_sel_hi:[1,0,1]
	v_sub_f32_e32 v12, v35, v111
	v_mov_b32_e32 v53, v87
	v_pk_mul_f32 v[78:79], v[52:53], s[46:47] op_sel_hi:[1,0]
	v_mul_f32_e32 v52, 0xbe47c5c2, v83
	v_mov_b32_e32 v53, v34
	v_pk_mov_b32 v[34:35], v[118:119], v[110:111] op_sel:[1,0]
	v_mul_f32_e32 v18, 0.5, v55
	v_pk_add_f32 v[34:35], v[52:53], v[34:35] neg_lo:[0,1] neg_hi:[0,1]
	v_mov_b32_e32 v71, v58
	v_pk_mul_f32 v[52:53], v[34:35], v[18:19]
	v_mov_b32_e32 v70, v34
	v_pk_fma_f32 v[56:57], v[56:57], v[52:53], v[52:53] op_sel:[0,1,0] op_sel_hi:[1,0,1]
	v_mov_b32_e32 v52, v53
	v_mov_b32_e32 v53, v18
	v_mul_f32_e32 v6, 0.5, v54
	v_pk_mul_f32 v[52:53], v[70:71], v[52:53]
	v_cvt_f32_f16_e32 v70, v46
	v_cvt_f32_f16_e32 v71, v47
	v_cvt_f32_f16_sdwa v47, v47 dst_sel:DWORD dst_unused:UNUSED_PAD src0_sel:WORD_1
	v_cvt_f32_f16_sdwa v46, v46 dst_sel:DWORD dst_unused:UNUSED_PAD src0_sel:WORD_1
	v_pk_fma_f32 v[74:75], v[76:77], 0.5, v[112:113] op_sel_hi:[1,0,1] neg_lo:[1,0,0] neg_hi:[1,0,0]
	v_mul_f32_e32 v12, 0.5, v12
	v_pk_add_f32 v[76:77], v[6:7], v[56:57]
	v_pk_add_f32 v[52:53], v[52:53], v[52:53] op_sel:[0,1] op_sel_hi:[0,1] neg_lo:[0,1] neg_hi:[0,1]
	v_fma_f32 v77, v54, 0.5, -v56
	v_pk_add_f32 v[54:55], v[12:13], v[52:53] op_sel_hi:[0,1] neg_hi:[0,1]
	v_pk_mul_f32 v[52:53], v[54:55], v[46:47]
	v_pk_mul_f32 v[54:55], v[54:55], v[70:71]
	v_pk_fma_f32 v[56:57], v[76:77], v[70:71], v[52:53] neg_lo:[0,0,1] neg_hi:[0,0,1]
	v_pk_fma_f32 v[52:53], v[76:77], v[70:71], v[52:53]
	v_pk_fma_f32 v[70:71], v[76:77], v[46:47], v[54:55]
	v_pk_fma_f32 v[46:47], v[76:77], v[46:47], v[54:55] neg_lo:[0,0,1] neg_hi:[0,0,1]
	v_pk_add_f32 v[54:55], v[56:57], v[52:53] op_sel:[0,1] op_sel_hi:[1,0]
	v_pk_add_f32 v[76:77], v[70:71], v[46:47] op_sel_hi:[0,1] neg_lo:[0,1] neg_hi:[0,1]
	v_pk_add_f32 v[52:53], v[56:57], v[52:53] op_sel_hi:[0,1] neg_lo:[0,1] neg_hi:[0,1]
	v_pk_add_f32 v[46:47], v[70:71], v[46:47] op_sel:[0,1] op_sel_hi:[1,0]
	v_mov_b32_e32 v55, v77
	v_mov_b32_e32 v47, v53
	v_pk_mul_f32 v[46:47], v[46:47], 0.5 op_sel_hi:[1,0]
	s_mov_b32 s25, s27
	v_pk_mul_f32 v[52:53], v[58:59], v[46:47] op_sel:[0,1] op_sel_hi:[0,0]
	v_pk_fma_f32 v[56:57], v[34:35], v[46:47], v[52:53] op_sel_hi:[0,1,1]
	v_pk_fma_f32 v[46:47], v[34:35], v[46:47], v[52:53] op_sel_hi:[0,1,1] neg_hi:[0,0,1]
	s_nop 0
	v_pk_fma_f32 v[52:53], v[54:55], 0.5, v[56:57] op_sel_hi:[1,0,1] neg_lo:[0,0,1] neg_hi:[0,0,1]
	v_pk_fma_f32 v[34:35], v[54:55], 0.5, v[46:47] op_sel_hi:[1,0,1]
	s_mov_b32 s66, s27
	v_mov_b32_e32 v53, v35
	v_pk_mul_f32 v[136:137], v[52:53], s[46:47] op_sel_hi:[1,0]
	v_pk_fma_f32 v[52:53], v[54:55], 0.5, v[46:47] op_sel_hi:[1,0,1] neg_lo:[1,0,0] neg_hi:[1,0,0]
	s_mov_b32 s67, s24
	v_pk_mul_f32 v[46:47], v[82:83], s[24:25] op_sel_hi:[0,1]
	v_pk_add_f32 v[54:55], v[108:109], v[40:41]
	v_pk_add_f32 v[40:41], v[40:41], v[108:109] neg_lo:[0,1] neg_hi:[0,1]
	v_pk_fma_f32 v[108:109], v[4:5], s[66:67], v[46:47] op_sel_hi:[0,1,1] neg_lo:[0,0,1] neg_hi:[0,0,1]
	v_mul_f32_e32 v12, 0.5, v41
	v_pk_fma_f32 v[70:71], v[4:5], s[66:67], v[46:47] op_sel_hi:[0,1,1]
	v_mov_b32_e32 v41, v55
	v_pk_mov_b32 v[56:57], v[108:109], v[70:71] op_sel:[0,1]
	s_nop 0
	v_pk_mul_f32 v[40:41], v[40:41], s[44:45]
	v_mul_f32_e32 v6, 0.5, v54
	v_pk_mul_f32 v[54:55], v[56:57], v[40:41] op_sel:[0,1] op_sel_hi:[1,0]
	v_cvt_f32_f16_sdwa v76, v38 dst_sel:DWORD dst_unused:UNUSED_PAD src0_sel:WORD_1
	v_cvt_f32_f16_e32 v77, v39
	v_cvt_f32_f16_sdwa v39, v39 dst_sel:DWORD dst_unused:UNUSED_PAD src0_sel:WORD_1
	v_cvt_f32_f16_e32 v38, v38
	v_pk_mul_f32 v[40:41], v[56:57], v[40:41]
	v_pk_add_f32 v[54:55], v[54:55], v[54:55] op_sel:[0,1] op_sel_hi:[0,1]
	v_pk_add_f32 v[112:113], v[6:7], v[54:55] op_sel_hi:[0,1] neg_hi:[0,1]
	s_nop 0
	v_pk_add_f32 v[40:41], v[40:41], v[40:41] op_sel:[0,1] op_sel_hi:[0,1] neg_lo:[0,1] neg_hi:[0,1]
	v_pk_add_f32 v[54:55], v[12:13], v[40:41] op_sel_hi:[0,1] neg_hi:[0,1]
	v_pk_mul_f32 v[40:41], v[54:55], v[38:39]
	v_pk_mul_f32 v[54:55], v[54:55], v[76:77]
	v_pk_fma_f32 v[40:41], v[112:113], v[76:77], v[40:41]
	v_pk_fma_f32 v[38:39], v[112:113], v[38:39], v[54:55] neg_lo:[0,0,1] neg_hi:[0,0,1]
	v_pk_mov_b32 v[110:111], v[70:71], v[108:109] op_sel:[1,0]
	v_pk_add_f32 v[54:55], v[38:39], v[40:41] op_sel:[0,1] op_sel_hi:[1,0] neg_lo:[0,1]
	v_pk_add_f32 v[76:77], v[38:39], v[40:41] op_sel:[0,1] op_sel_hi:[1,0]
	v_pk_add_f32 v[38:39], v[40:41], v[38:39] op_sel:[1,0] op_sel_hi:[0,1] neg_lo:[0,1] neg_hi:[0,1]
	v_pk_mul_f32 v[54:55], v[54:55], 0.5 op_sel_hi:[1,0]
	v_mov_b32_e32 v77, v39
	v_mul_f32_e32 v4, v108, v54
	v_pk_fma_f32 v[112:113], v[56:57], v[54:55], v[4:5] op_sel_hi:[1,1,0] neg_lo:[1,0,0] neg_hi:[1,0,0]
	v_mul_f32_e32 v4, v108, v55
	v_pk_fma_f32 v[54:55], v[110:111], v[54:55], v[4:5] op_sel_hi:[1,1,0]
	v_sub_f32_e32 v6, v45, v105
	v_mov_b32_e32 v112, v54
	v_pk_fma_f32 v[40:41], v[76:77], 0.5, v[54:55] op_sel_hi:[1,0,1] neg_lo:[0,0,1] neg_hi:[0,0,1]
	v_pk_fma_f32 v[38:39], v[76:77], 0.5, v[112:113] op_sel_hi:[1,0,1]
	v_pk_add_f32 v[54:55], v[104:105], v[44:45]
	v_mov_b32_e32 v41, v39
	v_pk_mul_f32 v[130:131], v[40:41], s[46:47] op_sel_hi:[1,0]
	v_mul_f32_e32 v40, 0xbf54db31, v83
	v_mov_b32_e32 v41, v44
	v_pk_mov_b32 v[44:45], v[46:47], v[104:105] op_sel:[1,0]
	v_mul_f32_e32 v18, 0.5, v55
	v_pk_add_f32 v[40:41], v[40:41], v[44:45] neg_lo:[0,1] neg_hi:[0,1]
	v_mov_b32_e32 v105, v108
	v_pk_mul_f32 v[44:45], v[40:41], v[18:19]
	v_mov_b32_e32 v104, v40
	v_pk_fma_f32 v[56:57], v[56:57], v[44:45], v[44:45] op_sel:[0,1,0] op_sel_hi:[1,0,1]
	v_mov_b32_e32 v44, v45
	v_mov_b32_e32 v45, v18
	v_mul_f32_e32 v4, 0.5, v54
	v_pk_mul_f32 v[44:45], v[104:105], v[44:45]
	v_cvt_f32_f16_e32 v104, v26
	v_cvt_f32_f16_e32 v105, v27
	v_cvt_f32_f16_sdwa v27, v27 dst_sel:DWORD dst_unused:UNUSED_PAD src0_sel:WORD_1
	v_cvt_f32_f16_sdwa v26, v26 dst_sel:DWORD dst_unused:UNUSED_PAD src0_sel:WORD_1
	v_mul_f32_e32 v6, 0.5, v6
	v_pk_add_f32 v[110:111], v[4:5], v[56:57]
	v_pk_add_f32 v[44:45], v[44:45], v[44:45] op_sel:[0,1] op_sel_hi:[0,1] neg_lo:[0,1] neg_hi:[0,1]
	v_fma_f32 v111, v54, 0.5, -v56
	v_pk_add_f32 v[54:55], v[6:7], v[44:45] op_sel_hi:[0,1] neg_hi:[0,1]
	v_pk_mul_f32 v[44:45], v[54:55], v[26:27]
	v_pk_mul_f32 v[54:55], v[54:55], v[104:105]
	v_pk_fma_f32 v[56:57], v[110:111], v[104:105], v[44:45] neg_lo:[0,0,1] neg_hi:[0,0,1]
	v_pk_fma_f32 v[44:45], v[110:111], v[104:105], v[44:45]
	v_pk_fma_f32 v[104:105], v[110:111], v[26:27], v[54:55]
	v_pk_fma_f32 v[26:27], v[110:111], v[26:27], v[54:55] neg_lo:[0,0,1] neg_hi:[0,0,1]
	v_pk_add_f32 v[54:55], v[56:57], v[44:45] op_sel:[0,1] op_sel_hi:[1,0]
	v_pk_add_f32 v[110:111], v[104:105], v[26:27] op_sel_hi:[0,1] neg_lo:[0,1] neg_hi:[0,1]
	v_pk_add_f32 v[44:45], v[56:57], v[44:45] op_sel_hi:[0,1] neg_lo:[0,1] neg_hi:[0,1]
	v_pk_add_f32 v[26:27], v[104:105], v[26:27] op_sel:[0,1] op_sel_hi:[1,0]
	v_mov_b32_e32 v55, v111
	v_mov_b32_e32 v27, v45
	v_pk_mul_f32 v[26:27], v[26:27], 0.5 op_sel_hi:[1,0]
	v_mov_b32_e32 v47, v102
	v_pk_mul_f32 v[44:45], v[108:109], v[26:27] op_sel:[0,1] op_sel_hi:[0,0]
	v_pk_fma_f32 v[56:57], v[40:41], v[26:27], v[44:45] op_sel_hi:[0,1,1]
	v_pk_fma_f32 v[40:41], v[40:41], v[26:27], v[44:45] op_sel_hi:[0,1,1] neg_hi:[0,0,1]
	v_pk_fma_f32 v[44:45], v[54:55], 0.5, v[56:57] op_sel_hi:[1,0,1] neg_lo:[0,0,1] neg_hi:[0,0,1]
	v_pk_fma_f32 v[26:27], v[54:55], 0.5, v[40:41] op_sel_hi:[1,0,1]
	v_pk_fma_f32 v[56:57], v[54:55], 0.5, v[40:41] op_sel_hi:[1,0,1] neg_lo:[1,0,0] neg_hi:[1,0,0]
	v_pk_add_f32 v[40:41], v[106:107], v[42:43]
	v_pk_add_f32 v[42:43], v[42:43], v[106:107] neg_lo:[0,1] neg_hi:[0,1]
	v_mov_b32_e32 v45, v27
	v_mul_f32_e32 v6, 0.5, v43
	v_mov_b32_e32 v43, v41
	v_pk_mul_f32 v[120:121], v[44:45], s[46:47] op_sel_hi:[1,0]
	v_mul_f32_e32 v4, 0.5, v40
	v_pk_mov_b32 v[44:45], v[108:109], v[70:71] op_sel:[1,0]
	v_pk_mul_f32 v[40:41], v[42:43], s[44:45]
	v_cvt_f32_f16_sdwa v54, v20 dst_sel:DWORD dst_unused:UNUSED_PAD src0_sel:WORD_1
	v_pk_mul_f32 v[42:43], v[44:45], v[40:41] op_sel:[0,1] op_sel_hi:[1,0]
	v_cvt_f32_f16_e32 v55, v21
	v_cvt_f32_f16_sdwa v21, v21 dst_sel:DWORD dst_unused:UNUSED_PAD src0_sel:WORD_1
	v_cvt_f32_f16_e32 v20, v20
	v_pk_mul_f32 v[40:41], v[44:45], v[40:41]
	v_pk_add_f32 v[42:43], v[42:43], v[42:43] op_sel:[0,1] op_sel_hi:[0,1]
	v_pk_add_f32 v[104:105], v[4:5], v[42:43] op_sel_hi:[0,1] neg_hi:[0,1]
	s_nop 0
	v_pk_add_f32 v[40:41], v[40:41], v[40:41] op_sel:[0,1] op_sel_hi:[0,1] neg_lo:[0,1] neg_hi:[0,1]
	v_pk_add_f32 v[42:43], v[6:7], v[40:41] op_sel_hi:[0,1] neg_hi:[0,1]
	v_pk_mul_f32 v[40:41], v[42:43], v[20:21]
	v_pk_mul_f32 v[42:43], v[42:43], v[54:55]
	v_pk_fma_f32 v[40:41], v[104:105], v[54:55], v[40:41]
	v_pk_fma_f32 v[20:21], v[104:105], v[20:21], v[42:43] neg_lo:[0,0,1] neg_hi:[0,0,1]
	v_mov_b32_e32 v71, v109
	v_pk_add_f32 v[42:43], v[20:21], v[40:41] op_sel:[0,1] op_sel_hi:[1,0] neg_lo:[0,1]
	v_pk_add_f32 v[54:55], v[20:21], v[40:41] op_sel:[0,1] op_sel_hi:[1,0]
	v_pk_add_f32 v[20:21], v[40:41], v[20:21] op_sel:[1,0] op_sel_hi:[0,1] neg_lo:[0,1] neg_hi:[0,1]
	v_pk_mul_f32 v[42:43], v[42:43], 0.5 op_sel_hi:[1,0]
	v_mov_b32_e32 v55, v21
	v_mul_f32_e32 v4, v109, v42
	v_pk_fma_f32 v[104:105], v[44:45], v[42:43], v[4:5] op_sel_hi:[1,1,0] neg_lo:[1,0,0] neg_hi:[1,0,0]
	v_mul_f32_e32 v4, v109, v43
	v_pk_fma_f32 v[42:43], v[70:71], v[42:43], v[4:5] op_sel_hi:[1,1,0]
	v_sub_f32_e32 v6, v23, v103
	v_mov_b32_e32 v104, v42
	v_pk_fma_f32 v[40:41], v[54:55], 0.5, v[42:43] op_sel_hi:[1,0,1] neg_lo:[0,0,1] neg_hi:[0,0,1]
	v_pk_fma_f32 v[20:21], v[54:55], 0.5, v[104:105] op_sel_hi:[1,0,1]
	v_pk_add_f32 v[42:43], v[102:103], v[22:23]
	v_mov_b32_e32 v41, v21
	v_pk_mul_f32 v[128:129], v[40:41], s[46:47] op_sel_hi:[1,0]
	v_mul_f32_e32 v40, 0xbf0e39da, v83
	v_mov_b32_e32 v41, v22
	v_mul_f32_e32 v18, 0.5, v43
	v_pk_add_f32 v[22:23], v[40:41], v[46:47] neg_lo:[0,1] neg_hi:[0,1]
	v_mov_b32_e32 v47, v109
	v_pk_mul_f32 v[40:41], v[22:23], v[18:19]
	v_mov_b32_e32 v46, v22
	v_pk_fma_f32 v[44:45], v[44:45], v[40:41], v[40:41] op_sel:[0,1,0] op_sel_hi:[1,0,1]
	v_mov_b32_e32 v40, v41
	v_mov_b32_e32 v41, v18
	v_mul_f32_e32 v4, 0.5, v42
	v_pk_mul_f32 v[40:41], v[46:47], v[40:41]
	v_cvt_f32_f16_e32 v46, v10
	v_cvt_f32_f16_e32 v47, v11
	v_cvt_f32_f16_sdwa v11, v11 dst_sel:DWORD dst_unused:UNUSED_PAD src0_sel:WORD_1
	v_cvt_f32_f16_sdwa v10, v10 dst_sel:DWORD dst_unused:UNUSED_PAD src0_sel:WORD_1
	v_pk_fma_f32 v[70:71], v[54:55], 0.5, v[104:105] op_sel_hi:[1,0,1] neg_lo:[1,0,0] neg_hi:[1,0,0]
	v_mul_f32_e32 v6, 0.5, v6
	v_pk_add_f32 v[54:55], v[4:5], v[44:45]
	v_pk_add_f32 v[40:41], v[40:41], v[40:41] op_sel:[0,1] op_sel_hi:[0,1] neg_lo:[0,1] neg_hi:[0,1]
	v_fma_f32 v55, v42, 0.5, -v44
	v_pk_add_f32 v[42:43], v[6:7], v[40:41] op_sel_hi:[0,1] neg_hi:[0,1]
	v_pk_mul_f32 v[40:41], v[42:43], v[10:11]
	v_pk_mul_f32 v[42:43], v[42:43], v[46:47]
	v_pk_fma_f32 v[44:45], v[54:55], v[46:47], v[40:41] neg_lo:[0,0,1] neg_hi:[0,0,1]
	v_pk_fma_f32 v[40:41], v[54:55], v[46:47], v[40:41]
	v_pk_fma_f32 v[46:47], v[54:55], v[10:11], v[42:43]
	v_pk_fma_f32 v[10:11], v[54:55], v[10:11], v[42:43] neg_lo:[0,0,1] neg_hi:[0,0,1]
	v_pk_add_f32 v[42:43], v[44:45], v[40:41] op_sel:[0,1] op_sel_hi:[1,0]
	v_pk_add_f32 v[54:55], v[46:47], v[10:11] op_sel_hi:[0,1] neg_lo:[0,1] neg_hi:[0,1]
	v_pk_add_f32 v[40:41], v[44:45], v[40:41] op_sel_hi:[0,1] neg_lo:[0,1] neg_hi:[0,1]
	v_pk_add_f32 v[10:11], v[46:47], v[10:11] op_sel:[0,1] op_sel_hi:[1,0]
	v_mov_b32_e32 v43, v55
	v_mov_b32_e32 v11, v41
	v_pk_mul_f32 v[10:11], v[10:11], 0.5 op_sel_hi:[1,0]
	v_mov_b32_e32 v119, v98
	v_pk_mul_f32 v[40:41], v[108:109], v[10:11] op_sel:[1,1] op_sel_hi:[1,0]
	v_pk_fma_f32 v[76:77], v[76:77], 0.5, v[112:113] op_sel_hi:[1,0,1] neg_lo:[1,0,0] neg_hi:[1,0,0]
	v_pk_fma_f32 v[44:45], v[22:23], v[10:11], v[40:41] op_sel_hi:[0,1,1]
	v_pk_fma_f32 v[10:11], v[22:23], v[10:11], v[40:41] op_sel_hi:[0,1,1] neg_hi:[0,0,1]
	v_pk_fma_f32 v[22:23], v[42:43], 0.5, v[44:45] op_sel_hi:[1,0,1] neg_lo:[0,0,1] neg_hi:[0,0,1]
	v_pk_fma_f32 v[40:41], v[42:43], 0.5, v[10:11] op_sel_hi:[1,0,1]
	v_pk_fma_f32 v[54:55], v[42:43], 0.5, v[10:11] op_sel_hi:[1,0,1] neg_lo:[1,0,0] neg_hi:[1,0,0]
	v_pk_add_f32 v[10:11], v[100:101], v[14:15]
	v_pk_add_f32 v[14:15], v[14:15], v[100:101] neg_lo:[0,1] neg_hi:[0,1]
	v_mov_b32_e32 v23, v41
	v_mul_f32_e32 v6, 0.5, v15
	v_mov_b32_e32 v15, v11
	v_pk_mul_f32 v[150:151], v[22:23], s[46:47] op_sel_hi:[1,0]
	v_mul_f32_e32 v4, 0.5, v10
	v_pk_mov_b32 v[22:23], v[58:59], v[72:73] op_sel:[1,0]
	v_pk_mul_f32 v[10:11], v[14:15], s[44:45]
	v_cvt_f32_f16_sdwa v42, v8 dst_sel:DWORD dst_unused:UNUSED_PAD src0_sel:WORD_1
	v_pk_mul_f32 v[14:15], v[22:23], v[10:11] op_sel:[0,1] op_sel_hi:[1,0]
	v_cvt_f32_f16_e32 v43, v9
	v_cvt_f32_f16_sdwa v9, v9 dst_sel:DWORD dst_unused:UNUSED_PAD src0_sel:WORD_1
	v_cvt_f32_f16_e32 v8, v8
	v_pk_mul_f32 v[10:11], v[22:23], v[10:11]
	v_pk_add_f32 v[14:15], v[14:15], v[14:15] op_sel:[0,1] op_sel_hi:[0,1]
	v_pk_add_f32 v[44:45], v[4:5], v[14:15] op_sel_hi:[0,1] neg_hi:[0,1]
	s_nop 0
	v_pk_add_f32 v[10:11], v[10:11], v[10:11] op_sel:[0,1] op_sel_hi:[0,1] neg_lo:[0,1] neg_hi:[0,1]
	v_pk_add_f32 v[14:15], v[6:7], v[10:11] op_sel_hi:[0,1] neg_hi:[0,1]
	v_pk_mul_f32 v[10:11], v[14:15], v[8:9]
	v_pk_mul_f32 v[14:15], v[14:15], v[42:43]
	v_pk_fma_f32 v[10:11], v[44:45], v[42:43], v[10:11]
	v_pk_fma_f32 v[8:9], v[44:45], v[8:9], v[14:15] neg_lo:[0,0,1] neg_hi:[0,0,1]
	v_mov_b32_e32 v73, v59
	v_pk_add_f32 v[14:15], v[8:9], v[10:11] op_sel:[0,1] op_sel_hi:[1,0] neg_lo:[0,1]
	v_pk_add_f32 v[42:43], v[8:9], v[10:11] op_sel:[0,1] op_sel_hi:[1,0]
	v_pk_add_f32 v[8:9], v[10:11], v[8:9] op_sel:[1,0] op_sel_hi:[0,1] neg_lo:[0,1] neg_hi:[0,1]
	v_pk_mul_f32 v[14:15], v[14:15], 0.5 op_sel_hi:[1,0]
	v_mov_b32_e32 v43, v9
	v_mul_f32_e32 v4, v59, v14
	v_pk_fma_f32 v[44:45], v[22:23], v[14:15], v[4:5] op_sel_hi:[1,1,0] neg_lo:[1,0,0] neg_hi:[1,0,0]
	v_mul_f32_e32 v4, v59, v15
	v_pk_fma_f32 v[14:15], v[72:73], v[14:15], v[4:5] op_sel_hi:[1,1,0]
	v_sub_f32_e32 v6, v37, v99
	v_mov_b32_e32 v44, v14
	v_pk_fma_f32 v[8:9], v[42:43], 0.5, v[14:15] op_sel_hi:[1,0,1] neg_lo:[0,0,1] neg_hi:[0,0,1]
	v_pk_fma_f32 v[10:11], v[42:43], 0.5, v[44:45] op_sel_hi:[1,0,1]
	v_pk_add_f32 v[14:15], v[98:99], v[36:37]
	v_mov_b32_e32 v9, v11
	v_pk_mul_f32 v[168:169], v[8:9], s[46:47] op_sel_hi:[1,0]
	v_mul_f32_e32 v8, 0xbf7b14be, v83
	v_mov_b32_e32 v9, v36
	v_mul_f32_e32 v18, 0.5, v15
	v_pk_add_f32 v[8:9], v[8:9], v[118:119] neg_lo:[0,1] neg_hi:[0,1]
	v_pk_fma_f32 v[72:73], v[42:43], 0.5, v[44:45] op_sel_hi:[1,0,1] neg_lo:[1,0,0] neg_hi:[1,0,0]
	v_pk_mul_f32 v[36:37], v[8:9], v[18:19]
	v_pk_mov_b32 v[42:43], v[8:9], v[58:59] op_sel:[0,1]
	v_pk_fma_f32 v[22:23], v[22:23], v[36:37], v[36:37] op_sel:[0,1,0] op_sel_hi:[1,0,1]
	v_mov_b32_e32 v36, v37
	v_mov_b32_e32 v37, v18
	v_mul_f32_e32 v4, 0.5, v14
	v_pk_mul_f32 v[36:37], v[42:43], v[36:37]
	v_cvt_f32_f16_e32 v44, v2
	v_cvt_f32_f16_e32 v45, v3
	v_cvt_f32_f16_sdwa v3, v3 dst_sel:DWORD dst_unused:UNUSED_PAD src0_sel:WORD_1
	v_cvt_f32_f16_sdwa v2, v2 dst_sel:DWORD dst_unused:UNUSED_PAD src0_sel:WORD_1
	v_mul_f32_e32 v6, 0.5, v6
	v_pk_add_f32 v[46:47], v[4:5], v[22:23]
	v_fma_f32 v4, v14, 0.5, -v22
	v_pk_add_f32 v[22:23], v[36:37], v[36:37] op_sel:[0,1] op_sel_hi:[0,1] neg_lo:[0,1] neg_hi:[0,1]
	v_pk_add_f32 v[36:37], v[6:7], v[22:23] op_sel_hi:[0,1] neg_hi:[0,1]
	v_pk_mov_b32 v[14:15], v[46:47], v[4:5] op_sel:[0,0]
	v_pk_mul_f32 v[22:23], v[4:5], v[44:45] op_sel_hi:[0,1]
	v_pk_mul_f32 v[82:83], v[36:37], v[2:3]
	v_pk_mul_f32 v[46:47], v[46:47], v[2:3]
	v_pk_mul_f32 v[36:37], v[36:37], v[44:45]
	v_pk_fma_f32 v[98:99], v[14:15], v[44:45], v[82:83] neg_lo:[0,0,1] neg_hi:[0,0,1]
	v_pk_fma_f32 v[2:3], v[14:15], v[2:3], v[36:37] neg_lo:[0,0,1] neg_hi:[0,0,1]
	v_add_f32_e32 v4, v23, v83
	v_add_f32_e32 v6, v46, v36
	v_pk_add_f32 v[22:23], v[6:7], v[2:3] op_sel_hi:[0,1] neg_lo:[0,1] neg_hi:[0,1]
	v_pk_add_f32 v[36:37], v[98:99], v[4:5] op_sel_hi:[1,0] neg_lo:[0,1] neg_hi:[0,1]
	v_pk_add_f32 v[2:3], v[6:7], v[2:3] op_sel_hi:[0,1]
	v_mov_b32_e32 v37, v3
	v_pk_mul_f32 v[2:3], v[36:37], 0.5 op_sel_hi:[1,0]
	v_pk_add_f32 v[14:15], v[98:99], v[4:5] op_sel_hi:[1,0]
	v_mul_f32_e32 v4, v59, v3
	v_pk_fma_f32 v[36:37], v[42:43], v[2:3], v[4:5] op_sel_hi:[1,1,0] neg_lo:[0,0,1] neg_hi:[0,0,1]
	v_pk_mov_b32 v[42:43], v[58:59], v[8:9] op_sel:[1,0]
	v_mul_f32_e32 v4, v8, v3
	v_pk_fma_f32 v[2:3], v[42:43], v[2:3], v[4:5] op_sel_hi:[1,1,0]
	v_mov_b32_e32 v15, v23
	v_pk_fma_f32 v[8:9], v[14:15], 0.5, v[2:3] op_sel_hi:[1,0,1] neg_lo:[0,0,1] neg_hi:[0,0,1]
	v_pk_fma_f32 v[42:43], v[14:15], 0.5, v[36:37] op_sel_hi:[1,0,0]
	v_pk_fma_f32 v[2:3], v[14:15], 0.5, v[2:3] op_sel_hi:[1,0,1]
	v_mov_b32_e32 v9, v43
	v_pk_fma_f32 v[58:59], v[22:23], 0.5, v[36:37] op_sel_hi:[1,0,0] neg_lo:[1,0,0] neg_hi:[1,0,0]
	v_pk_mul_f32 v[144:145], v[8:9], s[46:47] op_sel_hi:[1,0]
	v_mov_b32_e32 v58, v2
	v_mov_b32_e32 v72, v10
	v_mov_b32_e32 v54, v40
	v_mov_b32_e32 v70, v20
	v_mov_b32_e32 v56, v26
	v_mov_b32_e32 v76, v38
	v_mov_b32_e32 v52, v34
	v_mov_b32_e32 v74, v86
	v_mov_b32_e32 v48, v84
	v_mov_b32_e32 v50, v60
	v_mov_b32_e32 v28, v66
	v_mov_b32_e32 v32, v96
	v_mov_b32_e32 v12, v88
	v_mov_b32_e32 v16, v92
	v_mov_b32_e32 v4, v138
	v_mov_b32_e32 v6, v122
.LBB0_536:
	s_andn2_saveexec_b64 s[0:1], s[0:1]
	s_cbranch_execz .LBB0_538
	v_pk_add_f32 v[4:5], v[98:99], v[196:197]
	v_pk_add_f32 v[6:7], v[98:99], v[196:197] neg_lo:[0,1] neg_hi:[0,1]
	v_mul_f32_e32 v4, 0.5, v4
	v_mul_f32_e32 v12, 0.5, v7
	v_mov_b32_e32 v7, v5
	v_pk_mul_f32 v[6:7], v[6:7], s[44:45]
	v_pk_mov_b32 v[16:17], v[198:199], v[160:161] op_sel:[1,0]
	v_pk_mul_f32 v[24:25], v[190:191], v[6:7] op_sel:[0,1] op_sel_hi:[1,0]
	v_pk_mul_f32 v[6:7], v[190:191], v[6:7]
	v_pk_add_f32 v[24:25], v[24:25], v[24:25] op_sel:[0,1] op_sel_hi:[0,1]
	v_pk_add_f32 v[28:29], v[4:5], v[24:25] op_sel_hi:[0,1] neg_hi:[0,1]
	v_pk_add_f32 v[4:5], v[6:7], v[6:7] op_sel:[0,1] op_sel_hi:[0,1] neg_lo:[0,1] neg_hi:[0,1]
	v_pk_add_f32 v[6:7], v[12:13], v[4:5] op_sel_hi:[0,1] neg_hi:[0,1]
	v_pk_mul_f32 v[4:5], v[6:7], v[194:195]
	v_pk_mul_f32 v[6:7], v[6:7], v[192:193]
	v_pk_fma_f32 v[4:5], v[28:29], v[192:193], v[4:5]
	v_pk_fma_f32 v[6:7], v[28:29], v[194:195], v[6:7] neg_lo:[0,0,1] neg_hi:[0,0,1]
	s_mov_b32 s66, s19
	v_pk_add_f32 v[12:13], v[6:7], v[4:5] op_sel:[0,1] op_sel_hi:[1,0] neg_lo:[0,1]
	v_pk_add_f32 v[24:25], v[6:7], v[4:5] op_sel:[0,1] op_sel_hi:[1,0]
	v_pk_add_f32 v[4:5], v[4:5], v[6:7] op_sel:[1,0] op_sel_hi:[0,1] neg_lo:[0,1] neg_hi:[0,1]
	s_nop 0
	v_pk_mul_f32 v[12:13], v[12:13], 0.5 op_sel_hi:[1,0]
	v_mov_b32_e32 v25, v5
	v_mul_f32_e32 v28, v191, v13
	v_mul_f32_e32 v30, v160, v13
	v_pk_fma_f32 v[28:29], v[190:191], v[12:13], v[28:29] op_sel_hi:[1,1,0] neg_lo:[0,0,1] neg_hi:[0,0,1]
	v_pk_fma_f32 v[12:13], v[16:17], v[12:13], v[30:31] op_sel_hi:[1,1,0]
	v_mov_b32_e32 v7, v28
	v_mov_b32_e32 v6, v12
	v_pk_fma_f32 v[58:59], v[24:25], 0.5, v[12:13] op_sel_hi:[1,0,1] neg_lo:[0,0,1] neg_hi:[0,0,1]
	v_pk_fma_f32 v[98:99], v[24:25], 0.5, v[6:7] op_sel_hi:[1,0,1]
	v_pk_fma_f32 v[6:7], v[24:25], 0.5, v[12:13] op_sel_hi:[1,0,1]
	v_pk_fma_f32 v[160:161], v[4:5], 0.5, v[28:29] op_sel_hi:[1,0,0] neg_lo:[1,0,0] neg_hi:[1,0,0]
	v_pk_add_f32 v[4:5], v[100:101], v[188:189]
	v_pk_add_f32 v[12:13], v[100:101], v[188:189] neg_lo:[0,1] neg_hi:[0,1]
	v_pk_mov_b32 v[24:25], v[82:83], v[82:83] op_sel:[1,0]
	v_mul_f32_e32 v16, 0.5, v13
	v_pk_add_f32 v[28:29], v[186:187], v[24:25] neg_lo:[0,1] neg_hi:[0,1]
	v_pk_add_f32 v[30:31], v[186:187], v[24:25]
	v_mov_b32_e32 v13, v5
	v_pk_mov_b32 v[32:33], v[28:29], v[30:31] op_sel:[1,0]
	v_pk_mul_f32 v[12:13], v[12:13], s[44:45]
	v_mul_f32_e32 v4, 0.5, v4
	v_pk_mul_f32 v[48:49], v[32:33], v[12:13] op_sel:[0,1] op_sel_hi:[1,0]
	v_pk_mul_f32 v[12:13], v[32:33], v[12:13]
	v_pk_add_f32 v[48:49], v[48:49], v[48:49] op_sel:[0,1] op_sel_hi:[0,1]
	v_pk_add_f32 v[50:51], v[4:5], v[48:49] op_sel_hi:[0,1] neg_hi:[0,1]
	v_pk_add_f32 v[4:5], v[12:13], v[12:13] op_sel:[0,1] op_sel_hi:[0,1] neg_lo:[0,1] neg_hi:[0,1]
	v_pk_add_f32 v[12:13], v[16:17], v[4:5] op_sel_hi:[0,1] neg_hi:[0,1]
	v_pk_mul_f32 v[4:5], v[12:13], v[184:185]
	v_pk_mul_f32 v[12:13], v[12:13], v[170:171]
	v_pk_fma_f32 v[4:5], v[50:51], v[170:171], v[4:5]
	v_pk_fma_f32 v[12:13], v[50:51], v[184:185], v[12:13] neg_lo:[0,0,1] neg_hi:[0,0,1]
	v_mov_b32_e32 v31, v29
	v_pk_add_f32 v[16:17], v[12:13], v[4:5] op_sel:[0,1] op_sel_hi:[1,0] neg_lo:[0,1]
	v_pk_add_f32 v[48:49], v[12:13], v[4:5] op_sel:[0,1] op_sel_hi:[1,0]
	v_pk_add_f32 v[12:13], v[4:5], v[12:13] op_sel:[1,0] op_sel_hi:[0,1] neg_lo:[0,1] neg_hi:[0,1]
	v_pk_mul_f32 v[16:17], v[16:17], 0.5 op_sel_hi:[1,0]
	v_mov_b32_e32 v49, v13
	v_mul_f32_e32 v28, v30, v17
	v_pk_fma_f32 v[32:33], v[32:33], v[16:17], v[28:29] op_sel_hi:[1,1,0] neg_lo:[0,0,1] neg_hi:[0,0,1]
	v_mul_f32_e32 v28, v29, v17
	v_pk_fma_f32 v[16:17], v[30:31], v[16:17], v[28:29] op_sel_hi:[1,1,0]
	v_mov_b32_e32 v5, v32
	v_mov_b32_e32 v4, v16
	v_pk_fma_f32 v[72:73], v[48:49], 0.5, v[16:17] op_sel_hi:[1,0,1] neg_lo:[0,0,1] neg_hi:[0,0,1]
	v_pk_fma_f32 v[100:101], v[48:49], 0.5, v[4:5] op_sel_hi:[1,0,1]
	v_pk_fma_f32 v[4:5], v[48:49], 0.5, v[16:17] op_sel_hi:[1,0,1]
	v_pk_fma_f32 v[170:171], v[12:13], 0.5, v[32:33] op_sel_hi:[1,0,0] neg_lo:[1,0,0] neg_hi:[1,0,0]
	v_pk_mul_f32 v[12:13], v[24:25], s[36:37]
	v_pk_add_f32 v[16:17], v[102:103], v[182:183]
	v_pk_add_f32 v[24:25], v[102:103], v[182:183] neg_lo:[0,1] neg_hi:[0,1]
	v_pk_add_f32 v[30:31], v[18:19], v[12:13] op_sel:[0,1] op_sel_hi:[0,1] neg_lo:[0,1] neg_hi:[0,1]
	v_mul_f32_e32 v28, 0.5, v25
	v_pk_add_f32 v[32:33], v[18:19], v[12:13] op_sel:[0,1] op_sel_hi:[0,1]
	v_mov_b32_e32 v25, v17
	v_pk_mov_b32 v[48:49], v[30:31], v[32:33] op_sel:[0,1]
	v_pk_mul_f32 v[24:25], v[24:25], s[44:45]
	v_mul_f32_e32 v16, 0.5, v16
	v_pk_mul_f32 v[52:53], v[48:49], v[24:25] op_sel:[0,1] op_sel_hi:[1,0]
	v_pk_mul_f32 v[24:25], v[48:49], v[24:25]
	v_pk_add_f32 v[52:53], v[52:53], v[52:53] op_sel:[0,1] op_sel_hi:[0,1]
	v_pk_add_f32 v[54:55], v[16:17], v[52:53] op_sel_hi:[0,1] neg_hi:[0,1]
	v_pk_add_f32 v[16:17], v[24:25], v[24:25] op_sel:[0,1] op_sel_hi:[0,1] neg_lo:[0,1] neg_hi:[0,1]
	v_pk_add_f32 v[24:25], v[28:29], v[16:17] op_sel_hi:[0,1] neg_hi:[0,1]
	v_pk_mul_f32 v[16:17], v[24:25], v[180:181]
	v_pk_mul_f32 v[24:25], v[24:25], v[172:173]
	v_pk_fma_f32 v[16:17], v[54:55], v[172:173], v[16:17]
	v_pk_fma_f32 v[24:25], v[54:55], v[180:181], v[24:25] neg_lo:[0,0,1] neg_hi:[0,0,1]
	v_pk_mov_b32 v[50:51], v[32:33], v[30:31] op_sel:[1,0]
	v_pk_add_f32 v[28:29], v[24:25], v[16:17] op_sel:[0,1] op_sel_hi:[1,0] neg_lo:[0,1]
	v_pk_add_f32 v[52:53], v[24:25], v[16:17] op_sel:[0,1] op_sel_hi:[1,0]
	v_pk_add_f32 v[24:25], v[16:17], v[24:25] op_sel:[1,0] op_sel_hi:[0,1] neg_lo:[0,1] neg_hi:[0,1]
	v_pk_mul_f32 v[28:29], v[28:29], 0.5 op_sel_hi:[1,0]
	v_mov_b32_e32 v53, v25
	v_mul_f32_e32 v18, v33, v29
	v_pk_fma_f32 v[32:33], v[48:49], v[28:29], v[18:19] op_sel_hi:[1,1,0] neg_lo:[0,0,1] neg_hi:[0,0,1]
	v_mul_f32_e32 v18, v30, v29
	v_pk_fma_f32 v[28:29], v[50:51], v[28:29], v[18:19] op_sel_hi:[1,1,0]
	v_pk_fma_f32 v[172:173], v[24:25], 0.5, v[32:33] op_sel_hi:[1,0,0] neg_lo:[1,0,0] neg_hi:[1,0,0]
	v_pk_add_f32 v[24:25], v[106:107], v[176:177]
	v_pk_mov_b32 v[50:51], v[12:13], v[106:107] op_sel:[0,0]
	v_pk_mov_b32 v[12:13], v[12:13], v[176:177] op_sel:[1,0]
	v_mul_f32_e32 v18, 0.5, v25
	v_pk_add_f32 v[12:13], v[50:51], v[12:13] neg_lo:[0,1] neg_hi:[0,1]
	v_pk_mov_b32 v[16:17], v[28:29], v[32:33] op_sel:[0,0]
	v_pk_mul_f32 v[50:51], v[12:13], v[18:19]
	v_pk_fma_f32 v[54:55], v[52:53], 0.5, v[28:29] op_sel_hi:[1,0,1] neg_lo:[0,0,1] neg_hi:[0,0,1]
	v_pk_fma_f32 v[102:103], v[52:53], 0.5, v[16:17] op_sel_hi:[1,0,1]
	v_pk_fma_f32 v[16:17], v[52:53], 0.5, v[28:29] op_sel_hi:[1,0,1]
	v_mul_f32_e32 v28, 0.5, v24
	v_pk_fma_f32 v[48:49], v[48:49], v[50:51], v[50:51] op_sel:[0,1,0] op_sel_hi:[1,0,1]
	v_mov_b32_e32 v13, v30
	v_mov_b32_e32 v50, v51
	v_mov_b32_e32 v51, v18
	v_sub_f32_e32 v5, v107, v177
	v_pk_mul_f32 v[50:51], v[12:13], v[50:51]
	v_pk_add_f32 v[28:29], v[28:29], v[48:49]
	v_mul_f32_e32 v32, 0.5, v5
	v_fma_f32 v29, v24, 0.5, -v48
	v_pk_add_f32 v[24:25], v[50:51], v[50:51] op_sel:[0,1] op_sel_hi:[0,1] neg_lo:[0,1] neg_hi:[0,1]
	v_pk_add_f32 v[48:49], v[32:33], v[24:25] op_sel_hi:[0,1] neg_hi:[0,1]
	v_pk_mul_f32 v[24:25], v[48:49], v[178:179]
	v_pk_mul_f32 v[32:33], v[48:49], v[174:175]
	v_pk_fma_f32 v[24:25], v[28:29], v[174:175], v[24:25]
	v_pk_fma_f32 v[28:29], v[28:29], v[178:179], v[32:33] neg_lo:[0,0,1] neg_hi:[0,0,1]
	v_mov_b32_e32 v31, v12
	v_pk_add_f32 v[32:33], v[28:29], v[24:25] op_sel:[0,1] op_sel_hi:[1,0] neg_lo:[0,1]
	v_pk_add_f32 v[48:49], v[28:29], v[24:25] op_sel:[0,1] op_sel_hi:[1,0]
	v_pk_add_f32 v[24:25], v[24:25], v[28:29] op_sel:[1,0] op_sel_hi:[0,1] neg_lo:[0,1] neg_hi:[0,1]
	v_pk_mul_f32 v[32:33], v[32:33], 0.5 op_sel_hi:[1,0]
	v_mov_b32_e32 v49, v25
	v_mul_f32_e32 v18, v30, v33
	v_pk_fma_f32 v[50:51], v[12:13], v[32:33], v[18:19] op_sel_hi:[1,1,0] neg_lo:[0,0,1] neg_hi:[0,0,1]
	v_mul_f32_e32 v12, v12, v33
	v_pk_fma_f32 v[12:13], v[30:31], v[32:33], v[12:13] op_sel_hi:[1,1,0]
	v_mov_b32_e32 v29, v50
	v_mov_b32_e32 v28, v12
	s_mov_b32 s67, s16
	v_pk_fma_f32 v[106:107], v[48:49], 0.5, v[28:29] op_sel_hi:[1,0,1]
	v_pk_fma_f32 v[174:175], v[24:25], 0.5, v[50:51] op_sel_hi:[1,0,0] neg_lo:[1,0,0] neg_hi:[1,0,0]
	v_mov_b32_e32 v18, v83
	s_mov_b32 s17, s19
	v_pk_mul_f32 v[24:25], v[82:83], s[66:67] op_sel_hi:[0,1]
	v_pk_add_f32 v[28:29], v[104:105], v[162:163]
	v_pk_add_f32 v[30:31], v[104:105], v[162:163] neg_lo:[0,1] neg_hi:[0,1]
	v_pk_fma_f32 v[70:71], v[48:49], 0.5, v[12:13] op_sel_hi:[1,0,1] neg_lo:[0,0,1] neg_hi:[0,0,1]
	v_pk_fma_f32 v[12:13], v[48:49], 0.5, v[12:13] op_sel_hi:[1,0,1]
	v_mul_f32_e32 v32, 0.5, v31
	v_pk_fma_f32 v[48:49], v[18:19], s[16:17], v[24:25] op_sel_hi:[0,1,1] neg_lo:[0,0,1] neg_hi:[0,0,1]
	v_pk_fma_f32 v[50:51], v[18:19], s[16:17], v[24:25] op_sel_hi:[0,1,1]
	v_mov_b32_e32 v31, v29
	v_pk_mov_b32 v[52:53], v[48:49], v[50:51] op_sel:[0,1]
	v_pk_mul_f32 v[30:31], v[30:31], s[44:45]
	v_mul_f32_e32 v28, 0.5, v28
	v_pk_mul_f32 v[62:63], v[52:53], v[30:31] op_sel:[0,1] op_sel_hi:[1,0]
	v_pk_mul_f32 v[30:31], v[52:53], v[30:31]
	v_pk_add_f32 v[62:63], v[62:63], v[62:63] op_sel:[0,1] op_sel_hi:[0,1]
	v_pk_add_f32 v[64:65], v[28:29], v[62:63] op_sel_hi:[0,1] neg_hi:[0,1]
	v_pk_add_f32 v[28:29], v[30:31], v[30:31] op_sel:[0,1] op_sel_hi:[0,1] neg_lo:[0,1] neg_hi:[0,1]
	v_pk_add_f32 v[30:31], v[32:33], v[28:29] op_sel_hi:[0,1] neg_hi:[0,1]
	v_pk_mul_f32 v[28:29], v[30:31], v[166:167]
	v_pk_mul_f32 v[30:31], v[30:31], v[164:165]
	v_pk_fma_f32 v[28:29], v[64:65], v[164:165], v[28:29]
	v_pk_fma_f32 v[30:31], v[64:65], v[166:167], v[30:31] neg_lo:[0,0,1] neg_hi:[0,0,1]
	v_pk_mov_b32 v[56:57], v[50:51], v[48:49] op_sel:[1,0]
	v_pk_add_f32 v[32:33], v[30:31], v[28:29] op_sel:[0,1] op_sel_hi:[1,0] neg_lo:[0,1]
	v_pk_add_f32 v[62:63], v[30:31], v[28:29] op_sel:[0,1] op_sel_hi:[1,0]
	v_pk_add_f32 v[28:29], v[28:29], v[30:31] op_sel:[1,0] op_sel_hi:[0,1] neg_lo:[0,1] neg_hi:[0,1]
	v_pk_mul_f32 v[32:33], v[32:33], 0.5 op_sel_hi:[1,0]
	v_mov_b32_e32 v63, v29
	v_mul_f32_e32 v18, v51, v33
	v_pk_fma_f32 v[52:53], v[52:53], v[32:33], v[18:19] op_sel_hi:[1,1,0] neg_lo:[0,0,1] neg_hi:[0,0,1]
	v_mul_f32_e32 v18, v48, v33
	v_pk_fma_f32 v[32:33], v[56:57], v[32:33], v[18:19] op_sel_hi:[1,1,0]
	v_mov_b32_e32 v31, v52
	v_mov_b32_e32 v30, v32
	v_pk_fma_f32 v[56:57], v[62:63], 0.5, v[32:33] op_sel_hi:[1,0,1] neg_lo:[0,0,1] neg_hi:[0,0,1]
	v_pk_fma_f32 v[82:83], v[62:63], 0.5, v[30:31] op_sel_hi:[1,0,1]
	v_pk_fma_f32 v[32:33], v[62:63], 0.5, v[32:33] op_sel_hi:[1,0,1]
	v_pk_fma_f32 v[104:105], v[28:29], 0.5, v[52:53] op_sel_hi:[1,0,0] neg_lo:[1,0,0] neg_hi:[1,0,0]
	v_pk_add_f32 v[28:29], v[108:109], v[152:153]
	v_mov_b32_e32 v159, v108
	v_pk_mov_b32 v[62:63], v[24:25], v[152:153] op_sel:[1,0]
	v_mul_f32_e32 v18, 0.5, v29
	v_pk_add_f32 v[62:63], v[158:159], v[62:63] neg_lo:[0,1] neg_hi:[0,1]
	v_sub_f32_e32 v5, v109, v153
	v_pk_mul_f32 v[64:65], v[62:63], v[18:19]
	v_mov_b32_e32 v63, v48
	v_pk_fma_f32 v[68:69], v[48:49], v[64:65], v[64:65] op_sel:[0,1,0] op_sel_hi:[1,0,1]
	v_mov_b32_e32 v64, v65
	v_mov_b32_e32 v65, v18
	v_pk_mul_f32 v[64:65], v[62:63], v[64:65]
	v_mul_f32_e32 v30, 0.5, v28
	v_mul_f32_e32 v52, 0.5, v5
	v_pk_add_f32 v[64:65], v[64:65], v[64:65] op_sel:[0,1] op_sel_hi:[0,1] neg_lo:[0,1] neg_hi:[0,1]
	v_pk_add_f32 v[30:31], v[30:31], v[68:69]
	v_fma_f32 v18, v28, 0.5, -v68
	v_pk_add_f32 v[68:69], v[52:53], v[64:65] op_sel_hi:[0,1] neg_hi:[0,1]
	v_pk_mov_b32 v[28:29], v[30:31], v[18:19] op_sel:[0,0]
	v_pk_mul_f32 v[52:53], v[18:19], v[154:155] op_sel_hi:[0,1]
	v_pk_mul_f32 v[64:65], v[68:69], v[156:157]
	v_pk_mul_f32 v[30:31], v[30:31], v[156:157]
	v_pk_mul_f32 v[68:69], v[68:69], v[154:155]
	v_pk_fma_f32 v[74:75], v[28:29], v[154:155], v[64:65] neg_lo:[0,0,1] neg_hi:[0,0,1]
	v_pk_fma_f32 v[28:29], v[28:29], v[156:157], v[68:69] neg_lo:[0,0,1] neg_hi:[0,0,1]
	v_add_f32_e32 v18, v53, v65
	v_add_f32_e32 v30, v30, v68
	v_pk_add_f32 v[64:65], v[30:31], v[28:29] op_sel_hi:[0,1] neg_lo:[0,1] neg_hi:[0,1]
	v_pk_add_f32 v[68:69], v[74:75], v[18:19] op_sel_hi:[1,0] neg_lo:[0,1] neg_hi:[0,1]
	v_pk_add_f32 v[28:29], v[30:31], v[28:29] op_sel_hi:[0,1]
	v_mov_b32_e32 v69, v29
	v_pk_mul_f32 v[28:29], v[68:69], 0.5 op_sel_hi:[1,0]
	v_pk_add_f32 v[52:53], v[74:75], v[18:19] op_sel_hi:[1,0]
	v_mul_f32_e32 v18, v48, v29
	v_pk_fma_f32 v[30:31], v[62:63], v[28:29], v[18:19] op_sel_hi:[1,1,0] neg_lo:[0,0,1] neg_hi:[0,0,1]
	v_pk_mov_b32 v[68:69], v[48:49], v[62:63] op_sel:[0,0]
	v_mul_f32_e32 v18, v62, v29
	v_pk_fma_f32 v[28:29], v[68:69], v[28:29], v[18:19] op_sel_hi:[1,1,0]
	v_mov_b32_e32 v53, v65
	v_pk_mov_b32 v[62:63], v[28:29], v[30:31] op_sel:[0,0]
	v_pk_fma_f32 v[76:77], v[52:53], 0.5, v[28:29] op_sel_hi:[1,0,1] neg_lo:[0,0,1] neg_hi:[0,0,1]
	v_pk_fma_f32 v[108:109], v[52:53], 0.5, v[62:63] op_sel_hi:[1,0,1]
	v_pk_fma_f32 v[28:29], v[52:53], 0.5, v[28:29] op_sel_hi:[1,0,1]
	v_pk_fma_f32 v[152:153], v[64:65], 0.5, v[30:31] op_sel_hi:[1,0,0] neg_lo:[1,0,0] neg_hi:[1,0,0]
	v_pk_add_f32 v[30:31], v[134:135], v[110:111]
	v_pk_add_f32 v[52:53], v[110:111], v[134:135] neg_lo:[0,1] neg_hi:[0,1]
	v_mul_f32_e32 v18, 0.5, v30
	v_mul_f32_e32 v30, 0.5, v53
	v_mov_b32_e32 v53, v31
	v_pk_mov_b32 v[62:63], v[48:49], v[50:51] op_sel:[1,0]
	v_pk_mul_f32 v[52:53], v[52:53], s[44:45]
	v_mov_b32_e32 v51, v49
	v_pk_mul_f32 v[64:65], v[62:63], v[52:53] op_sel:[0,1] op_sel_hi:[1,0]
	v_pk_mul_f32 v[52:53], v[62:63], v[52:53]
	v_pk_add_f32 v[64:65], v[64:65], v[64:65] op_sel:[0,1] op_sel_hi:[0,1]
	v_pk_add_f32 v[68:69], v[18:19], v[64:65] op_sel_hi:[0,1] neg_hi:[0,1]
	v_pk_add_f32 v[52:53], v[52:53], v[52:53] op_sel:[0,1] op_sel_hi:[0,1] neg_lo:[0,1] neg_hi:[0,1]
	v_pk_add_f32 v[64:65], v[30:31], v[52:53] op_sel_hi:[0,1] neg_hi:[0,1]
	v_pk_mul_f32 v[30:31], v[64:65], v[142:143]
	v_pk_mul_f32 v[52:53], v[64:65], v[140:141]
	v_pk_fma_f32 v[30:31], v[68:69], v[140:141], v[30:31]
	v_pk_fma_f32 v[52:53], v[68:69], v[142:143], v[52:53] neg_lo:[0,0,1] neg_hi:[0,0,1]
	v_mov_b32_e32 v133, v112
	v_pk_add_f32 v[64:65], v[52:53], v[30:31] op_sel:[0,1] op_sel_hi:[1,0] neg_lo:[0,1]
	v_pk_add_f32 v[68:69], v[52:53], v[30:31] op_sel:[0,1] op_sel_hi:[1,0]
	v_pk_add_f32 v[30:31], v[30:31], v[52:53] op_sel:[1,0] op_sel_hi:[0,1] neg_lo:[0,1] neg_hi:[0,1]
	v_pk_mul_f32 v[64:65], v[64:65], 0.5 op_sel_hi:[1,0]
	v_mov_b32_e32 v69, v31
	v_mul_f32_e32 v18, v50, v65
	v_pk_fma_f32 v[74:75], v[62:63], v[64:65], v[18:19] op_sel_hi:[1,1,0] neg_lo:[0,0,1] neg_hi:[0,0,1]
	v_mul_f32_e32 v18, v49, v65
	v_pk_fma_f32 v[134:135], v[30:31], 0.5, v[74:75] op_sel_hi:[1,0,0] neg_lo:[1,0,0] neg_hi:[1,0,0]
	v_pk_add_f32 v[30:31], v[118:119], v[112:113]
	v_mov_b32_e32 v25, v118
	v_pk_fma_f32 v[50:51], v[50:51], v[64:65], v[18:19] op_sel_hi:[1,1,0]
	v_mul_f32_e32 v18, 0.5, v31
	v_pk_add_f32 v[24:25], v[132:133], v[24:25] neg_lo:[0,1] neg_hi:[0,1]
	v_mov_b32_e32 v65, v74
	v_pk_mul_f32 v[74:75], v[24:25], v[18:19]
	v_mov_b32_e32 v64, v50
	v_pk_fma_f32 v[62:63], v[62:63], v[74:75], v[74:75] op_sel:[0,1,0] op_sel_hi:[1,0,1]
	v_pk_mov_b32 v[78:79], v[24:25], v[48:49] op_sel:[0,1]
	v_mov_b32_e32 v74, v75
	v_mov_b32_e32 v75, v18
	v_pk_fma_f32 v[110:111], v[68:69], 0.5, v[64:65] op_sel_hi:[1,0,1]
	v_mul_f32_e32 v64, 0.5, v30
	v_sub_f32_e32 v5, v113, v119
	v_pk_mul_f32 v[74:75], v[78:79], v[74:75]
	v_pk_fma_f32 v[52:53], v[68:69], 0.5, v[50:51] op_sel_hi:[1,0,1] neg_lo:[0,0,1] neg_hi:[0,0,1]
	v_pk_fma_f32 v[50:51], v[68:69], 0.5, v[50:51] op_sel_hi:[1,0,1]
	v_mul_f32_e32 v68, 0.5, v5
	v_pk_add_f32 v[64:65], v[64:65], v[62:63]
	v_fma_f32 v18, v30, 0.5, -v62
	v_pk_add_f32 v[62:63], v[74:75], v[74:75] op_sel:[0,1] op_sel_hi:[0,1] neg_lo:[0,1] neg_hi:[0,1]
	v_pk_add_f32 v[74:75], v[68:69], v[62:63] op_sel_hi:[0,1] neg_hi:[0,1]
	v_pk_mov_b32 v[30:31], v[64:65], v[18:19] op_sel:[0,0]
	v_pk_mul_f32 v[62:63], v[18:19], v[124:125] op_sel_hi:[0,1]
	v_pk_mul_f32 v[68:69], v[74:75], v[126:127]
	v_pk_mul_f32 v[64:65], v[64:65], v[126:127]
	v_pk_mul_f32 v[74:75], v[74:75], v[124:125]
	v_pk_fma_f32 v[80:81], v[30:31], v[124:125], v[68:69] neg_lo:[0,0,1] neg_hi:[0,0,1]
	v_pk_fma_f32 v[30:31], v[30:31], v[126:127], v[74:75] neg_lo:[0,0,1] neg_hi:[0,0,1]
	v_add_f32_e32 v18, v63, v69
	v_add_f32_e32 v64, v64, v74
	v_pk_add_f32 v[68:69], v[64:65], v[30:31] op_sel_hi:[0,1] neg_lo:[0,1] neg_hi:[0,1]
	v_pk_add_f32 v[74:75], v[80:81], v[18:19] op_sel_hi:[1,0] neg_lo:[0,1] neg_hi:[0,1]
	v_pk_add_f32 v[30:31], v[64:65], v[30:31] op_sel_hi:[0,1]
	v_mov_b32_e32 v75, v31
	v_pk_mul_f32 v[30:31], v[74:75], 0.5 op_sel_hi:[1,0]
	v_pk_add_f32 v[62:63], v[80:81], v[18:19] op_sel_hi:[1,0]
	v_mul_f32_e32 v18, v49, v31
	v_pk_fma_f32 v[64:65], v[78:79], v[30:31], v[18:19] op_sel_hi:[1,1,0] neg_lo:[0,0,1] neg_hi:[0,0,1]
	v_pk_mov_b32 v[48:49], v[48:49], v[24:25] op_sel:[1,0]
	v_mul_f32_e32 v18, v24, v31
	v_pk_fma_f32 v[24:25], v[48:49], v[30:31], v[18:19] op_sel_hi:[1,1,0]
	v_mov_b32_e32 v63, v69
	v_pk_mov_b32 v[30:31], v[24:25], v[64:65] op_sel:[0,0]
	v_pk_fma_f32 v[74:75], v[62:63], 0.5, v[24:25] op_sel_hi:[1,0,1] neg_lo:[0,0,1] neg_hi:[0,0,1]
	v_pk_fma_f32 v[112:113], v[62:63], 0.5, v[30:31] op_sel_hi:[1,0,1]
	v_pk_fma_f32 v[48:49], v[62:63], 0.5, v[24:25] op_sel_hi:[1,0,1]
	v_mov_b32_e32 v62, v115
	v_mov_b32_e32 v18, v117
	v_mov_b32_e32 v30, v117
	v_pk_mul_f32 v[62:63], v[138:139], v[62:63] op_sel_hi:[1,0]
	v_pk_fma_f32 v[118:119], v[68:69], 0.5, v[64:65] op_sel_hi:[1,0,0] neg_lo:[1,0,0] neg_hi:[1,0,0]
	v_pk_fma_f32 v[64:65], v[138:139], v[18:19], v[62:63] op_sel:[1,0,0] op_sel_hi:[0,1,1]
	v_pk_fma_f32 v[30:31], v[138:139], v[30:31], v[62:63] op_sel:[1,0,0] op_sel_hi:[0,0,1] neg_lo:[0,0,1] neg_hi:[0,0,1]
	v_pk_add_f32 v[62:63], v[86:87], v[36:37]
	v_pk_add_f32 v[36:37], v[86:87], v[36:37] neg_lo:[0,1] neg_hi:[0,1]
	v_mul_f32_e32 v18, 0.5, v62
	v_mul_f32_e32 v62, 0.5, v37
	v_mov_b32_e32 v37, v63
	v_mov_b32_e32 v65, v31
	v_pk_mul_f32 v[36:37], v[36:37], s[44:45]
	s_mov_b32 s68, s11
	s_mov_b32 s69, s8
	s_mov_b32 s9, s11
	v_cvt_f32_f16_sdwa v69, v47 dst_sel:DWORD dst_unused:UNUSED_PAD src0_sel:WORD_1
	v_cvt_f32_f16_sdwa v78, v46 dst_sel:DWORD dst_unused:UNUSED_PAD src0_sel:WORD_1
	v_pk_mul_f32 v[30:31], v[64:65], s[46:47]
	v_pk_mul_f32 v[64:65], v[36:37], s[68:69]
	v_pk_mul_f32 v[36:37], v[36:37], s[8:9]
	v_cvt_f32_f16_e32 v68, v46
	v_cvt_f32_f16_e32 v79, v47
	v_pk_add_f32 v[64:65], v[64:65], v[64:65] op_sel:[1,0] op_sel_hi:[1,0]
	v_pk_add_f32 v[36:37], v[36:37], v[36:37] op_sel:[0,1] op_sel_hi:[0,1] neg_lo:[0,1] neg_hi:[0,1]
	v_pk_add_f32 v[80:81], v[18:19], v[64:65] op_sel_hi:[0,1]
	v_pk_add_f32 v[90:91], v[62:63], v[36:37] op_sel_hi:[0,1]
	v_pk_add_f32 v[36:37], v[62:63], v[36:37] op_sel_hi:[0,1] neg_lo:[0,1] neg_hi:[0,1]
	v_pk_mov_b32 v[46:47], v[68:69], v[78:79] op_sel:[1,0]
	v_pk_add_f32 v[64:65], v[18:19], v[64:65] op_sel_hi:[0,1] neg_lo:[0,1] neg_hi:[0,1]
	v_pk_mov_b32 v[62:63], v[90:91], v[36:37] op_sel:[0,1]
	v_pk_mov_b32 v[36:37], v[36:37], v[80:81] op_sel:[1,0]
	v_pk_mov_b32 v[86:87], v[80:81], v[64:65] op_sel:[0,1]
	v_pk_mov_b32 v[64:65], v[64:65], v[90:91] op_sel:[1,0]
	v_pk_mov_b32 v[90:91], v[78:79], v[68:69] op_sel:[1,0]
	v_pk_mul_f32 v[36:37], v[36:37], v[46:47]
	v_pk_mul_f32 v[46:47], v[62:63], v[78:79]
	v_pk_fma_f32 v[36:37], v[64:65], v[90:91], v[36:37]
	v_pk_fma_f32 v[46:47], v[86:87], v[68:69], v[46:47] neg_lo:[0,0,1] neg_hi:[0,0,1]
	s_mov_b32 s72, s45
	v_pk_add_f32 v[62:63], v[46:47], v[36:37] neg_lo:[0,1]
	v_pk_add_f32 v[64:65], v[46:47], v[36:37]
	v_pk_add_f32 v[36:37], v[36:37], v[46:47] neg_lo:[0,1] neg_hi:[0,1]
	s_nop 0
	v_pk_mul_f32 v[62:63], v[62:63], 0.5 op_sel_hi:[1,0]
	v_mov_b32_e32 v65, v37
	v_mul_f32_e32 v18, 0x3f7b14be, v62
	v_pk_fma_f32 v[68:69], v[62:63], s[8:9], v[18:19] op_sel_hi:[1,1,0] neg_lo:[1,0,0] neg_hi:[1,0,0]
	v_mul_f32_e32 v18, 0x3f7b14be, v63
	v_pk_fma_f32 v[62:63], v[62:63], s[68:69], v[18:19] op_sel_hi:[1,1,0]
	v_mov_b32_e32 v37, v69
	v_mov_b32_e32 v36, v62
	v_pk_fma_f32 v[46:47], v[64:65], 0.5, v[62:63] op_sel_hi:[1,0,1] neg_lo:[0,0,1] neg_hi:[0,0,1]
	v_pk_fma_f32 v[36:37], v[64:65], 0.5, v[36:37] op_sel_hi:[1,0,1]
	s_mov_b32 s73, s44
	v_mov_b32_e32 v47, v37
	v_pk_mul_f32 v[78:79], v[46:47], s[46:47] op_sel_hi:[1,0]
	v_pk_fma_f32 v[46:47], v[64:65], 0.5, v[68:69] op_sel_hi:[1,0,1] neg_lo:[1,0,0] neg_hi:[1,0,0]
	s_mov_b32 s74, s19
	v_mov_b32_e32 v37, v47
	v_pk_mul_f32 v[144:145], v[36:37], s[46:47] op_sel_hi:[1,0]
	v_pk_add_f32 v[36:37], v[96:97], v[84:85]
	v_pk_add_f32 v[46:47], v[96:97], v[84:85] neg_lo:[0,1] neg_hi:[0,1]
	v_mov_b32_e32 v80, v36
	v_pk_mov_b32 v[36:37], v[36:37], v[46:47] op_sel:[1,0]
	v_cvt_f32_f16_sdwa v62, v38 dst_sel:DWORD dst_unused:UNUSED_PAD src0_sel:WORD_1
	v_pk_mul_f32 v[36:37], v[36:37], s[72:73]
	v_mov_b32_e32 v81, v47
	v_pk_mul_f32 v[46:47], v[36:37], s[74:75] op_sel_hi:[1,0]
	v_cvt_f32_f16_e32 v63, v39
	v_cvt_f32_f16_e32 v65, v38
	v_cvt_f32_f16_sdwa v38, v39 dst_sel:DWORD dst_unused:UNUSED_PAD src0_sel:WORD_1
	v_pk_fma_f32 v[84:85], v[36:37], s[16:17], v[46:47] op_sel:[0,0,1] op_sel_hi:[1,0,0] neg_hi:[0,0,1]
	s_nop 0
	v_mov_b32_e32 v39, v62
	s_nop 0
	v_pk_fma_f32 v[36:37], v[80:81], 0.5, v[84:85] op_sel_hi:[1,0,1] neg_lo:[0,0,1] neg_hi:[0,0,1]
	v_pk_fma_f32 v[46:47], v[80:81], 0.5, v[84:85] op_sel_hi:[1,0,1]
	v_mov_b32_e32 v64, v63
	v_pk_mov_b32 v[84:85], v[36:37], v[46:47] op_sel:[1,0]
	v_mov_b32_e32 v69, v38
	v_pk_mov_b32 v[80:81], v[36:37], v[46:47] op_sel:[0,1]
	v_pk_mul_f32 v[38:39], v[84:85], v[38:39]
	v_mov_b32_e32 v68, v65
	v_pk_fma_f32 v[38:39], v[80:81], v[64:65], v[38:39]
	v_mov_b32_e32 v65, v36
	v_mov_b32_e32 v36, v47
	v_mov_b32_e32 v64, v46
	v_pk_mul_f32 v[36:37], v[36:37], v[62:63]
	v_sub_f32_e32 v13, v148, v149
	v_pk_fma_f32 v[36:37], v[64:65], v[68:69], v[36:37] neg_lo:[0,0,1] neg_hi:[0,0,1]
	v_add_f32_e32 v5, v148, v149
	v_mul_f32_e32 v13, v13, v114
	v_pk_add_f32 v[46:47], v[38:39], v[36:37]
	v_mul_f32_e32 v7, v5, v116
	v_fma_mix_f32 v25, v5, v122, -v13 op_sel_hi:[0,1,0]
	v_pk_add_f32 v[64:65], v[38:39], v[36:37] neg_hi:[0,1]
	v_sub_f32_e32 v5, v36, v38
	v_mul_f32_e32 v36, 0.5, v47
	v_mul_f32_e32 v18, 0.5, v5
	v_pk_mul_f32 v[36:37], v[36:37], s[16:17] op_sel_hi:[0,1]
	v_pk_fma_f32 v[38:39], v[18:19], s[66:67], v[36:37] op_sel_hi:[0,1,1]
	v_pk_fma_f32 v[36:37], v[18:19], s[66:67], v[36:37] op_sel_hi:[0,1,1] neg_lo:[0,0,1] neg_hi:[0,0,1]
	v_pk_mov_b32 v[46:47], v[38:39], v[36:37] op_sel:[0,1]
	v_pk_fma_f32 v[38:39], v[64:65], 0.5, v[38:39] op_sel_hi:[1,0,1] neg_lo:[0,0,1] neg_hi:[0,0,1]
	v_pk_fma_f32 v[46:47], v[64:65], 0.5, v[46:47] op_sel_hi:[1,0,1]
	v_pk_fma_f32 v[36:37], v[64:65], 0.5, v[36:37] op_sel_hi:[1,0,1] neg_lo:[1,0,0] neg_hi:[1,0,0]
	v_mov_b32_e32 v39, v47
	v_pk_mul_f32 v[62:63], v[38:39], s[46:47] op_sel_hi:[1,0]
	v_mov_b32_e32 v47, v37
	v_pk_add_f32 v[36:37], v[42:43], v[44:45]
	v_pk_add_f32 v[38:39], v[42:43], v[44:45] neg_lo:[0,1] neg_hi:[0,1]
	v_mov_b32_e32 v64, v36
	v_pk_mov_b32 v[36:37], v[36:37], v[38:39] op_sel:[1,0]
	s_mov_b32 s76, s27
	v_pk_mul_f32 v[36:37], v[36:37], s[72:73]
	v_cvt_f32_f16_sdwa v42, v26 dst_sel:DWORD dst_unused:UNUSED_PAD src0_sel:WORD_1
	v_mov_b32_e32 v65, v39
	v_pk_mul_f32 v[38:39], v[36:37], s[76:77] op_sel_hi:[1,0]
	v_cvt_f32_f16_e32 v43, v27
	v_cvt_f32_f16_e32 v45, v26
	v_cvt_f32_f16_sdwa v26, v27 dst_sel:DWORD dst_unused:UNUSED_PAD src0_sel:WORD_1
	v_pk_fma_f32 v[68:69], v[36:37], s[24:25], v[38:39] op_sel:[0,0,1] op_sel_hi:[1,0,0] neg_hi:[0,0,1]
	s_nop 0
	v_mov_b32_e32 v27, v42
	s_nop 0
	v_pk_fma_f32 v[36:37], v[64:65], 0.5, v[68:69] op_sel_hi:[1,0,1] neg_lo:[0,0,1] neg_hi:[0,0,1]
	v_pk_fma_f32 v[38:39], v[64:65], 0.5, v[68:69] op_sel_hi:[1,0,1]
	v_pk_mul_f32 v[80:81], v[46:47], s[46:47] op_sel_hi:[1,0]
	v_pk_mov_b32 v[68:69], v[36:37], v[38:39] op_sel:[1,0]
	v_mov_b32_e32 v44, v43
	v_mov_b32_e32 v47, v26
	v_pk_mov_b32 v[64:65], v[36:37], v[38:39] op_sel:[0,1]
	v_pk_mul_f32 v[26:27], v[68:69], v[26:27]
	v_mov_b32_e32 v46, v45
	v_pk_fma_f32 v[26:27], v[64:65], v[44:45], v[26:27]
	v_mov_b32_e32 v45, v36
	v_mov_b32_e32 v36, v39
	v_mov_b32_e32 v44, v38
	v_pk_mul_f32 v[36:37], v[36:37], v[42:43]
	s_mov_b32 s25, s27
	v_pk_fma_f32 v[36:37], v[44:45], v[46:47], v[36:37] neg_lo:[0,0,1] neg_hi:[0,0,1]
	s_mov_b32 s78, s27
	v_pk_add_f32 v[38:39], v[26:27], v[36:37]
	v_pk_add_f32 v[42:43], v[26:27], v[36:37] neg_hi:[0,1]
	v_sub_f32_e32 v5, v36, v26
	v_mul_f32_e32 v26, 0.5, v39
	v_mul_f32_e32 v18, 0.5, v5
	s_mov_b32 s79, s24
	v_pk_mul_f32 v[26:27], v[26:27], s[24:25] op_sel_hi:[0,1]
	v_pk_fma_f32 v[36:37], v[18:19], s[78:79], v[26:27] op_sel_hi:[0,1,1]
	v_pk_fma_f32 v[26:27], v[18:19], s[78:79], v[26:27] op_sel_hi:[0,1,1] neg_lo:[0,0,1] neg_hi:[0,0,1]
	s_nop 0
	v_pk_mov_b32 v[38:39], v[36:37], v[26:27] op_sel:[0,1]
	v_pk_fma_f32 v[36:37], v[42:43], 0.5, v[36:37] op_sel_hi:[1,0,1] neg_lo:[0,0,1] neg_hi:[0,0,1]
	v_pk_fma_f32 v[38:39], v[42:43], 0.5, v[38:39] op_sel_hi:[1,0,1]
	v_pk_fma_f32 v[26:27], v[42:43], 0.5, v[26:27] op_sel_hi:[1,0,1] neg_lo:[1,0,0] neg_hi:[1,0,0]
	v_mov_b32_e32 v37, v39
	v_pk_mul_f32 v[128:129], v[36:37], s[46:47] op_sel_hi:[1,0]
	v_mov_b32_e32 v39, v27
	v_pk_add_f32 v[26:27], v[92:93], v[88:89]
	v_pk_add_f32 v[36:37], v[92:93], v[88:89] neg_lo:[0,1] neg_hi:[0,1]
	v_add_f32_e32 v24, v7, v13
	v_pk_mul_f32 v[120:121], v[38:39], s[46:47] op_sel_hi:[1,0]
	v_mul_f32_e32 v5, 0.5, v27
	v_mul_f32_e32 v7, -0.5, v36
	v_cvt_f32_f16_sdwa v38, v20 dst_sel:DWORD dst_unused:UNUSED_PAD src0_sel:WORD_1
	v_mul_f32_e32 v5, 0x3f3504f3, v5
	v_mul_f32_e32 v13, 0x3f3504f3, v7
	v_cvt_f32_f16_e32 v39, v21
	v_cvt_f32_f16_e32 v43, v20
	v_cvt_f32_f16_sdwa v20, v21 dst_sel:DWORD dst_unused:UNUSED_PAD src0_sel:WORD_1
	v_mov_b32_e32 v27, v37
	v_add_f32_e32 v36, v13, v5
	v_fma_f32 v37, v7, s37, -v5
	v_pk_fma_f32 v[46:47], v[26:27], 0.5, v[36:37] op_sel_hi:[1,0,1] neg_lo:[0,0,1] neg_hi:[0,0,1]
	v_pk_fma_f32 v[26:27], v[26:27], 0.5, v[36:37] op_sel_hi:[1,0,1]
	v_mov_b32_e32 v21, v38
	v_pk_mov_b32 v[64:65], v[46:47], v[26:27] op_sel:[1,0]
	v_mov_b32_e32 v42, v39
	v_mov_b32_e32 v45, v20
	v_pk_mov_b32 v[36:37], v[46:47], v[26:27] op_sel:[0,1]
	v_pk_mul_f32 v[20:21], v[64:65], v[20:21]
	v_mov_b32_e32 v44, v43
	v_pk_fma_f32 v[20:21], v[36:37], v[42:43], v[20:21]
	v_mov_b32_e32 v37, v46
	v_mov_b32_e32 v46, v27
	v_mov_b32_e32 v36, v26
	v_pk_mul_f32 v[26:27], v[46:47], v[38:39]
	v_pk_mul_f32 v[24:25], v[24:25], 0.5 op_sel_hi:[1,0]
	v_pk_fma_f32 v[26:27], v[36:37], v[44:45], v[26:27] neg_lo:[0,0,1] neg_hi:[0,0,1]
	v_pk_mul_f32 v[24:25], v[24:25], s[46:47] op_sel_hi:[1,0]
	v_pk_add_f32 v[36:37], v[20:21], v[26:27]
	v_sub_f32_e32 v5, v26, v20
	v_mul_f32_e32 v7, 0.5, v37
	v_mul_f32_e32 v5, 0.5, v5
	v_mul_f32_e32 v7, 0x3f3504f3, v7
	v_pk_add_f32 v[38:39], v[20:21], v[26:27] neg_hi:[0,1]
	v_mul_f32_e32 v13, 0x3f3504f3, v5
	v_fma_f32 v18, v5, s37, -v7
	v_add_f32_e32 v20, v13, v7
	v_mov_b32_e32 v21, v18
	v_pk_fma_f32 v[26:27], v[38:39], 0.5, v[20:21] op_sel_hi:[1,0,1] neg_lo:[0,0,1]
	v_pk_fma_f32 v[20:21], v[38:39], 0.5, v[20:21] op_sel_hi:[1,0,1]
	v_cvt_f32_f16_e32 v37, v10
	v_pk_mul_f32 v[64:65], v[26:27], s[46:47] op_sel_hi:[1,0]
	v_pk_fma_f32 v[26:27], v[38:39], 0.5, v[18:19] op_sel_hi:[1,0,0] neg_lo:[1,0,0] neg_hi:[1,0,0]
	v_mov_b32_e32 v38, v37
	v_mov_b32_e32 v21, v27
	v_pk_mul_f32 v[68:69], v[20:21], s[46:47] op_sel_hi:[1,0]
	v_pk_add_f32 v[20:21], v[40:41], v[22:23]
	v_pk_add_f32 v[22:23], v[40:41], v[22:23] neg_lo:[0,1] neg_hi:[0,1]
	v_mov_b32_e32 v40, v20
	v_pk_mov_b32 v[20:21], v[20:21], v[22:23] op_sel:[1,0]
	v_cvt_f32_f16_sdwa v26, v10 dst_sel:DWORD dst_unused:UNUSED_PAD src0_sel:WORD_1
	v_pk_mul_f32 v[20:21], v[20:21], s[72:73]
	v_mov_b32_e32 v41, v23
	v_pk_mul_f32 v[22:23], v[20:21], s[24:25] op_sel_hi:[1,0]
	v_cvt_f32_f16_e32 v27, v11
	v_cvt_f32_f16_sdwa v10, v11 dst_sel:DWORD dst_unused:UNUSED_PAD src0_sel:WORD_1
	v_pk_fma_f32 v[42:43], v[20:21], s[76:77], v[22:23] op_sel:[0,0,1] op_sel_hi:[1,0,0] neg_hi:[0,0,1]
	s_nop 0
	v_mov_b32_e32 v11, v26
	s_nop 0
	v_pk_fma_f32 v[20:21], v[40:41], 0.5, v[42:43] op_sel_hi:[1,0,1] neg_lo:[0,0,1] neg_hi:[0,0,1]
	v_pk_fma_f32 v[22:23], v[40:41], 0.5, v[42:43] op_sel_hi:[1,0,1]
	v_mov_b32_e32 v36, v27
	v_pk_mov_b32 v[42:43], v[20:21], v[22:23] op_sel:[1,0]
	v_mov_b32_e32 v39, v10
	v_pk_mov_b32 v[40:41], v[20:21], v[22:23] op_sel:[0,1]
	v_pk_mul_f32 v[10:11], v[42:43], v[10:11]
	v_mov_b32_e32 v7, v161
	v_pk_fma_f32 v[10:11], v[40:41], v[36:37], v[10:11]
	v_mov_b32_e32 v37, v20
	v_mov_b32_e32 v20, v23
	v_mov_b32_e32 v36, v22
	v_pk_mul_f32 v[20:21], v[20:21], v[26:27]
	v_mov_b32_e32 v17, v173
	v_pk_fma_f32 v[20:21], v[36:37], v[38:39], v[20:21] neg_lo:[0,0,1] neg_hi:[0,0,1]
	v_mov_b32_e32 v13, v175
	v_pk_add_f32 v[22:23], v[10:11], v[20:21]
	v_sub_f32_e32 v5, v20, v10
	v_mul_f32_e32 v18, 0.5, v23
	v_pk_add_f32 v[26:27], v[10:11], v[20:21] neg_hi:[0,1]
	v_mul_f32_e32 v10, 0.5, v5
	v_pk_mul_f32 v[20:21], v[18:19], s[78:79] op_sel_hi:[0,1]
	v_pk_fma_f32 v[22:23], v[10:11], s[24:25], v[20:21] op_sel_hi:[0,1,1]
	v_pk_fma_f32 v[10:11], v[10:11], s[24:25], v[20:21] op_sel_hi:[0,1,1] neg_lo:[0,0,1] neg_hi:[0,0,1]
	v_pk_mov_b32 v[20:21], v[22:23], v[10:11] op_sel:[0,1]
	v_pk_fma_f32 v[22:23], v[26:27], 0.5, v[22:23] op_sel_hi:[1,0,1] neg_lo:[0,0,1] neg_hi:[0,0,1]
	v_pk_fma_f32 v[20:21], v[26:27], 0.5, v[20:21] op_sel_hi:[1,0,1]
	v_pk_fma_f32 v[10:11], v[26:27], 0.5, v[10:11] op_sel_hi:[1,0,1] neg_lo:[1,0,0] neg_hi:[1,0,0]
	v_mov_b32_e32 v23, v21
	v_mov_b32_e32 v21, v11
	v_pk_mul_f32 v[150:151], v[20:21], s[46:47] op_sel_hi:[1,0]
	v_pk_add_f32 v[10:11], v[66:67], v[60:61]
	v_pk_add_f32 v[20:21], v[60:61], v[66:67] neg_lo:[0,1] neg_hi:[0,1]
	v_mov_b32_e32 v38, v10
	v_pk_mov_b32 v[10:11], v[10:11], v[20:21] op_sel:[1,0]
	v_pk_mul_f32 v[130:131], v[22:23], s[46:47] op_sel_hi:[1,0]
	v_pk_mul_f32 v[10:11], v[10:11], s[72:73]
	v_cvt_f32_f16_sdwa v22, v8 dst_sel:DWORD dst_unused:UNUSED_PAD src0_sel:WORD_1
	v_mov_b32_e32 v39, v21
	v_pk_mul_f32 v[20:21], v[10:11], s[16:17] op_sel_hi:[1,0]
	v_cvt_f32_f16_e32 v23, v9
	v_cvt_f32_f16_e32 v27, v8
	v_cvt_f32_f16_sdwa v8, v9 dst_sel:DWORD dst_unused:UNUSED_PAD src0_sel:WORD_1
	v_pk_fma_f32 v[40:41], v[10:11], s[74:75], v[20:21] op_sel:[0,0,1] op_sel_hi:[1,0,0] neg_hi:[0,0,1]
	s_nop 0
	v_mov_b32_e32 v9, v22
	s_nop 0
	v_pk_fma_f32 v[10:11], v[38:39], 0.5, v[40:41] op_sel_hi:[1,0,1] neg_lo:[0,0,1] neg_hi:[0,0,1]
	v_pk_fma_f32 v[20:21], v[38:39], 0.5, v[40:41] op_sel_hi:[1,0,1]
	v_mov_b32_e32 v26, v23
	v_pk_mov_b32 v[40:41], v[10:11], v[20:21] op_sel:[1,0]
	v_mov_b32_e32 v37, v8
	v_pk_mov_b32 v[38:39], v[10:11], v[20:21] op_sel:[0,1]
	v_pk_mul_f32 v[8:9], v[40:41], v[8:9]
	v_mov_b32_e32 v36, v27
	v_pk_fma_f32 v[8:9], v[38:39], v[26:27], v[8:9]
	v_mov_b32_e32 v27, v10
	v_mov_b32_e32 v10, v21
	v_mov_b32_e32 v26, v20
	v_pk_mul_f32 v[10:11], v[10:11], v[22:23]
	v_mov_b32_e32 v33, v105
	v_pk_fma_f32 v[10:11], v[26:27], v[36:37], v[10:11] neg_lo:[0,0,1] neg_hi:[0,0,1]
	v_mov_b32_e32 v29, v153
	v_pk_add_f32 v[20:21], v[8:9], v[10:11]
	v_pk_add_f32 v[22:23], v[8:9], v[10:11] neg_hi:[0,1]
	v_sub_f32_e32 v5, v10, v8
	v_mul_f32_e32 v10, 0.5, v21
	v_mul_f32_e32 v8, 0.5, v5
	v_pk_mul_f32 v[10:11], v[10:11], s[66:67] op_sel_hi:[0,1]
	v_pk_fma_f32 v[20:21], v[8:9], s[16:17], v[10:11] op_sel_hi:[0,1,1]
	v_pk_fma_f32 v[8:9], v[8:9], s[16:17], v[10:11] op_sel_hi:[0,1,1] neg_lo:[0,0,1] neg_hi:[0,0,1]
	v_pk_mov_b32 v[10:11], v[20:21], v[8:9] op_sel:[0,1]
	v_pk_fma_f32 v[20:21], v[22:23], 0.5, v[20:21] op_sel_hi:[1,0,1] neg_lo:[0,0,1] neg_hi:[0,0,1]
	v_pk_fma_f32 v[10:11], v[22:23], 0.5, v[10:11] op_sel_hi:[1,0,1]
	v_pk_fma_f32 v[8:9], v[22:23], 0.5, v[8:9] op_sel_hi:[1,0,1] neg_lo:[1,0,0] neg_hi:[1,0,0]
	v_mov_b32_e32 v21, v11
	v_mov_b32_e32 v11, v9
	v_pk_mul_f32 v[90:91], v[10:11], s[46:47] op_sel_hi:[1,0]
	v_pk_add_f32 v[8:9], v[34:35], v[14:15]
	v_pk_add_f32 v[10:11], v[14:15], v[34:35] neg_lo:[0,1] neg_hi:[0,1]
	v_mov_b32_e32 v26, v8
	v_pk_mov_b32 v[8:9], v[8:9], v[10:11] op_sel:[1,0]
	v_cvt_f32_f16_sdwa v14, v2 dst_sel:DWORD dst_unused:UNUSED_PAD src0_sel:WORD_1
	v_pk_mul_f32 v[8:9], v[8:9], s[72:73]
	v_mov_b32_e32 v27, v11
	s_mov_b32 s66, s11
	v_pk_mul_f32 v[10:11], v[8:9], s[8:9] op_sel_hi:[1,0]
	v_pk_mul_f32 v[94:95], v[20:21], s[46:47] op_sel_hi:[1,0]
	v_cvt_f32_f16_e32 v15, v3
	v_cvt_f32_f16_e32 v21, v2
	v_cvt_f32_f16_sdwa v2, v3 dst_sel:DWORD dst_unused:UNUSED_PAD src0_sel:WORD_1
	v_pk_fma_f32 v[34:35], v[8:9], s[66:67], v[10:11] op_sel:[0,0,1] op_sel_hi:[1,0,0] neg_hi:[0,0,1]
	s_nop 0
	v_mov_b32_e32 v3, v14
	s_nop 0
	v_pk_fma_f32 v[8:9], v[26:27], 0.5, v[34:35] op_sel_hi:[1,0,1] neg_lo:[0,0,1] neg_hi:[0,0,1]
	v_pk_fma_f32 v[10:11], v[26:27], 0.5, v[34:35] op_sel_hi:[1,0,1]
	v_mov_b32_e32 v20, v15
	v_pk_mov_b32 v[34:35], v[8:9], v[10:11] op_sel:[1,0]
	v_mov_b32_e32 v23, v2
	v_pk_mov_b32 v[26:27], v[8:9], v[10:11] op_sel:[0,1]
	v_pk_mul_f32 v[2:3], v[34:35], v[2:3]
	v_mov_b32_e32 v22, v21
	v_pk_fma_f32 v[2:3], v[26:27], v[20:21], v[2:3]
	v_mov_b32_e32 v21, v8
	v_mov_b32_e32 v8, v11
	v_mov_b32_e32 v20, v10
	v_pk_mul_f32 v[8:9], v[8:9], v[14:15]
	v_mov_b32_e32 v5, v171
	v_pk_fma_f32 v[8:9], v[20:21], v[22:23], v[8:9] neg_lo:[0,0,1] neg_hi:[0,0,1]
	v_mov_b32_e32 v51, v135
	v_pk_add_f32 v[10:11], v[2:3], v[8:9]
	v_pk_add_f32 v[14:15], v[2:3], v[8:9] neg_hi:[0,1]
	v_sub_f32_e32 v2, v8, v2
	v_mul_f32_e32 v8, 0.5, v11
	v_mul_f32_e32 v2, 0.5, v2
	v_pk_mul_f32 v[8:9], v[8:9], s[68:69] op_sel_hi:[0,1]
	v_pk_fma_f32 v[10:11], v[2:3], s[8:9], v[8:9] op_sel_hi:[0,1,1]
	v_pk_fma_f32 v[2:3], v[2:3], s[8:9], v[8:9] op_sel_hi:[0,1,1] neg_lo:[0,0,1] neg_hi:[0,0,1]
	v_pk_mov_b32 v[8:9], v[10:11], v[2:3] op_sel:[0,1]
	v_pk_fma_f32 v[10:11], v[14:15], 0.5, v[10:11] op_sel_hi:[1,0,1] neg_lo:[0,0,1] neg_hi:[0,0,1]
	v_pk_fma_f32 v[8:9], v[14:15], 0.5, v[8:9] op_sel_hi:[1,0,1]
	v_pk_fma_f32 v[2:3], v[14:15], 0.5, v[2:3] op_sel_hi:[1,0,1] neg_lo:[1,0,0] neg_hi:[1,0,0]
	v_mov_b32_e32 v11, v9
	v_mov_b32_e32 v9, v3
	v_pk_mul_f32 v[168:169], v[10:11], s[46:47] op_sel_hi:[1,0]
	v_pk_mul_f32 v[136:137], v[8:9], s[46:47] op_sel_hi:[1,0]
	v_mov_b32_e32 v49, v119
	v_mov_b32_e32 v75, v113
	v_mov_b32_e32 v53, v111
	v_mov_b32_e32 v77, v109
	v_mov_b32_e32 v57, v83
	v_mov_b32_e32 v71, v107
	v_mov_b32_e32 v55, v103
	v_mov_b32_e32 v73, v101
	v_mov_b32_e32 v59, v99

.LBB0_546:
	s_or_b64 exec, exec, s[0:1]
	v_mov_b32_e32 v25, v210
	s_mov_b32 s62, s37
	v_and_b32_e32 v28, 0xff, v25
	v_lshlrev_b32_e32 v34, 5, v25
	v_cvt_f32_ubyte0_e32 v25, v25
	v_mul_f32_e32 v25, 0x39000000, v25
	v_sin_f32_e32 v43, v25
	v_cos_f32_e32 v42, v25
	v_and_or_b32 v28, v34, s33, v28
	v_ashrrev_i32_e32 v34, 5, v28
	v_pk_mul_f32 v[44:45], v[42:43], 1.0 op_sel:[1,0] op_sel_hi:[1,0] neg_lo:[1,0]
	s_nop 0
	v_pk_mul_f32 v[46:47], v[42:43], v[44:45] op_sel:[1,0] op_sel_hi:[0,1]
	v_pk_fma_f32 v[46:47], v[42:43], v[42:43], v[46:47] op_sel_hi:[1,0,1]
	v_lshlrev_b32_e32 v28, 3, v28
	v_pk_mul_f32 v[50:51], 1.0, v[46:47] op_sel:[0,1] op_sel_hi:[0,1] neg_lo:[0,1]
	v_pk_mul_f32 v[52:53], v[46:47], v[50:51] op_sel:[1,0] op_sel_hi:[0,1]
	v_pk_fma_f32 v[52:53], v[46:47], v[46:47], v[52:53] op_sel_hi:[1,0,1]
	v_lshlrev_b32_e32 v34, 3, v34
	v_pk_mul_f32 v[54:55], 1.0, v[52:53] op_sel:[0,1] op_sel_hi:[0,1] neg_lo:[0,1]
	v_pk_mul_f32 v[70:71], v[52:53], v[54:55] op_sel:[1,0] op_sel_hi:[0,1]
	v_pk_fma_f32 v[70:71], v[52:53], v[52:53], v[70:71] op_sel_hi:[1,0,1]
	v_pk_mul_f32 v[48:49], v[44:45], v[46:47] op_sel:[0,1] op_sel_hi:[1,0]
	v_pk_mul_f32 v[86:87], v[54:55], v[70:71] op_sel:[0,1] op_sel_hi:[1,0]
	v_add3_u32 v25, 0, v28, v34
	v_pk_fma_f32 v[86:87], v[52:53], v[70:71], v[86:87] op_sel_hi:[0,1,1]
	v_pk_mul_f32 v[102:103], v[54:55], v[86:87] op_sel:[0,1] op_sel_hi:[1,0]
	v_pk_fma_f32 v[48:49], v[42:43], v[46:47], v[48:49] op_sel_hi:[0,1,1]
	v_pk_fma_f32 v[102:103], v[52:53], v[86:87], v[102:103] op_sel_hi:[0,1,1]
	v_pk_mul_f32 v[118:119], v[54:55], v[102:103] op_sel:[0,1] op_sel_hi:[1,0]
	v_pk_mul_f32 v[56:57], v[48:49], 1.0 op_sel:[1,0] op_sel_hi:[1,0] neg_lo:[1,0]
	v_pk_fma_f32 v[118:119], v[52:53], v[102:103], v[118:119] op_sel_hi:[0,1,1]
	v_pk_mul_f32 v[134:135], v[118:119], v[54:55] op_sel:[1,0] op_sel_hi:[0,1]
	v_pk_fma_f32 v[134:135], v[52:53], v[118:119], v[134:135] op_sel_hi:[0,1,1]
	v_pk_mul_f32 v[152:153], v[54:55], v[134:135] op_sel:[0,1] op_sel_hi:[1,0]
	v_pk_mul_f32 v[58:59], v[44:45], v[52:53] op_sel:[0,1] op_sel_hi:[1,0]
	v_pk_fma_f32 v[152:153], v[52:53], v[134:135], v[152:153] op_sel_hi:[0,1,1]
	v_pk_mul_f32 v[74:75], v[44:45], v[70:71] op_sel:[0,1] op_sel_hi:[1,0]
	v_pk_mul_f32 v[90:91], v[44:45], v[86:87] op_sel:[0,1] op_sel_hi:[1,0]
	v_pk_mul_f32 v[106:107], v[44:45], v[102:103] op_sel:[0,1] op_sel_hi:[1,0]
	v_pk_mul_f32 v[122:123], v[44:45], v[118:119] op_sel:[0,1] op_sel_hi:[1,0]
	v_pk_mul_f32 v[138:139], v[44:45], v[134:135] op_sel:[0,1] op_sel_hi:[1,0]
	v_pk_mul_f32 v[156:157], v[44:45], v[152:153] op_sel:[0,1] op_sel_hi:[1,0]
	ds_read_b64 v[168:169], v25
	ds_read_b64 v[170:171], v25 offset:2112
	ds_read_b64 v[172:173], v25 offset:4224
	ds_read_b64 v[174:175], v25 offset:6336
	ds_read_b64 v[176:177], v25 offset:8448
	ds_read_b64 v[178:179], v25 offset:10560
	ds_read_b64 v[180:181], v25 offset:12672
	ds_read_b64 v[182:183], v25 offset:14784
	ds_read_b64 v[184:185], v25 offset:16896
	ds_read_b64 v[186:187], v25 offset:19008
	ds_read_b64 v[188:189], v25 offset:21120
	ds_read_b64 v[190:191], v25 offset:23232
	ds_read_b64 v[192:193], v25 offset:25344
	ds_read_b64 v[194:195], v25 offset:27456
	ds_read_b64 v[196:197], v25 offset:29568
	ds_read_b64 v[198:199], v25 offset:31680
	ds_read_b64 v[212:213], v25 offset:33792
	ds_read_b64 v[214:215], v25 offset:35904
	ds_read_b64 v[216:217], v25 offset:38016
	ds_read_b64 v[218:219], v25 offset:40128
	ds_read_b64 v[220:221], v25 offset:42240
	ds_read_b64 v[222:223], v25 offset:44352
	ds_read_b64 v[224:225], v25 offset:46464
	ds_read_b64 v[226:227], v25 offset:48576
	ds_read_b64 v[228:229], v25 offset:50688
	ds_read_b64 v[230:231], v25 offset:52800
	ds_read_b64 v[232:233], v25 offset:54912
	ds_read_b64 v[234:235], v25 offset:57024
	ds_read_b64 v[236:237], v25 offset:59136
	ds_read_b64 v[238:239], v25 offset:61248
	ds_read_b64 v[240:241], v25 offset:63360
	ds_read_b64 v[242:243], v25 offset:65472
	s_waitcnt lgkmcnt(14)
	v_pk_mul_f32 v[44:45], v[44:45], v[212:213] op_sel:[0,1] op_sel_hi:[1,0]
	v_pk_fma_f32 v[58:59], v[42:43], v[52:53], v[58:59] op_sel_hi:[0,1,1]
	v_pk_mul_f32 v[62:63], v[50:51], v[52:53] op_sel:[0,1] op_sel_hi:[1,0]
	v_pk_mul_f32 v[66:67], v[52:53], v[56:57] op_sel:[1,0] op_sel_hi:[0,1]
	v_pk_fma_f32 v[74:75], v[42:43], v[70:71], v[74:75] op_sel_hi:[0,1,1]
	v_pk_mul_f32 v[78:79], v[50:51], v[70:71] op_sel:[0,1] op_sel_hi:[1,0]
	v_pk_fma_f32 v[90:91], v[42:43], v[86:87], v[90:91] op_sel_hi:[0,1,1]
	v_pk_mul_f32 v[94:95], v[50:51], v[86:87] op_sel:[0,1] op_sel_hi:[1,0]
	v_pk_fma_f32 v[106:107], v[42:43], v[102:103], v[106:107] op_sel_hi:[0,1,1]
	v_pk_mul_f32 v[110:111], v[50:51], v[102:103] op_sel:[0,1] op_sel_hi:[1,0]
	v_pk_fma_f32 v[122:123], v[42:43], v[118:119], v[122:123] op_sel_hi:[0,1,1]
	v_pk_mul_f32 v[126:127], v[50:51], v[118:119] op_sel:[0,1] op_sel_hi:[1,0]
	v_pk_fma_f32 v[138:139], v[42:43], v[134:135], v[138:139] op_sel_hi:[0,1,1]
	v_pk_mul_f32 v[142:143], v[50:51], v[134:135] op_sel:[0,1] op_sel_hi:[1,0]
	v_pk_fma_f32 v[156:157], v[42:43], v[152:153], v[156:157] op_sel_hi:[0,1,1]
	v_pk_mul_f32 v[160:161], v[50:51], v[152:153] op_sel:[0,1] op_sel_hi:[1,0]
	v_pk_fma_f32 v[42:43], v[42:43], v[212:213], v[44:45] op_sel_hi:[0,1,1]
	v_pk_mul_f32 v[44:45], v[184:185], v[50:51] op_sel:[1,0] op_sel_hi:[0,1]
	v_pk_fma_f32 v[62:63], v[46:47], v[52:53], v[62:63] op_sel_hi:[0,1,1]
	v_pk_fma_f32 v[66:67], v[52:53], v[48:49], v[66:67] op_sel_hi:[1,0,1]
	v_pk_fma_f32 v[78:79], v[46:47], v[70:71], v[78:79] op_sel_hi:[0,1,1]
	v_pk_mul_f32 v[82:83], v[56:57], v[70:71] op_sel:[0,1] op_sel_hi:[1,0]
	v_pk_fma_f32 v[94:95], v[46:47], v[86:87], v[94:95] op_sel_hi:[0,1,1]
	v_pk_mul_f32 v[98:99], v[56:57], v[86:87] op_sel:[0,1] op_sel_hi:[1,0]
	v_pk_fma_f32 v[110:111], v[46:47], v[102:103], v[110:111] op_sel_hi:[0,1,1]
	v_pk_mul_f32 v[114:115], v[56:57], v[102:103] op_sel:[0,1] op_sel_hi:[1,0]
	v_pk_fma_f32 v[126:127], v[46:47], v[118:119], v[126:127] op_sel_hi:[0,1,1]
	v_pk_mul_f32 v[130:131], v[56:57], v[118:119] op_sel:[0,1] op_sel_hi:[1,0]
	v_pk_fma_f32 v[142:143], v[46:47], v[134:135], v[142:143] op_sel_hi:[0,1,1]
	v_pk_mul_f32 v[148:149], v[56:57], v[134:135] op_sel:[0,1] op_sel_hi:[1,0]
	v_pk_fma_f32 v[160:161], v[46:47], v[152:153], v[160:161] op_sel_hi:[0,1,1]
	v_pk_mul_f32 v[164:165], v[56:57], v[152:153] op_sel:[0,1] op_sel_hi:[1,0]
	v_pk_fma_f32 v[44:45], v[184:185], v[46:47], v[44:45] op_sel_hi:[1,0,1]
	s_waitcnt lgkmcnt(7)
	v_pk_mul_f32 v[46:47], v[56:57], v[228:229] op_sel:[0,1] op_sel_hi:[1,0]
	v_xor_b32_e32 v60, 0x80000000, v59
	v_xor_b32_e32 v64, 0x80000000, v63
	v_xor_b32_e32 v68, 0x80000000, v67
	v_xor_b32_e32 v72, 0x80000000, v71
	v_pk_fma_f32 v[82:83], v[48:49], v[70:71], v[82:83] op_sel_hi:[0,1,1]
	v_pk_fma_f32 v[98:99], v[48:49], v[86:87], v[98:99] op_sel_hi:[0,1,1]
	v_pk_fma_f32 v[114:115], v[48:49], v[102:103], v[114:115] op_sel_hi:[0,1,1]
	v_pk_fma_f32 v[130:131], v[48:49], v[118:119], v[130:131] op_sel_hi:[0,1,1]
	v_pk_fma_f32 v[148:149], v[48:49], v[134:135], v[148:149] op_sel_hi:[0,1,1]
	v_pk_fma_f32 v[164:165], v[48:49], v[152:153], v[164:165] op_sel_hi:[0,1,1]
	v_mov_b32_e32 v61, v59
	v_mov_b32_e32 v65, v63
	v_mov_b32_e32 v69, v67
	v_mov_b32_e32 v73, v71
	v_pk_fma_f32 v[46:47], v[48:49], v[228:229], v[46:47] op_sel_hi:[0,1,1]
	v_pk_mul_f32 v[48:49], v[176:177], v[54:55] op_sel:[1,0] op_sel_hi:[0,1]
	v_xor_b32_e32 v76, 0x80000000, v75
	v_xor_b32_e32 v80, 0x80000000, v79
	v_xor_b32_e32 v84, 0x80000000, v83
	v_xor_b32_e32 v88, 0x80000000, v87
	v_xor_b32_e32 v92, 0x80000000, v91
	v_xor_b32_e32 v96, 0x80000000, v95
	v_xor_b32_e32 v100, 0x80000000, v99
	v_xor_b32_e32 v104, 0x80000000, v103
	v_xor_b32_e32 v136, 0x80000000, v135
	v_mov_b32_e32 v77, v75
	v_mov_b32_e32 v81, v79
	v_mov_b32_e32 v85, v83
	v_mov_b32_e32 v89, v87
	v_mov_b32_e32 v93, v91
	v_mov_b32_e32 v97, v95
	v_mov_b32_e32 v101, v99
	v_mov_b32_e32 v105, v103
	v_mov_b32_e32 v137, v135
	v_pk_fma_f32 v[48:49], v[176:177], v[52:53], v[48:49] op_sel_hi:[1,0,1]
	v_pk_mul_f32 v[50:51], v[60:61], v[220:221] op_sel:[0,1] op_sel_hi:[1,0]
	v_pk_mul_f32 v[52:53], v[192:193], v[64:65] op_sel:[1,0] op_sel_hi:[0,1]
	s_waitcnt lgkmcnt(3)
	v_pk_mul_f32 v[54:55], v[68:69], v[236:237] op_sel:[0,1] op_sel_hi:[1,0]
	v_pk_mul_f32 v[56:57], v[172:173], v[72:73] op_sel:[1,0] op_sel_hi:[0,1]
	v_xor_b32_e32 v108, 0x80000000, v107
	v_xor_b32_e32 v112, 0x80000000, v111
	v_xor_b32_e32 v116, 0x80000000, v115
	v_xor_b32_e32 v120, 0x80000000, v119
	v_xor_b32_e32 v124, 0x80000000, v123
	v_xor_b32_e32 v128, 0x80000000, v127
	v_xor_b32_e32 v132, 0x80000000, v131
	v_xor_b32_e32 v140, 0x80000000, v139
	v_xor_b32_e32 v144, 0x80000000, v143
	v_xor_b32_e32 v150, 0x80000000, v149
	v_xor_b32_e32 v154, 0x80000000, v153
	v_xor_b32_e32 v158, 0x80000000, v157
	v_xor_b32_e32 v162, 0x80000000, v161
	v_xor_b32_e32 v166, 0x80000000, v165
	v_mov_b32_e32 v109, v107
	v_mov_b32_e32 v113, v111
	v_mov_b32_e32 v117, v115
	v_mov_b32_e32 v121, v119
	v_mov_b32_e32 v125, v123
	v_mov_b32_e32 v129, v127
	v_mov_b32_e32 v133, v131
	v_mov_b32_e32 v141, v139
	v_mov_b32_e32 v145, v143
	v_mov_b32_e32 v151, v149
	v_mov_b32_e32 v155, v153
	v_mov_b32_e32 v159, v157
	v_mov_b32_e32 v163, v161
	v_mov_b32_e32 v167, v165
	v_pk_fma_f32 v[50:51], v[58:59], v[220:221], v[50:51] op_sel_hi:[0,1,1]
	v_pk_fma_f32 v[52:53], v[192:193], v[62:63], v[52:53] op_sel_hi:[1,0,1]
	v_pk_fma_f32 v[54:55], v[66:67], v[236:237], v[54:55] op_sel_hi:[0,1,1]
	v_pk_fma_f32 v[56:57], v[172:173], v[70:71], v[56:57] op_sel_hi:[1,0,1]
	v_pk_mul_f32 v[58:59], v[216:217], v[76:77] op_sel:[1,0] op_sel_hi:[0,1]
	v_pk_mul_f32 v[60:61], v[188:189], v[80:81] op_sel:[1,0] op_sel_hi:[0,1]
	v_pk_mul_f32 v[62:63], v[84:85], v[232:233] op_sel:[0,1] op_sel_hi:[1,0]
	v_pk_mul_f32 v[64:65], v[180:181], v[88:89] op_sel:[1,0] op_sel_hi:[0,1]
	v_pk_mul_f32 v[66:67], v[224:225], v[92:93] op_sel:[1,0] op_sel_hi:[0,1]
	v_pk_mul_f32 v[68:69], v[196:197], v[96:97] op_sel:[1,0] op_sel_hi:[0,1]
	s_waitcnt lgkmcnt(1)
	v_pk_mul_f32 v[70:71], v[100:101], v[240:241] op_sel:[0,1] op_sel_hi:[1,0]
	v_pk_mul_f32 v[72:73], v[170:171], v[104:105] op_sel:[1,0] op_sel_hi:[0,1]
	v_pk_mul_f32 v[88:89], v[174:175], v[136:137] op_sel:[1,0] op_sel_hi:[0,1]
	v_pk_fma_f32 v[58:59], v[216:217], v[74:75], v[58:59] op_sel_hi:[1,0,1]
	v_pk_fma_f32 v[60:61], v[188:189], v[78:79], v[60:61] op_sel_hi:[1,0,1]
	v_pk_fma_f32 v[62:63], v[82:83], v[232:233], v[62:63] op_sel_hi:[0,1,1]
	v_pk_fma_f32 v[64:65], v[180:181], v[86:87], v[64:65] op_sel_hi:[1,0,1]
	v_pk_fma_f32 v[66:67], v[224:225], v[90:91], v[66:67] op_sel_hi:[1,0,1]
	v_pk_fma_f32 v[68:69], v[196:197], v[94:95], v[68:69] op_sel_hi:[1,0,1]
	v_pk_fma_f32 v[70:71], v[98:99], v[240:241], v[70:71] op_sel_hi:[0,1,1]
	v_pk_fma_f32 v[72:73], v[170:171], v[102:103], v[72:73] op_sel_hi:[1,0,1]
	v_pk_mul_f32 v[74:75], v[214:215], v[108:109] op_sel:[1,0] op_sel_hi:[0,1]
	v_pk_mul_f32 v[76:77], v[186:187], v[112:113] op_sel:[1,0] op_sel_hi:[0,1]
	v_pk_mul_f32 v[78:79], v[230:231], v[116:117] op_sel:[1,0] op_sel_hi:[0,1]
	v_pk_mul_f32 v[80:81], v[178:179], v[120:121] op_sel:[1,0] op_sel_hi:[0,1]
	v_pk_mul_f32 v[82:83], v[222:223], v[124:125] op_sel:[1,0] op_sel_hi:[0,1]
	v_pk_mul_f32 v[84:85], v[194:195], v[128:129] op_sel:[1,0] op_sel_hi:[0,1]
	v_pk_mul_f32 v[86:87], v[132:133], v[238:239] op_sel:[0,1] op_sel_hi:[1,0]
	v_pk_fma_f32 v[88:89], v[174:175], v[134:135], v[88:89] op_sel_hi:[1,0,1]
	v_pk_mul_f32 v[90:91], v[218:219], v[140:141] op_sel:[1,0] op_sel_hi:[0,1]
	v_pk_mul_f32 v[92:93], v[190:191], v[144:145] op_sel:[1,0] op_sel_hi:[0,1]
	v_pk_mul_f32 v[94:95], v[234:235], v[150:151] op_sel:[1,0] op_sel_hi:[0,1]
	v_pk_mul_f32 v[96:97], v[182:183], v[154:155] op_sel:[1,0] op_sel_hi:[0,1]
	v_pk_mul_f32 v[98:99], v[226:227], v[158:159] op_sel:[1,0] op_sel_hi:[0,1]
	v_pk_mul_f32 v[100:101], v[198:199], v[162:163] op_sel:[1,0] op_sel_hi:[0,1]
	s_waitcnt lgkmcnt(0)
	v_pk_mul_f32 v[102:103], v[242:243], v[166:167] op_sel:[1,0] op_sel_hi:[0,1]
	v_pk_fma_f32 v[74:75], v[214:215], v[106:107], v[74:75] op_sel_hi:[1,0,1]
	v_pk_fma_f32 v[76:77], v[186:187], v[110:111], v[76:77] op_sel_hi:[1,0,1]
	v_pk_fma_f32 v[78:79], v[230:231], v[114:115], v[78:79] op_sel_hi:[1,0,1]
	v_pk_fma_f32 v[80:81], v[178:179], v[118:119], v[80:81] op_sel_hi:[1,0,1]
	v_pk_fma_f32 v[82:83], v[222:223], v[122:123], v[82:83] op_sel_hi:[1,0,1]
	v_pk_fma_f32 v[84:85], v[194:195], v[126:127], v[84:85] op_sel_hi:[1,0,1]
	v_pk_fma_f32 v[86:87], v[130:131], v[238:239], v[86:87] op_sel_hi:[0,1,1]
	v_pk_fma_f32 v[90:91], v[218:219], v[138:139], v[90:91] op_sel_hi:[1,0,1]
	v_pk_fma_f32 v[92:93], v[190:191], v[142:143], v[92:93] op_sel_hi:[1,0,1]
	v_pk_fma_f32 v[94:95], v[234:235], v[148:149], v[94:95] op_sel_hi:[1,0,1]
	v_pk_fma_f32 v[96:97], v[182:183], v[152:153], v[96:97] op_sel_hi:[1,0,1]
	v_pk_fma_f32 v[98:99], v[226:227], v[156:157], v[98:99] op_sel_hi:[1,0,1]
	v_pk_fma_f32 v[100:101], v[198:199], v[160:161], v[100:101] op_sel_hi:[1,0,1]
	v_pk_fma_f32 v[102:103], v[242:243], v[164:165], v[102:103] op_sel_hi:[1,0,1]
	v_pk_add_f32 v[104:105], v[168:169], v[72:73]
	v_pk_add_f32 v[106:107], v[56:57], v[88:89]
	v_pk_add_f32 v[56:57], v[56:57], v[88:89] neg_lo:[0,1] neg_hi:[0,1]
	v_pk_add_f32 v[72:73], v[168:169], v[72:73] neg_lo:[0,1] neg_hi:[0,1]
	v_pk_add_f32 v[88:89], v[48:49], v[80:81]
	v_pk_add_f32 v[48:49], v[48:49], v[80:81] neg_lo:[0,1] neg_hi:[0,1]
	v_pk_add_f32 v[80:81], v[64:65], v[96:97]
	v_pk_add_f32 v[64:65], v[64:65], v[96:97] neg_lo:[0,1] neg_hi:[0,1]
	v_pk_add_f32 v[96:97], v[44:45], v[76:77]
	v_pk_add_f32 v[44:45], v[44:45], v[76:77] neg_lo:[0,1] neg_hi:[0,1]
	v_pk_add_f32 v[76:77], v[60:61], v[92:93]
	v_pk_add_f32 v[60:61], v[60:61], v[92:93] neg_lo:[0,1] neg_hi:[0,1]
	v_pk_add_f32 v[92:93], v[52:53], v[84:85]
	v_pk_add_f32 v[52:53], v[52:53], v[84:85] neg_lo:[0,1] neg_hi:[0,1]
	v_pk_add_f32 v[84:85], v[68:69], v[100:101]
	v_pk_add_f32 v[68:69], v[68:69], v[100:101] neg_lo:[0,1] neg_hi:[0,1]
	v_pk_add_f32 v[100:101], v[42:43], v[74:75]
	v_pk_add_f32 v[42:43], v[42:43], v[74:75] neg_lo:[0,1] neg_hi:[0,1]
	v_pk_add_f32 v[74:75], v[58:59], v[90:91]
	v_pk_add_f32 v[58:59], v[58:59], v[90:91] neg_lo:[0,1] neg_hi:[0,1]
	v_pk_add_f32 v[90:91], v[50:51], v[82:83]
	v_pk_add_f32 v[50:51], v[50:51], v[82:83] neg_lo:[0,1] neg_hi:[0,1]
	v_pk_add_f32 v[82:83], v[66:67], v[98:99]
	v_pk_add_f32 v[66:67], v[66:67], v[98:99] neg_lo:[0,1] neg_hi:[0,1]
	v_pk_add_f32 v[98:99], v[46:47], v[78:79]
	v_pk_add_f32 v[46:47], v[46:47], v[78:79] neg_lo:[0,1] neg_hi:[0,1]
	v_pk_add_f32 v[78:79], v[62:63], v[94:95]
	v_pk_add_f32 v[62:63], v[62:63], v[94:95] neg_lo:[0,1] neg_hi:[0,1]
	v_pk_add_f32 v[94:95], v[54:55], v[86:87]
	v_pk_add_f32 v[54:55], v[54:55], v[86:87] neg_lo:[0,1] neg_hi:[0,1]
	v_pk_add_f32 v[86:87], v[70:71], v[102:103]
	v_pk_add_f32 v[70:71], v[70:71], v[102:103] neg_lo:[0,1] neg_hi:[0,1]
	v_pk_add_f32 v[102:103], v[104:105], v[106:107]
	v_pk_add_f32 v[104:105], v[104:105], v[106:107] neg_lo:[0,1] neg_hi:[0,1]
	v_pk_mul_f32 v[106:107], v[56:57], 1.0 op_sel:[1,0] op_sel_hi:[0,0] neg_lo:[1,0]
	v_pk_add_f32 v[56:57], v[72:73], v[106:107]
	v_pk_add_f32 v[72:73], v[72:73], v[106:107] neg_lo:[0,1] neg_hi:[0,1]
	v_pk_add_f32 v[106:107], v[88:89], v[80:81]
	v_pk_add_f32 v[80:81], v[88:89], v[80:81] neg_lo:[0,1] neg_hi:[0,1]
	v_pk_mul_f32 v[88:89], v[64:65], 1.0 op_sel:[1,0] op_sel_hi:[0,0] neg_lo:[1,0]
	v_pk_add_f32 v[64:65], v[48:49], v[88:89]
	v_pk_add_f32 v[48:49], v[48:49], v[88:89] neg_lo:[0,1] neg_hi:[0,1]
	v_pk_add_f32 v[88:89], v[96:97], v[76:77]
	v_pk_add_f32 v[76:77], v[96:97], v[76:77] neg_lo:[0,1] neg_hi:[0,1]
	v_pk_mul_f32 v[96:97], v[60:61], 1.0 op_sel:[1,0] op_sel_hi:[0,0] neg_lo:[1,0]
	v_pk_add_f32 v[60:61], v[44:45], v[96:97]
	v_pk_add_f32 v[44:45], v[44:45], v[96:97] neg_lo:[0,1] neg_hi:[0,1]
	v_pk_add_f32 v[96:97], v[92:93], v[84:85]
	v_pk_add_f32 v[84:85], v[92:93], v[84:85] neg_lo:[0,1] neg_hi:[0,1]
	v_pk_mul_f32 v[92:93], v[68:69], 1.0 op_sel:[1,0] op_sel_hi:[0,0] neg_lo:[1,0]
	v_pk_add_f32 v[68:69], v[52:53], v[92:93]
	v_pk_add_f32 v[52:53], v[52:53], v[92:93] neg_lo:[0,1] neg_hi:[0,1]
	v_pk_add_f32 v[92:93], v[100:101], v[74:75]
	v_pk_add_f32 v[74:75], v[100:101], v[74:75] neg_lo:[0,1] neg_hi:[0,1]
	v_pk_mul_f32 v[100:101], v[58:59], 1.0 op_sel:[1,0] op_sel_hi:[0,0] neg_lo:[1,0]
	v_pk_add_f32 v[58:59], v[42:43], v[100:101]
	v_pk_add_f32 v[42:43], v[42:43], v[100:101] neg_lo:[0,1] neg_hi:[0,1]
	v_pk_add_f32 v[100:101], v[90:91], v[82:83]
	v_pk_add_f32 v[82:83], v[90:91], v[82:83] neg_lo:[0,1] neg_hi:[0,1]
	v_pk_mul_f32 v[90:91], v[66:67], 1.0 op_sel:[1,0] op_sel_hi:[0,0] neg_lo:[1,0]
	v_pk_add_f32 v[66:67], v[50:51], v[90:91]
	v_pk_add_f32 v[50:51], v[50:51], v[90:91] neg_lo:[0,1] neg_hi:[0,1]
	v_pk_add_f32 v[90:91], v[98:99], v[78:79]
	v_pk_add_f32 v[78:79], v[98:99], v[78:79] neg_lo:[0,1] neg_hi:[0,1]
	v_pk_mul_f32 v[98:99], v[62:63], 1.0 op_sel:[1,0] op_sel_hi:[0,0] neg_lo:[1,0]
	v_pk_add_f32 v[62:63], v[46:47], v[98:99]
	v_pk_add_f32 v[46:47], v[46:47], v[98:99] neg_lo:[0,1] neg_hi:[0,1]
	v_pk_add_f32 v[98:99], v[94:95], v[86:87]
	v_pk_add_f32 v[86:87], v[94:95], v[86:87] neg_lo:[0,1] neg_hi:[0,1]
	v_pk_mul_f32 v[94:95], v[70:71], 1.0 op_sel:[1,0] op_sel_hi:[0,0] neg_lo:[1,0]
	s_mov_b32 s63, s36
	v_pk_add_f32 v[70:71], v[54:55], v[94:95]
	v_pk_add_f32 v[54:55], v[54:55], v[94:95] neg_lo:[0,1] neg_hi:[0,1]
	v_pk_add_f32 v[94:95], v[102:103], v[106:107]
	v_pk_add_f32 v[102:103], v[102:103], v[106:107] neg_lo:[0,1] neg_hi:[0,1]
	s_mov_b32 s0, s37
	v_pk_mul_f32 v[106:107], v[64:65], s[62:63]
	s_mov_b32 s64, s19
	v_pk_fma_f32 v[64:65], v[64:65], s[0:1], v[106:107] op_sel:[0,0,1] op_sel_hi:[1,0,0]
	s_mov_b32 s65, s18
	v_pk_add_f32 v[106:107], v[56:57], v[64:65]
	v_pk_add_f32 v[56:57], v[56:57], v[64:65] neg_lo:[0,1] neg_hi:[0,1]
	v_pk_mul_f32 v[64:65], v[80:81], 1.0 op_sel:[1,0] op_sel_hi:[0,0] neg_lo:[1,0]
	s_nop 0
	v_pk_add_f32 v[80:81], v[104:105], v[64:65]
	v_pk_add_f32 v[64:65], v[104:105], v[64:65] neg_lo:[0,1] neg_hi:[0,1]
	v_pk_mul_f32 v[104:105], v[48:49], s[62:63]
	s_mov_b32 s66, s19
	v_pk_fma_f32 v[48:49], v[48:49], s[0:1], v[104:105] op_sel:[0,0,1] op_sel_hi:[1,0,0] neg_lo:[1,0,0] neg_hi:[1,0,0]
	s_mov_b32 s68, s11
	v_pk_add_f32 v[104:105], v[72:73], v[48:49]
	v_pk_add_f32 v[48:49], v[72:73], v[48:49] neg_lo:[0,1] neg_hi:[0,1]
	v_pk_add_f32 v[72:73], v[88:89], v[96:97]
	v_pk_add_f32 v[88:89], v[88:89], v[96:97] neg_lo:[0,1] neg_hi:[0,1]
	v_pk_mul_f32 v[96:97], v[68:69], s[62:63]
	s_mov_b32 s69, s10
	v_pk_fma_f32 v[68:69], v[68:69], s[0:1], v[96:97] op_sel:[0,0,1] op_sel_hi:[1,0,0]
	s_mov_b32 s72, s27
	v_pk_add_f32 v[96:97], v[60:61], v[68:69]
	v_pk_add_f32 v[60:61], v[60:61], v[68:69] neg_lo:[0,1] neg_hi:[0,1]
	v_pk_mul_f32 v[68:69], v[84:85], 1.0 op_sel:[1,0] op_sel_hi:[0,0] neg_lo:[1,0]
	s_nop 0
	v_pk_add_f32 v[84:85], v[76:77], v[68:69]
	v_pk_add_f32 v[68:69], v[76:77], v[68:69] neg_lo:[0,1] neg_hi:[0,1]
	v_pk_mul_f32 v[76:77], v[52:53], s[62:63]
	v_pk_mul_f32 v[108:109], v[96:97], s[64:65]
	v_pk_fma_f32 v[52:53], v[52:53], s[0:1], v[76:77] op_sel:[0,0,1] op_sel_hi:[1,0,0] neg_lo:[1,0,0] neg_hi:[1,0,0]
	v_pk_fma_f32 v[96:97], v[96:97], s[16:17], v[108:109] op_sel:[0,0,1] op_sel_hi:[1,0,0]
	v_pk_add_f32 v[76:77], v[44:45], v[52:53]
	v_pk_add_f32 v[44:45], v[44:45], v[52:53] neg_lo:[0,1] neg_hi:[0,1]
	v_pk_add_f32 v[52:53], v[92:93], v[100:101]
	v_pk_add_f32 v[92:93], v[92:93], v[100:101] neg_lo:[0,1] neg_hi:[0,1]
	v_pk_mul_f32 v[100:101], v[66:67], s[62:63]
	s_mov_b32 s17, s40
	v_pk_fma_f32 v[66:67], v[66:67], s[0:1], v[100:101] op_sel:[0,0,1] op_sel_hi:[1,0,0]
	v_pk_add_f32 v[108:109], v[106:107], v[96:97]
	v_pk_add_f32 v[100:101], v[58:59], v[66:67]
	v_pk_add_f32 v[58:59], v[58:59], v[66:67] neg_lo:[0,1] neg_hi:[0,1]
	v_pk_mul_f32 v[66:67], v[82:83], 1.0 op_sel:[1,0] op_sel_hi:[0,0] neg_lo:[1,0]
	v_pk_add_f32 v[82:83], v[74:75], v[66:67]
	v_pk_add_f32 v[66:67], v[74:75], v[66:67] neg_lo:[0,1] neg_hi:[0,1]
	v_pk_mul_f32 v[74:75], v[50:51], s[62:63]
	v_pk_add_f32 v[96:97], v[106:107], v[96:97] neg_lo:[0,1] neg_hi:[0,1]
	v_pk_fma_f32 v[50:51], v[50:51], s[0:1], v[74:75] op_sel:[0,0,1] op_sel_hi:[1,0,0] neg_lo:[1,0,0] neg_hi:[1,0,0]
	v_pk_mul_f32 v[106:107], v[84:85], s[62:63]
	v_pk_add_f32 v[74:75], v[42:43], v[50:51]
	v_pk_add_f32 v[42:43], v[42:43], v[50:51] neg_lo:[0,1] neg_hi:[0,1]
	v_pk_add_f32 v[50:51], v[90:91], v[98:99]
	v_pk_add_f32 v[90:91], v[90:91], v[98:99] neg_lo:[0,1] neg_hi:[0,1]
	v_pk_mul_f32 v[98:99], v[70:71], s[62:63]
	v_pk_fma_f32 v[84:85], v[84:85], s[0:1], v[106:107] op_sel:[0,0,1] op_sel_hi:[1,0,0]
	v_pk_fma_f32 v[70:71], v[70:71], s[0:1], v[98:99] op_sel:[0,0,1] op_sel_hi:[1,0,0]
	v_pk_add_f32 v[106:107], v[80:81], v[84:85]
	v_pk_add_f32 v[98:99], v[62:63], v[70:71]
	v_pk_add_f32 v[62:63], v[62:63], v[70:71] neg_lo:[0,1] neg_hi:[0,1]
	v_pk_mul_f32 v[70:71], v[86:87], 1.0 op_sel:[1,0] op_sel_hi:[0,0] neg_lo:[1,0]
	v_pk_mul_f32 v[110:111], v[98:99], s[64:65]
	v_pk_add_f32 v[86:87], v[78:79], v[70:71]
	v_pk_add_f32 v[70:71], v[78:79], v[70:71] neg_lo:[0,1] neg_hi:[0,1]
	v_pk_mul_f32 v[78:79], v[54:55], s[62:63]
	v_pk_fma_f32 v[98:99], v[98:99], s[16:17], v[110:111] op_sel:[0,0,1] op_sel_hi:[1,0,0]
	v_pk_fma_f32 v[54:55], v[54:55], s[0:1], v[78:79] op_sel:[0,0,1] op_sel_hi:[1,0,0] neg_lo:[1,0,0] neg_hi:[1,0,0]
	v_pk_add_f32 v[110:111], v[100:101], v[98:99]
	v_pk_add_f32 v[98:99], v[100:101], v[98:99] neg_lo:[0,1] neg_hi:[0,1]
	v_pk_mul_f32 v[100:101], v[86:87], s[62:63]
	v_pk_add_f32 v[78:79], v[46:47], v[54:55]
	v_pk_fma_f32 v[86:87], v[86:87], s[0:1], v[100:101] op_sel:[0,0,1] op_sel_hi:[1,0,0]
	v_pk_add_f32 v[46:47], v[46:47], v[54:55] neg_lo:[0,1] neg_hi:[0,1]
	v_pk_add_f32 v[100:101], v[82:83], v[86:87]
	v_pk_add_f32 v[82:83], v[82:83], v[86:87] neg_lo:[0,1] neg_hi:[0,1]
	v_pk_mul_f32 v[86:87], v[78:79], s[16:17]
	v_pk_add_f32 v[80:81], v[80:81], v[84:85] neg_lo:[0,1] neg_hi:[0,1]
	v_pk_fma_f32 v[78:79], v[78:79], s[66:67], v[86:87] op_sel:[0,0,1] op_sel_hi:[1,0,0]
	v_pk_mul_f32 v[84:85], v[76:77], s[16:17]
	v_pk_add_f32 v[86:87], v[74:75], v[78:79]
	v_pk_add_f32 v[74:75], v[74:75], v[78:79] neg_lo:[0,1] neg_hi:[0,1]
	v_pk_mul_f32 v[78:79], v[90:91], 1.0 op_sel:[1,0] op_sel_hi:[0,0] neg_lo:[1,0]
	v_pk_add_f32 v[90:91], v[92:93], v[78:79]
	v_pk_add_f32 v[78:79], v[92:93], v[78:79] neg_lo:[0,1] neg_hi:[0,1]
	v_pk_mul_f32 v[92:93], v[62:63], s[16:17]
	v_pk_fma_f32 v[76:77], v[76:77], s[66:67], v[84:85] op_sel:[0,0,1] op_sel_hi:[1,0,0]
	v_pk_fma_f32 v[62:63], v[62:63], s[66:67], v[92:93] op_sel:[0,0,1] op_sel_hi:[1,0,0] neg_lo:[1,0,0] neg_hi:[1,0,0]
	v_pk_add_f32 v[84:85], v[104:105], v[76:77]
	v_pk_add_f32 v[92:93], v[58:59], v[62:63]
	v_pk_add_f32 v[58:59], v[58:59], v[62:63] neg_lo:[0,1] neg_hi:[0,1]
	v_pk_mul_f32 v[62:63], v[70:71], s[62:63]
	v_pk_add_f32 v[76:77], v[104:105], v[76:77] neg_lo:[0,1] neg_hi:[0,1]
	v_pk_fma_f32 v[62:63], v[70:71], s[0:1], v[62:63] op_sel:[0,0,1] op_sel_hi:[1,0,0] neg_lo:[1,0,0] neg_hi:[1,0,0]
	v_pk_mul_f32 v[104:105], v[88:89], 1.0 op_sel:[1,0] op_sel_hi:[0,0] neg_lo:[1,0]
	v_pk_add_f32 v[70:71], v[66:67], v[62:63]
	v_pk_add_f32 v[62:63], v[66:67], v[62:63] neg_lo:[0,1] neg_hi:[0,1]
	v_pk_mul_f32 v[66:67], v[46:47], s[64:65]
	s_nop 0
	v_pk_fma_f32 v[46:47], v[46:47], s[16:17], v[66:67] op_sel:[0,0,1] op_sel_hi:[1,0,0] neg_lo:[1,0,0] neg_hi:[1,0,0]
	s_mov_b32 s73, s26
	v_pk_add_f32 v[66:67], v[42:43], v[46:47]
	v_pk_add_f32 v[42:43], v[42:43], v[46:47] neg_lo:[0,1] neg_hi:[0,1]
	v_pk_mul_f32 v[46:47], v[110:111], s[68:69]
	v_pk_add_f32 v[88:89], v[102:103], v[104:105]
	v_pk_fma_f32 v[46:47], v[110:111], s[8:9], v[46:47] op_sel:[0,0,1] op_sel_hi:[1,0,0]
	v_pk_add_f32 v[102:103], v[102:103], v[104:105] neg_lo:[0,1] neg_hi:[0,1]
	v_pk_add_f32 v[46:47], v[108:109], v[46:47]
	v_pk_mul_f32 v[108:109], v[100:101], s[64:65]
	v_pk_mul_f32 v[104:105], v[60:61], s[16:17]
	v_pk_fma_f32 v[100:101], v[100:101], s[16:17], v[108:109] op_sel:[0,0,1] op_sel_hi:[1,0,0]
	v_pk_fma_f32 v[60:61], v[60:61], s[66:67], v[104:105] op_sel:[0,0,1] op_sel_hi:[1,0,0] neg_lo:[1,0,0] neg_hi:[1,0,0]
	v_pk_add_f32 v[100:101], v[106:107], v[100:101]
	v_pk_mul_f32 v[106:107], v[86:87], s[72:73]
	v_pk_add_f32 v[104:105], v[56:57], v[60:61]
	v_pk_fma_f32 v[86:87], v[86:87], s[24:25], v[106:107] op_sel:[0,0,1] op_sel_hi:[1,0,0]
	v_pk_add_f32 v[56:57], v[56:57], v[60:61] neg_lo:[0,1] neg_hi:[0,1]
	v_pk_mul_f32 v[60:61], v[68:69], s[62:63]
	v_pk_add_f32 v[84:85], v[84:85], v[86:87]
	v_pk_mul_f32 v[86:87], v[90:91], s[62:63]
	v_pk_fma_f32 v[60:61], v[68:69], s[0:1], v[60:61] op_sel:[0,0,1] op_sel_hi:[1,0,0] neg_lo:[1,0,0] neg_hi:[1,0,0]
	v_pk_fma_f32 v[86:87], v[90:91], s[0:1], v[86:87] op_sel:[0,0,1] op_sel_hi:[1,0,0]
	v_pk_mul_f32 v[90:91], v[70:71], s[16:17]
	v_pk_add_f32 v[68:69], v[64:65], v[60:61]
	v_pk_fma_f32 v[70:71], v[70:71], s[66:67], v[90:91] op_sel:[0,0,1] op_sel_hi:[1,0,0]
	s_mov_b32 s9, s42
	s_mov_b32 s25, s38
	v_pk_add_f32 v[68:69], v[68:69], v[70:71]
	s_mov_b32 s76, s11
	v_pk_mul_f32 v[70:71], v[66:67], s[8:9]
	s_mov_b32 s74, s27
	v_pk_fma_f32 v[66:67], v[66:67], s[76:77], v[70:71] op_sel:[0,0,1] op_sel_hi:[1,0,0]
	v_pk_mul_f32 v[70:71], v[74:75], s[24:25]
	v_pk_add_f32 v[60:61], v[64:65], v[60:61] neg_lo:[0,1] neg_hi:[0,1]
	v_pk_fma_f32 v[70:71], v[74:75], s[74:75], v[70:71] op_sel:[0,0,1] op_sel_hi:[1,0,0] neg_lo:[1,0,0] neg_hi:[1,0,0]
	v_pk_mul_f32 v[64:65], v[44:45], s[64:65]
	v_pk_add_f32 v[70:71], v[76:77], v[70:71]
	v_pk_mul_f32 v[76:77], v[58:59], s[72:73]
	v_pk_fma_f32 v[44:45], v[44:45], s[16:17], v[64:65] op_sel:[0,0,1] op_sel_hi:[1,0,0] neg_lo:[1,0,0] neg_hi:[1,0,0]
	v_pk_fma_f32 v[58:59], v[58:59], s[24:25], v[76:77] op_sel:[0,0,1] op_sel_hi:[1,0,0] neg_lo:[1,0,0] neg_hi:[1,0,0]
	v_pk_add_f32 v[64:65], v[48:49], v[44:45]
	v_pk_add_f32 v[56:57], v[56:57], v[58:59]
	v_pk_mul_f32 v[58:59], v[62:63], s[64:65]
	v_pk_add_f32 v[44:45], v[48:49], v[44:45] neg_lo:[0,1] neg_hi:[0,1]
	v_pk_fma_f32 v[58:59], s[16:17], v[62:63], v[58:59] op_sel:[0,0,1] op_sel_hi:[0,1,0] neg_lo:[0,1,0] neg_hi:[0,1,0]
	v_pk_add_f32 v[58:59], v[60:61], v[58:59]
	v_pk_mul_f32 v[60:61], v[42:43], s[68:69]
	v_pk_add_f32 v[54:55], v[94:95], v[72:73] neg_lo:[0,1] neg_hi:[0,1]
	v_pk_add_f32 v[64:65], v[64:65], v[66:67]
	v_pk_add_f32 v[66:67], v[52:53], v[50:51] neg_lo:[0,1] neg_hi:[0,1]
	v_pk_fma_f32 v[42:43], v[42:43], s[8:9], v[60:61] op_sel:[0,0,1] op_sel_hi:[1,0,0] neg_lo:[1,0,0] neg_hi:[1,0,0]
	v_pk_add_f32 v[86:87], v[88:89], v[86:87]
	v_pk_mul_f32 v[88:89], v[92:93], s[24:25]
	v_pk_add_f32 v[48:49], v[54:55], v[66:67] op_sel:[0,1] op_sel_hi:[1,0] neg_lo:[0,1]
	v_pk_mul_f32 v[54:55], v[98:99], s[8:9]
	v_pk_mul_f32 v[66:67], v[82:83], s[16:17]
	v_pk_mul_f32 v[74:75], v[78:79], s[62:63]
	v_pk_add_f32 v[42:43], v[44:45], v[42:43]
	v_pk_add_f32 v[44:45], v[94:95], v[72:73]
	v_pk_add_f32 v[50:51], v[52:53], v[50:51]
	v_pk_fma_f32 v[88:89], v[92:93], s[74:75], v[88:89] op_sel:[0,0,1] op_sel_hi:[1,0,0]
	v_pk_fma_f32 v[54:55], v[98:99], s[76:77], v[54:55] op_sel:[0,0,1] op_sel_hi:[1,0,0] neg_lo:[1,0,0] neg_hi:[1,0,0]
	v_pk_fma_f32 v[66:67], v[82:83], s[66:67], v[66:67] op_sel:[0,0,1] op_sel_hi:[1,0,0] neg_lo:[1,0,0] neg_hi:[1,0,0]
	v_pk_fma_f32 v[74:75], v[78:79], s[0:1], v[74:75] op_sel:[0,0,1] op_sel_hi:[1,0,0] neg_lo:[1,0,0] neg_hi:[1,0,0]
	v_pk_add_f32 v[44:45], v[44:45], v[50:51]
	v_lshl_add_u32 v21, v21, 3, v36
	v_pk_add_f32 v[88:89], v[104:105], v[88:89]
	v_pk_add_f32 v[54:55], v[96:97], v[54:55]
	v_pk_add_f32 v[66:67], v[80:81], v[66:67]
	v_pk_add_f32 v[74:75], v[102:103], v[74:75]
	ds_write_b64 v25, v[44:45]
	ds_write_b64 v25, v[46:47] offset:2112
	ds_write_b64 v25, v[100:101] offset:4224
	ds_write_b64 v25, v[84:85] offset:6336
	ds_write_b64 v25, v[86:87] offset:8448
	ds_write_b64 v25, v[88:89] offset:10560
	ds_write_b64 v25, v[68:69] offset:12672
	ds_write_b64 v25, v[64:65] offset:14784
	ds_write_b64 v25, v[48:49] offset:16896
	ds_write_b64 v25, v[54:55] offset:19008
	ds_write_b64 v25, v[66:67] offset:21120
	ds_write_b64 v25, v[70:71] offset:23232
	ds_write_b64 v25, v[74:75] offset:25344
	ds_write_b64 v25, v[56:57] offset:27456
	ds_write_b64 v25, v[58:59] offset:29568
	ds_write_b64 v25, v[42:43] offset:31680
	v_ashrrev_i32_e32 v25, 5, v21
	v_lshlrev_b32_e32 v21, 3, v21
	v_lshlrev_b32_e32 v25, 3, v25
	s_waitcnt vmcnt(0)
	v_lshlrev_b32_e32 v41, 16, v41
	v_lshlrev_b32_e32 v39, 16, v39
	v_lshlrev_b32_e32 v35, 16, v35
	v_lshlrev_b32_e32 v29, 16, v29
	v_and_b32_e32 v48, 0xffff0000, v14
	v_add3_u32 v21, 0, v21, v25
	v_mov_b32_e32 v40, v48
	s_waitcnt lgkmcnt(0)
	s_barrier
	v_pk_mul_f32 v[44:45], v[30:31], v[40:41]
	ds_read2_b64 v[40:43], v21 offset1:1
	v_lshlrev_b32_e32 v28, 16, v14
	v_lshlrev_b32_e32 v49, 16, v15
	v_pk_fma_f32 v[44:45], v[30:31], v[28:29], v[44:45] op_sel:[0,0,1] op_sel_hi:[1,0,0]
	v_mov_b32_e32 v28, v31
	v_pk_fma_f32 v[44:45], v[20:21], v[48:49], v[44:45] op_sel_hi:[0,1,1]
	v_pk_add_f32 v[50:51], v[24:25], v[44:45] op_sel_hi:[0,1]
	ds_read2_b64 v[44:47], v21 offset0:2 offset1:3
	s_waitcnt lgkmcnt(1)
	v_pk_mul_f32 v[40:41], v[50:51], v[40:41]
	v_and_b32_e32 v51, 16, v16
	v_and_b32_e32 v50, 0xffff0000, v15
	v_pk_mov_b32 v[14:15], v[48:49], v[50:51] op_sel:[1,0]
	v_lshlrev_b32_e32 v53, 16, v16
	v_pk_mul_f32 v[14:15], v[30:31], v[14:15] op_sel_hi:[0,1]
	v_mov_b32_e32 v52, v50
	v_pk_fma_f32 v[14:15], v[28:29], v[48:49], v[14:15] op_sel_hi:[0,1,1]
	v_pk_fma_f32 v[14:15], v[20:21], v[52:53], v[14:15] op_sel_hi:[0,1,1]
	v_pk_add_f32 v[14:15], v[24:25], v[14:15] op_sel_hi:[0,1]
	v_pk_mul_f32 v[14:15], v[14:15], v[42:43]
	v_and_b32_e32 v43, 16, v17
	v_and_b32_e32 v42, 0xffff0000, v16
	v_lshlrev_b32_e32 v49, 16, v17
	v_mov_b32_e32 v48, v42
	v_pk_mov_b32 v[42:43], v[52:53], v[42:43] op_sel:[1,0]
	v_pk_mov_b32 v[16:17], v[16:17], v[10:11] op_sel:[1,0]
	v_pk_mul_f32 v[42:43], v[30:31], v[42:43] op_sel_hi:[0,1]
	v_and_b32_e32 v17, 16, v17
	v_and_b32_e32 v16, 0xffff0000, v16
	v_pk_fma_f32 v[42:43], v[28:29], v[52:53], v[42:43] op_sel_hi:[0,1,1]
	v_mov_b32_e32 v50, v16
	v_pk_mov_b32 v[16:17], v[48:49], v[16:17] op_sel:[1,0]
	v_pk_fma_f32 v[42:43], v[20:21], v[48:49], v[42:43] op_sel_hi:[0,1,1]
	v_pk_mul_f32 v[16:17], v[30:31], v[16:17] op_sel_hi:[0,1]
	v_pk_add_f32 v[42:43], v[24:25], v[42:43] op_sel_hi:[0,1]
	v_lshlrev_b32_e32 v51, 16, v10
	v_pk_fma_f32 v[16:17], v[28:29], v[48:49], v[16:17] op_sel_hi:[0,1,1]
	s_waitcnt lgkmcnt(0)
	v_pk_mul_f32 v[42:43], v[42:43], v[44:45]
	v_pk_fma_f32 v[16:17], v[20:21], v[50:51], v[16:17] op_sel_hi:[0,1,1]
	v_and_b32_e32 v45, 16, v11
	v_and_b32_e32 v44, 0xffff0000, v10
	v_pk_add_f32 v[16:17], v[24:25], v[16:17] op_sel_hi:[0,1]
	v_mov_b32_e32 v52, v44
	v_pk_mov_b32 v[44:45], v[50:51], v[44:45] op_sel:[1,0]
	v_pk_mul_f32 v[16:17], v[16:17], v[46:47]
	v_pk_mul_f32 v[48:49], v[30:31], v[44:45] op_sel_hi:[0,1]
	ds_read2_b64 v[44:47], v21 offset0:4 offset1:5
	v_lshlrev_b32_e32 v53, 16, v11
	v_pk_fma_f32 v[48:49], v[28:29], v[50:51], v[48:49] op_sel_hi:[0,1,1]
	v_pk_fma_f32 v[48:49], v[20:21], v[52:53], v[48:49] op_sel_hi:[0,1,1]
	v_pk_add_f32 v[54:55], v[24:25], v[48:49] op_sel_hi:[0,1]
	ds_read2_b64 v[48:51], v21 offset0:6 offset1:7
	s_waitcnt lgkmcnt(1)
	v_pk_mul_f32 v[44:45], v[54:55], v[44:45]
	v_and_b32_e32 v55, 16, v12
	v_and_b32_e32 v54, 0xffff0000, v11
	v_pk_mov_b32 v[10:11], v[52:53], v[54:55] op_sel:[1,0]
	v_lshlrev_b32_e32 v57, 16, v12
	v_pk_mul_f32 v[10:11], v[30:31], v[10:11] op_sel_hi:[0,1]
	v_mov_b32_e32 v56, v54
	v_pk_fma_f32 v[10:11], v[28:29], v[52:53], v[10:11] op_sel_hi:[0,1,1]
	v_pk_fma_f32 v[10:11], v[20:21], v[56:57], v[10:11] op_sel_hi:[0,1,1]
	v_pk_add_f32 v[10:11], v[24:25], v[10:11] op_sel_hi:[0,1]
	v_and_b32_e32 v38, 0xffff0000, v13
	v_pk_mul_f32 v[10:11], v[10:11], v[46:47]
	v_and_b32_e32 v47, 16, v13
	v_and_b32_e32 v46, 0xffff0000, v12
	v_lshlrev_b32_e32 v53, 16, v13
	v_mov_b32_e32 v52, v46
	v_pk_mov_b32 v[12:13], v[56:57], v[46:47] op_sel:[1,0]
	v_pk_mov_b32 v[46:47], v[52:53], v[38:39] op_sel:[1,0]
	v_pk_mul_f32 v[12:13], v[30:31], v[12:13] op_sel_hi:[0,1]
	v_pk_mul_f32 v[46:47], v[30:31], v[46:47] op_sel_hi:[0,1]
	v_pk_fma_f32 v[12:13], v[28:29], v[56:57], v[12:13] op_sel_hi:[0,1,1]
	v_pk_fma_f32 v[46:47], v[28:29], v[52:53], v[46:47] op_sel_hi:[0,1,1]
	v_pk_fma_f32 v[12:13], v[20:21], v[52:53], v[12:13] op_sel_hi:[0,1,1]
	v_pk_fma_f32 v[38:39], v[20:21], v[38:39], v[46:47] op_sel_hi:[0,1,1]
	s_xor_b64 s[50:51], s[50:51], -1
	v_pk_add_f32 v[12:13], v[24:25], v[12:13] op_sel_hi:[0,1]
	v_pk_add_f32 v[38:39], v[24:25], v[38:39] op_sel_hi:[0,1]
	s_waitcnt lgkmcnt(0)
	v_pk_mul_f32 v[12:13], v[12:13], v[48:49]
	v_pk_mul_f32 v[38:39], v[38:39], v[50:51]
	s_mov_b64 s[0:1], -1
	s_and_b64 vcc, exec, s[50:51]
	s_cbranch_vccz .LBB0_548
	v_bfe_u32 v46, v15, 16, 1
	v_add3_u32 v47, v15, v46, s4
	v_bfe_u32 v46, v14, 16, 1
	v_bfe_u32 v48, v16, 16, 1
	v_bfe_u32 v50, v42, 16, 1
	v_bfe_u32 v34, v17, 16, 1
	v_bfe_u32 v49, v40, 16, 1
	v_add3_u32 v50, v42, v50, s4
	v_add3_u32 v48, v16, v48, s4
	v_add3_u32 v46, v14, v46, s4
	v_bfe_u32 v25, v43, 16, 1
	v_bfe_u32 v28, v41, 16, 1
	v_add3_u32 v34, v17, v34, s4
	v_add3_u32 v49, v40, v49, s4
	v_lshrrev_b32_e32 v51, 16, v46
	v_lshrrev_b32_e32 v52, 16, v48
	v_lshrrev_b32_e32 v48, 16, v50
	v_bfe_u32 v50, v11, 16, 1
	v_add3_u32 v28, v41, v28, s4
	v_add3_u32 v25, v43, v25, s4
	v_lshrrev_b32_e32 v46, 16, v49
	v_and_or_b32 v49, v34, s91, v52
	v_and_or_b32 v47, v47, s91, v51
	v_add3_u32 v51, v11, v50, s4
	v_bfe_u32 v50, v10, 16, 1
	v_bfe_u32 v52, v38, 16, 1
	v_bfe_u32 v53, v44, 16, 1
	v_bfe_u32 v54, v12, 16, 1
	v_lshl_add_u64 v[36:37], v[36:37], 1, s[70:71]
	v_and_or_b32 v48, v25, s91, v48
	v_and_or_b32 v46, v28, s91, v46
	v_bfe_u32 v25, v13, 16, 1
	v_bfe_u32 v28, v45, 16, 1
	v_bfe_u32 v34, v39, 16, 1
	v_add3_u32 v54, v12, v54, s4
	v_add3_u32 v53, v44, v53, s4
	v_add3_u32 v52, v38, v52, s4
	v_add3_u32 v50, v10, v50, s4
	v_add3_u32 v34, v39, v34, s4
	v_add3_u32 v28, v45, v28, s4
	v_add3_u32 v25, v13, v25, s4
	v_lshrrev_b32_e32 v55, 16, v50
	v_lshrrev_b32_e32 v56, 16, v52
	v_lshrrev_b32_e32 v50, 16, v53
	v_lshrrev_b32_e32 v52, 16, v54
	v_lshl_add_u64 v[32:33], v[32:33], 1, v[36:37]
	v_and_or_b32 v52, v25, s91, v52
	v_and_or_b32 v50, v28, s91, v50
	v_and_or_b32 v53, v34, s91, v56
	v_and_or_b32 v51, v51, s91, v55
	global_store_dwordx4 v[32:33], v[46:49], off
	global_store_dwordx4 v[32:33], v[50:53], off offset:16
	s_mov_b64 s[0:1], 0

.LBB0_550:
	v_lshl_add_u32 v10, v18, 3, v26
	v_ashrrev_i32_e32 v11, 5, v10
	v_lshlrev_b32_e32 v10, 3, v10
	v_lshlrev_b32_e32 v11, 3, v11
	v_add3_u32 v18, 0, v10, v11
	s_waitcnt vmcnt(0)
	v_and_b32_e32 v32, 0xffff0000, v6
	v_mov_b32_e32 v34, v32
	ds_read2_b64 v[10:13], v18 offset1:1
	v_lshlrev_b32_e32 v14, 16, v6
	v_pk_mul_f32 v[16:17], v[30:31], v[34:35]
	v_mov_b32_e32 v21, v20
	v_lshlrev_b32_e32 v33, 16, v7
	v_pk_fma_f32 v[14:15], v[30:31], v[14:15], v[16:17] op_sel:[0,0,1] op_sel_hi:[1,0,0]
	v_mov_b32_e32 v25, v24
	v_pk_fma_f32 v[14:15], v[20:21], v[32:33], v[14:15]
	v_pk_mov_b32 v[36:37], v[30:31], v[30:31] op_sel:[0,0]
	v_pk_mov_b32 v[38:39], v[30:31], v[30:31] op_sel:[1,1]
	v_pk_add_f32 v[30:31], v[24:25], v[14:15]
	ds_read2_b64 v[14:17], v18 offset0:2 offset1:3
	s_waitcnt lgkmcnt(1)
	v_pk_mul_f32 v[10:11], v[30:31], v[10:11]
	v_and_b32_e32 v31, 16, v8
	v_and_b32_e32 v30, 0xffff0000, v7
	v_pk_mov_b32 v[6:7], v[32:33], v[30:31] op_sel:[1,0]
	v_lshlrev_b32_e32 v35, 16, v8
	v_pk_mul_f32 v[6:7], v[36:37], v[6:7]
	v_mov_b32_e32 v34, v30
	v_pk_fma_f32 v[6:7], v[38:39], v[32:33], v[6:7]
	v_lshlrev_b32_e32 v31, 16, v9
	v_pk_fma_f32 v[6:7], v[20:21], v[34:35], v[6:7]
	v_lshlrev_b32_e32 v33, 16, v2
	v_pk_add_f32 v[6:7], v[24:25], v[6:7]
	v_lshlrev_b32_e32 v43, 16, v4
	v_pk_mul_f32 v[6:7], v[6:7], v[12:13]
	v_and_b32_e32 v13, 16, v9
	v_and_b32_e32 v12, 0xffff0000, v8
	v_mov_b32_e32 v30, v12
	v_pk_mov_b32 v[12:13], v[34:35], v[12:13] op_sel:[1,0]
	v_pk_mov_b32 v[8:9], v[8:9], v[2:3] op_sel:[1,0]
	v_pk_mul_f32 v[12:13], v[36:37], v[12:13]
	v_and_b32_e32 v9, 16, v9
	v_and_b32_e32 v8, 0xffff0000, v8
	v_pk_fma_f32 v[12:13], v[38:39], v[34:35], v[12:13]
	v_mov_b32_e32 v32, v8
	v_pk_mov_b32 v[8:9], v[30:31], v[8:9] op_sel:[1,0]
	v_pk_fma_f32 v[12:13], v[20:21], v[30:31], v[12:13]
	v_pk_mul_f32 v[8:9], v[36:37], v[8:9]
	v_pk_add_f32 v[12:13], v[24:25], v[12:13]
	v_pk_fma_f32 v[8:9], v[38:39], v[30:31], v[8:9]
	s_waitcnt lgkmcnt(0)
	v_pk_mul_f32 v[12:13], v[12:13], v[14:15]
	v_pk_fma_f32 v[8:9], v[20:21], v[32:33], v[8:9]
	v_and_b32_e32 v15, 16, v3
	v_and_b32_e32 v14, 0xffff0000, v2
	v_pk_add_f32 v[8:9], v[24:25], v[8:9]
	v_mov_b32_e32 v34, v14
	v_pk_mov_b32 v[14:15], v[32:33], v[14:15] op_sel:[1,0]
	v_pk_mul_f32 v[8:9], v[8:9], v[16:17]
	v_pk_mul_f32 v[30:31], v[36:37], v[14:15]
	ds_read2_b64 v[14:17], v18 offset0:4 offset1:5
	v_lshlrev_b32_e32 v35, 16, v3
	v_pk_fma_f32 v[30:31], v[38:39], v[32:33], v[30:31]
	v_and_b32_e32 v28, 0xffff0000, v5
	v_pk_fma_f32 v[30:31], v[20:21], v[34:35], v[30:31]
	s_andn2_b64 vcc, exec, s[50:51]
	v_pk_add_f32 v[40:41], v[24:25], v[30:31]
	ds_read2_b64 v[30:33], v18 offset0:6 offset1:7
	s_waitcnt lgkmcnt(1)
	v_pk_mul_f32 v[14:15], v[40:41], v[14:15]
	v_and_b32_e32 v41, 16, v4
	v_and_b32_e32 v40, 0xffff0000, v3
	v_pk_mov_b32 v[2:3], v[34:35], v[40:41] op_sel:[1,0]
	v_mov_b32_e32 v42, v40
	v_pk_mul_f32 v[2:3], v[36:37], v[2:3]
	s_nop 0
	v_pk_fma_f32 v[2:3], v[38:39], v[34:35], v[2:3]
	v_lshlrev_b32_e32 v35, 16, v5
	v_pk_fma_f32 v[2:3], v[20:21], v[42:43], v[2:3]
	s_nop 0
	v_pk_add_f32 v[2:3], v[24:25], v[2:3]
	s_nop 0
	v_pk_mul_f32 v[2:3], v[2:3], v[16:17]
	v_and_b32_e32 v17, 16, v5
	v_and_b32_e32 v16, 0xffff0000, v4
	v_mov_b32_e32 v34, v16
	v_pk_mov_b32 v[4:5], v[42:43], v[16:17] op_sel:[1,0]
	v_pk_mov_b32 v[16:17], v[34:35], v[28:29] op_sel:[1,0]
	v_pk_mul_f32 v[4:5], v[36:37], v[4:5]
	v_pk_mul_f32 v[16:17], v[36:37], v[16:17]
	v_pk_fma_f32 v[4:5], v[38:39], v[42:43], v[4:5]
	v_pk_fma_f32 v[16:17], v[38:39], v[34:35], v[16:17]
	v_pk_fma_f32 v[4:5], v[20:21], v[34:35], v[4:5]
	v_pk_fma_f32 v[16:17], v[20:21], v[28:29], v[16:17]
	v_pk_add_f32 v[4:5], v[24:25], v[4:5]
	v_pk_add_f32 v[16:17], v[24:25], v[16:17]
	v_cndmask_b32_e64 v20, 0, 1, s[50:51]
	s_waitcnt lgkmcnt(0)
	v_pk_mul_f32 v[4:5], v[4:5], v[30:31]
	v_pk_mul_f32 v[16:17], v[16:17], v[32:33]
	v_cmp_ne_u32_e64 s[0:1], 1, v20
	s_mov_b64 s[50:51], -1
	s_cbranch_vccnz .LBB0_552
	v_lshl_add_u64 v[20:21], v[26:27], 1, s[70:71]
	v_bfe_u32 v26, v9, 16, 1
	v_bfe_u32 v27, v7, 16, 1
	v_add3_u32 v28, v7, v27, s4
	v_add3_u32 v27, v9, v26, s4
	v_bfe_u32 v26, v6, 16, 1
	v_bfe_u32 v30, v10, 16, 1
	v_bfe_u32 v31, v12, 16, 1
	v_bfe_u32 v24, v13, 16, 1
	v_bfe_u32 v25, v11, 16, 1
	v_add3_u32 v31, v12, v31, s4
	v_add3_u32 v30, v10, v30, s4
	v_add3_u32 v26, v6, v26, s4
	v_add3_u32 v25, v11, v25, s4
	v_add3_u32 v24, v13, v24, s4
	v_bfe_u32 v29, v8, 16, 1
	v_lshrrev_b32_e32 v32, 16, v26
	v_lshrrev_b32_e32 v30, 16, v30
	v_lshrrev_b32_e32 v26, 16, v31
	v_add3_u32 v29, v8, v29, s4
	v_and_or_b32 v26, v24, s91, v26
	v_and_or_b32 v24, v25, s91, v30
	v_bfe_u32 v30, v17, 16, 1
	v_bfe_u32 v31, v3, 16, 1
	v_lshrrev_b32_e32 v29, 16, v29
	v_and_or_b32 v25, v28, s91, v32
	v_add3_u32 v32, v3, v31, s4
	v_add3_u32 v31, v17, v30, s4
	v_bfe_u32 v30, v2, 16, 1
	v_bfe_u32 v33, v16, 16, 1
	v_bfe_u32 v34, v14, 16, 1
	v_bfe_u32 v35, v4, 16, 1
	v_and_or_b32 v27, v27, s91, v29
	v_bfe_u32 v28, v5, 16, 1
	v_bfe_u32 v29, v15, 16, 1
	v_add3_u32 v35, v4, v35, s4
	v_add3_u32 v34, v14, v34, s4
	v_add3_u32 v33, v16, v33, s4
	v_add3_u32 v30, v2, v30, s4
	v_add3_u32 v29, v15, v29, s4
	v_add3_u32 v28, v5, v28, s4
	v_lshrrev_b32_e32 v36, 16, v30
	v_lshrrev_b32_e32 v33, 16, v33
	v_lshrrev_b32_e32 v34, 16, v34
	v_lshrrev_b32_e32 v30, 16, v35
	v_lshl_add_u64 v[20:21], v[22:23], 1, v[20:21]
	s_mov_b64 s[50:51], 0
	v_and_or_b32 v30, v28, s91, v30
	v_and_or_b32 v28, v29, s91, v34
	v_and_or_b32 v31, v31, s91, v33
	v_and_or_b32 v29, v32, s91, v36
	global_store_dwordx4 v[20:21], v[24:27], off
	global_store_dwordx4 v[20:21], v[28:31], off offset:16

.LBB0_560:
	s_or_b64 exec, exec, s[0:1]
	v_mov_b32_e32 v2, v142
	s_waitcnt lgkmcnt(0)
	s_barrier
	s_mov_b32 s41, s38
	v_and_b32_e32 v4, 0x1ff, v2
	v_lshlrev_b32_e32 v2, 5, v2
	v_and_or_b32 v2, v2, s34, v4
	v_ashrrev_i32_e32 v6, 5, v2
	v_lshlrev_b32_e32 v2, 3, v2
	v_lshlrev_b32_e32 v7, 3, v6
	v_add3_u32 v2, 0, v2, v7
	v_add_u32_e32 v143, 0x10800, v2
	ds_read_b64 v[128:129], v2
	ds_read_b64 v[130:131], v2 offset:4224
	ds_read_b64 v[144:145], v2 offset:8448
	ds_read_b64 v[148:149], v2 offset:12672
	ds_read_b64 v[150:151], v2 offset:16896
	ds_read_b64 v[152:153], v2 offset:21120
	ds_read_b64 v[154:155], v2 offset:25344
	ds_read_b64 v[156:157], v2 offset:29568
	ds_read_b64 v[158:159], v2 offset:33792
	ds_read_b64 v[160:161], v2 offset:38016
	ds_read_b64 v[162:163], v2 offset:42240
	ds_read_b64 v[164:165], v2 offset:46464
	ds_read_b64 v[166:167], v2 offset:50688
	ds_read_b64 v[168:169], v2 offset:54912
	ds_read_b64 v[170:171], v2 offset:59136
	ds_read_b64 v[172:173], v2 offset:63360
	v_add_u32_e32 v212, 0x11880, v2
	v_add_u32_e32 v213, 0x12900, v2
	v_add_u32_e32 v214, 0x13980, v2
	ds_read_b64 v[174:175], v143
	ds_read_b64 v[176:177], v212
	ds_read_b64 v[178:179], v213
	ds_read_b64 v[180:181], v214
	v_add_u32_e32 v215, 0x14a00, v2
	s_waitcnt lgkmcnt(3)
	v_pk_add_f32 v[210:211], v[128:129], v[174:175]
	v_pk_add_f32 v[128:129], v[128:129], v[174:175] neg_lo:[0,1] neg_hi:[0,1]
	s_waitcnt lgkmcnt(2)
	v_pk_add_f32 v[174:175], v[130:131], v[176:177]
	v_pk_add_f32 v[130:131], v[130:131], v[176:177] neg_lo:[0,1] neg_hi:[0,1]
	v_add_u32_e32 v216, 0x15a80, v2
	v_pk_mul_f32 v[176:177], v[130:131], s[20:21]
	v_add_u32_e32 v217, 0x16b00, v2
	v_pk_fma_f32 v[130:131], v[130:131], s[10:11], v[176:177] op_sel:[0,0,1] op_sel_hi:[1,0,0]
	s_waitcnt lgkmcnt(1)
	v_pk_add_f32 v[176:177], v[144:145], v[178:179]
	v_pk_add_f32 v[144:145], v[144:145], v[178:179] neg_lo:[0,1] neg_hi:[0,1]
	v_add_u32_e32 v218, 0x17b80, v2
	v_pk_mul_f32 v[178:179], v[144:145], s[24:25]
	ds_read_b64 v[182:183], v215
	ds_read_b64 v[184:185], v216
	ds_read_b64 v[186:187], v217
	ds_read_b64 v[188:189], v218
	v_pk_fma_f32 v[144:145], v[144:145], s[22:23], v[178:179] op_sel:[0,0,1] op_sel_hi:[1,0,0]
	s_waitcnt lgkmcnt(4)
	v_pk_add_f32 v[178:179], v[148:149], v[180:181]
	v_pk_add_f32 v[148:149], v[148:149], v[180:181] neg_lo:[0,1] neg_hi:[0,1]
	s_mov_b32 s43, s26
	v_pk_mul_f32 v[180:181], v[148:149], s[36:37]
	s_mov_b32 s0, s37
	v_pk_fma_f32 v[148:149], v[148:149], s[26:27], v[180:181] op_sel:[0,0,1] op_sel_hi:[1,0,0]
	s_waitcnt lgkmcnt(3)
	v_pk_add_f32 v[180:181], v[150:151], v[182:183]
	v_pk_add_f32 v[150:151], v[150:151], v[182:183] neg_lo:[0,1] neg_hi:[0,1]
	s_mov_b32 s45, s22
	v_pk_mul_f32 v[182:183], v[150:151], s[40:41]
	v_add_u32_e32 v219, 0x18c00, v2
	v_pk_fma_f32 v[150:151], v[150:151], s[38:39], v[182:183] op_sel:[0,0,1] op_sel_hi:[1,0,0]
	s_waitcnt lgkmcnt(2)
	v_pk_add_f32 v[182:183], v[152:153], v[184:185]
	v_pk_add_f32 v[152:153], v[152:153], v[184:185] neg_lo:[0,1] neg_hi:[0,1]
	s_mov_b32 s50, s25
	v_pk_mul_f32 v[184:185], v[152:153], s[42:43]
	v_add_u32_e32 v220, 0x19c80, v2
	v_pk_fma_f32 v[152:153], v[152:153], s[0:1], v[184:185] op_sel:[0,0,1] op_sel_hi:[1,0,0]
	s_waitcnt lgkmcnt(1)
	v_pk_add_f32 v[184:185], v[154:155], v[186:187]
	v_pk_add_f32 v[154:155], v[154:155], v[186:187] neg_lo:[0,1] neg_hi:[0,1]
	v_add_u32_e32 v221, 0x1ad00, v2
	v_pk_mul_f32 v[186:187], v[154:155], s[44:45]
	v_add_u32_e32 v222, 0x1bd80, v2
	ds_read_b64 v[190:191], v219
	ds_read_b64 v[192:193], v220
	ds_read_b64 v[194:195], v221
	ds_read_b64 v[196:197], v222
	v_pk_fma_f32 v[154:155], v[154:155], s[50:51], v[186:187] op_sel:[0,0,1] op_sel_hi:[1,0,0]
	s_waitcnt lgkmcnt(4)
	v_pk_add_f32 v[186:187], v[156:157], v[188:189]
	v_pk_add_f32 v[156:157], v[156:157], v[188:189] neg_lo:[0,1] neg_hi:[0,1]
	v_add_u32_e32 v223, 0x1ce00, v2
	v_pk_mul_f32 v[188:189], v[156:157], s[8:9]
	v_add_u32_e32 v224, 0x1de80, v2
	v_pk_fma_f32 v[156:157], v[156:157], s[16:17], v[188:189] op_sel:[0,0,1] op_sel_hi:[1,0,0]
	s_waitcnt lgkmcnt(3)
	v_pk_add_f32 v[188:189], v[158:159], v[190:191]
	v_pk_add_f32 v[190:191], v[158:159], v[190:191] neg_lo:[0,1] neg_hi:[0,1]
	v_add_u32_e32 v225, 0x1ef00, v2
	s_waitcnt lgkmcnt(2)
	v_pk_add_f32 v[158:159], v[160:161], v[192:193]
	v_pk_add_f32 v[160:161], v[160:161], v[192:193] neg_lo:[0,1] neg_hi:[0,1]
	v_add_u32_e32 v226, 0x1ff80, v2
	v_pk_mul_f32 v[192:193], v[160:161], s[8:9]
	ds_read_b64 v[198:199], v223
	ds_read_b64 v[204:205], v224
	ds_read_b64 v[206:207], v225
	ds_read_b64 v[208:209], v226
	v_pk_fma_f32 v[160:161], v[160:161], s[16:17], v[192:193] op_sel:[0,0,1] op_sel_hi:[1,0,0] neg_lo:[1,0,0] neg_hi:[1,0,0]
	s_waitcnt lgkmcnt(5)
	v_pk_add_f32 v[192:193], v[162:163], v[194:195]
	v_pk_add_f32 v[162:163], v[162:163], v[194:195] neg_lo:[0,1] neg_hi:[0,1]
	v_cvt_f32_u32_e32 v5, v4
	v_pk_mul_f32 v[194:195], v[162:163], s[44:45]
	v_mul_f32_e32 v5, 0x38800000, v5
	v_pk_fma_f32 v[162:163], v[162:163], s[50:51], v[194:195] op_sel:[0,0,1] op_sel_hi:[1,0,0] neg_lo:[1,0,0] neg_hi:[1,0,0]
	s_waitcnt lgkmcnt(4)
	v_pk_add_f32 v[194:195], v[164:165], v[196:197]
	v_pk_add_f32 v[164:165], v[164:165], v[196:197] neg_lo:[0,1] neg_hi:[0,1]
	v_sin_f32_e32 v4, v5
	v_pk_mul_f32 v[196:197], v[164:165], s[42:43]
	v_cos_f32_e32 v6, v5
	v_pk_fma_f32 v[164:165], v[164:165], s[0:1], v[196:197] op_sel:[0,0,1] op_sel_hi:[1,0,0] neg_lo:[1,0,0] neg_hi:[1,0,0]
	s_waitcnt lgkmcnt(3)
	v_pk_add_f32 v[196:197], v[166:167], v[198:199]
	v_pk_add_f32 v[166:167], v[166:167], v[198:199] neg_lo:[0,1] neg_hi:[0,1]
	v_xor_b32_e32 v7, 0x80000000, v4
	v_pk_mul_f32 v[198:199], v[166:167], s[40:41]
	v_mov_b32_e32 v5, v7
	v_pk_fma_f32 v[166:167], v[166:167], s[38:39], v[198:199] op_sel:[0,0,1] op_sel_hi:[1,0,0] neg_lo:[1,0,0] neg_hi:[1,0,0]
	s_waitcnt lgkmcnt(2)
	v_pk_add_f32 v[198:199], v[168:169], v[204:205]
	v_pk_add_f32 v[168:169], v[168:169], v[204:205] neg_lo:[0,1] neg_hi:[0,1]
	v_pk_mul_f32 v[8:9], v[6:7], v[4:5] op_sel:[1,0] op_sel_hi:[0,1]
	v_pk_mul_f32 v[204:205], v[168:169], s[36:37]
	v_pk_fma_f32 v[8:9], v[6:7], v[6:7], v[8:9] op_sel_hi:[1,0,1]
	v_pk_fma_f32 v[168:169], v[168:169], s[26:27], v[204:205] op_sel:[0,0,1] op_sel_hi:[1,0,0] neg_lo:[1,0,0] neg_hi:[1,0,0]
	s_waitcnt lgkmcnt(1)
	v_pk_add_f32 v[204:205], v[170:171], v[206:207]
	v_pk_add_f32 v[170:171], v[170:171], v[206:207] neg_lo:[0,1] neg_hi:[0,1]
	v_pk_mul_f32 v[14:15], v[8:9], 1.0 op_sel:[1,0] op_sel_hi:[1,0] neg_lo:[1,0]
	v_pk_mul_f32 v[206:207], v[170:171], s[24:25]
	s_nop 0
	v_pk_fma_f32 v[170:171], v[170:171], s[22:23], v[206:207] op_sel:[0,0,1] op_sel_hi:[1,0,0] neg_lo:[1,0,0] neg_hi:[1,0,0]
	s_waitcnt lgkmcnt(0)
	v_pk_add_f32 v[206:207], v[172:173], v[208:209]
	v_pk_add_f32 v[172:173], v[172:173], v[208:209] neg_lo:[0,1] neg_hi:[0,1]
	v_pk_mul_f32 v[12:13], v[8:9], v[14:15] op_sel:[1,0] op_sel_hi:[0,1]
	v_pk_mul_f32 v[208:209], v[172:173], s[20:21]
	v_pk_fma_f32 v[12:13], v[8:9], v[8:9], v[12:13] op_sel_hi:[1,0,1]
	v_pk_fma_f32 v[172:173], v[172:173], s[10:11], v[208:209] op_sel:[0,0,1] op_sel_hi:[1,0,0] neg_lo:[1,0,0] neg_hi:[1,0,0]
	v_pk_add_f32 v[208:209], v[210:211], v[188:189]
	v_pk_add_f32 v[188:189], v[210:211], v[188:189] neg_lo:[0,1] neg_hi:[0,1]
	v_pk_add_f32 v[210:211], v[174:175], v[158:159]
	v_pk_add_f32 v[158:159], v[174:175], v[158:159] neg_lo:[0,1] neg_hi:[0,1]
	v_pk_mul_f32 v[16:17], v[12:13], 1.0 op_sel:[1,0] op_sel_hi:[1,0] neg_lo:[1,0]
	v_pk_mul_f32 v[174:175], v[158:159], s[24:25]
	s_nop 0
	v_pk_fma_f32 v[158:159], v[158:159], s[22:23], v[174:175] op_sel:[0,0,1] op_sel_hi:[1,0,0]
	v_pk_add_f32 v[174:175], v[176:177], v[192:193]
	v_pk_add_f32 v[176:177], v[176:177], v[192:193] neg_lo:[0,1] neg_hi:[0,1]
	v_pk_mul_f32 v[28:29], v[12:13], v[16:17] op_sel:[1,0] op_sel_hi:[0,1]
	v_pk_mul_f32 v[192:193], v[176:177], s[40:41]
	v_pk_fma_f32 v[28:29], v[12:13], v[12:13], v[28:29] op_sel_hi:[1,0,1]
	v_pk_fma_f32 v[176:177], v[176:177], s[38:39], v[192:193] op_sel:[0,0,1] op_sel_hi:[1,0,0]
	v_pk_add_f32 v[192:193], v[178:179], v[194:195]
	v_pk_add_f32 v[178:179], v[178:179], v[194:195] neg_lo:[0,1] neg_hi:[0,1]
	v_pk_mul_f32 v[44:45], v[16:17], v[28:29] op_sel:[0,1] op_sel_hi:[1,0]
	v_pk_mul_f32 v[194:195], v[178:179], s[44:45]
	v_pk_fma_f32 v[44:45], v[12:13], v[28:29], v[44:45] op_sel_hi:[0,1,1]
	v_pk_fma_f32 v[178:179], v[178:179], s[50:51], v[194:195] op_sel:[0,0,1] op_sel_hi:[1,0,0]
	v_pk_add_f32 v[194:195], v[180:181], v[196:197]
	v_pk_add_f32 v[196:197], v[180:181], v[196:197] neg_lo:[0,1] neg_hi:[0,1]
	v_pk_mul_f32 v[60:61], v[16:17], v[44:45] op_sel:[0,1] op_sel_hi:[1,0]
	v_pk_add_f32 v[180:181], v[182:183], v[198:199]
	v_pk_add_f32 v[182:183], v[182:183], v[198:199] neg_lo:[0,1] neg_hi:[0,1]
	v_pk_fma_f32 v[60:61], v[12:13], v[44:45], v[60:61] op_sel_hi:[0,1,1]
	v_pk_mul_f32 v[198:199], v[182:183], s[44:45]
	v_pk_mul_f32 v[76:77], v[16:17], v[60:61] op_sel:[0,1] op_sel_hi:[1,0]
	v_pk_fma_f32 v[182:183], v[182:183], s[50:51], v[198:199] op_sel:[0,0,1] op_sel_hi:[1,0,0] neg_lo:[1,0,0] neg_hi:[1,0,0]
	v_pk_add_f32 v[198:199], v[184:185], v[204:205]
	v_pk_add_f32 v[184:185], v[184:185], v[204:205] neg_lo:[0,1] neg_hi:[0,1]
	v_pk_fma_f32 v[76:77], v[12:13], v[60:61], v[76:77] op_sel_hi:[0,1,1]
	v_pk_mul_f32 v[204:205], v[184:185], s[40:41]
	v_pk_mul_f32 v[92:93], v[16:17], v[76:77] op_sel:[0,1] op_sel_hi:[1,0]
	v_pk_fma_f32 v[184:185], v[184:185], s[38:39], v[204:205] op_sel:[0,0,1] op_sel_hi:[1,0,0] neg_lo:[1,0,0] neg_hi:[1,0,0]
	v_pk_add_f32 v[204:205], v[186:187], v[206:207]
	v_pk_add_f32 v[186:187], v[186:187], v[206:207] neg_lo:[0,1] neg_hi:[0,1]
	v_pk_fma_f32 v[92:93], v[12:13], v[76:77], v[92:93] op_sel_hi:[0,1,1]
	v_pk_mul_f32 v[206:207], v[186:187], s[24:25]
	v_pk_mul_f32 v[108:109], v[16:17], v[92:93] op_sel:[0,1] op_sel_hi:[1,0]
	v_pk_fma_f32 v[186:187], v[186:187], s[22:23], v[206:207] op_sel:[0,0,1] op_sel_hi:[1,0,0] neg_lo:[1,0,0] neg_hi:[1,0,0]
	v_pk_add_f32 v[206:207], v[128:129], v[190:191] op_sel:[0,1] op_sel_hi:[1,0] neg_hi:[0,1]
	v_pk_add_f32 v[128:129], v[128:129], v[190:191] op_sel:[0,1] op_sel_hi:[1,0] neg_lo:[0,1]
	v_pk_add_f32 v[190:191], v[130:131], v[160:161]
	v_pk_add_f32 v[130:131], v[130:131], v[160:161] neg_lo:[0,1] neg_hi:[0,1]
	v_pk_mul_f32 v[10:11], v[4:5], v[8:9] op_sel:[0,1] op_sel_hi:[1,0]
	v_pk_mul_f32 v[160:161], v[130:131], s[24:25]
	v_pk_fma_f32 v[108:109], v[12:13], v[92:93], v[108:109] op_sel_hi:[0,1,1]
	v_pk_fma_f32 v[130:131], v[130:131], s[22:23], v[160:161] op_sel:[0,0,1] op_sel_hi:[1,0,0]
	v_pk_add_f32 v[160:161], v[144:145], v[162:163]
	v_pk_add_f32 v[144:145], v[144:145], v[162:163] neg_lo:[0,1] neg_hi:[0,1]
	v_pk_fma_f32 v[10:11], v[6:7], v[8:9], v[10:11] op_sel_hi:[0,1,1]
	v_pk_mul_f32 v[162:163], v[144:145], s[40:41]
	v_pk_mul_f32 v[18:19], v[4:5], v[12:13] op_sel:[0,1] op_sel_hi:[1,0]
	v_pk_fma_f32 v[144:145], v[144:145], s[38:39], v[162:163] op_sel:[0,0,1] op_sel_hi:[1,0,0]
	v_pk_add_f32 v[162:163], v[148:149], v[164:165]
	v_pk_add_f32 v[148:149], v[148:149], v[164:165] neg_lo:[0,1] neg_hi:[0,1]
	v_pk_mul_f32 v[32:33], v[4:5], v[28:29] op_sel:[0,1] op_sel_hi:[1,0]
	v_pk_mul_f32 v[164:165], v[148:149], s[44:45]
	v_pk_mul_f32 v[48:49], v[4:5], v[44:45] op_sel:[0,1] op_sel_hi:[1,0]
	v_pk_fma_f32 v[148:149], v[148:149], s[50:51], v[164:165] op_sel:[0,0,1] op_sel_hi:[1,0,0]
	v_pk_add_f32 v[164:165], v[150:151], v[166:167]
	v_pk_add_f32 v[166:167], v[150:151], v[166:167] neg_lo:[0,1] neg_hi:[0,1]
	v_pk_mul_f32 v[64:65], v[4:5], v[60:61] op_sel:[0,1] op_sel_hi:[1,0]
	v_pk_add_f32 v[150:151], v[152:153], v[168:169]
	v_pk_add_f32 v[152:153], v[152:153], v[168:169] neg_lo:[0,1] neg_hi:[0,1]
	v_pk_mul_f32 v[80:81], v[4:5], v[76:77] op_sel:[0,1] op_sel_hi:[1,0]
	v_pk_mul_f32 v[168:169], v[152:153], s[44:45]
	v_pk_mul_f32 v[96:97], v[4:5], v[92:93] op_sel:[0,1] op_sel_hi:[1,0]
	v_pk_fma_f32 v[152:153], v[152:153], s[50:51], v[168:169] op_sel:[0,0,1] op_sel_hi:[1,0,0] neg_lo:[1,0,0] neg_hi:[1,0,0]
	v_pk_add_f32 v[168:169], v[154:155], v[170:171]
	v_pk_add_f32 v[154:155], v[154:155], v[170:171] neg_lo:[0,1] neg_hi:[0,1]
	v_pk_mul_f32 v[112:113], v[4:5], v[108:109] op_sel:[0,1] op_sel_hi:[1,0]
	v_pk_mul_f32 v[170:171], v[154:155], s[40:41]
	v_pk_mul_f32 v[22:23], v[10:11], 1.0 op_sel:[1,0] op_sel_hi:[1,0] neg_lo:[1,0]
	v_pk_fma_f32 v[154:155], v[154:155], s[38:39], v[170:171] op_sel:[0,0,1] op_sel_hi:[1,0,0] neg_lo:[1,0,0] neg_hi:[1,0,0]
	v_pk_add_f32 v[170:171], v[156:157], v[172:173]
	v_pk_add_f32 v[156:157], v[156:157], v[172:173] neg_lo:[0,1] neg_hi:[0,1]
	s_nop 0
	v_pk_mul_f32 v[172:173], v[156:157], s[24:25]
	v_pk_fma_f32 v[18:19], v[6:7], v[12:13], v[18:19] op_sel_hi:[0,1,1]
	v_pk_fma_f32 v[156:157], v[156:157], s[22:23], v[172:173] op_sel:[0,0,1] op_sel_hi:[1,0,0] neg_lo:[1,0,0] neg_hi:[1,0,0]
	v_pk_add_f32 v[172:173], v[208:209], v[194:195]
	v_pk_add_f32 v[194:195], v[208:209], v[194:195] neg_lo:[0,1] neg_hi:[0,1]
	v_pk_add_f32 v[208:209], v[210:211], v[180:181]
	v_pk_add_f32 v[180:181], v[210:211], v[180:181] neg_lo:[0,1] neg_hi:[0,1]
	v_pk_mul_f32 v[20:21], v[14:15], v[12:13] op_sel:[0,1] op_sel_hi:[1,0]
	v_pk_mul_f32 v[210:211], v[180:181], s[40:41]
	v_pk_fma_f32 v[32:33], v[6:7], v[28:29], v[32:33] op_sel_hi:[0,1,1]
	v_pk_fma_f32 v[180:181], v[180:181], s[38:39], v[210:211] op_sel:[0,0,1] op_sel_hi:[1,0,0]
	v_pk_add_f32 v[210:211], v[174:175], v[198:199]
	v_pk_add_f32 v[198:199], v[174:175], v[198:199] neg_lo:[0,1] neg_hi:[0,1]
	v_pk_mul_f32 v[36:37], v[14:15], v[28:29] op_sel:[0,1] op_sel_hi:[1,0]
	v_pk_add_f32 v[174:175], v[192:193], v[204:205]
	v_pk_add_f32 v[192:193], v[192:193], v[204:205] neg_lo:[0,1] neg_hi:[0,1]
	v_pk_fma_f32 v[48:49], v[6:7], v[44:45], v[48:49] op_sel_hi:[0,1,1]
	v_pk_mul_f32 v[204:205], v[192:193], s[40:41]
	v_pk_mul_f32 v[52:53], v[14:15], v[44:45] op_sel:[0,1] op_sel_hi:[1,0]
	v_pk_fma_f32 v[192:193], v[192:193], s[38:39], v[204:205] op_sel:[0,0,1] op_sel_hi:[1,0,0] neg_lo:[1,0,0] neg_hi:[1,0,0]
	v_pk_add_f32 v[204:205], v[188:189], v[196:197] op_sel:[0,1] op_sel_hi:[1,0] neg_hi:[0,1]
	v_pk_add_f32 v[188:189], v[188:189], v[196:197] op_sel:[0,1] op_sel_hi:[1,0] neg_lo:[0,1]
	v_pk_add_f32 v[196:197], v[158:159], v[182:183]
	v_pk_add_f32 v[158:159], v[158:159], v[182:183] neg_lo:[0,1] neg_hi:[0,1]
	v_pk_fma_f32 v[64:65], v[6:7], v[60:61], v[64:65] op_sel_hi:[0,1,1]
	v_pk_mul_f32 v[182:183], v[158:159], s[40:41]
	v_pk_mul_f32 v[68:69], v[14:15], v[60:61] op_sel:[0,1] op_sel_hi:[1,0]
	v_pk_fma_f32 v[158:159], v[158:159], s[38:39], v[182:183] op_sel:[0,0,1] op_sel_hi:[1,0,0]
	v_pk_add_f32 v[182:183], v[176:177], v[184:185]
	v_pk_add_f32 v[184:185], v[176:177], v[184:185] neg_lo:[0,1] neg_hi:[0,1]
	v_pk_fma_f32 v[80:81], v[6:7], v[76:77], v[80:81] op_sel_hi:[0,1,1]
	v_pk_add_f32 v[176:177], v[178:179], v[186:187]
	v_pk_add_f32 v[178:179], v[178:179], v[186:187] neg_lo:[0,1] neg_hi:[0,1]
	v_pk_mul_f32 v[84:85], v[14:15], v[76:77] op_sel:[0,1] op_sel_hi:[1,0]
	v_pk_mul_f32 v[186:187], v[178:179], s[40:41]
	v_pk_fma_f32 v[96:97], v[6:7], v[92:93], v[96:97] op_sel_hi:[0,1,1]
	v_pk_fma_f32 v[178:179], v[178:179], s[38:39], v[186:187] op_sel:[0,0,1] op_sel_hi:[1,0,0] neg_lo:[1,0,0] neg_hi:[1,0,0]
	v_pk_add_f32 v[186:187], v[206:207], v[164:165]
	v_pk_add_f32 v[164:165], v[206:207], v[164:165] neg_lo:[0,1] neg_hi:[0,1]
	v_pk_add_f32 v[206:207], v[190:191], v[150:151]
	v_pk_add_f32 v[150:151], v[190:191], v[150:151] neg_lo:[0,1] neg_hi:[0,1]
	v_pk_mul_f32 v[100:101], v[14:15], v[92:93] op_sel:[0,1] op_sel_hi:[1,0]
	v_pk_mul_f32 v[190:191], v[150:151], s[40:41]
	v_pk_fma_f32 v[112:113], v[6:7], v[108:109], v[112:113] op_sel_hi:[0,1,1]
	v_pk_fma_f32 v[150:151], v[150:151], s[38:39], v[190:191] op_sel:[0,0,1] op_sel_hi:[1,0,0]
	v_pk_add_f32 v[190:191], v[160:161], v[168:169]
	v_pk_add_f32 v[168:169], v[160:161], v[168:169] neg_lo:[0,1] neg_hi:[0,1]
	v_pk_mul_f32 v[116:117], v[14:15], v[108:109] op_sel:[0,1] op_sel_hi:[1,0]
	v_pk_add_f32 v[160:161], v[162:163], v[170:171]
	v_pk_add_f32 v[162:163], v[162:163], v[170:171] neg_lo:[0,1] neg_hi:[0,1]
	v_pk_fma_f32 v[20:21], v[8:9], v[12:13], v[20:21] op_sel_hi:[0,1,1]
	v_pk_mul_f32 v[170:171], v[162:163], s[40:41]
	v_pk_mul_f32 v[24:25], v[12:13], v[22:23] op_sel:[1,0] op_sel_hi:[0,1]
	v_pk_fma_f32 v[162:163], v[162:163], s[38:39], v[170:171] op_sel:[0,0,1] op_sel_hi:[1,0,0] neg_lo:[1,0,0] neg_hi:[1,0,0]
	v_pk_add_f32 v[170:171], v[128:129], v[166:167] op_sel:[0,1] op_sel_hi:[1,0] neg_hi:[0,1]
	v_pk_add_f32 v[128:129], v[128:129], v[166:167] op_sel:[0,1] op_sel_hi:[1,0] neg_lo:[0,1]
	v_pk_add_f32 v[166:167], v[130:131], v[152:153]
	v_pk_add_f32 v[130:131], v[130:131], v[152:153] neg_lo:[0,1] neg_hi:[0,1]
	v_pk_fma_f32 v[36:37], v[8:9], v[28:29], v[36:37] op_sel_hi:[0,1,1]
	v_pk_mul_f32 v[152:153], v[130:131], s[40:41]
	v_pk_mul_f32 v[40:41], v[22:23], v[28:29] op_sel:[0,1] op_sel_hi:[1,0]
	v_pk_fma_f32 v[130:131], v[130:131], s[38:39], v[152:153] op_sel:[0,0,1] op_sel_hi:[1,0,0]
	v_pk_add_f32 v[152:153], v[144:145], v[154:155]
	v_pk_add_f32 v[154:155], v[144:145], v[154:155] neg_lo:[0,1] neg_hi:[0,1]
	v_pk_fma_f32 v[52:53], v[8:9], v[44:45], v[52:53] op_sel_hi:[0,1,1]
	v_pk_add_f32 v[144:145], v[148:149], v[156:157]
	v_pk_add_f32 v[148:149], v[148:149], v[156:157] neg_lo:[0,1] neg_hi:[0,1]
	v_pk_mul_f32 v[56:57], v[22:23], v[44:45] op_sel:[0,1] op_sel_hi:[1,0]
	v_pk_mul_f32 v[156:157], v[148:149], s[40:41]
	v_pk_fma_f32 v[68:69], v[8:9], v[60:61], v[68:69] op_sel_hi:[0,1,1]
	v_pk_fma_f32 v[148:149], v[148:149], s[38:39], v[156:157] op_sel:[0,0,1] op_sel_hi:[1,0,0] neg_lo:[1,0,0] neg_hi:[1,0,0]
	v_pk_add_f32 v[156:157], v[172:173], v[210:211]
	v_pk_add_f32 v[172:173], v[172:173], v[210:211] neg_lo:[0,1] neg_hi:[0,1]
	v_pk_add_f32 v[210:211], v[208:209], v[174:175]
	v_pk_add_f32 v[208:209], v[208:209], v[174:175] neg_lo:[0,1] neg_hi:[0,1]
	v_pk_mul_f32 v[72:73], v[22:23], v[60:61] op_sel:[0,1] op_sel_hi:[1,0]
	v_pk_add_f32 v[174:175], v[194:195], v[198:199] op_sel:[0,1] op_sel_hi:[1,0] neg_hi:[0,1]
	v_pk_add_f32 v[194:195], v[194:195], v[198:199] op_sel:[0,1] op_sel_hi:[1,0] neg_lo:[0,1]
	v_pk_add_f32 v[198:199], v[180:181], v[192:193]
	v_pk_add_f32 v[192:193], v[180:181], v[192:193] neg_lo:[0,1] neg_hi:[0,1]
	v_pk_fma_f32 v[84:85], v[8:9], v[76:77], v[84:85] op_sel_hi:[0,1,1]
	v_pk_add_f32 v[180:181], v[204:205], v[182:183]
	v_pk_add_f32 v[182:183], v[204:205], v[182:183] neg_lo:[0,1] neg_hi:[0,1]
	v_pk_add_f32 v[204:205], v[196:197], v[176:177]
	v_pk_add_f32 v[196:197], v[196:197], v[176:177] neg_lo:[0,1] neg_hi:[0,1]
	v_pk_mul_f32 v[88:89], v[22:23], v[76:77] op_sel:[0,1] op_sel_hi:[1,0]
	v_pk_add_f32 v[176:177], v[188:189], v[184:185] op_sel:[0,1] op_sel_hi:[1,0] neg_hi:[0,1]
	v_pk_add_f32 v[184:185], v[188:189], v[184:185] op_sel:[0,1] op_sel_hi:[1,0] neg_lo:[0,1]
	v_pk_add_f32 v[188:189], v[158:159], v[178:179]
	v_pk_add_f32 v[178:179], v[158:159], v[178:179] neg_lo:[0,1] neg_hi:[0,1]
	v_pk_fma_f32 v[100:101], v[8:9], v[92:93], v[100:101] op_sel_hi:[0,1,1]
	v_pk_add_f32 v[158:159], v[186:187], v[190:191]
	v_pk_add_f32 v[186:187], v[186:187], v[190:191] neg_lo:[0,1] neg_hi:[0,1]
	v_pk_add_f32 v[190:191], v[206:207], v[160:161]
	v_pk_add_f32 v[206:207], v[206:207], v[160:161] neg_lo:[0,1] neg_hi:[0,1]
	v_pk_mul_f32 v[104:105], v[22:23], v[92:93] op_sel:[0,1] op_sel_hi:[1,0]
	v_pk_add_f32 v[160:161], v[164:165], v[168:169] op_sel:[0,1] op_sel_hi:[1,0] neg_hi:[0,1]
	v_pk_add_f32 v[164:165], v[164:165], v[168:169] op_sel:[0,1] op_sel_hi:[1,0] neg_lo:[0,1]
	v_pk_add_f32 v[168:169], v[150:151], v[162:163]
	v_pk_add_f32 v[162:163], v[150:151], v[162:163] neg_lo:[0,1] neg_hi:[0,1]
	v_pk_fma_f32 v[116:117], v[8:9], v[108:109], v[116:117] op_sel_hi:[0,1,1]
	v_pk_add_f32 v[150:151], v[170:171], v[152:153]
	v_pk_add_f32 v[152:153], v[170:171], v[152:153] neg_lo:[0,1] neg_hi:[0,1]
	v_pk_add_f32 v[170:171], v[166:167], v[144:145]
	v_pk_add_f32 v[166:167], v[166:167], v[144:145] neg_lo:[0,1] neg_hi:[0,1]
	v_pk_mul_f32 v[120:121], v[22:23], v[108:109] op_sel:[0,1] op_sel_hi:[1,0]
	v_pk_add_f32 v[144:145], v[128:129], v[154:155] op_sel:[0,1] op_sel_hi:[1,0] neg_hi:[0,1]
	v_pk_add_f32 v[128:129], v[128:129], v[154:155] op_sel:[0,1] op_sel_hi:[1,0] neg_lo:[0,1]
	v_pk_add_f32 v[154:155], v[130:131], v[148:149]
	v_pk_add_f32 v[148:149], v[130:131], v[148:149] neg_lo:[0,1] neg_hi:[0,1]
	v_xor_b32_e32 v26, 0x80000000, v19
	v_pk_add_f32 v[130:131], v[156:157], v[210:211]
	v_pk_add_f32 v[156:157], v[156:157], v[210:211] neg_lo:[0,1] neg_hi:[0,1]
	v_pk_add_f32 v[210:211], v[172:173], v[208:209] op_sel:[0,1] op_sel_hi:[1,0] neg_hi:[0,1]
	v_pk_add_f32 v[172:173], v[172:173], v[208:209] op_sel:[0,1] op_sel_hi:[1,0] neg_lo:[0,1]
	v_pk_add_f32 v[208:209], v[174:175], v[198:199]
	v_pk_add_f32 v[174:175], v[174:175], v[198:199] neg_lo:[0,1] neg_hi:[0,1]
	v_pk_add_f32 v[198:199], v[194:195], v[192:193] op_sel:[0,1] op_sel_hi:[1,0] neg_hi:[0,1]
	v_pk_add_f32 v[192:193], v[194:195], v[192:193] op_sel:[0,1] op_sel_hi:[1,0] neg_lo:[0,1]
	v_pk_add_f32 v[194:195], v[180:181], v[204:205]
	v_pk_add_f32 v[180:181], v[180:181], v[204:205] neg_lo:[0,1] neg_hi:[0,1]
	v_pk_add_f32 v[204:205], v[182:183], v[196:197] op_sel:[0,1] op_sel_hi:[1,0] neg_hi:[0,1]
	v_pk_add_f32 v[182:183], v[182:183], v[196:197] op_sel:[0,1] op_sel_hi:[1,0] neg_lo:[0,1]
	v_pk_add_f32 v[196:197], v[176:177], v[188:189]
	v_pk_add_f32 v[176:177], v[176:177], v[188:189] neg_lo:[0,1] neg_hi:[0,1]
	v_pk_add_f32 v[188:189], v[184:185], v[178:179] op_sel:[0,1] op_sel_hi:[1,0] neg_hi:[0,1]
	v_pk_add_f32 v[178:179], v[184:185], v[178:179] op_sel:[0,1] op_sel_hi:[1,0] neg_lo:[0,1]
	v_pk_add_f32 v[184:185], v[158:159], v[190:191]
	v_pk_add_f32 v[158:159], v[158:159], v[190:191] neg_lo:[0,1] neg_hi:[0,1]
	v_pk_mul_f32 v[4:5], v[4:5], v[184:185] op_sel:[0,1] op_sel_hi:[1,0]
	v_pk_add_f32 v[190:191], v[186:187], v[206:207] op_sel:[0,1] op_sel_hi:[1,0] neg_hi:[0,1]
	v_pk_add_f32 v[186:187], v[186:187], v[206:207] op_sel:[0,1] op_sel_hi:[1,0] neg_lo:[0,1]
	v_pk_add_f32 v[206:207], v[160:161], v[168:169]
	v_pk_add_f32 v[160:161], v[160:161], v[168:169] neg_lo:[0,1] neg_hi:[0,1]
	v_pk_add_f32 v[168:169], v[164:165], v[162:163] op_sel:[0,1] op_sel_hi:[1,0] neg_hi:[0,1]
	v_pk_add_f32 v[162:163], v[164:165], v[162:163] op_sel:[0,1] op_sel_hi:[1,0] neg_lo:[0,1]
	v_pk_add_f32 v[164:165], v[150:151], v[170:171]
	v_pk_fma_f32 v[4:5], v[6:7], v[184:185], v[4:5] op_sel_hi:[0,1,1]
	v_pk_mul_f32 v[6:7], v[14:15], v[194:195] op_sel:[0,1] op_sel_hi:[1,0]
	v_xor_b32_e32 v30, 0x80000000, v21
	v_pk_fma_f32 v[6:7], v[8:9], v[194:195], v[6:7] op_sel_hi:[0,1,1]
	v_pk_mul_f32 v[8:9], v[22:23], v[164:165] op_sel:[0,1] op_sel_hi:[1,0]
	v_pk_fma_f32 v[24:25], v[12:13], v[10:11], v[24:25] op_sel_hi:[1,0,1]
	v_pk_fma_f32 v[40:41], v[10:11], v[28:29], v[40:41] op_sel_hi:[0,1,1]
	v_pk_fma_f32 v[56:57], v[10:11], v[44:45], v[56:57] op_sel_hi:[0,1,1]
	v_pk_fma_f32 v[72:73], v[10:11], v[60:61], v[72:73] op_sel_hi:[0,1,1]
	v_pk_fma_f32 v[88:89], v[10:11], v[76:77], v[88:89] op_sel_hi:[0,1,1]
	v_pk_fma_f32 v[104:105], v[10:11], v[92:93], v[104:105] op_sel_hi:[0,1,1]
	v_pk_fma_f32 v[120:121], v[10:11], v[108:109], v[120:121] op_sel_hi:[0,1,1]
	v_mov_b32_e32 v27, v19
	v_mov_b32_e32 v31, v21
	v_pk_fma_f32 v[8:9], v[10:11], v[164:165], v[8:9] op_sel_hi:[0,1,1]
	v_pk_mul_f32 v[10:11], v[16:17], v[208:209] op_sel:[0,1] op_sel_hi:[1,0]
	v_pk_mul_f32 v[34:35], v[24:25], 1.0 op_sel:[1,0] op_sel_hi:[1,0] neg_lo:[1,0]
	v_pk_mul_f32 v[38:39], v[28:29], 1.0 op_sel:[1,0] op_sel_hi:[1,0] neg_lo:[1,0]
	v_pk_mul_f32 v[42:43], v[32:33], 1.0 op_sel:[1,0] op_sel_hi:[1,0] neg_lo:[1,0]
	v_pk_mul_f32 v[46:47], v[36:37], 1.0 op_sel:[1,0] op_sel_hi:[1,0] neg_lo:[1,0]
	v_pk_add_f32 v[150:151], v[150:151], v[170:171] neg_lo:[0,1] neg_hi:[0,1]
	v_pk_add_f32 v[170:171], v[152:153], v[166:167] op_sel:[0,1] op_sel_hi:[1,0] neg_hi:[0,1]
	v_pk_add_f32 v[152:153], v[152:153], v[166:167] op_sel:[0,1] op_sel_hi:[1,0] neg_lo:[0,1]
	v_pk_add_f32 v[166:167], v[144:145], v[154:155]
	v_pk_fma_f32 v[10:11], v[12:13], v[208:209], v[10:11] op_sel_hi:[0,1,1]
	v_pk_mul_f32 v[12:13], v[26:27], v[206:207] op_sel:[0,1] op_sel_hi:[1,0]
	v_pk_mul_f32 v[14:15], v[30:31], v[196:197] op_sel:[0,1] op_sel_hi:[1,0]
	v_xor_b32_e32 v50, 0x80000000, v41
	v_xor_b32_e32 v54, 0x80000000, v45
	v_xor_b32_e32 v58, 0x80000000, v49
	v_xor_b32_e32 v62, 0x80000000, v53
	v_xor_b32_e32 v66, 0x80000000, v57
	v_xor_b32_e32 v70, 0x80000000, v61
	v_xor_b32_e32 v74, 0x80000000, v65
	v_mov_b32_e32 v51, v41
	v_mov_b32_e32 v55, v45
	v_mov_b32_e32 v59, v49
	v_mov_b32_e32 v63, v53
	v_mov_b32_e32 v67, v57
	v_mov_b32_e32 v71, v61
	v_mov_b32_e32 v75, v65
	v_pk_add_f32 v[144:145], v[144:145], v[154:155] neg_lo:[0,1] neg_hi:[0,1]
	v_pk_add_f32 v[154:155], v[128:129], v[148:149] op_sel:[0,1] op_sel_hi:[1,0] neg_hi:[0,1]
	v_pk_fma_f32 v[12:13], v[18:19], v[206:207], v[12:13] op_sel_hi:[0,1,1]
	v_pk_fma_f32 v[14:15], v[20:21], v[196:197], v[14:15] op_sel_hi:[0,1,1]
	v_pk_mul_f32 v[16:17], v[34:35], v[166:167] op_sel:[0,1] op_sel_hi:[1,0]
	v_pk_mul_f32 v[18:19], v[38:39], v[210:211] op_sel:[0,1] op_sel_hi:[1,0]
	v_pk_mul_f32 v[20:21], v[42:43], v[190:191] op_sel:[0,1] op_sel_hi:[1,0]
	v_pk_mul_f32 v[22:23], v[46:47], v[204:205] op_sel:[0,1] op_sel_hi:[1,0]
	v_xor_b32_e32 v78, 0x80000000, v69
	v_xor_b32_e32 v82, 0x80000000, v73
	v_xor_b32_e32 v86, 0x80000000, v77
	v_xor_b32_e32 v90, 0x80000000, v81
	v_xor_b32_e32 v94, 0x80000000, v85
	v_xor_b32_e32 v98, 0x80000000, v89
	v_xor_b32_e32 v102, 0x80000000, v93
	v_xor_b32_e32 v106, 0x80000000, v97
	v_xor_b32_e32 v110, 0x80000000, v101
	v_xor_b32_e32 v114, 0x80000000, v105
	v_xor_b32_e32 v118, 0x80000000, v109
	v_xor_b32_e32 v122, 0x80000000, v113
	v_xor_b32_e32 v124, 0x80000000, v117
	v_xor_b32_e32 v126, 0x80000000, v121
	v_mov_b32_e32 v79, v69
	v_mov_b32_e32 v83, v73
	v_mov_b32_e32 v87, v77
	v_mov_b32_e32 v91, v81
	v_mov_b32_e32 v95, v85
	v_mov_b32_e32 v99, v89
	v_mov_b32_e32 v103, v93
	v_mov_b32_e32 v107, v97
	v_mov_b32_e32 v111, v101
	v_mov_b32_e32 v115, v105
	v_mov_b32_e32 v119, v109
	v_mov_b32_e32 v123, v113
	v_mov_b32_e32 v125, v117
	v_mov_b32_e32 v127, v121
	v_pk_add_f32 v[128:129], v[128:129], v[148:149] op_sel:[0,1] op_sel_hi:[1,0] neg_lo:[0,1]
	v_pk_fma_f32 v[16:17], v[24:25], v[166:167], v[16:17] op_sel_hi:[0,1,1]
	v_pk_fma_f32 v[18:19], v[28:29], v[210:211], v[18:19] op_sel_hi:[0,1,1]
	v_pk_fma_f32 v[20:21], v[32:33], v[190:191], v[20:21] op_sel_hi:[0,1,1]
	v_pk_fma_f32 v[22:23], v[36:37], v[204:205], v[22:23] op_sel_hi:[0,1,1]
	v_pk_mul_f32 v[24:25], v[50:51], v[170:171] op_sel:[0,1] op_sel_hi:[1,0]
	v_pk_mul_f32 v[26:27], v[54:55], v[198:199] op_sel:[0,1] op_sel_hi:[1,0]
	v_pk_mul_f32 v[28:29], v[58:59], v[168:169] op_sel:[0,1] op_sel_hi:[1,0]
	v_pk_mul_f32 v[30:31], v[62:63], v[188:189] op_sel:[0,1] op_sel_hi:[1,0]
	v_pk_mul_f32 v[32:33], v[66:67], v[154:155] op_sel:[0,1] op_sel_hi:[1,0]
	v_pk_mul_f32 v[34:35], v[70:71], v[156:157] op_sel:[0,1] op_sel_hi:[1,0]
	v_pk_mul_f32 v[36:37], v[74:75], v[158:159] op_sel:[0,1] op_sel_hi:[1,0]
	v_pk_fma_f32 v[24:25], v[40:41], v[170:171], v[24:25] op_sel_hi:[0,1,1]
	v_pk_fma_f32 v[26:27], v[44:45], v[198:199], v[26:27] op_sel_hi:[0,1,1]
	v_pk_fma_f32 v[28:29], v[48:49], v[168:169], v[28:29] op_sel_hi:[0,1,1]
	v_pk_fma_f32 v[30:31], v[52:53], v[188:189], v[30:31] op_sel_hi:[0,1,1]
	v_pk_fma_f32 v[32:33], v[56:57], v[154:155], v[32:33] op_sel_hi:[0,1,1]
	v_pk_fma_f32 v[34:35], v[60:61], v[156:157], v[34:35] op_sel_hi:[0,1,1]
	v_pk_fma_f32 v[36:37], v[64:65], v[158:159], v[36:37] op_sel_hi:[0,1,1]
	v_pk_mul_f32 v[38:39], v[78:79], v[180:181] op_sel:[0,1] op_sel_hi:[1,0]
	v_pk_mul_f32 v[40:41], v[82:83], v[150:151] op_sel:[0,1] op_sel_hi:[1,0]
	v_pk_mul_f32 v[42:43], v[86:87], v[174:175] op_sel:[0,1] op_sel_hi:[1,0]
	v_pk_mul_f32 v[44:45], v[90:91], v[160:161] op_sel:[0,1] op_sel_hi:[1,0]
	v_pk_mul_f32 v[46:47], v[94:95], v[176:177] op_sel:[0,1] op_sel_hi:[1,0]
	v_pk_mul_f32 v[48:49], v[98:99], v[144:145] op_sel:[0,1] op_sel_hi:[1,0]
	v_pk_mul_f32 v[50:51], v[102:103], v[172:173] op_sel:[0,1] op_sel_hi:[1,0]
	v_pk_mul_f32 v[52:53], v[106:107], v[186:187] op_sel:[0,1] op_sel_hi:[1,0]
	v_pk_mul_f32 v[54:55], v[110:111], v[182:183] op_sel:[0,1] op_sel_hi:[1,0]
	v_pk_mul_f32 v[56:57], v[114:115], v[152:153] op_sel:[0,1] op_sel_hi:[1,0]
	v_pk_mul_f32 v[58:59], v[118:119], v[192:193] op_sel:[0,1] op_sel_hi:[1,0]
	v_pk_mul_f32 v[60:61], v[122:123], v[162:163] op_sel:[0,1] op_sel_hi:[1,0]
	v_pk_mul_f32 v[62:63], v[124:125], v[178:179] op_sel:[0,1] op_sel_hi:[1,0]
	v_pk_mul_f32 v[64:65], v[126:127], v[128:129] op_sel:[0,1] op_sel_hi:[1,0]
	v_pk_fma_f32 v[38:39], v[68:69], v[180:181], v[38:39] op_sel_hi:[0,1,1]
	v_pk_fma_f32 v[40:41], v[72:73], v[150:151], v[40:41] op_sel_hi:[0,1,1]
	v_pk_fma_f32 v[42:43], v[76:77], v[174:175], v[42:43] op_sel_hi:[0,1,1]
	v_pk_fma_f32 v[44:45], v[80:81], v[160:161], v[44:45] op_sel_hi:[0,1,1]
	v_pk_fma_f32 v[46:47], v[84:85], v[176:177], v[46:47] op_sel_hi:[0,1,1]
	v_pk_fma_f32 v[48:49], v[88:89], v[144:145], v[48:49] op_sel_hi:[0,1,1]
	v_pk_fma_f32 v[50:51], v[92:93], v[172:173], v[50:51] op_sel_hi:[0,1,1]
	v_pk_fma_f32 v[52:53], v[96:97], v[186:187], v[52:53] op_sel_hi:[0,1,1]
	v_pk_fma_f32 v[54:55], v[100:101], v[182:183], v[54:55] op_sel_hi:[0,1,1]
	v_pk_fma_f32 v[56:57], v[104:105], v[152:153], v[56:57] op_sel_hi:[0,1,1]
	v_pk_fma_f32 v[58:59], v[108:109], v[192:193], v[58:59] op_sel_hi:[0,1,1]
	v_pk_fma_f32 v[60:61], v[112:113], v[162:163], v[60:61] op_sel_hi:[0,1,1]
	v_pk_fma_f32 v[62:63], v[116:117], v[178:179], v[62:63] op_sel_hi:[0,1,1]
	v_pk_fma_f32 v[64:65], v[120:121], v[128:129], v[64:65] op_sel_hi:[0,1,1]
	ds_write_b64 v2, v[130:131]
	ds_write_b64 v2, v[34:35] offset:4224
	ds_write_b64 v2, v[18:19] offset:8448
	ds_write_b64 v2, v[50:51] offset:12672
	ds_write_b64 v2, v[10:11] offset:16896
	ds_write_b64 v2, v[42:43] offset:21120
	ds_write_b64 v2, v[26:27] offset:25344
	ds_write_b64 v2, v[58:59] offset:29568
	ds_write_b64 v2, v[6:7] offset:33792
	ds_write_b64 v2, v[38:39] offset:38016
	ds_write_b64 v2, v[22:23] offset:42240
	ds_write_b64 v2, v[54:55] offset:46464
	ds_write_b64 v2, v[14:15] offset:50688
	ds_write_b64 v2, v[46:47] offset:54912
	ds_write_b64 v2, v[30:31] offset:59136
	ds_write_b64 v2, v[62:63] offset:63360
	ds_write_b64 v143, v[4:5]
	ds_write_b64 v212, v[36:37]
	ds_write_b64 v213, v[20:21]
	ds_write_b64 v214, v[52:53]
	ds_write_b64 v215, v[12:13]
	ds_write_b64 v216, v[44:45]
	ds_write_b64 v217, v[28:29]
	ds_write_b64 v218, v[60:61]
	ds_write_b64 v219, v[8:9]
	ds_write_b64 v220, v[40:41]
	ds_write_b64 v221, v[24:25]
	ds_write_b64 v222, v[56:57]
	ds_write_b64 v223, v[16:17]
	ds_write_b64 v224, v[48:49]
	ds_write_b64 v225, v[32:33]
	ds_write_b64 v226, v[64:65]
	v_mov_b32_e32 v2, v142
	s_waitcnt lgkmcnt(0)
	s_barrier
	s_nop 0
	v_and_b32_e32 v4, 15, v2
	v_lshlrev_b32_e32 v2, 5, v2
	v_and_b32_e32 v2, 0xfffffe00, v2
	v_lshl_add_u32 v5, v2, 3, 0
	v_lshlrev_b32_e32 v7, 3, v4
	v_ashrrev_i32_e32 v2, 2, v2
	v_add3_u32 v2, v5, v7, v2
	v_add_u32_e32 v143, 0x800, v2
	ds_read2_b64 v[128:131], v2 offset1:16
	ds_read2_b64 v[148:151], v2 offset0:33 offset1:49
	ds_read2_b64 v[152:155], v2 offset0:66 offset1:82
	ds_read2_b64 v[156:159], v2 offset0:99 offset1:115
	ds_read2_b64 v[160:163], v2 offset0:132 offset1:148
	ds_read2_b64 v[164:167], v2 offset0:165 offset1:181
	ds_read2_b64 v[168:171], v2 offset0:198 offset1:214
	ds_read2_b64 v[172:175], v2 offset0:231 offset1:247
	ds_read2_b64 v[176:179], v143 offset0:8 offset1:24
	ds_read2_b64 v[180:183], v143 offset0:41 offset1:57
	ds_read2_b64 v[184:187], v143 offset0:74 offset1:90
	ds_read2_b64 v[188:191], v143 offset0:107 offset1:123
	ds_read2_b64 v[192:195], v143 offset0:140 offset1:156
	ds_read2_b64 v[196:199], v143 offset0:173 offset1:189
	ds_read2_b64 v[204:207], v143 offset0:206 offset1:222
	ds_read2_b64 v[208:211], v143 offset0:239 offset1:255
	s_waitcnt lgkmcnt(7)
	v_pk_add_f32 v[144:145], v[128:129], v[176:177]
	v_pk_add_f32 v[128:129], v[128:129], v[176:177] neg_lo:[0,1] neg_hi:[0,1]
	v_pk_add_f32 v[176:177], v[130:131], v[178:179]
	v_pk_add_f32 v[130:131], v[130:131], v[178:179] neg_lo:[0,1] neg_hi:[0,1]
	v_cvt_f32_ubyte0_e32 v4, v4
	v_pk_mul_f32 v[178:179], v[130:131], s[20:21]
	v_mul_f32_e32 v6, 0x3b000000, v4
	v_pk_fma_f32 v[130:131], v[130:131], s[10:11], v[178:179] op_sel:[0,0,1] op_sel_hi:[1,0,0]
	s_waitcnt lgkmcnt(6)
	v_pk_add_f32 v[178:179], v[148:149], v[180:181]
	v_pk_add_f32 v[148:149], v[148:149], v[180:181] neg_lo:[0,1] neg_hi:[0,1]
	v_sin_f32_e32 v4, v6
	v_pk_mul_f32 v[180:181], v[148:149], s[24:25]
	v_cos_f32_e32 v6, v6
	v_pk_fma_f32 v[148:149], v[148:149], s[22:23], v[180:181] op_sel:[0,0,1] op_sel_hi:[1,0,0]
	v_pk_add_f32 v[180:181], v[150:151], v[182:183]
	v_pk_add_f32 v[150:151], v[150:151], v[182:183] neg_lo:[0,1] neg_hi:[0,1]
	v_xor_b32_e32 v7, 0x80000000, v4
	v_pk_mul_f32 v[182:183], v[150:151], s[36:37]
	v_mov_b32_e32 v5, v7
	v_pk_fma_f32 v[150:151], v[150:151], s[26:27], v[182:183] op_sel:[0,0,1] op_sel_hi:[1,0,0]
	s_waitcnt lgkmcnt(5)
	v_pk_add_f32 v[182:183], v[152:153], v[184:185]
	v_pk_add_f32 v[152:153], v[152:153], v[184:185] neg_lo:[0,1] neg_hi:[0,1]
	v_pk_mul_f32 v[8:9], v[6:7], v[4:5] op_sel:[1,0] op_sel_hi:[0,1]
	v_pk_mul_f32 v[184:185], v[152:153], s[40:41]
	v_pk_fma_f32 v[8:9], v[6:7], v[6:7], v[8:9] op_sel_hi:[1,0,1]
	v_pk_fma_f32 v[152:153], v[152:153], s[38:39], v[184:185] op_sel:[0,0,1] op_sel_hi:[1,0,0]
	v_pk_add_f32 v[184:185], v[154:155], v[186:187]
	v_pk_add_f32 v[154:155], v[154:155], v[186:187] neg_lo:[0,1] neg_hi:[0,1]
	v_pk_mul_f32 v[14:15], v[8:9], 1.0 op_sel:[1,0] op_sel_hi:[1,0] neg_lo:[1,0]
	v_pk_mul_f32 v[186:187], v[154:155], s[42:43]
	s_nop 0
	v_pk_fma_f32 v[154:155], v[154:155], s[0:1], v[186:187] op_sel:[0,0,1] op_sel_hi:[1,0,0]
	s_waitcnt lgkmcnt(4)
	v_pk_add_f32 v[186:187], v[156:157], v[188:189]
	v_pk_add_f32 v[156:157], v[156:157], v[188:189] neg_lo:[0,1] neg_hi:[0,1]
	v_pk_mul_f32 v[12:13], v[8:9], v[14:15] op_sel:[1,0] op_sel_hi:[0,1]
	v_pk_mul_f32 v[188:189], v[156:157], s[44:45]
	v_pk_fma_f32 v[12:13], v[8:9], v[8:9], v[12:13] op_sel_hi:[1,0,1]
	v_pk_fma_f32 v[156:157], v[156:157], s[50:51], v[188:189] op_sel:[0,0,1] op_sel_hi:[1,0,0]
	v_pk_add_f32 v[188:189], v[158:159], v[190:191]
	v_pk_add_f32 v[158:159], v[158:159], v[190:191] neg_lo:[0,1] neg_hi:[0,1]
	v_pk_mul_f32 v[16:17], v[12:13], 1.0 op_sel:[1,0] op_sel_hi:[1,0] neg_lo:[1,0]
	v_pk_mul_f32 v[190:191], v[158:159], s[8:9]
	s_nop 0
	v_pk_fma_f32 v[158:159], v[158:159], s[16:17], v[190:191] op_sel:[0,0,1] op_sel_hi:[1,0,0]
	s_waitcnt lgkmcnt(3)
	v_pk_add_f32 v[190:191], v[160:161], v[192:193]
	v_pk_add_f32 v[192:193], v[160:161], v[192:193] neg_lo:[0,1] neg_hi:[0,1]
	v_pk_mul_f32 v[28:29], v[12:13], v[16:17] op_sel:[1,0] op_sel_hi:[0,1]
	v_pk_add_f32 v[160:161], v[162:163], v[194:195]
	v_pk_add_f32 v[162:163], v[162:163], v[194:195] neg_lo:[0,1] neg_hi:[0,1]
	v_pk_fma_f32 v[28:29], v[12:13], v[12:13], v[28:29] op_sel_hi:[1,0,1]
	v_pk_mul_f32 v[194:195], v[162:163], s[8:9]
	v_pk_mul_f32 v[44:45], v[16:17], v[28:29] op_sel:[0,1] op_sel_hi:[1,0]
	v_pk_fma_f32 v[162:163], v[162:163], s[16:17], v[194:195] op_sel:[0,0,1] op_sel_hi:[1,0,0] neg_lo:[1,0,0] neg_hi:[1,0,0]
	s_waitcnt lgkmcnt(2)
	v_pk_add_f32 v[194:195], v[164:165], v[196:197]
	v_pk_add_f32 v[164:165], v[164:165], v[196:197] neg_lo:[0,1] neg_hi:[0,1]
	v_pk_fma_f32 v[44:45], v[12:13], v[28:29], v[44:45] op_sel_hi:[0,1,1]
	v_pk_mul_f32 v[196:197], v[164:165], s[44:45]
	v_pk_mul_f32 v[60:61], v[16:17], v[44:45] op_sel:[0,1] op_sel_hi:[1,0]
	v_pk_fma_f32 v[164:165], v[164:165], s[50:51], v[196:197] op_sel:[0,0,1] op_sel_hi:[1,0,0] neg_lo:[1,0,0] neg_hi:[1,0,0]
	v_pk_add_f32 v[196:197], v[166:167], v[198:199]
	v_pk_add_f32 v[166:167], v[166:167], v[198:199] neg_lo:[0,1] neg_hi:[0,1]
	v_pk_fma_f32 v[60:61], v[12:13], v[44:45], v[60:61] op_sel_hi:[0,1,1]
	v_pk_mul_f32 v[198:199], v[166:167], s[42:43]
	v_pk_mul_f32 v[76:77], v[16:17], v[60:61] op_sel:[0,1] op_sel_hi:[1,0]
	v_pk_fma_f32 v[166:167], v[166:167], s[0:1], v[198:199] op_sel:[0,0,1] op_sel_hi:[1,0,0] neg_lo:[1,0,0] neg_hi:[1,0,0]
	s_waitcnt lgkmcnt(1)
	v_pk_add_f32 v[198:199], v[168:169], v[204:205]
	v_pk_add_f32 v[168:169], v[168:169], v[204:205] neg_lo:[0,1] neg_hi:[0,1]
	v_pk_fma_f32 v[76:77], v[12:13], v[60:61], v[76:77] op_sel_hi:[0,1,1]
	v_pk_mul_f32 v[204:205], v[168:169], s[40:41]
	v_pk_mul_f32 v[92:93], v[16:17], v[76:77] op_sel:[0,1] op_sel_hi:[1,0]
	v_pk_fma_f32 v[168:169], v[168:169], s[38:39], v[204:205] op_sel:[0,0,1] op_sel_hi:[1,0,0] neg_lo:[1,0,0] neg_hi:[1,0,0]
	v_pk_add_f32 v[204:205], v[170:171], v[206:207]
	v_pk_add_f32 v[170:171], v[170:171], v[206:207] neg_lo:[0,1] neg_hi:[0,1]
	v_pk_fma_f32 v[92:93], v[12:13], v[76:77], v[92:93] op_sel_hi:[0,1,1]
	v_pk_mul_f32 v[206:207], v[170:171], s[36:37]
	v_pk_mul_f32 v[108:109], v[16:17], v[92:93] op_sel:[0,1] op_sel_hi:[1,0]
	v_pk_fma_f32 v[170:171], v[170:171], s[26:27], v[206:207] op_sel:[0,0,1] op_sel_hi:[1,0,0] neg_lo:[1,0,0] neg_hi:[1,0,0]
	s_waitcnt lgkmcnt(0)
	v_pk_add_f32 v[206:207], v[172:173], v[208:209]
	v_pk_add_f32 v[172:173], v[172:173], v[208:209] neg_lo:[0,1] neg_hi:[0,1]
	v_pk_mul_f32 v[10:11], v[4:5], v[8:9] op_sel:[0,1] op_sel_hi:[1,0]
	v_pk_mul_f32 v[208:209], v[172:173], s[24:25]
	v_pk_fma_f32 v[108:109], v[12:13], v[92:93], v[108:109] op_sel_hi:[0,1,1]
	v_pk_fma_f32 v[172:173], v[172:173], s[22:23], v[208:209] op_sel:[0,0,1] op_sel_hi:[1,0,0] neg_lo:[1,0,0] neg_hi:[1,0,0]
	v_pk_add_f32 v[208:209], v[174:175], v[210:211]
	v_pk_add_f32 v[174:175], v[174:175], v[210:211] neg_lo:[0,1] neg_hi:[0,1]
	v_pk_fma_f32 v[10:11], v[6:7], v[8:9], v[10:11] op_sel_hi:[0,1,1]
	v_pk_mul_f32 v[210:211], v[174:175], s[20:21]
	v_pk_mul_f32 v[18:19], v[4:5], v[12:13] op_sel:[0,1] op_sel_hi:[1,0]
	v_pk_fma_f32 v[174:175], v[174:175], s[10:11], v[210:211] op_sel:[0,0,1] op_sel_hi:[1,0,0] neg_lo:[1,0,0] neg_hi:[1,0,0]
	v_pk_add_f32 v[210:211], v[144:145], v[190:191]
	v_pk_add_f32 v[144:145], v[144:145], v[190:191] neg_lo:[0,1] neg_hi:[0,1]
	v_pk_add_f32 v[190:191], v[176:177], v[160:161]
	v_pk_add_f32 v[160:161], v[176:177], v[160:161] neg_lo:[0,1] neg_hi:[0,1]
	v_pk_mul_f32 v[32:33], v[4:5], v[28:29] op_sel:[0,1] op_sel_hi:[1,0]
	v_pk_mul_f32 v[176:177], v[160:161], s[24:25]
	v_pk_mul_f32 v[48:49], v[4:5], v[44:45] op_sel:[0,1] op_sel_hi:[1,0]
	v_pk_fma_f32 v[160:161], v[160:161], s[22:23], v[176:177] op_sel:[0,0,1] op_sel_hi:[1,0,0]
	v_pk_add_f32 v[176:177], v[178:179], v[194:195]
	v_pk_add_f32 v[178:179], v[178:179], v[194:195] neg_lo:[0,1] neg_hi:[0,1]
	v_pk_mul_f32 v[64:65], v[4:5], v[60:61] op_sel:[0,1] op_sel_hi:[1,0]
	v_pk_mul_f32 v[194:195], v[178:179], s[40:41]
	v_pk_mul_f32 v[80:81], v[4:5], v[76:77] op_sel:[0,1] op_sel_hi:[1,0]
	v_pk_fma_f32 v[178:179], v[178:179], s[38:39], v[194:195] op_sel:[0,0,1] op_sel_hi:[1,0,0]
	v_pk_add_f32 v[194:195], v[180:181], v[196:197]
	v_pk_add_f32 v[180:181], v[180:181], v[196:197] neg_lo:[0,1] neg_hi:[0,1]
	v_pk_mul_f32 v[96:97], v[4:5], v[92:93] op_sel:[0,1] op_sel_hi:[1,0]
	v_pk_mul_f32 v[196:197], v[180:181], s[44:45]
	v_pk_mul_f32 v[112:113], v[4:5], v[108:109] op_sel:[0,1] op_sel_hi:[1,0]
	v_pk_fma_f32 v[180:181], v[180:181], s[50:51], v[196:197] op_sel:[0,0,1] op_sel_hi:[1,0,0]
	v_pk_add_f32 v[196:197], v[182:183], v[198:199]
	v_pk_add_f32 v[198:199], v[182:183], v[198:199] neg_lo:[0,1] neg_hi:[0,1]
	v_pk_mul_f32 v[22:23], v[10:11], 1.0 op_sel:[1,0] op_sel_hi:[1,0] neg_lo:[1,0]
	v_pk_add_f32 v[182:183], v[184:185], v[204:205]
	v_pk_add_f32 v[184:185], v[184:185], v[204:205] neg_lo:[0,1] neg_hi:[0,1]
	s_nop 0
	v_pk_mul_f32 v[204:205], v[184:185], s[44:45]
	v_pk_fma_f32 v[18:19], v[6:7], v[12:13], v[18:19] op_sel_hi:[0,1,1]
	v_pk_fma_f32 v[184:185], v[184:185], s[50:51], v[204:205] op_sel:[0,0,1] op_sel_hi:[1,0,0] neg_lo:[1,0,0] neg_hi:[1,0,0]
	v_pk_add_f32 v[204:205], v[186:187], v[206:207]
	v_pk_add_f32 v[186:187], v[186:187], v[206:207] neg_lo:[0,1] neg_hi:[0,1]
	v_pk_mul_f32 v[20:21], v[14:15], v[12:13] op_sel:[0,1] op_sel_hi:[1,0]
	v_pk_mul_f32 v[206:207], v[186:187], s[40:41]
	v_pk_fma_f32 v[32:33], v[6:7], v[28:29], v[32:33] op_sel_hi:[0,1,1]
	v_pk_fma_f32 v[186:187], v[186:187], s[38:39], v[206:207] op_sel:[0,0,1] op_sel_hi:[1,0,0] neg_lo:[1,0,0] neg_hi:[1,0,0]
	v_pk_add_f32 v[206:207], v[188:189], v[208:209]
	v_pk_add_f32 v[188:189], v[188:189], v[208:209] neg_lo:[0,1] neg_hi:[0,1]
	v_pk_mul_f32 v[36:37], v[14:15], v[28:29] op_sel:[0,1] op_sel_hi:[1,0]
	v_pk_mul_f32 v[208:209], v[188:189], s[24:25]
	v_pk_fma_f32 v[48:49], v[6:7], v[44:45], v[48:49] op_sel_hi:[0,1,1]
	v_pk_fma_f32 v[188:189], v[188:189], s[22:23], v[208:209] op_sel:[0,0,1] op_sel_hi:[1,0,0] neg_lo:[1,0,0] neg_hi:[1,0,0]
	v_pk_add_f32 v[208:209], v[128:129], v[192:193] op_sel:[0,1] op_sel_hi:[1,0] neg_hi:[0,1]
	v_pk_add_f32 v[128:129], v[128:129], v[192:193] op_sel:[0,1] op_sel_hi:[1,0] neg_lo:[0,1]
	v_pk_add_f32 v[192:193], v[130:131], v[162:163]
	v_pk_add_f32 v[130:131], v[130:131], v[162:163] neg_lo:[0,1] neg_hi:[0,1]
	v_pk_mul_f32 v[52:53], v[14:15], v[44:45] op_sel:[0,1] op_sel_hi:[1,0]
	v_pk_mul_f32 v[162:163], v[130:131], s[24:25]
	v_pk_fma_f32 v[64:65], v[6:7], v[60:61], v[64:65] op_sel_hi:[0,1,1]
	v_pk_fma_f32 v[130:131], v[130:131], s[22:23], v[162:163] op_sel:[0,0,1] op_sel_hi:[1,0,0]
	v_pk_add_f32 v[162:163], v[148:149], v[164:165]
	v_pk_add_f32 v[148:149], v[148:149], v[164:165] neg_lo:[0,1] neg_hi:[0,1]
	v_pk_mul_f32 v[68:69], v[14:15], v[60:61] op_sel:[0,1] op_sel_hi:[1,0]
	v_pk_mul_f32 v[164:165], v[148:149], s[40:41]
	v_pk_fma_f32 v[80:81], v[6:7], v[76:77], v[80:81] op_sel_hi:[0,1,1]
	v_pk_fma_f32 v[148:149], v[148:149], s[38:39], v[164:165] op_sel:[0,0,1] op_sel_hi:[1,0,0]
	v_pk_add_f32 v[164:165], v[150:151], v[166:167]
	v_pk_add_f32 v[150:151], v[150:151], v[166:167] neg_lo:[0,1] neg_hi:[0,1]
	v_pk_mul_f32 v[84:85], v[14:15], v[76:77] op_sel:[0,1] op_sel_hi:[1,0]
	v_pk_mul_f32 v[166:167], v[150:151], s[44:45]
	v_pk_fma_f32 v[96:97], v[6:7], v[92:93], v[96:97] op_sel_hi:[0,1,1]
	v_pk_fma_f32 v[150:151], v[150:151], s[50:51], v[166:167] op_sel:[0,0,1] op_sel_hi:[1,0,0]
	v_pk_add_f32 v[166:167], v[152:153], v[168:169]
	v_pk_add_f32 v[168:169], v[152:153], v[168:169] neg_lo:[0,1] neg_hi:[0,1]
	v_pk_mul_f32 v[100:101], v[14:15], v[92:93] op_sel:[0,1] op_sel_hi:[1,0]
	v_pk_add_f32 v[152:153], v[154:155], v[170:171]
	v_pk_add_f32 v[154:155], v[154:155], v[170:171] neg_lo:[0,1] neg_hi:[0,1]
	v_pk_fma_f32 v[112:113], v[6:7], v[108:109], v[112:113] op_sel_hi:[0,1,1]
	v_pk_mul_f32 v[170:171], v[154:155], s[44:45]
	v_pk_mul_f32 v[116:117], v[14:15], v[108:109] op_sel:[0,1] op_sel_hi:[1,0]
	v_pk_fma_f32 v[154:155], v[154:155], s[50:51], v[170:171] op_sel:[0,0,1] op_sel_hi:[1,0,0] neg_lo:[1,0,0] neg_hi:[1,0,0]
	v_pk_add_f32 v[170:171], v[156:157], v[172:173]
	v_pk_add_f32 v[156:157], v[156:157], v[172:173] neg_lo:[0,1] neg_hi:[0,1]
	v_pk_fma_f32 v[20:21], v[8:9], v[12:13], v[20:21] op_sel_hi:[0,1,1]
	v_pk_mul_f32 v[172:173], v[156:157], s[40:41]
	v_pk_mul_f32 v[24:25], v[12:13], v[22:23] op_sel:[1,0] op_sel_hi:[0,1]
	v_pk_fma_f32 v[156:157], v[156:157], s[38:39], v[172:173] op_sel:[0,0,1] op_sel_hi:[1,0,0] neg_lo:[1,0,0] neg_hi:[1,0,0]
	v_pk_add_f32 v[172:173], v[158:159], v[174:175]
	v_pk_add_f32 v[158:159], v[158:159], v[174:175] neg_lo:[0,1] neg_hi:[0,1]
	v_pk_fma_f32 v[36:37], v[8:9], v[28:29], v[36:37] op_sel_hi:[0,1,1]
	v_pk_mul_f32 v[174:175], v[158:159], s[24:25]
	v_pk_mul_f32 v[40:41], v[22:23], v[28:29] op_sel:[0,1] op_sel_hi:[1,0]
	v_pk_fma_f32 v[158:159], v[158:159], s[22:23], v[174:175] op_sel:[0,0,1] op_sel_hi:[1,0,0] neg_lo:[1,0,0] neg_hi:[1,0,0]
	v_pk_add_f32 v[174:175], v[210:211], v[196:197]
	v_pk_add_f32 v[196:197], v[210:211], v[196:197] neg_lo:[0,1] neg_hi:[0,1]
	v_pk_add_f32 v[210:211], v[190:191], v[182:183]
	v_pk_add_f32 v[182:183], v[190:191], v[182:183] neg_lo:[0,1] neg_hi:[0,1]
	v_pk_fma_f32 v[52:53], v[8:9], v[44:45], v[52:53] op_sel_hi:[0,1,1]
	v_pk_mul_f32 v[190:191], v[182:183], s[40:41]
	v_pk_mul_f32 v[56:57], v[22:23], v[44:45] op_sel:[0,1] op_sel_hi:[1,0]
	v_pk_fma_f32 v[182:183], v[182:183], s[38:39], v[190:191] op_sel:[0,0,1] op_sel_hi:[1,0,0]
	v_pk_add_f32 v[190:191], v[176:177], v[204:205]
	v_pk_add_f32 v[204:205], v[176:177], v[204:205] neg_lo:[0,1] neg_hi:[0,1]
	v_pk_fma_f32 v[68:69], v[8:9], v[60:61], v[68:69] op_sel_hi:[0,1,1]
	v_pk_add_f32 v[176:177], v[194:195], v[206:207]
	v_pk_add_f32 v[194:195], v[194:195], v[206:207] neg_lo:[0,1] neg_hi:[0,1]
	v_pk_mul_f32 v[72:73], v[22:23], v[60:61] op_sel:[0,1] op_sel_hi:[1,0]
	v_pk_mul_f32 v[206:207], v[194:195], s[40:41]
	v_pk_fma_f32 v[84:85], v[8:9], v[76:77], v[84:85] op_sel_hi:[0,1,1]
	v_pk_fma_f32 v[194:195], v[194:195], s[38:39], v[206:207] op_sel:[0,0,1] op_sel_hi:[1,0,0] neg_lo:[1,0,0] neg_hi:[1,0,0]
	v_pk_add_f32 v[206:207], v[144:145], v[198:199] op_sel:[0,1] op_sel_hi:[1,0] neg_hi:[0,1]
	v_pk_add_f32 v[144:145], v[144:145], v[198:199] op_sel:[0,1] op_sel_hi:[1,0] neg_lo:[0,1]
	v_pk_add_f32 v[198:199], v[160:161], v[184:185]
	v_pk_add_f32 v[160:161], v[160:161], v[184:185] neg_lo:[0,1] neg_hi:[0,1]
	v_pk_mul_f32 v[88:89], v[22:23], v[76:77] op_sel:[0,1] op_sel_hi:[1,0]
	v_pk_mul_f32 v[184:185], v[160:161], s[40:41]
	v_pk_fma_f32 v[100:101], v[8:9], v[92:93], v[100:101] op_sel_hi:[0,1,1]
	v_pk_fma_f32 v[160:161], v[160:161], s[38:39], v[184:185] op_sel:[0,0,1] op_sel_hi:[1,0,0]
	v_pk_add_f32 v[184:185], v[178:179], v[186:187]
	v_pk_add_f32 v[186:187], v[178:179], v[186:187] neg_lo:[0,1] neg_hi:[0,1]
	v_pk_mul_f32 v[104:105], v[22:23], v[92:93] op_sel:[0,1] op_sel_hi:[1,0]
	v_pk_add_f32 v[178:179], v[180:181], v[188:189]
	v_pk_add_f32 v[180:181], v[180:181], v[188:189] neg_lo:[0,1] neg_hi:[0,1]
	v_pk_fma_f32 v[116:117], v[8:9], v[108:109], v[116:117] op_sel_hi:[0,1,1]
	v_pk_mul_f32 v[188:189], v[180:181], s[40:41]
	v_pk_mul_f32 v[120:121], v[22:23], v[108:109] op_sel:[0,1] op_sel_hi:[1,0]
	v_pk_fma_f32 v[180:181], v[180:181], s[38:39], v[188:189] op_sel:[0,0,1] op_sel_hi:[1,0,0] neg_lo:[1,0,0] neg_hi:[1,0,0]
	v_pk_add_f32 v[188:189], v[208:209], v[166:167]
	v_pk_add_f32 v[166:167], v[208:209], v[166:167] neg_lo:[0,1] neg_hi:[0,1]
	v_pk_add_f32 v[208:209], v[192:193], v[152:153]
	v_pk_add_f32 v[152:153], v[192:193], v[152:153] neg_lo:[0,1] neg_hi:[0,1]
	v_xor_b32_e32 v26, 0x80000000, v19
	v_pk_mul_f32 v[192:193], v[152:153], s[40:41]
	v_xor_b32_e32 v30, 0x80000000, v21
	v_pk_fma_f32 v[152:153], v[152:153], s[38:39], v[192:193] op_sel:[0,0,1] op_sel_hi:[1,0,0]
	v_pk_add_f32 v[192:193], v[162:163], v[170:171]
	v_pk_add_f32 v[170:171], v[162:163], v[170:171] neg_lo:[0,1] neg_hi:[0,1]
	v_pk_fma_f32 v[24:25], v[12:13], v[10:11], v[24:25] op_sel_hi:[1,0,1]
	v_pk_add_f32 v[162:163], v[164:165], v[172:173]
	v_pk_add_f32 v[164:165], v[164:165], v[172:173] neg_lo:[0,1] neg_hi:[0,1]
	v_pk_fma_f32 v[40:41], v[10:11], v[28:29], v[40:41] op_sel_hi:[0,1,1]
	v_pk_mul_f32 v[172:173], v[164:165], s[40:41]
	v_pk_fma_f32 v[56:57], v[10:11], v[44:45], v[56:57] op_sel_hi:[0,1,1]
	v_pk_fma_f32 v[164:165], v[164:165], s[38:39], v[172:173] op_sel:[0,0,1] op_sel_hi:[1,0,0] neg_lo:[1,0,0] neg_hi:[1,0,0]
	v_pk_add_f32 v[172:173], v[128:129], v[168:169] op_sel:[0,1] op_sel_hi:[1,0] neg_hi:[0,1]
	v_pk_add_f32 v[128:129], v[128:129], v[168:169] op_sel:[0,1] op_sel_hi:[1,0] neg_lo:[0,1]
	v_pk_add_f32 v[168:169], v[130:131], v[154:155]
	v_pk_add_f32 v[130:131], v[130:131], v[154:155] neg_lo:[0,1] neg_hi:[0,1]
	v_pk_fma_f32 v[72:73], v[10:11], v[60:61], v[72:73] op_sel_hi:[0,1,1]
	v_pk_mul_f32 v[154:155], v[130:131], s[40:41]
	v_pk_fma_f32 v[88:89], v[10:11], v[76:77], v[88:89] op_sel_hi:[0,1,1]
	v_pk_fma_f32 v[130:131], v[130:131], s[38:39], v[154:155] op_sel:[0,0,1] op_sel_hi:[1,0,0]
	v_pk_add_f32 v[154:155], v[148:149], v[156:157]
	v_pk_add_f32 v[156:157], v[148:149], v[156:157] neg_lo:[0,1] neg_hi:[0,1]
	v_pk_fma_f32 v[104:105], v[10:11], v[92:93], v[104:105] op_sel_hi:[0,1,1]
	v_pk_add_f32 v[148:149], v[150:151], v[158:159]
	v_pk_add_f32 v[150:151], v[150:151], v[158:159] neg_lo:[0,1] neg_hi:[0,1]
	v_pk_fma_f32 v[120:121], v[10:11], v[108:109], v[120:121] op_sel_hi:[0,1,1]
	v_pk_mul_f32 v[158:159], v[150:151], s[40:41]
	v_mov_b32_e32 v27, v19
	v_pk_fma_f32 v[150:151], v[150:151], s[38:39], v[158:159] op_sel:[0,0,1] op_sel_hi:[1,0,0] neg_lo:[1,0,0] neg_hi:[1,0,0]
	v_pk_add_f32 v[158:159], v[174:175], v[190:191]
	v_pk_add_f32 v[174:175], v[174:175], v[190:191] neg_lo:[0,1] neg_hi:[0,1]
	v_pk_add_f32 v[190:191], v[210:211], v[176:177]
	v_pk_add_f32 v[210:211], v[210:211], v[176:177] neg_lo:[0,1] neg_hi:[0,1]
	v_mov_b32_e32 v31, v21
	v_pk_add_f32 v[176:177], v[196:197], v[204:205] op_sel:[0,1] op_sel_hi:[1,0] neg_hi:[0,1]
	v_pk_add_f32 v[196:197], v[196:197], v[204:205] op_sel:[0,1] op_sel_hi:[1,0] neg_lo:[0,1]
	v_pk_add_f32 v[204:205], v[182:183], v[194:195]
	v_pk_add_f32 v[194:195], v[182:183], v[194:195] neg_lo:[0,1] neg_hi:[0,1]
	v_xor_b32_e32 v34, 0x80000000, v25
	v_pk_add_f32 v[182:183], v[206:207], v[184:185]
	v_pk_add_f32 v[184:185], v[206:207], v[184:185] neg_lo:[0,1] neg_hi:[0,1]
	v_pk_add_f32 v[206:207], v[198:199], v[178:179]
	v_pk_add_f32 v[198:199], v[198:199], v[178:179] neg_lo:[0,1] neg_hi:[0,1]
	v_xor_b32_e32 v38, 0x80000000, v29
	v_pk_add_f32 v[178:179], v[144:145], v[186:187] op_sel:[0,1] op_sel_hi:[1,0] neg_hi:[0,1]
	v_pk_add_f32 v[144:145], v[144:145], v[186:187] op_sel:[0,1] op_sel_hi:[1,0] neg_lo:[0,1]
	v_pk_add_f32 v[186:187], v[160:161], v[180:181]
	v_pk_add_f32 v[180:181], v[160:161], v[180:181] neg_lo:[0,1] neg_hi:[0,1]
	v_xor_b32_e32 v42, 0x80000000, v33
	v_pk_add_f32 v[160:161], v[188:189], v[192:193]
	v_pk_add_f32 v[188:189], v[188:189], v[192:193] neg_lo:[0,1] neg_hi:[0,1]
	v_pk_add_f32 v[192:193], v[208:209], v[162:163]
	v_pk_add_f32 v[208:209], v[208:209], v[162:163] neg_lo:[0,1] neg_hi:[0,1]
	v_xor_b32_e32 v46, 0x80000000, v37
	v_pk_add_f32 v[162:163], v[166:167], v[170:171] op_sel:[0,1] op_sel_hi:[1,0] neg_hi:[0,1]
	v_pk_add_f32 v[166:167], v[166:167], v[170:171] op_sel:[0,1] op_sel_hi:[1,0] neg_lo:[0,1]
	v_pk_add_f32 v[170:171], v[152:153], v[164:165]
	v_pk_add_f32 v[164:165], v[152:153], v[164:165] neg_lo:[0,1] neg_hi:[0,1]
	v_mov_b32_e32 v35, v25
	v_pk_add_f32 v[152:153], v[172:173], v[154:155]
	v_pk_add_f32 v[154:155], v[172:173], v[154:155] neg_lo:[0,1] neg_hi:[0,1]
	v_pk_add_f32 v[172:173], v[168:169], v[148:149]
	v_pk_add_f32 v[168:169], v[168:169], v[148:149] neg_lo:[0,1] neg_hi:[0,1]
	v_mov_b32_e32 v39, v29
	v_pk_add_f32 v[148:149], v[128:129], v[156:157] op_sel:[0,1] op_sel_hi:[1,0] neg_hi:[0,1]
	v_pk_add_f32 v[128:129], v[128:129], v[156:157] op_sel:[0,1] op_sel_hi:[1,0] neg_lo:[0,1]
	v_pk_add_f32 v[156:157], v[130:131], v[150:151]
	v_pk_add_f32 v[130:131], v[130:131], v[150:151] neg_lo:[0,1] neg_hi:[0,1]
	v_mov_b32_e32 v43, v33
	v_pk_mul_f32 v[150:151], v[130:131], 1.0 op_sel:[1,0] op_sel_hi:[0,0] neg_hi:[1,0]
	v_pk_add_f32 v[130:131], v[158:159], v[190:191]
	v_pk_add_f32 v[158:159], v[158:159], v[190:191] neg_lo:[0,1] neg_hi:[0,1]
	v_pk_add_f32 v[190:191], v[174:175], v[210:211] op_sel:[0,1] op_sel_hi:[1,0] neg_hi:[0,1]
	v_pk_add_f32 v[174:175], v[174:175], v[210:211] op_sel:[0,1] op_sel_hi:[1,0] neg_lo:[0,1]
	v_pk_add_f32 v[210:211], v[176:177], v[204:205]
	v_pk_add_f32 v[176:177], v[176:177], v[204:205] neg_lo:[0,1] neg_hi:[0,1]
	v_pk_add_f32 v[204:205], v[196:197], v[194:195] op_sel:[0,1] op_sel_hi:[1,0] neg_hi:[0,1]
	v_pk_add_f32 v[194:195], v[196:197], v[194:195] op_sel:[0,1] op_sel_hi:[1,0] neg_lo:[0,1]
	v_pk_add_f32 v[196:197], v[182:183], v[206:207]
	v_pk_add_f32 v[182:183], v[182:183], v[206:207] neg_lo:[0,1] neg_hi:[0,1]
	v_pk_add_f32 v[206:207], v[184:185], v[198:199] op_sel:[0,1] op_sel_hi:[1,0] neg_hi:[0,1]
	v_pk_add_f32 v[184:185], v[184:185], v[198:199] op_sel:[0,1] op_sel_hi:[1,0] neg_lo:[0,1]
	v_pk_add_f32 v[198:199], v[178:179], v[186:187]
	v_pk_add_f32 v[178:179], v[178:179], v[186:187] neg_lo:[0,1] neg_hi:[0,1]
	v_pk_add_f32 v[186:187], v[144:145], v[180:181] op_sel:[0,1] op_sel_hi:[1,0] neg_hi:[0,1]
	v_pk_add_f32 v[144:145], v[144:145], v[180:181] op_sel:[0,1] op_sel_hi:[1,0] neg_lo:[0,1]
	v_pk_add_f32 v[180:181], v[160:161], v[192:193]
	v_pk_add_f32 v[160:161], v[160:161], v[192:193] neg_lo:[0,1] neg_hi:[0,1]
	v_pk_mul_f32 v[4:5], v[4:5], v[180:181] op_sel:[0,1] op_sel_hi:[1,0]
	v_pk_add_f32 v[192:193], v[188:189], v[208:209] op_sel:[0,1] op_sel_hi:[1,0] neg_hi:[0,1]
	v_pk_add_f32 v[188:189], v[188:189], v[208:209] op_sel:[0,1] op_sel_hi:[1,0] neg_lo:[0,1]
	v_pk_add_f32 v[208:209], v[162:163], v[170:171]
	v_pk_add_f32 v[162:163], v[162:163], v[170:171] neg_lo:[0,1] neg_hi:[0,1]
	v_pk_add_f32 v[170:171], v[166:167], v[164:165] op_sel:[0,1] op_sel_hi:[1,0] neg_hi:[0,1]
	v_pk_add_f32 v[164:165], v[166:167], v[164:165] op_sel:[0,1] op_sel_hi:[1,0] neg_lo:[0,1]
	v_pk_add_f32 v[166:167], v[152:153], v[172:173]
	v_pk_fma_f32 v[4:5], v[6:7], v[180:181], v[4:5] op_sel_hi:[0,1,1]
	v_pk_mul_f32 v[6:7], v[14:15], v[196:197] op_sel:[0,1] op_sel_hi:[1,0]
	v_mov_b32_e32 v47, v37
	v_pk_fma_f32 v[6:7], v[8:9], v[196:197], v[6:7] op_sel_hi:[0,1,1]
	v_pk_mul_f32 v[8:9], v[22:23], v[166:167] op_sel:[0,1] op_sel_hi:[1,0]
	v_pk_add_f32 v[152:153], v[152:153], v[172:173] neg_lo:[0,1] neg_hi:[0,1]
	v_pk_fma_f32 v[8:9], v[10:11], v[166:167], v[8:9] op_sel_hi:[0,1,1]
	v_pk_mul_f32 v[10:11], v[16:17], v[210:211] op_sel:[0,1] op_sel_hi:[1,0]
	v_pk_add_f32 v[172:173], v[154:155], v[168:169] op_sel:[0,1] op_sel_hi:[1,0] neg_hi:[0,1]
	v_pk_add_f32 v[154:155], v[154:155], v[168:169] op_sel:[0,1] op_sel_hi:[1,0] neg_lo:[0,1]
	v_pk_add_f32 v[168:169], v[148:149], v[156:157]
	v_pk_fma_f32 v[10:11], v[12:13], v[210:211], v[10:11] op_sel_hi:[0,1,1]
	v_pk_mul_f32 v[12:13], v[26:27], v[208:209] op_sel:[0,1] op_sel_hi:[1,0]
	v_pk_mul_f32 v[14:15], v[30:31], v[198:199] op_sel:[0,1] op_sel_hi:[1,0]
	v_xor_b32_e32 v50, 0x80000000, v41
	v_xor_b32_e32 v54, 0x80000000, v45
	v_xor_b32_e32 v58, 0x80000000, v49
	v_xor_b32_e32 v62, 0x80000000, v53
	v_xor_b32_e32 v66, 0x80000000, v57
	v_xor_b32_e32 v70, 0x80000000, v61
	v_xor_b32_e32 v74, 0x80000000, v65
	v_mov_b32_e32 v51, v41
	v_mov_b32_e32 v55, v45
	v_mov_b32_e32 v59, v49
	v_mov_b32_e32 v63, v53
	v_mov_b32_e32 v67, v57
	v_mov_b32_e32 v71, v61
	v_mov_b32_e32 v75, v65
	v_pk_add_f32 v[148:149], v[148:149], v[156:157] neg_lo:[0,1] neg_hi:[0,1]
	v_pk_add_f32 v[156:157], v[128:129], v[150:151]
	v_pk_fma_f32 v[12:13], v[18:19], v[208:209], v[12:13] op_sel_hi:[0,1,1]
	v_pk_fma_f32 v[14:15], v[20:21], v[198:199], v[14:15] op_sel_hi:[0,1,1]
	v_pk_mul_f32 v[16:17], v[34:35], v[168:169] op_sel:[0,1] op_sel_hi:[1,0]
	v_pk_mul_f32 v[18:19], v[38:39], v[190:191] op_sel:[0,1] op_sel_hi:[1,0]
	v_pk_mul_f32 v[20:21], v[42:43], v[192:193] op_sel:[0,1] op_sel_hi:[1,0]
	v_pk_mul_f32 v[22:23], v[46:47], v[206:207] op_sel:[0,1] op_sel_hi:[1,0]
	v_xor_b32_e32 v78, 0x80000000, v69
	v_xor_b32_e32 v82, 0x80000000, v73
	v_xor_b32_e32 v86, 0x80000000, v77
	v_xor_b32_e32 v90, 0x80000000, v81
	v_xor_b32_e32 v94, 0x80000000, v85
	v_xor_b32_e32 v98, 0x80000000, v89
	v_xor_b32_e32 v102, 0x80000000, v93
	v_xor_b32_e32 v106, 0x80000000, v97
	v_xor_b32_e32 v110, 0x80000000, v101
	v_xor_b32_e32 v114, 0x80000000, v105
	v_xor_b32_e32 v118, 0x80000000, v109
	v_xor_b32_e32 v122, 0x80000000, v113
	v_xor_b32_e32 v124, 0x80000000, v117
	v_xor_b32_e32 v126, 0x80000000, v121
	v_mov_b32_e32 v79, v69
	v_mov_b32_e32 v83, v73
	v_mov_b32_e32 v87, v77
	v_mov_b32_e32 v91, v81
	v_mov_b32_e32 v95, v85
	v_mov_b32_e32 v99, v89
	v_mov_b32_e32 v103, v93
	v_mov_b32_e32 v107, v97
	v_mov_b32_e32 v111, v101
	v_mov_b32_e32 v115, v105
	v_mov_b32_e32 v119, v109
	v_mov_b32_e32 v123, v113
	v_mov_b32_e32 v125, v117
	v_mov_b32_e32 v127, v121
	v_pk_add_f32 v[128:129], v[128:129], v[150:151] neg_lo:[0,1] neg_hi:[0,1]
	v_pk_fma_f32 v[16:17], v[24:25], v[168:169], v[16:17] op_sel_hi:[0,1,1]
	v_pk_fma_f32 v[18:19], v[28:29], v[190:191], v[18:19] op_sel_hi:[0,1,1]
	v_pk_fma_f32 v[20:21], v[32:33], v[192:193], v[20:21] op_sel_hi:[0,1,1]
	v_pk_fma_f32 v[22:23], v[36:37], v[206:207], v[22:23] op_sel_hi:[0,1,1]
	v_pk_mul_f32 v[24:25], v[50:51], v[172:173] op_sel:[0,1] op_sel_hi:[1,0]
	v_pk_mul_f32 v[26:27], v[54:55], v[204:205] op_sel:[0,1] op_sel_hi:[1,0]
	v_pk_mul_f32 v[28:29], v[58:59], v[170:171] op_sel:[0,1] op_sel_hi:[1,0]
	v_pk_mul_f32 v[30:31], v[62:63], v[186:187] op_sel:[0,1] op_sel_hi:[1,0]
	v_pk_mul_f32 v[32:33], v[66:67], v[156:157] op_sel:[0,1] op_sel_hi:[1,0]
	v_pk_mul_f32 v[34:35], v[70:71], v[158:159] op_sel:[0,1] op_sel_hi:[1,0]
	v_pk_mul_f32 v[36:37], v[74:75], v[160:161] op_sel:[0,1] op_sel_hi:[1,0]
	v_pk_fma_f32 v[24:25], v[40:41], v[172:173], v[24:25] op_sel_hi:[0,1,1]
	v_pk_fma_f32 v[26:27], v[44:45], v[204:205], v[26:27] op_sel_hi:[0,1,1]
	v_pk_fma_f32 v[28:29], v[48:49], v[170:171], v[28:29] op_sel_hi:[0,1,1]
	v_pk_fma_f32 v[30:31], v[52:53], v[186:187], v[30:31] op_sel_hi:[0,1,1]
	v_pk_fma_f32 v[32:33], v[56:57], v[156:157], v[32:33] op_sel_hi:[0,1,1]
	v_pk_fma_f32 v[34:35], v[60:61], v[158:159], v[34:35] op_sel_hi:[0,1,1]
	v_pk_fma_f32 v[36:37], v[64:65], v[160:161], v[36:37] op_sel_hi:[0,1,1]
	v_pk_mul_f32 v[38:39], v[78:79], v[182:183] op_sel:[0,1] op_sel_hi:[1,0]
	v_pk_mul_f32 v[40:41], v[82:83], v[152:153] op_sel:[0,1] op_sel_hi:[1,0]
	v_pk_mul_f32 v[42:43], v[86:87], v[176:177] op_sel:[0,1] op_sel_hi:[1,0]
	v_pk_mul_f32 v[44:45], v[90:91], v[162:163] op_sel:[0,1] op_sel_hi:[1,0]
	v_pk_mul_f32 v[46:47], v[94:95], v[178:179] op_sel:[0,1] op_sel_hi:[1,0]
	v_pk_mul_f32 v[48:49], v[98:99], v[148:149] op_sel:[0,1] op_sel_hi:[1,0]
	v_pk_mul_f32 v[50:51], v[102:103], v[174:175] op_sel:[0,1] op_sel_hi:[1,0]
	v_pk_mul_f32 v[52:53], v[106:107], v[188:189] op_sel:[0,1] op_sel_hi:[1,0]
	v_pk_mul_f32 v[54:55], v[110:111], v[184:185] op_sel:[0,1] op_sel_hi:[1,0]
	v_pk_mul_f32 v[56:57], v[114:115], v[154:155] op_sel:[0,1] op_sel_hi:[1,0]
	v_pk_mul_f32 v[58:59], v[118:119], v[194:195] op_sel:[0,1] op_sel_hi:[1,0]
	v_pk_mul_f32 v[60:61], v[122:123], v[164:165] op_sel:[0,1] op_sel_hi:[1,0]
	v_pk_mul_f32 v[62:63], v[124:125], v[144:145] op_sel:[0,1] op_sel_hi:[1,0]
	v_pk_mul_f32 v[64:65], v[126:127], v[128:129] op_sel:[0,1] op_sel_hi:[1,0]
	v_pk_fma_f32 v[38:39], v[68:69], v[182:183], v[38:39] op_sel_hi:[0,1,1]
	v_pk_fma_f32 v[40:41], v[72:73], v[152:153], v[40:41] op_sel_hi:[0,1,1]
	v_pk_fma_f32 v[42:43], v[76:77], v[176:177], v[42:43] op_sel_hi:[0,1,1]
	v_pk_fma_f32 v[44:45], v[80:81], v[162:163], v[44:45] op_sel_hi:[0,1,1]
	v_pk_fma_f32 v[46:47], v[84:85], v[178:179], v[46:47] op_sel_hi:[0,1,1]
	v_pk_fma_f32 v[48:49], v[88:89], v[148:149], v[48:49] op_sel_hi:[0,1,1]
	v_pk_fma_f32 v[50:51], v[92:93], v[174:175], v[50:51] op_sel_hi:[0,1,1]
	v_pk_fma_f32 v[52:53], v[96:97], v[188:189], v[52:53] op_sel_hi:[0,1,1]
	v_pk_fma_f32 v[54:55], v[100:101], v[184:185], v[54:55] op_sel_hi:[0,1,1]
	v_pk_fma_f32 v[56:57], v[104:105], v[154:155], v[56:57] op_sel_hi:[0,1,1]
	v_pk_fma_f32 v[58:59], v[108:109], v[194:195], v[58:59] op_sel_hi:[0,1,1]
	v_pk_fma_f32 v[60:61], v[112:113], v[164:165], v[60:61] op_sel_hi:[0,1,1]
	v_pk_fma_f32 v[62:63], v[116:117], v[144:145], v[62:63] op_sel_hi:[0,1,1]
	v_pk_fma_f32 v[64:65], v[120:121], v[128:129], v[64:65] op_sel_hi:[0,1,1]
	ds_write2_b64 v2, v[130:131], v[34:35] offset1:16
	ds_write2_b64 v2, v[18:19], v[50:51] offset0:33 offset1:49
	ds_write2_b64 v2, v[10:11], v[42:43] offset0:66 offset1:82
	ds_write2_b64 v2, v[26:27], v[58:59] offset0:99 offset1:115
	ds_write2_b64 v2, v[6:7], v[38:39] offset0:132 offset1:148
	ds_write2_b64 v2, v[22:23], v[54:55] offset0:165 offset1:181
	ds_write2_b64 v2, v[14:15], v[46:47] offset0:198 offset1:214
	ds_write2_b64 v2, v[30:31], v[62:63] offset0:231 offset1:247
	ds_write2_b64 v143, v[4:5], v[36:37] offset0:8 offset1:24
	ds_write2_b64 v143, v[20:21], v[52:53] offset0:41 offset1:57
	ds_write2_b64 v143, v[12:13], v[44:45] offset0:74 offset1:90
	ds_write2_b64 v143, v[28:29], v[60:61] offset0:107 offset1:123
	ds_write2_b64 v143, v[8:9], v[40:41] offset0:140 offset1:156
	ds_write2_b64 v143, v[24:25], v[56:57] offset0:173 offset1:189
	ds_write2_b64 v143, v[16:17], v[48:49] offset0:206 offset1:222
	ds_write2_b64 v143, v[32:33], v[64:65] offset0:239 offset1:255
	s_waitcnt lgkmcnt(0)
	s_barrier
	s_nop 0
	v_ashrrev_i32_e32 v2, 31, v142
	v_lshrrev_b32_e32 v2, 23, v2
	v_add_u32_e32 v2, v142, v2
	v_ashrrev_i32_e32 v2, 9, v2
	v_mul_i32_i24_e32 v4, 0x200, v2
	v_sub_u32_e32 v144, v142, v4
	v_lshlrev_b32_e32 v143, 14, v2
	v_lshlrev_b32_e32 v2, 1, v144
	v_bfrev_b32_e32 v2, v2
	v_lshrrev_b32_e32 v2, 22, v2
	v_sub_u32_e32 v2, 0x400, v2
	v_bfrev_b32_e32 v2, v2
	v_lshrrev_b32_e32 v2, 18, v2
	v_and_b32_e32 v2, 0x3ff0, v2
	v_cmp_eq_u32_e32 vcc, 0, v144
	v_lshl_add_u32 v4, v144, 5, v143
	v_lshlrev_b32_e32 v5, 3, v4
	v_cndmask_b32_e64 v2, v2, 16, vcc
	v_ashrrev_i32_e32 v4, 2, v4
	v_or_b32_e32 v2, v2, v143
	v_add3_u32 v56, 0, v5, v4
	v_ashrrev_i32_e32 v4, 5, v2
	v_lshlrev_b32_e32 v2, 3, v2
	v_lshlrev_b32_e32 v4, 3, v4
	v_add3_u32 v2, 0, v2, v4
	ds_read2_b64 v[4:7], v56 offset1:1
	ds_read2_b64 v[8:11], v56 offset0:2 offset1:3
	ds_read2_b64 v[12:15], v2 offset1:1
	ds_read2_b64 v[16:19], v2 offset0:2 offset1:3
	ds_read2_b64 v[20:23], v56 offset0:4 offset1:5
	ds_read2_b64 v[24:27], v56 offset0:6 offset1:7
	ds_read2_b64 v[28:31], v2 offset0:4 offset1:5
	ds_read2_b64 v[32:35], v2 offset0:6 offset1:7
	ds_read2_b64 v[36:39], v56 offset0:8 offset1:9
	ds_read2_b64 v[40:43], v56 offset0:10 offset1:11
	ds_read2_b64 v[48:51], v2 offset0:8 offset1:9
	ds_read2_b64 v[52:55], v2 offset0:10 offset1:11
	ds_read2_b64 v[44:47], v56 offset0:12 offset1:13
	ds_read2_b64 v[56:59], v56 offset0:14 offset1:15
	ds_read2_b64 v[70:73], v2 offset0:12 offset1:13
	ds_read2_b64 v[98:101], v2 offset0:14 offset1:15
	s_waitcnt lgkmcnt(7)
	v_pk_add_f32 v[60:61], v[4:5], v[36:37]
	v_pk_add_f32 v[4:5], v[4:5], v[36:37] neg_lo:[0,1] neg_hi:[0,1]
	v_pk_add_f32 v[36:37], v[6:7], v[38:39]
	v_pk_add_f32 v[6:7], v[6:7], v[38:39] neg_lo:[0,1] neg_hi:[0,1]
	s_waitcnt lgkmcnt(3)
	v_pk_add_f32 v[62:63], v[22:23], v[46:47]
	v_pk_mul_f32 v[38:39], v[6:7], s[24:25]
	v_pk_add_f32 v[22:23], v[22:23], v[46:47] neg_lo:[0,1] neg_hi:[0,1]
	v_pk_fma_f32 v[6:7], v[6:7], s[22:23], v[38:39] op_sel:[0,0,1] op_sel_hi:[1,0,0]
	v_pk_add_f32 v[38:39], v[8:9], v[40:41]
	v_pk_add_f32 v[8:9], v[8:9], v[40:41] neg_lo:[0,1] neg_hi:[0,1]
	v_pk_mul_f32 v[46:47], v[22:23], s[44:45]
	v_pk_mul_f32 v[40:41], v[8:9], s[40:41]
	v_pk_fma_f32 v[22:23], v[22:23], s[50:51], v[46:47] op_sel:[0,0,1] op_sel_hi:[1,0,0] neg_lo:[1,0,0] neg_hi:[1,0,0]
	v_pk_fma_f32 v[8:9], v[8:9], s[38:39], v[40:41] op_sel:[0,0,1] op_sel_hi:[1,0,0]
	v_pk_add_f32 v[40:41], v[10:11], v[42:43]
	v_pk_add_f32 v[10:11], v[10:11], v[42:43] neg_lo:[0,1] neg_hi:[0,1]
	s_waitcnt lgkmcnt(2)
	v_pk_add_f32 v[46:47], v[24:25], v[56:57]
	v_pk_add_f32 v[24:25], v[24:25], v[56:57] neg_lo:[0,1] neg_hi:[0,1]
	v_pk_mul_f32 v[42:43], v[10:11], s[44:45]
	v_pk_mul_f32 v[56:57], v[24:25], s[40:41]
	v_pk_fma_f32 v[10:11], v[10:11], s[50:51], v[42:43] op_sel:[0,0,1] op_sel_hi:[1,0,0]
	v_pk_add_f32 v[42:43], v[20:21], v[44:45]
	v_pk_add_f32 v[44:45], v[20:21], v[44:45] neg_lo:[0,1] neg_hi:[0,1]
	v_pk_fma_f32 v[24:25], v[24:25], s[38:39], v[56:57] op_sel:[0,0,1] op_sel_hi:[1,0,0] neg_lo:[1,0,0] neg_hi:[1,0,0]
	v_pk_add_f32 v[56:57], v[26:27], v[58:59]
	v_pk_add_f32 v[26:27], v[26:27], v[58:59] neg_lo:[0,1] neg_hi:[0,1]
	s_nop 0
	v_pk_mul_f32 v[58:59], v[26:27], s[24:25]
	v_pk_add_f32 v[64:65], v[40:41], v[56:57]
	v_pk_add_f32 v[40:41], v[40:41], v[56:57] neg_lo:[0,1] neg_hi:[0,1]
	v_pk_fma_f32 v[26:27], v[26:27], s[22:23], v[58:59] op_sel:[0,0,1] op_sel_hi:[1,0,0] neg_lo:[1,0,0] neg_hi:[1,0,0]
	v_pk_mul_f32 v[56:57], v[40:41], s[40:41]
	v_pk_add_f32 v[20:21], v[4:5], v[44:45] op_sel:[0,1] op_sel_hi:[1,0] neg_hi:[0,1]
	v_pk_add_f32 v[4:5], v[4:5], v[44:45] op_sel:[0,1] op_sel_hi:[1,0] neg_lo:[0,1]
	v_pk_add_f32 v[44:45], v[6:7], v[22:23]
	v_pk_add_f32 v[6:7], v[6:7], v[22:23] neg_lo:[0,1] neg_hi:[0,1]
	v_pk_fma_f32 v[40:41], v[40:41], s[38:39], v[56:57] op_sel:[0,0,1] op_sel_hi:[1,0,0] neg_lo:[1,0,0] neg_hi:[1,0,0]
	v_pk_mul_f32 v[22:23], v[6:7], s[40:41]
	v_pk_add_f32 v[56:57], v[10:11], v[26:27]
	v_pk_add_f32 v[10:11], v[10:11], v[26:27] neg_lo:[0,1] neg_hi:[0,1]
	v_pk_add_f32 v[58:59], v[60:61], v[42:43]
	v_pk_add_f32 v[42:43], v[60:61], v[42:43] neg_lo:[0,1] neg_hi:[0,1]
	v_pk_add_f32 v[60:61], v[36:37], v[62:63]
	v_pk_add_f32 v[36:37], v[36:37], v[62:63] neg_lo:[0,1] neg_hi:[0,1]
	v_pk_fma_f32 v[6:7], v[6:7], s[38:39], v[22:23] op_sel:[0,0,1] op_sel_hi:[1,0,0]
	v_pk_add_f32 v[22:23], v[8:9], v[24:25]
	v_pk_add_f32 v[24:25], v[8:9], v[24:25] neg_lo:[0,1] neg_hi:[0,1]
	v_pk_mul_f32 v[26:27], v[10:11], s[40:41]
	v_pk_mul_f32 v[62:63], v[36:37], s[40:41]
	v_pk_fma_f32 v[10:11], v[10:11], s[38:39], v[26:27] op_sel:[0,0,1] op_sel_hi:[1,0,0] neg_lo:[1,0,0] neg_hi:[1,0,0]
	v_pk_fma_f32 v[36:37], v[36:37], s[38:39], v[62:63] op_sel:[0,0,1] op_sel_hi:[1,0,0]
	v_pk_add_f32 v[62:63], v[38:39], v[46:47]
	v_pk_add_f32 v[66:67], v[20:21], v[22:23]
	v_pk_add_f32 v[20:21], v[20:21], v[22:23] neg_lo:[0,1] neg_hi:[0,1]
	v_pk_add_f32 v[22:23], v[44:45], v[56:57]
	v_pk_add_f32 v[44:45], v[44:45], v[56:57] neg_lo:[0,1] neg_hi:[0,1]
	v_pk_add_f32 v[8:9], v[4:5], v[24:25] op_sel:[0,1] op_sel_hi:[1,0] neg_hi:[0,1]
	v_pk_add_f32 v[4:5], v[4:5], v[24:25] op_sel:[0,1] op_sel_hi:[1,0] neg_lo:[0,1]
	v_pk_add_f32 v[24:25], v[6:7], v[10:11]
	v_pk_add_f32 v[10:11], v[6:7], v[10:11] neg_lo:[0,1] neg_hi:[0,1]
	v_pk_add_f32 v[26:27], v[58:59], v[62:63]
	v_pk_add_f32 v[58:59], v[58:59], v[62:63] neg_lo:[0,1] neg_hi:[0,1]
	v_pk_add_f32 v[62:63], v[60:61], v[64:65]
	v_pk_add_f32 v[60:61], v[60:61], v[64:65] neg_lo:[0,1] neg_hi:[0,1]
	v_pk_mul_f32 v[56:57], v[44:45], 1.0 op_sel:[1,0] op_sel_hi:[0,0] neg_hi:[1,0]
	v_pk_mul_f32 v[64:65], v[60:61], 1.0 op_sel:[1,0] op_sel_hi:[0,0] neg_hi:[1,0]
	v_pk_add_f32 v[130:131], v[26:27], v[62:63]
	v_pk_add_f32 v[92:93], v[26:27], v[62:63] neg_lo:[0,1] neg_hi:[0,1]
	v_pk_add_f32 v[62:63], v[20:21], v[56:57]
	v_pk_add_f32 v[78:79], v[20:21], v[56:57] neg_lo:[0,1] neg_hi:[0,1]
	v_pk_add_f32 v[56:57], v[4:5], v[10:11] op_sel:[0,1] op_sel_hi:[1,0] neg_hi:[0,1]
	v_pk_add_f32 v[90:91], v[4:5], v[10:11] op_sel:[0,1] op_sel_hi:[1,0] neg_lo:[0,1]
	v_pk_add_f32 v[10:11], v[14:15], v[50:51] neg_lo:[0,1] neg_hi:[0,1]
	v_pk_add_f32 v[46:47], v[38:39], v[46:47] neg_lo:[0,1] neg_hi:[0,1]
	v_pk_add_f32 v[84:85], v[58:59], v[64:65]
	v_pk_add_f32 v[86:87], v[58:59], v[64:65] neg_lo:[0,1] neg_hi:[0,1]
	v_pk_add_f32 v[80:81], v[8:9], v[24:25]
	v_pk_add_f32 v[64:65], v[8:9], v[24:25] neg_lo:[0,1] neg_hi:[0,1]
	v_pk_add_f32 v[4:5], v[12:13], v[48:49]
	v_pk_add_f32 v[6:7], v[12:13], v[48:49] neg_lo:[0,1] neg_hi:[0,1]
	v_pk_add_f32 v[8:9], v[14:15], v[50:51]
	v_pk_mul_f32 v[12:13], v[10:11], s[24:25]
	v_pk_add_f32 v[14:15], v[16:17], v[52:53] neg_lo:[0,1] neg_hi:[0,1]
	v_pk_fma_f32 v[10:11], v[10:11], s[22:23], v[12:13] op_sel:[0,0,1] op_sel_hi:[1,0,0]
	v_pk_add_f32 v[12:13], v[16:17], v[52:53]
	v_pk_mul_f32 v[16:17], v[14:15], s[40:41]
	v_pk_add_f32 v[38:39], v[42:43], v[46:47] op_sel:[0,1] op_sel_hi:[1,0] neg_hi:[0,1]
	v_pk_add_f32 v[42:43], v[42:43], v[46:47] op_sel:[0,1] op_sel_hi:[1,0] neg_lo:[0,1]
	v_pk_add_f32 v[46:47], v[36:37], v[40:41]
	v_pk_fma_f32 v[14:15], v[14:15], s[38:39], v[16:17] op_sel:[0,0,1] op_sel_hi:[1,0,0]
	v_pk_add_f32 v[16:17], v[18:19], v[54:55]
	v_pk_add_f32 v[18:19], v[18:19], v[54:55] neg_lo:[0,1] neg_hi:[0,1]
	v_pk_add_f32 v[88:89], v[38:39], v[46:47]
	v_pk_add_f32 v[68:69], v[38:39], v[46:47] neg_lo:[0,1] neg_hi:[0,1]
	v_pk_add_f32 v[96:97], v[66:67], v[22:23]
	v_pk_add_f32 v[46:47], v[66:67], v[22:23] neg_lo:[0,1] neg_hi:[0,1]
	v_pk_mul_f32 v[20:21], v[18:19], s[44:45]
	s_waitcnt lgkmcnt(1)
	v_pk_add_f32 v[24:25], v[28:29], v[70:71] neg_lo:[0,1] neg_hi:[0,1]
	v_pk_add_f32 v[26:27], v[30:31], v[72:73] neg_lo:[0,1] neg_hi:[0,1]
	v_pk_fma_f32 v[18:19], v[18:19], s[50:51], v[20:21] op_sel:[0,0,1] op_sel_hi:[1,0,0]
	v_pk_add_f32 v[20:21], v[28:29], v[70:71]
	v_pk_add_f32 v[22:23], v[30:31], v[72:73]
	v_pk_mul_f32 v[28:29], v[26:27], s[44:45]
	s_waitcnt lgkmcnt(0)
	v_pk_add_f32 v[30:31], v[32:33], v[98:99] neg_lo:[0,1] neg_hi:[0,1]
	v_pk_fma_f32 v[26:27], v[26:27], s[50:51], v[28:29] op_sel:[0,0,1] op_sel_hi:[1,0,0] neg_lo:[1,0,0] neg_hi:[1,0,0]
	v_pk_add_f32 v[28:29], v[32:33], v[98:99]
	v_pk_mul_f32 v[32:33], v[30:31], s[40:41]
	v_pk_add_f32 v[36:37], v[36:37], v[40:41] neg_lo:[0,1] neg_hi:[0,1]
	v_pk_fma_f32 v[30:31], v[30:31], s[38:39], v[32:33] op_sel:[0,0,1] op_sel_hi:[1,0,0] neg_lo:[1,0,0] neg_hi:[1,0,0]
	v_pk_add_f32 v[32:33], v[34:35], v[100:101]
	v_pk_add_f32 v[34:35], v[34:35], v[100:101] neg_lo:[0,1] neg_hi:[0,1]
	v_pk_mul_f32 v[40:41], v[36:37], 1.0 op_sel:[1,0] op_sel_hi:[0,0] neg_hi:[1,0]
	v_pk_mul_f32 v[36:37], v[34:35], s[24:25]
	v_mov_b32_e32 v2, v130
	v_pk_fma_f32 v[34:35], v[34:35], s[22:23], v[36:37] op_sel:[0,0,1] op_sel_hi:[1,0,0] neg_lo:[1,0,0] neg_hi:[1,0,0]
	v_pk_add_f32 v[36:37], v[4:5], v[20:21]
	v_pk_add_f32 v[4:5], v[4:5], v[20:21] neg_lo:[0,1] neg_hi:[0,1]
	v_pk_add_f32 v[20:21], v[8:9], v[22:23]
	v_pk_add_f32 v[8:9], v[8:9], v[22:23] neg_lo:[0,1] neg_hi:[0,1]
	v_cmp_ne_u32_e64 s[0:1], 0, v144
	v_pk_mul_f32 v[22:23], v[8:9], s[40:41]
	v_pk_add_f32 v[74:75], v[42:43], v[40:41]
	v_pk_fma_f32 v[8:9], v[8:9], s[38:39], v[22:23] op_sel:[0,0,1] op_sel_hi:[1,0,0]
	v_pk_add_f32 v[22:23], v[12:13], v[28:29]
	v_pk_add_f32 v[28:29], v[12:13], v[28:29] neg_lo:[0,1] neg_hi:[0,1]
	v_pk_add_f32 v[94:95], v[42:43], v[40:41] neg_lo:[0,1] neg_hi:[0,1]
	v_pk_add_f32 v[12:13], v[16:17], v[32:33]
	v_pk_add_f32 v[16:17], v[16:17], v[32:33] neg_lo:[0,1] neg_hi:[0,1]
	s_nop 0
	v_pk_mul_f32 v[32:33], v[16:17], s[40:41]
	s_nop 0
	v_pk_fma_f32 v[16:17], v[16:17], s[38:39], v[32:33] op_sel:[0,0,1] op_sel_hi:[1,0,0] neg_lo:[1,0,0] neg_hi:[1,0,0]
	v_pk_add_f32 v[32:33], v[6:7], v[24:25] op_sel:[0,1] op_sel_hi:[1,0] neg_hi:[0,1]
	v_pk_add_f32 v[6:7], v[6:7], v[24:25] op_sel:[0,1] op_sel_hi:[1,0] neg_lo:[0,1]
	v_pk_add_f32 v[24:25], v[10:11], v[26:27]
	v_pk_add_f32 v[10:11], v[10:11], v[26:27] neg_lo:[0,1] neg_hi:[0,1]
	s_nop 0
	v_pk_mul_f32 v[26:27], v[10:11], s[40:41]
	s_nop 0
	v_pk_fma_f32 v[10:11], v[10:11], s[38:39], v[26:27] op_sel:[0,0,1] op_sel_hi:[1,0,0]
	v_pk_add_f32 v[26:27], v[14:15], v[30:31]
	v_pk_add_f32 v[30:31], v[14:15], v[30:31] neg_lo:[0,1] neg_hi:[0,1]
	s_nop 0
	v_pk_add_f32 v[14:15], v[18:19], v[34:35]
	v_pk_add_f32 v[18:19], v[18:19], v[34:35] neg_lo:[0,1] neg_hi:[0,1]
	s_nop 0
	v_pk_mul_f32 v[34:35], v[18:19], s[40:41]
	s_nop 0
	v_pk_fma_f32 v[18:19], v[18:19], s[38:39], v[34:35] op_sel:[0,0,1] op_sel_hi:[1,0,0] neg_lo:[1,0,0] neg_hi:[1,0,0]
	v_pk_add_f32 v[34:35], v[36:37], v[22:23]
	v_pk_add_f32 v[22:23], v[36:37], v[22:23] neg_lo:[0,1] neg_hi:[0,1]
	v_pk_add_f32 v[36:37], v[20:21], v[12:13]
	v_pk_add_f32 v[12:13], v[20:21], v[12:13] neg_lo:[0,1] neg_hi:[0,1]
	v_pk_add_f32 v[98:99], v[34:35], v[36:37]
	v_pk_mul_f32 v[20:21], v[12:13], 1.0 op_sel:[1,0] op_sel_hi:[0,0] neg_hi:[1,0]
	v_pk_add_f32 v[12:13], v[4:5], v[28:29] op_sel:[0,1] op_sel_hi:[1,0] neg_hi:[0,1]
	v_pk_add_f32 v[4:5], v[4:5], v[28:29] op_sel:[0,1] op_sel_hi:[1,0] neg_lo:[0,1]
	v_pk_add_f32 v[28:29], v[8:9], v[16:17]
	v_pk_add_f32 v[8:9], v[8:9], v[16:17] neg_lo:[0,1] neg_hi:[0,1]
	v_pk_add_f32 v[100:101], v[34:35], v[36:37] neg_lo:[0,1] neg_hi:[0,1]
	v_pk_mul_f32 v[16:17], v[8:9], 1.0 op_sel:[1,0] op_sel_hi:[0,0] neg_hi:[1,0]
	v_pk_add_f32 v[8:9], v[32:33], v[26:27]
	v_pk_add_f32 v[26:27], v[32:33], v[26:27] neg_lo:[0,1] neg_hi:[0,1]
	v_pk_add_f32 v[32:33], v[24:25], v[14:15]
	v_pk_add_f32 v[14:15], v[24:25], v[14:15] neg_lo:[0,1] neg_hi:[0,1]
	v_pk_add_f32 v[102:103], v[22:23], v[20:21]
	v_pk_mul_f32 v[24:25], v[14:15], 1.0 op_sel:[1,0] op_sel_hi:[0,0] neg_hi:[1,0]
	v_pk_add_f32 v[14:15], v[6:7], v[30:31] op_sel:[0,1] op_sel_hi:[1,0] neg_hi:[0,1]
	v_pk_add_f32 v[6:7], v[6:7], v[30:31] op_sel:[0,1] op_sel_hi:[1,0] neg_lo:[0,1]
	v_pk_add_f32 v[30:31], v[10:11], v[18:19]
	v_pk_add_f32 v[10:11], v[10:11], v[18:19] neg_lo:[0,1] neg_hi:[0,1]
	v_pk_add_f32 v[104:105], v[22:23], v[20:21] neg_lo:[0,1] neg_hi:[0,1]
	v_pk_mul_f32 v[18:19], v[10:11], 1.0 op_sel:[1,0] op_sel_hi:[0,0] neg_hi:[1,0]
	v_pk_add_f32 v[106:107], v[12:13], v[28:29]
	v_pk_add_f32 v[108:109], v[12:13], v[28:29] neg_lo:[0,1] neg_hi:[0,1]
	v_pk_add_f32 v[110:111], v[4:5], v[16:17]
	v_pk_add_f32 v[112:113], v[4:5], v[16:17] neg_lo:[0,1] neg_hi:[0,1]
	v_pk_add_f32 v[114:115], v[8:9], v[32:33]
	v_pk_add_f32 v[116:117], v[8:9], v[32:33] neg_lo:[0,1] neg_hi:[0,1]
	v_pk_add_f32 v[118:119], v[26:27], v[24:25]
	v_pk_add_f32 v[120:121], v[26:27], v[24:25] neg_lo:[0,1] neg_hi:[0,1]
	v_pk_add_f32 v[122:123], v[14:15], v[30:31]
	v_pk_add_f32 v[124:125], v[14:15], v[30:31] neg_lo:[0,1] neg_hi:[0,1]
	v_pk_add_f32 v[126:127], v[6:7], v[18:19]
	v_pk_add_f32 v[128:129], v[6:7], v[18:19] neg_lo:[0,1] neg_hi:[0,1]
	v_pk_mov_b32 v[4:5], v[130:131], v[2:3] op_sel:[1,1]
	v_mov_b64_e32 v[6:7], v[2:3]
	s_and_saveexec_b64 s[50:51], s[0:1]
	s_xor_b64 s[0:1], exec, s[50:51]
	s_cbranch_execz .LBB0_562
	v_pk_add_f32 v[4:5], v[96:97], v[112:113]
	v_pk_add_f32 v[24:25], v[96:97], v[112:113] neg_lo:[0,1] neg_hi:[0,1]
	v_pk_add_f32 v[148:149], v[130:131], v[128:129]
	v_pk_add_f32 v[8:9], v[130:131], v[128:129] neg_lo:[0,1] neg_hi:[0,1]
	v_pk_add_f32 v[128:129], v[126:127], v[92:93]
	v_pk_add_f32 v[10:11], v[126:127], v[92:93] neg_lo:[0,1] neg_hi:[0,1]
	v_pk_add_f32 v[92:93], v[84:85], v[124:125]
	v_pk_add_f32 v[12:13], v[84:85], v[124:125] neg_lo:[0,1] neg_hi:[0,1]
	v_pk_add_f32 v[84:85], v[122:123], v[86:87]
	v_pk_add_f32 v[14:15], v[122:123], v[86:87] neg_lo:[0,1] neg_hi:[0,1]
	v_pk_add_f32 v[86:87], v[88:89], v[120:121]
	v_pk_add_f32 v[16:17], v[88:89], v[120:121] neg_lo:[0,1] neg_hi:[0,1]
	v_pk_add_f32 v[88:89], v[118:119], v[68:69]
	v_pk_add_f32 v[18:19], v[118:119], v[68:69] neg_lo:[0,1] neg_hi:[0,1]
	v_pk_add_f32 v[68:69], v[74:75], v[116:117]
	v_pk_add_f32 v[20:21], v[74:75], v[116:117] neg_lo:[0,1] neg_hi:[0,1]
	v_pk_add_f32 v[74:75], v[114:115], v[94:95]
	v_pk_add_f32 v[22:23], v[114:115], v[94:95] neg_lo:[0,1] neg_hi:[0,1]
	v_pk_mov_b32 v[6:7], v[4:5], v[24:25] op_sel:[0,1]
	v_pk_mov_b32 v[4:5], v[4:5], v[24:25] op_sel:[1,0]
	v_pk_add_f32 v[94:95], v[110:111], v[46:47]
	v_pk_add_f32 v[24:25], v[110:111], v[46:47] neg_lo:[0,1] neg_hi:[0,1]
	v_pk_add_f32 v[46:47], v[62:63], v[108:109]
	v_pk_add_f32 v[26:27], v[62:63], v[108:109] neg_lo:[0,1] neg_hi:[0,1]
	v_pk_add_f32 v[62:63], v[106:107], v[78:79]
	v_pk_add_f32 v[28:29], v[106:107], v[78:79] neg_lo:[0,1] neg_hi:[0,1]
	v_pk_add_f32 v[78:79], v[80:81], v[104:105]
	v_pk_add_f32 v[30:31], v[80:81], v[104:105] neg_lo:[0,1] neg_hi:[0,1]
	v_pk_add_f32 v[80:81], v[102:103], v[64:65]
	v_pk_add_f32 v[32:33], v[102:103], v[64:65] neg_lo:[0,1] neg_hi:[0,1]
	v_pk_add_f32 v[64:65], v[56:57], v[100:101]
	v_pk_add_f32 v[34:35], v[56:57], v[100:101] neg_lo:[0,1] neg_hi:[0,1]
	v_pk_add_f32 v[56:57], v[98:99], v[90:91]
	v_pk_add_f32 v[36:37], v[98:99], v[90:91] neg_lo:[0,1] neg_hi:[0,1]
	v_pk_mul_f32 v[6:7], v[6:7], 0.5 op_sel_hi:[1,0]
	v_pk_mul_f32 v[4:5], v[4:5], s[46:47]
	v_mov_b32_e32 v39, v8
	v_mov_b32_e32 v38, v149
	v_mov_b32_e32 v41, v10
	v_mov_b32_e32 v40, v129
	v_mov_b32_e32 v43, v12
	v_mov_b32_e32 v42, v93
	v_mov_b32_e32 v45, v14
	v_mov_b32_e32 v44, v85
	v_mov_b32_e32 v49, v16
	v_mov_b32_e32 v48, v87
	v_mov_b32_e32 v51, v18
	v_mov_b32_e32 v50, v89
	v_mov_b32_e32 v53, v20
	v_mov_b32_e32 v52, v69
	v_mov_b32_e32 v55, v22
	v_mov_b32_e32 v54, v75
	v_mov_b32_e32 v59, v24
	v_mov_b32_e32 v58, v95
	v_mov_b32_e32 v61, v26
	v_mov_b32_e32 v60, v47
	v_mov_b32_e32 v67, v28
	v_mov_b32_e32 v66, v63
	v_mov_b32_e32 v71, v30
	v_mov_b32_e32 v70, v79
	v_mov_b32_e32 v73, v32
	v_mov_b32_e32 v72, v81
	v_mov_b32_e32 v77, v34
	v_mov_b32_e32 v76, v65
	v_mov_b32_e32 v83, v36
	v_mov_b32_e32 v82, v57
	v_mov_b32_e32 v8, v148
	v_mov_b32_e32 v10, v128
	v_mov_b32_e32 v12, v92
	v_mov_b32_e32 v14, v84
	v_mov_b32_e32 v16, v86
	v_mov_b32_e32 v18, v88
	v_mov_b32_e32 v20, v68
	v_mov_b32_e32 v22, v74
	v_mov_b32_e32 v24, v94
	v_mov_b32_e32 v26, v46
	v_mov_b32_e32 v28, v62
	v_mov_b32_e32 v30, v78
	v_mov_b32_e32 v32, v80
	v_mov_b32_e32 v34, v64
	v_mov_b32_e32 v36, v56
.LBB0_562:
	s_andn2_saveexec_b64 s[0:1], s[0:1]
	s_cbranch_execz .LBB0_564
	s_lshl_b64 s[50:51], s[48:49], 2
	v_pk_add_f32 v[38:39], v[98:99], v[128:129]
	v_pk_add_f32 v[98:99], v[98:99], v[128:129] neg_lo:[0,1] neg_hi:[0,1]
	v_pk_add_f32 v[40:41], v[126:127], v[100:101]
	v_pk_add_f32 v[100:101], v[126:127], v[100:101] neg_lo:[0,1] neg_hi:[0,1]
	v_pk_add_f32 v[42:43], v[102:103], v[124:125]
	v_pk_add_f32 v[102:103], v[102:103], v[124:125] neg_lo:[0,1] neg_hi:[0,1]
	v_pk_add_f32 v[44:45], v[122:123], v[104:105]
	v_pk_add_f32 v[104:105], v[122:123], v[104:105] neg_lo:[0,1] neg_hi:[0,1]
	v_pk_add_f32 v[48:49], v[106:107], v[120:121]
	v_pk_add_f32 v[106:107], v[106:107], v[120:121] neg_lo:[0,1] neg_hi:[0,1]
	v_pk_add_f32 v[50:51], v[118:119], v[108:109]
	v_pk_add_f32 v[108:109], v[118:119], v[108:109] neg_lo:[0,1] neg_hi:[0,1]
	v_pk_add_f32 v[52:53], v[110:111], v[116:117]
	v_pk_add_f32 v[110:111], v[110:111], v[116:117] neg_lo:[0,1] neg_hi:[0,1]
	v_pk_add_f32 v[54:55], v[114:115], v[112:113]
	v_pk_add_f32 v[112:113], v[114:115], v[112:113] neg_lo:[0,1] neg_hi:[0,1]
	s_add_u32 s50, s6, s50
	v_pk_add_f32 v[58:59], v[96:97], v[90:91]
	v_pk_add_f32 v[90:91], v[96:97], v[90:91] neg_lo:[0,1] neg_hi:[0,1]
	v_pk_add_f32 v[60:61], v[88:89], v[94:95]
	v_pk_add_f32 v[88:89], v[88:89], v[94:95] neg_lo:[0,1] neg_hi:[0,1]
	v_pk_add_f32 v[66:67], v[80:81], v[78:79]
	v_pk_add_f32 v[78:79], v[80:81], v[78:79] neg_lo:[0,1] neg_hi:[0,1]
	v_pk_add_f32 v[70:71], v[84:85], v[86:87]
	v_pk_add_f32 v[80:81], v[84:85], v[86:87] neg_lo:[0,1] neg_hi:[0,1]
	v_pk_add_f32 v[72:73], v[62:63], v[64:65]
	v_pk_add_f32 v[62:63], v[62:63], v[64:65] neg_lo:[0,1] neg_hi:[0,1]
	v_pk_add_f32 v[64:65], v[74:75], v[68:69]
	v_pk_add_f32 v[68:69], v[74:75], v[68:69] neg_lo:[0,1] neg_hi:[0,1]
	v_pk_add_f32 v[74:75], v[56:57], v[46:47]
	v_pk_add_f32 v[46:47], v[56:57], v[46:47] neg_lo:[0,1] neg_hi:[0,1]
	s_addc_u32 s51, s7, s51
	v_pk_mov_b32 v[36:37], v[74:75], v[46:47] op_sel:[0,1]
	s_nop 0
	v_pk_mov_b32 v[34:35], v[64:65], v[68:69] op_sel:[0,1]
	s_nop 0
	v_pk_mov_b32 v[32:33], v[72:73], v[62:63] op_sel:[0,1]
	v_pk_mov_b32 v[30:31], v[70:71], v[80:81] op_sel:[0,1]
	v_pk_mov_b32 v[28:29], v[66:67], v[78:79] op_sel:[0,1]
	v_pk_mov_b32 v[26:27], v[60:61], v[88:89] op_sel:[0,1]
	v_pk_mov_b32 v[24:25], v[58:59], v[90:91] op_sel:[0,1]
	v_pk_mov_b32 v[22:23], v[54:55], v[112:113] op_sel:[0,1]
	v_pk_mov_b32 v[20:21], v[52:53], v[110:111] op_sel:[0,1]
	v_pk_mov_b32 v[18:19], v[50:51], v[108:109] op_sel:[0,1]
	v_pk_mov_b32 v[16:17], v[48:49], v[106:107] op_sel:[0,1]
	v_pk_mov_b32 v[14:15], v[44:45], v[104:105] op_sel:[0,1]
	v_pk_mov_b32 v[12:13], v[42:43], v[102:103] op_sel:[0,1]
	v_pk_mov_b32 v[10:11], v[40:41], v[100:101] op_sel:[0,1]
	v_pk_mov_b32 v[8:9], v[38:39], v[98:99] op_sel:[0,1]
	v_pk_mov_b32 v[82:83], v[74:75], v[46:47] op_sel:[1,0]
	v_pk_mov_b32 v[76:77], v[64:65], v[68:69] op_sel:[1,0]
	v_mov_b32_e32 v72, v73
	v_mov_b32_e32 v73, v62
	v_mov_b32_e32 v70, v71
	v_mov_b32_e32 v71, v80
	v_mov_b32_e32 v66, v67
	v_mov_b32_e32 v67, v78
	v_mov_b32_e32 v60, v61
	v_mov_b32_e32 v61, v88
	v_mov_b32_e32 v58, v59
	v_mov_b32_e32 v59, v90
	v_mov_b32_e32 v54, v55
	v_mov_b32_e32 v55, v112
	v_mov_b32_e32 v52, v53
	v_mov_b32_e32 v53, v110
	v_mov_b32_e32 v50, v51
	v_mov_b32_e32 v51, v108
	v_mov_b32_e32 v48, v49
	v_mov_b32_e32 v49, v106
	v_mov_b32_e32 v44, v45
	v_mov_b32_e32 v45, v104
	v_mov_b32_e32 v42, v43
	v_mov_b32_e32 v43, v102
	v_mov_b32_e32 v40, v41
	v_mov_b32_e32 v41, v100
	v_mov_b32_e32 v38, v39
	v_mov_b32_e32 v39, v98
	global_store_dwordx2 v3, v[92:93], s[50:51]

.LBB0_574:
	s_or_b64 exec, exec, s[0:1]
	v_mov_b32_e32 v2, v142
	s_waitcnt lgkmcnt(0)
	s_barrier
	s_mov_b32 s19, s16
	v_and_b32_e32 v4, 0xff, v2
	v_lshlrev_b32_e32 v5, 5, v2
	v_and_or_b32 v4, v5, s68, v4
	v_ashrrev_i32_e32 v5, 5, v4
	v_cvt_f32_ubyte0_e32 v2, v2
	v_lshlrev_b32_e32 v7, 3, v4
	v_mul_f32_e32 v2, 0x39000000, v2
	v_lshlrev_b32_e32 v5, 3, v5
	v_sin_f32_e32 v4, v2
	v_cos_f32_e32 v6, v2
	v_add3_u32 v2, 0, v7, v5
	ds_read_b64 v[128:129], v2
	ds_read_b64 v[130:131], v2 offset:2112
	ds_read_b64 v[144:145], v2 offset:4224
	ds_read_b64 v[148:149], v2 offset:6336
	ds_read_b64 v[150:151], v2 offset:8448
	ds_read_b64 v[152:153], v2 offset:10560
	ds_read_b64 v[154:155], v2 offset:12672
	ds_read_b64 v[156:157], v2 offset:14784
	ds_read_b64 v[158:159], v2 offset:16896
	ds_read_b64 v[160:161], v2 offset:19008
	ds_read_b64 v[162:163], v2 offset:21120
	ds_read_b64 v[164:165], v2 offset:23232
	ds_read_b64 v[166:167], v2 offset:25344
	ds_read_b64 v[168:169], v2 offset:27456
	ds_read_b64 v[170:171], v2 offset:29568
	ds_read_b64 v[172:173], v2 offset:31680
	ds_read_b64 v[174:175], v2 offset:33792
	ds_read_b64 v[176:177], v2 offset:35904
	ds_read_b64 v[178:179], v2 offset:38016
	ds_read_b64 v[180:181], v2 offset:40128
	ds_read_b64 v[182:183], v2 offset:42240
	ds_read_b64 v[184:185], v2 offset:44352
	ds_read_b64 v[186:187], v2 offset:46464
	ds_read_b64 v[188:189], v2 offset:48576
	ds_read_b64 v[190:191], v2 offset:50688
	ds_read_b64 v[192:193], v2 offset:52800
	ds_read_b64 v[194:195], v2 offset:54912
	ds_read_b64 v[196:197], v2 offset:57024
	ds_read_b64 v[198:199], v2 offset:59136
	ds_read_b64 v[204:205], v2 offset:61248
	ds_read_b64 v[206:207], v2 offset:63360
	ds_read_b64 v[208:209], v2 offset:65472
	s_waitcnt lgkmcnt(14)
	v_pk_add_f32 v[210:211], v[128:129], v[174:175]
	v_pk_add_f32 v[128:129], v[128:129], v[174:175] neg_lo:[0,1] neg_hi:[0,1]
	v_pk_add_f32 v[174:175], v[130:131], v[176:177]
	v_pk_add_f32 v[130:131], v[130:131], v[176:177] neg_lo:[0,1] neg_hi:[0,1]
	s_mov_b32 s0, s9
	v_pk_mul_f32 v[176:177], v[130:131], s[18:19]
	s_mov_b32 s41, s38
	v_pk_fma_f32 v[130:131], v[130:131], s[0:1], v[176:177] op_sel:[0,0,1] op_sel_hi:[1,0,0]
	s_waitcnt lgkmcnt(13)
	v_pk_add_f32 v[176:177], v[144:145], v[178:179]
	v_pk_add_f32 v[144:145], v[144:145], v[178:179] neg_lo:[0,1] neg_hi:[0,1]
	s_mov_b32 s43, s26
	v_pk_mul_f32 v[178:179], v[144:145], s[24:25]
	s_mov_b32 s62, s37
	v_pk_fma_f32 v[144:145], v[144:145], s[22:23], v[178:179] op_sel:[0,0,1] op_sel_hi:[1,0,0]
	s_waitcnt lgkmcnt(12)
	v_pk_add_f32 v[178:179], v[148:149], v[180:181]
	v_pk_add_f32 v[148:149], v[148:149], v[180:181] neg_lo:[0,1] neg_hi:[0,1]
	s_mov_b32 s45, s22
	v_pk_mul_f32 v[180:181], v[148:149], s[36:37]
	s_mov_b32 s50, s25
	v_pk_fma_f32 v[148:149], v[148:149], s[26:27], v[180:181] op_sel:[0,0,1] op_sel_hi:[1,0,0]
	s_waitcnt lgkmcnt(11)
	v_pk_add_f32 v[180:181], v[150:151], v[182:183]
	v_pk_add_f32 v[150:151], v[150:151], v[182:183] neg_lo:[0,1] neg_hi:[0,1]
	v_xor_b32_e32 v7, 0x80000000, v4
	v_pk_mul_f32 v[182:183], v[150:151], s[40:41]
	v_mov_b32_e32 v5, v7
	v_pk_fma_f32 v[150:151], v[150:151], s[38:39], v[182:183] op_sel:[0,0,1] op_sel_hi:[1,0,0]
	s_waitcnt lgkmcnt(10)
	v_pk_add_f32 v[182:183], v[152:153], v[184:185]
	v_pk_add_f32 v[152:153], v[152:153], v[184:185] neg_lo:[0,1] neg_hi:[0,1]
	v_pk_mul_f32 v[8:9], v[6:7], v[4:5] op_sel:[1,0] op_sel_hi:[0,1]
	v_pk_mul_f32 v[184:185], v[152:153], s[42:43]
	v_pk_fma_f32 v[8:9], v[6:7], v[6:7], v[8:9] op_sel_hi:[1,0,1]
	v_pk_fma_f32 v[152:153], v[152:153], s[62:63], v[184:185] op_sel:[0,0,1] op_sel_hi:[1,0,0]
	s_waitcnt lgkmcnt(9)
	v_pk_add_f32 v[184:185], v[154:155], v[186:187]
	v_pk_add_f32 v[154:155], v[154:155], v[186:187] neg_lo:[0,1] neg_hi:[0,1]
	v_pk_mul_f32 v[14:15], v[8:9], 1.0 op_sel:[1,0] op_sel_hi:[1,0] neg_lo:[1,0]
	v_pk_mul_f32 v[186:187], v[154:155], s[44:45]
	s_nop 0
	v_pk_fma_f32 v[154:155], v[154:155], s[50:51], v[186:187] op_sel:[0,0,1] op_sel_hi:[1,0,0]
	s_waitcnt lgkmcnt(8)
	v_pk_add_f32 v[186:187], v[156:157], v[188:189]
	v_pk_add_f32 v[156:157], v[156:157], v[188:189] neg_lo:[0,1] neg_hi:[0,1]
	v_pk_mul_f32 v[12:13], v[8:9], v[14:15] op_sel:[1,0] op_sel_hi:[0,1]
	v_pk_mul_f32 v[188:189], v[156:157], s[8:9]
	v_pk_fma_f32 v[12:13], v[8:9], v[8:9], v[12:13] op_sel_hi:[1,0,1]
	v_pk_fma_f32 v[156:157], v[156:157], s[16:17], v[188:189] op_sel:[0,0,1] op_sel_hi:[1,0,0]
	s_waitcnt lgkmcnt(7)
	v_pk_add_f32 v[188:189], v[158:159], v[190:191]
	v_pk_add_f32 v[190:191], v[158:159], v[190:191] neg_lo:[0,1] neg_hi:[0,1]
	v_pk_mul_f32 v[16:17], v[12:13], 1.0 op_sel:[1,0] op_sel_hi:[1,0] neg_lo:[1,0]
	s_waitcnt lgkmcnt(6)
	v_pk_add_f32 v[158:159], v[160:161], v[192:193]
	v_pk_add_f32 v[160:161], v[160:161], v[192:193] neg_lo:[0,1] neg_hi:[0,1]
	s_nop 0
	v_pk_mul_f32 v[192:193], v[160:161], s[8:9]
	v_pk_mul_f32 v[28:29], v[12:13], v[16:17] op_sel:[1,0] op_sel_hi:[0,1]
	v_pk_fma_f32 v[160:161], v[160:161], s[16:17], v[192:193] op_sel:[0,0,1] op_sel_hi:[1,0,0] neg_lo:[1,0,0] neg_hi:[1,0,0]
	s_waitcnt lgkmcnt(5)
	v_pk_add_f32 v[192:193], v[162:163], v[194:195]
	v_pk_add_f32 v[162:163], v[162:163], v[194:195] neg_lo:[0,1] neg_hi:[0,1]
	v_pk_fma_f32 v[28:29], v[12:13], v[12:13], v[28:29] op_sel_hi:[1,0,1]
	v_pk_mul_f32 v[194:195], v[162:163], s[44:45]
	v_pk_mul_f32 v[44:45], v[16:17], v[28:29] op_sel:[0,1] op_sel_hi:[1,0]
	v_pk_fma_f32 v[162:163], v[162:163], s[50:51], v[194:195] op_sel:[0,0,1] op_sel_hi:[1,0,0] neg_lo:[1,0,0] neg_hi:[1,0,0]
	s_waitcnt lgkmcnt(4)
	v_pk_add_f32 v[194:195], v[164:165], v[196:197]
	v_pk_add_f32 v[164:165], v[164:165], v[196:197] neg_lo:[0,1] neg_hi:[0,1]
	v_pk_fma_f32 v[44:45], v[12:13], v[28:29], v[44:45] op_sel_hi:[0,1,1]
	v_pk_mul_f32 v[196:197], v[164:165], s[42:43]
	v_pk_mul_f32 v[60:61], v[16:17], v[44:45] op_sel:[0,1] op_sel_hi:[1,0]
	v_pk_fma_f32 v[164:165], v[164:165], s[62:63], v[196:197] op_sel:[0,0,1] op_sel_hi:[1,0,0] neg_lo:[1,0,0] neg_hi:[1,0,0]
	s_waitcnt lgkmcnt(3)
	v_pk_add_f32 v[196:197], v[166:167], v[198:199]
	v_pk_add_f32 v[166:167], v[166:167], v[198:199] neg_lo:[0,1] neg_hi:[0,1]
	v_pk_fma_f32 v[60:61], v[12:13], v[44:45], v[60:61] op_sel_hi:[0,1,1]
	v_pk_mul_f32 v[198:199], v[166:167], s[40:41]
	v_pk_mul_f32 v[76:77], v[16:17], v[60:61] op_sel:[0,1] op_sel_hi:[1,0]
	v_pk_fma_f32 v[166:167], v[166:167], s[38:39], v[198:199] op_sel:[0,0,1] op_sel_hi:[1,0,0] neg_lo:[1,0,0] neg_hi:[1,0,0]
	s_waitcnt lgkmcnt(2)
	v_pk_add_f32 v[198:199], v[168:169], v[204:205]
	v_pk_add_f32 v[168:169], v[168:169], v[204:205] neg_lo:[0,1] neg_hi:[0,1]
	v_pk_fma_f32 v[76:77], v[12:13], v[60:61], v[76:77] op_sel_hi:[0,1,1]
	v_pk_mul_f32 v[204:205], v[168:169], s[36:37]
	v_pk_mul_f32 v[92:93], v[16:17], v[76:77] op_sel:[0,1] op_sel_hi:[1,0]
	v_pk_fma_f32 v[168:169], v[168:169], s[26:27], v[204:205] op_sel:[0,0,1] op_sel_hi:[1,0,0] neg_lo:[1,0,0] neg_hi:[1,0,0]
	s_waitcnt lgkmcnt(1)
	v_pk_add_f32 v[204:205], v[170:171], v[206:207]
	v_pk_add_f32 v[170:171], v[170:171], v[206:207] neg_lo:[0,1] neg_hi:[0,1]
	v_pk_fma_f32 v[92:93], v[12:13], v[76:77], v[92:93] op_sel_hi:[0,1,1]
	v_pk_mul_f32 v[206:207], v[170:171], s[24:25]
	v_pk_mul_f32 v[108:109], v[16:17], v[92:93] op_sel:[0,1] op_sel_hi:[1,0]
	v_pk_fma_f32 v[170:171], v[170:171], s[22:23], v[206:207] op_sel:[0,0,1] op_sel_hi:[1,0,0] neg_lo:[1,0,0] neg_hi:[1,0,0]
	s_waitcnt lgkmcnt(0)
	v_pk_add_f32 v[206:207], v[172:173], v[208:209]
	v_pk_add_f32 v[172:173], v[172:173], v[208:209] neg_lo:[0,1] neg_hi:[0,1]
	v_pk_mul_f32 v[10:11], v[4:5], v[8:9] op_sel:[0,1] op_sel_hi:[1,0]
	v_pk_mul_f32 v[208:209], v[172:173], s[18:19]
	v_pk_fma_f32 v[108:109], v[12:13], v[92:93], v[108:109] op_sel_hi:[0,1,1]
	v_pk_fma_f32 v[172:173], v[172:173], s[0:1], v[208:209] op_sel:[0,0,1] op_sel_hi:[1,0,0] neg_lo:[1,0,0] neg_hi:[1,0,0]
	v_pk_add_f32 v[208:209], v[210:211], v[188:189]
	v_pk_add_f32 v[188:189], v[210:211], v[188:189] neg_lo:[0,1] neg_hi:[0,1]
	v_pk_add_f32 v[210:211], v[174:175], v[158:159]
	v_pk_add_f32 v[158:159], v[174:175], v[158:159] neg_lo:[0,1] neg_hi:[0,1]
	v_pk_fma_f32 v[10:11], v[6:7], v[8:9], v[10:11] op_sel_hi:[0,1,1]
	v_pk_mul_f32 v[174:175], v[158:159], s[24:25]
	v_pk_mul_f32 v[18:19], v[4:5], v[12:13] op_sel:[0,1] op_sel_hi:[1,0]
	v_pk_fma_f32 v[158:159], v[158:159], s[22:23], v[174:175] op_sel:[0,0,1] op_sel_hi:[1,0,0]
	v_pk_add_f32 v[174:175], v[176:177], v[192:193]
	v_pk_add_f32 v[176:177], v[176:177], v[192:193] neg_lo:[0,1] neg_hi:[0,1]
	v_pk_mul_f32 v[32:33], v[4:5], v[28:29] op_sel:[0,1] op_sel_hi:[1,0]
	v_pk_mul_f32 v[192:193], v[176:177], s[40:41]
	v_pk_mul_f32 v[48:49], v[4:5], v[44:45] op_sel:[0,1] op_sel_hi:[1,0]
	v_pk_fma_f32 v[176:177], v[176:177], s[38:39], v[192:193] op_sel:[0,0,1] op_sel_hi:[1,0,0]
	v_pk_add_f32 v[192:193], v[178:179], v[194:195]
	v_pk_add_f32 v[178:179], v[178:179], v[194:195] neg_lo:[0,1] neg_hi:[0,1]
	v_pk_mul_f32 v[64:65], v[4:5], v[60:61] op_sel:[0,1] op_sel_hi:[1,0]
	v_pk_mul_f32 v[194:195], v[178:179], s[44:45]
	v_pk_mul_f32 v[80:81], v[4:5], v[76:77] op_sel:[0,1] op_sel_hi:[1,0]
	v_pk_fma_f32 v[178:179], v[178:179], s[50:51], v[194:195] op_sel:[0,0,1] op_sel_hi:[1,0,0]
	v_pk_add_f32 v[194:195], v[180:181], v[196:197]
	v_pk_add_f32 v[196:197], v[180:181], v[196:197] neg_lo:[0,1] neg_hi:[0,1]
	v_pk_mul_f32 v[96:97], v[4:5], v[92:93] op_sel:[0,1] op_sel_hi:[1,0]
	v_pk_add_f32 v[180:181], v[182:183], v[198:199]
	v_pk_add_f32 v[182:183], v[182:183], v[198:199] neg_lo:[0,1] neg_hi:[0,1]
	v_pk_mul_f32 v[112:113], v[4:5], v[108:109] op_sel:[0,1] op_sel_hi:[1,0]
	v_pk_mul_f32 v[198:199], v[182:183], s[44:45]
	v_pk_mul_f32 v[22:23], v[10:11], 1.0 op_sel:[1,0] op_sel_hi:[1,0] neg_lo:[1,0]
	v_pk_fma_f32 v[182:183], v[182:183], s[50:51], v[198:199] op_sel:[0,0,1] op_sel_hi:[1,0,0] neg_lo:[1,0,0] neg_hi:[1,0,0]
	v_pk_add_f32 v[198:199], v[184:185], v[204:205]
	v_pk_add_f32 v[184:185], v[184:185], v[204:205] neg_lo:[0,1] neg_hi:[0,1]
	s_nop 0
	v_pk_mul_f32 v[204:205], v[184:185], s[40:41]
	v_pk_fma_f32 v[18:19], v[6:7], v[12:13], v[18:19] op_sel_hi:[0,1,1]
	v_pk_fma_f32 v[184:185], v[184:185], s[38:39], v[204:205] op_sel:[0,0,1] op_sel_hi:[1,0,0] neg_lo:[1,0,0] neg_hi:[1,0,0]
	v_pk_add_f32 v[204:205], v[186:187], v[206:207]
	v_pk_add_f32 v[186:187], v[186:187], v[206:207] neg_lo:[0,1] neg_hi:[0,1]
	v_pk_mul_f32 v[20:21], v[14:15], v[12:13] op_sel:[0,1] op_sel_hi:[1,0]
	v_pk_mul_f32 v[206:207], v[186:187], s[24:25]
	v_pk_fma_f32 v[32:33], v[6:7], v[28:29], v[32:33] op_sel_hi:[0,1,1]
	v_pk_fma_f32 v[186:187], v[186:187], s[22:23], v[206:207] op_sel:[0,0,1] op_sel_hi:[1,0,0] neg_lo:[1,0,0] neg_hi:[1,0,0]
	v_pk_add_f32 v[206:207], v[128:129], v[190:191] op_sel:[0,1] op_sel_hi:[1,0] neg_hi:[0,1]
	v_pk_add_f32 v[128:129], v[128:129], v[190:191] op_sel:[0,1] op_sel_hi:[1,0] neg_lo:[0,1]
	v_pk_add_f32 v[190:191], v[130:131], v[160:161]
	v_pk_add_f32 v[130:131], v[130:131], v[160:161] neg_lo:[0,1] neg_hi:[0,1]
	v_pk_mul_f32 v[36:37], v[14:15], v[28:29] op_sel:[0,1] op_sel_hi:[1,0]
	v_pk_mul_f32 v[160:161], v[130:131], s[24:25]
	v_pk_fma_f32 v[48:49], v[6:7], v[44:45], v[48:49] op_sel_hi:[0,1,1]
	v_pk_fma_f32 v[130:131], v[130:131], s[22:23], v[160:161] op_sel:[0,0,1] op_sel_hi:[1,0,0]
	v_pk_add_f32 v[160:161], v[144:145], v[162:163]
	v_pk_add_f32 v[144:145], v[144:145], v[162:163] neg_lo:[0,1] neg_hi:[0,1]
	v_pk_mul_f32 v[52:53], v[14:15], v[44:45] op_sel:[0,1] op_sel_hi:[1,0]
	v_pk_mul_f32 v[162:163], v[144:145], s[40:41]
	v_pk_fma_f32 v[64:65], v[6:7], v[60:61], v[64:65] op_sel_hi:[0,1,1]
	v_pk_fma_f32 v[144:145], v[144:145], s[38:39], v[162:163] op_sel:[0,0,1] op_sel_hi:[1,0,0]
	v_pk_add_f32 v[162:163], v[148:149], v[164:165]
	v_pk_add_f32 v[148:149], v[148:149], v[164:165] neg_lo:[0,1] neg_hi:[0,1]
	v_pk_mul_f32 v[68:69], v[14:15], v[60:61] op_sel:[0,1] op_sel_hi:[1,0]
	v_pk_mul_f32 v[164:165], v[148:149], s[44:45]
	v_pk_fma_f32 v[80:81], v[6:7], v[76:77], v[80:81] op_sel_hi:[0,1,1]
	v_pk_fma_f32 v[148:149], v[148:149], s[50:51], v[164:165] op_sel:[0,0,1] op_sel_hi:[1,0,0]
	v_pk_add_f32 v[164:165], v[150:151], v[166:167]
	v_pk_add_f32 v[166:167], v[150:151], v[166:167] neg_lo:[0,1] neg_hi:[0,1]
	v_pk_mul_f32 v[84:85], v[14:15], v[76:77] op_sel:[0,1] op_sel_hi:[1,0]
	v_pk_add_f32 v[150:151], v[152:153], v[168:169]
	v_pk_add_f32 v[152:153], v[152:153], v[168:169] neg_lo:[0,1] neg_hi:[0,1]
	v_pk_fma_f32 v[96:97], v[6:7], v[92:93], v[96:97] op_sel_hi:[0,1,1]
	v_pk_mul_f32 v[168:169], v[152:153], s[44:45]
	v_pk_mul_f32 v[100:101], v[14:15], v[92:93] op_sel:[0,1] op_sel_hi:[1,0]
	v_pk_fma_f32 v[152:153], v[152:153], s[50:51], v[168:169] op_sel:[0,0,1] op_sel_hi:[1,0,0] neg_lo:[1,0,0] neg_hi:[1,0,0]
	v_pk_add_f32 v[168:169], v[154:155], v[170:171]
	v_pk_add_f32 v[154:155], v[154:155], v[170:171] neg_lo:[0,1] neg_hi:[0,1]
	v_pk_fma_f32 v[112:113], v[6:7], v[108:109], v[112:113] op_sel_hi:[0,1,1]
	v_pk_mul_f32 v[170:171], v[154:155], s[40:41]
	v_pk_mul_f32 v[116:117], v[14:15], v[108:109] op_sel:[0,1] op_sel_hi:[1,0]
	v_pk_fma_f32 v[154:155], v[154:155], s[38:39], v[170:171] op_sel:[0,0,1] op_sel_hi:[1,0,0] neg_lo:[1,0,0] neg_hi:[1,0,0]
	v_pk_add_f32 v[170:171], v[156:157], v[172:173]
	v_pk_add_f32 v[156:157], v[156:157], v[172:173] neg_lo:[0,1] neg_hi:[0,1]
	v_pk_fma_f32 v[20:21], v[8:9], v[12:13], v[20:21] op_sel_hi:[0,1,1]
	v_pk_mul_f32 v[172:173], v[156:157], s[24:25]
	v_pk_mul_f32 v[24:25], v[12:13], v[22:23] op_sel:[1,0] op_sel_hi:[0,1]
	v_pk_fma_f32 v[156:157], v[156:157], s[22:23], v[172:173] op_sel:[0,0,1] op_sel_hi:[1,0,0] neg_lo:[1,0,0] neg_hi:[1,0,0]
	v_pk_add_f32 v[172:173], v[208:209], v[194:195]
	v_pk_add_f32 v[194:195], v[208:209], v[194:195] neg_lo:[0,1] neg_hi:[0,1]
	v_pk_add_f32 v[208:209], v[210:211], v[180:181]
	v_pk_add_f32 v[180:181], v[210:211], v[180:181] neg_lo:[0,1] neg_hi:[0,1]
	v_pk_fma_f32 v[36:37], v[8:9], v[28:29], v[36:37] op_sel_hi:[0,1,1]
	v_pk_mul_f32 v[210:211], v[180:181], s[40:41]
	v_pk_mul_f32 v[40:41], v[22:23], v[28:29] op_sel:[0,1] op_sel_hi:[1,0]
	v_pk_fma_f32 v[180:181], v[180:181], s[38:39], v[210:211] op_sel:[0,0,1] op_sel_hi:[1,0,0]
	v_pk_add_f32 v[210:211], v[174:175], v[198:199]
	v_pk_add_f32 v[198:199], v[174:175], v[198:199] neg_lo:[0,1] neg_hi:[0,1]
	v_pk_fma_f32 v[52:53], v[8:9], v[44:45], v[52:53] op_sel_hi:[0,1,1]
	v_pk_add_f32 v[174:175], v[192:193], v[204:205]
	v_pk_add_f32 v[192:193], v[192:193], v[204:205] neg_lo:[0,1] neg_hi:[0,1]
	v_pk_mul_f32 v[56:57], v[22:23], v[44:45] op_sel:[0,1] op_sel_hi:[1,0]
	v_pk_mul_f32 v[204:205], v[192:193], s[40:41]
	v_pk_fma_f32 v[68:69], v[8:9], v[60:61], v[68:69] op_sel_hi:[0,1,1]
	v_pk_fma_f32 v[192:193], v[192:193], s[38:39], v[204:205] op_sel:[0,0,1] op_sel_hi:[1,0,0] neg_lo:[1,0,0] neg_hi:[1,0,0]
	v_pk_add_f32 v[204:205], v[188:189], v[196:197] op_sel:[0,1] op_sel_hi:[1,0] neg_hi:[0,1]
	v_pk_add_f32 v[188:189], v[188:189], v[196:197] op_sel:[0,1] op_sel_hi:[1,0] neg_lo:[0,1]
	v_pk_add_f32 v[196:197], v[158:159], v[182:183]
	v_pk_add_f32 v[158:159], v[158:159], v[182:183] neg_lo:[0,1] neg_hi:[0,1]
	v_pk_mul_f32 v[72:73], v[22:23], v[60:61] op_sel:[0,1] op_sel_hi:[1,0]
	v_pk_mul_f32 v[182:183], v[158:159], s[40:41]
	v_pk_fma_f32 v[84:85], v[8:9], v[76:77], v[84:85] op_sel_hi:[0,1,1]
	v_pk_fma_f32 v[158:159], v[158:159], s[38:39], v[182:183] op_sel:[0,0,1] op_sel_hi:[1,0,0]
	v_pk_add_f32 v[182:183], v[176:177], v[184:185]
	v_pk_add_f32 v[184:185], v[176:177], v[184:185] neg_lo:[0,1] neg_hi:[0,1]
	v_pk_mul_f32 v[88:89], v[22:23], v[76:77] op_sel:[0,1] op_sel_hi:[1,0]
	v_pk_add_f32 v[176:177], v[178:179], v[186:187]
	v_pk_add_f32 v[178:179], v[178:179], v[186:187] neg_lo:[0,1] neg_hi:[0,1]
	v_pk_fma_f32 v[100:101], v[8:9], v[92:93], v[100:101] op_sel_hi:[0,1,1]
	v_pk_mul_f32 v[186:187], v[178:179], s[40:41]
	v_pk_mul_f32 v[104:105], v[22:23], v[92:93] op_sel:[0,1] op_sel_hi:[1,0]
	v_pk_fma_f32 v[178:179], v[178:179], s[38:39], v[186:187] op_sel:[0,0,1] op_sel_hi:[1,0,0] neg_lo:[1,0,0] neg_hi:[1,0,0]
	v_pk_add_f32 v[186:187], v[206:207], v[164:165]
	v_pk_add_f32 v[164:165], v[206:207], v[164:165] neg_lo:[0,1] neg_hi:[0,1]
	v_pk_add_f32 v[206:207], v[190:191], v[150:151]
	v_pk_add_f32 v[150:151], v[190:191], v[150:151] neg_lo:[0,1] neg_hi:[0,1]
	v_pk_fma_f32 v[116:117], v[8:9], v[108:109], v[116:117] op_sel_hi:[0,1,1]
	v_pk_mul_f32 v[190:191], v[150:151], s[40:41]
	v_pk_mul_f32 v[120:121], v[22:23], v[108:109] op_sel:[0,1] op_sel_hi:[1,0]
	v_pk_fma_f32 v[150:151], v[150:151], s[38:39], v[190:191] op_sel:[0,0,1] op_sel_hi:[1,0,0]
	v_pk_add_f32 v[190:191], v[160:161], v[168:169]
	v_pk_add_f32 v[168:169], v[160:161], v[168:169] neg_lo:[0,1] neg_hi:[0,1]
	v_xor_b32_e32 v26, 0x80000000, v19
	v_pk_add_f32 v[160:161], v[162:163], v[170:171]
	v_pk_add_f32 v[162:163], v[162:163], v[170:171] neg_lo:[0,1] neg_hi:[0,1]
	v_xor_b32_e32 v30, 0x80000000, v21
	v_pk_mul_f32 v[170:171], v[162:163], s[40:41]
	v_pk_fma_f32 v[24:25], v[12:13], v[10:11], v[24:25] op_sel_hi:[1,0,1]
	v_pk_fma_f32 v[162:163], v[162:163], s[38:39], v[170:171] op_sel:[0,0,1] op_sel_hi:[1,0,0] neg_lo:[1,0,0] neg_hi:[1,0,0]
	v_pk_add_f32 v[170:171], v[128:129], v[166:167] op_sel:[0,1] op_sel_hi:[1,0] neg_hi:[0,1]
	v_pk_add_f32 v[128:129], v[128:129], v[166:167] op_sel:[0,1] op_sel_hi:[1,0] neg_lo:[0,1]
	v_pk_add_f32 v[166:167], v[130:131], v[152:153]
	v_pk_add_f32 v[130:131], v[130:131], v[152:153] neg_lo:[0,1] neg_hi:[0,1]
	v_pk_fma_f32 v[40:41], v[10:11], v[28:29], v[40:41] op_sel_hi:[0,1,1]
	v_pk_mul_f32 v[152:153], v[130:131], s[40:41]
	v_pk_fma_f32 v[56:57], v[10:11], v[44:45], v[56:57] op_sel_hi:[0,1,1]
	v_pk_fma_f32 v[130:131], v[130:131], s[38:39], v[152:153] op_sel:[0,0,1] op_sel_hi:[1,0,0]
	v_pk_add_f32 v[152:153], v[144:145], v[154:155]
	v_pk_add_f32 v[154:155], v[144:145], v[154:155] neg_lo:[0,1] neg_hi:[0,1]
	v_pk_fma_f32 v[72:73], v[10:11], v[60:61], v[72:73] op_sel_hi:[0,1,1]
	v_pk_add_f32 v[144:145], v[148:149], v[156:157]
	v_pk_add_f32 v[148:149], v[148:149], v[156:157] neg_lo:[0,1] neg_hi:[0,1]
	v_pk_fma_f32 v[88:89], v[10:11], v[76:77], v[88:89] op_sel_hi:[0,1,1]
	v_pk_mul_f32 v[156:157], v[148:149], s[40:41]
	v_pk_fma_f32 v[104:105], v[10:11], v[92:93], v[104:105] op_sel_hi:[0,1,1]
	v_pk_fma_f32 v[148:149], v[148:149], s[38:39], v[156:157] op_sel:[0,0,1] op_sel_hi:[1,0,0] neg_lo:[1,0,0] neg_hi:[1,0,0]
	v_pk_add_f32 v[156:157], v[172:173], v[210:211]
	v_pk_add_f32 v[172:173], v[172:173], v[210:211] neg_lo:[0,1] neg_hi:[0,1]
	v_pk_add_f32 v[210:211], v[208:209], v[174:175]
	v_pk_add_f32 v[208:209], v[208:209], v[174:175] neg_lo:[0,1] neg_hi:[0,1]
	v_pk_fma_f32 v[120:121], v[10:11], v[108:109], v[120:121] op_sel_hi:[0,1,1]
	v_pk_add_f32 v[174:175], v[194:195], v[198:199] op_sel:[0,1] op_sel_hi:[1,0] neg_hi:[0,1]
	v_pk_add_f32 v[194:195], v[194:195], v[198:199] op_sel:[0,1] op_sel_hi:[1,0] neg_lo:[0,1]
	v_pk_add_f32 v[198:199], v[180:181], v[192:193]
	v_pk_add_f32 v[192:193], v[180:181], v[192:193] neg_lo:[0,1] neg_hi:[0,1]
	v_mov_b32_e32 v27, v19
	v_pk_add_f32 v[180:181], v[204:205], v[182:183]
	v_pk_add_f32 v[182:183], v[204:205], v[182:183] neg_lo:[0,1] neg_hi:[0,1]
	v_pk_add_f32 v[204:205], v[196:197], v[176:177]
	v_pk_add_f32 v[196:197], v[196:197], v[176:177] neg_lo:[0,1] neg_hi:[0,1]
	v_mov_b32_e32 v31, v21
	v_pk_add_f32 v[176:177], v[188:189], v[184:185] op_sel:[0,1] op_sel_hi:[1,0] neg_hi:[0,1]
	v_pk_add_f32 v[184:185], v[188:189], v[184:185] op_sel:[0,1] op_sel_hi:[1,0] neg_lo:[0,1]
	v_pk_add_f32 v[188:189], v[158:159], v[178:179]
	v_pk_add_f32 v[178:179], v[158:159], v[178:179] neg_lo:[0,1] neg_hi:[0,1]
	v_xor_b32_e32 v34, 0x80000000, v25
	v_pk_add_f32 v[158:159], v[186:187], v[190:191]
	v_pk_add_f32 v[186:187], v[186:187], v[190:191] neg_lo:[0,1] neg_hi:[0,1]
	v_pk_add_f32 v[190:191], v[206:207], v[160:161]
	v_pk_add_f32 v[206:207], v[206:207], v[160:161] neg_lo:[0,1] neg_hi:[0,1]
	v_xor_b32_e32 v38, 0x80000000, v29
	v_pk_add_f32 v[160:161], v[164:165], v[168:169] op_sel:[0,1] op_sel_hi:[1,0] neg_hi:[0,1]
	v_pk_add_f32 v[164:165], v[164:165], v[168:169] op_sel:[0,1] op_sel_hi:[1,0] neg_lo:[0,1]
	v_pk_add_f32 v[168:169], v[150:151], v[162:163]
	v_pk_add_f32 v[162:163], v[150:151], v[162:163] neg_lo:[0,1] neg_hi:[0,1]
	v_xor_b32_e32 v42, 0x80000000, v33
	v_pk_add_f32 v[150:151], v[170:171], v[152:153]
	v_pk_add_f32 v[152:153], v[170:171], v[152:153] neg_lo:[0,1] neg_hi:[0,1]
	v_pk_add_f32 v[170:171], v[166:167], v[144:145]
	v_pk_add_f32 v[166:167], v[166:167], v[144:145] neg_lo:[0,1] neg_hi:[0,1]
	v_xor_b32_e32 v46, 0x80000000, v37
	v_pk_add_f32 v[144:145], v[128:129], v[154:155] op_sel:[0,1] op_sel_hi:[1,0] neg_hi:[0,1]
	v_pk_add_f32 v[128:129], v[128:129], v[154:155] op_sel:[0,1] op_sel_hi:[1,0] neg_lo:[0,1]
	v_pk_add_f32 v[154:155], v[130:131], v[148:149]
	v_pk_add_f32 v[130:131], v[130:131], v[148:149] neg_lo:[0,1] neg_hi:[0,1]
	v_mov_b32_e32 v35, v25
	v_pk_mul_f32 v[148:149], v[130:131], 1.0 op_sel:[1,0] op_sel_hi:[0,0] neg_hi:[1,0]
	v_pk_add_f32 v[130:131], v[156:157], v[210:211]
	v_pk_add_f32 v[156:157], v[156:157], v[210:211] neg_lo:[0,1] neg_hi:[0,1]
	v_pk_add_f32 v[210:211], v[172:173], v[208:209] op_sel:[0,1] op_sel_hi:[1,0] neg_hi:[0,1]
	v_pk_add_f32 v[172:173], v[172:173], v[208:209] op_sel:[0,1] op_sel_hi:[1,0] neg_lo:[0,1]
	v_pk_add_f32 v[208:209], v[174:175], v[198:199]
	v_pk_add_f32 v[174:175], v[174:175], v[198:199] neg_lo:[0,1] neg_hi:[0,1]
	v_pk_add_f32 v[198:199], v[194:195], v[192:193] op_sel:[0,1] op_sel_hi:[1,0] neg_hi:[0,1]
	v_pk_add_f32 v[192:193], v[194:195], v[192:193] op_sel:[0,1] op_sel_hi:[1,0] neg_lo:[0,1]
	v_pk_add_f32 v[194:195], v[180:181], v[204:205]
	v_pk_add_f32 v[180:181], v[180:181], v[204:205] neg_lo:[0,1] neg_hi:[0,1]
	v_pk_add_f32 v[204:205], v[182:183], v[196:197] op_sel:[0,1] op_sel_hi:[1,0] neg_hi:[0,1]
	v_pk_add_f32 v[182:183], v[182:183], v[196:197] op_sel:[0,1] op_sel_hi:[1,0] neg_lo:[0,1]
	v_pk_add_f32 v[196:197], v[176:177], v[188:189]
	v_pk_add_f32 v[176:177], v[176:177], v[188:189] neg_lo:[0,1] neg_hi:[0,1]
	v_pk_add_f32 v[188:189], v[184:185], v[178:179] op_sel:[0,1] op_sel_hi:[1,0] neg_hi:[0,1]
	v_pk_add_f32 v[178:179], v[184:185], v[178:179] op_sel:[0,1] op_sel_hi:[1,0] neg_lo:[0,1]
	v_pk_add_f32 v[184:185], v[158:159], v[190:191]
	v_pk_add_f32 v[158:159], v[158:159], v[190:191] neg_lo:[0,1] neg_hi:[0,1]
	v_pk_mul_f32 v[4:5], v[4:5], v[184:185] op_sel:[0,1] op_sel_hi:[1,0]
	v_pk_add_f32 v[190:191], v[186:187], v[206:207] op_sel:[0,1] op_sel_hi:[1,0] neg_hi:[0,1]
	v_pk_add_f32 v[186:187], v[186:187], v[206:207] op_sel:[0,1] op_sel_hi:[1,0] neg_lo:[0,1]
	v_pk_add_f32 v[206:207], v[160:161], v[168:169]
	v_pk_add_f32 v[160:161], v[160:161], v[168:169] neg_lo:[0,1] neg_hi:[0,1]
	v_pk_add_f32 v[168:169], v[164:165], v[162:163] op_sel:[0,1] op_sel_hi:[1,0] neg_hi:[0,1]
	v_pk_add_f32 v[162:163], v[164:165], v[162:163] op_sel:[0,1] op_sel_hi:[1,0] neg_lo:[0,1]
	v_pk_add_f32 v[164:165], v[150:151], v[170:171]
	v_pk_fma_f32 v[4:5], v[6:7], v[184:185], v[4:5] op_sel_hi:[0,1,1]
	v_pk_mul_f32 v[6:7], v[14:15], v[194:195] op_sel:[0,1] op_sel_hi:[1,0]
	v_mov_b32_e32 v39, v29
	v_pk_fma_f32 v[6:7], v[8:9], v[194:195], v[6:7] op_sel_hi:[0,1,1]
	v_pk_mul_f32 v[8:9], v[22:23], v[164:165] op_sel:[0,1] op_sel_hi:[1,0]
	v_mov_b32_e32 v43, v33
	v_pk_fma_f32 v[8:9], v[10:11], v[164:165], v[8:9] op_sel_hi:[0,1,1]
	v_pk_mul_f32 v[10:11], v[16:17], v[208:209] op_sel:[0,1] op_sel_hi:[1,0]
	v_mov_b32_e32 v47, v37
	v_pk_add_f32 v[150:151], v[150:151], v[170:171] neg_lo:[0,1] neg_hi:[0,1]
	v_pk_add_f32 v[170:171], v[152:153], v[166:167] op_sel:[0,1] op_sel_hi:[1,0] neg_hi:[0,1]
	v_pk_add_f32 v[152:153], v[152:153], v[166:167] op_sel:[0,1] op_sel_hi:[1,0] neg_lo:[0,1]
	v_pk_add_f32 v[166:167], v[144:145], v[154:155]
	v_pk_fma_f32 v[10:11], v[12:13], v[208:209], v[10:11] op_sel_hi:[0,1,1]
	v_pk_mul_f32 v[12:13], v[26:27], v[206:207] op_sel:[0,1] op_sel_hi:[1,0]
	v_pk_mul_f32 v[14:15], v[30:31], v[196:197] op_sel:[0,1] op_sel_hi:[1,0]
	v_xor_b32_e32 v50, 0x80000000, v41
	v_xor_b32_e32 v54, 0x80000000, v45
	v_xor_b32_e32 v58, 0x80000000, v49
	v_xor_b32_e32 v62, 0x80000000, v53
	v_xor_b32_e32 v66, 0x80000000, v57
	v_xor_b32_e32 v70, 0x80000000, v61
	v_xor_b32_e32 v74, 0x80000000, v65
	v_mov_b32_e32 v51, v41
	v_mov_b32_e32 v55, v45
	v_mov_b32_e32 v59, v49
	v_mov_b32_e32 v63, v53
	v_mov_b32_e32 v67, v57
	v_mov_b32_e32 v71, v61
	v_mov_b32_e32 v75, v65
	v_pk_add_f32 v[144:145], v[144:145], v[154:155] neg_lo:[0,1] neg_hi:[0,1]
	v_pk_add_f32 v[154:155], v[128:129], v[148:149]
	v_pk_fma_f32 v[12:13], v[18:19], v[206:207], v[12:13] op_sel_hi:[0,1,1]
	v_pk_fma_f32 v[14:15], v[20:21], v[196:197], v[14:15] op_sel_hi:[0,1,1]
	v_pk_mul_f32 v[16:17], v[34:35], v[166:167] op_sel:[0,1] op_sel_hi:[1,0]
	v_pk_mul_f32 v[18:19], v[38:39], v[210:211] op_sel:[0,1] op_sel_hi:[1,0]
	v_pk_mul_f32 v[20:21], v[42:43], v[190:191] op_sel:[0,1] op_sel_hi:[1,0]
	v_pk_mul_f32 v[22:23], v[46:47], v[204:205] op_sel:[0,1] op_sel_hi:[1,0]
	v_xor_b32_e32 v78, 0x80000000, v69
	v_xor_b32_e32 v82, 0x80000000, v73
	v_xor_b32_e32 v86, 0x80000000, v77
	v_xor_b32_e32 v90, 0x80000000, v81
	v_xor_b32_e32 v94, 0x80000000, v85
	v_xor_b32_e32 v98, 0x80000000, v89
	v_xor_b32_e32 v102, 0x80000000, v93
	v_xor_b32_e32 v106, 0x80000000, v97
	v_xor_b32_e32 v110, 0x80000000, v101
	v_xor_b32_e32 v114, 0x80000000, v105
	v_xor_b32_e32 v118, 0x80000000, v109
	v_xor_b32_e32 v122, 0x80000000, v113
	v_xor_b32_e32 v124, 0x80000000, v117
	v_xor_b32_e32 v126, 0x80000000, v121
	v_mov_b32_e32 v79, v69
	v_mov_b32_e32 v83, v73
	v_mov_b32_e32 v87, v77
	v_mov_b32_e32 v91, v81
	v_mov_b32_e32 v95, v85
	v_mov_b32_e32 v99, v89
	v_mov_b32_e32 v103, v93
	v_mov_b32_e32 v107, v97
	v_mov_b32_e32 v111, v101
	v_mov_b32_e32 v115, v105
	v_mov_b32_e32 v119, v109
	v_mov_b32_e32 v123, v113
	v_mov_b32_e32 v125, v117
	v_mov_b32_e32 v127, v121
	v_pk_add_f32 v[128:129], v[128:129], v[148:149] neg_lo:[0,1] neg_hi:[0,1]
	v_pk_fma_f32 v[16:17], v[24:25], v[166:167], v[16:17] op_sel_hi:[0,1,1]
	v_pk_fma_f32 v[18:19], v[28:29], v[210:211], v[18:19] op_sel_hi:[0,1,1]
	v_pk_fma_f32 v[20:21], v[32:33], v[190:191], v[20:21] op_sel_hi:[0,1,1]
	v_pk_fma_f32 v[22:23], v[36:37], v[204:205], v[22:23] op_sel_hi:[0,1,1]
	v_pk_mul_f32 v[24:25], v[50:51], v[170:171] op_sel:[0,1] op_sel_hi:[1,0]
	v_pk_mul_f32 v[26:27], v[54:55], v[198:199] op_sel:[0,1] op_sel_hi:[1,0]
	v_pk_mul_f32 v[28:29], v[58:59], v[168:169] op_sel:[0,1] op_sel_hi:[1,0]
	v_pk_mul_f32 v[30:31], v[62:63], v[188:189] op_sel:[0,1] op_sel_hi:[1,0]
	v_pk_mul_f32 v[32:33], v[66:67], v[154:155] op_sel:[0,1] op_sel_hi:[1,0]
	v_pk_mul_f32 v[34:35], v[70:71], v[156:157] op_sel:[0,1] op_sel_hi:[1,0]
	v_pk_mul_f32 v[36:37], v[74:75], v[158:159] op_sel:[0,1] op_sel_hi:[1,0]
	v_pk_fma_f32 v[24:25], v[40:41], v[170:171], v[24:25] op_sel_hi:[0,1,1]
	v_pk_fma_f32 v[26:27], v[44:45], v[198:199], v[26:27] op_sel_hi:[0,1,1]
	v_pk_fma_f32 v[28:29], v[48:49], v[168:169], v[28:29] op_sel_hi:[0,1,1]
	v_pk_fma_f32 v[30:31], v[52:53], v[188:189], v[30:31] op_sel_hi:[0,1,1]
	v_pk_fma_f32 v[32:33], v[56:57], v[154:155], v[32:33] op_sel_hi:[0,1,1]
	v_pk_fma_f32 v[34:35], v[60:61], v[156:157], v[34:35] op_sel_hi:[0,1,1]
	v_pk_fma_f32 v[36:37], v[64:65], v[158:159], v[36:37] op_sel_hi:[0,1,1]
	v_pk_mul_f32 v[38:39], v[78:79], v[180:181] op_sel:[0,1] op_sel_hi:[1,0]
	v_pk_mul_f32 v[40:41], v[82:83], v[150:151] op_sel:[0,1] op_sel_hi:[1,0]
	v_pk_mul_f32 v[42:43], v[86:87], v[174:175] op_sel:[0,1] op_sel_hi:[1,0]
	v_pk_mul_f32 v[44:45], v[90:91], v[160:161] op_sel:[0,1] op_sel_hi:[1,0]
	v_pk_mul_f32 v[46:47], v[94:95], v[176:177] op_sel:[0,1] op_sel_hi:[1,0]
	v_pk_mul_f32 v[48:49], v[98:99], v[144:145] op_sel:[0,1] op_sel_hi:[1,0]
	v_pk_mul_f32 v[50:51], v[102:103], v[172:173] op_sel:[0,1] op_sel_hi:[1,0]
	v_pk_mul_f32 v[52:53], v[106:107], v[186:187] op_sel:[0,1] op_sel_hi:[1,0]
	v_pk_mul_f32 v[54:55], v[110:111], v[182:183] op_sel:[0,1] op_sel_hi:[1,0]
	v_pk_mul_f32 v[56:57], v[114:115], v[152:153] op_sel:[0,1] op_sel_hi:[1,0]
	v_pk_mul_f32 v[58:59], v[118:119], v[192:193] op_sel:[0,1] op_sel_hi:[1,0]
	v_pk_mul_f32 v[60:61], v[122:123], v[162:163] op_sel:[0,1] op_sel_hi:[1,0]
	v_pk_mul_f32 v[62:63], v[124:125], v[178:179] op_sel:[0,1] op_sel_hi:[1,0]
	v_pk_mul_f32 v[64:65], v[126:127], v[128:129] op_sel:[0,1] op_sel_hi:[1,0]
	v_pk_fma_f32 v[38:39], v[68:69], v[180:181], v[38:39] op_sel_hi:[0,1,1]
	v_pk_fma_f32 v[40:41], v[72:73], v[150:151], v[40:41] op_sel_hi:[0,1,1]
	v_pk_fma_f32 v[42:43], v[76:77], v[174:175], v[42:43] op_sel_hi:[0,1,1]
	v_pk_fma_f32 v[44:45], v[80:81], v[160:161], v[44:45] op_sel_hi:[0,1,1]
	v_pk_fma_f32 v[46:47], v[84:85], v[176:177], v[46:47] op_sel_hi:[0,1,1]
	v_pk_fma_f32 v[48:49], v[88:89], v[144:145], v[48:49] op_sel_hi:[0,1,1]
	v_pk_fma_f32 v[50:51], v[92:93], v[172:173], v[50:51] op_sel_hi:[0,1,1]
	v_pk_fma_f32 v[52:53], v[96:97], v[186:187], v[52:53] op_sel_hi:[0,1,1]
	v_pk_fma_f32 v[54:55], v[100:101], v[182:183], v[54:55] op_sel_hi:[0,1,1]
	v_pk_fma_f32 v[56:57], v[104:105], v[152:153], v[56:57] op_sel_hi:[0,1,1]
	v_pk_fma_f32 v[58:59], v[108:109], v[192:193], v[58:59] op_sel_hi:[0,1,1]
	v_pk_fma_f32 v[60:61], v[112:113], v[162:163], v[60:61] op_sel_hi:[0,1,1]
	v_pk_fma_f32 v[62:63], v[116:117], v[178:179], v[62:63] op_sel_hi:[0,1,1]
	v_pk_fma_f32 v[64:65], v[120:121], v[128:129], v[64:65] op_sel_hi:[0,1,1]
	ds_write_b64 v2, v[130:131]
	ds_write_b64 v2, v[34:35] offset:2112
	ds_write_b64 v2, v[18:19] offset:4224
	ds_write_b64 v2, v[50:51] offset:6336
	ds_write_b64 v2, v[10:11] offset:8448
	ds_write_b64 v2, v[42:43] offset:10560
	ds_write_b64 v2, v[26:27] offset:12672
	ds_write_b64 v2, v[58:59] offset:14784
	ds_write_b64 v2, v[6:7] offset:16896
	ds_write_b64 v2, v[38:39] offset:19008
	ds_write_b64 v2, v[22:23] offset:21120
	ds_write_b64 v2, v[54:55] offset:23232
	ds_write_b64 v2, v[14:15] offset:25344
	ds_write_b64 v2, v[46:47] offset:27456
	ds_write_b64 v2, v[30:31] offset:29568
	ds_write_b64 v2, v[62:63] offset:31680
	ds_write_b64 v2, v[4:5] offset:33792
	ds_write_b64 v2, v[36:37] offset:35904
	ds_write_b64 v2, v[20:21] offset:38016
	ds_write_b64 v2, v[52:53] offset:40128
	ds_write_b64 v2, v[12:13] offset:42240
	ds_write_b64 v2, v[44:45] offset:44352
	ds_write_b64 v2, v[28:29] offset:46464
	ds_write_b64 v2, v[60:61] offset:48576
	ds_write_b64 v2, v[8:9] offset:50688
	ds_write_b64 v2, v[40:41] offset:52800
	ds_write_b64 v2, v[24:25] offset:54912
	ds_write_b64 v2, v[56:57] offset:57024
	ds_write_b64 v2, v[16:17] offset:59136
	ds_write_b64 v2, v[48:49] offset:61248
	ds_write_b64 v2, v[32:33] offset:63360
	ds_write_b64 v2, v[64:65] offset:65472
	v_mov_b32_e32 v2, v142
	s_waitcnt lgkmcnt(0)
	s_barrier
	s_nop 0
	v_and_b32_e32 v5, 15, v2
	v_cvt_f32_ubyte0_e32 v4, v5
	v_mul_f32_e32 v6, 0x3b800000, v4
	v_sin_f32_e32 v4, v6
	v_cos_f32_e32 v6, v6
	v_lshlrev_b32_e32 v64, 3, v5
	v_lshlrev_b32_e32 v2, 4, v2
	v_xor_b32_e32 v7, 0x80000000, v4
	v_mov_b32_e32 v5, v7
	v_pk_mul_f32 v[8:9], v[6:7], v[4:5] op_sel:[1,0] op_sel_hi:[0,1]
	v_pk_fma_f32 v[8:9], v[6:7], v[6:7], v[8:9] op_sel_hi:[1,0,1]
	v_and_b32_e32 v2, 0xffffff00, v2
	v_pk_mul_f32 v[14:15], 1.0, v[8:9] op_sel:[0,1] op_sel_hi:[0,1] neg_lo:[0,1]
	v_pk_mul_f32 v[12:13], v[8:9], v[14:15] op_sel:[1,0] op_sel_hi:[0,1]
	v_pk_fma_f32 v[12:13], v[8:9], v[8:9], v[12:13] op_sel_hi:[1,0,1]
	v_pk_mul_f32 v[10:11], v[4:5], v[8:9] op_sel:[0,1] op_sel_hi:[1,0]
	v_pk_mul_f32 v[16:17], 1.0, v[12:13] op_sel:[0,1] op_sel_hi:[0,1] neg_lo:[0,1]
	v_pk_mul_f32 v[32:33], v[12:13], v[16:17] op_sel:[1,0] op_sel_hi:[0,1]
	v_pk_fma_f32 v[32:33], v[12:13], v[12:13], v[32:33] op_sel_hi:[1,0,1]
	v_pk_mul_f32 v[18:19], v[4:5], v[12:13] op_sel:[0,1] op_sel_hi:[1,0]
	v_pk_mul_f32 v[48:49], v[16:17], v[32:33] op_sel:[0,1] op_sel_hi:[1,0]
	v_pk_mul_f32 v[36:37], v[4:5], v[32:33] op_sel:[0,1] op_sel_hi:[1,0]
	v_pk_fma_f32 v[48:49], v[12:13], v[32:33], v[48:49] op_sel_hi:[0,1,1]
	v_pk_mul_f32 v[52:53], v[4:5], v[48:49] op_sel:[0,1] op_sel_hi:[1,0]
	v_pk_fma_f32 v[10:11], v[6:7], v[8:9], v[10:11] op_sel_hi:[0,1,1]
	v_pk_fma_f32 v[18:19], v[6:7], v[12:13], v[18:19] op_sel_hi:[0,1,1]
	v_pk_fma_f32 v[36:37], v[6:7], v[32:33], v[36:37] op_sel_hi:[0,1,1]
	v_pk_fma_f32 v[52:53], v[6:7], v[48:49], v[52:53] op_sel_hi:[0,1,1]
	v_lshlrev_b32_e32 v7, 3, v2
	v_add3_u32 v7, 0, v64, v7
	v_ashrrev_i32_e32 v64, 2, v2
	v_add_u32_e32 v106, v7, v64
	ds_read2_b64 v[64:67], v106 offset1:16
	ds_read2_b64 v[68:71], v106 offset0:33 offset1:49
	ds_read2_b64 v[72:75], v106 offset0:66 offset1:82
	ds_read2_b64 v[76:79], v106 offset0:132 offset1:148
	ds_read2_b64 v[80:83], v106 offset0:99 offset1:115
	ds_read2_b64 v[84:87], v106 offset0:165 offset1:181
	ds_read2_b64 v[88:91], v106 offset0:198 offset1:214
	ds_read2_b64 v[92:95], v106 offset0:231 offset1:247
	s_waitcnt lgkmcnt(4)
	v_pk_add_f32 v[96:97], v[64:65], v[76:77]
	v_pk_add_f32 v[64:65], v[64:65], v[76:77] neg_lo:[0,1] neg_hi:[0,1]
	v_pk_add_f32 v[76:77], v[66:67], v[78:79]
	v_pk_add_f32 v[66:67], v[66:67], v[78:79] neg_lo:[0,1] neg_hi:[0,1]
	s_waitcnt lgkmcnt(1)
	v_pk_add_f32 v[98:99], v[74:75], v[90:91]
	v_pk_mul_f32 v[78:79], v[66:67], s[24:25]
	v_pk_add_f32 v[74:75], v[74:75], v[90:91] neg_lo:[0,1] neg_hi:[0,1]
	v_pk_fma_f32 v[66:67], v[66:67], s[22:23], v[78:79] op_sel:[0,0,1] op_sel_hi:[1,0,0]
	v_pk_add_f32 v[78:79], v[68:69], v[84:85]
	v_pk_add_f32 v[68:69], v[68:69], v[84:85] neg_lo:[0,1] neg_hi:[0,1]
	v_pk_mul_f32 v[90:91], v[74:75], s[44:45]
	v_pk_mul_f32 v[84:85], v[68:69], s[40:41]
	v_pk_fma_f32 v[74:75], v[74:75], s[50:51], v[90:91] op_sel:[0,0,1] op_sel_hi:[1,0,0] neg_lo:[1,0,0] neg_hi:[1,0,0]
	v_pk_fma_f32 v[68:69], v[68:69], s[38:39], v[84:85] op_sel:[0,0,1] op_sel_hi:[1,0,0]
	v_pk_add_f32 v[84:85], v[70:71], v[86:87]
	v_pk_add_f32 v[70:71], v[70:71], v[86:87] neg_lo:[0,1] neg_hi:[0,1]
	s_waitcnt lgkmcnt(0)
	v_pk_add_f32 v[90:91], v[80:81], v[92:93]
	v_pk_add_f32 v[80:81], v[80:81], v[92:93] neg_lo:[0,1] neg_hi:[0,1]
	v_pk_mul_f32 v[86:87], v[70:71], s[44:45]
	v_pk_mul_f32 v[92:93], v[80:81], s[40:41]
	v_pk_fma_f32 v[70:71], v[70:71], s[50:51], v[86:87] op_sel:[0,0,1] op_sel_hi:[1,0,0]
	v_pk_add_f32 v[86:87], v[72:73], v[88:89]
	v_pk_add_f32 v[88:89], v[72:73], v[88:89] neg_lo:[0,1] neg_hi:[0,1]
	v_pk_fma_f32 v[80:81], v[80:81], s[38:39], v[92:93] op_sel:[0,0,1] op_sel_hi:[1,0,0] neg_lo:[1,0,0] neg_hi:[1,0,0]
	v_pk_add_f32 v[92:93], v[82:83], v[94:95]
	v_pk_add_f32 v[82:83], v[82:83], v[94:95] neg_lo:[0,1] neg_hi:[0,1]
	s_nop 0
	v_pk_mul_f32 v[94:95], v[82:83], s[24:25]
	s_nop 0
	v_pk_fma_f32 v[82:83], v[82:83], s[22:23], v[94:95] op_sel:[0,0,1] op_sel_hi:[1,0,0] neg_lo:[1,0,0] neg_hi:[1,0,0]
	v_pk_add_f32 v[94:95], v[96:97], v[86:87]
	v_pk_add_f32 v[86:87], v[96:97], v[86:87] neg_lo:[0,1] neg_hi:[0,1]
	v_pk_add_f32 v[96:97], v[76:77], v[98:99]
	v_pk_add_f32 v[76:77], v[76:77], v[98:99] neg_lo:[0,1] neg_hi:[0,1]
	v_pk_add_f32 v[100:101], v[84:85], v[92:93]
	v_pk_add_f32 v[84:85], v[84:85], v[92:93] neg_lo:[0,1] neg_hi:[0,1]
	v_pk_add_f32 v[72:73], v[64:65], v[88:89] op_sel:[0,1] op_sel_hi:[1,0] neg_hi:[0,1]
	v_pk_add_f32 v[64:65], v[64:65], v[88:89] op_sel:[0,1] op_sel_hi:[1,0] neg_lo:[0,1]
	v_pk_add_f32 v[88:89], v[66:67], v[74:75]
	v_pk_add_f32 v[66:67], v[66:67], v[74:75] neg_lo:[0,1] neg_hi:[0,1]
	v_pk_mul_f32 v[98:99], v[76:77], s[40:41]
	v_pk_mul_f32 v[92:93], v[84:85], s[40:41]
	v_pk_mul_f32 v[74:75], v[66:67], s[40:41]
	v_pk_fma_f32 v[76:77], v[76:77], s[38:39], v[98:99] op_sel:[0,0,1] op_sel_hi:[1,0,0]
	v_pk_add_f32 v[98:99], v[78:79], v[90:91]
	v_pk_add_f32 v[90:91], v[78:79], v[90:91] neg_lo:[0,1] neg_hi:[0,1]
	v_pk_fma_f32 v[84:85], v[84:85], s[38:39], v[92:93] op_sel:[0,0,1] op_sel_hi:[1,0,0] neg_lo:[1,0,0] neg_hi:[1,0,0]
	v_pk_fma_f32 v[66:67], v[66:67], s[38:39], v[74:75] op_sel:[0,0,1] op_sel_hi:[1,0,0]
	v_pk_add_f32 v[74:75], v[68:69], v[80:81]
	v_pk_add_f32 v[92:93], v[70:71], v[82:83]
	v_pk_add_f32 v[70:71], v[70:71], v[82:83] neg_lo:[0,1] neg_hi:[0,1]
	v_pk_add_f32 v[80:81], v[68:69], v[80:81] neg_lo:[0,1] neg_hi:[0,1]
	v_pk_mul_f32 v[82:83], v[70:71], s[40:41]
	v_pk_add_f32 v[102:103], v[72:73], v[74:75]
	v_pk_add_f32 v[72:73], v[72:73], v[74:75] neg_lo:[0,1] neg_hi:[0,1]
	v_pk_add_f32 v[74:75], v[88:89], v[92:93]
	v_pk_add_f32 v[92:93], v[88:89], v[92:93] neg_lo:[0,1] neg_hi:[0,1]
	v_pk_mul_f32 v[20:21], v[10:11], 1.0 op_sel:[1,0] op_sel_hi:[1,0] neg_lo:[1,0]
	v_pk_mul_f32 v[24:25], v[14:15], v[12:13] op_sel:[0,1] op_sel_hi:[1,0]
	v_pk_fma_f32 v[70:71], v[70:71], s[38:39], v[82:83] op_sel:[0,0,1] op_sel_hi:[1,0,0] neg_lo:[1,0,0] neg_hi:[1,0,0]
	v_pk_add_f32 v[78:79], v[86:87], v[90:91] op_sel:[0,1] op_sel_hi:[1,0] neg_hi:[0,1]
	v_pk_add_f32 v[86:87], v[86:87], v[90:91] op_sel:[0,1] op_sel_hi:[1,0] neg_lo:[0,1]
	v_pk_add_f32 v[90:91], v[76:77], v[84:85]
	v_pk_add_f32 v[84:85], v[76:77], v[84:85] neg_lo:[0,1] neg_hi:[0,1]
	v_pk_mul_f32 v[22:23], v[18:19], 1.0 op_sel:[1,0] op_sel_hi:[1,0] neg_lo:[1,0]
	v_pk_fma_f32 v[24:25], v[8:9], v[12:13], v[24:25] op_sel_hi:[0,1,1]
	v_pk_mul_f32 v[28:29], v[12:13], v[20:21] op_sel:[1,0] op_sel_hi:[0,1]
	v_pk_add_f32 v[68:69], v[64:65], v[80:81] op_sel:[0,1] op_sel_hi:[1,0] neg_hi:[0,1]
	v_pk_add_f32 v[64:65], v[64:65], v[80:81] op_sel:[0,1] op_sel_hi:[1,0] neg_lo:[0,1]
	v_pk_add_f32 v[80:81], v[66:67], v[70:71]
	v_pk_add_f32 v[70:71], v[66:67], v[70:71] neg_lo:[0,1] neg_hi:[0,1]
	v_pk_add_f32 v[88:89], v[72:73], v[92:93] op_sel:[0,1] op_sel_hi:[1,0] neg_hi:[0,1]
	v_pk_mul_f32 v[26:27], v[24:25], 1.0 op_sel:[1,0] op_sel_hi:[1,0] neg_lo:[1,0]
	v_pk_fma_f32 v[28:29], v[12:13], v[10:11], v[28:29] op_sel_hi:[1,0,1]
	v_pk_add_f32 v[76:77], v[86:87], v[84:85] op_sel:[0,1] op_sel_hi:[1,0] neg_hi:[0,1]
	v_pk_add_f32 v[72:73], v[72:73], v[92:93] op_sel:[0,1] op_sel_hi:[1,0] neg_lo:[0,1]
	v_pk_mul_f32 v[92:93], v[22:23], v[88:89] op_sel:[0,1] op_sel_hi:[1,0]
	v_pk_mul_f32 v[30:31], v[28:29], 1.0 op_sel:[1,0] op_sel_hi:[1,0] neg_lo:[1,0]
	v_pk_add_f32 v[82:83], v[94:95], v[98:99]
	v_pk_add_f32 v[94:95], v[94:95], v[98:99] neg_lo:[0,1] neg_hi:[0,1]
	v_pk_add_f32 v[98:99], v[96:97], v[100:101]
	v_pk_add_f32 v[66:67], v[64:65], v[70:71] op_sel:[0,1] op_sel_hi:[1,0] neg_hi:[0,1]
	v_pk_fma_f32 v[88:89], v[18:19], v[88:89], v[92:93] op_sel_hi:[0,1,1]
	v_pk_mul_f32 v[92:93], v[26:27], v[76:77] op_sel:[0,1] op_sel_hi:[1,0]
	v_pk_mul_f32 v[34:35], v[32:33], 1.0 op_sel:[1,0] op_sel_hi:[1,0] neg_lo:[1,0]
	v_pk_mul_f32 v[40:41], v[14:15], v[32:33] op_sel:[0,1] op_sel_hi:[1,0]
	v_pk_add_f32 v[104:105], v[82:83], v[98:99]
	v_pk_add_f32 v[82:83], v[82:83], v[98:99] neg_lo:[0,1] neg_hi:[0,1]
	v_pk_fma_f32 v[76:77], v[24:25], v[76:77], v[92:93] op_sel_hi:[0,1,1]
	v_pk_mul_f32 v[92:93], v[30:31], v[66:67] op_sel:[0,1] op_sel_hi:[1,0]
	v_pk_mul_f32 v[38:39], v[36:37], 1.0 op_sel:[1,0] op_sel_hi:[1,0] neg_lo:[1,0]
	v_pk_fma_f32 v[40:41], v[8:9], v[32:33], v[40:41] op_sel_hi:[0,1,1]
	v_pk_mul_f32 v[44:45], v[20:21], v[32:33] op_sel:[0,1] op_sel_hi:[1,0]
	v_pk_add_f32 v[84:85], v[86:87], v[84:85] op_sel:[0,1] op_sel_hi:[1,0] neg_lo:[0,1]
	v_pk_add_f32 v[86:87], v[102:103], v[74:75]
	v_pk_add_f32 v[74:75], v[102:103], v[74:75] neg_lo:[0,1] neg_hi:[0,1]
	v_pk_fma_f32 v[66:67], v[28:29], v[66:67], v[92:93] op_sel_hi:[0,1,1]
	v_pk_mul_f32 v[92:93], v[34:35], v[82:83] op_sel:[0,1] op_sel_hi:[1,0]
	v_pk_mul_f32 v[42:43], v[40:41], 1.0 op_sel:[1,0] op_sel_hi:[1,0] neg_lo:[1,0]
	v_pk_fma_f32 v[44:45], v[10:11], v[32:33], v[44:45] op_sel_hi:[0,1,1]
	v_pk_add_f32 v[100:101], v[96:97], v[100:101] neg_lo:[0,1] neg_hi:[0,1]
	v_pk_add_f32 v[98:99], v[78:79], v[90:91]
	v_pk_add_f32 v[78:79], v[78:79], v[90:91] neg_lo:[0,1] neg_hi:[0,1]
	v_pk_fma_f32 v[82:83], v[32:33], v[82:83], v[92:93] op_sel_hi:[0,1,1]
	v_pk_mul_f32 v[92:93], v[38:39], v[74:75] op_sel:[0,1] op_sel_hi:[1,0]
	v_pk_mul_f32 v[46:47], v[44:45], 1.0 op_sel:[1,0] op_sel_hi:[1,0] neg_lo:[1,0]
	v_pk_add_f32 v[90:91], v[68:69], v[80:81]
	v_pk_add_f32 v[68:69], v[68:69], v[80:81] neg_lo:[0,1] neg_hi:[0,1]
	v_pk_fma_f32 v[74:75], v[36:37], v[74:75], v[92:93] op_sel_hi:[0,1,1]
	v_pk_mul_f32 v[92:93], v[42:43], v[78:79] op_sel:[0,1] op_sel_hi:[1,0]
	v_pk_mul_f32 v[50:51], v[48:49], 1.0 op_sel:[1,0] op_sel_hi:[1,0] neg_lo:[1,0]
	v_pk_mul_f32 v[56:57], v[14:15], v[48:49] op_sel:[0,1] op_sel_hi:[1,0]
	v_pk_add_f32 v[96:97], v[94:95], v[100:101] op_sel:[0,1] op_sel_hi:[1,0] neg_hi:[0,1]
	v_pk_add_f32 v[94:95], v[94:95], v[100:101] op_sel:[0,1] op_sel_hi:[1,0] neg_lo:[0,1]
	v_pk_fma_f32 v[78:79], v[40:41], v[78:79], v[92:93] op_sel_hi:[0,1,1]
	v_pk_mul_f32 v[92:93], v[46:47], v[68:69] op_sel:[0,1] op_sel_hi:[1,0]
	v_pk_mul_f32 v[54:55], v[52:53], 1.0 op_sel:[1,0] op_sel_hi:[1,0] neg_lo:[1,0]
	v_pk_fma_f32 v[56:57], v[8:9], v[48:49], v[56:57] op_sel_hi:[0,1,1]
	v_pk_mul_f32 v[60:61], v[20:21], v[48:49] op_sel:[0,1] op_sel_hi:[1,0]
	v_pk_fma_f32 v[68:69], v[44:45], v[68:69], v[92:93] op_sel_hi:[0,1,1]
	v_pk_mul_f32 v[92:93], v[50:51], v[94:95] op_sel:[0,1] op_sel_hi:[1,0]
	v_pk_mul_f32 v[58:59], v[56:57], 1.0 op_sel:[1,0] op_sel_hi:[1,0] neg_lo:[1,0]
	v_pk_fma_f32 v[60:61], v[10:11], v[48:49], v[60:61] op_sel_hi:[0,1,1]
	v_pk_add_f32 v[64:65], v[64:65], v[70:71] op_sel:[0,1] op_sel_hi:[1,0] neg_lo:[0,1]
	v_pk_mul_f32 v[70:71], v[4:5], v[86:87] op_sel:[0,1] op_sel_hi:[1,0]
	v_pk_fma_f32 v[92:93], v[48:49], v[94:95], v[92:93] op_sel_hi:[0,1,1]
	v_pk_mul_f32 v[94:95], v[54:55], v[72:73] op_sel:[0,1] op_sel_hi:[1,0]
	v_pk_mul_f32 v[62:63], v[60:61], 1.0 op_sel:[1,0] op_sel_hi:[1,0] neg_lo:[1,0]
	v_pk_fma_f32 v[70:71], v[6:7], v[86:87], v[70:71] op_sel_hi:[0,1,1]
	v_pk_mul_f32 v[86:87], v[20:21], v[90:91] op_sel:[0,1] op_sel_hi:[1,0]
	v_pk_fma_f32 v[72:73], v[52:53], v[72:73], v[94:95] op_sel_hi:[0,1,1]
	v_pk_mul_f32 v[94:95], v[58:59], v[84:85] op_sel:[0,1] op_sel_hi:[1,0]
	v_add_u32_e32 v2, 0x2000, v2
	v_pk_mul_f32 v[80:81], v[14:15], v[98:99] op_sel:[0,1] op_sel_hi:[1,0]
	v_pk_fma_f32 v[86:87], v[10:11], v[90:91], v[86:87] op_sel_hi:[0,1,1]
	v_pk_mul_f32 v[90:91], v[16:17], v[96:97] op_sel:[0,1] op_sel_hi:[1,0]
	v_pk_fma_f32 v[84:85], v[56:57], v[84:85], v[94:95] op_sel_hi:[0,1,1]
	v_pk_mul_f32 v[94:95], v[62:63], v[64:65] op_sel:[0,1] op_sel_hi:[1,0]
	v_ashrrev_i32_e32 v2, 2, v2
	v_pk_fma_f32 v[80:81], v[8:9], v[98:99], v[80:81] op_sel_hi:[0,1,1]
	v_pk_fma_f32 v[90:91], v[12:13], v[96:97], v[90:91] op_sel_hi:[0,1,1]
	v_pk_fma_f32 v[64:65], v[60:61], v[64:65], v[94:95] op_sel_hi:[0,1,1]
	ds_write2_b64 v106, v[104:105], v[82:83] offset1:16
	ds_write2_b64 v106, v[90:91], v[92:93] offset0:33 offset1:49
	ds_write2_b64 v106, v[80:81], v[78:79] offset0:66 offset1:82
	ds_write2_b64 v106, v[76:77], v[84:85] offset0:99 offset1:115
	ds_write2_b64 v106, v[70:71], v[74:75] offset0:132 offset1:148
	ds_write2_b64 v106, v[88:89], v[72:73] offset0:165 offset1:181
	ds_write2_b64 v106, v[86:87], v[68:69] offset0:198 offset1:214
	ds_write2_b64 v106, v[66:67], v[64:65] offset0:231 offset1:247
	v_add3_u32 v2, v7, v2, s60
	ds_read2_b64 v[64:67], v2 offset1:16
	ds_read2_b64 v[68:71], v2 offset0:33 offset1:49
	ds_read2_b64 v[72:75], v2 offset0:66 offset1:82
	ds_read2_b64 v[76:79], v2 offset0:132 offset1:148
	ds_read2_b64 v[80:83], v2 offset0:99 offset1:115
	ds_read2_b64 v[84:87], v2 offset0:165 offset1:181
	ds_read2_b64 v[88:91], v2 offset0:198 offset1:214
	ds_read2_b64 v[92:95], v2 offset0:231 offset1:247
	s_waitcnt lgkmcnt(4)
	v_pk_add_f32 v[96:97], v[64:65], v[76:77]
	v_pk_add_f32 v[64:65], v[64:65], v[76:77] neg_lo:[0,1] neg_hi:[0,1]
	v_pk_add_f32 v[76:77], v[66:67], v[78:79]
	v_pk_add_f32 v[66:67], v[66:67], v[78:79] neg_lo:[0,1] neg_hi:[0,1]
	s_waitcnt lgkmcnt(1)
	v_pk_add_f32 v[98:99], v[74:75], v[90:91]
	v_pk_mul_f32 v[78:79], v[66:67], s[24:25]
	v_pk_add_f32 v[74:75], v[74:75], v[90:91] neg_lo:[0,1] neg_hi:[0,1]
	v_pk_fma_f32 v[66:67], v[66:67], s[22:23], v[78:79] op_sel:[0,0,1] op_sel_hi:[1,0,0]
	v_pk_add_f32 v[78:79], v[68:69], v[84:85]
	v_pk_add_f32 v[68:69], v[68:69], v[84:85] neg_lo:[0,1] neg_hi:[0,1]
	v_pk_mul_f32 v[90:91], v[74:75], s[44:45]
	v_pk_mul_f32 v[84:85], v[68:69], s[40:41]
	v_pk_fma_f32 v[74:75], v[74:75], s[50:51], v[90:91] op_sel:[0,0,1] op_sel_hi:[1,0,0] neg_lo:[1,0,0] neg_hi:[1,0,0]
	s_waitcnt lgkmcnt(0)
	v_pk_add_f32 v[90:91], v[80:81], v[92:93]
	v_pk_add_f32 v[80:81], v[80:81], v[92:93] neg_lo:[0,1] neg_hi:[0,1]
	v_pk_fma_f32 v[68:69], v[68:69], s[38:39], v[84:85] op_sel:[0,0,1] op_sel_hi:[1,0,0]
	v_pk_add_f32 v[84:85], v[70:71], v[86:87]
	v_pk_add_f32 v[70:71], v[70:71], v[86:87] neg_lo:[0,1] neg_hi:[0,1]
	v_pk_mul_f32 v[92:93], v[80:81], s[40:41]
	v_pk_mul_f32 v[86:87], v[70:71], s[44:45]
	v_pk_fma_f32 v[80:81], v[80:81], s[38:39], v[92:93] op_sel:[0,0,1] op_sel_hi:[1,0,0] neg_lo:[1,0,0] neg_hi:[1,0,0]
	v_pk_add_f32 v[92:93], v[82:83], v[94:95]
	v_pk_add_f32 v[82:83], v[82:83], v[94:95] neg_lo:[0,1] neg_hi:[0,1]
	v_pk_fma_f32 v[70:71], v[70:71], s[50:51], v[86:87] op_sel:[0,0,1] op_sel_hi:[1,0,0]
	v_pk_add_f32 v[86:87], v[72:73], v[88:89]
	v_pk_mul_f32 v[94:95], v[82:83], s[24:25]
	v_pk_add_f32 v[88:89], v[72:73], v[88:89] neg_lo:[0,1] neg_hi:[0,1]
	v_pk_fma_f32 v[82:83], v[82:83], s[22:23], v[94:95] op_sel:[0,0,1] op_sel_hi:[1,0,0] neg_lo:[1,0,0] neg_hi:[1,0,0]
	v_pk_add_f32 v[94:95], v[96:97], v[86:87]
	v_pk_add_f32 v[86:87], v[96:97], v[86:87] neg_lo:[0,1] neg_hi:[0,1]
	v_pk_add_f32 v[96:97], v[76:77], v[98:99]
	v_pk_add_f32 v[76:77], v[76:77], v[98:99] neg_lo:[0,1] neg_hi:[0,1]
	s_nop 0
	v_pk_mul_f32 v[98:99], v[76:77], s[40:41]
	v_pk_add_f32 v[100:101], v[84:85], v[92:93]
	v_pk_add_f32 v[84:85], v[84:85], v[92:93] neg_lo:[0,1] neg_hi:[0,1]
	v_pk_fma_f32 v[76:77], v[76:77], s[38:39], v[98:99] op_sel:[0,0,1] op_sel_hi:[1,0,0]
	v_pk_add_f32 v[98:99], v[78:79], v[90:91]
	v_pk_add_f32 v[90:91], v[78:79], v[90:91] neg_lo:[0,1] neg_hi:[0,1]
	v_pk_mul_f32 v[92:93], v[84:85], s[40:41]
	v_pk_add_f32 v[72:73], v[64:65], v[88:89] op_sel:[0,1] op_sel_hi:[1,0] neg_hi:[0,1]
	v_pk_add_f32 v[64:65], v[64:65], v[88:89] op_sel:[0,1] op_sel_hi:[1,0] neg_lo:[0,1]
	v_pk_add_f32 v[88:89], v[66:67], v[74:75]
	v_pk_add_f32 v[66:67], v[66:67], v[74:75] neg_lo:[0,1] neg_hi:[0,1]
	v_pk_fma_f32 v[84:85], v[84:85], s[38:39], v[92:93] op_sel:[0,0,1] op_sel_hi:[1,0,0] neg_lo:[1,0,0] neg_hi:[1,0,0]
	v_pk_mul_f32 v[74:75], v[66:67], s[40:41]
	s_nop 0
	v_pk_fma_f32 v[66:67], v[66:67], s[38:39], v[74:75] op_sel:[0,0,1] op_sel_hi:[1,0,0]
	v_pk_add_f32 v[74:75], v[68:69], v[80:81]
	v_pk_add_f32 v[92:93], v[70:71], v[82:83]
	v_pk_add_f32 v[70:71], v[70:71], v[82:83] neg_lo:[0,1] neg_hi:[0,1]
	v_pk_add_f32 v[78:79], v[86:87], v[90:91] op_sel:[0,1] op_sel_hi:[1,0] neg_hi:[0,1]
	v_pk_add_f32 v[86:87], v[86:87], v[90:91] op_sel:[0,1] op_sel_hi:[1,0] neg_lo:[0,1]
	v_pk_add_f32 v[90:91], v[76:77], v[84:85]
	v_pk_add_f32 v[84:85], v[76:77], v[84:85] neg_lo:[0,1] neg_hi:[0,1]
	v_pk_add_f32 v[80:81], v[68:69], v[80:81] neg_lo:[0,1] neg_hi:[0,1]
	v_pk_mul_f32 v[82:83], v[70:71], s[40:41]
	v_pk_add_f32 v[102:103], v[72:73], v[74:75]
	v_pk_add_f32 v[72:73], v[72:73], v[74:75] neg_lo:[0,1] neg_hi:[0,1]
	v_pk_add_f32 v[74:75], v[88:89], v[92:93]
	v_pk_fma_f32 v[70:71], v[70:71], s[38:39], v[82:83] op_sel:[0,0,1] op_sel_hi:[1,0,0] neg_lo:[1,0,0] neg_hi:[1,0,0]
	v_pk_add_f32 v[82:83], v[94:95], v[98:99]
	v_pk_add_f32 v[94:95], v[94:95], v[98:99] neg_lo:[0,1] neg_hi:[0,1]
	v_pk_add_f32 v[98:99], v[96:97], v[100:101]
	v_pk_add_f32 v[76:77], v[86:87], v[84:85] op_sel:[0,1] op_sel_hi:[1,0] neg_hi:[0,1]
	v_pk_add_f32 v[84:85], v[86:87], v[84:85] op_sel:[0,1] op_sel_hi:[1,0] neg_lo:[0,1]
	v_pk_add_f32 v[86:87], v[102:103], v[74:75]
	v_pk_add_f32 v[100:101], v[96:97], v[100:101] neg_lo:[0,1] neg_hi:[0,1]
	v_pk_add_f32 v[68:69], v[64:65], v[80:81] op_sel:[0,1] op_sel_hi:[1,0] neg_hi:[0,1]
	v_pk_add_f32 v[64:65], v[64:65], v[80:81] op_sel:[0,1] op_sel_hi:[1,0] neg_lo:[0,1]
	v_pk_add_f32 v[80:81], v[66:67], v[70:71]
	v_pk_add_f32 v[104:105], v[82:83], v[98:99]
	v_pk_add_f32 v[82:83], v[82:83], v[98:99] neg_lo:[0,1] neg_hi:[0,1]
	v_pk_add_f32 v[98:99], v[78:79], v[90:91]
	v_pk_mul_f32 v[4:5], v[4:5], v[86:87] op_sel:[0,1] op_sel_hi:[1,0]
	v_pk_add_f32 v[92:93], v[88:89], v[92:93] neg_lo:[0,1] neg_hi:[0,1]
	v_pk_add_f32 v[78:79], v[78:79], v[90:91] neg_lo:[0,1] neg_hi:[0,1]
	v_pk_add_f32 v[90:91], v[68:69], v[80:81]
	v_pk_fma_f32 v[4:5], v[6:7], v[86:87], v[4:5] op_sel_hi:[0,1,1]
	v_pk_mul_f32 v[6:7], v[14:15], v[98:99] op_sel:[0,1] op_sel_hi:[1,0]
	v_pk_add_f32 v[70:71], v[66:67], v[70:71] neg_lo:[0,1] neg_hi:[0,1]
	v_pk_add_f32 v[96:97], v[94:95], v[100:101] op_sel:[0,1] op_sel_hi:[1,0] neg_hi:[0,1]
	v_pk_fma_f32 v[6:7], v[8:9], v[98:99], v[6:7] op_sel_hi:[0,1,1]
	v_pk_mul_f32 v[8:9], v[20:21], v[90:91] op_sel:[0,1] op_sel_hi:[1,0]
	v_pk_add_f32 v[88:89], v[72:73], v[92:93] op_sel:[0,1] op_sel_hi:[1,0] neg_hi:[0,1]
	v_pk_fma_f32 v[8:9], v[10:11], v[90:91], v[8:9] op_sel_hi:[0,1,1]
	v_pk_mul_f32 v[10:11], v[16:17], v[96:97] op_sel:[0,1] op_sel_hi:[1,0]
	v_pk_add_f32 v[66:67], v[64:65], v[70:71] op_sel:[0,1] op_sel_hi:[1,0] neg_hi:[0,1]
	v_pk_fma_f32 v[10:11], v[12:13], v[96:97], v[10:11] op_sel_hi:[0,1,1]
	v_pk_mul_f32 v[12:13], v[22:23], v[88:89] op_sel:[0,1] op_sel_hi:[1,0]
	v_pk_add_f32 v[94:95], v[94:95], v[100:101] op_sel:[0,1] op_sel_hi:[1,0] neg_lo:[0,1]
	v_pk_add_f32 v[74:75], v[102:103], v[74:75] neg_lo:[0,1] neg_hi:[0,1]
	v_pk_add_f32 v[72:73], v[72:73], v[92:93] op_sel:[0,1] op_sel_hi:[1,0] neg_lo:[0,1]
	v_pk_add_f32 v[68:69], v[68:69], v[80:81] neg_lo:[0,1] neg_hi:[0,1]
	v_pk_add_f32 v[64:65], v[64:65], v[70:71] op_sel:[0,1] op_sel_hi:[1,0] neg_lo:[0,1]
	v_pk_fma_f32 v[12:13], v[18:19], v[88:89], v[12:13] op_sel_hi:[0,1,1]
	v_pk_mul_f32 v[14:15], v[26:27], v[76:77] op_sel:[0,1] op_sel_hi:[1,0]
	v_pk_mul_f32 v[16:17], v[30:31], v[66:67] op_sel:[0,1] op_sel_hi:[1,0]
	v_pk_mul_f32 v[18:19], v[34:35], v[82:83] op_sel:[0,1] op_sel_hi:[1,0]
	v_pk_fma_f32 v[14:15], v[24:25], v[76:77], v[14:15] op_sel_hi:[0,1,1]
	v_pk_fma_f32 v[16:17], v[28:29], v[66:67], v[16:17] op_sel_hi:[0,1,1]
	v_pk_fma_f32 v[18:19], v[32:33], v[82:83], v[18:19] op_sel_hi:[0,1,1]
	v_pk_mul_f32 v[20:21], v[38:39], v[74:75] op_sel:[0,1] op_sel_hi:[1,0]
	v_pk_mul_f32 v[22:23], v[42:43], v[78:79] op_sel:[0,1] op_sel_hi:[1,0]
	v_pk_mul_f32 v[24:25], v[46:47], v[68:69] op_sel:[0,1] op_sel_hi:[1,0]
	v_pk_mul_f32 v[26:27], v[50:51], v[94:95] op_sel:[0,1] op_sel_hi:[1,0]
	v_pk_mul_f32 v[28:29], v[54:55], v[72:73] op_sel:[0,1] op_sel_hi:[1,0]
	v_pk_mul_f32 v[30:31], v[58:59], v[84:85] op_sel:[0,1] op_sel_hi:[1,0]
	v_pk_mul_f32 v[32:33], v[62:63], v[64:65] op_sel:[0,1] op_sel_hi:[1,0]
	v_pk_fma_f32 v[20:21], v[36:37], v[74:75], v[20:21] op_sel_hi:[0,1,1]
	v_pk_fma_f32 v[22:23], v[40:41], v[78:79], v[22:23] op_sel_hi:[0,1,1]
	v_pk_fma_f32 v[24:25], v[44:45], v[68:69], v[24:25] op_sel_hi:[0,1,1]
	v_pk_fma_f32 v[26:27], v[48:49], v[94:95], v[26:27] op_sel_hi:[0,1,1]
	v_pk_fma_f32 v[28:29], v[52:53], v[72:73], v[28:29] op_sel_hi:[0,1,1]
	v_pk_fma_f32 v[30:31], v[56:57], v[84:85], v[30:31] op_sel_hi:[0,1,1]
	v_pk_fma_f32 v[32:33], v[60:61], v[64:65], v[32:33] op_sel_hi:[0,1,1]
	ds_write2_b64 v2, v[104:105], v[18:19] offset1:16
	ds_write2_b64 v2, v[10:11], v[26:27] offset0:33 offset1:49
	ds_write2_b64 v2, v[6:7], v[22:23] offset0:66 offset1:82
	ds_write2_b64 v2, v[14:15], v[30:31] offset0:99 offset1:115
	ds_write2_b64 v2, v[4:5], v[20:21] offset0:132 offset1:148
	ds_write2_b64 v2, v[12:13], v[28:29] offset0:165 offset1:181
	ds_write2_b64 v2, v[8:9], v[24:25] offset0:198 offset1:214
	ds_write2_b64 v2, v[16:17], v[32:33] offset0:231 offset1:247
	s_waitcnt lgkmcnt(0)
	s_barrier
	s_nop 0
	v_ashrrev_i32_e32 v2, 31, v142
	v_add_u32_sdwa v2, v142, v2 dst_sel:DWORD dst_unused:UNUSED_PAD src0_sel:DWORD src1_sel:BYTE_3
	v_ashrrev_i32_e32 v145, 8, v2
	v_mul_i32_i24_e32 v2, 0x100, v145
	v_sub_u32_e32 v144, v142, v2
	v_lshlrev_b32_e32 v2, 1, v144
	v_bfrev_b32_e32 v2, v2
	v_lshrrev_b32_e32 v2, 23, v2
	v_sub_u32_e32 v2, 0x200, v2
	v_bfrev_b32_e32 v2, v2
	v_lshrrev_b32_e32 v2, 19, v2
	v_lshlrev_b32_e32 v143, 13, v145
	v_and_b32_e32 v2, 0x1ff0, v2
	v_cmp_eq_u32_e32 vcc, 0, v144
	v_lshl_add_u32 v4, v144, 5, v143
	v_lshlrev_b32_e32 v5, 3, v4
	v_cndmask_b32_e64 v2, v2, 16, vcc
	v_ashrrev_i32_e32 v4, 2, v4
	v_or_b32_e32 v2, v2, v143
	v_add3_u32 v56, 0, v5, v4
	v_ashrrev_i32_e32 v4, 5, v2
	v_lshlrev_b32_e32 v2, 3, v2
	v_lshlrev_b32_e32 v4, 3, v4
	v_add3_u32 v2, 0, v2, v4
	ds_read2_b64 v[4:7], v56 offset1:1
	ds_read2_b64 v[8:11], v56 offset0:2 offset1:3
	ds_read2_b64 v[12:15], v2 offset1:1
	ds_read2_b64 v[16:19], v2 offset0:2 offset1:3
	ds_read2_b64 v[20:23], v56 offset0:4 offset1:5
	ds_read2_b64 v[24:27], v56 offset0:6 offset1:7
	ds_read2_b64 v[28:31], v2 offset0:4 offset1:5
	ds_read2_b64 v[32:35], v2 offset0:6 offset1:7
	ds_read2_b64 v[36:39], v56 offset0:8 offset1:9
	ds_read2_b64 v[40:43], v56 offset0:10 offset1:11
	ds_read2_b64 v[44:47], v2 offset0:8 offset1:9
	ds_read2_b64 v[52:55], v2 offset0:10 offset1:11
	ds_read2_b64 v[48:51], v56 offset0:12 offset1:13
	ds_read2_b64 v[56:59], v56 offset0:14 offset1:15
	ds_read2_b64 v[62:65], v2 offset0:12 offset1:13
	ds_read2_b64 v[74:77], v2 offset0:14 offset1:15
	s_waitcnt lgkmcnt(7)
	v_pk_add_f32 v[60:61], v[4:5], v[36:37]
	v_pk_add_f32 v[4:5], v[4:5], v[36:37] neg_lo:[0,1] neg_hi:[0,1]
	v_pk_add_f32 v[36:37], v[6:7], v[38:39]
	v_pk_add_f32 v[6:7], v[6:7], v[38:39] neg_lo:[0,1] neg_hi:[0,1]
	s_waitcnt lgkmcnt(3)
	v_pk_add_f32 v[66:67], v[22:23], v[50:51]
	v_pk_mul_f32 v[38:39], v[6:7], s[24:25]
	v_pk_add_f32 v[22:23], v[22:23], v[50:51] neg_lo:[0,1] neg_hi:[0,1]
	v_pk_fma_f32 v[6:7], v[6:7], s[22:23], v[38:39] op_sel:[0,0,1] op_sel_hi:[1,0,0]
	v_pk_add_f32 v[38:39], v[8:9], v[40:41]
	v_pk_add_f32 v[8:9], v[8:9], v[40:41] neg_lo:[0,1] neg_hi:[0,1]
	v_pk_mul_f32 v[50:51], v[22:23], s[44:45]
	v_pk_mul_f32 v[40:41], v[8:9], s[40:41]
	v_pk_fma_f32 v[22:23], v[22:23], s[50:51], v[50:51] op_sel:[0,0,1] op_sel_hi:[1,0,0] neg_lo:[1,0,0] neg_hi:[1,0,0]
	v_pk_fma_f32 v[8:9], v[8:9], s[38:39], v[40:41] op_sel:[0,0,1] op_sel_hi:[1,0,0]
	v_pk_add_f32 v[40:41], v[10:11], v[42:43]
	v_pk_add_f32 v[10:11], v[10:11], v[42:43] neg_lo:[0,1] neg_hi:[0,1]
	s_waitcnt lgkmcnt(2)
	v_pk_add_f32 v[50:51], v[24:25], v[56:57]
	v_pk_add_f32 v[24:25], v[24:25], v[56:57] neg_lo:[0,1] neg_hi:[0,1]
	v_pk_mul_f32 v[42:43], v[10:11], s[44:45]
	v_pk_mul_f32 v[56:57], v[24:25], s[40:41]
	v_pk_fma_f32 v[10:11], v[10:11], s[50:51], v[42:43] op_sel:[0,0,1] op_sel_hi:[1,0,0]
	v_pk_add_f32 v[42:43], v[20:21], v[48:49]
	v_pk_add_f32 v[48:49], v[20:21], v[48:49] neg_lo:[0,1] neg_hi:[0,1]
	v_pk_fma_f32 v[24:25], v[24:25], s[38:39], v[56:57] op_sel:[0,0,1] op_sel_hi:[1,0,0] neg_lo:[1,0,0] neg_hi:[1,0,0]
	v_pk_add_f32 v[56:57], v[26:27], v[58:59]
	v_pk_add_f32 v[26:27], v[26:27], v[58:59] neg_lo:[0,1] neg_hi:[0,1]
	s_nop 0
	v_pk_mul_f32 v[58:59], v[26:27], s[24:25]
	v_pk_add_f32 v[68:69], v[40:41], v[56:57]
	v_pk_add_f32 v[40:41], v[40:41], v[56:57] neg_lo:[0,1] neg_hi:[0,1]
	v_pk_fma_f32 v[26:27], v[26:27], s[22:23], v[58:59] op_sel:[0,0,1] op_sel_hi:[1,0,0] neg_lo:[1,0,0] neg_hi:[1,0,0]
	v_pk_mul_f32 v[56:57], v[40:41], s[40:41]
	v_pk_add_f32 v[20:21], v[4:5], v[48:49] op_sel:[0,1] op_sel_hi:[1,0] neg_hi:[0,1]
	v_pk_add_f32 v[4:5], v[4:5], v[48:49] op_sel:[0,1] op_sel_hi:[1,0] neg_lo:[0,1]
	v_pk_add_f32 v[48:49], v[6:7], v[22:23]
	v_pk_add_f32 v[6:7], v[6:7], v[22:23] neg_lo:[0,1] neg_hi:[0,1]
	v_pk_fma_f32 v[40:41], v[40:41], s[38:39], v[56:57] op_sel:[0,0,1] op_sel_hi:[1,0,0] neg_lo:[1,0,0] neg_hi:[1,0,0]
	v_pk_mul_f32 v[22:23], v[6:7], s[40:41]
	v_pk_add_f32 v[56:57], v[10:11], v[26:27]
	v_pk_add_f32 v[10:11], v[10:11], v[26:27] neg_lo:[0,1] neg_hi:[0,1]
	v_pk_add_f32 v[58:59], v[60:61], v[42:43]
	v_pk_add_f32 v[42:43], v[60:61], v[42:43] neg_lo:[0,1] neg_hi:[0,1]
	v_pk_add_f32 v[60:61], v[36:37], v[66:67]
	v_pk_add_f32 v[36:37], v[36:37], v[66:67] neg_lo:[0,1] neg_hi:[0,1]
	v_pk_fma_f32 v[6:7], v[6:7], s[38:39], v[22:23] op_sel:[0,0,1] op_sel_hi:[1,0,0]
	v_pk_add_f32 v[22:23], v[8:9], v[24:25]
	v_pk_add_f32 v[24:25], v[8:9], v[24:25] neg_lo:[0,1] neg_hi:[0,1]
	v_pk_mul_f32 v[26:27], v[10:11], s[40:41]
	v_pk_mul_f32 v[66:67], v[36:37], s[40:41]
	v_pk_fma_f32 v[10:11], v[10:11], s[38:39], v[26:27] op_sel:[0,0,1] op_sel_hi:[1,0,0] neg_lo:[1,0,0] neg_hi:[1,0,0]
	v_pk_fma_f32 v[36:37], v[36:37], s[38:39], v[66:67] op_sel:[0,0,1] op_sel_hi:[1,0,0]
	v_pk_add_f32 v[66:67], v[38:39], v[50:51]
	v_pk_add_f32 v[8:9], v[4:5], v[24:25] op_sel:[0,1] op_sel_hi:[1,0] neg_hi:[0,1]
	v_pk_add_f32 v[4:5], v[4:5], v[24:25] op_sel:[0,1] op_sel_hi:[1,0] neg_lo:[0,1]
	v_pk_add_f32 v[24:25], v[6:7], v[10:11]
	v_pk_add_f32 v[10:11], v[6:7], v[10:11] neg_lo:[0,1] neg_hi:[0,1]
	v_pk_add_f32 v[26:27], v[58:59], v[66:67]
	v_pk_add_f32 v[58:59], v[58:59], v[66:67] neg_lo:[0,1] neg_hi:[0,1]
	v_pk_add_f32 v[66:67], v[60:61], v[68:69]
	v_pk_add_f32 v[68:69], v[60:61], v[68:69] neg_lo:[0,1] neg_hi:[0,1]
	v_pk_add_f32 v[60:61], v[4:5], v[10:11] op_sel:[0,1] op_sel_hi:[1,0] neg_hi:[0,1]
	v_pk_add_f32 v[90:91], v[4:5], v[10:11] op_sel:[0,1] op_sel_hi:[1,0] neg_lo:[0,1]
	v_pk_add_f32 v[10:11], v[14:15], v[46:47] neg_lo:[0,1] neg_hi:[0,1]
	v_pk_add_f32 v[50:51], v[38:39], v[50:51] neg_lo:[0,1] neg_hi:[0,1]
	v_pk_add_f32 v[84:85], v[58:59], v[68:69] op_sel:[0,1] op_sel_hi:[1,0] neg_hi:[0,1]
	v_pk_add_f32 v[86:87], v[58:59], v[68:69] op_sel:[0,1] op_sel_hi:[1,0] neg_lo:[0,1]
	v_pk_add_f32 v[82:83], v[8:9], v[24:25]
	v_pk_add_f32 v[68:69], v[8:9], v[24:25] neg_lo:[0,1] neg_hi:[0,1]
	v_pk_add_f32 v[4:5], v[12:13], v[44:45]
	v_pk_add_f32 v[6:7], v[12:13], v[44:45] neg_lo:[0,1] neg_hi:[0,1]
	v_pk_add_f32 v[8:9], v[14:15], v[46:47]
	v_pk_mul_f32 v[12:13], v[10:11], s[24:25]
	v_pk_add_f32 v[14:15], v[16:17], v[52:53] neg_lo:[0,1] neg_hi:[0,1]
	v_pk_add_f32 v[70:71], v[20:21], v[22:23]
	v_pk_add_f32 v[20:21], v[20:21], v[22:23] neg_lo:[0,1] neg_hi:[0,1]
	v_pk_add_f32 v[22:23], v[48:49], v[56:57]
	v_pk_add_f32 v[48:49], v[48:49], v[56:57] neg_lo:[0,1] neg_hi:[0,1]
	v_pk_fma_f32 v[10:11], v[10:11], s[22:23], v[12:13] op_sel:[0,0,1] op_sel_hi:[1,0,0]
	v_pk_add_f32 v[12:13], v[16:17], v[52:53]
	v_pk_mul_f32 v[16:17], v[14:15], s[40:41]
	v_pk_add_f32 v[38:39], v[42:43], v[50:51] op_sel:[0,1] op_sel_hi:[1,0] neg_hi:[0,1]
	v_pk_add_f32 v[42:43], v[42:43], v[50:51] op_sel:[0,1] op_sel_hi:[1,0] neg_lo:[0,1]
	v_pk_add_f32 v[50:51], v[36:37], v[40:41]
	v_pk_mul_f32 v[56:57], v[48:49], 1.0 op_sel:[1,0] op_sel_hi:[0,0] neg_hi:[1,0]
	v_pk_fma_f32 v[14:15], v[14:15], s[38:39], v[16:17] op_sel:[0,0,1] op_sel_hi:[1,0,0]
	v_pk_add_f32 v[16:17], v[18:19], v[54:55]
	v_pk_add_f32 v[18:19], v[18:19], v[54:55] neg_lo:[0,1] neg_hi:[0,1]
	v_pk_add_f32 v[130:131], v[26:27], v[66:67]
	v_pk_add_f32 v[92:93], v[26:27], v[66:67] neg_lo:[0,1] neg_hi:[0,1]
	v_pk_add_f32 v[88:89], v[38:39], v[50:51]
	v_pk_add_f32 v[72:73], v[38:39], v[50:51] neg_lo:[0,1] neg_hi:[0,1]
	v_pk_add_f32 v[96:97], v[70:71], v[22:23]
	v_pk_add_f32 v[50:51], v[70:71], v[22:23] neg_lo:[0,1] neg_hi:[0,1]
	v_pk_add_f32 v[66:67], v[20:21], v[56:57]
	v_pk_add_f32 v[80:81], v[20:21], v[56:57] neg_lo:[0,1] neg_hi:[0,1]
	v_pk_mul_f32 v[20:21], v[18:19], s[44:45]
	s_waitcnt lgkmcnt(1)
	v_pk_add_f32 v[24:25], v[28:29], v[62:63] neg_lo:[0,1] neg_hi:[0,1]
	v_pk_add_f32 v[26:27], v[30:31], v[64:65] neg_lo:[0,1] neg_hi:[0,1]
	v_pk_fma_f32 v[18:19], v[18:19], s[50:51], v[20:21] op_sel:[0,0,1] op_sel_hi:[1,0,0]
	v_pk_add_f32 v[20:21], v[28:29], v[62:63]
	v_pk_add_f32 v[22:23], v[30:31], v[64:65]
	v_pk_mul_f32 v[28:29], v[26:27], s[44:45]
	s_waitcnt lgkmcnt(0)
	v_pk_add_f32 v[30:31], v[32:33], v[74:75] neg_lo:[0,1] neg_hi:[0,1]
	v_pk_fma_f32 v[26:27], v[26:27], s[50:51], v[28:29] op_sel:[0,0,1] op_sel_hi:[1,0,0] neg_lo:[1,0,0] neg_hi:[1,0,0]
	v_pk_add_f32 v[28:29], v[32:33], v[74:75]
	v_pk_mul_f32 v[32:33], v[30:31], s[40:41]
	v_pk_add_f32 v[36:37], v[36:37], v[40:41] neg_lo:[0,1] neg_hi:[0,1]
	v_pk_fma_f32 v[30:31], v[30:31], s[38:39], v[32:33] op_sel:[0,0,1] op_sel_hi:[1,0,0] neg_lo:[1,0,0] neg_hi:[1,0,0]
	v_pk_add_f32 v[32:33], v[34:35], v[76:77]
	v_pk_add_f32 v[34:35], v[34:35], v[76:77] neg_lo:[0,1] neg_hi:[0,1]
	v_pk_mul_f32 v[40:41], v[36:37], 1.0 op_sel:[1,0] op_sel_hi:[0,0] neg_hi:[1,0]
	v_pk_mul_f32 v[36:37], v[34:35], s[24:25]
	v_mov_b32_e32 v2, v130
	v_pk_fma_f32 v[34:35], v[34:35], s[22:23], v[36:37] op_sel:[0,0,1] op_sel_hi:[1,0,0] neg_lo:[1,0,0] neg_hi:[1,0,0]
	v_pk_add_f32 v[36:37], v[4:5], v[20:21]
	v_pk_add_f32 v[4:5], v[4:5], v[20:21] neg_lo:[0,1] neg_hi:[0,1]
	v_pk_add_f32 v[20:21], v[8:9], v[22:23]
	v_pk_add_f32 v[8:9], v[8:9], v[22:23] neg_lo:[0,1] neg_hi:[0,1]
	v_cmp_ne_u32_e64 s[0:1], 0, v144
	v_pk_mul_f32 v[22:23], v[8:9], s[40:41]
	v_pk_add_f32 v[78:79], v[42:43], v[40:41]
	v_pk_fma_f32 v[8:9], v[8:9], s[38:39], v[22:23] op_sel:[0,0,1] op_sel_hi:[1,0,0]
	v_pk_add_f32 v[22:23], v[12:13], v[28:29]
	v_pk_add_f32 v[28:29], v[12:13], v[28:29] neg_lo:[0,1] neg_hi:[0,1]
	v_pk_add_f32 v[94:95], v[42:43], v[40:41] neg_lo:[0,1] neg_hi:[0,1]
	v_pk_add_f32 v[12:13], v[16:17], v[32:33]
	v_pk_add_f32 v[16:17], v[16:17], v[32:33] neg_lo:[0,1] neg_hi:[0,1]
	s_nop 0
	v_pk_mul_f32 v[32:33], v[16:17], s[40:41]
	s_nop 0
	v_pk_fma_f32 v[16:17], v[16:17], s[38:39], v[32:33] op_sel:[0,0,1] op_sel_hi:[1,0,0] neg_lo:[1,0,0] neg_hi:[1,0,0]
	v_pk_add_f32 v[32:33], v[6:7], v[24:25] op_sel:[0,1] op_sel_hi:[1,0] neg_hi:[0,1]
	v_pk_add_f32 v[6:7], v[6:7], v[24:25] op_sel:[0,1] op_sel_hi:[1,0] neg_lo:[0,1]
	v_pk_add_f32 v[24:25], v[10:11], v[26:27]
	v_pk_add_f32 v[10:11], v[10:11], v[26:27] neg_lo:[0,1] neg_hi:[0,1]
	s_nop 0
	v_pk_mul_f32 v[26:27], v[10:11], s[40:41]
	s_nop 0
	v_pk_fma_f32 v[10:11], v[10:11], s[38:39], v[26:27] op_sel:[0,0,1] op_sel_hi:[1,0,0]
	v_pk_add_f32 v[26:27], v[14:15], v[30:31]
	v_pk_add_f32 v[30:31], v[14:15], v[30:31] neg_lo:[0,1] neg_hi:[0,1]
	s_nop 0
	v_pk_add_f32 v[14:15], v[18:19], v[34:35]
	v_pk_add_f32 v[18:19], v[18:19], v[34:35] neg_lo:[0,1] neg_hi:[0,1]
	s_nop 0
	v_pk_mul_f32 v[34:35], v[18:19], s[40:41]
	s_nop 0
	v_pk_fma_f32 v[18:19], v[18:19], s[38:39], v[34:35] op_sel:[0,0,1] op_sel_hi:[1,0,0] neg_lo:[1,0,0] neg_hi:[1,0,0]
	v_pk_add_f32 v[34:35], v[36:37], v[22:23]
	v_pk_add_f32 v[22:23], v[36:37], v[22:23] neg_lo:[0,1] neg_hi:[0,1]
	v_pk_add_f32 v[36:37], v[20:21], v[12:13]
	v_pk_add_f32 v[12:13], v[20:21], v[12:13] neg_lo:[0,1] neg_hi:[0,1]
	v_pk_add_f32 v[98:99], v[34:35], v[36:37]
	v_pk_mul_f32 v[20:21], v[12:13], 1.0 op_sel:[1,0] op_sel_hi:[0,0] neg_hi:[1,0]
	v_pk_add_f32 v[12:13], v[4:5], v[28:29] op_sel:[0,1] op_sel_hi:[1,0] neg_hi:[0,1]
	v_pk_add_f32 v[4:5], v[4:5], v[28:29] op_sel:[0,1] op_sel_hi:[1,0] neg_lo:[0,1]
	v_pk_add_f32 v[28:29], v[8:9], v[16:17]
	v_pk_add_f32 v[8:9], v[8:9], v[16:17] neg_lo:[0,1] neg_hi:[0,1]
	v_pk_add_f32 v[100:101], v[34:35], v[36:37] neg_lo:[0,1] neg_hi:[0,1]
	v_pk_mul_f32 v[16:17], v[8:9], 1.0 op_sel:[1,0] op_sel_hi:[0,0] neg_hi:[1,0]
	v_pk_add_f32 v[8:9], v[32:33], v[26:27]
	v_pk_add_f32 v[26:27], v[32:33], v[26:27] neg_lo:[0,1] neg_hi:[0,1]
	v_pk_add_f32 v[32:33], v[24:25], v[14:15]
	v_pk_add_f32 v[14:15], v[24:25], v[14:15] neg_lo:[0,1] neg_hi:[0,1]
	v_pk_add_f32 v[102:103], v[22:23], v[20:21]
	v_pk_mul_f32 v[24:25], v[14:15], 1.0 op_sel:[1,0] op_sel_hi:[0,0] neg_hi:[1,0]
	v_pk_add_f32 v[14:15], v[6:7], v[30:31] op_sel:[0,1] op_sel_hi:[1,0] neg_hi:[0,1]
	v_pk_add_f32 v[6:7], v[6:7], v[30:31] op_sel:[0,1] op_sel_hi:[1,0] neg_lo:[0,1]
	v_pk_add_f32 v[30:31], v[10:11], v[18:19]
	v_pk_add_f32 v[10:11], v[10:11], v[18:19] neg_lo:[0,1] neg_hi:[0,1]
	v_pk_add_f32 v[104:105], v[22:23], v[20:21] neg_lo:[0,1] neg_hi:[0,1]
	v_pk_mul_f32 v[18:19], v[10:11], 1.0 op_sel:[1,0] op_sel_hi:[0,0] neg_hi:[1,0]
	v_pk_add_f32 v[106:107], v[12:13], v[28:29]
	v_pk_add_f32 v[108:109], v[12:13], v[28:29] neg_lo:[0,1] neg_hi:[0,1]
	v_pk_add_f32 v[110:111], v[4:5], v[16:17]
	v_pk_add_f32 v[112:113], v[4:5], v[16:17] neg_lo:[0,1] neg_hi:[0,1]
	v_pk_add_f32 v[114:115], v[8:9], v[32:33]
	v_pk_add_f32 v[116:117], v[8:9], v[32:33] neg_lo:[0,1] neg_hi:[0,1]
	v_pk_add_f32 v[118:119], v[26:27], v[24:25]
	v_pk_add_f32 v[120:121], v[26:27], v[24:25] neg_lo:[0,1] neg_hi:[0,1]
	v_pk_add_f32 v[122:123], v[14:15], v[30:31]
	v_pk_add_f32 v[124:125], v[14:15], v[30:31] neg_lo:[0,1] neg_hi:[0,1]
	v_pk_add_f32 v[126:127], v[6:7], v[18:19]
	v_pk_add_f32 v[128:129], v[6:7], v[18:19] neg_lo:[0,1] neg_hi:[0,1]
	v_pk_mov_b32 v[4:5], v[130:131], v[2:3] op_sel:[1,1]
	v_mov_b64_e32 v[6:7], v[2:3]
	s_and_saveexec_b64 s[50:51], s[0:1]
	s_xor_b64 s[0:1], exec, s[50:51]
	s_cbranch_execz .LBB0_576
	v_pk_add_f32 v[4:5], v[96:97], v[112:113]
	v_pk_add_f32 v[24:25], v[96:97], v[112:113] neg_lo:[0,1] neg_hi:[0,1]
	v_pk_add_f32 v[148:149], v[130:131], v[128:129]
	v_pk_add_f32 v[8:9], v[130:131], v[128:129] neg_lo:[0,1] neg_hi:[0,1]
	v_pk_add_f32 v[128:129], v[126:127], v[92:93]
	v_pk_add_f32 v[10:11], v[126:127], v[92:93] neg_lo:[0,1] neg_hi:[0,1]
	v_pk_add_f32 v[92:93], v[84:85], v[124:125]
	v_pk_add_f32 v[12:13], v[84:85], v[124:125] neg_lo:[0,1] neg_hi:[0,1]
	v_pk_add_f32 v[84:85], v[122:123], v[86:87]
	v_pk_add_f32 v[14:15], v[122:123], v[86:87] neg_lo:[0,1] neg_hi:[0,1]
	v_pk_add_f32 v[86:87], v[88:89], v[120:121]
	v_pk_add_f32 v[16:17], v[88:89], v[120:121] neg_lo:[0,1] neg_hi:[0,1]
	v_pk_add_f32 v[88:89], v[118:119], v[72:73]
	v_pk_add_f32 v[18:19], v[118:119], v[72:73] neg_lo:[0,1] neg_hi:[0,1]
	v_pk_add_f32 v[72:73], v[78:79], v[116:117]
	v_pk_add_f32 v[20:21], v[78:79], v[116:117] neg_lo:[0,1] neg_hi:[0,1]
	v_pk_add_f32 v[78:79], v[114:115], v[94:95]
	v_pk_add_f32 v[22:23], v[114:115], v[94:95] neg_lo:[0,1] neg_hi:[0,1]
	v_pk_mov_b32 v[6:7], v[4:5], v[24:25] op_sel:[0,1]
	v_pk_mov_b32 v[4:5], v[4:5], v[24:25] op_sel:[1,0]
	v_pk_add_f32 v[94:95], v[110:111], v[50:51]
	v_pk_add_f32 v[24:25], v[110:111], v[50:51] neg_lo:[0,1] neg_hi:[0,1]
	v_pk_add_f32 v[50:51], v[66:67], v[108:109]
	v_pk_add_f32 v[26:27], v[66:67], v[108:109] neg_lo:[0,1] neg_hi:[0,1]
	v_pk_add_f32 v[66:67], v[106:107], v[80:81]
	v_pk_add_f32 v[28:29], v[106:107], v[80:81] neg_lo:[0,1] neg_hi:[0,1]
	v_pk_add_f32 v[80:81], v[82:83], v[104:105]
	v_pk_add_f32 v[30:31], v[82:83], v[104:105] neg_lo:[0,1] neg_hi:[0,1]
	v_pk_add_f32 v[82:83], v[102:103], v[68:69]
	v_pk_add_f32 v[32:33], v[102:103], v[68:69] neg_lo:[0,1] neg_hi:[0,1]
	v_pk_add_f32 v[68:69], v[60:61], v[100:101]
	v_pk_add_f32 v[34:35], v[60:61], v[100:101] neg_lo:[0,1] neg_hi:[0,1]
	v_pk_add_f32 v[60:61], v[98:99], v[90:91]
	v_pk_add_f32 v[36:37], v[98:99], v[90:91] neg_lo:[0,1] neg_hi:[0,1]
	v_pk_mul_f32 v[6:7], v[6:7], 0.5 op_sel_hi:[1,0]
	v_pk_mul_f32 v[4:5], v[4:5], s[46:47]
	v_mov_b32_e32 v39, v8
	v_mov_b32_e32 v38, v149
	v_mov_b32_e32 v41, v10
	v_mov_b32_e32 v40, v129
	v_mov_b32_e32 v43, v12
	v_mov_b32_e32 v42, v93
	v_mov_b32_e32 v45, v14
	v_mov_b32_e32 v44, v85
	v_mov_b32_e32 v47, v16
	v_mov_b32_e32 v46, v87
	v_mov_b32_e32 v49, v18
	v_mov_b32_e32 v48, v89
	v_mov_b32_e32 v53, v20
	v_mov_b32_e32 v52, v73
	v_mov_b32_e32 v55, v22
	v_mov_b32_e32 v54, v79
	v_mov_b32_e32 v57, v24
	v_mov_b32_e32 v56, v95
	v_mov_b32_e32 v59, v26
	v_mov_b32_e32 v58, v51
	v_mov_b32_e32 v63, v28
	v_mov_b32_e32 v62, v67
	v_mov_b32_e32 v65, v30
	v_mov_b32_e32 v64, v81
	v_mov_b32_e32 v71, v32
	v_mov_b32_e32 v70, v83
	v_mov_b32_e32 v75, v34
	v_mov_b32_e32 v74, v69
	v_mov_b32_e32 v77, v36
	v_mov_b32_e32 v76, v61
	v_mov_b32_e32 v8, v148
	v_mov_b32_e32 v10, v128
	v_mov_b32_e32 v12, v92
	v_mov_b32_e32 v14, v84
	v_mov_b32_e32 v16, v86
	v_mov_b32_e32 v18, v88
	v_mov_b32_e32 v20, v72
	v_mov_b32_e32 v22, v78
	v_mov_b32_e32 v24, v94
	v_mov_b32_e32 v26, v50
	v_mov_b32_e32 v28, v66
	v_mov_b32_e32 v30, v80
	v_mov_b32_e32 v32, v82
	v_mov_b32_e32 v34, v68
	v_mov_b32_e32 v36, v60
.LBB0_576:
	s_andn2_saveexec_b64 s[0:1], s[0:1]
	s_cbranch_execz .LBB0_578
	s_add_i32 s19, s48, 0x400
	v_lshl_add_u32 v8, v145, 10, s19
	v_ashrrev_i32_e32 v9, 31, v8
	v_pk_add_f32 v[38:39], v[98:99], v[128:129]
	v_pk_add_f32 v[98:99], v[98:99], v[128:129] neg_lo:[0,1] neg_hi:[0,1]
	v_pk_add_f32 v[40:41], v[126:127], v[100:101]
	v_pk_add_f32 v[100:101], v[126:127], v[100:101] neg_lo:[0,1] neg_hi:[0,1]
	v_pk_add_f32 v[42:43], v[102:103], v[124:125]
	v_pk_add_f32 v[102:103], v[102:103], v[124:125] neg_lo:[0,1] neg_hi:[0,1]
	v_pk_add_f32 v[44:45], v[122:123], v[104:105]
	v_pk_add_f32 v[104:105], v[122:123], v[104:105] neg_lo:[0,1] neg_hi:[0,1]
	v_pk_add_f32 v[46:47], v[106:107], v[120:121]
	v_pk_add_f32 v[106:107], v[106:107], v[120:121] neg_lo:[0,1] neg_hi:[0,1]
	v_pk_add_f32 v[48:49], v[118:119], v[108:109]
	v_pk_add_f32 v[108:109], v[118:119], v[108:109] neg_lo:[0,1] neg_hi:[0,1]
	v_pk_add_f32 v[52:53], v[110:111], v[116:117]
	v_pk_add_f32 v[110:111], v[110:111], v[116:117] neg_lo:[0,1] neg_hi:[0,1]
	v_pk_add_f32 v[54:55], v[114:115], v[112:113]
	v_pk_add_f32 v[112:113], v[114:115], v[112:113] neg_lo:[0,1] neg_hi:[0,1]
	v_lshl_add_u64 v[8:9], v[8:9], 2, s[6:7]
	v_pk_add_f32 v[56:57], v[96:97], v[90:91]
	v_pk_add_f32 v[90:91], v[96:97], v[90:91] neg_lo:[0,1] neg_hi:[0,1]
	v_pk_add_f32 v[58:59], v[88:89], v[94:95]
	v_pk_add_f32 v[88:89], v[88:89], v[94:95] neg_lo:[0,1] neg_hi:[0,1]
	v_pk_add_f32 v[62:63], v[82:83], v[80:81]
	v_pk_add_f32 v[80:81], v[82:83], v[80:81] neg_lo:[0,1] neg_hi:[0,1]
	v_pk_add_f32 v[64:65], v[84:85], v[86:87]
	v_pk_add_f32 v[82:83], v[84:85], v[86:87] neg_lo:[0,1] neg_hi:[0,1]
	v_pk_add_f32 v[70:71], v[66:67], v[68:69]
	v_pk_add_f32 v[66:67], v[66:67], v[68:69] neg_lo:[0,1] neg_hi:[0,1]
	v_pk_add_f32 v[68:69], v[78:79], v[72:73]
	v_pk_add_f32 v[72:73], v[78:79], v[72:73] neg_lo:[0,1] neg_hi:[0,1]
	v_pk_add_f32 v[74:75], v[60:61], v[50:51]
	v_pk_add_f32 v[50:51], v[60:61], v[50:51] neg_lo:[0,1] neg_hi:[0,1]
	global_store_dwordx2 v[8:9], v[92:93], off
	v_pk_mov_b32 v[36:37], v[74:75], v[50:51] op_sel:[0,1]
	v_pk_mov_b32 v[34:35], v[68:69], v[72:73] op_sel:[0,1]
	v_pk_mov_b32 v[32:33], v[70:71], v[66:67] op_sel:[0,1]
	v_pk_mov_b32 v[30:31], v[64:65], v[82:83] op_sel:[0,1]
	v_pk_mov_b32 v[28:29], v[62:63], v[80:81] op_sel:[0,1]
	v_pk_mov_b32 v[26:27], v[58:59], v[88:89] op_sel:[0,1]
	v_pk_mov_b32 v[24:25], v[56:57], v[90:91] op_sel:[0,1]
	v_pk_mov_b32 v[22:23], v[54:55], v[112:113] op_sel:[0,1]
	v_pk_mov_b32 v[20:21], v[52:53], v[110:111] op_sel:[0,1]
	v_pk_mov_b32 v[18:19], v[48:49], v[108:109] op_sel:[0,1]
	v_pk_mov_b32 v[16:17], v[46:47], v[106:107] op_sel:[0,1]
	v_pk_mov_b32 v[14:15], v[44:45], v[104:105] op_sel:[0,1]
	v_pk_mov_b32 v[12:13], v[42:43], v[102:103] op_sel:[0,1]
	v_pk_mov_b32 v[10:11], v[40:41], v[100:101] op_sel:[0,1]
	v_pk_mov_b32 v[8:9], v[38:39], v[98:99] op_sel:[0,1]
	v_pk_mov_b32 v[76:77], v[74:75], v[50:51] op_sel:[1,0]
	v_pk_mov_b32 v[74:75], v[68:69], v[72:73] op_sel:[1,0]
	v_mov_b32_e32 v70, v71
	v_mov_b32_e32 v71, v66
	v_mov_b32_e32 v64, v65
	v_mov_b32_e32 v65, v82
	v_mov_b32_e32 v62, v63
	v_mov_b32_e32 v63, v80
	v_mov_b32_e32 v58, v59
	v_mov_b32_e32 v59, v88
	v_mov_b32_e32 v56, v57
	v_mov_b32_e32 v57, v90
	v_mov_b32_e32 v54, v55
	v_mov_b32_e32 v55, v112
	v_mov_b32_e32 v52, v53
	v_mov_b32_e32 v53, v110
	v_mov_b32_e32 v48, v49
	v_mov_b32_e32 v49, v108
	v_mov_b32_e32 v46, v47
	v_mov_b32_e32 v47, v106
	v_mov_b32_e32 v44, v45
	v_mov_b32_e32 v45, v104
	v_mov_b32_e32 v42, v43
	v_mov_b32_e32 v43, v102
	v_mov_b32_e32 v40, v41
	v_mov_b32_e32 v41, v100
	v_mov_b32_e32 v38, v39
	v_mov_b32_e32 v39, v98
